# removed 288 s_nop 0 that hipcc put after default-op_sel_hi v_pk_*_f32 results (its DST_OP_SEL hazard check misfires on VOP3P op_sel_hi; pk results with op_sel_hi[0]=0 are consumed adjacent elsewhere i
# baseline (speedup 1.0000x reference)
.LBB0_53:
	v_lshl_or_b32 v144, s6, 7, v152
	s_sub_i32 s6, s7, s5
	v_lshl_add_u32 v155, s6, 10, v151
	ds_read2_b32 v[148:149], v155 offset1:16
	v_lshl_add_u32 v154, s7, 8, v1
	v_ashrrev_i32_e32 v145, 31, v144
	v_mov_b64_e32 v[142:143], s[80:81]
	v_mad_i64_i32 v[146:147], s[6:7], v154, s86, v[142:143]
	s_waitcnt lgkmcnt(0)
	v_pk_mul_f32 v[126:127], v[126:127], v[148:149] op_sel_hi:[1,0]
	v_pk_mul_f32 v[122:123], v[122:123], v[148:149] op_sel_hi:[1,0]
	v_mul_f32_e32 v156, 0xbfb8aa3b, v126
	v_mul_f32_e32 v157, 0xbfb8aa3b, v127
	v_exp_f32_e32 v156, v156
	v_exp_f32_e32 v157, v157
	v_pk_mul_f32 v[124:125], v[124:125], v[148:149] op_sel_hi:[1,0]
	v_pk_mul_f32 v[118:119], v[118:119], v[148:149] op_sel_hi:[1,0]
	v_add_f32_e32 v156, 1.0, v156
	v_add_f32_e32 v157, 1.0, v157
	v_rcp_f32_e32 v156, v156
	v_rcp_f32_e32 v157, v157
	v_pk_mul_f32 v[114:115], v[114:115], v[148:149] op_sel_hi:[1,0]
	v_pk_mul_f32 v[116:117], v[116:117], v[148:149] op_sel_hi:[1,0]
	v_lshlrev_b64 v[144:145], 1, v[144:145]
	v_pk_mul_f32 v[126:127], v[126:127], v[156:157]
	v_lshl_add_u64 v[146:147], v[146:147], 0, v[144:145]
	v_pk_mul_f32 v[122:123], v[122:123], v[126:127]
	v_pk_mul_f32 v[126:127], v[128:129], v[148:149] op_sel_hi:[1,0]
	s_mov_b64 s[28:29], -1
	v_mul_f32_e32 v128, 0xbfb8aa3b, v126
	v_mul_f32_e32 v129, 0xbfb8aa3b, v127
	v_exp_f32_e32 v128, v128
	v_exp_f32_e32 v129, v129
	s_andn2_b64 vcc, exec, s[42:43]
	v_add_f32_e32 v128, 1.0, v128
	v_add_f32_e32 v129, 1.0, v129
	v_rcp_f32_e32 v128, v128
	v_rcp_f32_e32 v129, v129
	s_nop 0
	v_pk_mul_f32 v[126:127], v[126:127], v[128:129]
	v_pk_mul_f32 v[124:125], v[124:125], v[126:127]
	v_mul_f32_e32 v126, 0xbfb8aa3b, v118
	v_mul_f32_e32 v127, 0xbfb8aa3b, v119
	v_exp_f32_e32 v126, v126
	v_exp_f32_e32 v127, v127
	v_add_f32_e32 v126, 1.0, v126
	v_add_f32_e32 v127, 1.0, v127
	v_rcp_f32_e32 v126, v126
	v_rcp_f32_e32 v127, v127
	s_nop 0
	v_pk_mul_f32 v[118:119], v[118:119], v[126:127]
	v_pk_mul_f32 v[118:119], v[114:115], v[118:119]
	v_pk_mul_f32 v[114:115], v[120:121], v[148:149] op_sel_hi:[1,0]
	v_mul_f32_e32 v120, 0xbfb8aa3b, v114
	v_mul_f32_e32 v121, 0xbfb8aa3b, v115
	v_exp_f32_e32 v120, v120
	v_exp_f32_e32 v121, v121
	v_add_f32_e32 v120, 1.0, v120
	v_add_f32_e32 v121, 1.0, v121
	v_rcp_f32_e32 v120, v120
	v_rcp_f32_e32 v121, v121
	s_nop 0
	v_pk_mul_f32 v[114:115], v[114:115], v[120:121]
	v_pk_mul_f32 v[120:121], v[116:117], v[114:115]
	v_cvt_pk_bf16_f32 v114, v122, v123
	v_cvt_pk_bf16_f32 v115, v124, v125
	v_cvt_pk_bf16_f32 v116, v118, v119
	v_cvt_pk_bf16_f32 v117, v120, v121
	global_store_dwordx4 v[146:147], v[114:117], off
	s_nop 1
	v_mov_b32_e32 v116, v149
	v_pk_mul_f32 v[110:111], v[110:111], v[116:117] op_sel_hi:[1,0]
	v_or_b32_e32 v114, 16, v154
	v_mul_f32_e32 v117, 0xbfb8aa3b, v110
	v_exp_f32_e32 v117, v117
	v_mad_i64_i32 v[114:115], s[6:7], v114, s86, v[142:143]
	v_lshl_add_u64 v[114:115], v[114:115], 0, v[144:145]
	v_add_f32_e32 v117, 1.0, v117
	v_rcp_f32_e32 v118, v117
	v_pk_mul_f32 v[106:107], v[106:107], v[116:117] op_sel_hi:[1,0]
	v_mul_f32_e32 v117, 0xbfb8aa3b, v111
	v_exp_f32_e32 v117, v117
	s_nop 0
	v_add_f32_e32 v117, 1.0, v117
	v_rcp_f32_e32 v119, v117
	v_pk_mul_f32 v[108:109], v[108:109], v[116:117] op_sel_hi:[1,0]
	v_pk_mul_f32 v[102:103], v[102:103], v[116:117] op_sel_hi:[1,0]
	v_pk_mul_f32 v[98:99], v[98:99], v[116:117] op_sel_hi:[1,0]
	v_pk_mul_f32 v[110:111], v[110:111], v[118:119]
	v_pk_mul_f32 v[100:101], v[100:101], v[116:117] op_sel_hi:[1,0]
	v_pk_mul_f32 v[106:107], v[106:107], v[110:111]
	v_pk_mul_f32 v[110:111], v[112:113], v[116:117] op_sel_hi:[1,0]
	v_mul_f32_e32 v112, 0xbfb8aa3b, v110
	v_mul_f32_e32 v113, 0xbfb8aa3b, v111
	v_exp_f32_e32 v112, v112
	v_exp_f32_e32 v113, v113
	v_add_f32_e32 v112, 1.0, v112
	v_add_f32_e32 v113, 1.0, v113
	v_rcp_f32_e32 v112, v112
	v_rcp_f32_e32 v113, v113
	s_nop 0
	v_pk_mul_f32 v[110:111], v[110:111], v[112:113]
	v_pk_mul_f32 v[108:109], v[108:109], v[110:111]
	v_mul_f32_e32 v110, 0xbfb8aa3b, v102
	v_mul_f32_e32 v111, 0xbfb8aa3b, v103
	v_exp_f32_e32 v110, v110
	v_exp_f32_e32 v111, v111
	v_add_f32_e32 v110, 1.0, v110
	v_add_f32_e32 v111, 1.0, v111
	v_rcp_f32_e32 v110, v110
	v_rcp_f32_e32 v111, v111
	s_nop 0
	v_pk_mul_f32 v[102:103], v[102:103], v[110:111]
	v_pk_mul_f32 v[102:103], v[98:99], v[102:103]
	v_pk_mul_f32 v[98:99], v[104:105], v[116:117] op_sel_hi:[1,0]
	v_mul_f32_e32 v104, 0xbfb8aa3b, v98
	v_mul_f32_e32 v105, 0xbfb8aa3b, v99
	v_exp_f32_e32 v104, v104
	v_exp_f32_e32 v105, v105
	v_add_f32_e32 v104, 1.0, v104
	v_add_f32_e32 v105, 1.0, v105
	v_rcp_f32_e32 v104, v104
	v_rcp_f32_e32 v105, v105
	s_nop 0
	v_pk_mul_f32 v[98:99], v[98:99], v[104:105]
	v_pk_mul_f32 v[104:105], v[100:101], v[98:99]
	v_cvt_pk_bf16_f32 v98, v106, v107
	v_cvt_pk_bf16_f32 v99, v108, v109
	v_cvt_pk_bf16_f32 v100, v102, v103
	v_cvt_pk_bf16_f32 v101, v104, v105
	global_store_dwordx4 v[114:115], v[98:101], off
	ds_read2_b32 v[100:101], v155 offset0:32 offset1:48
	s_waitcnt lgkmcnt(0)
	v_pk_mul_f32 v[94:95], v[94:95], v[100:101] op_sel_hi:[1,0]
	v_mul_f32_e32 v102, 0xbfb8aa3b, v94
	v_mul_f32_e32 v103, 0xbfb8aa3b, v95
	v_exp_f32_e32 v102, v102
	v_exp_f32_e32 v103, v103
	v_pk_mul_f32 v[90:91], v[90:91], v[100:101] op_sel_hi:[1,0]
	v_pk_mul_f32 v[92:93], v[92:93], v[100:101] op_sel_hi:[1,0]
	v_add_f32_e32 v102, 1.0, v102
	v_add_f32_e32 v103, 1.0, v103
	v_rcp_f32_e32 v102, v102
	v_rcp_f32_e32 v103, v103
	v_pk_mul_f32 v[86:87], v[86:87], v[100:101] op_sel_hi:[1,0]
	v_pk_mul_f32 v[82:83], v[82:83], v[100:101] op_sel_hi:[1,0]
	v_or_b32_e32 v98, 32, v154
	v_pk_mul_f32 v[94:95], v[94:95], v[102:103]
	v_pk_mul_f32 v[84:85], v[84:85], v[100:101] op_sel_hi:[1,0]
	v_pk_mul_f32 v[90:91], v[90:91], v[94:95]
	v_pk_mul_f32 v[94:95], v[96:97], v[100:101] op_sel_hi:[1,0]
	v_mad_i64_i32 v[98:99], s[6:7], v98, s86, v[142:143]
	v_mul_f32_e32 v96, 0xbfb8aa3b, v94
	v_mul_f32_e32 v97, 0xbfb8aa3b, v95
	v_exp_f32_e32 v96, v96
	v_exp_f32_e32 v97, v97
	v_lshl_add_u64 v[98:99], v[98:99], 0, v[144:145]
	v_add_f32_e32 v96, 1.0, v96
	v_add_f32_e32 v97, 1.0, v97
	v_rcp_f32_e32 v96, v96
	v_rcp_f32_e32 v97, v97
	s_nop 0
	v_pk_mul_f32 v[94:95], v[94:95], v[96:97]
	v_pk_mul_f32 v[92:93], v[92:93], v[94:95]
	v_mul_f32_e32 v94, 0xbfb8aa3b, v86
	v_mul_f32_e32 v95, 0xbfb8aa3b, v87
	v_exp_f32_e32 v94, v94
	v_exp_f32_e32 v95, v95
	v_add_f32_e32 v94, 1.0, v94
	v_add_f32_e32 v95, 1.0, v95
	v_rcp_f32_e32 v94, v94
	v_rcp_f32_e32 v95, v95
	s_nop 0
	v_pk_mul_f32 v[86:87], v[86:87], v[94:95]
	v_pk_mul_f32 v[86:87], v[82:83], v[86:87]
	v_pk_mul_f32 v[82:83], v[88:89], v[100:101] op_sel_hi:[1,0]
	v_mul_f32_e32 v88, 0xbfb8aa3b, v82
	v_mul_f32_e32 v89, 0xbfb8aa3b, v83
	v_exp_f32_e32 v88, v88
	v_exp_f32_e32 v89, v89
	v_add_f32_e32 v88, 1.0, v88
	v_add_f32_e32 v89, 1.0, v89
	v_rcp_f32_e32 v88, v88
	v_rcp_f32_e32 v89, v89
	s_nop 0
	v_pk_mul_f32 v[82:83], v[82:83], v[88:89]
	v_pk_mul_f32 v[88:89], v[84:85], v[82:83]
	v_cvt_pk_bf16_f32 v82, v90, v91
	v_cvt_pk_bf16_f32 v83, v92, v93
	v_cvt_pk_bf16_f32 v84, v86, v87
	v_cvt_pk_bf16_f32 v85, v88, v89
	global_store_dwordx4 v[98:99], v[82:85], off
	s_nop 1
	v_mov_b32_e32 v84, v101
	v_pk_mul_f32 v[78:79], v[78:79], v[84:85] op_sel_hi:[1,0]
	v_or_b32_e32 v82, 48, v154
	v_mul_f32_e32 v85, 0xbfb8aa3b, v78
	v_exp_f32_e32 v85, v85
	v_mad_i64_i32 v[82:83], s[6:7], v82, s86, v[142:143]
	v_lshl_add_u64 v[82:83], v[82:83], 0, v[144:145]
	v_add_f32_e32 v85, 1.0, v85
	v_rcp_f32_e32 v86, v85
	v_pk_mul_f32 v[74:75], v[74:75], v[84:85] op_sel_hi:[1,0]
	v_mul_f32_e32 v85, 0xbfb8aa3b, v79
	v_exp_f32_e32 v85, v85
	s_nop 0
	v_add_f32_e32 v85, 1.0, v85
	v_rcp_f32_e32 v87, v85
	v_pk_mul_f32 v[76:77], v[76:77], v[84:85] op_sel_hi:[1,0]
	v_pk_mul_f32 v[70:71], v[70:71], v[84:85] op_sel_hi:[1,0]
	v_pk_mul_f32 v[66:67], v[66:67], v[84:85] op_sel_hi:[1,0]
	v_pk_mul_f32 v[78:79], v[78:79], v[86:87]
	v_pk_mul_f32 v[68:69], v[68:69], v[84:85] op_sel_hi:[1,0]
	v_pk_mul_f32 v[74:75], v[74:75], v[78:79]
	v_pk_mul_f32 v[78:79], v[80:81], v[84:85] op_sel_hi:[1,0]
	v_mul_f32_e32 v80, 0xbfb8aa3b, v78
	v_mul_f32_e32 v81, 0xbfb8aa3b, v79
	v_exp_f32_e32 v80, v80
	v_exp_f32_e32 v81, v81
	v_add_f32_e32 v80, 1.0, v80
	v_add_f32_e32 v81, 1.0, v81
	v_rcp_f32_e32 v80, v80
	v_rcp_f32_e32 v81, v81
	s_nop 0
	v_pk_mul_f32 v[78:79], v[78:79], v[80:81]
	v_pk_mul_f32 v[76:77], v[76:77], v[78:79]
	v_mul_f32_e32 v78, 0xbfb8aa3b, v70
	v_mul_f32_e32 v79, 0xbfb8aa3b, v71
	v_exp_f32_e32 v78, v78
	v_exp_f32_e32 v79, v79
	v_add_f32_e32 v78, 1.0, v78
	v_add_f32_e32 v79, 1.0, v79
	v_rcp_f32_e32 v78, v78
	v_rcp_f32_e32 v79, v79
	s_nop 0
	v_pk_mul_f32 v[70:71], v[70:71], v[78:79]
	v_pk_mul_f32 v[70:71], v[66:67], v[70:71]
	v_pk_mul_f32 v[66:67], v[72:73], v[84:85] op_sel_hi:[1,0]
	v_mul_f32_e32 v72, 0xbfb8aa3b, v66
	v_mul_f32_e32 v73, 0xbfb8aa3b, v67
	v_exp_f32_e32 v72, v72
	v_exp_f32_e32 v73, v73
	v_add_f32_e32 v72, 1.0, v72
	v_add_f32_e32 v73, 1.0, v73
	v_rcp_f32_e32 v72, v72
	v_rcp_f32_e32 v73, v73
	s_nop 0
	v_pk_mul_f32 v[66:67], v[66:67], v[72:73]
	v_pk_mul_f32 v[72:73], v[68:69], v[66:67]
	v_cvt_pk_bf16_f32 v66, v74, v75
	v_cvt_pk_bf16_f32 v67, v76, v77
	v_cvt_pk_bf16_f32 v68, v70, v71
	v_cvt_pk_bf16_f32 v69, v72, v73
	global_store_dwordx4 v[82:83], v[66:69], off
	ds_read2_b32 v[68:69], v155 offset0:128 offset1:144
	s_waitcnt lgkmcnt(0)
	v_pk_mul_f32 v[62:63], v[62:63], v[68:69] op_sel_hi:[1,0]
	v_mul_f32_e32 v70, 0xbfb8aa3b, v62
	v_mul_f32_e32 v71, 0xbfb8aa3b, v63
	v_exp_f32_e32 v70, v70
	v_exp_f32_e32 v71, v71
	v_pk_mul_f32 v[58:59], v[58:59], v[68:69] op_sel_hi:[1,0]
	v_pk_mul_f32 v[60:61], v[60:61], v[68:69] op_sel_hi:[1,0]
	v_add_f32_e32 v70, 1.0, v70
	v_add_f32_e32 v71, 1.0, v71
	v_rcp_f32_e32 v70, v70
	v_rcp_f32_e32 v71, v71
	v_pk_mul_f32 v[54:55], v[54:55], v[68:69] op_sel_hi:[1,0]
	v_pk_mul_f32 v[50:51], v[50:51], v[68:69] op_sel_hi:[1,0]
	v_add_u32_e32 v66, 0x80, v154
	v_pk_mul_f32 v[62:63], v[62:63], v[70:71]
	v_pk_mul_f32 v[52:53], v[52:53], v[68:69] op_sel_hi:[1,0]
	v_pk_mul_f32 v[58:59], v[58:59], v[62:63]
	v_pk_mul_f32 v[62:63], v[64:65], v[68:69] op_sel_hi:[1,0]
	v_mad_i64_i32 v[66:67], s[6:7], v66, s86, v[142:143]
	v_mul_f32_e32 v64, 0xbfb8aa3b, v62
	v_mul_f32_e32 v65, 0xbfb8aa3b, v63
	v_exp_f32_e32 v64, v64
	v_exp_f32_e32 v65, v65
	v_lshl_add_u64 v[66:67], v[66:67], 0, v[144:145]
	v_add_f32_e32 v64, 1.0, v64
	v_add_f32_e32 v65, 1.0, v65
	v_rcp_f32_e32 v64, v64
	v_rcp_f32_e32 v65, v65
	s_nop 0
	v_pk_mul_f32 v[62:63], v[62:63], v[64:65]
	v_pk_mul_f32 v[60:61], v[60:61], v[62:63]
	v_mul_f32_e32 v62, 0xbfb8aa3b, v54
	v_mul_f32_e32 v63, 0xbfb8aa3b, v55
	v_exp_f32_e32 v62, v62
	v_exp_f32_e32 v63, v63
	v_add_f32_e32 v62, 1.0, v62
	v_add_f32_e32 v63, 1.0, v63
	v_rcp_f32_e32 v62, v62
	v_rcp_f32_e32 v63, v63
	s_nop 0
	v_pk_mul_f32 v[54:55], v[54:55], v[62:63]
	v_pk_mul_f32 v[54:55], v[50:51], v[54:55]
	v_pk_mul_f32 v[50:51], v[56:57], v[68:69] op_sel_hi:[1,0]
	v_mul_f32_e32 v56, 0xbfb8aa3b, v50
	v_mul_f32_e32 v57, 0xbfb8aa3b, v51
	v_exp_f32_e32 v56, v56
	v_exp_f32_e32 v57, v57
	v_add_f32_e32 v56, 1.0, v56
	v_add_f32_e32 v57, 1.0, v57
	v_rcp_f32_e32 v56, v56
	v_rcp_f32_e32 v57, v57
	s_nop 0
	v_pk_mul_f32 v[50:51], v[50:51], v[56:57]
	v_pk_mul_f32 v[56:57], v[52:53], v[50:51]
	v_cvt_pk_bf16_f32 v50, v58, v59
	v_cvt_pk_bf16_f32 v51, v60, v61
	v_cvt_pk_bf16_f32 v52, v54, v55
	v_cvt_pk_bf16_f32 v53, v56, v57
	global_store_dwordx4 v[66:67], v[50:53], off
	s_nop 1
	v_mov_b32_e32 v52, v69
	v_pk_mul_f32 v[46:47], v[46:47], v[52:53] op_sel_hi:[1,0]
	v_add_u32_e32 v50, 0x90, v154
	v_mul_f32_e32 v53, 0xbfb8aa3b, v46
	v_exp_f32_e32 v53, v53
	v_mad_i64_i32 v[50:51], s[6:7], v50, s86, v[142:143]
	v_lshl_add_u64 v[50:51], v[50:51], 0, v[144:145]
	v_add_f32_e32 v53, 1.0, v53
	v_rcp_f32_e32 v54, v53
	v_pk_mul_f32 v[42:43], v[42:43], v[52:53] op_sel_hi:[1,0]
	v_mul_f32_e32 v53, 0xbfb8aa3b, v47
	v_exp_f32_e32 v53, v53
	s_nop 0
	v_add_f32_e32 v53, 1.0, v53
	v_rcp_f32_e32 v55, v53
	v_pk_mul_f32 v[44:45], v[44:45], v[52:53] op_sel_hi:[1,0]
	v_pk_mul_f32 v[38:39], v[38:39], v[52:53] op_sel_hi:[1,0]
	v_pk_mul_f32 v[34:35], v[34:35], v[52:53] op_sel_hi:[1,0]
	v_pk_mul_f32 v[46:47], v[46:47], v[54:55]
	v_pk_mul_f32 v[36:37], v[36:37], v[52:53] op_sel_hi:[1,0]
	v_pk_mul_f32 v[42:43], v[42:43], v[46:47]
	v_pk_mul_f32 v[46:47], v[48:49], v[52:53] op_sel_hi:[1,0]
	v_mul_f32_e32 v48, 0xbfb8aa3b, v46
	v_mul_f32_e32 v49, 0xbfb8aa3b, v47
	v_exp_f32_e32 v48, v48
	v_exp_f32_e32 v49, v49
	v_add_f32_e32 v48, 1.0, v48
	v_add_f32_e32 v49, 1.0, v49
	v_rcp_f32_e32 v48, v48
	v_rcp_f32_e32 v49, v49
	s_nop 0
	v_pk_mul_f32 v[46:47], v[46:47], v[48:49]
	v_pk_mul_f32 v[44:45], v[44:45], v[46:47]
	v_mul_f32_e32 v46, 0xbfb8aa3b, v38
	v_mul_f32_e32 v47, 0xbfb8aa3b, v39
	v_exp_f32_e32 v46, v46
	v_exp_f32_e32 v47, v47
	v_add_f32_e32 v46, 1.0, v46
	v_add_f32_e32 v47, 1.0, v47
	v_rcp_f32_e32 v46, v46
	v_rcp_f32_e32 v47, v47
	s_nop 0
	v_pk_mul_f32 v[38:39], v[38:39], v[46:47]
	v_pk_mul_f32 v[38:39], v[34:35], v[38:39]
	v_pk_mul_f32 v[34:35], v[40:41], v[52:53] op_sel_hi:[1,0]
	v_mul_f32_e32 v40, 0xbfb8aa3b, v34
	v_mul_f32_e32 v41, 0xbfb8aa3b, v35
	v_exp_f32_e32 v40, v40
	v_exp_f32_e32 v41, v41
	v_add_f32_e32 v40, 1.0, v40
	v_add_f32_e32 v41, 1.0, v41
	v_rcp_f32_e32 v40, v40
	v_rcp_f32_e32 v41, v41
	s_nop 0
	v_pk_mul_f32 v[34:35], v[34:35], v[40:41]
	v_pk_mul_f32 v[40:41], v[36:37], v[34:35]
	v_cvt_pk_bf16_f32 v34, v42, v43
	v_cvt_pk_bf16_f32 v35, v44, v45
	v_cvt_pk_bf16_f32 v36, v38, v39
	v_cvt_pk_bf16_f32 v37, v40, v41
	global_store_dwordx4 v[50:51], v[34:37], off
	ds_read2_b32 v[36:37], v155 offset0:160 offset1:176
	s_waitcnt lgkmcnt(0)
	v_pk_mul_f32 v[30:31], v[30:31], v[36:37] op_sel_hi:[1,0]
	v_mul_f32_e32 v38, 0xbfb8aa3b, v30
	v_mul_f32_e32 v39, 0xbfb8aa3b, v31
	v_exp_f32_e32 v38, v38
	v_exp_f32_e32 v39, v39
	v_pk_mul_f32 v[26:27], v[26:27], v[36:37] op_sel_hi:[1,0]
	v_pk_mul_f32 v[28:29], v[28:29], v[36:37] op_sel_hi:[1,0]
	v_add_f32_e32 v38, 1.0, v38
	v_add_f32_e32 v39, 1.0, v39
	v_rcp_f32_e32 v38, v38
	v_rcp_f32_e32 v39, v39
	v_pk_mul_f32 v[22:23], v[22:23], v[36:37] op_sel_hi:[1,0]
	v_pk_mul_f32 v[18:19], v[18:19], v[36:37] op_sel_hi:[1,0]
	v_add_u32_e32 v34, 0xa0, v154
	v_pk_mul_f32 v[30:31], v[30:31], v[38:39]
	v_pk_mul_f32 v[20:21], v[20:21], v[36:37] op_sel_hi:[1,0]
	v_pk_mul_f32 v[26:27], v[26:27], v[30:31]
	v_pk_mul_f32 v[30:31], v[32:33], v[36:37] op_sel_hi:[1,0]
	v_mad_i64_i32 v[34:35], s[6:7], v34, s86, v[142:143]
	v_mul_f32_e32 v32, 0xbfb8aa3b, v30
	v_mul_f32_e32 v33, 0xbfb8aa3b, v31
	v_exp_f32_e32 v32, v32
	v_exp_f32_e32 v33, v33
	v_lshl_add_u64 v[34:35], v[34:35], 0, v[144:145]
	v_add_f32_e32 v32, 1.0, v32
	v_add_f32_e32 v33, 1.0, v33
	v_rcp_f32_e32 v32, v32
	v_rcp_f32_e32 v33, v33
	s_nop 0
	v_pk_mul_f32 v[30:31], v[30:31], v[32:33]
	v_pk_mul_f32 v[28:29], v[28:29], v[30:31]
	v_mul_f32_e32 v30, 0xbfb8aa3b, v22
	v_mul_f32_e32 v31, 0xbfb8aa3b, v23
	v_exp_f32_e32 v30, v30
	v_exp_f32_e32 v31, v31
	v_add_f32_e32 v30, 1.0, v30
	v_add_f32_e32 v31, 1.0, v31
	v_rcp_f32_e32 v30, v30
	v_rcp_f32_e32 v31, v31
	s_nop 0
	v_pk_mul_f32 v[22:23], v[22:23], v[30:31]
	v_pk_mul_f32 v[22:23], v[18:19], v[22:23]
	v_pk_mul_f32 v[18:19], v[24:25], v[36:37] op_sel_hi:[1,0]
	v_mul_f32_e32 v24, 0xbfb8aa3b, v18
	v_mul_f32_e32 v25, 0xbfb8aa3b, v19
	v_exp_f32_e32 v24, v24
	v_exp_f32_e32 v25, v25
	v_add_f32_e32 v24, 1.0, v24
	v_add_f32_e32 v25, 1.0, v25
	v_rcp_f32_e32 v24, v24
	v_rcp_f32_e32 v25, v25
	s_nop 0
	v_pk_mul_f32 v[18:19], v[18:19], v[24:25]
	v_pk_mul_f32 v[24:25], v[20:21], v[18:19]
	v_cvt_pk_bf16_f32 v18, v26, v27
	v_cvt_pk_bf16_f32 v19, v28, v29
	v_cvt_pk_bf16_f32 v20, v22, v23
	v_cvt_pk_bf16_f32 v21, v24, v25
	global_store_dwordx4 v[34:35], v[18:21], off
	s_nop 1
	v_mov_b32_e32 v20, v37
	v_pk_mul_f32 v[14:15], v[14:15], v[20:21] op_sel_hi:[1,0]
	v_add_u32_e32 v18, 0xb0, v154
	v_mul_f32_e32 v21, 0xbfb8aa3b, v14
	v_exp_f32_e32 v21, v21
	v_mad_i64_i32 v[18:19], s[6:7], v18, s86, v[142:143]
	v_lshl_add_u64 v[18:19], v[18:19], 0, v[144:145]
	v_add_f32_e32 v21, 1.0, v21
	v_rcp_f32_e32 v22, v21
	v_pk_mul_f32 v[10:11], v[10:11], v[20:21] op_sel_hi:[1,0]
	v_mul_f32_e32 v21, 0xbfb8aa3b, v15
	v_exp_f32_e32 v21, v21
	s_nop 0
	v_add_f32_e32 v21, 1.0, v21
	v_rcp_f32_e32 v23, v21
	v_pk_mul_f32 v[12:13], v[12:13], v[20:21] op_sel_hi:[1,0]
	v_pk_mul_f32 v[6:7], v[6:7], v[20:21] op_sel_hi:[1,0]
	v_pk_mul_f32 v[2:3], v[2:3], v[20:21] op_sel_hi:[1,0]
	v_pk_mul_f32 v[14:15], v[14:15], v[22:23]
	v_pk_mul_f32 v[4:5], v[4:5], v[20:21] op_sel_hi:[1,0]
	v_pk_mul_f32 v[10:11], v[10:11], v[14:15]
	v_pk_mul_f32 v[14:15], v[16:17], v[20:21] op_sel_hi:[1,0]
	v_mul_f32_e32 v16, 0xbfb8aa3b, v14
	v_mul_f32_e32 v17, 0xbfb8aa3b, v15
	v_exp_f32_e32 v16, v16
	v_exp_f32_e32 v17, v17
	v_add_f32_e32 v16, 1.0, v16
	v_add_f32_e32 v17, 1.0, v17
	v_rcp_f32_e32 v16, v16
	v_rcp_f32_e32 v17, v17
	s_nop 0
	v_pk_mul_f32 v[14:15], v[14:15], v[16:17]
	v_pk_mul_f32 v[12:13], v[12:13], v[14:15]
	v_mul_f32_e32 v14, 0xbfb8aa3b, v6
	v_mul_f32_e32 v15, 0xbfb8aa3b, v7
	v_exp_f32_e32 v14, v14
	v_exp_f32_e32 v15, v15
	v_add_f32_e32 v14, 1.0, v14
	v_add_f32_e32 v15, 1.0, v15
	v_rcp_f32_e32 v14, v14
	v_rcp_f32_e32 v15, v15
	s_nop 0
	v_pk_mul_f32 v[6:7], v[6:7], v[14:15]
	v_pk_mul_f32 v[6:7], v[2:3], v[6:7]
	v_pk_mul_f32 v[2:3], v[8:9], v[20:21] op_sel_hi:[1,0]
	v_mul_f32_e32 v8, 0xbfb8aa3b, v2
	v_mul_f32_e32 v9, 0xbfb8aa3b, v3
	v_exp_f32_e32 v8, v8
	v_exp_f32_e32 v9, v9
	v_add_f32_e32 v8, 1.0, v8
	v_add_f32_e32 v9, 1.0, v9
	v_rcp_f32_e32 v8, v8
	v_rcp_f32_e32 v9, v9
	s_nop 0
	v_pk_mul_f32 v[2:3], v[2:3], v[8:9]
	v_pk_mul_f32 v[8:9], v[4:5], v[2:3]
	v_cvt_pk_bf16_f32 v2, v10, v11
	v_cvt_pk_bf16_f32 v3, v12, v13
	v_cvt_pk_bf16_f32 v4, v6, v7
	v_cvt_pk_bf16_f32 v5, v8, v9
	global_store_dwordx4 v[18:19], v[2:5], off
	s_cbranch_vccnz .LBB0_46
	s_andn2_b64 vcc, exec, s[44:45]
	s_cbranch_vccnz .LBB0_45
	s_barrier
	s_branch .LBB0_45

.LBB0_103:
	v_mov_b32_e32 v28, v242
	s_and_b32 s42, s40, 0xfffff000
	v_readfirstlane_b32 s7, v28
	s_ashr_i32 s6, s7, 6
	s_add_i32 s8, s34, s45
	s_cmpk_lt_i32 s8, 0x800
	s_cselect_b32 s8, s8, s45
	s_lshl_b32 s9, s8, 4
	s_lshl_b32 s10, s8, 6
	s_and_b32 s9, s9, 0xfffff000
	s_and_b32 s10, s10, 0xfc0
	s_or_b32 s43, s9, s10
	s_ashr_i32 s9, s8, 31
	s_lshl_b64 s[10:11], s[8:9], 14
	v_lshl_add_u64 v[6:7], v[36:37], 0, s[10:11]
	s_add_i32 s10, s43, s5
	s_mul_i32 s11, s10, 0x1800
	s_mul_hi_i32 s9, s10, 0x1800
	s_add_u32 s11, s80, s11
	s_addc_u32 s9, s81, s9
	s_lshl_b32 s8, s8, 2
	s_and_b32 s43, s8, 0x300
	s_add_u32 s8, s11, s43
	s_addc_u32 s9, s9, 0
	v_lshl_add_u64 v[26:27], s[8:9], 0, v[130:131]
	s_or_b32 s8, s10, 1
	s_mul_hi_i32 s9, s8, 0x1800
	s_mulk_i32 s8, 0x1800
	s_add_u32 s8, s80, s8
	s_addc_u32 s9, s81, s9
	v_add_co_u32_e32 v26, vcc, s90, v26
	s_add_u32 s8, s8, s43
	s_nop 0
	v_addc_co_u32_e32 v27, vcc, 0, v27, vcc
	s_addc_u32 s9, s9, 0
	s_waitcnt vmcnt(0)
	v_mov_b32_e32 v60, v44
	global_load_dwordx4 v[2:5], v[6:7], off
	s_nop 0
	global_load_dwordx4 v[6:9], v[6:7], off offset:1024
	v_mov_b32_e32 v59, v43
	global_load_dword v44, v[26:27], off offset:1024
	v_lshl_add_u64 v[26:27], s[8:9], 0, v[130:131]
	s_or_b32 s8, s10, 2
	s_mul_hi_i32 s9, s8, 0x1800
	s_mulk_i32 s8, 0x1800
	s_add_u32 s8, s80, s8
	s_addc_u32 s9, s81, s9
	v_add_co_u32_e32 v26, vcc, s90, v26
	s_add_u32 s8, s8, s43
	s_nop 0
	v_addc_co_u32_e32 v27, vcc, 0, v27, vcc
	s_addc_u32 s9, s9, 0
	global_load_dword v43, v[26:27], off offset:1024
	v_lshl_add_u64 v[26:27], s[8:9], 0, v[130:131]
	s_or_b32 s8, s10, 3
	s_mul_hi_i32 s9, s8, 0x1800
	s_mulk_i32 s8, 0x1800
	s_add_u32 s8, s80, s8
	s_addc_u32 s9, s81, s9
	v_add_co_u32_e32 v26, vcc, s90, v26
	s_add_u32 s8, s8, s43
	s_nop 0
	v_addc_co_u32_e32 v27, vcc, 0, v27, vcc
	s_addc_u32 s9, s9, 0
	v_mov_b32_e32 v58, v42
	global_load_dword v42, v[26:27], off offset:1024
	v_lshl_add_u64 v[26:27], s[8:9], 0, v[130:131]
	s_or_b32 s8, s10, 4
	s_mul_hi_i32 s9, s8, 0x1800
	s_mulk_i32 s8, 0x1800
	s_add_u32 s8, s80, s8
	s_addc_u32 s9, s81, s9
	v_add_co_u32_e32 v26, vcc, s90, v26
	s_add_u32 s8, s8, s43
	s_nop 0
	v_addc_co_u32_e32 v27, vcc, 0, v27, vcc
	s_addc_u32 s9, s9, 0
	v_mov_b32_e32 v57, v41
	global_load_dword v41, v[26:27], off offset:1024
	v_lshl_add_u64 v[26:27], s[8:9], 0, v[130:131]
	s_or_b32 s8, s10, 5
	s_mul_hi_i32 s9, s8, 0x1800
	s_mulk_i32 s8, 0x1800
	s_add_u32 s8, s80, s8
	s_addc_u32 s9, s81, s9
	v_add_co_u32_e32 v26, vcc, s90, v26
	s_add_u32 s8, s8, s43
	s_nop 0
	v_addc_co_u32_e32 v27, vcc, 0, v27, vcc
	s_addc_u32 s9, s9, 0
	v_mov_b32_e32 v56, v40
	global_load_dword v40, v[26:27], off offset:1024
	v_lshl_add_u64 v[26:27], s[8:9], 0, v[130:131]
	s_or_b32 s8, s10, 6
	s_mul_hi_i32 s9, s8, 0x1800
	s_mulk_i32 s8, 0x1800
	s_add_u32 s8, s80, s8
	s_addc_u32 s9, s81, s9
	v_add_co_u32_e32 v26, vcc, s90, v26
	s_add_u32 s8, s8, s43
	s_nop 0
	v_addc_co_u32_e32 v27, vcc, 0, v27, vcc
	s_addc_u32 s9, s9, 0
	v_mov_b32_e32 v55, v39
	global_load_dword v39, v[26:27], off offset:1024
	v_lshl_add_u64 v[26:27], s[8:9], 0, v[130:131]
	s_or_b32 s8, s10, 7
	s_mul_hi_i32 s9, s8, 0x1800
	s_mulk_i32 s8, 0x1800
	s_add_u32 s8, s80, s8
	s_addc_u32 s9, s81, s9
	v_add_co_u32_e32 v26, vcc, s90, v26
	s_add_u32 s8, s8, s43
	s_nop 0
	v_addc_co_u32_e32 v27, vcc, 0, v27, vcc
	s_addc_u32 s9, s9, 0
	v_mov_b32_e32 v54, v38
	global_load_dword v38, v[26:27], off offset:1024
	v_lshl_add_u64 v[26:27], s[8:9], 0, v[130:131]
	v_add_co_u32_e32 v26, vcc, s90, v26
	v_mov_b32_e32 v53, v1
	s_nop 0
	v_addc_co_u32_e32 v27, vcc, 0, v27, vcc
	global_load_dword v1, v[26:27], off offset:1024
	v_lshrrev_b32_e32 v27, 3, v28
	s_lshl_b32 s8, s6, 5
	v_and_b32_e32 v27, 4, v27
	v_and_b32_e32 v26, 31, v28
	v_and_or_b32 v27, s8, 32, v27
	s_and_b32 s7, s7, 0xffffff80
	s_add_i32 s7, s7, 0
	v_lshlrev_b32_e32 v26, 2, v26
	v_mul_u32_u24_e32 v27, 0x210, v27
	v_and_b32_e32 v61, 63, v28
	v_lshlrev_b32_e32 v28, 16, v22
	v_add3_u32 v26, s7, v26, v27
	v_and_b32_e32 v22, 0xffff0000, v22
	ds_write2_b32 v26, v28, v22 offset1:132
	v_lshlrev_b32_e32 v22, 16, v23
	v_and_b32_e32 v23, 0xffff0000, v23
	v_add_u32_e32 v27, 0x400, v26
	ds_write2_b32 v27, v22, v23 offset0:8 offset1:140
	v_lshlrev_b32_e32 v22, 16, v24
	v_and_b32_e32 v23, 0xffff0000, v24
	v_add_u32_e32 v24, 0x1000, v26
	ds_write2_b32 v24, v22, v23 offset0:32 offset1:164
	v_lshlrev_b32_e32 v22, 16, v25
	v_and_b32_e32 v23, 0xffff0000, v25
	v_add_u32_e32 v24, 0x1400, v26
	ds_write2_b32 v24, v22, v23 offset0:40 offset1:172
	v_lshlrev_b32_e32 v22, 16, v18
	v_and_b32_e32 v18, 0xffff0000, v18
	v_add_u32_e32 v23, 0x2000, v26
	ds_write2_b32 v23, v22, v18 offset0:64 offset1:196
	v_lshlrev_b32_e32 v18, 16, v19
	v_and_b32_e32 v19, 0xffff0000, v19
	v_add_u32_e32 v22, 0x2400, v26
	ds_write2_b32 v22, v18, v19 offset0:72 offset1:204
	v_lshlrev_b32_e32 v18, 16, v20
	v_and_b32_e32 v19, 0xffff0000, v20
	v_add_u32_e32 v20, 0x3000, v26
	s_lshl_b32 s43, s6, 3
	s_mulk_i32 s6, 0x1080
	ds_write2_b32 v20, v18, v19 offset0:96 offset1:228
	v_lshlrev_b32_e32 v18, 16, v21
	v_and_b32_e32 v19, 0xffff0000, v21
	v_add_u32_e32 v20, 0x3400, v26
	s_add_i32 s6, s6, 0
	ds_write2_b32 v20, v18, v19 offset0:104 offset1:236
	v_lshl_add_u32 v20, v61, 3, s6
	s_waitcnt lgkmcnt(0)
	s_barrier
	ds_read2_b64 v[30:33], v20 offset1:66
	ds_read2_b64 v[26:29], v20 offset0:132 offset1:198
	v_add_u32_e32 v20, 0x800, v20
	ds_read2_b64 v[22:25], v20 offset0:8 offset1:74
	s_and_b32 s8, s41, 0xfc0
	s_waitcnt lgkmcnt(2)
	v_pk_mul_f32 v[18:19], v[30:31], v[30:31]
	s_or_b32 s8, s42, s8
	v_add_f32_e32 v64, v18, v19
	v_pk_mul_f32 v[18:19], v[32:33], v[32:33]
	s_add_i32 s42, s43, s8
	v_add_f32_e32 v65, v18, v19
	s_waitcnt lgkmcnt(1)
	v_pk_mul_f32 v[18:19], v[26:27], v[26:27]
	s_ashr_i32 s43, s42, 31
	v_add_f32_e32 v66, v18, v19
	v_pk_mul_f32 v[18:19], v[28:29], v[28:29]
	s_and_b32 s11, s44, 0x180
	v_add_f32_e32 v67, v18, v19
	s_waitcnt lgkmcnt(0)
	v_pk_mul_f32 v[18:19], v[22:23], v[22:23]
	s_lshl_b64 s[8:9], s[42:43], 11
	v_add_f32_e32 v68, v18, v19
	v_pk_mul_f32 v[18:19], v[24:25], v[24:25]
	s_add_u32 s8, s76, s8
	v_add_f32_e32 v69, v18, v19
	ds_read2_b64 v[18:21], v20 offset0:140 offset1:206
	s_addc_u32 s9, s77, s9
	s_waitcnt lgkmcnt(0)
	v_pk_mul_f32 v[62:63], v[18:19], v[18:19]
	v_add_f32_e32 v70, v62, v63
	v_pk_mul_f32 v[62:63], v[20:21], v[20:21]
	v_add_f32_e32 v62, v62, v63
	v_add_f32_dpp v63, v64, v64 quad_perm:[1,0,3,2] row_mask:0xf bank_mask:0xf bound_ctrl:1
	v_add_f32_dpp v64, v65, v65 quad_perm:[1,0,3,2] row_mask:0xf bank_mask:0xf bound_ctrl:1
	v_add_f32_dpp v65, v66, v66 quad_perm:[1,0,3,2] row_mask:0xf bank_mask:0xf bound_ctrl:1
	v_add_f32_dpp v63, v63, v63 quad_perm:[2,3,0,1] row_mask:0xf bank_mask:0xf bound_ctrl:1
	v_add_f32_dpp v66, v67, v67 quad_perm:[1,0,3,2] row_mask:0xf bank_mask:0xf bound_ctrl:1
	v_add_f32_dpp v67, v68, v68 quad_perm:[1,0,3,2] row_mask:0xf bank_mask:0xf bound_ctrl:1
	v_add_f32_dpp v63, v63, v63 row_half_mirror row_mask:0xf bank_mask:0xf bound_ctrl:1
	v_add_f32_dpp v68, v69, v69 quad_perm:[1,0,3,2] row_mask:0xf bank_mask:0xf bound_ctrl:1
	v_add_f32_dpp v69, v70, v70 quad_perm:[1,0,3,2] row_mask:0xf bank_mask:0xf bound_ctrl:1
	v_add_f32_dpp v64, v64, v64 quad_perm:[2,3,0,1] row_mask:0xf bank_mask:0xf bound_ctrl:1
	v_add_f32_dpp v63, v63, v63 row_mirror row_mask:0xf bank_mask:0xf bound_ctrl:1
	v_mov_b32_e32 v70, v131
	v_add_f32_dpp v64, v64, v64 row_half_mirror row_mask:0xf bank_mask:0xf bound_ctrl:1
	v_add_f32_dpp v65, v65, v65 quad_perm:[2,3,0,1] row_mask:0xf bank_mask:0xf bound_ctrl:1
	v_mov_b32_dpp v70, v63 row_bcast:15 row_mask:0xa bank_mask:0xf
	v_add_f32_dpp v64, v64, v64 row_mirror row_mask:0xf bank_mask:0xf bound_ctrl:1
	v_add_f32_e32 v63, v63, v70
	v_mov_b32_e32 v70, v131
	v_add_f32_dpp v65, v65, v65 row_half_mirror row_mask:0xf bank_mask:0xf bound_ctrl:1
	v_add_f32_dpp v66, v66, v66 quad_perm:[2,3,0,1] row_mask:0xf bank_mask:0xf bound_ctrl:1
	v_mov_b32_dpp v70, v64 row_bcast:15 row_mask:0xa bank_mask:0xf
	v_add_f32_dpp v65, v65, v65 row_mirror row_mask:0xf bank_mask:0xf bound_ctrl:1
	v_add_f32_e32 v64, v64, v70
	v_mov_b32_e32 v70, v131
	v_add_f32_dpp v66, v66, v66 row_half_mirror row_mask:0xf bank_mask:0xf bound_ctrl:1
	v_add_f32_dpp v67, v67, v67 quad_perm:[2,3,0,1] row_mask:0xf bank_mask:0xf bound_ctrl:1
	v_mov_b32_dpp v70, v65 row_bcast:15 row_mask:0xa bank_mask:0xf
	v_add_f32_dpp v66, v66, v66 row_mirror row_mask:0xf bank_mask:0xf bound_ctrl:1
	v_add_f32_e32 v65, v65, v70
	v_mov_b32_e32 v70, v131
	v_add_f32_dpp v67, v67, v67 row_half_mirror row_mask:0xf bank_mask:0xf bound_ctrl:1
	v_add_f32_dpp v68, v68, v68 quad_perm:[2,3,0,1] row_mask:0xf bank_mask:0xf bound_ctrl:1
	v_mov_b32_dpp v70, v66 row_bcast:15 row_mask:0xa bank_mask:0xf
	v_add_f32_dpp v67, v67, v67 row_mirror row_mask:0xf bank_mask:0xf bound_ctrl:1
	v_add_f32_e32 v66, v66, v70
	v_mov_b32_e32 v70, v131
	v_add_f32_dpp v68, v68, v68 row_half_mirror row_mask:0xf bank_mask:0xf bound_ctrl:1
	v_add_f32_dpp v69, v69, v69 quad_perm:[2,3,0,1] row_mask:0xf bank_mask:0xf bound_ctrl:1
	v_mov_b32_dpp v70, v67 row_bcast:15 row_mask:0xa bank_mask:0xf
	v_add_f32_dpp v68, v68, v68 row_mirror row_mask:0xf bank_mask:0xf bound_ctrl:1
	v_add_f32_e32 v67, v67, v70
	v_mov_b32_e32 v70, v131
	v_add_f32_dpp v62, v62, v62 quad_perm:[1,0,3,2] row_mask:0xf bank_mask:0xf bound_ctrl:1
	v_add_f32_dpp v69, v69, v69 row_half_mirror row_mask:0xf bank_mask:0xf bound_ctrl:1
	v_mov_b32_dpp v70, v68 row_bcast:15 row_mask:0xa bank_mask:0xf
	v_add_f32_dpp v62, v62, v62 quad_perm:[2,3,0,1] row_mask:0xf bank_mask:0xf bound_ctrl:1
	v_add_f32_dpp v69, v69, v69 row_mirror row_mask:0xf bank_mask:0xf bound_ctrl:1
	v_add_f32_e32 v68, v68, v70
	v_mov_b32_e32 v70, v131
	v_add_f32_dpp v62, v62, v62 row_half_mirror row_mask:0xf bank_mask:0xf bound_ctrl:1
	s_nop 0
	v_mov_b32_dpp v70, v69 row_bcast:15 row_mask:0xa bank_mask:0xf
	v_add_f32_dpp v62, v62, v62 row_mirror row_mask:0xf bank_mask:0xf bound_ctrl:1
	v_add_f32_e32 v69, v69, v70
	v_mov_b32_e32 v70, v131
	s_nop 1
	v_mov_b32_dpp v70, v62 row_bcast:15 row_mask:0xa bank_mask:0xf
	v_add_f32_e32 v62, v62, v70
	v_mov_b32_e32 v70, v131
	s_nop 1
	v_mov_b32_dpp v70, v63 row_bcast:31 row_mask:0xc bank_mask:0xf
	v_add_f32_e32 v63, v63, v70
	v_mov_b32_e32 v70, v131
	v_readlane_b32 s6, v63, 63
	s_nop 0
	v_mov_b32_dpp v70, v64 row_bcast:31 row_mask:0xc bank_mask:0xf
	v_add_f32_e32 v64, v64, v70
	v_mov_b32_e32 v70, v131
	v_readlane_b32 s10, v64, 63
	v_lshlrev_b32_e32 v64, 16, v52
	v_mov_b32_dpp v70, v65 row_bcast:31 row_mask:0xc bank_mask:0xf
	v_add_f32_e32 v65, v65, v70
	v_mov_b32_e32 v70, v131
	v_readlane_b32 s50, v65, 63
	v_and_b32_e32 v65, 0xffff0000, v52
	v_mov_b32_dpp v70, v66 row_bcast:31 row_mask:0xc bank_mask:0xf
	v_mul_f32_e32 v52, 0xbfb8aa3b, v64
	v_add_f32_e32 v66, v66, v70
	v_mov_b32_e32 v70, v131
	v_exp_f32_e32 v52, v52
	v_readlane_b32 s49, v66, 63
	v_mov_b32_dpp v70, v67 row_bcast:31 row_mask:0xc bank_mask:0xf
	v_add_f32_e32 v67, v67, v70
	v_mov_b32_e32 v70, v131
	v_add_f32_e32 v52, 1.0, v52
	v_rcp_f32_e32 v66, v52
	v_mov_b32_dpp v70, v68 row_bcast:31 row_mask:0xc bank_mask:0xf
	v_add_f32_e32 v68, v68, v70
	v_mov_b32_e32 v70, v131
	v_mul_f32_e32 v52, 0xbfb8aa3b, v65
	v_exp_f32_e32 v52, v52
	v_mov_b32_dpp v70, v69 row_bcast:31 row_mask:0xc bank_mask:0xf
	v_add_f32_e32 v69, v69, v70
	v_mov_b32_e32 v70, v131
	v_add_f32_e32 v52, 1.0, v52
	v_readlane_b32 s48, v67, 63
	v_mov_b32_dpp v70, v62 row_bcast:31 row_mask:0xc bank_mask:0xf
	v_add_f32_e32 v62, v62, v70
	v_rcp_f32_e32 v67, v52
	v_readlane_b32 s7, v62, 63
	v_fma_f32 v62, s6, v233, v225
	v_rsq_f32_e32 v62, v62
	s_lshl_b32 s6, s11, 1
	s_add_u32 s8, s8, s6
	s_addc_u32 s9, s9, 0
	v_pk_mul_f32 v[30:31], v[30:31], v[62:63] op_sel_hi:[1,0]
	v_pk_mul_f32 v[62:63], v[66:67], v[64:65]
	v_pk_mul_f32 v[30:31], v[34:35], v[30:31]
	v_readlane_b32 s47, v68, 63
	v_pk_mul_f32 v[30:31], v[62:63], v[30:31]
	v_lshlrev_b32_e32 v62, 16, v51
	v_cvt_pk_bf16_f32 v31, v30, v31
	v_lshlrev_b32_e32 v30, 2, v61
	global_store_dword v30, v31, s[8:9] offset:1024
	v_fma_f32 v31, s10, v233, v225
	v_rsq_f32_e32 v52, v31
	v_mul_f32_e32 v31, 0xbfb8aa3b, v62
	v_exp_f32_e32 v31, v31
	v_and_b32_e32 v63, 0xffff0000, v51
	s_or_b32 s8, s42, 1
	s_ashr_i32 s9, s8, 31
	v_add_f32_e32 v31, 1.0, v31
	v_rcp_f32_e32 v64, v31
	v_mul_f32_e32 v31, 0xbfb8aa3b, v63
	v_exp_f32_e32 v31, v31
	s_lshl_b64 s[8:9], s[8:9], 11
	v_pk_mul_f32 v[32:33], v[32:33], v[52:53] op_sel_hi:[1,0]
	s_add_u32 s8, s76, s8
	v_add_f32_e32 v31, 1.0, v31
	v_rcp_f32_e32 v65, v31
	v_pk_mul_f32 v[32:33], v[34:35], v[32:33]
	s_addc_u32 s9, s77, s9
	s_add_u32 s8, s8, s6
	v_pk_mul_f32 v[62:63], v[64:65], v[62:63]
	s_addc_u32 s9, s9, 0
	v_pk_mul_f32 v[32:33], v[62:63], v[32:33]
	v_lshlrev_b32_e32 v62, 16, v50
	v_cvt_pk_bf16_f32 v31, v32, v33
	global_store_dword v30, v31, s[8:9] offset:1024
	v_fma_f32 v31, s50, v233, v225
	v_rsq_f32_e32 v32, v31
	v_mul_f32_e32 v31, 0xbfb8aa3b, v62
	v_exp_f32_e32 v31, v31
	v_and_b32_e32 v63, 0xffff0000, v50
	s_or_b32 s8, s42, 2
	s_ashr_i32 s9, s8, 31
	v_add_f32_e32 v31, 1.0, v31
	v_rcp_f32_e32 v50, v31
	v_mul_f32_e32 v31, 0xbfb8aa3b, v63
	v_exp_f32_e32 v31, v31
	v_pk_mul_f32 v[26:27], v[26:27], v[32:33] op_sel_hi:[1,0]
	s_lshl_b64 s[8:9], s[8:9], 11
	v_pk_mul_f32 v[26:27], v[34:35], v[26:27]
	v_add_f32_e32 v31, 1.0, v31
	v_rcp_f32_e32 v51, v31
	s_add_u32 s8, s76, s8
	s_addc_u32 s9, s77, s9
	s_add_u32 s8, s8, s6
	v_pk_mul_f32 v[32:33], v[50:51], v[62:63]
	s_addc_u32 s9, s9, 0
	v_pk_mul_f32 v[26:27], v[32:33], v[26:27]
	v_lshlrev_b32_e32 v32, 16, v49
	v_cvt_pk_bf16_f32 v26, v26, v27
	v_mul_f32_e32 v27, 0xbfb8aa3b, v32
	v_exp_f32_e32 v27, v27
	global_store_dword v30, v26, s[8:9] offset:1024
	v_fma_f32 v26, s49, v233, v225
	v_rsq_f32_e32 v26, v26
	v_add_f32_e32 v27, 1.0, v27
	v_and_b32_e32 v33, 0xffff0000, v49
	v_rcp_f32_e32 v50, v27
	s_or_b32 s8, s42, 3
	v_pk_mul_f32 v[26:27], v[28:29], v[26:27] op_sel_hi:[1,0]
	v_mul_f32_e32 v28, 0xbfb8aa3b, v33
	v_exp_f32_e32 v28, v28
	s_ashr_i32 s9, s8, 31
	s_lshl_b64 s[8:9], s[8:9], 11
	s_add_u32 s8, s76, s8
	v_add_f32_e32 v28, 1.0, v28
	v_rcp_f32_e32 v51, v28
	v_pk_mul_f32 v[26:27], v[34:35], v[26:27]
	s_addc_u32 s9, s77, s9
	s_add_u32 s8, s8, s6
	v_pk_mul_f32 v[28:29], v[50:51], v[32:33]
	s_addc_u32 s9, s9, 0
	v_pk_mul_f32 v[26:27], v[28:29], v[26:27]
	v_lshlrev_b32_e32 v28, 16, v48
	v_cvt_pk_bf16_f32 v26, v26, v27
	v_mul_f32_e32 v27, 0xbfb8aa3b, v28
	global_store_dword v30, v26, s[8:9] offset:1024
	v_fma_f32 v26, s48, v233, v225
	v_exp_f32_e32 v27, v27
	v_rsq_f32_e32 v26, v26
	v_and_b32_e32 v29, 0xffff0000, v48
	s_or_b32 s8, s42, 4
	v_add_f32_e32 v27, 1.0, v27
	v_rcp_f32_e32 v32, v27
	v_pk_mul_f32 v[22:23], v[22:23], v[26:27] op_sel_hi:[1,0]
	v_mul_f32_e32 v26, 0xbfb8aa3b, v29
	v_exp_f32_e32 v26, v26
	s_ashr_i32 s9, s8, 31
	s_lshl_b64 s[8:9], s[8:9], 11
	v_pk_mul_f32 v[22:23], v[34:35], v[22:23]
	v_add_f32_e32 v26, 1.0, v26
	v_rcp_f32_e32 v33, v26
	s_add_u32 s8, s76, s8
	s_addc_u32 s9, s77, s9
	s_add_u32 s8, s8, s6
	v_pk_mul_f32 v[26:27], v[32:33], v[28:29]
	s_addc_u32 s9, s9, 0
	v_pk_mul_f32 v[22:23], v[26:27], v[22:23]
	v_lshlrev_b32_e32 v26, 16, v47
	v_cvt_pk_bf16_f32 v22, v22, v23
	v_mul_f32_e32 v23, 0xbfb8aa3b, v26
	v_exp_f32_e32 v23, v23
	global_store_dword v30, v22, s[8:9] offset:1024
	v_fma_f32 v22, s47, v233, v225
	v_rsq_f32_e32 v22, v22
	v_add_f32_e32 v23, 1.0, v23
	v_and_b32_e32 v27, 0xffff0000, v47
	v_rcp_f32_e32 v28, v23
	s_or_b32 s8, s42, 5
	v_pk_mul_f32 v[22:23], v[24:25], v[22:23] op_sel_hi:[1,0]
	v_mul_f32_e32 v24, 0xbfb8aa3b, v27
	v_exp_f32_e32 v24, v24
	s_ashr_i32 s9, s8, 31
	s_lshl_b64 s[8:9], s[8:9], 11
	s_add_u32 s8, s76, s8
	v_add_f32_e32 v24, 1.0, v24
	v_rcp_f32_e32 v29, v24
	v_pk_mul_f32 v[22:23], v[34:35], v[22:23]
	s_addc_u32 s9, s77, s9
	s_add_u32 s8, s8, s6
	v_pk_mul_f32 v[24:25], v[28:29], v[26:27]
	v_readlane_b32 s46, v69, 63
	v_pk_mul_f32 v[22:23], v[24:25], v[22:23]
	v_lshlrev_b32_e32 v24, 16, v46
	v_cvt_pk_bf16_f32 v22, v22, v23
	s_addc_u32 s9, s9, 0
	v_mul_f32_e32 v23, 0xbfb8aa3b, v24
	global_store_dword v30, v22, s[8:9] offset:1024
	v_fma_f32 v22, s46, v233, v225
	v_exp_f32_e32 v23, v23
	v_rsq_f32_e32 v22, v22
	v_and_b32_e32 v25, 0xffff0000, v46
	s_or_b32 s8, s42, 6
	v_add_f32_e32 v23, 1.0, v23
	v_rcp_f32_e32 v26, v23
	v_pk_mul_f32 v[18:19], v[18:19], v[22:23] op_sel_hi:[1,0]
	v_mul_f32_e32 v22, 0xbfb8aa3b, v25
	v_exp_f32_e32 v22, v22
	s_ashr_i32 s9, s8, 31
	s_lshl_b64 s[8:9], s[8:9], 11
	v_pk_mul_f32 v[18:19], v[34:35], v[18:19]
	v_add_f32_e32 v22, 1.0, v22
	v_rcp_f32_e32 v27, v22
	s_add_u32 s8, s76, s8
	s_addc_u32 s9, s77, s9
	s_add_u32 s8, s8, s6
	v_pk_mul_f32 v[22:23], v[26:27], v[24:25]
	s_addc_u32 s9, s9, 0
	v_pk_mul_f32 v[18:19], v[22:23], v[18:19]
	v_lshlrev_b32_e32 v22, 16, v45
	v_cvt_pk_bf16_f32 v18, v18, v19
	v_mul_f32_e32 v19, 0xbfb8aa3b, v22
	v_exp_f32_e32 v19, v19
	global_store_dword v30, v18, s[8:9] offset:1024
	v_fma_f32 v18, s7, v233, v225
	v_rsq_f32_e32 v18, v18
	v_add_f32_e32 v19, 1.0, v19
	v_and_b32_e32 v23, 0xffff0000, v45
	v_rcp_f32_e32 v24, v19
	s_or_b32 s8, s42, 7
	v_pk_mul_f32 v[18:19], v[20:21], v[18:19] op_sel_hi:[1,0]
	v_mul_f32_e32 v20, 0xbfb8aa3b, v23
	v_exp_f32_e32 v20, v20
	s_ashr_i32 s9, s8, 31
	s_lshl_b64 s[8:9], s[8:9], 11
	s_add_u32 s7, s76, s8
	v_add_f32_e32 v20, 1.0, v20
	v_rcp_f32_e32 v25, v20
	v_pk_mul_f32 v[18:19], v[34:35], v[18:19]
	s_addc_u32 s8, s77, s9
	s_add_u32 s6, s7, s6
	v_pk_mul_f32 v[20:21], v[24:25], v[22:23]
	s_addc_u32 s7, s8, 0
	v_pk_mul_f32 v[18:19], v[20:21], v[18:19]
	v_mov_b64_e32 v[24:25], v[16:17]
	v_cvt_pk_bf16_f32 v18, v18, v19
	global_store_dword v30, v18, s[6:7] offset:1024
	v_mov_b64_e32 v[20:21], v[12:13]
	s_add_i32 s45, s45, s4
	s_add_i32 s44, s44, s34
	s_add_i32 s41, s41, s28
	s_add_i32 s40, s40, s29
	v_mov_b64_e32 v[22:23], v[14:15]
	v_mov_b64_e32 v[18:19], v[10:11]
	s_waitcnt vmcnt(17)
	v_mov_b64_e32 v[16:17], v[4:5]
	s_waitcnt vmcnt(16)
	v_mov_b64_e32 v[12:13], v[8:9]
	s_cmpk_gt_i32 s45, 0x7ff
	v_mov_b32_e32 v52, v60
	v_mov_b32_e32 v51, v59
	v_mov_b32_e32 v50, v58
	v_mov_b32_e32 v49, v57
	v_mov_b32_e32 v48, v56
	v_mov_b32_e32 v47, v55
	v_mov_b32_e32 v46, v54
	v_mov_b32_e32 v45, v53
	v_mov_b64_e32 v[14:15], v[2:3]
	v_mov_b64_e32 v[10:11], v[6:7]
	s_barrier
	s_cbranch_scc0 .LBB0_103

.LBB0_111:
	v_mov_b32_e32 v1, v242
	s_movk_i32 s6, 0xc90
	v_ashrrev_i32_e32 v30, 6, v1
	v_cmp_gt_i32_e32 vcc, s6, v1
	v_readfirstlane_b32 s48, v30
	s_and_saveexec_b64 s[28:29], vcc
	v_lshl_add_u32 v31, v1, 4, 0
	v_add_u32_e32 v31, 0x18000, v31
	ds_write_b128 v31, v[6:9]
	s_or_b64 exec, exec, s[28:29]
	s_movk_i32 s6, 0xa90
	v_cmp_gt_i32_e32 vcc, s6, v1
	s_and_saveexec_b64 s[28:29], vcc
	s_add_i32 s6, 0, 0x18000
	v_lshl_add_u32 v6, v1, 4, s6
	ds_write_b128 v6, v[2:5] offset:8192
	s_or_b64 exec, exec, s[28:29]
	s_movk_i32 s6, 0x890
	v_cmp_gt_i32_e32 vcc, s6, v1
	s_and_saveexec_b64 s[28:29], vcc
	s_add_i32 s6, 0, 0x18000
	v_lshl_add_u32 v2, v1, 4, s6
	ds_write_b128 v2, v[14:17] offset:16384
	s_or_b64 exec, exec, s[28:29]
	s_movk_i32 s6, 0x690
	v_cmp_gt_i32_e32 vcc, s6, v1
	s_and_saveexec_b64 s[28:29], vcc
	s_add_i32 s6, 0, 0x18000
	v_lshl_add_u32 v2, v1, 4, s6
	ds_write_b128 v2, v[10:13] offset:24576
	s_or_b64 exec, exec, s[28:29]
	s_movk_i32 s6, 0x490
	v_cmp_gt_i32_e32 vcc, s6, v1
	s_and_saveexec_b64 s[28:29], vcc
	s_add_i32 s6, 0, 0x18000
	v_lshl_add_u32 v2, v1, 4, s6
	ds_write_b128 v2, v[22:25] offset:32768
	s_or_b64 exec, exec, s[28:29]
	s_movk_i32 s6, 0x290
	v_cmp_gt_i32_e32 vcc, s6, v1
	s_and_saveexec_b64 s[28:29], vcc
	s_add_i32 s6, 0, 0x18000
	v_lshl_add_u32 v2, v1, 4, s6
	ds_write_b128 v2, v[18:21] offset:40960
	s_or_b64 exec, exec, s[28:29]
	s_movk_i32 s6, 0x90
	v_cmp_gt_i32_e32 vcc, s6, v1
	s_and_saveexec_b64 s[28:29], vcc
	s_add_i32 s6, 0, 0x18000
	v_lshl_add_u32 v2, v1, 4, s6
	ds_write_b128 v2, v[26:29] offset:49152
	s_or_b64 exec, exec, s[28:29]
	v_and_b32_e32 v93, 63, v1
	v_lshlrev_b32_e32 v2, 11, v30
	s_add_i32 s49, 0, 0x18000
	v_lshlrev_b32_e32 v3, 1, v93
	v_lshlrev_b32_e32 v94, 2, v93
	v_add3_u32 v22, s49, v2, v94
	v_bitop3_b32 v2, v3, v30, 6 bitop3:0x6c
	v_lshlrev_b32_e32 v4, 8, v93
	s_add_i32 s6, 0, 0x10000
	v_lshlrev_b32_e32 v2, 4, v2
	s_waitcnt lgkmcnt(0)
	s_barrier
	v_add3_u32 v20, s6, v4, v2
	ds_read2st64_b32 v[4:5], v22 offset0:8 offset1:9
	v_or_b32_e32 v2, 1, v3
	v_bitop3_b32 v3, v2, v30, 7 bitop3:0x6c
	v_lshlrev_b32_e32 v2, 7, v2
	v_lshlrev_b32_e32 v3, 4, v3
	v_add3_u32 v21, s6, v2, v3
	ds_read_b32 v3, v22 offset:2560
	ds_read2st64_b32 v[16:17], v22 offset0:4 offset1:5
	s_waitcnt lgkmcnt(2)
	v_lshlrev_b32_e32 v6, 16, v5
	v_and_b32_e32 v7, 0xffff0000, v5
	v_lshlrev_b32_e32 v8, 16, v4
	v_and_b32_e32 v9, 0xffff0000, v4
	ds_read2st64_b32 v[4:5], v22 offset0:6 offset1:7
	s_waitcnt lgkmcnt(1)
	v_lshlrev_b32_e32 v24, 16, v17
	v_and_b32_e32 v25, 0xffff0000, v17
	v_lshlrev_b32_e32 v2, 16, v3
	v_and_b32_e32 v3, 0xffff0000, v3
	s_waitcnt lgkmcnt(0)
	v_lshlrev_b32_e32 v12, 16, v4
	v_and_b32_e32 v13, 0xffff0000, v4
	v_lshlrev_b32_e32 v14, 16, v5
	v_and_b32_e32 v15, 0xffff0000, v5
	s_waitcnt vmcnt(3)
	v_pk_mul_f32 v[4:5], v[86:87], v[12:13]
	v_pk_mul_f32 v[10:11], v[86:87], v[14:15]
	v_pk_fma_f32 v[4:5], v[84:85], v[14:15], v[4:5]
	v_pk_fma_f32 v[10:11], v[84:85], v[8:9], v[10:11]
	v_pk_fma_f32 v[4:5], v[80:81], v[8:9], v[4:5]
	v_pk_fma_f32 v[10:11], v[80:81], v[6:7], v[10:11]
	v_pk_fma_f32 v[4:5], v[82:83], v[6:7], v[4:5]
	v_pk_fma_f32 v[2:3], v[82:83], v[2:3], v[10:11]
	v_pk_mul_f32 v[6:7], v[4:5], s[96:97] op_sel_hi:[1,0]
	v_pk_mul_f32 v[10:11], v[2:3], s[96:97] op_sel_hi:[1,0]
	v_exp_f32_e32 v6, v6
	v_exp_f32_e32 v7, v7
	v_exp_f32_e32 v10, v10
	v_exp_f32_e32 v11, v11
	v_lshlrev_b32_e32 v23, 12, v30
	v_pk_add_f32 v[6:7], v[6:7], 1.0 op_sel_hi:[1,0]
	v_lshlrev_b32_e32 v92, 3, v93
	v_rcp_f32_e32 v6, v6
	v_rcp_f32_e32 v7, v7
	v_pk_add_f32 v[10:11], v[10:11], 1.0 op_sel_hi:[1,0]
	v_add3_u32 v23, 0, v23, v92
	v_rcp_f32_e32 v10, v10
	v_pk_mul_f32 v[4:5], v[4:5], v[6:7]
	v_pk_mul_f32 v[6:7], v[86:87], v[24:25]
	v_rcp_f32_e32 v11, v11
	v_pk_fma_f32 v[6:7], v[84:85], v[12:13], v[6:7]
	s_cmp_eq_u32 s48, 7
	v_pk_fma_f32 v[6:7], v[80:81], v[14:15], v[6:7]
	v_pk_mul_f32 v[2:3], v[2:3], v[10:11]
	v_pk_fma_f32 v[6:7], v[82:83], v[8:9], v[6:7]
	v_lshlrev_b32_e32 v10, 16, v16
	v_pk_mul_f32 v[8:9], v[6:7], s[96:97] op_sel_hi:[1,0]
	v_and_b32_e32 v11, 0xffff0000, v16
	v_exp_f32_e32 v8, v8
	v_exp_f32_e32 v9, v9
	s_cselect_b64 s[94:95], -1, 0
	s_cmp_lg_u32 s48, 7
	v_pk_add_f32 v[8:9], v[8:9], 1.0 op_sel_hi:[1,0]
	v_rcp_f32_e32 v8, v8
	v_rcp_f32_e32 v9, v9
	s_nop 0
	v_pk_mul_f32 v[6:7], v[6:7], v[8:9]
	v_pk_mul_f32 v[8:9], v[86:87], v[10:11]
	v_pk_fma_f32 v[8:9], v[84:85], v[24:25], v[8:9]
	v_pk_fma_f32 v[8:9], v[80:81], v[12:13], v[8:9]
	v_pk_fma_f32 v[8:9], v[82:83], v[14:15], v[8:9]
	s_nop 0
	v_pk_mul_f32 v[14:15], v[8:9], s[96:97] op_sel_hi:[1,0]
	v_exp_f32_e32 v14, v14
	v_exp_f32_e32 v15, v15
	s_nop 0
	v_pk_add_f32 v[14:15], v[14:15], 1.0 op_sel_hi:[1,0]
	v_rcp_f32_e32 v14, v14
	v_rcp_f32_e32 v15, v15
	s_nop 0
	v_pk_mul_f32 v[8:9], v[8:9], v[14:15]
	ds_read2st64_b32 v[14:15], v22 offset0:2 offset1:3
	s_waitcnt lgkmcnt(0)
	v_lshlrev_b32_e32 v16, 16, v15
	v_and_b32_e32 v17, 0xffff0000, v15
	v_pk_mul_f32 v[18:19], v[86:87], v[16:17]
	v_pk_fma_f32 v[18:19], v[84:85], v[10:11], v[18:19]
	v_pk_fma_f32 v[18:19], v[80:81], v[24:25], v[18:19]
	v_pk_fma_f32 v[12:13], v[82:83], v[12:13], v[18:19]
	s_nop 0
	v_pk_mul_f32 v[18:19], v[12:13], s[96:97] op_sel_hi:[1,0]
	v_exp_f32_e32 v18, v18
	v_exp_f32_e32 v19, v19
	s_nop 0
	v_pk_add_f32 v[18:19], v[18:19], 1.0 op_sel_hi:[1,0]
	v_rcp_f32_e32 v18, v18
	v_rcp_f32_e32 v19, v19
	s_nop 0
	v_pk_mul_f32 v[12:13], v[12:13], v[18:19]
	v_lshlrev_b32_e32 v18, 16, v14
	v_and_b32_e32 v19, 0xffff0000, v14
	v_pk_mul_f32 v[14:15], v[86:87], v[18:19]
	v_pk_fma_f32 v[14:15], v[84:85], v[16:17], v[14:15]
	v_pk_fma_f32 v[14:15], v[80:81], v[10:11], v[14:15]
	v_pk_fma_f32 v[14:15], v[82:83], v[24:25], v[14:15]
	s_nop 0
	v_pk_mul_f32 v[24:25], v[14:15], s[96:97] op_sel_hi:[1,0]
	v_exp_f32_e32 v24, v24
	v_exp_f32_e32 v25, v25
	s_nop 0
	v_pk_add_f32 v[24:25], v[24:25], 1.0 op_sel_hi:[1,0]
	v_rcp_f32_e32 v24, v24
	v_rcp_f32_e32 v25, v25
	s_nop 0
	v_pk_mul_f32 v[14:15], v[14:15], v[24:25]
	ds_read2st64_b32 v[24:25], v22 offset1:1
	s_waitcnt lgkmcnt(0)
	v_lshlrev_b32_e32 v26, 16, v25
	v_and_b32_e32 v27, 0xffff0000, v25
	v_pk_mul_f32 v[28:29], v[86:87], v[26:27]
	v_pk_fma_f32 v[28:29], v[84:85], v[18:19], v[28:29]
	v_pk_fma_f32 v[28:29], v[80:81], v[16:17], v[28:29]
	v_pk_fma_f32 v[10:11], v[82:83], v[10:11], v[28:29]
	s_nop 0
	v_pk_mul_f32 v[28:29], v[10:11], s[96:97] op_sel_hi:[1,0]
	v_exp_f32_e32 v28, v28
	v_exp_f32_e32 v29, v29
	s_nop 0
	v_pk_add_f32 v[28:29], v[28:29], 1.0 op_sel_hi:[1,0]
	v_rcp_f32_e32 v28, v28
	v_rcp_f32_e32 v29, v29
	s_nop 0
	v_pk_mul_f32 v[10:11], v[10:11], v[28:29]
	v_lshlrev_b32_e32 v28, 16, v24
	v_and_b32_e32 v29, 0xffff0000, v24
	v_pk_mul_f32 v[24:25], v[86:87], v[28:29]
	v_pk_fma_f32 v[24:25], v[84:85], v[26:27], v[24:25]
	v_pk_fma_f32 v[18:19], v[80:81], v[18:19], v[24:25]
	v_pk_fma_f32 v[16:17], v[82:83], v[16:17], v[18:19]
	s_nop 0
	v_pk_mul_f32 v[18:19], v[16:17], s[96:97] op_sel_hi:[1,0]
	v_exp_f32_e32 v18, v18
	v_exp_f32_e32 v19, v19
	s_nop 0
	v_pk_add_f32 v[18:19], v[18:19], 1.0 op_sel_hi:[1,0]
	v_rcp_f32_e32 v18, v18
	v_rcp_f32_e32 v19, v19
	s_nop 0
	v_pk_mul_f32 v[16:17], v[16:17], v[18:19]
	ds_write2st64_b64 v23, v[16:17], v[10:11] offset1:1
	ds_write2st64_b64 v23, v[14:15], v[12:13] offset0:2 offset1:3
	ds_write2st64_b64 v23, v[8:9], v[6:7] offset0:4 offset1:5
	ds_write2st64_b64 v23, v[4:5], v[2:3] offset0:6 offset1:7
	ds_read2st64_b32 v[4:5], v22 offset0:75 offset1:76
	ds_read_b32 v3, v22 offset:19712
	ds_read2st64_b32 v[16:17], v22 offset0:71 offset1:72
	s_waitcnt lgkmcnt(2)
	v_lshlrev_b32_e32 v6, 16, v5
	v_and_b32_e32 v7, 0xffff0000, v5
	v_lshlrev_b32_e32 v8, 16, v4
	v_and_b32_e32 v9, 0xffff0000, v4
	ds_read2st64_b32 v[4:5], v22 offset0:73 offset1:74
	s_waitcnt lgkmcnt(1)
	v_lshlrev_b32_e32 v24, 16, v17
	v_and_b32_e32 v25, 0xffff0000, v17
	v_lshlrev_b32_e32 v2, 16, v3
	v_and_b32_e32 v3, 0xffff0000, v3
	s_waitcnt lgkmcnt(0)
	v_lshlrev_b32_e32 v12, 16, v4
	v_and_b32_e32 v13, 0xffff0000, v4
	v_lshlrev_b32_e32 v14, 16, v5
	v_and_b32_e32 v15, 0xffff0000, v5
	v_pk_mul_f32 v[4:5], v[72:73], v[12:13]
	v_pk_mul_f32 v[10:11], v[72:73], v[14:15]
	v_pk_fma_f32 v[4:5], v[74:75], v[14:15], v[4:5]
	v_pk_fma_f32 v[10:11], v[74:75], v[8:9], v[10:11]
	v_pk_fma_f32 v[4:5], v[78:79], v[8:9], v[4:5]
	v_pk_fma_f32 v[10:11], v[78:79], v[6:7], v[10:11]
	s_waitcnt vmcnt(2)
	v_pk_fma_f32 v[4:5], v[76:77], v[6:7], v[4:5]
	v_pk_fma_f32 v[2:3], v[76:77], v[2:3], v[10:11]
	v_pk_mul_f32 v[6:7], v[4:5], s[96:97] op_sel_hi:[1,0]
	v_pk_mul_f32 v[10:11], v[2:3], s[96:97] op_sel_hi:[1,0]
	v_exp_f32_e32 v6, v6
	v_exp_f32_e32 v7, v7
	v_exp_f32_e32 v10, v10
	v_exp_f32_e32 v11, v11
	v_pk_add_f32 v[6:7], v[6:7], 1.0 op_sel_hi:[1,0]
	s_nop 0
	v_rcp_f32_e32 v6, v6
	v_rcp_f32_e32 v7, v7
	v_pk_add_f32 v[10:11], v[10:11], 1.0 op_sel_hi:[1,0]
	v_pk_mul_f32 v[4:5], v[4:5], v[6:7]
	v_pk_mul_f32 v[6:7], v[72:73], v[24:25]
	v_rcp_f32_e32 v10, v10
	v_pk_fma_f32 v[6:7], v[74:75], v[12:13], v[6:7]
	v_rcp_f32_e32 v11, v11
	v_pk_fma_f32 v[6:7], v[78:79], v[14:15], v[6:7]
	v_pk_mul_f32 v[2:3], v[2:3], v[10:11]
	v_pk_fma_f32 v[6:7], v[76:77], v[8:9], v[6:7]
	v_lshlrev_b32_e32 v10, 16, v16
	v_pk_mul_f32 v[8:9], v[6:7], s[96:97] op_sel_hi:[1,0]
	v_and_b32_e32 v11, 0xffff0000, v16
	v_exp_f32_e32 v8, v8
	v_exp_f32_e32 v9, v9
	s_nop 0
	v_pk_add_f32 v[8:9], v[8:9], 1.0 op_sel_hi:[1,0]
	v_rcp_f32_e32 v8, v8
	v_rcp_f32_e32 v9, v9
	s_nop 0
	v_pk_mul_f32 v[6:7], v[6:7], v[8:9]
	v_pk_mul_f32 v[8:9], v[72:73], v[10:11]
	v_pk_fma_f32 v[8:9], v[74:75], v[24:25], v[8:9]
	v_pk_fma_f32 v[8:9], v[78:79], v[12:13], v[8:9]
	v_pk_fma_f32 v[8:9], v[76:77], v[14:15], v[8:9]
	s_nop 0
	v_pk_mul_f32 v[14:15], v[8:9], s[96:97] op_sel_hi:[1,0]
	v_exp_f32_e32 v14, v14
	v_exp_f32_e32 v15, v15
	s_nop 0
	v_pk_add_f32 v[14:15], v[14:15], 1.0 op_sel_hi:[1,0]
	v_rcp_f32_e32 v14, v14
	v_rcp_f32_e32 v15, v15
	s_nop 0
	v_pk_mul_f32 v[8:9], v[8:9], v[14:15]
	ds_read2st64_b32 v[14:15], v22 offset0:69 offset1:70
	s_waitcnt lgkmcnt(0)
	v_lshlrev_b32_e32 v16, 16, v15
	v_and_b32_e32 v17, 0xffff0000, v15
	v_pk_mul_f32 v[18:19], v[72:73], v[16:17]
	v_pk_fma_f32 v[18:19], v[74:75], v[10:11], v[18:19]
	v_pk_fma_f32 v[18:19], v[78:79], v[24:25], v[18:19]
	v_pk_fma_f32 v[12:13], v[76:77], v[12:13], v[18:19]
	s_nop 0
	v_pk_mul_f32 v[18:19], v[12:13], s[96:97] op_sel_hi:[1,0]
	v_exp_f32_e32 v18, v18
	v_exp_f32_e32 v19, v19
	s_nop 0
	v_pk_add_f32 v[18:19], v[18:19], 1.0 op_sel_hi:[1,0]
	v_rcp_f32_e32 v18, v18
	v_rcp_f32_e32 v19, v19
	s_nop 0
	v_pk_mul_f32 v[12:13], v[12:13], v[18:19]
	v_lshlrev_b32_e32 v18, 16, v14
	v_and_b32_e32 v19, 0xffff0000, v14
	v_pk_mul_f32 v[14:15], v[72:73], v[18:19]
	v_pk_fma_f32 v[14:15], v[74:75], v[16:17], v[14:15]
	v_pk_fma_f32 v[14:15], v[78:79], v[10:11], v[14:15]
	v_pk_fma_f32 v[14:15], v[76:77], v[24:25], v[14:15]
	s_nop 0
	v_pk_mul_f32 v[24:25], v[14:15], s[96:97] op_sel_hi:[1,0]
	v_exp_f32_e32 v24, v24
	v_exp_f32_e32 v25, v25
	s_nop 0
	v_pk_add_f32 v[24:25], v[24:25], 1.0 op_sel_hi:[1,0]
	v_rcp_f32_e32 v24, v24
	v_rcp_f32_e32 v25, v25
	s_nop 0
	v_pk_mul_f32 v[14:15], v[14:15], v[24:25]
	ds_read2st64_b32 v[24:25], v22 offset0:67 offset1:68
	s_waitcnt lgkmcnt(0)
	v_lshlrev_b32_e32 v26, 16, v25
	v_and_b32_e32 v27, 0xffff0000, v25
	v_pk_mul_f32 v[28:29], v[72:73], v[26:27]
	v_pk_fma_f32 v[28:29], v[74:75], v[18:19], v[28:29]
	v_pk_fma_f32 v[28:29], v[78:79], v[16:17], v[28:29]
	v_pk_fma_f32 v[10:11], v[76:77], v[10:11], v[28:29]
	s_nop 0
	v_pk_mul_f32 v[28:29], v[10:11], s[96:97] op_sel_hi:[1,0]
	v_exp_f32_e32 v28, v28
	v_exp_f32_e32 v29, v29
	s_nop 0
	v_pk_add_f32 v[28:29], v[28:29], 1.0 op_sel_hi:[1,0]
	v_rcp_f32_e32 v28, v28
	v_rcp_f32_e32 v29, v29
	s_nop 0
	v_pk_mul_f32 v[10:11], v[10:11], v[28:29]
	v_lshlrev_b32_e32 v28, 16, v24
	v_and_b32_e32 v29, 0xffff0000, v24
	v_pk_mul_f32 v[24:25], v[72:73], v[28:29]
	v_pk_fma_f32 v[24:25], v[74:75], v[26:27], v[24:25]
	v_pk_fma_f32 v[18:19], v[78:79], v[18:19], v[24:25]
	v_pk_fma_f32 v[16:17], v[76:77], v[16:17], v[18:19]
	s_nop 0
	v_pk_mul_f32 v[18:19], v[16:17], s[96:97] op_sel_hi:[1,0]
	v_exp_f32_e32 v18, v18
	v_exp_f32_e32 v19, v19
	s_nop 0
	v_pk_add_f32 v[18:19], v[18:19], 1.0 op_sel_hi:[1,0]
	v_rcp_f32_e32 v18, v18
	v_rcp_f32_e32 v19, v19
	s_nop 0
	v_pk_mul_f32 v[16:17], v[16:17], v[18:19]
	ds_write2st64_b64 v23, v[16:17], v[10:11] offset0:64 offset1:65
	ds_write2st64_b64 v23, v[14:15], v[12:13] offset0:66 offset1:67
	ds_write2st64_b64 v23, v[8:9], v[6:7] offset0:68 offset1:69
	ds_write2st64_b64 v23, v[4:5], v[2:3] offset0:70 offset1:71
	ds_read_b32 v3, v22 offset:36864
	ds_read2st64_b32 v[8:9], v22 offset0:142 offset1:143
	ds_read2st64_b32 v[12:13], v22 offset0:140 offset1:141
	s_waitcnt lgkmcnt(2)
	v_lshlrev_b32_e32 v2, 16, v3
	s_waitcnt lgkmcnt(1)
	v_lshlrev_b32_e32 v4, 16, v9
	v_and_b32_e32 v5, 0xffff0000, v9
	v_lshlrev_b32_e32 v6, 16, v8
	v_and_b32_e32 v7, 0xffff0000, v8
	s_waitcnt lgkmcnt(0)
	v_lshlrev_b32_e32 v8, 16, v13
	v_and_b32_e32 v9, 0xffff0000, v13
	v_pk_mul_f32 v[10:11], v[66:67], v[8:9]
	v_and_b32_e32 v3, 0xffff0000, v3
	s_waitcnt vmcnt(0)
	v_pk_fma_f32 v[10:11], v[64:65], v[6:7], v[10:11]
	v_pk_fma_f32 v[10:11], v[62:63], v[4:5], v[10:11]
	v_pk_fma_f32 v[2:3], v[68:69], v[2:3], v[10:11]
	s_nop 0
	v_pk_mul_f32 v[10:11], v[2:3], s[96:97] op_sel_hi:[1,0]
	v_exp_f32_e32 v10, v10
	v_exp_f32_e32 v11, v11
	s_nop 0
	v_pk_add_f32 v[10:11], v[10:11], 1.0 op_sel_hi:[1,0]
	v_rcp_f32_e32 v10, v10
	v_rcp_f32_e32 v11, v11
	s_nop 0
	v_pk_mul_f32 v[2:3], v[2:3], v[10:11]
	ds_read2st64_b32 v[10:11], v22 offset0:136 offset1:137
	s_waitcnt lgkmcnt(0)
	v_lshlrev_b32_e32 v14, 16, v11
	v_and_b32_e32 v15, 0xffff0000, v11
	v_lshlrev_b32_e32 v16, 16, v10
	v_and_b32_e32 v17, 0xffff0000, v10
	ds_read2st64_b32 v[10:11], v22 offset0:134 offset1:135
	ds_read2st64_b32 v[22:23], v22 offset0:138 offset1:139
	s_waitcnt lgkmcnt(1)
	v_lshlrev_b32_e32 v24, 16, v10
	v_and_b32_e32 v25, 0xffff0000, v10
	v_lshlrev_b32_e32 v18, 16, v11
	v_and_b32_e32 v19, 0xffff0000, v11
	v_pk_mul_f32 v[10:11], v[66:67], v[24:25]
	v_pk_fma_f32 v[10:11], v[64:65], v[18:19], v[10:11]
	v_pk_mul_f32 v[18:19], v[66:67], v[18:19]
	v_pk_fma_f32 v[10:11], v[62:63], v[16:17], v[10:11]
	v_pk_fma_f32 v[18:19], v[64:65], v[16:17], v[18:19]
	v_pk_fma_f32 v[10:11], v[68:69], v[14:15], v[10:11]
	v_pk_fma_f32 v[18:19], v[62:63], v[14:15], v[18:19]
	v_pk_mul_f32 v[24:25], v[10:11], s[96:97] op_sel_hi:[1,0]
	v_pk_mul_f32 v[16:17], v[66:67], v[16:17]
	v_exp_f32_e32 v24, v24
	v_exp_f32_e32 v25, v25
	v_pk_fma_f32 v[16:17], v[64:65], v[14:15], v[16:17]
	v_pk_add_f32 v[24:25], v[24:25], 1.0 op_sel_hi:[1,0]
	v_rcp_f32_e32 v24, v24
	v_rcp_f32_e32 v25, v25
	s_nop 0
	v_pk_mul_f32 v[10:11], v[10:11], v[24:25]
	s_waitcnt lgkmcnt(0)
	v_lshlrev_b32_e32 v24, 16, v22
	v_and_b32_e32 v25, 0xffff0000, v22
	v_pk_fma_f32 v[18:19], v[68:69], v[24:25], v[18:19]
	v_lshlrev_b32_e32 v22, 16, v23
	v_pk_mul_f32 v[26:27], v[18:19], s[96:97] op_sel_hi:[1,0]
	v_and_b32_e32 v23, 0xffff0000, v23
	v_exp_f32_e32 v26, v26
	v_exp_f32_e32 v27, v27
	v_pk_fma_f32 v[16:17], v[62:63], v[24:25], v[16:17]
	v_pk_add_f32 v[26:27], v[26:27], 1.0 op_sel_hi:[1,0]
	v_rcp_f32_e32 v26, v26
	v_rcp_f32_e32 v27, v27
	v_pk_fma_f32 v[16:17], v[68:69], v[22:23], v[16:17]
	v_pk_mul_f32 v[18:19], v[18:19], v[26:27]
	v_pk_mul_f32 v[26:27], v[16:17], s[96:97] op_sel_hi:[1,0]
	v_exp_f32_e32 v26, v26
	v_exp_f32_e32 v27, v27
	s_nop 0
	v_pk_add_f32 v[26:27], v[26:27], 1.0 op_sel_hi:[1,0]
	v_rcp_f32_e32 v26, v26
	v_rcp_f32_e32 v27, v27
	s_nop 0
	v_pk_mul_f32 v[16:17], v[16:17], v[26:27]
	v_lshlrev_b32_e32 v26, 16, v12
	v_and_b32_e32 v27, 0xffff0000, v12
	v_pk_mul_f32 v[12:13], v[66:67], v[14:15]
	v_pk_fma_f32 v[12:13], v[64:65], v[24:25], v[12:13]
	v_pk_fma_f32 v[12:13], v[62:63], v[22:23], v[12:13]
	v_pk_fma_f32 v[12:13], v[68:69], v[26:27], v[12:13]
	s_nop 0
	v_pk_mul_f32 v[14:15], v[12:13], s[96:97] op_sel_hi:[1,0]
	v_exp_f32_e32 v14, v14
	v_exp_f32_e32 v15, v15
	s_nop 0
	v_pk_add_f32 v[14:15], v[14:15], 1.0 op_sel_hi:[1,0]
	v_rcp_f32_e32 v14, v14
	v_rcp_f32_e32 v15, v15
	s_nop 0
	v_pk_mul_f32 v[12:13], v[12:13], v[14:15]
	v_pk_mul_f32 v[14:15], v[66:67], v[24:25]
	v_pk_fma_f32 v[14:15], v[64:65], v[22:23], v[14:15]
	v_pk_mul_f32 v[22:23], v[66:67], v[22:23]
	v_pk_fma_f32 v[14:15], v[62:63], v[26:27], v[14:15]
	v_pk_fma_f32 v[22:23], v[64:65], v[26:27], v[22:23]
	v_pk_fma_f32 v[14:15], v[68:69], v[8:9], v[14:15]
	v_pk_fma_f32 v[22:23], v[62:63], v[8:9], v[22:23]
	v_pk_mul_f32 v[24:25], v[14:15], s[96:97] op_sel_hi:[1,0]
	v_pk_fma_f32 v[22:23], v[68:69], v[6:7], v[22:23]
	v_exp_f32_e32 v24, v24
	v_exp_f32_e32 v25, v25
	s_nop 0
	v_pk_add_f32 v[24:25], v[24:25], 1.0 op_sel_hi:[1,0]
	v_rcp_f32_e32 v24, v24
	v_rcp_f32_e32 v25, v25
	s_nop 0
	v_pk_mul_f32 v[14:15], v[14:15], v[24:25]
	v_pk_mul_f32 v[24:25], v[22:23], s[96:97] op_sel_hi:[1,0]
	v_exp_f32_e32 v24, v24
	v_exp_f32_e32 v25, v25
	s_nop 0
	v_pk_add_f32 v[24:25], v[24:25], 1.0 op_sel_hi:[1,0]
	v_rcp_f32_e32 v24, v24
	v_rcp_f32_e32 v25, v25
	s_nop 0
	v_pk_mul_f32 v[22:23], v[22:23], v[24:25]
	v_pk_mul_f32 v[24:25], v[66:67], v[26:27]
	v_pk_fma_f32 v[8:9], v[64:65], v[8:9], v[24:25]
	v_pk_fma_f32 v[6:7], v[62:63], v[6:7], v[8:9]
	v_pk_fma_f32 v[4:5], v[68:69], v[4:5], v[6:7]
	s_nop 0
	v_pk_mul_f32 v[6:7], v[4:5], s[96:97] op_sel_hi:[1,0]
	v_exp_f32_e32 v6, v6
	v_exp_f32_e32 v7, v7
	s_nop 0
	v_pk_add_f32 v[6:7], v[6:7], 1.0 op_sel_hi:[1,0]
	v_rcp_f32_e32 v6, v6
	v_rcp_f32_e32 v7, v7
	s_nop 0
	v_pk_mul_f32 v[8:9], v[4:5], v[6:7]
	v_cvt_pk_bf16_f32 v7, v8, v2
	v_cvt_pk_bf16_f32 v6, v14, v22
	v_cvt_pk_bf16_f32 v5, v16, v12
	v_cvt_pk_bf16_f32 v4, v10, v18
	ds_write_b128 v20, v[4:7]
	v_cvt_pk_bf16_f32 v5, v9, v3
	v_cvt_pk_bf16_f32 v4, v15, v23
	v_cvt_pk_bf16_f32 v3, v17, v13
	v_cvt_pk_bf16_f32 v2, v11, v19
	ds_write_b128 v21, v[2:5]
	s_cbranch_scc1 .LBB0_127
	v_lshl_add_u32 v2, v93, 2, 0
	v_add_u32_e32 v3, 0x24900, v2
	v_add_u32_e32 v4, 0x24a00, v2
	v_add_u32_e32 v5, 0x24b00, v2
	v_add_u32_e32 v2, 0x24c00, v2
	ds_write_b32 v3, v88
	ds_write_b32 v4, v89
	ds_write_b32 v5, v91
	ds_write_b32 v2, v90

.LBB0_225:
	s_or_b64 exec, exec, s[28:29]
	v_pk_fma_f32 v[10:11], v[10:11], v[24:25], v[22:23] op_sel_hi:[1,0,1] neg_lo:[0,1,0] neg_hi:[0,1,0]
	v_pk_fma_f32 v[6:7], v[6:7], v[20:21], v[10:11] op_sel_hi:[1,0,1] neg_lo:[0,1,0] neg_hi:[0,1,0]
	v_or_b32_e32 v10, v28, v98
	v_mul_f32_e32 v11, v97, v6
	v_cvt_pk_bf16_f32 v16, v11, s0
	v_mad_u64_u32 v[10:11], s[6:7], v10, s8, v[14:15]
	v_lshl_add_u32 v10, v10, 1, 0
	v_add_u32_e32 v11, 0x18000, v10
	ds_write_b16 v11, v16
	v_mul_f32_e32 v11, v93, v6
	v_cvt_pk_bf16_f32 v11, v11, s0
	v_add_u32_e32 v10, 0x1a400, v10
	ds_write_b16 v10, v11
	s_and_saveexec_b64 s[28:29], vcc
	s_cbranch_execz .LBB0_227
	v_mad_u32_u24 v10, v28, s8, v14
	v_lshl_add_u32 v10, v10, 1, 0
	v_add_u32_e32 v11, 0x18000, v10
	v_add_u32_e32 v10, 0x1a400, v10
	s_movk_i32 s6, 0x90
	ds_write_b16 v10, v131
	v_mad_u32_u24 v10, v28, s6, v33
	ds_write_b16 v11, v131
	ds_write_b32 v10, v6

.LBB0_254:
	v_mov_b32_e32 v3, v242
	s_nop 0
	v_writelane_b32 v254, s6, 27
	s_load_dwordx4 s[8:11], s[0:1], 0x18
	s_load_dwordx2 s[6:7], s[0:1], 0x30
	s_waitcnt lgkmcnt(0)
	v_add_u32_e32 v4, s66, v3
	v_ashrrev_i32_e32 v5, 31, v4
	v_and_b32_e32 v1, 63, v3
	v_readfirstlane_b32 s5, v3
	v_lshl_add_u64 v[4:5], v[4:5], 2, s[6:7]
	global_load_dword v2, v[4:5], off
	v_lshl_add_u32 v4, v3, 2, s40
	s_ashr_i32 s34, s5, 6
	s_lshl_b32 s6, s34, 4
	s_add_i32 s6, s17, s6
	s_add_i32 s7, s6, -1
	s_mul_hi_i32 s7, s7, 0x1800
	v_lshlrev_b32_e32 v7, 1, v1
	s_mov_b32 s19, s60
	s_mov_b32 s13, s66
	v_lshlrev_b32_e32 v130, 4, v1
	s_waitcnt vmcnt(0)
	ds_write_b32 v4, v2
	v_or_b32_e32 v4, s84, v1
	v_ashrrev_i32_e32 v5, 31, v4
	v_lshlrev_b64 v[4:5], 2, v[4:5]
	v_lshl_add_u64 v[18:19], s[8:9], 0, v[4:5]
	s_mul_i32 s8, s6, 0x1800
	s_add_i32 s9, s8, 0xffffe800
	s_add_u32 s28, s80, s9
	s_addc_u32 s29, s81, s7
	s_mul_hi_i32 s7, s6, 0x1800
	s_add_u32 s88, s80, s8
	s_addc_u32 s89, s81, s7
	s_add_i32 s7, s6, 1
	s_add_i32 s9, s8, 0x1800
	v_lshl_add_u64 v[4:5], s[10:11], 0, v[4:5]
	s_mul_hi_i32 s7, s7, 0x1800
	s_mov_b64 s[10:11], s[84:85]
	s_add_u32 s84, s80, s9
	s_addc_u32 s85, s81, s7
	s_add_i32 s7, s6, 2
	s_add_i32 s9, s8, 0x3000
	s_mul_hi_i32 s7, s7, 0x1800
	s_add_u32 s40, s80, s9
	global_load_dword v14, v[18:19], off
	global_load_dword v16, v[4:5], off
	global_load_dword v10, v[18:19], off offset:256
	global_load_dword v12, v[4:5], off offset:256
	global_load_dword v6, v[18:19], off offset:512
	global_load_dword v8, v[4:5], off offset:512
	global_load_dword v2, v[18:19], off offset:768
	s_nop 0
	global_load_dword v4, v[4:5], off offset:768
	s_addc_u32 s41, s81, s7
	global_load_ushort v9, v7, s[28:29] offset:512
	global_load_ushort v11, v7, s[88:89] offset:512
	global_load_ushort v13, v7, s[84:85] offset:512
	global_load_ushort v15, v7, s[40:41] offset:512
	s_add_i32 s7, s6, 3
	s_add_i32 s9, s8, 0x4800
	s_mul_hi_i32 s7, s7, 0x1800
	s_add_u32 s58, s80, s9
	s_addc_u32 s59, s81, s7
	s_add_i32 s7, s6, 4
	s_add_i32 s9, s8, 0x6000
	s_mul_hi_i32 s7, s7, 0x1800
	s_add_u32 s60, s80, s9
	s_addc_u32 s61, s81, s7
	s_add_i32 s7, s6, 5
	s_add_i32 s9, s8, 0x7800
	s_mul_hi_i32 s7, s7, 0x1800
	s_add_u32 s56, s80, s9
	s_addc_u32 s57, s81, s7
	s_add_i32 s7, s6, 6
	s_add_i32 s9, s8, 0x9000
	s_mul_hi_i32 s7, s7, 0x1800
	s_add_u32 s94, s80, s9
	s_addc_u32 s95, s81, s7
	s_add_i32 s7, s6, 7
	s_add_i32 s9, s8, 0xa800
	s_mul_hi_i32 s7, s7, 0x1800
	s_add_u32 s48, s80, s9
	s_addc_u32 s49, s81, s7
	s_add_i32 s7, s6, 8
	s_add_i32 s9, s8, 0xc000
	s_mul_hi_i32 s7, s7, 0x1800
	s_add_u32 s50, s80, s9
	s_addc_u32 s51, s81, s7
	s_add_i32 s7, s6, 9
	s_add_i32 s9, s8, 0xd800
	s_mul_hi_i32 s7, s7, 0x1800
	s_add_u32 s54, s80, s9
	s_addc_u32 s55, s81, s7
	s_add_i32 s7, s6, 10
	s_add_i32 s9, s8, 0xf000
	s_mul_hi_i32 s7, s7, 0x1800
	s_add_u32 s66, s80, s9
	s_addc_u32 s67, s81, s7
	s_add_i32 s7, s6, 11
	s_add_i32 s9, s8, 0x10800
	s_mul_hi_i32 s7, s7, 0x1800
	s_add_u32 s52, s80, s9
	v_mov_b64_e32 v[18:19], s[44:45]
	s_addc_u32 s53, s81, s7
	s_add_i32 s7, s6, 12
	s_add_i32 s9, s8, 0x12000
	s_mul_hi_i32 s7, s7, 0x1800
	s_add_u32 s64, s80, s9
	s_addc_u32 s65, s81, s7
	s_add_i32 s7, s6, 13
	s_add_i32 s9, s8, 0x13800
	s_mul_hi_i32 s7, s7, 0x1800
	s_add_u32 s68, s80, s9
	s_addc_u32 s69, s81, s7
	s_add_i32 s6, s6, 14
	s_add_i32 s8, s8, 0x15000
	s_mul_hi_i32 s6, s6, 0x1800
	s_add_u32 s72, s80, s8
	s_addc_u32 s73, s81, s6
	s_lshl_b32 s34, s34, 5
	s_add_i32 s6, s34, 0
	v_mov_b32_e32 v5, s6
	v_mad_u32_u24 v5, v1, s42, v5
	s_ashr_i32 s5, s5, 7
	s_waitcnt vmcnt(3)
	v_lshlrev_b32_e32 v22, 16, v9
	v_fma_f32 v9, |v22|, s92, 1.0
	v_rcp_f32_e32 v26, v9
	v_mul_f32_e32 v9, v22, v22
	s_waitcnt vmcnt(2)
	v_lshlrev_b32_e32 v23, 16, v11
	v_mul_f32_e32 v9, 0xbf38aa3b, v9
	v_exp_f32_e32 v24, v9
	v_fma_f32 v9, |v23|, s92, 1.0
	v_rcp_f32_e32 v27, v9
	v_mul_f32_e32 v9, v23, v23
	s_waitcnt vmcnt(1)
	v_lshlrev_b32_e32 v20, 16, v13
	v_mul_f32_e32 v9, 0xbf38aa3b, v9
	v_exp_f32_e32 v25, v9
	v_fma_f32 v9, |v20|, s92, 1.0
	v_rcp_f32_e32 v30, v9
	v_mul_f32_e32 v9, v20, v20
	s_waitcnt vmcnt(0)
	v_lshlrev_b32_e32 v21, 16, v15
	v_mul_f32_e32 v9, 0xbf38aa3b, v9
	v_exp_f32_e32 v28, v9
	v_fma_f32 v9, |v21|, s92, 1.0
	v_rcp_f32_e32 v31, v9
	v_mul_f32_e32 v9, v21, v21
	v_mul_f32_e32 v9, 0xbf38aa3b, v9
	v_exp_f32_e32 v29, v9
	global_load_ushort v9, v7, s[28:29] offset:640
	global_load_ushort v11, v7, s[88:89] offset:640
	global_load_ushort v13, v7, s[84:85] offset:640
	global_load_ushort v15, v7, s[40:41] offset:640
	v_pk_fma_f32 v[32:33], v[26:27], s[12:13], v[18:19] op_sel_hi:[1,0,0]
	v_pk_fma_f32 v[34:35], v[30:31], s[12:13], v[18:19] op_sel_hi:[1,0,0]
	v_pk_fma_f32 v[32:33], v[26:27], v[32:33], s[14:15] op_sel_hi:[1,1,0]
	v_pk_fma_f32 v[34:35], v[30:31], v[34:35], s[14:15] op_sel_hi:[1,1,0]
	v_pk_fma_f32 v[32:33], v[26:27], v[32:33], s[16:17] op_sel_hi:[1,1,0]
	v_pk_fma_f32 v[34:35], v[30:31], v[34:35], s[16:17] op_sel_hi:[1,1,0]
	v_pk_fma_f32 v[32:33], v[26:27], v[32:33], s[18:19] op_sel_hi:[1,1,0]
	v_pk_fma_f32 v[34:35], v[30:31], v[34:35], s[18:19] op_sel_hi:[1,1,0]
	v_pk_mul_f32 v[26:27], v[26:27], v[32:33]
	v_cmp_gt_f32_e32 vcc, 0, v22
	v_pk_mul_f32 v[24:25], v[24:25], v[26:27]
	v_pk_mul_f32 v[30:31], v[30:31], v[34:35]
	v_pk_mul_f32 v[26:27], v[24:25], v[22:23]
	v_pk_fma_f32 v[32:33], v[24:25], v[22:23], v[22:23] neg_lo:[1,0,0] neg_hi:[1,0,0]
	v_pk_mul_f32 v[28:29], v[28:29], v[30:31]
	v_cndmask_b32_e32 v22, v32, v26, vcc
	v_pk_mul_f32 v[30:31], v[28:29], v[20:21]
	v_pk_fma_f32 v[24:25], v[28:29], v[20:21], v[20:21] neg_lo:[1,0,0] neg_hi:[1,0,0]
	v_cmp_gt_f32_e64 s[42:43], 0, v23
	v_cmp_gt_f32_e64 s[44:45], 0, v20
	v_cmp_gt_f32_e64 s[46:47], 0, v21
	v_cndmask_b32_e64 v23, v33, v27, s[42:43]
	v_cndmask_b32_e64 v24, v24, v30, s[44:45]
	v_cndmask_b32_e64 v25, v25, v31, s[46:47]
	s_waitcnt vmcnt(3)
	v_lshlrev_b32_e32 v26, 16, v9
	v_fma_f32 v9, |v26|, s92, 1.0
	v_rcp_f32_e32 v28, v9
	v_mul_f32_e32 v9, v26, v26
	s_waitcnt vmcnt(2)
	v_lshlrev_b32_e32 v27, 16, v11
	v_mul_f32_e32 v9, 0xbf38aa3b, v9
	v_exp_f32_e32 v30, v9
	v_fma_f32 v9, |v27|, s92, 1.0
	v_rcp_f32_e32 v29, v9
	v_mul_f32_e32 v9, v27, v27
	s_waitcnt vmcnt(1)
	v_lshlrev_b32_e32 v20, 16, v13
	v_mul_f32_e32 v9, 0xbf38aa3b, v9
	v_exp_f32_e32 v31, v9
	v_fma_f32 v9, |v20|, s92, 1.0
	v_rcp_f32_e32 v32, v9
	v_mul_f32_e32 v9, v20, v20
	s_waitcnt vmcnt(0)
	v_lshlrev_b32_e32 v21, 16, v15
	v_mul_f32_e32 v9, 0xbf38aa3b, v9
	v_exp_f32_e32 v34, v9
	v_fma_f32 v9, |v21|, s92, 1.0
	v_rcp_f32_e32 v33, v9
	v_mul_f32_e32 v9, v21, v21
	v_mul_f32_e32 v9, 0xbf38aa3b, v9
	v_exp_f32_e32 v35, v9
	global_load_ushort v9, v7, s[28:29] offset:768
	global_load_ushort v11, v7, s[88:89] offset:768
	global_load_ushort v13, v7, s[84:85] offset:768
	global_load_ushort v15, v7, s[40:41] offset:768
	v_pk_fma_f32 v[36:37], v[28:29], s[12:13], v[18:19] op_sel_hi:[1,0,0]
	v_pk_fma_f32 v[38:39], v[32:33], s[12:13], v[18:19] op_sel_hi:[1,0,0]
	v_pk_fma_f32 v[36:37], v[28:29], v[36:37], s[14:15] op_sel_hi:[1,1,0]
	v_pk_fma_f32 v[38:39], v[32:33], v[38:39], s[14:15] op_sel_hi:[1,1,0]
	v_pk_fma_f32 v[36:37], v[28:29], v[36:37], s[16:17] op_sel_hi:[1,1,0]
	v_pk_fma_f32 v[38:39], v[32:33], v[38:39], s[16:17] op_sel_hi:[1,1,0]
	v_pk_fma_f32 v[36:37], v[28:29], v[36:37], s[18:19] op_sel_hi:[1,1,0]
	v_pk_fma_f32 v[38:39], v[32:33], v[38:39], s[18:19] op_sel_hi:[1,1,0]
	v_pk_mul_f32 v[28:29], v[28:29], v[36:37]
	v_pk_mul_f32 v[32:33], v[32:33], v[38:39]
	v_pk_mul_f32 v[28:29], v[30:31], v[28:29]
	v_cmp_gt_f32_e32 vcc, 0, v26
	v_pk_mul_f32 v[30:31], v[28:29], v[26:27]
	v_pk_fma_f32 v[28:29], v[28:29], v[26:27], v[26:27] neg_lo:[1,0,0] neg_hi:[1,0,0]
	v_pk_mul_f32 v[32:33], v[34:35], v[32:33]
	v_cndmask_b32_e32 v28, v28, v30, vcc
	v_pk_mul_f32 v[34:35], v[32:33], v[20:21]
	v_pk_fma_f32 v[32:33], v[32:33], v[20:21], v[20:21] neg_lo:[1,0,0] neg_hi:[1,0,0]
	v_cmp_gt_f32_e64 s[44:45], 0, v20
	v_cmp_gt_f32_e64 s[42:43], 0, v27
	v_cmp_gt_f32_e64 s[46:47], 0, v21
	v_cndmask_b32_e64 v26, v32, v34, s[44:45]
	v_cndmask_b32_e64 v29, v29, v31, s[42:43]
	v_cndmask_b32_e64 v27, v33, v35, s[46:47]
	s_waitcnt vmcnt(3)
	v_lshlrev_b32_e32 v30, 16, v9
	v_fma_f32 v9, |v30|, s92, 1.0
	v_rcp_f32_e32 v32, v9
	v_mul_f32_e32 v9, v30, v30
	s_waitcnt vmcnt(2)
	v_lshlrev_b32_e32 v31, 16, v11
	v_mul_f32_e32 v9, 0xbf38aa3b, v9
	v_exp_f32_e32 v34, v9
	v_fma_f32 v9, |v31|, s92, 1.0
	v_rcp_f32_e32 v33, v9
	v_mul_f32_e32 v9, v31, v31
	s_waitcnt vmcnt(1)
	v_lshlrev_b32_e32 v20, 16, v13
	v_mul_f32_e32 v9, 0xbf38aa3b, v9
	v_exp_f32_e32 v35, v9
	v_fma_f32 v9, |v20|, s92, 1.0
	v_rcp_f32_e32 v36, v9
	v_mul_f32_e32 v9, v20, v20
	s_waitcnt vmcnt(0)
	v_lshlrev_b32_e32 v21, 16, v15
	v_mul_f32_e32 v9, 0xbf38aa3b, v9
	v_exp_f32_e32 v38, v9
	v_fma_f32 v9, |v21|, s92, 1.0
	v_rcp_f32_e32 v37, v9
	v_mul_f32_e32 v9, v21, v21
	v_mul_f32_e32 v9, 0xbf38aa3b, v9
	v_exp_f32_e32 v39, v9
	global_load_ushort v9, v7, s[28:29] offset:896
	global_load_ushort v11, v7, s[88:89] offset:896
	global_load_ushort v13, v7, s[84:85] offset:896
	global_load_ushort v15, v7, s[40:41] offset:896
	v_pk_fma_f32 v[40:41], v[32:33], s[12:13], v[18:19] op_sel_hi:[1,0,0]
	v_pk_fma_f32 v[42:43], v[36:37], s[12:13], v[18:19] op_sel_hi:[1,0,0]
	v_pk_fma_f32 v[40:41], v[32:33], v[40:41], s[14:15] op_sel_hi:[1,1,0]
	v_pk_fma_f32 v[42:43], v[36:37], v[42:43], s[14:15] op_sel_hi:[1,1,0]
	v_pk_fma_f32 v[40:41], v[32:33], v[40:41], s[16:17] op_sel_hi:[1,1,0]
	v_pk_fma_f32 v[42:43], v[36:37], v[42:43], s[16:17] op_sel_hi:[1,1,0]
	v_pk_fma_f32 v[40:41], v[32:33], v[40:41], s[18:19] op_sel_hi:[1,1,0]
	v_pk_fma_f32 v[42:43], v[36:37], v[42:43], s[18:19] op_sel_hi:[1,1,0]
	v_pk_mul_f32 v[32:33], v[32:33], v[40:41]
	v_pk_mul_f32 v[36:37], v[36:37], v[42:43]
	v_pk_mul_f32 v[32:33], v[34:35], v[32:33]
	v_cmp_gt_f32_e32 vcc, 0, v30
	v_pk_mul_f32 v[34:35], v[32:33], v[30:31]
	v_pk_fma_f32 v[32:33], v[32:33], v[30:31], v[30:31] neg_lo:[1,0,0] neg_hi:[1,0,0]
	v_pk_mul_f32 v[36:37], v[38:39], v[36:37]
	v_cndmask_b32_e32 v32, v32, v34, vcc
	v_pk_mul_f32 v[38:39], v[36:37], v[20:21]
	v_pk_fma_f32 v[36:37], v[36:37], v[20:21], v[20:21] neg_lo:[1,0,0] neg_hi:[1,0,0]
	v_cmp_gt_f32_e64 s[44:45], 0, v20
	v_cmp_gt_f32_e64 s[42:43], 0, v31
	v_cmp_gt_f32_e64 s[46:47], 0, v21
	v_cndmask_b32_e64 v30, v36, v38, s[44:45]
	v_cndmask_b32_e64 v33, v33, v35, s[42:43]
	v_cndmask_b32_e64 v31, v37, v39, s[46:47]
	s_mov_b64 s[84:85], s[10:11]
	s_mov_b32 s10, 0x3b800000
	v_readlane_b32 s40, v253, 54
	s_waitcnt vmcnt(3)
	v_lshlrev_b32_e32 v34, 16, v9
	v_fma_f32 v9, |v34|, s92, 1.0
	v_rcp_f32_e32 v36, v9
	v_mul_f32_e32 v9, v34, v34
	s_waitcnt vmcnt(2)
	v_lshlrev_b32_e32 v35, 16, v11
	v_mul_f32_e32 v9, 0xbf38aa3b, v9
	v_exp_f32_e32 v38, v9
	v_fma_f32 v9, |v35|, s92, 1.0
	v_rcp_f32_e32 v37, v9
	v_mul_f32_e32 v9, v35, v35
	s_waitcnt vmcnt(1)
	v_lshlrev_b32_e32 v20, 16, v13
	v_mul_f32_e32 v9, 0xbf38aa3b, v9
	v_exp_f32_e32 v39, v9
	v_fma_f32 v9, |v20|, s92, 1.0
	v_rcp_f32_e32 v40, v9
	v_mul_f32_e32 v9, v20, v20
	s_waitcnt vmcnt(0)
	v_lshlrev_b32_e32 v21, 16, v15
	v_mul_f32_e32 v9, 0xbf38aa3b, v9
	v_exp_f32_e32 v42, v9
	v_fma_f32 v9, |v21|, s92, 1.0
	v_rcp_f32_e32 v41, v9
	v_pk_fma_f32 v[44:45], v[36:37], s[12:13], v[18:19] op_sel_hi:[1,0,0]
	v_mul_f32_e32 v9, v21, v21
	v_pk_fma_f32 v[44:45], v[36:37], v[44:45], s[14:15] op_sel_hi:[1,1,0]
	v_pk_fma_f32 v[46:47], v[40:41], s[12:13], v[18:19] op_sel_hi:[1,0,0]
	v_pk_fma_f32 v[44:45], v[36:37], v[44:45], s[16:17] op_sel_hi:[1,1,0]
	v_mul_f32_e32 v9, 0xbf38aa3b, v9
	v_pk_fma_f32 v[46:47], v[40:41], v[46:47], s[14:15] op_sel_hi:[1,1,0]
	v_pk_fma_f32 v[44:45], v[36:37], v[44:45], s[18:19] op_sel_hi:[1,1,0]
	v_exp_f32_e32 v43, v9
	v_pk_fma_f32 v[46:47], v[40:41], v[46:47], s[16:17] op_sel_hi:[1,1,0]
	v_pk_mul_f32 v[36:37], v[36:37], v[44:45]
	v_pk_fma_f32 v[46:47], v[40:41], v[46:47], s[18:19] op_sel_hi:[1,1,0]
	v_pk_mul_f32 v[36:37], v[38:39], v[36:37]
	v_pk_mul_f32 v[40:41], v[40:41], v[46:47]
	v_pk_mul_f32 v[38:39], v[36:37], v[34:35]
	v_pk_fma_f32 v[36:37], v[36:37], v[34:35], v[34:35] neg_lo:[1,0,0] neg_hi:[1,0,0]
	v_cmp_gt_f32_e32 vcc, 0, v34
	v_pk_mul_f32 v[40:41], v[42:43], v[40:41]
	v_cmp_gt_f32_e64 s[42:43], 0, v35
	v_cndmask_b32_e32 v36, v36, v38, vcc
	v_pk_mul_f32 v[42:43], v[40:41], v[20:21]
	v_pk_fma_f32 v[40:41], v[40:41], v[20:21], v[20:21] neg_lo:[1,0,0] neg_hi:[1,0,0]
	v_cmp_gt_f32_e64 s[44:45], 0, v20
	v_cmp_gt_f32_e64 s[46:47], 0, v21
	v_cndmask_b32_e64 v37, v37, v39, s[42:43]
	v_mov_b32_e32 v20, v22
	v_mov_b32_e32 v21, v32
	v_mov_b32_e32 v38, v28
	v_mov_b32_e32 v39, v36
	v_cndmask_b32_e64 v35, v41, v43, s[46:47]
	v_cndmask_b32_e64 v34, v40, v42, s[44:45]
	v_pk_add_f32 v[42:43], v[20:21], v[38:39]
	v_mov_b32_e32 v11, v131
	v_add_f32_e32 v9, v42, v43
	v_mov_b32_e32 v20, v23
	v_mov_b32_e32 v21, v33
	v_add_f32_dpp v9, v9, v9 quad_perm:[1,0,3,2] row_mask:0xf bank_mask:0xf bound_ctrl:1
	v_mov_b32_e32 v38, v29
	v_mov_b32_e32 v39, v37
	v_add_f32_dpp v9, v9, v9 quad_perm:[2,3,0,1] row_mask:0xf bank_mask:0xf bound_ctrl:1
	v_pk_add_f32 v[40:41], v[20:21], v[38:39]
	v_mov_b32_e32 v20, v24
	v_add_f32_dpp v9, v9, v9 row_half_mirror row_mask:0xf bank_mask:0xf bound_ctrl:1
	v_mov_b32_e32 v21, v30
	v_mov_b32_e32 v38, v26
	v_add_f32_dpp v9, v9, v9 row_mirror row_mask:0xf bank_mask:0xf bound_ctrl:1
	v_mov_b32_e32 v39, v34
	v_pk_add_f32 v[38:39], v[20:21], v[38:39]
	v_mov_b32_dpp v11, v9 row_bcast:15 row_mask:0xa bank_mask:0xf
	v_add_f32_e32 v9, v9, v11
	v_mov_b32_e32 v11, v131
	v_mov_b32_e32 v20, v25
	v_mov_b32_e32 v21, v31
	v_mov_b32_dpp v11, v9 row_bcast:31 row_mask:0xc bank_mask:0xf
	v_add_f32_e32 v9, v9, v11
	v_mov_b32_e32 v11, v131
	v_readlane_b32 s6, v9, 63
	v_add_f32_e32 v9, v40, v41
	v_mov_b32_e32 v44, v27
	v_mov_b32_e32 v45, v35
	v_add_f32_dpp v9, v9, v9 quad_perm:[1,0,3,2] row_mask:0xf bank_mask:0xf bound_ctrl:1
	v_pk_add_f32 v[20:21], v[20:21], v[44:45]
	s_xor_b32 s6, s6, 0x80000000
	v_add_f32_dpp v9, v9, v9 quad_perm:[2,3,0,1] row_mask:0xf bank_mask:0xf bound_ctrl:1
	s_nop 1
	v_add_f32_dpp v9, v9, v9 row_half_mirror row_mask:0xf bank_mask:0xf bound_ctrl:1
	s_nop 1
	v_add_f32_dpp v9, v9, v9 row_mirror row_mask:0xf bank_mask:0xf bound_ctrl:1
	s_nop 1
	v_mov_b32_dpp v11, v9 row_bcast:15 row_mask:0xa bank_mask:0xf
	v_add_f32_e32 v9, v9, v11
	v_mov_b32_e32 v11, v131
	s_nop 1
	v_mov_b32_dpp v11, v9 row_bcast:31 row_mask:0xc bank_mask:0xf
	v_add_f32_e32 v9, v9, v11
	v_mov_b32_e32 v11, v131
	v_readlane_b32 s7, v9, 63
	v_add_f32_e32 v9, v38, v39
	s_xor_b32 s7, s7, 0x80000000
	s_nop 0
	v_add_f32_dpp v9, v9, v9 quad_perm:[1,0,3,2] row_mask:0xf bank_mask:0xf bound_ctrl:1
	s_nop 1
	v_add_f32_dpp v9, v9, v9 quad_perm:[2,3,0,1] row_mask:0xf bank_mask:0xf bound_ctrl:1
	s_nop 1
	v_add_f32_dpp v9, v9, v9 row_half_mirror row_mask:0xf bank_mask:0xf bound_ctrl:1
	s_nop 1
	v_add_f32_dpp v9, v9, v9 row_mirror row_mask:0xf bank_mask:0xf bound_ctrl:1
	s_nop 1
	v_mov_b32_dpp v11, v9 row_bcast:15 row_mask:0xa bank_mask:0xf
	v_add_f32_e32 v9, v9, v11
	v_mov_b32_e32 v11, v131
	s_nop 1
	v_mov_b32_dpp v11, v9 row_bcast:31 row_mask:0xc bank_mask:0xf
	v_add_f32_e32 v9, v9, v11
	v_mov_b32_e32 v11, v131
	v_readlane_b32 s8, v9, 63
	v_add_f32_e32 v9, v20, v21
	v_mov_b64_e32 v[20:21], s[10:11]
	v_pk_fma_f32 v[42:43], s[6:7], v[20:21], v[28:29] op_sel_hi:[1,0,1]
	v_add_f32_dpp v9, v9, v9 quad_perm:[1,0,3,2] row_mask:0xf bank_mask:0xf bound_ctrl:1
	v_pk_fma_f32 v[38:39], s[6:7], v[20:21], v[36:37] op_sel_hi:[1,0,1]
	s_xor_b32 s8, s8, 0x80000000
	v_add_f32_dpp v9, v9, v9 quad_perm:[2,3,0,1] row_mask:0xf bank_mask:0xf bound_ctrl:1
	v_pk_fma_f32 v[44:45], s[6:7], v[20:21], v[22:23] op_sel_hi:[1,0,1]
	v_pk_fma_f32 v[28:29], s[6:7], v[20:21], v[32:33] op_sel_hi:[1,0,1]
	v_add_f32_dpp v9, v9, v9 row_half_mirror row_mask:0xf bank_mask:0xf bound_ctrl:1
	v_mov_b32_e32 v32, v42
	v_mov_b32_e32 v33, v38
	v_add_f32_dpp v9, v9, v9 row_mirror row_mask:0xf bank_mask:0xf bound_ctrl:1
	v_pk_mul_f32 v[32:33], v[32:33], v[32:33]
	s_nop 0
	v_mov_b32_dpp v11, v9 row_bcast:15 row_mask:0xa bank_mask:0xf
	v_add_f32_e32 v9, v9, v11
	v_mov_b32_e32 v11, v131
	s_nop 1
	v_mov_b32_dpp v11, v9 row_bcast:31 row_mask:0xc bank_mask:0xf
	v_add_f32_e32 v9, v9, v11
	v_mov_b32_e32 v11, v131
	v_readlane_b32 s9, v9, 63
	s_xor_b32 s9, s9, 0x80000000
	s_nop 0
	v_pk_fma_f32 v[40:41], s[8:9], v[20:21], v[24:25] op_sel_hi:[1,0,1]
	v_pk_fma_f32 v[24:25], s[8:9], v[20:21], v[30:31] op_sel_hi:[1,0,1]
	v_mov_b32_e32 v30, v44
	v_mov_b32_e32 v31, v28
	v_pk_fma_f32 v[30:31], v[30:31], v[30:31], v[32:33]
	v_mov_b32_e32 v32, v43
	v_add_f32_e32 v9, v30, v31
	v_mov_b32_e32 v33, v39
	v_mov_b32_e32 v30, v45
	v_add_f32_dpp v9, v9, v9 quad_perm:[1,0,3,2] row_mask:0xf bank_mask:0xf bound_ctrl:1
	v_mov_b32_e32 v31, v29
	v_pk_mul_f32 v[32:33], v[32:33], v[32:33]
	v_add_f32_dpp v9, v9, v9 quad_perm:[2,3,0,1] row_mask:0xf bank_mask:0xf bound_ctrl:1
	v_pk_fma_f32 v[30:31], v[30:31], v[30:31], v[32:33]
	v_pk_fma_f32 v[26:27], s[8:9], v[20:21], v[26:27] op_sel_hi:[1,0,1]
	v_add_f32_dpp v9, v9, v9 row_half_mirror row_mask:0xf bank_mask:0xf bound_ctrl:1
	v_pk_fma_f32 v[22:23], s[8:9], v[20:21], v[34:35] op_sel_hi:[1,0,1]
	v_mov_b32_e32 v32, v26
	v_add_f32_dpp v9, v9, v9 row_mirror row_mask:0xf bank_mask:0xf bound_ctrl:1
	v_mov_b32_e32 v33, v22
	v_pk_mul_f32 v[32:33], v[32:33], v[32:33]
	v_mov_b32_dpp v11, v9 row_bcast:15 row_mask:0xa bank_mask:0xf
	v_add_f32_e32 v9, v9, v11
	v_mov_b32_e32 v11, v131
	s_nop 1
	v_mov_b32_dpp v11, v9 row_bcast:31 row_mask:0xc bank_mask:0xf
	v_add_f32_e32 v9, v9, v11
	v_mov_b32_e32 v11, v131
	v_readlane_b32 s6, v9, 63
	s_nop 1
	v_fma_f32 v9, s6, v235, v225
	v_rsq_f32_e32 v46, v9
	v_add_f32_e32 v9, v30, v31
	v_mov_b32_e32 v30, v40
	v_mov_b32_e32 v31, v24
	v_add_f32_dpp v9, v9, v9 quad_perm:[1,0,3,2] row_mask:0xf bank_mask:0xf bound_ctrl:1
	v_pk_fma_f32 v[30:31], v[30:31], v[30:31], v[32:33]
	v_mov_b32_e32 v32, v27
	v_add_f32_dpp v9, v9, v9 quad_perm:[2,3,0,1] row_mask:0xf bank_mask:0xf bound_ctrl:1
	v_mov_b32_e32 v33, v23
	v_pk_mul_f32 v[32:33], v[32:33], v[32:33]
	v_add_f32_dpp v9, v9, v9 row_half_mirror row_mask:0xf bank_mask:0xf bound_ctrl:1
	s_nop 1
	v_add_f32_dpp v9, v9, v9 row_mirror row_mask:0xf bank_mask:0xf bound_ctrl:1
	s_nop 1
	v_mov_b32_dpp v11, v9 row_bcast:15 row_mask:0xa bank_mask:0xf
	v_add_f32_e32 v9, v9, v11
	v_mov_b32_e32 v11, v131
	s_nop 1
	v_mov_b32_dpp v11, v9 row_bcast:31 row_mask:0xc bank_mask:0xf
	v_add_f32_e32 v9, v9, v11
	v_mov_b32_e32 v11, v131
	v_readlane_b32 s6, v9, 63
	s_nop 1
	v_fma_f32 v9, s6, v235, v225
	v_rsq_f32_e32 v47, v9
	v_add_f32_e32 v9, v30, v31
	v_mov_b32_e32 v30, v41
	v_mov_b32_e32 v31, v25
	v_add_f32_dpp v9, v9, v9 quad_perm:[1,0,3,2] row_mask:0xf bank_mask:0xf bound_ctrl:1
	v_pk_fma_f32 v[30:31], v[30:31], v[30:31], v[32:33]
	v_pk_mul_f32 v[28:29], v[28:29], v[46:47]
	v_add_f32_dpp v9, v9, v9 quad_perm:[2,3,0,1] row_mask:0xf bank_mask:0xf bound_ctrl:1
	s_nop 1
	v_add_f32_dpp v9, v9, v9 row_half_mirror row_mask:0xf bank_mask:0xf bound_ctrl:1
	s_nop 1
	v_add_f32_dpp v9, v9, v9 row_mirror row_mask:0xf bank_mask:0xf bound_ctrl:1
	s_nop 1
	v_mov_b32_dpp v11, v9 row_bcast:15 row_mask:0xa bank_mask:0xf
	v_add_f32_e32 v9, v9, v11
	v_mov_b32_e32 v11, v131
	s_nop 1
	v_mov_b32_dpp v11, v9 row_bcast:31 row_mask:0xc bank_mask:0xf
	v_add_f32_e32 v9, v9, v11
	v_mov_b32_e32 v11, v131
	v_readlane_b32 s6, v9, 63
	s_nop 1
	v_fma_f32 v9, s6, v235, v225
	v_rsq_f32_e32 v48, v9
	v_add_f32_e32 v9, v30, v31
	v_pk_mul_f32 v[30:31], v[44:45], v[46:47]
	s_nop 0
	v_add_f32_dpp v9, v9, v9 quad_perm:[1,0,3,2] row_mask:0xf bank_mask:0xf bound_ctrl:1
	v_pk_fma_f32 v[36:37], v[14:15], v[30:31], v[16:17] op_sel_hi:[0,1,0]
	s_nop 0
	v_add_f32_dpp v9, v9, v9 quad_perm:[2,3,0,1] row_mask:0xf bank_mask:0xf bound_ctrl:1
	s_nop 1
	v_add_f32_dpp v9, v9, v9 row_half_mirror row_mask:0xf bank_mask:0xf bound_ctrl:1
	s_nop 1
	v_add_f32_dpp v9, v9, v9 row_mirror row_mask:0xf bank_mask:0xf bound_ctrl:1
	s_nop 1
	v_mov_b32_dpp v11, v9 row_bcast:15 row_mask:0xa bank_mask:0xf
	v_add_f32_e32 v9, v9, v11
	v_mov_b32_e32 v11, v131
	s_nop 1
	v_mov_b32_dpp v11, v9 row_bcast:31 row_mask:0xc bank_mask:0xf
	v_add_f32_e32 v9, v9, v11
	s_nop 0
	v_readlane_b32 s6, v9, 63
	s_nop 1
	v_fma_f32 v9, s6, v235, v225
	v_rsq_f32_e32 v49, v9
	v_pk_fma_f32 v[28:29], v[6:7], v[28:29], v[8:9] op_sel_hi:[0,1,0]
	v_pk_mul_f32 v[32:33], v[40:41], v[48:49]
	v_pk_fma_f32 v[34:35], v[14:15], v[32:33], v[16:17] op_sel_hi:[0,1,0]
	v_pk_mul_f32 v[32:33], v[42:43], v[46:47]
	v_pk_mul_f32 v[26:27], v[26:27], v[48:49]
	v_pk_mul_f32 v[24:25], v[24:25], v[48:49]
	v_pk_fma_f32 v[30:31], v[10:11], v[26:27], v[12:13] op_sel_hi:[0,1,0]
	v_pk_fma_f32 v[32:33], v[10:11], v[32:33], v[12:13] op_sel_hi:[0,1,0]
	v_pk_fma_f32 v[26:27], v[6:7], v[24:25], v[8:9] op_sel_hi:[0,1,0]
	global_load_ushort v9, v7, s[58:59] offset:512
	global_load_ushort v11, v7, s[60:61] offset:512
	global_load_ushort v13, v7, s[56:57] offset:512
	global_load_ushort v15, v7, s[94:95] offset:512
	v_pk_mul_f32 v[24:25], v[38:39], v[46:47]
	v_pk_mul_f32 v[22:23], v[22:23], v[48:49]
	v_pk_fma_f32 v[24:25], v[2:3], v[24:25], v[4:5] op_sel_hi:[0,1,0]
	v_pk_fma_f32 v[22:23], v[2:3], v[22:23], v[4:5] op_sel_hi:[0,1,0]
	s_waitcnt vmcnt(3)
	v_lshlrev_b32_e32 v40, 16, v9
	v_fma_f32 v9, |v40|, s92, 1.0
	v_rcp_f32_e32 v42, v9
	v_mul_f32_e32 v9, v40, v40
	s_waitcnt vmcnt(2)
	v_lshlrev_b32_e32 v41, 16, v11
	v_mul_f32_e32 v9, 0xbf38aa3b, v9
	v_exp_f32_e32 v44, v9
	v_fma_f32 v9, |v41|, s92, 1.0
	v_rcp_f32_e32 v43, v9
	v_mul_f32_e32 v9, v41, v41
	s_waitcnt vmcnt(1)
	v_lshlrev_b32_e32 v38, 16, v13
	v_mul_f32_e32 v9, 0xbf38aa3b, v9
	v_exp_f32_e32 v45, v9
	v_fma_f32 v9, |v38|, s92, 1.0
	v_rcp_f32_e32 v46, v9
	v_mul_f32_e32 v9, v38, v38
	s_waitcnt vmcnt(0)
	v_lshlrev_b32_e32 v39, 16, v15
	v_mul_f32_e32 v9, 0xbf38aa3b, v9
	v_exp_f32_e32 v48, v9
	v_fma_f32 v9, |v39|, s92, 1.0
	v_rcp_f32_e32 v47, v9
	v_mul_f32_e32 v9, v39, v39
	v_mul_f32_e32 v9, 0xbf38aa3b, v9
	v_exp_f32_e32 v49, v9
	global_load_ushort v9, v7, s[58:59] offset:640
	global_load_ushort v11, v7, s[60:61] offset:640
	global_load_ushort v13, v7, s[56:57] offset:640
	global_load_ushort v15, v7, s[94:95] offset:640
	v_pk_fma_f32 v[50:51], v[42:43], s[12:13], v[18:19] op_sel_hi:[1,0,0]
	v_pk_fma_f32 v[52:53], v[46:47], s[12:13], v[18:19] op_sel_hi:[1,0,0]
	v_pk_fma_f32 v[50:51], v[42:43], v[50:51], s[14:15] op_sel_hi:[1,1,0]
	v_pk_fma_f32 v[52:53], v[46:47], v[52:53], s[14:15] op_sel_hi:[1,1,0]
	v_pk_fma_f32 v[50:51], v[42:43], v[50:51], s[16:17] op_sel_hi:[1,1,0]
	v_pk_fma_f32 v[52:53], v[46:47], v[52:53], s[16:17] op_sel_hi:[1,1,0]
	v_pk_fma_f32 v[50:51], v[42:43], v[50:51], s[18:19] op_sel_hi:[1,1,0]
	v_pk_fma_f32 v[52:53], v[46:47], v[52:53], s[18:19] op_sel_hi:[1,1,0]
	v_pk_mul_f32 v[42:43], v[42:43], v[50:51]
	v_pk_mul_f32 v[46:47], v[46:47], v[52:53]
	v_pk_mul_f32 v[42:43], v[44:45], v[42:43]
	v_pk_mul_f32 v[46:47], v[48:49], v[46:47]
	v_pk_mul_f32 v[44:45], v[42:43], v[40:41]
	v_pk_fma_f32 v[42:43], v[42:43], v[40:41], v[40:41] neg_lo:[1,0,0] neg_hi:[1,0,0]
	v_cmp_gt_f32_e32 vcc, 0, v40
	v_pk_mul_f32 v[48:49], v[46:47], v[38:39]
	v_pk_fma_f32 v[46:47], v[46:47], v[38:39], v[38:39] neg_lo:[1,0,0] neg_hi:[1,0,0]
	v_cmp_gt_f32_e64 s[44:45], 0, v38
	v_cndmask_b32_e32 v38, v42, v44, vcc
	v_cmp_gt_f32_e64 s[42:43], 0, v41
	v_cndmask_b32_e64 v40, v46, v48, s[44:45]
	v_cmp_gt_f32_e64 s[46:47], 0, v39
	v_cndmask_b32_e64 v39, v43, v45, s[42:43]
	s_waitcnt vmcnt(3)
	v_lshlrev_b32_e32 v44, 16, v9
	v_fma_f32 v9, |v44|, s92, 1.0
	v_rcp_f32_e32 v46, v9
	v_mul_f32_e32 v9, v44, v44
	s_waitcnt vmcnt(2)
	v_lshlrev_b32_e32 v45, 16, v11
	v_mul_f32_e32 v9, 0xbf38aa3b, v9
	v_exp_f32_e32 v48, v9
	v_fma_f32 v9, |v45|, s92, 1.0
	v_cndmask_b32_e64 v41, v47, v49, s[46:47]
	v_rcp_f32_e32 v47, v9
	v_mul_f32_e32 v9, v45, v45
	s_waitcnt vmcnt(1)
	v_lshlrev_b32_e32 v42, 16, v13
	v_mul_f32_e32 v9, 0xbf38aa3b, v9
	v_exp_f32_e32 v49, v9
	v_fma_f32 v9, |v42|, s92, 1.0
	v_rcp_f32_e32 v50, v9
	v_mul_f32_e32 v9, v42, v42
	s_waitcnt vmcnt(0)
	v_lshlrev_b32_e32 v43, 16, v15
	v_mul_f32_e32 v9, 0xbf38aa3b, v9
	v_exp_f32_e32 v52, v9
	v_fma_f32 v9, |v43|, s92, 1.0
	v_rcp_f32_e32 v51, v9
	v_mul_f32_e32 v9, v43, v43
	v_mul_f32_e32 v9, 0xbf38aa3b, v9
	v_exp_f32_e32 v53, v9
	global_load_ushort v9, v7, s[58:59] offset:768
	global_load_ushort v11, v7, s[60:61] offset:768
	global_load_ushort v13, v7, s[56:57] offset:768
	global_load_ushort v15, v7, s[94:95] offset:768
	v_pk_fma_f32 v[54:55], v[46:47], s[12:13], v[18:19] op_sel_hi:[1,0,0]
	v_pk_fma_f32 v[56:57], v[50:51], s[12:13], v[18:19] op_sel_hi:[1,0,0]
	v_pk_fma_f32 v[54:55], v[46:47], v[54:55], s[14:15] op_sel_hi:[1,1,0]
	v_pk_fma_f32 v[56:57], v[50:51], v[56:57], s[14:15] op_sel_hi:[1,1,0]
	v_pk_fma_f32 v[54:55], v[46:47], v[54:55], s[16:17] op_sel_hi:[1,1,0]
	v_pk_fma_f32 v[56:57], v[50:51], v[56:57], s[16:17] op_sel_hi:[1,1,0]
	v_pk_fma_f32 v[54:55], v[46:47], v[54:55], s[18:19] op_sel_hi:[1,1,0]
	v_pk_fma_f32 v[56:57], v[50:51], v[56:57], s[18:19] op_sel_hi:[1,1,0]
	v_pk_mul_f32 v[46:47], v[46:47], v[54:55]
	v_pk_mul_f32 v[50:51], v[50:51], v[56:57]
	v_pk_mul_f32 v[46:47], v[48:49], v[46:47]
	v_cmp_gt_f32_e32 vcc, 0, v44
	v_pk_mul_f32 v[48:49], v[46:47], v[44:45]
	v_pk_fma_f32 v[46:47], v[46:47], v[44:45], v[44:45] neg_lo:[1,0,0] neg_hi:[1,0,0]
	v_pk_mul_f32 v[50:51], v[52:53], v[50:51]
	v_cndmask_b32_e32 v44, v46, v48, vcc
	v_pk_mul_f32 v[52:53], v[50:51], v[42:43]
	v_pk_fma_f32 v[50:51], v[50:51], v[42:43], v[42:43] neg_lo:[1,0,0] neg_hi:[1,0,0]
	v_cmp_gt_f32_e64 s[44:45], 0, v42
	v_cmp_gt_f32_e64 s[42:43], 0, v45
	v_cmp_gt_f32_e64 s[46:47], 0, v43
	v_cndmask_b32_e64 v42, v50, v52, s[44:45]
	v_cndmask_b32_e64 v45, v47, v49, s[42:43]
	v_cndmask_b32_e64 v43, v51, v53, s[46:47]
	s_waitcnt vmcnt(3)
	v_lshlrev_b32_e32 v48, 16, v9
	v_fma_f32 v9, |v48|, s92, 1.0
	v_rcp_f32_e32 v50, v9
	v_mul_f32_e32 v9, v48, v48
	s_waitcnt vmcnt(2)
	v_lshlrev_b32_e32 v49, 16, v11
	v_mul_f32_e32 v9, 0xbf38aa3b, v9
	v_exp_f32_e32 v52, v9
	v_fma_f32 v9, |v49|, s92, 1.0
	v_rcp_f32_e32 v51, v9
	v_mul_f32_e32 v9, v49, v49
	s_waitcnt vmcnt(1)
	v_lshlrev_b32_e32 v46, 16, v13
	v_mul_f32_e32 v9, 0xbf38aa3b, v9
	v_exp_f32_e32 v53, v9
	v_fma_f32 v9, |v46|, s92, 1.0
	v_rcp_f32_e32 v54, v9
	v_mul_f32_e32 v9, v46, v46
	s_waitcnt vmcnt(0)
	v_lshlrev_b32_e32 v47, 16, v15
	v_mul_f32_e32 v9, 0xbf38aa3b, v9
	v_exp_f32_e32 v56, v9
	v_fma_f32 v9, |v47|, s92, 1.0
	v_rcp_f32_e32 v55, v9
	v_mul_f32_e32 v9, v47, v47
	v_mul_f32_e32 v9, 0xbf38aa3b, v9
	v_exp_f32_e32 v57, v9
	global_load_ushort v9, v7, s[58:59] offset:896
	global_load_ushort v11, v7, s[60:61] offset:896
	global_load_ushort v13, v7, s[56:57] offset:896
	global_load_ushort v15, v7, s[94:95] offset:896
	v_pk_fma_f32 v[58:59], v[50:51], s[12:13], v[18:19] op_sel_hi:[1,0,0]
	v_pk_fma_f32 v[60:61], v[54:55], s[12:13], v[18:19] op_sel_hi:[1,0,0]
	v_pk_fma_f32 v[58:59], v[50:51], v[58:59], s[14:15] op_sel_hi:[1,1,0]
	v_pk_fma_f32 v[60:61], v[54:55], v[60:61], s[14:15] op_sel_hi:[1,1,0]
	v_pk_fma_f32 v[58:59], v[50:51], v[58:59], s[16:17] op_sel_hi:[1,1,0]
	v_pk_fma_f32 v[60:61], v[54:55], v[60:61], s[16:17] op_sel_hi:[1,1,0]
	v_pk_fma_f32 v[58:59], v[50:51], v[58:59], s[18:19] op_sel_hi:[1,1,0]
	v_pk_fma_f32 v[60:61], v[54:55], v[60:61], s[18:19] op_sel_hi:[1,1,0]
	v_pk_mul_f32 v[50:51], v[50:51], v[58:59]
	v_pk_mul_f32 v[54:55], v[54:55], v[60:61]
	v_pk_mul_f32 v[50:51], v[52:53], v[50:51]
	v_cmp_gt_f32_e32 vcc, 0, v48
	v_pk_mul_f32 v[52:53], v[50:51], v[48:49]
	v_pk_fma_f32 v[50:51], v[50:51], v[48:49], v[48:49] neg_lo:[1,0,0] neg_hi:[1,0,0]
	v_pk_mul_f32 v[54:55], v[56:57], v[54:55]
	v_cndmask_b32_e32 v48, v50, v52, vcc
	v_pk_mul_f32 v[56:57], v[54:55], v[46:47]
	v_pk_fma_f32 v[54:55], v[54:55], v[46:47], v[46:47] neg_lo:[1,0,0] neg_hi:[1,0,0]
	v_cmp_gt_f32_e64 s[44:45], 0, v46
	v_cmp_gt_f32_e64 s[42:43], 0, v49
	v_cmp_gt_f32_e64 s[46:47], 0, v47
	v_cndmask_b32_e64 v46, v54, v56, s[44:45]
	v_cndmask_b32_e64 v49, v51, v53, s[42:43]
	v_cndmask_b32_e64 v47, v55, v57, s[46:47]
	global_load_ushort v68, v7, s[48:49] offset:512
	global_load_ushort v69, v7, s[50:51] offset:512
	global_load_ushort v70, v7, s[54:55] offset:512
	global_load_ushort v71, v7, s[66:67] offset:512
	global_load_ushort v72, v7, s[48:49] offset:640
	global_load_ushort v73, v7, s[50:51] offset:640
	global_load_ushort v74, v7, s[54:55] offset:640
	global_load_ushort v75, v7, s[66:67] offset:640
	global_load_ushort v76, v7, s[48:49] offset:768
	global_load_ushort v77, v7, s[50:51] offset:768
	global_load_ushort v78, v7, s[54:55] offset:768
	global_load_ushort v79, v7, s[66:67] offset:768
	global_load_ushort v80, v7, s[48:49] offset:896
	global_load_ushort v81, v7, s[50:51] offset:896
	global_load_ushort v82, v7, s[54:55] offset:896
	global_load_ushort v83, v7, s[66:67] offset:896
	s_mov_b32 s60, s19
	s_mov_b32 s66, s13
	s_waitcnt vmcnt(19)
	v_lshlrev_b32_e32 v52, 16, v9
	v_fma_f32 v9, |v52|, s92, 1.0
	v_rcp_f32_e32 v54, v9
	v_mul_f32_e32 v9, v52, v52
	s_waitcnt vmcnt(18)
	v_lshlrev_b32_e32 v53, 16, v11
	v_mul_f32_e32 v9, 0xbf38aa3b, v9
	v_exp_f32_e32 v56, v9
	v_fma_f32 v9, |v53|, s92, 1.0
	v_rcp_f32_e32 v55, v9
	v_mul_f32_e32 v9, v53, v53
	s_waitcnt vmcnt(17)
	v_lshlrev_b32_e32 v50, 16, v13
	v_mul_f32_e32 v9, 0xbf38aa3b, v9
	v_exp_f32_e32 v57, v9
	v_fma_f32 v9, |v50|, s92, 1.0
	v_rcp_f32_e32 v58, v9
	v_mul_f32_e32 v9, v50, v50
	s_waitcnt vmcnt(16)
	v_lshlrev_b32_e32 v51, 16, v15
	v_mul_f32_e32 v9, 0xbf38aa3b, v9
	v_exp_f32_e32 v60, v9
	v_fma_f32 v9, |v51|, s92, 1.0
	v_rcp_f32_e32 v59, v9
	v_pk_fma_f32 v[62:63], v[54:55], s[12:13], v[18:19] op_sel_hi:[1,0,0]
	v_mul_f32_e32 v9, v51, v51
	v_pk_fma_f32 v[62:63], v[54:55], v[62:63], s[14:15] op_sel_hi:[1,1,0]
	v_pk_fma_f32 v[64:65], v[58:59], s[12:13], v[18:19] op_sel_hi:[1,0,0]
	v_pk_fma_f32 v[62:63], v[54:55], v[62:63], s[16:17] op_sel_hi:[1,1,0]
	v_mul_f32_e32 v9, 0xbf38aa3b, v9
	v_pk_fma_f32 v[64:65], v[58:59], v[64:65], s[14:15] op_sel_hi:[1,1,0]
	v_pk_fma_f32 v[62:63], v[54:55], v[62:63], s[18:19] op_sel_hi:[1,1,0]
	v_exp_f32_e32 v61, v9
	v_pk_fma_f32 v[64:65], v[58:59], v[64:65], s[16:17] op_sel_hi:[1,1,0]
	v_pk_mul_f32 v[54:55], v[54:55], v[62:63]
	v_pk_fma_f32 v[64:65], v[58:59], v[64:65], s[18:19] op_sel_hi:[1,1,0]
	v_pk_mul_f32 v[54:55], v[56:57], v[54:55]
	v_pk_mul_f32 v[58:59], v[58:59], v[64:65]
	v_pk_mul_f32 v[56:57], v[54:55], v[52:53]
	v_pk_fma_f32 v[54:55], v[54:55], v[52:53], v[52:53] neg_lo:[1,0,0] neg_hi:[1,0,0]
	v_cmp_gt_f32_e32 vcc, 0, v52
	v_pk_mul_f32 v[58:59], v[60:61], v[58:59]
	v_cmp_gt_f32_e64 s[42:43], 0, v53
	v_cndmask_b32_e32 v52, v54, v56, vcc
	v_pk_mul_f32 v[60:61], v[58:59], v[50:51]
	v_pk_fma_f32 v[58:59], v[58:59], v[50:51], v[50:51] neg_lo:[1,0,0] neg_hi:[1,0,0]
	v_cmp_gt_f32_e64 s[44:45], 0, v50
	v_cmp_gt_f32_e64 s[46:47], 0, v51
	v_cndmask_b32_e64 v53, v55, v57, s[42:43]
	v_mov_b32_e32 v54, v38
	v_mov_b32_e32 v55, v48
	v_mov_b32_e32 v56, v44
	v_mov_b32_e32 v57, v52
	v_cndmask_b32_e64 v51, v59, v61, s[46:47]
	v_cndmask_b32_e64 v50, v58, v60, s[44:45]
	v_pk_add_f32 v[60:61], v[54:55], v[56:57]
	v_mov_b32_e32 v11, v131
	v_add_f32_e32 v9, v60, v61
	v_mov_b32_e32 v54, v39
	v_mov_b32_e32 v55, v49
	v_add_f32_dpp v9, v9, v9 quad_perm:[1,0,3,2] row_mask:0xf bank_mask:0xf bound_ctrl:1
	v_mov_b32_e32 v56, v45
	v_mov_b32_e32 v57, v53
	v_add_f32_dpp v9, v9, v9 quad_perm:[2,3,0,1] row_mask:0xf bank_mask:0xf bound_ctrl:1
	v_pk_add_f32 v[58:59], v[54:55], v[56:57]
	v_mov_b32_e32 v54, v40
	v_add_f32_dpp v9, v9, v9 row_half_mirror row_mask:0xf bank_mask:0xf bound_ctrl:1
	v_mov_b32_e32 v55, v46
	v_mov_b32_e32 v56, v42
	v_add_f32_dpp v9, v9, v9 row_mirror row_mask:0xf bank_mask:0xf bound_ctrl:1
	v_mov_b32_e32 v57, v50
	v_pk_add_f32 v[56:57], v[54:55], v[56:57]
	v_mov_b32_dpp v11, v9 row_bcast:15 row_mask:0xa bank_mask:0xf
	v_add_f32_e32 v9, v9, v11
	v_mov_b32_e32 v11, v131
	v_mov_b32_e32 v54, v41
	v_mov_b32_e32 v55, v47
	v_mov_b32_dpp v11, v9 row_bcast:31 row_mask:0xc bank_mask:0xf
	v_add_f32_e32 v9, v9, v11
	v_mov_b32_e32 v11, v131
	v_readlane_b32 s6, v9, 63
	v_add_f32_e32 v9, v58, v59
	v_mov_b32_e32 v62, v43
	v_mov_b32_e32 v63, v51
	v_add_f32_dpp v9, v9, v9 quad_perm:[1,0,3,2] row_mask:0xf bank_mask:0xf bound_ctrl:1
	v_pk_add_f32 v[54:55], v[54:55], v[62:63]
	s_xor_b32 s6, s6, 0x80000000
	v_add_f32_dpp v9, v9, v9 quad_perm:[2,3,0,1] row_mask:0xf bank_mask:0xf bound_ctrl:1
	v_cvt_pk_bf16_f32 v63, v34, v35
	v_cvt_pk_bf16_f32 v62, v36, v37
	v_add_f32_dpp v9, v9, v9 row_half_mirror row_mask:0xf bank_mask:0xf bound_ctrl:1
	s_nop 1
	v_add_f32_dpp v9, v9, v9 row_mirror row_mask:0xf bank_mask:0xf bound_ctrl:1
	s_nop 1
	v_mov_b32_dpp v11, v9 row_bcast:15 row_mask:0xa bank_mask:0xf
	v_add_f32_e32 v9, v9, v11
	v_mov_b32_e32 v11, v131
	s_nop 1
	v_mov_b32_dpp v11, v9 row_bcast:31 row_mask:0xc bank_mask:0xf
	v_add_f32_e32 v9, v9, v11
	v_mov_b32_e32 v11, v131
	v_readlane_b32 s7, v9, 63
	v_add_f32_e32 v9, v56, v57
	s_xor_b32 s7, s7, 0x80000000
	v_pk_fma_f32 v[56:57], s[6:7], v[20:21], v[44:45] op_sel_hi:[1,0,1]
	v_add_f32_dpp v9, v9, v9 quad_perm:[1,0,3,2] row_mask:0xf bank_mask:0xf bound_ctrl:1
	v_pk_fma_f32 v[60:61], s[6:7], v[20:21], v[38:39] op_sel_hi:[1,0,1]
	v_pk_fma_f32 v[44:45], s[6:7], v[20:21], v[48:49] op_sel_hi:[1,0,1]
	v_add_f32_dpp v9, v9, v9 quad_perm:[2,3,0,1] row_mask:0xf bank_mask:0xf bound_ctrl:1
	v_mov_b32_e32 v48, v56
	s_nop 0
	v_add_f32_dpp v9, v9, v9 row_half_mirror row_mask:0xf bank_mask:0xf bound_ctrl:1
	s_nop 1
	v_add_f32_dpp v9, v9, v9 row_mirror row_mask:0xf bank_mask:0xf bound_ctrl:1
	s_nop 1
	v_mov_b32_dpp v11, v9 row_bcast:15 row_mask:0xa bank_mask:0xf
	v_add_f32_e32 v9, v9, v11
	v_mov_b32_e32 v11, v131
	s_nop 1
	v_mov_b32_dpp v11, v9 row_bcast:31 row_mask:0xc bank_mask:0xf
	v_add_f32_e32 v9, v9, v11
	v_mov_b32_e32 v11, v131
	v_readlane_b32 s8, v9, 63
	v_add_f32_e32 v9, v54, v55
	s_xor_b32 s8, s8, 0x80000000
	s_nop 0
	v_add_f32_dpp v9, v9, v9 quad_perm:[1,0,3,2] row_mask:0xf bank_mask:0xf bound_ctrl:1
	s_nop 1
	v_add_f32_dpp v9, v9, v9 quad_perm:[2,3,0,1] row_mask:0xf bank_mask:0xf bound_ctrl:1
	s_nop 1
	v_add_f32_dpp v9, v9, v9 row_half_mirror row_mask:0xf bank_mask:0xf bound_ctrl:1
	s_nop 1
	v_add_f32_dpp v9, v9, v9 row_mirror row_mask:0xf bank_mask:0xf bound_ctrl:1
	s_nop 1
	v_mov_b32_dpp v11, v9 row_bcast:15 row_mask:0xa bank_mask:0xf
	v_add_f32_e32 v9, v9, v11
	v_mov_b32_e32 v11, v131
	s_nop 1
	v_mov_b32_dpp v11, v9 row_bcast:31 row_mask:0xc bank_mask:0xf
	v_add_f32_e32 v9, v9, v11
	v_mov_b32_e32 v11, v131
	v_readlane_b32 s9, v9, 63
	s_xor_b32 s9, s9, 0x80000000
	s_nop 0
	v_pk_fma_f32 v[58:59], s[8:9], v[20:21], v[40:41] op_sel_hi:[1,0,1]
	v_pk_fma_f32 v[40:41], s[6:7], v[20:21], v[52:53] op_sel_hi:[1,0,1]
	v_pk_fma_f32 v[54:55], s[8:9], v[20:21], v[42:43] op_sel_hi:[1,0,1]
	v_mov_b32_e32 v49, v40
	v_pk_fma_f32 v[42:43], s[8:9], v[20:21], v[46:47] op_sel_hi:[1,0,1]
	v_mov_b32_e32 v46, v60
	v_mov_b32_e32 v47, v44
	v_pk_mul_f32 v[48:49], v[48:49], v[48:49]
	v_pk_fma_f32 v[38:39], s[8:9], v[20:21], v[50:51] op_sel_hi:[1,0,1]
	v_pk_fma_f32 v[46:47], v[46:47], v[46:47], v[48:49]
	v_mov_b32_e32 v50, v57
	v_add_f32_e32 v9, v46, v47
	v_mov_b32_e32 v51, v41
	v_mov_b32_e32 v48, v61
	v_add_f32_dpp v9, v9, v9 quad_perm:[1,0,3,2] row_mask:0xf bank_mask:0xf bound_ctrl:1
	v_mov_b32_e32 v49, v45
	v_pk_mul_f32 v[50:51], v[50:51], v[50:51]
	v_add_f32_dpp v9, v9, v9 quad_perm:[2,3,0,1] row_mask:0xf bank_mask:0xf bound_ctrl:1
	v_pk_fma_f32 v[48:49], v[48:49], v[48:49], v[50:51]
	v_mov_b32_e32 v50, v54
	v_add_f32_dpp v9, v9, v9 row_half_mirror row_mask:0xf bank_mask:0xf bound_ctrl:1
	v_mov_b32_e32 v51, v38
	v_pk_mul_f32 v[50:51], v[50:51], v[50:51]
	v_add_f32_dpp v9, v9, v9 row_mirror row_mask:0xf bank_mask:0xf bound_ctrl:1
	s_nop 1
	v_mov_b32_dpp v11, v9 row_bcast:15 row_mask:0xa bank_mask:0xf
	v_add_f32_e32 v9, v9, v11
	v_mov_b32_e32 v11, v131
	s_nop 1
	v_mov_b32_dpp v11, v9 row_bcast:31 row_mask:0xc bank_mask:0xf
	v_add_f32_e32 v9, v9, v11
	v_mov_b32_e32 v11, v131
	v_readlane_b32 s6, v9, 63
	s_nop 1
	v_fma_f32 v9, s6, v235, v225
	v_rsq_f32_e32 v46, v9
	v_add_f32_e32 v9, v48, v49
	v_mov_b32_e32 v48, v58
	v_mov_b32_e32 v49, v42
	v_add_f32_dpp v9, v9, v9 quad_perm:[1,0,3,2] row_mask:0xf bank_mask:0xf bound_ctrl:1
	v_pk_fma_f32 v[48:49], v[48:49], v[48:49], v[50:51]
	v_mov_b32_e32 v50, v55
	v_add_f32_dpp v9, v9, v9 quad_perm:[2,3,0,1] row_mask:0xf bank_mask:0xf bound_ctrl:1
	v_mov_b32_e32 v51, v39
	v_pk_mul_f32 v[50:51], v[50:51], v[50:51]
	v_add_f32_dpp v9, v9, v9 row_half_mirror row_mask:0xf bank_mask:0xf bound_ctrl:1
	s_nop 1
	v_add_f32_dpp v9, v9, v9 row_mirror row_mask:0xf bank_mask:0xf bound_ctrl:1
	s_nop 1
	v_mov_b32_dpp v11, v9 row_bcast:15 row_mask:0xa bank_mask:0xf
	v_add_f32_e32 v9, v9, v11
	v_mov_b32_e32 v11, v131
	s_nop 1
	v_mov_b32_dpp v11, v9 row_bcast:31 row_mask:0xc bank_mask:0xf
	v_add_f32_e32 v9, v9, v11
	v_mov_b32_e32 v11, v131
	v_readlane_b32 s6, v9, 63
	s_nop 1
	v_fma_f32 v9, s6, v235, v225
	v_rsq_f32_e32 v47, v9
	v_add_f32_e32 v9, v48, v49
	v_mov_b32_e32 v48, v59
	v_mov_b32_e32 v49, v43
	v_add_f32_dpp v9, v9, v9 quad_perm:[1,0,3,2] row_mask:0xf bank_mask:0xf bound_ctrl:1
	v_pk_fma_f32 v[48:49], v[48:49], v[48:49], v[50:51]
	v_pk_mul_f32 v[34:35], v[56:57], v[46:47]
	v_add_f32_dpp v9, v9, v9 quad_perm:[2,3,0,1] row_mask:0xf bank_mask:0xf bound_ctrl:1
	s_nop 1
	v_add_f32_dpp v9, v9, v9 row_half_mirror row_mask:0xf bank_mask:0xf bound_ctrl:1
	s_nop 1
	v_add_f32_dpp v9, v9, v9 row_mirror row_mask:0xf bank_mask:0xf bound_ctrl:1
	s_nop 1
	v_mov_b32_dpp v11, v9 row_bcast:15 row_mask:0xa bank_mask:0xf
	v_add_f32_e32 v9, v9, v11
	v_mov_b32_e32 v11, v131
	s_nop 1
	v_mov_b32_dpp v11, v9 row_bcast:31 row_mask:0xc bank_mask:0xf
	v_add_f32_e32 v9, v9, v11
	v_mov_b32_e32 v11, v131
	v_readlane_b32 s6, v9, 63
	s_nop 1
	v_fma_f32 v9, s6, v235, v225
	v_rsq_f32_e32 v66, v9
	v_add_f32_e32 v9, v48, v49
	v_pk_mul_f32 v[48:49], v[60:61], v[46:47]
	s_nop 0
	v_add_f32_dpp v9, v9, v9 quad_perm:[1,0,3,2] row_mask:0xf bank_mask:0xf bound_ctrl:1
	v_pk_fma_f32 v[48:49], v[14:15], v[48:49], v[16:17] op_sel_hi:[0,1,0]
	v_cvt_pk_bf16_f32 v64, v48, v49
	v_add_f32_dpp v9, v9, v9 quad_perm:[2,3,0,1] row_mask:0xf bank_mask:0xf bound_ctrl:1
	s_nop 1
	v_add_f32_dpp v9, v9, v9 row_half_mirror row_mask:0xf bank_mask:0xf bound_ctrl:1
	s_nop 1
	v_add_f32_dpp v9, v9, v9 row_mirror row_mask:0xf bank_mask:0xf bound_ctrl:1
	s_nop 1
	v_mov_b32_dpp v11, v9 row_bcast:15 row_mask:0xa bank_mask:0xf
	v_add_f32_e32 v9, v9, v11
	v_mov_b32_e32 v11, v131
	s_nop 1
	v_mov_b32_dpp v11, v9 row_bcast:31 row_mask:0xc bank_mask:0xf
	v_add_f32_e32 v9, v9, v11
	s_nop 0
	v_readlane_b32 s6, v9, 63
	s_nop 1
	v_fma_f32 v9, s6, v235, v225
	v_rsq_f32_e32 v67, v9
	s_nop 0
	v_pk_mul_f32 v[50:51], v[58:59], v[66:67]
	v_pk_fma_f32 v[50:51], v[14:15], v[50:51], v[16:17] op_sel_hi:[0,1,0]
	v_cvt_pk_bf16_f32 v65, v50, v51
	global_load_ushort v58, v7, s[52:53] offset:512
	global_load_ushort v59, v7, s[64:65] offset:512
	global_load_ushort v60, v7, s[68:69] offset:512
	global_load_ushort v61, v7, s[72:73] offset:512
	global_load_ushort v50, v7, s[52:53] offset:640
	global_load_ushort v51, v7, s[64:65] offset:640
	global_load_ushort v52, v7, s[68:69] offset:640
	global_load_ushort v53, v7, s[72:73] offset:640
	global_load_ushort v15, v7, s[52:53] offset:768
	global_load_ushort v17, v7, s[64:65] offset:768
	global_load_ushort v48, v7, s[68:69] offset:768
	global_load_ushort v49, v7, s[72:73] offset:768
	global_load_ushort v9, v7, s[52:53] offset:896
	global_load_ushort v11, v7, s[64:65] offset:896
	global_load_ushort v13, v7, s[68:69] offset:896
	s_nop 0
	global_load_ushort v7, v7, s[72:73] offset:896
	v_pk_mul_f32 v[36:37], v[54:55], v[66:67]
	ds_write_b128 v5, v[62:65]
	s_waitcnt vmcnt(1)
	v_pk_fma_f32 v[36:37], v[10:11], v[36:37], v[12:13] op_sel_hi:[0,1,0]
	v_pk_fma_f32 v[34:35], v[10:11], v[34:35], v[12:13] op_sel_hi:[0,1,0]
	v_cvt_pk_bf16_f32 v37, v36, v37
	v_cvt_pk_bf16_f32 v36, v34, v35
	v_cvt_pk_bf16_f32 v35, v30, v31
	v_cvt_pk_bf16_f32 v34, v32, v33
	v_pk_mul_f32 v[30:31], v[44:45], v[46:47]
	v_pk_mul_f32 v[32:33], v[42:43], v[66:67]
	s_waitcnt vmcnt(0)
	v_pk_fma_f32 v[30:31], v[6:7], v[30:31], v[8:9] op_sel_hi:[0,1,0]
	v_pk_fma_f32 v[32:33], v[6:7], v[32:33], v[8:9] op_sel_hi:[0,1,0]
	v_cvt_pk_bf16_f32 v33, v32, v33
	v_cvt_pk_bf16_f32 v32, v30, v31
	v_cvt_pk_bf16_f32 v31, v26, v27
	v_cvt_pk_bf16_f32 v30, v28, v29
	v_pk_mul_f32 v[26:27], v[40:41], v[46:47]
	v_pk_mul_f32 v[28:29], v[38:39], v[66:67]
	v_pk_fma_f32 v[26:27], v[2:3], v[26:27], v[4:5] op_sel_hi:[0,1,0]
	v_pk_fma_f32 v[28:29], v[2:3], v[28:29], v[4:5] op_sel_hi:[0,1,0]
	v_cvt_pk_bf16_f32 v29, v28, v29
	v_cvt_pk_bf16_f32 v28, v26, v27
	v_cvt_pk_bf16_f32 v27, v22, v23
	v_cvt_pk_bf16_f32 v26, v24, v25
	v_lshlrev_b32_e32 v24, 16, v68
	ds_write_b128 v5, v[26:29] offset:52224
	v_lshlrev_b32_e32 v22, 16, v70
	v_mul_f32_e32 v27, v24, v24
	ds_write_b128 v5, v[30:33] offset:34816
	v_lshlrev_b32_e32 v25, 16, v69
	v_mul_f32_e32 v27, 0xbf38aa3b, v27
	v_mul_f32_e32 v31, v22, v22
	v_lshlrev_b32_e32 v23, 16, v71
	v_fma_f32 v26, |v24|, s92, 1.0
	v_exp_f32_e32 v28, v27
	v_fma_f32 v27, |v25|, s92, 1.0
	v_mul_f32_e32 v31, 0xbf38aa3b, v31
	v_rcp_f32_e32 v26, v26
	v_rcp_f32_e32 v27, v27
	v_fma_f32 v30, |v22|, s92, 1.0
	v_exp_f32_e32 v32, v31
	v_fma_f32 v31, |v23|, s92, 1.0
	v_rcp_f32_e32 v30, v30
	v_rcp_f32_e32 v31, v31
	v_mul_f32_e32 v29, v25, v25
	ds_write_b128 v5, v[34:37] offset:17408
	v_mul_f32_e32 v29, 0xbf38aa3b, v29
	v_pk_fma_f32 v[34:35], v[26:27], s[12:13], v[18:19] op_sel_hi:[1,0,0]
	v_mul_f32_e32 v33, v23, v23
	v_exp_f32_e32 v29, v29
	v_pk_fma_f32 v[36:37], v[30:31], s[12:13], v[18:19] op_sel_hi:[1,0,0]
	v_pk_fma_f32 v[34:35], v[26:27], v[34:35], s[14:15] op_sel_hi:[1,1,0]
	v_mul_f32_e32 v33, 0xbf38aa3b, v33
	v_pk_fma_f32 v[36:37], v[30:31], v[36:37], s[14:15] op_sel_hi:[1,1,0]
	v_pk_fma_f32 v[34:35], v[26:27], v[34:35], s[16:17] op_sel_hi:[1,1,0]
	v_exp_f32_e32 v33, v33
	v_pk_fma_f32 v[36:37], v[30:31], v[36:37], s[16:17] op_sel_hi:[1,1,0]
	v_pk_fma_f32 v[34:35], v[26:27], v[34:35], s[18:19] op_sel_hi:[1,1,0]
	v_pk_fma_f32 v[36:37], v[30:31], v[36:37], s[18:19] op_sel_hi:[1,1,0]
	v_pk_mul_f32 v[26:27], v[26:27], v[34:35]
	v_pk_mul_f32 v[30:31], v[30:31], v[36:37]
	v_pk_mul_f32 v[26:27], v[28:29], v[26:27]
	v_pk_mul_f32 v[30:31], v[32:33], v[30:31]
	v_pk_mul_f32 v[28:29], v[26:27], v[24:25]
	v_pk_fma_f32 v[26:27], v[26:27], v[24:25], v[24:25] neg_lo:[1,0,0] neg_hi:[1,0,0]
	v_cmp_gt_f32_e32 vcc, 0, v24
	v_pk_mul_f32 v[32:33], v[30:31], v[22:23]
	v_pk_fma_f32 v[30:31], v[30:31], v[22:23], v[22:23] neg_lo:[1,0,0] neg_hi:[1,0,0]
	v_cmp_gt_f32_e64 s[44:45], 0, v22
	v_cmp_gt_f32_e64 s[46:47], 0, v23
	v_cndmask_b32_e32 v22, v26, v28, vcc
	v_lshlrev_b32_e32 v28, 16, v72
	v_cmp_gt_f32_e64 s[42:43], 0, v25
	v_cndmask_b32_e64 v25, v31, v33, s[46:47]
	v_lshlrev_b32_e32 v26, 16, v74
	v_mul_f32_e32 v31, v28, v28
	v_cndmask_b32_e64 v23, v27, v29, s[42:43]
	v_lshlrev_b32_e32 v29, 16, v73
	v_mul_f32_e32 v31, 0xbf38aa3b, v31
	v_mul_f32_e32 v35, v26, v26
	v_cndmask_b32_e64 v24, v30, v32, s[44:45]
	v_lshlrev_b32_e32 v27, 16, v75
	v_fma_f32 v30, |v28|, s92, 1.0
	v_exp_f32_e32 v32, v31
	v_fma_f32 v31, |v29|, s92, 1.0
	v_mul_f32_e32 v35, 0xbf38aa3b, v35
	v_rcp_f32_e32 v30, v30
	v_rcp_f32_e32 v31, v31
	v_fma_f32 v34, |v26|, s92, 1.0
	v_exp_f32_e32 v36, v35
	v_fma_f32 v35, |v27|, s92, 1.0
	v_rcp_f32_e32 v34, v34
	v_rcp_f32_e32 v35, v35
	v_mul_f32_e32 v33, v29, v29
	v_mul_f32_e32 v33, 0xbf38aa3b, v33
	v_pk_fma_f32 v[38:39], v[30:31], s[12:13], v[18:19] op_sel_hi:[1,0,0]
	v_mul_f32_e32 v37, v27, v27
	v_exp_f32_e32 v33, v33
	v_pk_fma_f32 v[40:41], v[34:35], s[12:13], v[18:19] op_sel_hi:[1,0,0]
	v_pk_fma_f32 v[38:39], v[30:31], v[38:39], s[14:15] op_sel_hi:[1,1,0]
	v_mul_f32_e32 v37, 0xbf38aa3b, v37
	v_pk_fma_f32 v[40:41], v[34:35], v[40:41], s[14:15] op_sel_hi:[1,1,0]
	v_pk_fma_f32 v[38:39], v[30:31], v[38:39], s[16:17] op_sel_hi:[1,1,0]
	v_exp_f32_e32 v37, v37
	v_pk_fma_f32 v[40:41], v[34:35], v[40:41], s[16:17] op_sel_hi:[1,1,0]
	v_pk_fma_f32 v[38:39], v[30:31], v[38:39], s[18:19] op_sel_hi:[1,1,0]
	v_pk_fma_f32 v[40:41], v[34:35], v[40:41], s[18:19] op_sel_hi:[1,1,0]
	v_pk_mul_f32 v[30:31], v[30:31], v[38:39]
	v_pk_mul_f32 v[34:35], v[34:35], v[40:41]
	v_pk_mul_f32 v[30:31], v[32:33], v[30:31]
	v_pk_mul_f32 v[34:35], v[36:37], v[34:35]
	v_pk_mul_f32 v[32:33], v[30:31], v[28:29]
	v_pk_fma_f32 v[30:31], v[30:31], v[28:29], v[28:29] neg_lo:[1,0,0] neg_hi:[1,0,0]
	v_cmp_gt_f32_e32 vcc, 0, v28
	v_pk_mul_f32 v[36:37], v[34:35], v[26:27]
	v_pk_fma_f32 v[34:35], v[34:35], v[26:27], v[26:27] neg_lo:[1,0,0] neg_hi:[1,0,0]
	v_cmp_gt_f32_e64 s[46:47], 0, v27
	v_cndmask_b32_e32 v28, v30, v32, vcc
	v_lshlrev_b32_e32 v32, 16, v76
	v_cmp_gt_f32_e64 s[42:43], 0, v29
	v_cndmask_b32_e64 v27, v35, v37, s[46:47]
	v_lshlrev_b32_e32 v30, 16, v78
	v_mul_f32_e32 v35, v32, v32
	v_cmp_gt_f32_e64 s[44:45], 0, v26
	v_cndmask_b32_e64 v29, v31, v33, s[42:43]
	v_lshlrev_b32_e32 v33, 16, v77
	v_mul_f32_e32 v35, 0xbf38aa3b, v35
	v_mul_f32_e32 v39, v30, v30
	v_cndmask_b32_e64 v26, v34, v36, s[44:45]
	v_lshlrev_b32_e32 v31, 16, v79
	v_fma_f32 v34, |v32|, s92, 1.0
	v_exp_f32_e32 v36, v35
	v_fma_f32 v35, |v33|, s92, 1.0
	v_mul_f32_e32 v39, 0xbf38aa3b, v39
	v_rcp_f32_e32 v34, v34
	v_rcp_f32_e32 v35, v35
	v_fma_f32 v38, |v30|, s92, 1.0
	v_exp_f32_e32 v40, v39
	v_fma_f32 v39, |v31|, s92, 1.0
	v_rcp_f32_e32 v38, v38
	v_rcp_f32_e32 v39, v39
	v_mul_f32_e32 v37, v33, v33
	v_mul_f32_e32 v37, 0xbf38aa3b, v37
	v_pk_fma_f32 v[42:43], v[34:35], s[12:13], v[18:19] op_sel_hi:[1,0,0]
	v_mul_f32_e32 v41, v31, v31
	v_exp_f32_e32 v37, v37
	v_pk_fma_f32 v[44:45], v[38:39], s[12:13], v[18:19] op_sel_hi:[1,0,0]
	v_pk_fma_f32 v[42:43], v[34:35], v[42:43], s[14:15] op_sel_hi:[1,1,0]
	v_mul_f32_e32 v41, 0xbf38aa3b, v41
	v_pk_fma_f32 v[44:45], v[38:39], v[44:45], s[14:15] op_sel_hi:[1,1,0]
	v_pk_fma_f32 v[42:43], v[34:35], v[42:43], s[16:17] op_sel_hi:[1,1,0]
	v_exp_f32_e32 v41, v41
	v_pk_fma_f32 v[44:45], v[38:39], v[44:45], s[16:17] op_sel_hi:[1,1,0]
	v_pk_fma_f32 v[42:43], v[34:35], v[42:43], s[18:19] op_sel_hi:[1,1,0]
	v_pk_fma_f32 v[44:45], v[38:39], v[44:45], s[18:19] op_sel_hi:[1,1,0]
	v_pk_mul_f32 v[34:35], v[34:35], v[42:43]
	v_pk_mul_f32 v[38:39], v[38:39], v[44:45]
	v_pk_mul_f32 v[34:35], v[36:37], v[34:35]
	v_pk_mul_f32 v[38:39], v[40:41], v[38:39]
	v_pk_mul_f32 v[36:37], v[34:35], v[32:33]
	v_pk_fma_f32 v[34:35], v[34:35], v[32:33], v[32:33] neg_lo:[1,0,0] neg_hi:[1,0,0]
	v_cmp_gt_f32_e32 vcc, 0, v32
	v_pk_mul_f32 v[40:41], v[38:39], v[30:31]
	v_pk_fma_f32 v[38:39], v[38:39], v[30:31], v[30:31] neg_lo:[1,0,0] neg_hi:[1,0,0]
	v_cmp_gt_f32_e64 s[46:47], 0, v31
	v_cndmask_b32_e32 v32, v34, v36, vcc
	v_lshlrev_b32_e32 v36, 16, v80
	v_cmp_gt_f32_e64 s[42:43], 0, v33
	v_cndmask_b32_e64 v31, v39, v41, s[46:47]
	v_mul_f32_e32 v39, v36, v36
	v_cmp_gt_f32_e64 s[44:45], 0, v30
	v_cndmask_b32_e64 v33, v35, v37, s[42:43]
	v_lshlrev_b32_e32 v34, 16, v82
	v_lshlrev_b32_e32 v37, 16, v81
	v_mul_f32_e32 v39, 0xbf38aa3b, v39
	v_cndmask_b32_e64 v30, v38, v40, s[44:45]
	v_fma_f32 v38, |v36|, s92, 1.0
	v_exp_f32_e32 v40, v39
	v_fma_f32 v39, |v37|, s92, 1.0
	v_mul_f32_e32 v43, v34, v34
	v_lshlrev_b32_e32 v35, 16, v83
	v_rcp_f32_e32 v38, v38
	v_rcp_f32_e32 v39, v39
	v_mul_f32_e32 v43, 0xbf38aa3b, v43
	v_fma_f32 v42, |v34|, s92, 1.0
	v_exp_f32_e32 v44, v43
	v_fma_f32 v43, |v35|, s92, 1.0
	v_rcp_f32_e32 v42, v42
	v_rcp_f32_e32 v43, v43
	v_mul_f32_e32 v41, v37, v37
	v_mul_f32_e32 v41, 0xbf38aa3b, v41
	v_pk_fma_f32 v[46:47], v[38:39], s[12:13], v[18:19] op_sel_hi:[1,0,0]
	v_exp_f32_e32 v41, v41
	v_pk_fma_f32 v[46:47], v[38:39], v[46:47], s[14:15] op_sel_hi:[1,1,0]
	v_mul_f32_e32 v45, v35, v35
	v_pk_fma_f32 v[54:55], v[42:43], s[12:13], v[18:19] op_sel_hi:[1,0,0]
	v_pk_fma_f32 v[46:47], v[38:39], v[46:47], s[16:17] op_sel_hi:[1,1,0]
	v_mul_f32_e32 v45, 0xbf38aa3b, v45
	v_pk_fma_f32 v[54:55], v[42:43], v[54:55], s[14:15] op_sel_hi:[1,1,0]
	v_pk_fma_f32 v[46:47], v[38:39], v[46:47], s[18:19] op_sel_hi:[1,1,0]
	v_exp_f32_e32 v45, v45
	v_pk_fma_f32 v[54:55], v[42:43], v[54:55], s[16:17] op_sel_hi:[1,1,0]
	v_pk_mul_f32 v[38:39], v[38:39], v[46:47]
	v_pk_fma_f32 v[54:55], v[42:43], v[54:55], s[18:19] op_sel_hi:[1,1,0]
	v_pk_mul_f32 v[38:39], v[40:41], v[38:39]
	v_pk_mul_f32 v[42:43], v[42:43], v[54:55]
	v_pk_mul_f32 v[40:41], v[38:39], v[36:37]
	v_pk_fma_f32 v[38:39], v[38:39], v[36:37], v[36:37] neg_lo:[1,0,0] neg_hi:[1,0,0]
	v_cmp_gt_f32_e32 vcc, 0, v36
	v_pk_mul_f32 v[42:43], v[44:45], v[42:43]
	v_cmp_gt_f32_e64 s[42:43], 0, v37
	v_cndmask_b32_e32 v36, v38, v40, vcc
	v_pk_mul_f32 v[44:45], v[42:43], v[34:35]
	v_pk_fma_f32 v[42:43], v[42:43], v[34:35], v[34:35] neg_lo:[1,0,0] neg_hi:[1,0,0]
	v_cmp_gt_f32_e64 s[44:45], 0, v34
	v_cmp_gt_f32_e64 s[46:47], 0, v35
	v_cndmask_b32_e64 v37, v39, v41, s[42:43]
	v_mov_b32_e32 v38, v22
	v_mov_b32_e32 v39, v32
	v_mov_b32_e32 v40, v28
	v_mov_b32_e32 v41, v36
	v_cndmask_b32_e64 v35, v43, v45, s[46:47]
	v_cndmask_b32_e64 v34, v42, v44, s[44:45]
	v_pk_add_f32 v[44:45], v[38:39], v[40:41]
	v_mov_b32_e32 v38, v23
	v_mov_b32_e32 v39, v33
	v_mov_b32_e32 v40, v29
	v_mov_b32_e32 v41, v37
	v_pk_add_f32 v[42:43], v[38:39], v[40:41]
	v_mov_b32_e32 v38, v24
	v_mov_b32_e32 v39, v30
	v_mov_b32_e32 v40, v26
	v_mov_b32_e32 v41, v34
	v_pk_add_f32 v[40:41], v[38:39], v[40:41]
	v_mov_b32_e32 v38, v25
	v_mov_b32_e32 v39, v31
	v_mov_b32_e32 v46, v27
	v_mov_b32_e32 v47, v35
	v_add_f32_e32 v44, v44, v45
	v_add_f32_e32 v42, v42, v43
	v_pk_add_f32 v[38:39], v[38:39], v[46:47]
	v_add_f32_dpp v44, v44, v44 quad_perm:[1,0,3,2] row_mask:0xf bank_mask:0xf bound_ctrl:1
	v_add_f32_dpp v42, v42, v42 quad_perm:[1,0,3,2] row_mask:0xf bank_mask:0xf bound_ctrl:1
	v_add_f32_e32 v40, v40, v41
	v_add_f32_dpp v44, v44, v44 quad_perm:[2,3,0,1] row_mask:0xf bank_mask:0xf bound_ctrl:1
	v_add_f32_dpp v42, v42, v42 quad_perm:[2,3,0,1] row_mask:0xf bank_mask:0xf bound_ctrl:1
	v_add_f32_e32 v38, v38, v39
	v_add_f32_dpp v44, v44, v44 row_half_mirror row_mask:0xf bank_mask:0xf bound_ctrl:1
	v_add_f32_dpp v42, v42, v42 row_half_mirror row_mask:0xf bank_mask:0xf bound_ctrl:1
	v_add_f32_dpp v40, v40, v40 quad_perm:[1,0,3,2] row_mask:0xf bank_mask:0xf bound_ctrl:1
	v_add_f32_dpp v38, v38, v38 quad_perm:[1,0,3,2] row_mask:0xf bank_mask:0xf bound_ctrl:1
	v_add_f32_dpp v44, v44, v44 row_mirror row_mask:0xf bank_mask:0xf bound_ctrl:1
	v_mov_b32_e32 v45, v131
	v_add_f32_dpp v42, v42, v42 row_mirror row_mask:0xf bank_mask:0xf bound_ctrl:1
	v_mov_b32_e32 v43, v131
	v_add_f32_dpp v40, v40, v40 quad_perm:[2,3,0,1] row_mask:0xf bank_mask:0xf bound_ctrl:1
	v_add_f32_dpp v38, v38, v38 quad_perm:[2,3,0,1] row_mask:0xf bank_mask:0xf bound_ctrl:1
	v_mov_b32_dpp v45, v44 row_bcast:15 row_mask:0xa bank_mask:0xf
	v_mov_b32_dpp v43, v42 row_bcast:15 row_mask:0xa bank_mask:0xf
	v_add_f32_dpp v40, v40, v40 row_half_mirror row_mask:0xf bank_mask:0xf bound_ctrl:1
	v_add_f32_dpp v38, v38, v38 row_half_mirror row_mask:0xf bank_mask:0xf bound_ctrl:1
	v_add_f32_e32 v44, v44, v45
	v_mov_b32_e32 v45, v131
	v_add_f32_e32 v42, v42, v43
	v_mov_b32_e32 v43, v131
	v_add_f32_dpp v40, v40, v40 row_mirror row_mask:0xf bank_mask:0xf bound_ctrl:1
	v_mov_b32_e32 v41, v131
	v_add_f32_dpp v38, v38, v38 row_mirror row_mask:0xf bank_mask:0xf bound_ctrl:1
	v_mov_b32_e32 v39, v131
	v_mov_b32_dpp v45, v44 row_bcast:31 row_mask:0xc bank_mask:0xf
	v_mov_b32_dpp v43, v42 row_bcast:31 row_mask:0xc bank_mask:0xf
	v_mov_b32_dpp v41, v40 row_bcast:15 row_mask:0xa bank_mask:0xf
	v_mov_b32_dpp v39, v38 row_bcast:15 row_mask:0xa bank_mask:0xf
	v_add_f32_e32 v44, v44, v45
	v_add_f32_e32 v42, v42, v43
	v_add_f32_e32 v40, v40, v41
	v_mov_b32_e32 v41, v131
	v_add_f32_e32 v38, v38, v39
	v_mov_b32_e32 v39, v131
	v_readlane_b32 s6, v44, 63
	v_readlane_b32 s7, v42, 63
	v_mov_b32_dpp v41, v40 row_bcast:31 row_mask:0xc bank_mask:0xf
	v_mov_b32_dpp v39, v38 row_bcast:31 row_mask:0xc bank_mask:0xf
	v_add_f32_e32 v40, v40, v41
	v_add_f32_e32 v38, v38, v39
	s_xor_b32 s7, s7, 0x80000000
	s_xor_b32 s6, s6, 0x80000000
	v_readlane_b32 s8, v40, 63
	v_readlane_b32 s9, v38, 63
	v_pk_fma_f32 v[42:43], s[6:7], v[20:21], v[28:29] op_sel_hi:[1,0,1]
	v_pk_fma_f32 v[38:39], s[6:7], v[20:21], v[36:37] op_sel_hi:[1,0,1]
	s_xor_b32 s9, s9, 0x80000000
	s_xor_b32 s8, s8, 0x80000000
	v_pk_fma_f32 v[44:45], s[6:7], v[20:21], v[22:23] op_sel_hi:[1,0,1]
	v_pk_fma_f32 v[28:29], s[6:7], v[20:21], v[32:33] op_sel_hi:[1,0,1]
	v_mov_b32_e32 v32, v42
	v_mov_b32_e32 v33, v38
	v_pk_fma_f32 v[40:41], s[8:9], v[20:21], v[24:25] op_sel_hi:[1,0,1]
	v_pk_fma_f32 v[24:25], s[8:9], v[20:21], v[30:31] op_sel_hi:[1,0,1]
	v_mov_b32_e32 v30, v44
	v_mov_b32_e32 v31, v28
	v_pk_mul_f32 v[32:33], v[32:33], v[32:33]
	v_pk_fma_f32 v[26:27], s[8:9], v[20:21], v[26:27] op_sel_hi:[1,0,1]
	v_pk_fma_f32 v[30:31], v[30:31], v[30:31], v[32:33]
	v_mov_b32_e32 v32, v43
	v_add_f32_e32 v30, v30, v31
	v_mov_b32_e32 v31, v131
	v_mov_b32_e32 v33, v39
	v_add_f32_dpp v30, v30, v30 quad_perm:[1,0,3,2] row_mask:0xf bank_mask:0xf bound_ctrl:1
	v_pk_mul_f32 v[32:33], v[32:33], v[32:33]
	v_pk_fma_f32 v[22:23], s[8:9], v[20:21], v[34:35] op_sel_hi:[1,0,1]
	v_add_f32_dpp v30, v30, v30 quad_perm:[2,3,0,1] row_mask:0xf bank_mask:0xf bound_ctrl:1
	s_nop 1
	v_add_f32_dpp v30, v30, v30 row_half_mirror row_mask:0xf bank_mask:0xf bound_ctrl:1
	s_nop 1
	v_add_f32_dpp v30, v30, v30 row_mirror row_mask:0xf bank_mask:0xf bound_ctrl:1
	s_nop 1
	v_mov_b32_dpp v31, v30 row_bcast:15 row_mask:0xa bank_mask:0xf
	v_add_f32_e32 v30, v30, v31
	v_mov_b32_e32 v31, v131
	s_nop 1
	v_mov_b32_dpp v31, v30 row_bcast:31 row_mask:0xc bank_mask:0xf
	v_add_f32_e32 v30, v30, v31
	v_mov_b32_e32 v31, v29
	v_readlane_b32 s6, v30, 63
	s_nop 1
	v_fma_f32 v30, s6, v235, v225
	v_rsq_f32_e32 v46, v30
	v_mov_b32_e32 v30, v45
	v_pk_fma_f32 v[30:31], v[30:31], v[30:31], v[32:33]
	v_mov_b32_e32 v32, v26
	v_add_f32_e32 v30, v30, v31
	v_mov_b32_e32 v31, v131
	v_mov_b32_e32 v33, v22
	v_add_f32_dpp v30, v30, v30 quad_perm:[1,0,3,2] row_mask:0xf bank_mask:0xf bound_ctrl:1
	v_pk_mul_f32 v[32:33], v[32:33], v[32:33]
	s_nop 0
	v_add_f32_dpp v30, v30, v30 quad_perm:[2,3,0,1] row_mask:0xf bank_mask:0xf bound_ctrl:1
	s_nop 1
	v_add_f32_dpp v30, v30, v30 row_half_mirror row_mask:0xf bank_mask:0xf bound_ctrl:1
	s_nop 1
	v_add_f32_dpp v30, v30, v30 row_mirror row_mask:0xf bank_mask:0xf bound_ctrl:1
	s_nop 1
	v_mov_b32_dpp v31, v30 row_bcast:15 row_mask:0xa bank_mask:0xf
	v_add_f32_e32 v30, v30, v31
	v_mov_b32_e32 v31, v131
	s_nop 1
	v_mov_b32_dpp v31, v30 row_bcast:31 row_mask:0xc bank_mask:0xf
	v_add_f32_e32 v30, v30, v31
	v_mov_b32_e32 v31, v24
	v_readlane_b32 s6, v30, 63
	s_nop 1
	v_fma_f32 v30, s6, v235, v225
	v_rsq_f32_e32 v47, v30
	v_mov_b32_e32 v30, v40
	v_pk_fma_f32 v[30:31], v[30:31], v[30:31], v[32:33]
	v_mov_b32_e32 v32, v27
	v_add_f32_e32 v30, v30, v31
	v_mov_b32_e32 v31, v131
	v_mov_b32_e32 v33, v23
	v_add_f32_dpp v30, v30, v30 quad_perm:[1,0,3,2] row_mask:0xf bank_mask:0xf bound_ctrl:1
	v_pk_mul_f32 v[32:33], v[32:33], v[32:33]
	v_pk_mul_f32 v[28:29], v[28:29], v[46:47]
	v_add_f32_dpp v30, v30, v30 quad_perm:[2,3,0,1] row_mask:0xf bank_mask:0xf bound_ctrl:1
	v_pk_fma_f32 v[28:29], v[6:7], v[28:29], v[8:9] op_sel_hi:[0,1,0]
	s_nop 0
	v_add_f32_dpp v30, v30, v30 row_half_mirror row_mask:0xf bank_mask:0xf bound_ctrl:1
	s_nop 1
	v_add_f32_dpp v30, v30, v30 row_mirror row_mask:0xf bank_mask:0xf bound_ctrl:1
	s_nop 1
	v_mov_b32_dpp v31, v30 row_bcast:15 row_mask:0xa bank_mask:0xf
	v_add_f32_e32 v30, v30, v31
	v_mov_b32_e32 v31, v131
	s_nop 1
	v_mov_b32_dpp v31, v30 row_bcast:31 row_mask:0xc bank_mask:0xf
	v_add_f32_e32 v30, v30, v31
	v_mov_b32_e32 v31, v25
	v_readlane_b32 s6, v30, 63
	s_nop 1
	v_fma_f32 v30, s6, v235, v225
	v_rsq_f32_e32 v54, v30
	v_mov_b32_e32 v30, v41
	v_pk_fma_f32 v[30:31], v[30:31], v[30:31], v[32:33]
	v_add_f32_e32 v30, v30, v31
	v_mov_b32_e32 v31, v131
	s_nop 0
	v_add_f32_dpp v30, v30, v30 quad_perm:[1,0,3,2] row_mask:0xf bank_mask:0xf bound_ctrl:1
	s_nop 1
	v_add_f32_dpp v30, v30, v30 quad_perm:[2,3,0,1] row_mask:0xf bank_mask:0xf bound_ctrl:1
	s_nop 1
	v_add_f32_dpp v30, v30, v30 row_half_mirror row_mask:0xf bank_mask:0xf bound_ctrl:1
	s_nop 1
	v_add_f32_dpp v30, v30, v30 row_mirror row_mask:0xf bank_mask:0xf bound_ctrl:1
	s_nop 1
	v_mov_b32_dpp v31, v30 row_bcast:15 row_mask:0xa bank_mask:0xf
	v_add_f32_e32 v30, v30, v31
	v_mov_b32_e32 v31, v131
	s_nop 1
	v_mov_b32_dpp v31, v30 row_bcast:31 row_mask:0xc bank_mask:0xf
	v_add_f32_e32 v30, v30, v31
	s_nop 0
	v_readlane_b32 s6, v30, 63
	s_nop 1
	v_fma_f32 v30, s6, v235, v225
	v_rsq_f32_e32 v55, v30
	v_pk_mul_f32 v[30:31], v[44:45], v[46:47]
	v_pk_mul_f32 v[32:33], v[40:41], v[54:55]
	v_pk_mul_f32 v[26:27], v[26:27], v[54:55]
	v_pk_mul_f32 v[24:25], v[24:25], v[54:55]
	v_lshlrev_b32_e32 v40, 16, v58
	v_pk_fma_f32 v[34:35], v[14:15], v[32:33], v[16:17] op_sel_hi:[0,1,0]
	v_pk_fma_f32 v[36:37], v[14:15], v[30:31], v[16:17] op_sel_hi:[0,1,0]
	v_pk_mul_f32 v[32:33], v[42:43], v[46:47]
	v_pk_fma_f32 v[30:31], v[10:11], v[26:27], v[12:13] op_sel_hi:[0,1,0]
	v_pk_fma_f32 v[26:27], v[6:7], v[24:25], v[8:9] op_sel_hi:[0,1,0]
	v_pk_mul_f32 v[24:25], v[38:39], v[46:47]
	v_lshlrev_b32_e32 v38, 16, v60
	v_mul_f32_e32 v43, v40, v40
	v_lshlrev_b32_e32 v41, 16, v59
	v_mul_f32_e32 v43, 0xbf38aa3b, v43
	v_mul_f32_e32 v47, v38, v38
	v_lshlrev_b32_e32 v39, 16, v61
	v_fma_f32 v42, |v40|, s92, 1.0
	v_exp_f32_e32 v44, v43
	v_fma_f32 v43, |v41|, s92, 1.0
	v_mul_f32_e32 v47, 0xbf38aa3b, v47
	v_pk_mul_f32 v[22:23], v[22:23], v[54:55]
	v_rcp_f32_e32 v42, v42
	v_rcp_f32_e32 v43, v43
	v_fma_f32 v46, |v38|, s92, 1.0
	v_exp_f32_e32 v54, v47
	v_fma_f32 v47, |v39|, s92, 1.0
	v_rcp_f32_e32 v46, v46
	v_rcp_f32_e32 v47, v47
	v_mul_f32_e32 v45, v41, v41
	v_mul_f32_e32 v45, 0xbf38aa3b, v45
	v_pk_fma_f32 v[56:57], v[42:43], s[12:13], v[18:19] op_sel_hi:[1,0,0]
	v_mul_f32_e32 v55, v39, v39
	v_exp_f32_e32 v45, v45
	v_pk_fma_f32 v[58:59], v[46:47], s[12:13], v[18:19] op_sel_hi:[1,0,0]
	v_pk_fma_f32 v[56:57], v[42:43], v[56:57], s[14:15] op_sel_hi:[1,1,0]
	v_mul_f32_e32 v55, 0xbf38aa3b, v55
	v_pk_fma_f32 v[58:59], v[46:47], v[58:59], s[14:15] op_sel_hi:[1,1,0]
	v_pk_fma_f32 v[56:57], v[42:43], v[56:57], s[16:17] op_sel_hi:[1,1,0]
	v_exp_f32_e32 v55, v55
	v_pk_fma_f32 v[58:59], v[46:47], v[58:59], s[16:17] op_sel_hi:[1,1,0]
	v_pk_fma_f32 v[56:57], v[42:43], v[56:57], s[18:19] op_sel_hi:[1,1,0]
	v_pk_fma_f32 v[58:59], v[46:47], v[58:59], s[18:19] op_sel_hi:[1,1,0]
	v_pk_mul_f32 v[42:43], v[42:43], v[56:57]
	v_pk_mul_f32 v[46:47], v[46:47], v[58:59]
	v_pk_mul_f32 v[42:43], v[44:45], v[42:43]
	v_pk_mul_f32 v[46:47], v[54:55], v[46:47]
	v_pk_mul_f32 v[44:45], v[42:43], v[40:41]
	v_pk_fma_f32 v[42:43], v[42:43], v[40:41], v[40:41] neg_lo:[1,0,0] neg_hi:[1,0,0]
	v_cmp_gt_f32_e32 vcc, 0, v40
	v_pk_mul_f32 v[54:55], v[46:47], v[38:39]
	v_pk_fma_f32 v[46:47], v[46:47], v[38:39], v[38:39] neg_lo:[1,0,0] neg_hi:[1,0,0]
	v_cmp_gt_f32_e64 s[44:45], 0, v38
	v_cmp_gt_f32_e64 s[46:47], 0, v39
	v_cndmask_b32_e32 v38, v42, v44, vcc
	v_lshlrev_b32_e32 v44, 16, v50
	v_cmp_gt_f32_e64 s[42:43], 0, v41
	v_cndmask_b32_e64 v41, v47, v55, s[46:47]
	v_mul_f32_e32 v47, v44, v44
	v_cndmask_b32_e64 v39, v43, v45, s[42:43]
	v_lshlrev_b32_e32 v45, 16, v51
	v_mul_f32_e32 v47, 0xbf38aa3b, v47
	v_cndmask_b32_e64 v40, v46, v54, s[44:45]
	v_fma_f32 v46, |v44|, s92, 1.0
	v_exp_f32_e32 v50, v47
	v_fma_f32 v47, |v45|, s92, 1.0
	v_lshlrev_b32_e32 v42, 16, v52
	v_rcp_f32_e32 v46, v46
	v_rcp_f32_e32 v47, v47
	v_lshlrev_b32_e32 v43, 16, v53
	v_mul_f32_e32 v53, v42, v42
	v_mul_f32_e32 v53, 0xbf38aa3b, v53
	v_mul_f32_e32 v51, v45, v45
	v_fma_f32 v52, |v42|, s92, 1.0
	v_exp_f32_e32 v54, v53
	v_fma_f32 v53, |v43|, s92, 1.0
	v_mul_f32_e32 v51, 0xbf38aa3b, v51
	v_rcp_f32_e32 v52, v52
	v_rcp_f32_e32 v53, v53
	v_pk_fma_f32 v[56:57], v[46:47], s[12:13], v[18:19] op_sel_hi:[1,0,0]
	v_exp_f32_e32 v51, v51
	v_pk_fma_f32 v[56:57], v[46:47], v[56:57], s[14:15] op_sel_hi:[1,1,0]
	v_mul_f32_e32 v55, v43, v43
	v_pk_fma_f32 v[56:57], v[46:47], v[56:57], s[16:17] op_sel_hi:[1,1,0]
	v_pk_fma_f32 v[58:59], v[52:53], s[12:13], v[18:19] op_sel_hi:[1,0,0]
	v_pk_fma_f32 v[56:57], v[46:47], v[56:57], s[18:19] op_sel_hi:[1,1,0]
	v_mul_f32_e32 v55, 0xbf38aa3b, v55
	v_pk_mul_f32 v[46:47], v[46:47], v[56:57]
	v_pk_fma_f32 v[58:59], v[52:53], v[58:59], s[14:15] op_sel_hi:[1,1,0]
	v_exp_f32_e32 v55, v55
	v_pk_mul_f32 v[46:47], v[50:51], v[46:47]
	v_pk_fma_f32 v[58:59], v[52:53], v[58:59], s[16:17] op_sel_hi:[1,1,0]
	v_pk_mul_f32 v[50:51], v[46:47], v[44:45]
	v_pk_fma_f32 v[46:47], v[46:47], v[44:45], v[44:45] neg_lo:[1,0,0] neg_hi:[1,0,0]
	v_cmp_gt_f32_e32 vcc, 0, v44
	v_pk_fma_f32 v[58:59], v[52:53], v[58:59], s[18:19] op_sel_hi:[1,1,0]
	v_cmp_gt_f32_e64 s[42:43], 0, v45
	v_cndmask_b32_e32 v44, v46, v50, vcc
	v_lshlrev_b32_e32 v46, 16, v48
	v_lshlrev_b32_e32 v48, 16, v15
	v_pk_mul_f32 v[52:53], v[52:53], v[58:59]
	v_fma_f32 v15, |v48|, s92, 1.0
	v_pk_mul_f32 v[52:53], v[54:55], v[52:53]
	v_rcp_f32_e32 v50, v15
	v_mul_f32_e32 v15, v48, v48
	v_pk_mul_f32 v[54:55], v[52:53], v[42:43]
	v_pk_fma_f32 v[52:53], v[52:53], v[42:43], v[42:43] neg_lo:[1,0,0] neg_hi:[1,0,0]
	v_cmp_gt_f32_e64 s[44:45], 0, v42
	v_cndmask_b32_e64 v45, v47, v51, s[42:43]
	v_lshlrev_b32_e32 v47, 16, v49
	v_lshlrev_b32_e32 v49, 16, v17
	v_mul_f32_e32 v15, 0xbf38aa3b, v15
	v_cndmask_b32_e64 v42, v52, v54, s[44:45]
	v_exp_f32_e32 v52, v15
	v_fma_f32 v15, |v49|, s92, 1.0
	v_rcp_f32_e32 v51, v15
	v_mul_f32_e32 v15, v49, v49
	v_cmp_gt_f32_e64 s[46:47], 0, v43
	v_mul_f32_e32 v15, 0xbf38aa3b, v15
	v_pk_fma_f32 v[58:59], v[50:51], s[12:13], v[18:19] op_sel_hi:[1,0,0]
	v_cndmask_b32_e64 v43, v53, v55, s[46:47]
	v_exp_f32_e32 v53, v15
	v_fma_f32 v15, |v46|, s92, 1.0
	v_rcp_f32_e32 v54, v15
	v_mul_f32_e32 v15, v46, v46
	v_mul_f32_e32 v15, 0xbf38aa3b, v15
	v_exp_f32_e32 v56, v15
	v_fma_f32 v15, |v47|, s92, 1.0
	v_rcp_f32_e32 v55, v15
	v_pk_fma_f32 v[58:59], v[50:51], v[58:59], s[14:15] op_sel_hi:[1,1,0]
	v_mul_f32_e32 v15, v47, v47
	v_pk_fma_f32 v[58:59], v[50:51], v[58:59], s[16:17] op_sel_hi:[1,1,0]
	v_pk_fma_f32 v[60:61], v[54:55], s[12:13], v[18:19] op_sel_hi:[1,0,0]
	v_mul_f32_e32 v15, 0xbf38aa3b, v15
	v_pk_fma_f32 v[60:61], v[54:55], v[60:61], s[14:15] op_sel_hi:[1,1,0]
	v_pk_fma_f32 v[58:59], v[50:51], v[58:59], s[18:19] op_sel_hi:[1,1,0]
	v_exp_f32_e32 v57, v15
	v_pk_fma_f32 v[60:61], v[54:55], v[60:61], s[16:17] op_sel_hi:[1,1,0]
	v_pk_mul_f32 v[50:51], v[50:51], v[58:59]
	v_pk_fma_f32 v[60:61], v[54:55], v[60:61], s[18:19] op_sel_hi:[1,1,0]
	v_pk_mul_f32 v[50:51], v[52:53], v[50:51]
	v_pk_mul_f32 v[54:55], v[54:55], v[60:61]
	v_pk_mul_f32 v[52:53], v[50:51], v[48:49]
	v_pk_fma_f32 v[50:51], v[50:51], v[48:49], v[48:49] neg_lo:[1,0,0] neg_hi:[1,0,0]
	v_cmp_gt_f32_e32 vcc, 0, v48
	v_pk_mul_f32 v[54:55], v[56:57], v[54:55]
	v_cmp_gt_f32_e64 s[42:43], 0, v49
	v_cndmask_b32_e32 v48, v50, v52, vcc
	v_lshlrev_b32_e32 v52, 16, v9
	v_pk_mul_f32 v[56:57], v[54:55], v[46:47]
	v_pk_fma_f32 v[54:55], v[54:55], v[46:47], v[46:47] neg_lo:[1,0,0] neg_hi:[1,0,0]
	v_cmp_gt_f32_e64 s[44:45], 0, v46
	v_cndmask_b32_e64 v49, v51, v53, s[42:43]
	v_lshlrev_b32_e32 v51, 16, v7
	v_fma_f32 v7, |v52|, s92, 1.0
	v_cndmask_b32_e64 v46, v54, v56, s[44:45]
	v_rcp_f32_e32 v54, v7
	v_mul_f32_e32 v7, v52, v52
	v_lshlrev_b32_e32 v53, 16, v11
	v_mul_f32_e32 v7, 0xbf38aa3b, v7
	v_cmp_gt_f32_e64 s[46:47], 0, v47
	v_exp_f32_e32 v56, v7
	v_fma_f32 v7, |v53|, s92, 1.0
	v_cndmask_b32_e64 v47, v55, v57, s[46:47]
	v_rcp_f32_e32 v55, v7
	v_mul_f32_e32 v7, v53, v53
	v_lshlrev_b32_e32 v50, 16, v13
	v_mul_f32_e32 v7, 0xbf38aa3b, v7
	v_exp_f32_e32 v57, v7
	v_fma_f32 v7, |v50|, s92, 1.0
	v_rcp_f32_e32 v58, v7
	v_mul_f32_e32 v7, v50, v50
	v_mul_f32_e32 v7, 0xbf38aa3b, v7
	v_exp_f32_e32 v60, v7
	v_fma_f32 v7, |v51|, s92, 1.0
	v_rcp_f32_e32 v59, v7
	v_pk_fma_f32 v[62:63], v[54:55], s[12:13], v[18:19] op_sel_hi:[1,0,0]
	v_mul_f32_e32 v7, v51, v51
	v_pk_fma_f32 v[62:63], v[54:55], v[62:63], s[14:15] op_sel_hi:[1,1,0]
	v_pk_fma_f32 v[18:19], v[58:59], s[12:13], v[18:19] op_sel_hi:[1,0,0]
	v_mul_f32_e32 v7, 0xbf38aa3b, v7
	v_pk_fma_f32 v[18:19], v[58:59], v[18:19], s[14:15] op_sel_hi:[1,1,0]
	v_pk_fma_f32 v[62:63], v[54:55], v[62:63], s[16:17] op_sel_hi:[1,1,0]
	v_exp_f32_e32 v61, v7
	v_pk_fma_f32 v[18:19], v[58:59], v[18:19], s[16:17] op_sel_hi:[1,1,0]
	v_pk_fma_f32 v[62:63], v[54:55], v[62:63], s[18:19] op_sel_hi:[1,1,0]
	v_pk_fma_f32 v[18:19], v[58:59], v[18:19], s[18:19] op_sel_hi:[1,1,0]
	v_pk_mul_f32 v[54:55], v[54:55], v[62:63]
	v_pk_mul_f32 v[18:19], v[58:59], v[18:19]
	v_pk_mul_f32 v[54:55], v[56:57], v[54:55]
	v_pk_mul_f32 v[18:19], v[60:61], v[18:19]
	v_pk_mul_f32 v[56:57], v[54:55], v[52:53]
	v_pk_fma_f32 v[54:55], v[54:55], v[52:53], v[52:53] neg_lo:[1,0,0] neg_hi:[1,0,0]
	v_cmp_gt_f32_e32 vcc, 0, v52
	v_pk_mul_f32 v[58:59], v[18:19], v[50:51]
	v_pk_fma_f32 v[18:19], v[18:19], v[50:51], v[50:51] neg_lo:[1,0,0] neg_hi:[1,0,0]
	v_cmp_gt_f32_e64 s[42:43], 0, v53
	v_cmp_gt_f32_e64 s[44:45], 0, v50
	v_cndmask_b32_e32 v50, v54, v56, vcc
	v_cmp_gt_f32_e64 s[46:47], 0, v51
	v_cndmask_b32_e64 v51, v55, v57, s[42:43]
	v_mov_b32_e32 v52, v38
	v_mov_b32_e32 v53, v48
	v_mov_b32_e32 v54, v44
	v_mov_b32_e32 v55, v50
	v_cndmask_b32_e64 v19, v19, v59, s[46:47]
	v_cndmask_b32_e64 v18, v18, v58, s[44:45]
	v_pk_add_f32 v[58:59], v[52:53], v[54:55]
	v_mov_b32_e32 v9, v131
	v_add_f32_e32 v7, v58, v59
	v_mov_b32_e32 v52, v39
	v_mov_b32_e32 v53, v49
	v_add_f32_dpp v7, v7, v7 quad_perm:[1,0,3,2] row_mask:0xf bank_mask:0xf bound_ctrl:1
	v_mov_b32_e32 v54, v45
	v_mov_b32_e32 v55, v51
	v_add_f32_dpp v7, v7, v7 quad_perm:[2,3,0,1] row_mask:0xf bank_mask:0xf bound_ctrl:1
	v_pk_add_f32 v[56:57], v[52:53], v[54:55]
	v_mov_b32_e32 v52, v40
	v_add_f32_dpp v7, v7, v7 row_half_mirror row_mask:0xf bank_mask:0xf bound_ctrl:1
	v_mov_b32_e32 v53, v46
	v_mov_b32_e32 v54, v42
	v_add_f32_dpp v7, v7, v7 row_mirror row_mask:0xf bank_mask:0xf bound_ctrl:1
	v_mov_b32_e32 v55, v18
	v_pk_add_f32 v[54:55], v[52:53], v[54:55]
	v_mov_b32_dpp v9, v7 row_bcast:15 row_mask:0xa bank_mask:0xf
	v_add_f32_e32 v7, v7, v9
	v_mov_b32_e32 v9, v131
	v_mov_b32_e32 v52, v41
	v_mov_b32_e32 v53, v47
	v_mov_b32_dpp v9, v7 row_bcast:31 row_mask:0xc bank_mask:0xf
	v_add_f32_e32 v7, v7, v9
	v_mov_b32_e32 v9, v131
	v_readlane_b32 s6, v7, 63
	v_add_f32_e32 v7, v56, v57
	v_mov_b32_e32 v60, v43
	v_mov_b32_e32 v61, v19
	v_add_f32_dpp v7, v7, v7 quad_perm:[1,0,3,2] row_mask:0xf bank_mask:0xf bound_ctrl:1
	v_pk_add_f32 v[52:53], v[52:53], v[60:61]
	s_xor_b32 s6, s6, 0x80000000
	v_add_f32_dpp v7, v7, v7 quad_perm:[2,3,0,1] row_mask:0xf bank_mask:0xf bound_ctrl:1
	v_pk_fma_f32 v[32:33], v[10:11], v[32:33], v[12:13] op_sel_hi:[0,1,0]
	v_pk_fma_f32 v[22:23], v[2:3], v[22:23], v[4:5] op_sel_hi:[0,1,0]
	v_add_f32_dpp v7, v7, v7 row_half_mirror row_mask:0xf bank_mask:0xf bound_ctrl:1
	v_pk_fma_f32 v[24:25], v[2:3], v[24:25], v[4:5] op_sel_hi:[0,1,0]
	s_movk_i32 s42, 0x110
	v_add_f32_dpp v7, v7, v7 row_mirror row_mask:0xf bank_mask:0xf bound_ctrl:1
	s_mov_b32 s44, 0xbf3a00e3
	s_nop 0
	v_mov_b32_dpp v9, v7 row_bcast:15 row_mask:0xa bank_mask:0xf
	v_add_f32_e32 v7, v7, v9
	v_mov_b32_e32 v9, v131
	s_nop 1
	v_mov_b32_dpp v9, v7 row_bcast:31 row_mask:0xc bank_mask:0xf
	v_add_f32_e32 v7, v7, v9
	v_mov_b32_e32 v9, v131
	v_readlane_b32 s7, v7, 63
	v_add_f32_e32 v7, v54, v55
	s_xor_b32 s7, s7, 0x80000000
	v_pk_fma_f32 v[54:55], s[6:7], v[20:21], v[38:39] op_sel_hi:[1,0,1]
	v_add_f32_dpp v7, v7, v7 quad_perm:[1,0,3,2] row_mask:0xf bank_mask:0xf bound_ctrl:1
	v_pk_fma_f32 v[44:45], s[6:7], v[20:21], v[44:45] op_sel_hi:[1,0,1]
	s_nop 0
	v_add_f32_dpp v7, v7, v7 quad_perm:[2,3,0,1] row_mask:0xf bank_mask:0xf bound_ctrl:1
	s_nop 1
	v_add_f32_dpp v7, v7, v7 row_half_mirror row_mask:0xf bank_mask:0xf bound_ctrl:1
	s_nop 1
	v_add_f32_dpp v7, v7, v7 row_mirror row_mask:0xf bank_mask:0xf bound_ctrl:1
	s_nop 1
	v_mov_b32_dpp v9, v7 row_bcast:15 row_mask:0xa bank_mask:0xf
	v_add_f32_e32 v7, v7, v9
	v_mov_b32_e32 v9, v131
	s_nop 1
	v_mov_b32_dpp v9, v7 row_bcast:31 row_mask:0xc bank_mask:0xf
	v_add_f32_e32 v7, v7, v9
	v_mov_b32_e32 v9, v131
	v_readlane_b32 s8, v7, 63
	v_add_f32_e32 v7, v52, v53
	s_xor_b32 s8, s8, 0x80000000
	s_nop 0
	v_add_f32_dpp v7, v7, v7 quad_perm:[1,0,3,2] row_mask:0xf bank_mask:0xf bound_ctrl:1
	s_nop 1
	v_add_f32_dpp v7, v7, v7 quad_perm:[2,3,0,1] row_mask:0xf bank_mask:0xf bound_ctrl:1
	s_nop 1
	v_add_f32_dpp v7, v7, v7 row_half_mirror row_mask:0xf bank_mask:0xf bound_ctrl:1
	s_nop 1
	v_add_f32_dpp v7, v7, v7 row_mirror row_mask:0xf bank_mask:0xf bound_ctrl:1
	s_nop 1
	v_mov_b32_dpp v9, v7 row_bcast:15 row_mask:0xa bank_mask:0xf
	v_add_f32_e32 v7, v7, v9
	v_mov_b32_e32 v9, v131
	s_nop 1
	v_mov_b32_dpp v9, v7 row_bcast:31 row_mask:0xc bank_mask:0xf
	v_add_f32_e32 v7, v7, v9
	v_mov_b32_e32 v9, v131
	v_readlane_b32 s9, v7, 63
	s_xor_b32 s9, s9, 0x80000000
	s_nop 0
	v_pk_fma_f32 v[52:53], s[8:9], v[20:21], v[40:41] op_sel_hi:[1,0,1]
	v_pk_fma_f32 v[42:43], s[8:9], v[20:21], v[42:43] op_sel_hi:[1,0,1]
	v_pk_fma_f32 v[38:39], s[8:9], v[20:21], v[46:47] op_sel_hi:[1,0,1]
	v_pk_fma_f32 v[40:41], s[6:7], v[20:21], v[48:49] op_sel_hi:[1,0,1]
	v_pk_fma_f32 v[18:19], s[8:9], v[20:21], v[18:19] op_sel_hi:[1,0,1]
	v_pk_fma_f32 v[20:21], s[6:7], v[20:21], v[50:51] op_sel_hi:[1,0,1]
	v_mov_b32_e32 v48, v44
	v_mov_b32_e32 v49, v20
	v_mov_b32_e32 v46, v54
	v_mov_b32_e32 v47, v40
	v_pk_mul_f32 v[48:49], v[48:49], v[48:49]
	v_mov_b32_e32 v50, v45
	v_pk_fma_f32 v[46:47], v[46:47], v[46:47], v[48:49]
	v_mov_b32_e32 v51, v21
	v_add_f32_e32 v7, v46, v47
	v_mov_b32_e32 v48, v55
	v_mov_b32_e32 v49, v41
	v_add_f32_dpp v7, v7, v7 quad_perm:[1,0,3,2] row_mask:0xf bank_mask:0xf bound_ctrl:1
	v_pk_mul_f32 v[50:51], v[50:51], v[50:51]
	v_mov_b32_e32 v56, v43
	v_add_f32_dpp v7, v7, v7 quad_perm:[2,3,0,1] row_mask:0xf bank_mask:0xf bound_ctrl:1
	v_pk_fma_f32 v[48:49], v[48:49], v[48:49], v[50:51]
	v_mov_b32_e32 v50, v42
	v_add_f32_dpp v7, v7, v7 row_half_mirror row_mask:0xf bank_mask:0xf bound_ctrl:1
	v_mov_b32_e32 v51, v18
	v_pk_mul_f32 v[50:51], v[50:51], v[50:51]
	v_add_f32_dpp v7, v7, v7 row_mirror row_mask:0xf bank_mask:0xf bound_ctrl:1
	v_mov_b32_e32 v57, v19
	v_pk_mul_f32 v[56:57], v[56:57], v[56:57]
	v_mov_b32_dpp v9, v7 row_bcast:15 row_mask:0xa bank_mask:0xf
	v_add_f32_e32 v7, v7, v9
	v_mov_b32_e32 v9, v131
	v_readlane_b32 s9, v254, 29
	s_movk_i32 s8, 0x2000
	v_mov_b32_dpp v9, v7 row_bcast:31 row_mask:0xc bank_mask:0xf
	v_add_f32_e32 v7, v7, v9
	v_mov_b32_e32 v9, v131
	v_readlane_b32 s6, v7, 63
	s_nop 1
	v_fma_f32 v7, s6, v235, v225
	v_rsq_f32_e32 v46, v7
	v_add_f32_e32 v7, v48, v49
	v_mov_b32_e32 v48, v52
	v_mov_b32_e32 v49, v38
	v_add_f32_dpp v7, v7, v7 quad_perm:[1,0,3,2] row_mask:0xf bank_mask:0xf bound_ctrl:1
	v_pk_fma_f32 v[48:49], v[48:49], v[48:49], v[50:51]
	v_mov_b32_e32 v50, v53
	v_add_f32_dpp v7, v7, v7 quad_perm:[2,3,0,1] row_mask:0xf bank_mask:0xf bound_ctrl:1
	v_mov_b32_e32 v51, v39
	v_pk_fma_f32 v[50:51], v[50:51], v[50:51], v[56:57]
	v_add_f32_dpp v7, v7, v7 row_half_mirror row_mask:0xf bank_mask:0xf bound_ctrl:1
	s_nop 1
	v_add_f32_dpp v7, v7, v7 row_mirror row_mask:0xf bank_mask:0xf bound_ctrl:1
	s_nop 1
	v_mov_b32_dpp v9, v7 row_bcast:15 row_mask:0xa bank_mask:0xf
	v_add_f32_e32 v7, v7, v9
	v_mov_b32_e32 v9, v131
	s_nop 1
	v_mov_b32_dpp v9, v7 row_bcast:31 row_mask:0xc bank_mask:0xf
	v_add_f32_e32 v7, v7, v9
	v_mov_b32_e32 v9, v131
	v_readlane_b32 s6, v7, 63
	s_nop 1
	v_fma_f32 v7, s6, v235, v225
	v_rsq_f32_e32 v47, v7
	v_add_f32_e32 v7, v48, v49
	s_nop 1
	v_add_f32_dpp v7, v7, v7 quad_perm:[1,0,3,2] row_mask:0xf bank_mask:0xf bound_ctrl:1
	s_nop 1
	v_add_f32_dpp v7, v7, v7 quad_perm:[2,3,0,1] row_mask:0xf bank_mask:0xf bound_ctrl:1
	s_nop 1
	v_add_f32_dpp v7, v7, v7 row_half_mirror row_mask:0xf bank_mask:0xf bound_ctrl:1
	s_nop 1
	v_add_f32_dpp v7, v7, v7 row_mirror row_mask:0xf bank_mask:0xf bound_ctrl:1
	s_nop 1
	v_mov_b32_dpp v9, v7 row_bcast:15 row_mask:0xa bank_mask:0xf
	v_add_f32_e32 v7, v7, v9
	v_mov_b32_e32 v9, v131
	s_nop 1
	v_mov_b32_dpp v9, v7 row_bcast:31 row_mask:0xc bank_mask:0xf
	v_add_f32_e32 v7, v7, v9
	v_mov_b32_e32 v9, v131
	v_readlane_b32 s6, v7, 63
	s_nop 1
	v_fma_f32 v7, s6, v235, v225
	v_rsq_f32_e32 v48, v7
	v_add_f32_e32 v7, v50, v51
	v_pk_mul_f32 v[50:51], v[54:55], v[46:47]
	s_nop 0
	v_add_f32_dpp v7, v7, v7 quad_perm:[1,0,3,2] row_mask:0xf bank_mask:0xf bound_ctrl:1
	s_nop 1
	v_add_f32_dpp v7, v7, v7 quad_perm:[2,3,0,1] row_mask:0xf bank_mask:0xf bound_ctrl:1
	s_nop 1
	v_add_f32_dpp v7, v7, v7 row_half_mirror row_mask:0xf bank_mask:0xf bound_ctrl:1
	s_nop 1
	v_add_f32_dpp v7, v7, v7 row_mirror row_mask:0xf bank_mask:0xf bound_ctrl:1
	s_nop 1
	v_mov_b32_dpp v9, v7 row_bcast:15 row_mask:0xa bank_mask:0xf
	v_add_f32_e32 v7, v7, v9
	v_mov_b32_e32 v9, v131
	s_nop 1
	v_mov_b32_dpp v9, v7 row_bcast:31 row_mask:0xc bank_mask:0xf
	v_add_f32_e32 v7, v7, v9
	s_nop 0
	v_readlane_b32 s6, v7, 63
	s_nop 1
	v_fma_f32 v7, s6, v235, v225
	v_rsq_f32_e32 v49, v7
	s_add_i32 s6, s5, s15
	s_mul_hi_i32 s7, s6, 0x5000
	s_mulk_i32 s6, 0x5000
	v_pk_mul_f32 v[52:53], v[52:53], v[48:49]
	s_lshl_b32 s5, s5, 9
	v_pk_fma_f32 v[52:53], v[14:15], v[52:53], v[16:17] op_sel_hi:[0,1,0]
	v_pk_fma_f32 v[14:15], v[14:15], v[50:51], v[16:17] op_sel_hi:[0,1,0]
	v_cvt_pk_bf16_f32 v17, v52, v53
	v_cvt_pk_bf16_f32 v16, v14, v15
	v_cvt_pk_bf16_f32 v15, v34, v35
	v_cvt_pk_bf16_f32 v14, v36, v37
	ds_write_b128 v5, v[14:17] offset:16
	v_pk_mul_f32 v[14:15], v[44:45], v[46:47]
	v_pk_mul_f32 v[16:17], v[42:43], v[48:49]
	s_add_u32 s28, s9, s6
	v_pk_fma_f32 v[16:17], v[10:11], v[16:17], v[12:13] op_sel_hi:[0,1,0]
	v_pk_fma_f32 v[10:11], v[10:11], v[14:15], v[12:13] op_sel_hi:[0,1,0]
	v_cvt_pk_bf16_f32 v13, v16, v17
	v_cvt_pk_bf16_f32 v12, v10, v11
	v_cvt_pk_bf16_f32 v11, v30, v31
	v_cvt_pk_bf16_f32 v10, v32, v33
	ds_write_b128 v5, v[10:13] offset:17424
	v_pk_mul_f32 v[10:11], v[40:41], v[46:47]
	v_pk_mul_f32 v[12:13], v[38:39], v[48:49]
	v_readlane_b32 s6, v254, 31
	v_pk_fma_f32 v[12:13], v[6:7], v[12:13], v[8:9] op_sel_hi:[0,1,0]
	v_pk_fma_f32 v[6:7], v[6:7], v[10:11], v[8:9] op_sel_hi:[0,1,0]
	v_cvt_pk_bf16_f32 v9, v12, v13
	v_cvt_pk_bf16_f32 v8, v6, v7
	v_cvt_pk_bf16_f32 v7, v26, v27
	v_cvt_pk_bf16_f32 v6, v28, v29
	ds_write_b128 v5, v[6:9] offset:34832
	v_pk_mul_f32 v[6:7], v[20:21], v[46:47]
	v_pk_mul_f32 v[8:9], v[18:19], v[48:49]
	v_pk_fma_f32 v[6:7], v[2:3], v[6:7], v[4:5] op_sel_hi:[0,1,0]
	v_pk_fma_f32 v[8:9], v[2:3], v[8:9], v[4:5] op_sel_hi:[0,1,0]
	v_bfe_u32 v4, v3, 5, 1
	v_and_or_b32 v2, v3, 31, s34
	v_mul_lo_u32 v3, v2, s42
	v_lshlrev_b32_e32 v164, 4, v4
	v_cvt_pk_bf16_f32 v9, v8, v9
	v_cvt_pk_bf16_f32 v8, v6, v7
	v_cvt_pk_bf16_f32 v7, v22, v23
	v_cvt_pk_bf16_f32 v6, v24, v25
	v_add3_u32 v3, 0, v3, v164
	ds_write_b128 v5, v[6:9] offset:52240
	s_waitcnt lgkmcnt(0)
	s_barrier
	ds_read_b128 v[18:21], v3
	ds_read_b128 v[22:25], v3 offset:32
	ds_read_b128 v[26:29], v3 offset:64
	ds_read_b128 v[30:33], v3 offset:96
	ds_read_b128 v[34:37], v3 offset:128
	ds_read_b128 v[38:41], v3 offset:160
	ds_read_b128 v[42:45], v3 offset:192
	ds_read_b128 v[46:49], v3 offset:224
	s_addc_u32 s29, s6, s7
	v_ashrrev_i32_e32 v3, 31, v2
	v_lshl_add_u32 v94, v4, 2, s17
	v_lshlrev_b64 v[106:107], 1, v[2:3]
	global_load_dwordx4 v[2:5], v130, s[28:29]
	global_load_dwordx4 v[50:53], v130, s[28:29] offset:1024
	v_lshl_add_u64 v[90:91], s[28:29], 0, v[130:131]
	v_add_co_u32_e32 v54, vcc, s90, v90
	v_lshl_add_u64 v[92:93], s[80:81], 0, v[106:107]
	s_nop 0
	v_addc_co_u32_e32 v55, vcc, 0, v91, vcc
	v_add_u32_e32 v72, 15, v94
	v_add_u32_e32 v68, 16, v94
	v_add_u32_e32 v66, 17, v94
	v_add_u32_e32 v64, 18, v94
	v_add_u32_e32 v158, 33, v94
	v_add_u32_e32 v156, 34, v94
	v_add_u32_e32 v154, 39, v94
	v_add_u32_e32 v152, 40, v94
	v_add_u32_e32 v150, 41, v94
	v_add_co_u32_e32 v70, vcc, s8, v90
	v_add_u32_e32 v120, -1, v94
	v_add_u32_e32 v118, 1, v94
	v_add_u32_e32 v116, 2, v94
	v_add_u32_e32 v114, 7, v94
	v_add_u32_e32 v112, 8, v94
	v_add_u32_e32 v110, 9, v94
	v_add_u32_e32 v108, 10, v94
	v_mad_i64_i32 v[126:127], s[6:7], v72, s87, v[92:93]
	v_mad_i64_i32 v[128:129], s[6:7], v68, s87, v[92:93]
	v_mad_i64_i32 v[132:133], s[6:7], v66, s87, v[92:93]
	v_mad_i64_i32 v[134:135], s[6:7], v64, s87, v[92:93]
	v_add_u32_e32 v62, 23, v94
	v_add_u32_e32 v60, 24, v94
	v_add_u32_e32 v58, 25, v94
	v_add_u32_e32 v56, 26, v94
	v_add_u32_e32 v162, 31, v94
	v_add_u32_e32 v160, 32, v94
	v_mad_i64_i32 v[172:173], s[6:7], v158, s87, v[92:93]
	v_mad_i64_i32 v[174:175], s[6:7], v156, s87, v[92:93]
	v_mad_i64_i32 v[176:177], s[6:7], v154, s87, v[92:93]
	v_mad_i64_i32 v[178:179], s[6:7], v152, s87, v[92:93]
	v_mad_i64_i32 v[180:181], s[6:7], v150, s87, v[92:93]
	v_add_u32_e32 v148, 42, v94
	v_add_u32_e32 v146, 47, v94
	v_add_u32_e32 v144, 48, v94
	v_add_u32_e32 v142, 49, v94
	v_add_u32_e32 v104, 50, v94
	v_add_u32_e32 v102, 55, v94
	v_add_u32_e32 v100, 56, v94
	v_add_u32_e32 v98, 57, v94
	v_add_u32_e32 v96, 58, v94
	v_addc_co_u32_e32 v71, vcc, 0, v91, vcc
	v_mad_i64_i32 v[6:7], s[6:7], v120, s87, v[92:93]
	v_mad_i64_i32 v[8:9], s[6:7], v94, s87, v[92:93]
	v_mad_i64_i32 v[10:11], s[6:7], v118, s87, v[92:93]
	v_mad_i64_i32 v[12:13], s[6:7], v116, s87, v[92:93]
	v_mad_i64_i32 v[14:15], s[6:7], v114, s87, v[92:93]
	v_mad_i64_i32 v[16:17], s[6:7], v112, s87, v[92:93]
	v_mad_i64_i32 v[122:123], s[6:7], v110, s87, v[92:93]
	v_mad_i64_i32 v[124:125], s[6:7], v108, s87, v[92:93]
	v_mad_i64_i32 v[136:137], s[6:7], v62, s87, v[92:93]
	v_mad_i64_i32 v[138:139], s[6:7], v60, s87, v[92:93]
	v_mad_i64_i32 v[140:141], s[6:7], v58, s87, v[92:93]
	v_mad_i64_i32 v[166:167], s[6:7], v56, s87, v[92:93]
	v_mad_i64_i32 v[168:169], s[6:7], v162, s87, v[92:93]
	v_mad_i64_i32 v[170:171], s[6:7], v160, s87, v[92:93]
	v_mad_i64_i32 v[188:189], s[6:7], v148, s87, v[92:93]
	v_mad_i64_i32 v[190:191], s[6:7], v146, s87, v[92:93]
	v_mad_i64_i32 v[192:193], s[6:7], v144, s87, v[92:93]
	v_mad_i64_i32 v[194:195], s[6:7], v142, s87, v[92:93]
	v_mad_i64_i32 v[196:197], s[6:7], v104, s87, v[92:93]
	v_mad_i64_i32 v[198:199], s[6:7], v102, s87, v[92:93]
	v_mad_i64_i32 v[200:201], s[6:7], v100, s87, v[92:93]
	v_mad_i64_i32 v[202:203], s[6:7], v98, s87, v[92:93]
	v_mad_i64_i32 v[204:205], s[6:7], v96, s87, v[92:93]
	global_load_dwordx4 v[74:77], v130, s[28:29] offset:2048
	global_load_dwordx4 v[78:81], v130, s[28:29] offset:3072
	global_load_dwordx4 v[82:85], v[70:71], off offset:-4096
	global_load_dwordx4 v[86:89], v[54:55], off offset:1024
	global_load_ushort v1, v[6:7], off
	s_nop 0
	global_load_ushort v130, v[8:9], off
	global_load_ushort v165, v[10:11], off
	global_load_ushort v206, v[12:13], off
	global_load_ushort v207, v[14:15], off
	global_load_ushort v208, v[16:17], off
	global_load_ushort v209, v[122:123], off
	global_load_ushort v210, v[124:125], off
	s_nop 0
	global_load_ushort v126, v[126:127], off
	s_nop 0
	global_load_ushort v127, v[128:129], off
	s_nop 0
	global_load_ushort v128, v[132:133], off
	global_load_ushort v129, v[134:135], off
	s_nop 0
	global_load_ushort v132, v[136:137], off
	global_load_ushort v133, v[138:139], off
	global_load_ushort v134, v[140:141], off
	global_load_ushort v135, v[166:167], off
	global_load_ushort v187, v[168:169], off
	global_load_ushort v186, v[170:171], off
	global_load_ushort v185, v[172:173], off
	global_load_ushort v184, v[174:175], off
	global_load_ushort v183, v[176:177], off
	global_load_ushort v182, v[178:179], off
	s_nop 0
	global_load_ushort v181, v[180:181], off
	s_nop 0
	global_load_ushort v180, v[188:189], off
	global_load_ushort v179, v[190:191], off
	global_load_ushort v178, v[192:193], off
	global_load_ushort v177, v[194:195], off
	global_load_ushort v176, v[196:197], off
	global_load_ushort v175, v[198:199], off
	global_load_ushort v174, v[200:201], off
	global_load_ushort v173, v[202:203], off
	global_load_ushort v172, v[204:205], off
	s_waitcnt vmcnt(37) lgkmcnt(7)
	v_mfma_f32_32x32x16_bf16 v[2:17], v[2:5], v[18:21], 0
	s_add_i32 s5, s40, s5
	v_ashrrev_i32_e32 v121, 31, v120
	v_lshl_add_u64 v[106:107], s[76:77], 0, v[106:107]
	v_lshlrev_b64 v[120:121], 11, v[120:121]
	v_lshl_add_u64 v[120:121], v[106:107], 0, v[120:121]
	v_ashrrev_i32_e32 v95, 31, v94
	s_waitcnt vmcnt(36) lgkmcnt(6)
	v_mfma_f32_32x32x16_bf16 v[2:17], v[50:53], v[22:25], v[2:17]
	v_ashrrev_i32_e32 v119, 31, v118
	v_ashrrev_i32_e32 v117, 31, v116
	v_ashrrev_i32_e32 v115, 31, v114
	v_ashrrev_i32_e32 v113, 31, v112
	v_ashrrev_i32_e32 v111, 31, v110
	v_ashrrev_i32_e32 v109, 31, v108
	v_ashrrev_i32_e32 v73, 31, v72
	v_ashrrev_i32_e32 v69, 31, v68
	v_ashrrev_i32_e32 v67, 31, v66
	v_ashrrev_i32_e32 v65, 31, v64
	v_ashrrev_i32_e32 v63, 31, v62
	v_ashrrev_i32_e32 v61, 31, v60
	v_ashrrev_i32_e32 v59, 31, v58
	v_ashrrev_i32_e32 v57, 31, v56
	v_add_u32_e32 v140, 63, v94
	v_add_u32_e32 v138, 64, v94
	v_ashrrev_i32_e32 v163, 31, v162
	v_ashrrev_i32_e32 v161, 31, v160
	v_ashrrev_i32_e32 v159, 31, v158
	v_ashrrev_i32_e32 v157, 31, v156
	v_ashrrev_i32_e32 v155, 31, v154
	v_ashrrev_i32_e32 v153, 31, v152
	v_ashrrev_i32_e32 v151, 31, v150
	v_ashrrev_i32_e32 v149, 31, v148
	v_ashrrev_i32_e32 v147, 31, v146
	v_ashrrev_i32_e32 v145, 31, v144
	v_ashrrev_i32_e32 v143, 31, v142
	v_ashrrev_i32_e32 v105, 31, v104
	v_ashrrev_i32_e32 v103, 31, v102
	v_ashrrev_i32_e32 v101, 31, v100
	v_ashrrev_i32_e32 v99, 31, v98
	v_ashrrev_i32_e32 v97, 31, v96
	v_ashrrev_i32_e32 v141, 31, v140
	v_ashrrev_i32_e32 v139, 31, v138
	s_waitcnt vmcnt(31)
	v_lshlrev_b32_e32 v1, 16, v1
	v_fma_f32 v50, |v1|, s92, 1.0
	v_rcp_f32_e32 v50, v50
	v_cmp_gt_f32_e32 vcc, 0, v1
	v_fmamk_f32 v51, v50, 0x3f07dc22, v236
	v_fmaak_f32 v51, v50, v51, 0x3f35f0e3
	v_fmaak_f32 v51, v50, v51, 0xbe11a98e
	v_fmaak_f32 v51, v50, v51, 0x3e027906
	v_mul_f32_e32 v50, v50, v51
	v_mul_f32_e32 v51, v1, v1
	v_mul_f32_e32 v51, 0xbf38aa3b, v51
	v_exp_f32_e32 v51, v51
	s_nop 0
	v_mul_f32_e32 v50, v51, v50
	v_mul_f32_e32 v51, v50, v1
	v_fma_f32 v50, -v50, v1, v1
	v_add_u32_e32 v1, s5, v164
	v_cndmask_b32_e32 v136, v50, v51, vcc
	ds_read_b128 v[50:53], v1
	ds_read_b128 v[122:125], v1 offset:32
	s_movk_i32 s5, 0x3000
	s_waitcnt lgkmcnt(1)
	v_add_f32_e32 v2, v2, v50
	v_mul_f32_e32 v2, v136, v2
	v_cvt_pk_bf16_f32 v2, v2, s0
	global_store_short v[120:121], v2, off
	s_waitcnt vmcnt(31)
	v_lshlrev_b32_e32 v2, 16, v130
	v_fma_f32 v50, |v2|, s92, 1.0
	v_rcp_f32_e32 v50, v50
	v_cmp_gt_f32_e32 vcc, 0, v2
	v_add_f32_e32 v3, v3, v51
	v_add_u32_e32 v136, 0x41, v94
	v_fmamk_f32 v120, v50, 0x3f07dc22, v236
	v_fmaak_f32 v120, v50, v120, 0x3f35f0e3
	v_fmaak_f32 v120, v50, v120, 0xbe11a98e
	v_fmaak_f32 v120, v50, v120, 0x3e027906
	v_mul_f32_e32 v50, v50, v120
	v_mul_f32_e32 v120, v2, v2
	v_mul_f32_e32 v120, 0xbf38aa3b, v120
	v_exp_f32_e32 v120, v120
	v_ashrrev_i32_e32 v137, 31, v136
	v_mul_f32_e32 v50, v120, v50
	v_mul_f32_e32 v120, v50, v2
	v_fma_f32 v50, -v50, v2, v2
	v_cndmask_b32_e32 v2, v50, v120, vcc
	v_mul_f32_e32 v2, v2, v3
	v_cvt_pk_bf16_f32 v50, v2, s0
	v_lshlrev_b64 v[2:3], 11, v[94:95]
	v_lshl_add_u64 v[2:3], v[106:107], 0, v[2:3]
	global_store_short v[2:3], v50, off
	s_waitcnt vmcnt(31)
	v_lshlrev_b32_e32 v2, 16, v165
	v_fma_f32 v3, |v2|, s92, 1.0
	v_rcp_f32_e32 v3, v3
	v_cmp_gt_f32_e32 vcc, 0, v2
	v_add_u32_e32 v120, 0x59, v94
	v_ashrrev_i32_e32 v121, 31, v120
	v_fmamk_f32 v50, v3, 0x3f07dc22, v236
	v_fmaak_f32 v50, v3, v50, 0x3f35f0e3
	v_fmaak_f32 v50, v3, v50, 0xbe11a98e
	v_fmaak_f32 v50, v3, v50, 0x3e027906
	v_mul_f32_e32 v3, v3, v50
	v_mul_f32_e32 v50, v2, v2
	v_mul_f32_e32 v50, 0xbf38aa3b, v50
	v_exp_f32_e32 v50, v50
	s_nop 0
	v_mul_f32_e32 v3, v50, v3
	v_mul_f32_e32 v50, v3, v2
	v_fma_f32 v3, -v3, v2, v2
	v_cndmask_b32_e32 v2, v3, v50, vcc
	v_add_f32_e32 v3, v4, v52
	v_mul_f32_e32 v2, v2, v3
	v_cvt_pk_bf16_f32 v4, v2, s0
	v_lshlrev_b64 v[2:3], 11, v[118:119]
	v_lshl_add_u64 v[2:3], v[106:107], 0, v[2:3]
	global_store_short v[2:3], v4, off
	s_waitcnt vmcnt(31)
	v_lshlrev_b32_e32 v2, 16, v206
	v_fma_f32 v3, |v2|, s92, 1.0
	v_rcp_f32_e32 v3, v3
	v_cmp_gt_f32_e32 vcc, 0, v2
	v_add_u32_e32 v118, 0x4a, v94
	v_ashrrev_i32_e32 v119, 31, v118
	v_fmamk_f32 v4, v3, 0x3f07dc22, v236
	v_fmaak_f32 v4, v3, v4, 0x3f35f0e3
	v_fmaak_f32 v4, v3, v4, 0xbe11a98e
	v_fmaak_f32 v4, v3, v4, 0x3e027906
	v_mul_f32_e32 v3, v3, v4
	v_mul_f32_e32 v4, v2, v2
	v_mul_f32_e32 v4, 0xbf38aa3b, v4
	v_exp_f32_e32 v4, v4
	s_nop 0
	v_mul_f32_e32 v3, v4, v3
	v_mul_f32_e32 v4, v3, v2
	v_fma_f32 v3, -v3, v2, v2
	v_cndmask_b32_e32 v2, v3, v4, vcc
	v_add_f32_e32 v3, v5, v53
	v_mul_f32_e32 v2, v2, v3
	v_cvt_pk_bf16_f32 v4, v2, s0
	v_lshlrev_b64 v[2:3], 11, v[116:117]
	v_lshl_add_u64 v[2:3], v[106:107], 0, v[2:3]
	global_store_short v[2:3], v4, off
	s_waitcnt vmcnt(31)
	v_lshlrev_b32_e32 v2, 16, v207
	v_fma_f32 v3, |v2|, s92, 1.0
	v_rcp_f32_e32 v3, v3
	v_cmp_gt_f32_e32 vcc, 0, v2
	v_add_u32_e32 v116, 0x4f, v94
	v_mad_i64_i32 v[164:165], s[6:7], v116, s87, v[92:93]
	v_fmamk_f32 v4, v3, 0x3f07dc22, v236
	v_fmaak_f32 v4, v3, v4, 0x3f35f0e3
	v_fmaak_f32 v4, v3, v4, 0xbe11a98e
	v_fmaak_f32 v4, v3, v4, 0x3e027906
	v_mul_f32_e32 v3, v3, v4
	v_mul_f32_e32 v4, v2, v2
	v_mul_f32_e32 v4, 0xbf38aa3b, v4
	v_exp_f32_e32 v4, v4
	v_mad_i64_i32 v[206:207], s[6:7], v120, s87, v[92:93]
	v_ashrrev_i32_e32 v117, 31, v116
	v_mul_f32_e32 v3, v4, v3
	v_mul_f32_e32 v4, v3, v2
	v_fma_f32 v3, -v3, v2, v2
	v_cndmask_b32_e32 v2, v3, v4, vcc
	s_waitcnt lgkmcnt(0)
	v_add_f32_e32 v3, v6, v122
	v_mul_f32_e32 v2, v2, v3
	v_cvt_pk_bf16_f32 v4, v2, s0
	v_lshlrev_b64 v[2:3], 11, v[114:115]
	v_lshl_add_u64 v[2:3], v[106:107], 0, v[2:3]
	global_store_short v[2:3], v4, off
	s_waitcnt vmcnt(31)
	v_lshlrev_b32_e32 v2, 16, v208
	v_fma_f32 v3, |v2|, s92, 1.0
	v_rcp_f32_e32 v3, v3
	v_cmp_gt_f32_e32 vcc, 0, v2
	v_add_u32_e32 v122, 0x49, v94
	v_add_u32_e32 v114, 0x5a, v94
	v_fmamk_f32 v4, v3, 0x3f07dc22, v236
	v_fmaak_f32 v4, v3, v4, 0x3f35f0e3
	v_fmaak_f32 v4, v3, v4, 0xbe11a98e
	v_fmaak_f32 v4, v3, v4, 0x3e027906
	v_mul_f32_e32 v3, v3, v4
	v_mul_f32_e32 v4, v2, v2
	v_mul_f32_e32 v4, 0xbf38aa3b, v4
	v_exp_f32_e32 v4, v4
	v_ashrrev_i32_e32 v115, 31, v114
	v_mul_f32_e32 v3, v4, v3
	v_mul_f32_e32 v4, v3, v2
	v_fma_f32 v3, -v3, v2, v2
	v_cndmask_b32_e32 v2, v3, v4, vcc
	v_add_f32_e32 v3, v7, v123
	v_mul_f32_e32 v2, v2, v3
	v_cvt_pk_bf16_f32 v4, v2, s0
	v_lshlrev_b64 v[2:3], 11, v[112:113]
	v_lshl_add_u64 v[2:3], v[106:107], 0, v[2:3]
	global_store_short v[2:3], v4, off
	s_waitcnt vmcnt(31)
	v_lshlrev_b32_e32 v2, 16, v209
	v_fma_f32 v3, |v2|, s92, 1.0
	v_rcp_f32_e32 v3, v3
	v_cmp_gt_f32_e32 vcc, 0, v2
	v_add_u32_e32 v112, 0x50, v94
	v_mad_i64_i32 v[166:167], s[6:7], v112, s87, v[92:93]
	v_fmamk_f32 v4, v3, 0x3f07dc22, v236
	v_fmaak_f32 v4, v3, v4, 0x3f35f0e3
	v_fmaak_f32 v4, v3, v4, 0xbe11a98e
	v_fmaak_f32 v4, v3, v4, 0x3e027906
	v_mul_f32_e32 v3, v3, v4
	v_mul_f32_e32 v4, v2, v2
	v_mul_f32_e32 v4, 0xbf38aa3b, v4
	v_exp_f32_e32 v4, v4
	v_mad_i64_i32 v[208:209], s[6:7], v114, s87, v[92:93]
	v_ashrrev_i32_e32 v123, 31, v122
	v_mul_f32_e32 v3, v4, v3
	v_mul_f32_e32 v4, v3, v2
	v_fma_f32 v3, -v3, v2, v2
	v_cndmask_b32_e32 v2, v3, v4, vcc
	v_add_f32_e32 v3, v8, v124
	v_mul_f32_e32 v2, v2, v3
	v_cvt_pk_bf16_f32 v4, v2, s0
	v_lshlrev_b64 v[2:3], 11, v[110:111]
	v_lshl_add_u64 v[2:3], v[106:107], 0, v[2:3]
	global_store_short v[2:3], v4, off
	s_waitcnt vmcnt(31)
	v_lshlrev_b32_e32 v2, 16, v210
	v_fma_f32 v3, |v2|, s92, 1.0
	v_rcp_f32_e32 v3, v3
	v_cmp_gt_f32_e32 vcc, 0, v2
	v_add_u32_e32 v110, 0x51, v94
	v_add_u32_e32 v124, 0x58, v94
	v_fmamk_f32 v4, v3, 0x3f07dc22, v236
	v_fmaak_f32 v4, v3, v4, 0x3f35f0e3
	v_fmaak_f32 v4, v3, v4, 0xbe11a98e
	v_fmaak_f32 v4, v3, v4, 0x3e027906
	v_mul_f32_e32 v3, v3, v4
	v_mul_f32_e32 v4, v2, v2
	v_mul_f32_e32 v4, 0xbf38aa3b, v4
	v_exp_f32_e32 v4, v4
	v_mad_i64_i32 v[168:169], s[6:7], v110, s87, v[92:93]
	v_mad_i64_i32 v[204:205], s[6:7], v124, s87, v[92:93]
	v_mul_f32_e32 v3, v4, v3
	v_mul_f32_e32 v4, v3, v2
	v_fma_f32 v3, -v3, v2, v2
	v_cndmask_b32_e32 v2, v3, v4, vcc
	v_add_f32_e32 v3, v9, v125
	v_mul_f32_e32 v2, v2, v3
	v_cvt_pk_bf16_f32 v4, v2, s0
	v_lshlrev_b64 v[2:3], 11, v[108:109]
	v_lshl_add_u64 v[2:3], v[106:107], 0, v[2:3]
	global_store_short v[2:3], v4, off
	s_waitcnt vmcnt(31)
	v_lshlrev_b32_e32 v2, 16, v126
	v_fma_f32 v3, |v2|, s92, 1.0
	v_rcp_f32_e32 v3, v3
	v_cmp_gt_f32_e32 vcc, 0, v2
	v_add_u32_e32 v126, 0x48, v94
	v_add_u32_e32 v108, 0x52, v94
	v_fmamk_f32 v4, v3, 0x3f07dc22, v236
	v_fmaak_f32 v4, v3, v4, 0x3f35f0e3
	v_fmaak_f32 v4, v3, v4, 0xbe11a98e
	v_fmaak_f32 v4, v3, v4, 0x3e027906
	v_mul_f32_e32 v3, v3, v4
	v_mul_f32_e32 v4, v2, v2
	v_mul_f32_e32 v4, 0xbf38aa3b, v4
	v_exp_f32_e32 v4, v4
	v_mad_i64_i32 v[170:171], s[6:7], v108, s87, v[92:93]
	v_ashrrev_i32_e32 v113, 31, v112
	v_mul_f32_e32 v3, v4, v3
	v_mul_f32_e32 v4, v3, v2
	v_fma_f32 v3, -v3, v2, v2
	v_cndmask_b32_e32 v6, v3, v4, vcc
	ds_read_b128 v[2:5], v1 offset:64
	v_ashrrev_i32_e32 v111, 31, v110
	v_ashrrev_i32_e32 v109, 31, v108
	v_ashrrev_i32_e32 v125, 31, v124
	s_waitcnt lgkmcnt(0)
	v_add_f32_e32 v2, v10, v2
	v_mul_f32_e32 v2, v6, v2
	v_lshlrev_b64 v[6:7], 11, v[72:73]
	v_cvt_pk_bf16_f32 v2, v2, s0
	v_lshl_add_u64 v[6:7], v[106:107], 0, v[6:7]
	global_store_short v[6:7], v2, off
	s_waitcnt vmcnt(31)
	v_lshlrev_b32_e32 v2, 16, v127
	v_fma_f32 v6, |v2|, s92, 1.0
	v_rcp_f32_e32 v6, v6
	v_cmp_gt_f32_e32 vcc, 0, v2
	v_add_f32_e32 v3, v11, v3
	v_ashrrev_i32_e32 v127, 31, v126
	v_fmamk_f32 v7, v6, 0x3f07dc22, v236
	v_fmaak_f32 v7, v6, v7, 0x3f35f0e3
	v_fmaak_f32 v7, v6, v7, 0xbe11a98e
	v_fmaak_f32 v7, v6, v7, 0x3e027906
	v_mul_f32_e32 v6, v6, v7
	v_mul_f32_e32 v7, v2, v2
	v_mul_f32_e32 v7, 0xbf38aa3b, v7
	v_exp_f32_e32 v7, v7
	s_nop 0
	v_mul_f32_e32 v6, v7, v6
	v_mul_f32_e32 v7, v6, v2
	v_fma_f32 v6, -v6, v2, v2
	v_cndmask_b32_e32 v2, v6, v7, vcc
	v_mul_f32_e32 v2, v2, v3
	v_cvt_pk_bf16_f32 v6, v2, s0
	v_lshlrev_b64 v[2:3], 11, v[68:69]
	v_lshl_add_u64 v[2:3], v[106:107], 0, v[2:3]
	global_store_short v[2:3], v6, off
	s_waitcnt vmcnt(31)
	v_lshlrev_b32_e32 v2, 16, v128
	v_fma_f32 v3, |v2|, s92, 1.0
	v_rcp_f32_e32 v3, v3
	v_cmp_gt_f32_e32 vcc, 0, v2
	v_add_u32_e32 v128, 0x57, v94
	v_mad_i64_i32 v[188:189], s[6:7], v128, s87, v[92:93]
	v_fmamk_f32 v6, v3, 0x3f07dc22, v236
	v_fmaak_f32 v6, v3, v6, 0x3f35f0e3
	v_fmaak_f32 v6, v3, v6, 0xbe11a98e
	v_fmaak_f32 v6, v3, v6, 0x3e027906
	v_mul_f32_e32 v3, v3, v6
	v_mul_f32_e32 v6, v2, v2
	v_mul_f32_e32 v6, 0xbf38aa3b, v6
	v_exp_f32_e32 v6, v6
	s_nop 0
	v_mul_f32_e32 v3, v6, v3
	v_mul_f32_e32 v6, v3, v2
	v_fma_f32 v3, -v3, v2, v2
	v_cndmask_b32_e32 v2, v3, v6, vcc
	v_add_f32_e32 v3, v12, v4
	v_mul_f32_e32 v2, v2, v3
	v_cvt_pk_bf16_f32 v4, v2, s0
	v_lshlrev_b64 v[2:3], 11, v[66:67]
	v_lshl_add_u64 v[2:3], v[106:107], 0, v[2:3]
	global_store_short v[2:3], v4, off
	s_waitcnt vmcnt(31)
	v_lshlrev_b32_e32 v2, 16, v129
	v_fma_f32 v3, |v2|, s92, 1.0
	v_rcp_f32_e32 v3, v3
	v_cmp_gt_f32_e32 vcc, 0, v2
	v_ashrrev_i32_e32 v129, 31, v128
	v_fmamk_f32 v4, v3, 0x3f07dc22, v236
	v_fmaak_f32 v4, v3, v4, 0x3f35f0e3
	v_fmaak_f32 v4, v3, v4, 0xbe11a98e
	v_fmaak_f32 v4, v3, v4, 0x3e027906
	v_mul_f32_e32 v3, v3, v4
	v_mul_f32_e32 v4, v2, v2
	v_mul_f32_e32 v4, 0xbf38aa3b, v4
	v_exp_f32_e32 v4, v4
	s_nop 0
	v_mul_f32_e32 v3, v4, v3
	v_mul_f32_e32 v4, v3, v2
	v_fma_f32 v3, -v3, v2, v2
	v_cndmask_b32_e32 v2, v3, v4, vcc
	v_add_f32_e32 v3, v13, v5
	v_mul_f32_e32 v2, v2, v3
	v_cvt_pk_bf16_f32 v4, v2, s0
	v_lshlrev_b64 v[2:3], 11, v[64:65]
	v_lshl_add_u64 v[2:3], v[106:107], 0, v[2:3]
	global_store_short v[2:3], v4, off
	s_waitcnt vmcnt(31)
	v_lshlrev_b32_e32 v2, 16, v132
	v_fma_f32 v3, |v2|, s92, 1.0
	v_rcp_f32_e32 v3, v3
	v_cmp_gt_f32_e32 vcc, 0, v2
	v_add_u32_e32 v132, 0x47, v94
	v_mad_i64_i32 v[10:11], s[6:7], v132, s87, v[92:93]
	v_fmamk_f32 v4, v3, 0x3f07dc22, v236
	v_fmaak_f32 v4, v3, v4, 0x3f35f0e3
	v_fmaak_f32 v4, v3, v4, 0xbe11a98e
	v_fmaak_f32 v4, v3, v4, 0x3e027906
	v_mul_f32_e32 v3, v3, v4
	v_mul_f32_e32 v4, v2, v2
	v_mul_f32_e32 v4, 0xbf38aa3b, v4
	v_exp_f32_e32 v4, v4
	v_mad_i64_i32 v[12:13], s[6:7], v126, s87, v[92:93]
	v_mul_f32_e32 v3, v4, v3
	v_mul_f32_e32 v4, v3, v2
	v_fma_f32 v3, -v3, v2, v2
	v_cndmask_b32_e32 v6, v3, v4, vcc
	ds_read_b128 v[2:5], v1 offset:96
	s_waitcnt lgkmcnt(0)
	v_add_f32_e32 v2, v14, v2
	v_mul_f32_e32 v2, v6, v2
	v_lshlrev_b64 v[6:7], 11, v[62:63]
	v_cvt_pk_bf16_f32 v2, v2, s0
	v_lshl_add_u64 v[6:7], v[106:107], 0, v[6:7]
	global_store_short v[6:7], v2, off
	s_waitcnt vmcnt(31)
	v_lshlrev_b32_e32 v2, 16, v133
	v_fma_f32 v6, |v2|, s92, 1.0
	v_rcp_f32_e32 v6, v6
	v_cmp_gt_f32_e32 vcc, 0, v2
	v_add_f32_e32 v3, v15, v3
	v_mad_i64_i32 v[14:15], s[6:7], v122, s87, v[92:93]
	v_fmamk_f32 v7, v6, 0x3f07dc22, v236
	v_fmaak_f32 v7, v6, v7, 0x3f35f0e3
	v_fmaak_f32 v7, v6, v7, 0xbe11a98e
	v_fmaak_f32 v7, v6, v7, 0x3e027906
	v_mul_f32_e32 v6, v6, v7
	v_mul_f32_e32 v7, v2, v2
	v_mul_f32_e32 v7, 0xbf38aa3b, v7
	v_exp_f32_e32 v7, v7
	v_ashrrev_i32_e32 v133, 31, v132
	v_mul_f32_e32 v6, v7, v6
	v_mul_f32_e32 v7, v6, v2
	v_fma_f32 v6, -v6, v2, v2
	v_cndmask_b32_e32 v2, v6, v7, vcc
	v_mul_f32_e32 v2, v2, v3
	v_cvt_pk_bf16_f32 v6, v2, s0
	v_lshlrev_b64 v[2:3], 11, v[60:61]
	v_lshl_add_u64 v[2:3], v[106:107], 0, v[2:3]
	global_store_short v[2:3], v6, off
	s_waitcnt vmcnt(31)
	v_lshlrev_b32_e32 v2, 16, v134
	v_fma_f32 v3, |v2|, s92, 1.0
	v_rcp_f32_e32 v3, v3
	v_cmp_gt_f32_e32 vcc, 0, v2
	v_add_u32_e32 v134, 0x42, v94
	v_mad_i64_i32 v[8:9], s[6:7], v134, s87, v[92:93]
	v_fmamk_f32 v6, v3, 0x3f07dc22, v236
	v_fmaak_f32 v6, v3, v6, 0x3f35f0e3
	v_fmaak_f32 v6, v3, v6, 0xbe11a98e
	v_fmaak_f32 v6, v3, v6, 0x3e027906
	v_mul_f32_e32 v3, v3, v6
	v_mul_f32_e32 v6, v2, v2
	v_mul_f32_e32 v6, 0xbf38aa3b, v6
	v_exp_f32_e32 v6, v6
	s_nop 0
	v_mul_f32_e32 v3, v6, v3
	v_mul_f32_e32 v6, v3, v2
	v_fma_f32 v3, -v3, v2, v2
	v_cndmask_b32_e32 v2, v3, v6, vcc
	v_add_f32_e32 v3, v16, v4
	v_mul_f32_e32 v2, v2, v3
	v_cvt_pk_bf16_f32 v4, v2, s0
	v_lshlrev_b64 v[2:3], 11, v[58:59]
	v_lshl_add_u64 v[2:3], v[106:107], 0, v[2:3]
	global_store_short v[2:3], v4, off
	s_waitcnt vmcnt(31)
	v_lshlrev_b32_e32 v2, 16, v135
	v_fma_f32 v3, |v2|, s92, 1.0
	v_rcp_f32_e32 v3, v3
	v_cmp_gt_f32_e32 vcc, 0, v2
	v_mad_i64_i32 v[6:7], s[6:7], v136, s87, v[92:93]
	v_fmamk_f32 v4, v3, 0x3f07dc22, v236
	v_fmaak_f32 v4, v3, v4, 0x3f35f0e3
	v_fmaak_f32 v4, v3, v4, 0xbe11a98e
	v_fmaak_f32 v4, v3, v4, 0x3e027906
	v_mul_f32_e32 v3, v3, v4
	v_mul_f32_e32 v4, v2, v2
	v_mul_f32_e32 v4, 0xbf38aa3b, v4
	v_exp_f32_e32 v4, v4
	v_ashrrev_i32_e32 v135, 31, v134
	v_mul_f32_e32 v3, v4, v3
	v_mul_f32_e32 v4, v3, v2
	v_fma_f32 v3, -v3, v2, v2
	v_cndmask_b32_e32 v2, v3, v4, vcc
	v_add_f32_e32 v3, v17, v5
	v_mul_f32_e32 v2, v2, v3
	v_cvt_pk_bf16_f32 v4, v2, s0
	v_lshlrev_b64 v[2:3], 11, v[56:57]
	v_lshl_add_u64 v[2:3], v[106:107], 0, v[2:3]
	global_store_short v[2:3], v4, off
	v_mad_i64_i32 v[2:3], s[6:7], v140, s87, v[92:93]
	v_mad_i64_i32 v[4:5], s[6:7], v138, s87, v[92:93]
	v_mad_i64_i32 v[16:17], s[6:7], v118, s87, v[92:93]
	global_load_dwordx4 v[50:53], v[54:55], off offset:2048
	s_nop 0
	global_load_dwordx4 v[54:57], v[54:55], off offset:3072
	s_nop 0
	global_load_dwordx4 v[58:61], v[70:71], off
	global_load_dwordx4 v[62:65], v[70:71], off offset:1024
	global_load_dwordx4 v[66:69], v[70:71], off offset:2048
	s_nop 0
	global_load_dwordx4 v[70:73], v[70:71], off offset:3072
	s_nop 0
	global_load_ushort v202, v[2:3], off
	global_load_ushort v201, v[4:5], off
	global_load_ushort v200, v[6:7], off
	global_load_ushort v199, v[8:9], off
	global_load_ushort v198, v[10:11], off
	global_load_ushort v197, v[12:13], off
	global_load_ushort v196, v[14:15], off
	global_load_ushort v195, v[16:17], off
	global_load_ushort v194, v[164:165], off
	global_load_ushort v193, v[166:167], off
	global_load_ushort v192, v[168:169], off
	global_load_ushort v191, v[170:171], off
	global_load_ushort v190, v[188:189], off
	s_nop 0
	global_load_ushort v189, v[204:205], off
	global_load_ushort v188, v[206:207], off
	global_load_ushort v130, v[208:209], off
	v_mfma_f32_32x32x16_bf16 v[2:17], v[74:77], v[18:21], 0
	s_waitcnt vmcnt(53)
	v_lshlrev_b32_e32 v74, 16, v187
	v_fma_f32 v75, |v74|, s92, 1.0
	v_rcp_f32_e32 v75, v75
	v_cmp_gt_f32_e32 vcc, 0, v74
	v_add_u32_e32 v170, 0x6f, v94
	v_fmamk_f32 v76, v75, 0x3f07dc22, v236
	v_mfma_f32_32x32x16_bf16 v[2:17], v[78:81], v[22:25], v[2:17]
	v_fmaak_f32 v76, v75, v76, 0x3f35f0e3
	v_fmaak_f32 v76, v75, v76, 0xbe11a98e
	v_fmaak_f32 v76, v75, v76, 0x3e027906
	v_mul_f32_e32 v75, v75, v76
	v_mul_f32_e32 v76, v74, v74
	v_mul_f32_e32 v76, 0xbf38aa3b, v76
	v_exp_f32_e32 v76, v76
	v_mfma_f32_32x32x16_bf16 v[2:17], v[82:85], v[26:29], v[2:17]
	v_add_u32_e32 v168, 0x70, v94
	v_add_u32_e32 v166, 0x71, v94
	v_mul_f32_e32 v75, v76, v75
	v_mul_f32_e32 v76, v75, v74
	v_fma_f32 v75, -v75, v74, v74
	v_cndmask_b32_e32 v82, v75, v76, vcc
	ds_read_b128 v[74:77], v1 offset:128
	ds_read_b128 v[78:81], v1 offset:160
	v_mfma_f32_32x32x16_bf16 v[2:17], v[86:89], v[30:33], v[2:17]
	v_add_u32_e32 v164, 0x72, v94
	v_ashrrev_i32_e32 v171, 31, v170
	v_ashrrev_i32_e32 v169, 31, v168
	v_ashrrev_i32_e32 v167, 31, v166
	v_ashrrev_i32_e32 v165, 31, v164
	s_waitcnt lgkmcnt(1)
	s_nop 5
	v_add_f32_e32 v2, v2, v74
	v_mul_f32_e32 v2, v82, v2
	v_lshlrev_b64 v[82:83], 11, v[162:163]
	v_cvt_pk_bf16_f32 v2, v2, s0
	v_lshl_add_u64 v[82:83], v[106:107], 0, v[82:83]
	global_store_short v[82:83], v2, off
	s_waitcnt vmcnt(53)
	v_lshlrev_b32_e32 v2, 16, v186
	v_fma_f32 v74, |v2|, s92, 1.0
	v_rcp_f32_e32 v74, v74
	v_cmp_gt_f32_e32 vcc, 0, v2
	v_add_f32_e32 v3, v3, v75
	v_add_u32_e32 v162, 0x77, v94
	v_fmamk_f32 v82, v74, 0x3f07dc22, v236
	v_fmaak_f32 v82, v74, v82, 0x3f35f0e3
	v_fmaak_f32 v82, v74, v82, 0xbe11a98e
	v_fmaak_f32 v82, v74, v82, 0x3e027906
	v_mul_f32_e32 v74, v74, v82
	v_mul_f32_e32 v82, v2, v2
	v_mul_f32_e32 v82, 0xbf38aa3b, v82
	v_exp_f32_e32 v82, v82
	v_ashrrev_i32_e32 v163, 31, v162
	v_mul_f32_e32 v74, v82, v74
	v_mul_f32_e32 v82, v74, v2
	v_fma_f32 v74, -v74, v2, v2
	v_cndmask_b32_e32 v2, v74, v82, vcc
	v_mul_f32_e32 v2, v2, v3
	v_cvt_pk_bf16_f32 v74, v2, s0
	v_lshlrev_b64 v[2:3], 11, v[160:161]
	v_lshl_add_u64 v[2:3], v[106:107], 0, v[2:3]
	global_store_short v[2:3], v74, off
	s_waitcnt vmcnt(53)
	v_lshlrev_b32_e32 v2, 16, v185
	v_fma_f32 v3, |v2|, s92, 1.0
	v_rcp_f32_e32 v3, v3
	v_cmp_gt_f32_e32 vcc, 0, v2
	v_add_u32_e32 v160, 0x78, v94
	v_ashrrev_i32_e32 v161, 31, v160
	v_fmamk_f32 v74, v3, 0x3f07dc22, v236
	v_fmaak_f32 v74, v3, v74, 0x3f35f0e3
	v_fmaak_f32 v74, v3, v74, 0xbe11a98e
	v_fmaak_f32 v74, v3, v74, 0x3e027906
	v_mul_f32_e32 v3, v3, v74
	v_mul_f32_e32 v74, v2, v2
	v_mul_f32_e32 v74, 0xbf38aa3b, v74
	v_exp_f32_e32 v74, v74
	s_nop 0
	v_mul_f32_e32 v3, v74, v3
	v_mul_f32_e32 v74, v3, v2
	v_fma_f32 v3, -v3, v2, v2
	v_cndmask_b32_e32 v2, v3, v74, vcc
	v_add_f32_e32 v3, v4, v76
	v_mul_f32_e32 v2, v2, v3
	v_cvt_pk_bf16_f32 v4, v2, s0
	v_lshlrev_b64 v[2:3], 11, v[158:159]
	v_lshl_add_u64 v[2:3], v[106:107], 0, v[2:3]
	global_store_short v[2:3], v4, off
	s_waitcnt vmcnt(53)
	v_lshlrev_b32_e32 v2, 16, v184
	v_fma_f32 v3, |v2|, s92, 1.0
	v_rcp_f32_e32 v3, v3
	v_cmp_gt_f32_e32 vcc, 0, v2
	v_add_u32_e32 v158, 0x79, v94
	v_mad_i64_i32 v[184:185], s[6:7], v160, s87, v[92:93]
	v_fmamk_f32 v4, v3, 0x3f07dc22, v236
	v_fmaak_f32 v4, v3, v4, 0x3f35f0e3
	v_fmaak_f32 v4, v3, v4, 0xbe11a98e
	v_fmaak_f32 v4, v3, v4, 0x3e027906
	v_mul_f32_e32 v3, v3, v4
	v_mul_f32_e32 v4, v2, v2
	v_mul_f32_e32 v4, 0xbf38aa3b, v4
	v_exp_f32_e32 v4, v4
	v_mad_i64_i32 v[186:187], s[6:7], v158, s87, v[92:93]
	v_ashrrev_i32_e32 v159, 31, v158
	v_mul_f32_e32 v3, v4, v3
	v_mul_f32_e32 v4, v3, v2
	v_fma_f32 v3, -v3, v2, v2
	v_cndmask_b32_e32 v2, v3, v4, vcc
	v_add_f32_e32 v3, v5, v77
	v_mul_f32_e32 v2, v2, v3
	v_cvt_pk_bf16_f32 v4, v2, s0
	v_lshlrev_b64 v[2:3], 11, v[156:157]
	v_lshl_add_u64 v[2:3], v[106:107], 0, v[2:3]
	global_store_short v[2:3], v4, off
	s_waitcnt vmcnt(53)
	v_lshlrev_b32_e32 v2, 16, v183
	v_fma_f32 v3, |v2|, s92, 1.0
	v_rcp_f32_e32 v3, v3
	v_cmp_gt_f32_e32 vcc, 0, v2
	v_add_u32_e32 v156, 0x7a, v94
	v_mad_i64_i32 v[214:215], s[6:7], v156, s87, v[92:93]
	v_fmamk_f32 v4, v3, 0x3f07dc22, v236
	v_fmaak_f32 v4, v3, v4, 0x3f35f0e3
	v_fmaak_f32 v4, v3, v4, 0xbe11a98e
	v_fmaak_f32 v4, v3, v4, 0x3e027906
	v_mul_f32_e32 v3, v3, v4
	v_mul_f32_e32 v4, v2, v2
	v_mul_f32_e32 v4, 0xbf38aa3b, v4
	v_exp_f32_e32 v4, v4
	v_ashrrev_i32_e32 v157, 31, v156
	v_mul_f32_e32 v3, v4, v3
	v_mul_f32_e32 v4, v3, v2
	v_fma_f32 v3, -v3, v2, v2
	v_cndmask_b32_e32 v2, v3, v4, vcc
	s_waitcnt lgkmcnt(0)
	v_add_f32_e32 v3, v6, v78
	v_mul_f32_e32 v2, v2, v3
	v_cvt_pk_bf16_f32 v4, v2, s0
	v_lshlrev_b64 v[2:3], 11, v[154:155]
	v_lshl_add_u64 v[2:3], v[106:107], 0, v[2:3]
	global_store_short v[2:3], v4, off
	s_waitcnt vmcnt(53)
	v_lshlrev_b32_e32 v2, 16, v182
	v_fma_f32 v3, |v2|, s92, 1.0
	v_rcp_f32_e32 v3, v3
	v_cmp_gt_f32_e32 vcc, 0, v2
	v_add_u32_e32 v154, 0x60, v94
	v_mad_i64_i32 v[182:183], s[6:7], v162, s87, v[92:93]
	v_fmamk_f32 v4, v3, 0x3f07dc22, v236
	v_fmaak_f32 v4, v3, v4, 0x3f35f0e3
	v_fmaak_f32 v4, v3, v4, 0xbe11a98e
	v_fmaak_f32 v4, v3, v4, 0x3e027906
	v_mul_f32_e32 v3, v3, v4
	v_mul_f32_e32 v4, v2, v2
	v_mul_f32_e32 v4, 0xbf38aa3b, v4
	v_exp_f32_e32 v4, v4
	v_ashrrev_i32_e32 v155, 31, v154
	v_mul_f32_e32 v3, v4, v3
	v_mul_f32_e32 v4, v3, v2
	v_fma_f32 v3, -v3, v2, v2
	v_cndmask_b32_e32 v2, v3, v4, vcc
	v_add_f32_e32 v3, v7, v79
	v_mul_f32_e32 v2, v2, v3
	v_cvt_pk_bf16_f32 v4, v2, s0
	v_lshlrev_b64 v[2:3], 11, v[152:153]
	v_lshl_add_u64 v[2:3], v[106:107], 0, v[2:3]
	global_store_short v[2:3], v4, off
	s_waitcnt vmcnt(53)
	v_lshlrev_b32_e32 v2, 16, v181
	v_fma_f32 v3, |v2|, s92, 1.0
	v_rcp_f32_e32 v3, v3
	v_cmp_gt_f32_e32 vcc, 0, v2
	v_add_u32_e32 v152, 0x61, v94
	v_ashrrev_i32_e32 v153, 31, v152
	v_fmamk_f32 v4, v3, 0x3f07dc22, v236
	v_fmaak_f32 v4, v3, v4, 0x3f35f0e3
	v_fmaak_f32 v4, v3, v4, 0xbe11a98e
	v_fmaak_f32 v4, v3, v4, 0x3e027906
	v_mul_f32_e32 v3, v3, v4
	v_mul_f32_e32 v4, v2, v2
	v_mul_f32_e32 v4, 0xbf38aa3b, v4
	v_exp_f32_e32 v4, v4
	s_nop 0
	v_mul_f32_e32 v3, v4, v3
	v_mul_f32_e32 v4, v3, v2
	v_fma_f32 v3, -v3, v2, v2
	v_cndmask_b32_e32 v2, v3, v4, vcc
	v_add_f32_e32 v3, v8, v80
	v_mul_f32_e32 v2, v2, v3
	v_cvt_pk_bf16_f32 v4, v2, s0
	v_lshlrev_b64 v[2:3], 11, v[150:151]
	v_lshl_add_u64 v[2:3], v[106:107], 0, v[2:3]
	global_store_short v[2:3], v4, off
	s_waitcnt vmcnt(53)
	v_lshlrev_b32_e32 v2, 16, v180
	v_fma_f32 v3, |v2|, s92, 1.0
	v_rcp_f32_e32 v3, v3
	v_cmp_gt_f32_e32 vcc, 0, v2
	v_add_u32_e32 v150, 0x67, v94
	v_mad_i64_i32 v[180:181], s[6:7], v164, s87, v[92:93]
	v_fmamk_f32 v4, v3, 0x3f07dc22, v236
	v_fmaak_f32 v4, v3, v4, 0x3f35f0e3
	v_fmaak_f32 v4, v3, v4, 0xbe11a98e
	v_fmaak_f32 v4, v3, v4, 0x3e027906
	v_mul_f32_e32 v3, v3, v4
	v_mul_f32_e32 v4, v2, v2
	v_mul_f32_e32 v4, 0xbf38aa3b, v4
	v_exp_f32_e32 v4, v4
	v_ashrrev_i32_e32 v151, 31, v150
	v_mul_f32_e32 v3, v4, v3
	v_mul_f32_e32 v4, v3, v2
	v_fma_f32 v3, -v3, v2, v2
	v_cndmask_b32_e32 v2, v3, v4, vcc
	v_add_f32_e32 v3, v9, v81
	v_mul_f32_e32 v2, v2, v3
	v_cvt_pk_bf16_f32 v4, v2, s0
	v_lshlrev_b64 v[2:3], 11, v[148:149]
	v_lshl_add_u64 v[2:3], v[106:107], 0, v[2:3]
	global_store_short v[2:3], v4, off
	s_waitcnt vmcnt(53)
	v_lshlrev_b32_e32 v2, 16, v179
	v_fma_f32 v3, |v2|, s92, 1.0
	v_rcp_f32_e32 v3, v3
	v_cmp_gt_f32_e32 vcc, 0, v2
	v_add_u32_e32 v148, 0x62, v94
	v_mad_i64_i32 v[8:9], s[6:7], v148, s87, v[92:93]
	v_fmamk_f32 v4, v3, 0x3f07dc22, v236
	v_fmaak_f32 v4, v3, v4, 0x3f35f0e3
	v_fmaak_f32 v4, v3, v4, 0xbe11a98e
	v_fmaak_f32 v4, v3, v4, 0x3e027906
	v_mul_f32_e32 v3, v3, v4
	v_mul_f32_e32 v4, v2, v2
	v_mul_f32_e32 v4, 0xbf38aa3b, v4
	v_exp_f32_e32 v4, v4
	v_ashrrev_i32_e32 v149, 31, v148
	v_mul_f32_e32 v3, v4, v3
	v_mul_f32_e32 v4, v3, v2
	v_fma_f32 v3, -v3, v2, v2
	v_cndmask_b32_e32 v6, v3, v4, vcc
	ds_read_b128 v[2:5], v1 offset:192
	s_waitcnt lgkmcnt(0)
	v_add_f32_e32 v2, v10, v2
	v_mul_f32_e32 v2, v6, v2
	v_lshlrev_b64 v[6:7], 11, v[146:147]
	v_cvt_pk_bf16_f32 v2, v2, s0
	v_lshl_add_u64 v[6:7], v[106:107], 0, v[6:7]
	global_store_short v[6:7], v2, off
	s_waitcnt vmcnt(53)
	v_lshlrev_b32_e32 v2, 16, v178
	v_fma_f32 v6, |v2|, s92, 1.0
	v_rcp_f32_e32 v6, v6
	v_cmp_gt_f32_e32 vcc, 0, v2
	v_add_f32_e32 v3, v11, v3
	v_add_u32_e32 v146, 0x68, v94
	v_fmamk_f32 v7, v6, 0x3f07dc22, v236
	v_fmaak_f32 v7, v6, v7, 0x3f35f0e3
	v_fmaak_f32 v7, v6, v7, 0xbe11a98e
	v_fmaak_f32 v7, v6, v7, 0x3e027906
	v_mul_f32_e32 v6, v6, v7
	v_mul_f32_e32 v7, v2, v2
	v_mul_f32_e32 v7, 0xbf38aa3b, v7
	v_exp_f32_e32 v7, v7
	v_mad_i64_i32 v[10:11], s[6:7], v150, s87, v[92:93]
	v_mad_i64_i32 v[178:179], s[6:7], v166, s87, v[92:93]
	v_mul_f32_e32 v6, v7, v6
	v_mul_f32_e32 v7, v6, v2
	v_fma_f32 v6, -v6, v2, v2
	v_cndmask_b32_e32 v2, v6, v7, vcc
	v_mul_f32_e32 v2, v2, v3
	v_cvt_pk_bf16_f32 v6, v2, s0
	v_lshlrev_b64 v[2:3], 11, v[144:145]
	v_lshl_add_u64 v[2:3], v[106:107], 0, v[2:3]
	global_store_short v[2:3], v6, off
	s_waitcnt vmcnt(53)
	v_lshlrev_b32_e32 v2, 16, v177
	v_fma_f32 v3, |v2|, s92, 1.0
	v_rcp_f32_e32 v3, v3
	v_cmp_gt_f32_e32 vcc, 0, v2
	v_add_u32_e32 v144, 0x69, v94
	v_ashrrev_i32_e32 v147, 31, v146
	v_fmamk_f32 v6, v3, 0x3f07dc22, v236
	v_fmaak_f32 v6, v3, v6, 0x3f35f0e3
	v_fmaak_f32 v6, v3, v6, 0xbe11a98e
	v_fmaak_f32 v6, v3, v6, 0x3e027906
	v_mul_f32_e32 v3, v3, v6
	v_mul_f32_e32 v6, v2, v2
	v_mul_f32_e32 v6, 0xbf38aa3b, v6
	v_exp_f32_e32 v6, v6
	v_ashrrev_i32_e32 v145, 31, v144
	v_mul_f32_e32 v3, v6, v3
	v_mul_f32_e32 v6, v3, v2
	v_fma_f32 v3, -v3, v2, v2
	v_cndmask_b32_e32 v2, v3, v6, vcc
	v_add_f32_e32 v3, v12, v4
	v_mul_f32_e32 v2, v2, v3
	v_cvt_pk_bf16_f32 v4, v2, s0
	v_lshlrev_b64 v[2:3], 11, v[142:143]
	v_lshl_add_u64 v[2:3], v[106:107], 0, v[2:3]
	global_store_short v[2:3], v4, off
	s_waitcnt vmcnt(53)
	v_lshlrev_b32_e32 v2, 16, v176
	v_fma_f32 v3, |v2|, s92, 1.0
	v_rcp_f32_e32 v3, v3
	v_cmp_gt_f32_e32 vcc, 0, v2
	v_add_u32_e32 v142, 0x5f, v94
	v_mad_i64_i32 v[176:177], s[6:7], v168, s87, v[92:93]
	v_fmamk_f32 v4, v3, 0x3f07dc22, v236
	v_fmaak_f32 v4, v3, v4, 0x3f35f0e3
	v_fmaak_f32 v4, v3, v4, 0xbe11a98e
	v_fmaak_f32 v4, v3, v4, 0x3e027906
	v_mul_f32_e32 v3, v3, v4
	v_mul_f32_e32 v4, v2, v2
	v_mul_f32_e32 v4, 0xbf38aa3b, v4
	v_exp_f32_e32 v4, v4
	v_ashrrev_i32_e32 v143, 31, v142
	v_mul_f32_e32 v3, v4, v3
	v_mul_f32_e32 v4, v3, v2
	v_fma_f32 v3, -v3, v2, v2
	v_cndmask_b32_e32 v2, v3, v4, vcc
	v_add_f32_e32 v3, v13, v5
	v_mul_f32_e32 v2, v2, v3
	v_cvt_pk_bf16_f32 v4, v2, s0
	v_lshlrev_b64 v[2:3], 11, v[104:105]
	v_lshl_add_u64 v[2:3], v[106:107], 0, v[2:3]
	global_store_short v[2:3], v4, off
	s_waitcnt vmcnt(53)
	v_lshlrev_b32_e32 v2, 16, v175
	v_fma_f32 v3, |v2|, s92, 1.0
	v_rcp_f32_e32 v3, v3
	v_cmp_gt_f32_e32 vcc, 0, v2
	v_mad_i64_i32 v[12:13], s[6:7], v146, s87, v[92:93]
	v_fmamk_f32 v4, v3, 0x3f07dc22, v236
	v_fmaak_f32 v4, v3, v4, 0x3f35f0e3
	v_fmaak_f32 v4, v3, v4, 0xbe11a98e
	v_fmaak_f32 v4, v3, v4, 0x3e027906
	v_mul_f32_e32 v3, v3, v4
	v_mul_f32_e32 v4, v2, v2
	v_mul_f32_e32 v4, 0xbf38aa3b, v4
	v_exp_f32_e32 v4, v4
	s_nop 0
	v_mul_f32_e32 v3, v4, v3
	v_mul_f32_e32 v4, v3, v2
	v_fma_f32 v3, -v3, v2, v2
	v_cndmask_b32_e32 v6, v3, v4, vcc
	ds_read_b128 v[2:5], v1 offset:224
	s_waitcnt lgkmcnt(0)
	v_add_f32_e32 v2, v14, v2
	v_mul_f32_e32 v2, v6, v2
	v_lshlrev_b64 v[6:7], 11, v[102:103]
	v_cvt_pk_bf16_f32 v2, v2, s0
	v_lshl_add_u64 v[6:7], v[106:107], 0, v[6:7]
	global_store_short v[6:7], v2, off
	s_waitcnt vmcnt(53)
	v_lshlrev_b32_e32 v2, 16, v174
	v_fma_f32 v6, |v2|, s92, 1.0
	v_rcp_f32_e32 v6, v6
	v_cmp_gt_f32_e32 vcc, 0, v2
	v_add_f32_e32 v3, v15, v3
	v_mad_i64_i32 v[14:15], s[6:7], v144, s87, v[92:93]
	v_fmamk_f32 v7, v6, 0x3f07dc22, v236
	v_fmaak_f32 v7, v6, v7, 0x3f35f0e3
	v_fmaak_f32 v7, v6, v7, 0xbe11a98e
	v_fmaak_f32 v7, v6, v7, 0x3e027906
	v_mul_f32_e32 v6, v6, v7
	v_mul_f32_e32 v7, v2, v2
	v_mul_f32_e32 v7, 0xbf38aa3b, v7
	v_exp_f32_e32 v7, v7
	v_mad_i64_i32 v[174:175], s[6:7], v170, s87, v[92:93]
	v_mul_f32_e32 v6, v7, v6
	v_mul_f32_e32 v7, v6, v2
	v_fma_f32 v6, -v6, v2, v2
	v_cndmask_b32_e32 v2, v6, v7, vcc
	v_mul_f32_e32 v2, v2, v3
	v_cvt_pk_bf16_f32 v6, v2, s0
	v_lshlrev_b64 v[2:3], 11, v[100:101]
	v_lshl_add_u64 v[2:3], v[106:107], 0, v[2:3]
	global_store_short v[2:3], v6, off
	s_waitcnt vmcnt(53)
	v_lshlrev_b32_e32 v2, 16, v173
	v_fma_f32 v3, |v2|, s92, 1.0
	v_rcp_f32_e32 v3, v3
	v_cmp_gt_f32_e32 vcc, 0, v2
	v_fmamk_f32 v6, v3, 0x3f07dc22, v236
	v_fmaak_f32 v6, v3, v6, 0x3f35f0e3
	v_fmaak_f32 v6, v3, v6, 0xbe11a98e
	v_fmaak_f32 v6, v3, v6, 0x3e027906
	v_mul_f32_e32 v3, v3, v6
	v_mul_f32_e32 v6, v2, v2
	v_mul_f32_e32 v6, 0xbf38aa3b, v6
	v_exp_f32_e32 v6, v6
	s_nop 0
	v_mul_f32_e32 v3, v6, v3
	v_mul_f32_e32 v6, v3, v2
	v_fma_f32 v3, -v3, v2, v2
	v_cndmask_b32_e32 v2, v3, v6, vcc
	v_add_f32_e32 v3, v16, v4
	v_mul_f32_e32 v2, v2, v3
	v_cvt_pk_bf16_f32 v4, v2, s0
	v_lshlrev_b64 v[2:3], 11, v[98:99]
	v_lshl_add_u64 v[2:3], v[106:107], 0, v[2:3]
	global_store_short v[2:3], v4, off
	s_waitcnt vmcnt(53)
	v_lshlrev_b32_e32 v2, 16, v172
	v_fma_f32 v3, |v2|, s92, 1.0
	v_rcp_f32_e32 v3, v3
	v_cmp_gt_f32_e32 vcc, 0, v2
	v_add_u32_e32 v172, 0x6a, v94
	v_mad_i64_i32 v[6:7], s[6:7], v152, s87, v[92:93]
	v_fmamk_f32 v4, v3, 0x3f07dc22, v236
	v_fmaak_f32 v4, v3, v4, 0x3f35f0e3
	v_fmaak_f32 v4, v3, v4, 0xbe11a98e
	v_fmaak_f32 v4, v3, v4, 0x3e027906
	v_mul_f32_e32 v3, v3, v4
	v_mul_f32_e32 v4, v2, v2
	v_mul_f32_e32 v4, 0xbf38aa3b, v4
	v_exp_f32_e32 v4, v4
	v_ashrrev_i32_e32 v173, 31, v172
	v_mul_f32_e32 v3, v4, v3
	v_mul_f32_e32 v4, v3, v2
	v_fma_f32 v3, -v3, v2, v2
	v_cndmask_b32_e32 v2, v3, v4, vcc
	v_add_f32_e32 v3, v17, v5
	v_mul_f32_e32 v2, v2, v3
	v_cvt_pk_bf16_f32 v4, v2, s0
	v_lshlrev_b64 v[2:3], 11, v[96:97]
	v_add_co_u32_e32 v86, vcc, s5, v90
	v_lshl_add_u64 v[2:3], v[106:107], 0, v[2:3]
	s_nop 0
	v_addc_co_u32_e32 v87, vcc, 0, v91, vcc
	global_store_short v[2:3], v4, off
	v_add_co_u32_e32 v102, vcc, s97, v90
	v_mad_i64_i32 v[2:3], s[6:7], v142, s87, v[92:93]
	v_mad_i64_i32 v[4:5], s[6:7], v154, s87, v[92:93]
	v_mad_i64_i32 v[16:17], s[6:7], v172, s87, v[92:93]
	v_addc_co_u32_e32 v103, vcc, 0, v91, vcc
	global_load_dwordx4 v[74:77], v[102:103], off offset:-4096
	global_load_dwordx4 v[78:81], v[86:87], off offset:1024
	global_load_dwordx4 v[82:85], v[86:87], off offset:2048
	s_nop 0
	global_load_dwordx4 v[86:89], v[86:87], off offset:3072
	s_nop 0
	global_load_dwordx4 v[90:93], v[102:103], off
	global_load_dwordx4 v[94:97], v[102:103], off offset:1024
	global_load_dwordx4 v[98:101], v[102:103], off offset:2048
	s_nop 0
	global_load_dwordx4 v[102:105], v[102:103], off offset:3072
	s_nop 0
	global_load_ushort v212, v[2:3], off
	global_load_ushort v211, v[4:5], off
	global_load_ushort v210, v[6:7], off
	global_load_ushort v209, v[8:9], off
	global_load_ushort v208, v[10:11], off
	global_load_ushort v207, v[12:13], off
	global_load_ushort v206, v[14:15], off
	global_load_ushort v205, v[16:17], off
	global_load_ushort v204, v[174:175], off
	global_load_ushort v203, v[176:177], off
	s_nop 0
	global_load_ushort v179, v[178:179], off
	s_nop 0
	global_load_ushort v178, v[180:181], off
	global_load_ushort v177, v[182:183], off
	global_load_ushort v176, v[184:185], off
	global_load_ushort v175, v[186:187], off
	global_load_ushort v174, v[214:215], off
	s_waitcnt vmcnt(61)
	v_mfma_f32_32x32x16_bf16 v[2:17], v[50:53], v[18:21], 0
	s_waitcnt vmcnt(55)
	v_lshlrev_b32_e32 v50, 16, v202
	v_fma_f32 v51, |v50|, s92, 1.0
	v_rcp_f32_e32 v51, v51
	v_cmp_gt_f32_e32 vcc, 0, v50
	v_readlane_b32 s6, v254, 27
	v_fmamk_f32 v52, v51, 0x3f07dc22, v236
	v_mfma_f32_32x32x16_bf16 v[2:17], v[54:57], v[22:25], v[2:17]
	v_fmaak_f32 v52, v51, v52, 0x3f35f0e3
	v_fmaak_f32 v52, v51, v52, 0xbe11a98e
	v_fmaak_f32 v52, v51, v52, 0x3e027906
	v_mul_f32_e32 v51, v51, v52
	v_mul_f32_e32 v52, v50, v50
	v_mul_f32_e32 v52, 0xbf38aa3b, v52
	v_exp_f32_e32 v52, v52
	v_mfma_f32_32x32x16_bf16 v[2:17], v[58:61], v[26:29], v[2:17]
	v_readlane_b32 s5, v254, 33
	s_add_i32 s6, s6, s19
	v_mul_f32_e32 v51, v52, v51
	v_mul_f32_e32 v52, v51, v50
	v_fma_f32 v51, -v51, v50, v50
	v_cndmask_b32_e32 v58, v51, v52, vcc
	ds_read_b128 v[54:57], v1 offset:256
	ds_read_b128 v[50:53], v1 offset:288
	v_mfma_f32_32x32x16_bf16 v[2:17], v[62:65], v[30:33], v[2:17]
	s_add_i32 s17, s17, s5
	s_cmpk_gt_i32 s6, 0xff
	v_mfma_f32_32x32x16_bf16 v[2:17], v[66:69], v[34:37], v[2:17]
	v_mfma_f32_32x32x16_bf16 v[2:17], v[70:73], v[38:41], v[2:17]
	s_waitcnt lgkmcnt(1)
	s_nop 10
	v_add_f32_e32 v2, v2, v54
	v_mul_f32_e32 v2, v58, v2
	v_lshlrev_b64 v[58:59], 11, v[140:141]
	v_cvt_pk_bf16_f32 v2, v2, s0
	v_lshl_add_u64 v[58:59], v[106:107], 0, v[58:59]
	global_store_short v[58:59], v2, off
	s_waitcnt vmcnt(55)
	v_lshlrev_b32_e32 v2, 16, v201
	v_fma_f32 v54, |v2|, s92, 1.0
	v_rcp_f32_e32 v54, v54
	v_cmp_gt_f32_e32 vcc, 0, v2
	v_add_f32_e32 v3, v3, v55
	v_fmamk_f32 v58, v54, 0x3f07dc22, v236
	v_fmaak_f32 v58, v54, v58, 0x3f35f0e3
	v_fmaak_f32 v58, v54, v58, 0xbe11a98e
	v_fmaak_f32 v58, v54, v58, 0x3e027906
	v_mul_f32_e32 v54, v54, v58
	v_mul_f32_e32 v58, v2, v2
	v_mul_f32_e32 v58, 0xbf38aa3b, v58
	v_exp_f32_e32 v58, v58
	s_nop 0
	v_mul_f32_e32 v54, v58, v54
	v_mul_f32_e32 v58, v54, v2
	v_fma_f32 v54, -v54, v2, v2
	v_cndmask_b32_e32 v2, v54, v58, vcc
	v_mul_f32_e32 v2, v2, v3
	v_cvt_pk_bf16_f32 v54, v2, s0
	v_lshlrev_b64 v[2:3], 11, v[138:139]
	v_lshl_add_u64 v[2:3], v[106:107], 0, v[2:3]
	global_store_short v[2:3], v54, off
	s_waitcnt vmcnt(55)
	v_lshlrev_b32_e32 v2, 16, v200
	v_fma_f32 v3, |v2|, s92, 1.0
	v_rcp_f32_e32 v3, v3
	v_cmp_gt_f32_e32 vcc, 0, v2
	v_fmamk_f32 v54, v3, 0x3f07dc22, v236
	v_fmaak_f32 v54, v3, v54, 0x3f35f0e3
	v_fmaak_f32 v54, v3, v54, 0xbe11a98e
	v_fmaak_f32 v54, v3, v54, 0x3e027906
	v_mul_f32_e32 v3, v3, v54
	v_mul_f32_e32 v54, v2, v2
	v_mul_f32_e32 v54, 0xbf38aa3b, v54
	v_exp_f32_e32 v54, v54
	s_nop 0
	v_mul_f32_e32 v3, v54, v3
	v_mul_f32_e32 v54, v3, v2
	v_fma_f32 v3, -v3, v2, v2
	v_cndmask_b32_e32 v2, v3, v54, vcc
	v_add_f32_e32 v3, v4, v56
	v_mul_f32_e32 v2, v2, v3
	v_cvt_pk_bf16_f32 v4, v2, s0
	v_lshlrev_b64 v[2:3], 11, v[136:137]
	v_lshl_add_u64 v[2:3], v[106:107], 0, v[2:3]
	global_store_short v[2:3], v4, off
	s_waitcnt vmcnt(55)
	v_lshlrev_b32_e32 v2, 16, v199
	v_fma_f32 v3, |v2|, s92, 1.0
	v_rcp_f32_e32 v3, v3
	v_cmp_gt_f32_e32 vcc, 0, v2
	v_fmamk_f32 v4, v3, 0x3f07dc22, v236
	v_fmaak_f32 v4, v3, v4, 0x3f35f0e3
	v_fmaak_f32 v4, v3, v4, 0xbe11a98e
	v_fmaak_f32 v4, v3, v4, 0x3e027906
	v_mul_f32_e32 v3, v3, v4
	v_mul_f32_e32 v4, v2, v2
	v_mul_f32_e32 v4, 0xbf38aa3b, v4
	v_exp_f32_e32 v4, v4
	s_nop 0
	v_mul_f32_e32 v3, v4, v3
	v_mul_f32_e32 v4, v3, v2
	v_fma_f32 v3, -v3, v2, v2
	v_cndmask_b32_e32 v2, v3, v4, vcc
	v_add_f32_e32 v3, v5, v57
	v_mul_f32_e32 v2, v2, v3
	v_cvt_pk_bf16_f32 v4, v2, s0
	v_lshlrev_b64 v[2:3], 11, v[134:135]
	v_lshl_add_u64 v[2:3], v[106:107], 0, v[2:3]
	global_store_short v[2:3], v4, off
	s_waitcnt vmcnt(55)
	v_lshlrev_b32_e32 v2, 16, v198
	v_fma_f32 v3, |v2|, s92, 1.0
	v_rcp_f32_e32 v3, v3
	v_cmp_gt_f32_e32 vcc, 0, v2
	v_fmamk_f32 v4, v3, 0x3f07dc22, v236
	v_fmaak_f32 v4, v3, v4, 0x3f35f0e3
	v_fmaak_f32 v4, v3, v4, 0xbe11a98e
	v_fmaak_f32 v4, v3, v4, 0x3e027906
	v_mul_f32_e32 v3, v3, v4
	v_mul_f32_e32 v4, v2, v2
	v_mul_f32_e32 v4, 0xbf38aa3b, v4
	v_exp_f32_e32 v4, v4
	s_nop 0
	v_mul_f32_e32 v3, v4, v3
	v_mul_f32_e32 v4, v3, v2
	v_fma_f32 v3, -v3, v2, v2
	v_cndmask_b32_e32 v2, v3, v4, vcc
	s_waitcnt lgkmcnt(0)
	v_add_f32_e32 v3, v6, v50
	v_mul_f32_e32 v2, v2, v3
	v_cvt_pk_bf16_f32 v4, v2, s0
	v_lshlrev_b64 v[2:3], 11, v[132:133]
	v_lshl_add_u64 v[2:3], v[106:107], 0, v[2:3]
	global_store_short v[2:3], v4, off
	s_waitcnt vmcnt(55)
	v_lshlrev_b32_e32 v2, 16, v197
	v_fma_f32 v3, |v2|, s92, 1.0
	v_rcp_f32_e32 v3, v3
	v_cmp_gt_f32_e32 vcc, 0, v2
	v_fmamk_f32 v4, v3, 0x3f07dc22, v236
	v_fmaak_f32 v4, v3, v4, 0x3f35f0e3
	v_fmaak_f32 v4, v3, v4, 0xbe11a98e
	v_fmaak_f32 v4, v3, v4, 0x3e027906
	v_mul_f32_e32 v3, v3, v4
	v_mul_f32_e32 v4, v2, v2
	v_mul_f32_e32 v4, 0xbf38aa3b, v4
	v_exp_f32_e32 v4, v4
	s_nop 0
	v_mul_f32_e32 v3, v4, v3
	v_mul_f32_e32 v4, v3, v2
	v_fma_f32 v3, -v3, v2, v2
	v_cndmask_b32_e32 v2, v3, v4, vcc
	v_add_f32_e32 v3, v7, v51
	v_mul_f32_e32 v2, v2, v3
	v_cvt_pk_bf16_f32 v4, v2, s0
	v_lshlrev_b64 v[2:3], 11, v[126:127]
	v_lshl_add_u64 v[2:3], v[106:107], 0, v[2:3]
	global_store_short v[2:3], v4, off
	s_waitcnt vmcnt(55)
	v_lshlrev_b32_e32 v2, 16, v196
	v_fma_f32 v3, |v2|, s92, 1.0
	v_rcp_f32_e32 v3, v3
	v_cmp_gt_f32_e32 vcc, 0, v2
	v_fmamk_f32 v4, v3, 0x3f07dc22, v236
	v_fmaak_f32 v4, v3, v4, 0x3f35f0e3
	v_fmaak_f32 v4, v3, v4, 0xbe11a98e
	v_fmaak_f32 v4, v3, v4, 0x3e027906
	v_mul_f32_e32 v3, v3, v4
	v_mul_f32_e32 v4, v2, v2
	v_mul_f32_e32 v4, 0xbf38aa3b, v4
	v_exp_f32_e32 v4, v4
	s_nop 0
	v_mul_f32_e32 v3, v4, v3
	v_mul_f32_e32 v4, v3, v2
	v_fma_f32 v3, -v3, v2, v2
	v_cndmask_b32_e32 v2, v3, v4, vcc
	v_add_f32_e32 v3, v8, v52
	v_mul_f32_e32 v2, v2, v3
	v_cvt_pk_bf16_f32 v4, v2, s0
	v_lshlrev_b64 v[2:3], 11, v[122:123]
	v_lshl_add_u64 v[2:3], v[106:107], 0, v[2:3]
	global_store_short v[2:3], v4, off
	s_waitcnt vmcnt(55)
	v_lshlrev_b32_e32 v2, 16, v195
	v_fma_f32 v3, |v2|, s92, 1.0
	v_rcp_f32_e32 v3, v3
	v_cmp_gt_f32_e32 vcc, 0, v2
	v_fmamk_f32 v4, v3, 0x3f07dc22, v236
	v_fmaak_f32 v4, v3, v4, 0x3f35f0e3
	v_fmaak_f32 v4, v3, v4, 0xbe11a98e
	v_fmaak_f32 v4, v3, v4, 0x3e027906
	v_mul_f32_e32 v3, v3, v4
	v_mul_f32_e32 v4, v2, v2
	v_mul_f32_e32 v4, 0xbf38aa3b, v4
	v_exp_f32_e32 v4, v4
	s_nop 0
	v_mul_f32_e32 v3, v4, v3
	v_mul_f32_e32 v4, v3, v2
	v_fma_f32 v3, -v3, v2, v2
	v_cndmask_b32_e32 v2, v3, v4, vcc
	v_add_f32_e32 v3, v9, v53
	v_mul_f32_e32 v2, v2, v3
	v_cvt_pk_bf16_f32 v4, v2, s0
	v_lshlrev_b64 v[2:3], 11, v[118:119]
	v_lshl_add_u64 v[2:3], v[106:107], 0, v[2:3]
	global_store_short v[2:3], v4, off
	s_waitcnt vmcnt(55)
	v_lshlrev_b32_e32 v2, 16, v194
	v_fma_f32 v3, |v2|, s92, 1.0
	v_rcp_f32_e32 v3, v3
	v_cmp_gt_f32_e32 vcc, 0, v2
	v_fmamk_f32 v4, v3, 0x3f07dc22, v236
	v_fmaak_f32 v4, v3, v4, 0x3f35f0e3
	v_fmaak_f32 v4, v3, v4, 0xbe11a98e
	v_fmaak_f32 v4, v3, v4, 0x3e027906
	v_mul_f32_e32 v3, v3, v4
	v_mul_f32_e32 v4, v2, v2
	v_mul_f32_e32 v4, 0xbf38aa3b, v4
	v_exp_f32_e32 v4, v4
	s_nop 0
	v_mul_f32_e32 v3, v4, v3
	v_mul_f32_e32 v4, v3, v2
	v_fma_f32 v3, -v3, v2, v2
	v_cndmask_b32_e32 v6, v3, v4, vcc
	ds_read_b128 v[2:5], v1 offset:320
	s_waitcnt lgkmcnt(0)
	v_add_f32_e32 v2, v10, v2
	v_mul_f32_e32 v2, v6, v2
	v_lshlrev_b64 v[6:7], 11, v[116:117]
	v_cvt_pk_bf16_f32 v2, v2, s0
	v_lshl_add_u64 v[6:7], v[106:107], 0, v[6:7]
	global_store_short v[6:7], v2, off
	s_waitcnt vmcnt(55)
	v_lshlrev_b32_e32 v2, 16, v193
	v_fma_f32 v6, |v2|, s92, 1.0
	v_rcp_f32_e32 v6, v6
	v_cmp_gt_f32_e32 vcc, 0, v2
	v_add_f32_e32 v3, v11, v3
	v_fmamk_f32 v7, v6, 0x3f07dc22, v236
	v_fmaak_f32 v7, v6, v7, 0x3f35f0e3
	v_fmaak_f32 v7, v6, v7, 0xbe11a98e
	v_fmaak_f32 v7, v6, v7, 0x3e027906
	v_mul_f32_e32 v6, v6, v7
	v_mul_f32_e32 v7, v2, v2
	v_mul_f32_e32 v7, 0xbf38aa3b, v7
	v_exp_f32_e32 v7, v7
	s_nop 0
	v_mul_f32_e32 v6, v7, v6
	v_mul_f32_e32 v7, v6, v2
	v_fma_f32 v6, -v6, v2, v2
	v_cndmask_b32_e32 v2, v6, v7, vcc
	v_mul_f32_e32 v2, v2, v3
	v_cvt_pk_bf16_f32 v6, v2, s0
	v_lshlrev_b64 v[2:3], 11, v[112:113]
	v_lshl_add_u64 v[2:3], v[106:107], 0, v[2:3]
	global_store_short v[2:3], v6, off
	s_waitcnt vmcnt(55)
	v_lshlrev_b32_e32 v2, 16, v192
	v_fma_f32 v3, |v2|, s92, 1.0
	v_rcp_f32_e32 v3, v3
	v_cmp_gt_f32_e32 vcc, 0, v2
	v_fmamk_f32 v6, v3, 0x3f07dc22, v236
	v_fmaak_f32 v6, v3, v6, 0x3f35f0e3
	v_fmaak_f32 v6, v3, v6, 0xbe11a98e
	v_fmaak_f32 v6, v3, v6, 0x3e027906
	v_mul_f32_e32 v3, v3, v6
	v_mul_f32_e32 v6, v2, v2
	v_mul_f32_e32 v6, 0xbf38aa3b, v6
	v_exp_f32_e32 v6, v6
	s_nop 0
	v_mul_f32_e32 v3, v6, v3
	v_mul_f32_e32 v6, v3, v2
	v_fma_f32 v3, -v3, v2, v2
	v_cndmask_b32_e32 v2, v3, v6, vcc
	v_add_f32_e32 v3, v12, v4
	v_mul_f32_e32 v2, v2, v3
	v_cvt_pk_bf16_f32 v4, v2, s0
	v_lshlrev_b64 v[2:3], 11, v[110:111]
	v_lshl_add_u64 v[2:3], v[106:107], 0, v[2:3]
	global_store_short v[2:3], v4, off
	s_waitcnt vmcnt(55)
	v_lshlrev_b32_e32 v2, 16, v191
	v_fma_f32 v3, |v2|, s92, 1.0
	v_rcp_f32_e32 v3, v3
	v_cmp_gt_f32_e32 vcc, 0, v2
	v_fmamk_f32 v4, v3, 0x3f07dc22, v236
	v_fmaak_f32 v4, v3, v4, 0x3f35f0e3
	v_fmaak_f32 v4, v3, v4, 0xbe11a98e
	v_fmaak_f32 v4, v3, v4, 0x3e027906
	v_mul_f32_e32 v3, v3, v4
	v_mul_f32_e32 v4, v2, v2
	v_mul_f32_e32 v4, 0xbf38aa3b, v4
	v_exp_f32_e32 v4, v4
	s_nop 0
	v_mul_f32_e32 v3, v4, v3
	v_mul_f32_e32 v4, v3, v2
	v_fma_f32 v3, -v3, v2, v2
	v_cndmask_b32_e32 v2, v3, v4, vcc
	v_add_f32_e32 v3, v13, v5
	v_mul_f32_e32 v2, v2, v3
	v_cvt_pk_bf16_f32 v4, v2, s0
	v_lshlrev_b64 v[2:3], 11, v[108:109]
	v_lshl_add_u64 v[2:3], v[106:107], 0, v[2:3]
	global_store_short v[2:3], v4, off
	s_waitcnt vmcnt(55)
	v_lshlrev_b32_e32 v2, 16, v190
	v_fma_f32 v3, |v2|, s92, 1.0
	v_rcp_f32_e32 v3, v3
	v_cmp_gt_f32_e32 vcc, 0, v2
	v_fmamk_f32 v4, v3, 0x3f07dc22, v236
	v_fmaak_f32 v4, v3, v4, 0x3f35f0e3
	v_fmaak_f32 v4, v3, v4, 0xbe11a98e
	v_fmaak_f32 v4, v3, v4, 0x3e027906
	v_mul_f32_e32 v3, v3, v4
	v_mul_f32_e32 v4, v2, v2
	v_mul_f32_e32 v4, 0xbf38aa3b, v4
	v_exp_f32_e32 v4, v4
	s_nop 0
	v_mul_f32_e32 v3, v4, v3
	v_mul_f32_e32 v4, v3, v2
	v_fma_f32 v3, -v3, v2, v2
	v_cndmask_b32_e32 v6, v3, v4, vcc
	ds_read_b128 v[2:5], v1 offset:352
	s_waitcnt lgkmcnt(0)
	v_add_f32_e32 v2, v14, v2
	v_mul_f32_e32 v2, v6, v2
	v_lshlrev_b64 v[6:7], 11, v[128:129]
	v_cvt_pk_bf16_f32 v2, v2, s0
	v_lshl_add_u64 v[6:7], v[106:107], 0, v[6:7]
	global_store_short v[6:7], v2, off
	s_waitcnt vmcnt(55)
	v_lshlrev_b32_e32 v2, 16, v189
	v_fma_f32 v6, |v2|, s92, 1.0
	v_rcp_f32_e32 v6, v6
	v_cmp_gt_f32_e32 vcc, 0, v2
	v_add_f32_e32 v3, v15, v3
	v_fmamk_f32 v7, v6, 0x3f07dc22, v236
	v_fmaak_f32 v7, v6, v7, 0x3f35f0e3
	v_fmaak_f32 v7, v6, v7, 0xbe11a98e
	v_fmaak_f32 v7, v6, v7, 0x3e027906
	v_mul_f32_e32 v6, v6, v7
	v_mul_f32_e32 v7, v2, v2
	v_mul_f32_e32 v7, 0xbf38aa3b, v7
	v_exp_f32_e32 v7, v7
	s_nop 0
	v_mul_f32_e32 v6, v7, v6
	v_mul_f32_e32 v7, v6, v2
	v_fma_f32 v6, -v6, v2, v2
	v_cndmask_b32_e32 v2, v6, v7, vcc
	v_mul_f32_e32 v2, v2, v3
	v_cvt_pk_bf16_f32 v6, v2, s0
	v_lshlrev_b64 v[2:3], 11, v[124:125]
	v_lshl_add_u64 v[2:3], v[106:107], 0, v[2:3]
	global_store_short v[2:3], v6, off
	s_waitcnt vmcnt(55)
	v_lshlrev_b32_e32 v2, 16, v188
	v_fma_f32 v3, |v2|, s92, 1.0
	v_rcp_f32_e32 v3, v3
	v_cmp_gt_f32_e32 vcc, 0, v2
	v_fmamk_f32 v6, v3, 0x3f07dc22, v236
	v_fmaak_f32 v6, v3, v6, 0x3f35f0e3
	v_fmaak_f32 v6, v3, v6, 0xbe11a98e
	v_fmaak_f32 v6, v3, v6, 0x3e027906
	v_mul_f32_e32 v3, v3, v6
	v_mul_f32_e32 v6, v2, v2
	v_mul_f32_e32 v6, 0xbf38aa3b, v6
	v_exp_f32_e32 v6, v6
	s_nop 0
	v_mul_f32_e32 v3, v6, v3
	v_mul_f32_e32 v6, v3, v2
	v_fma_f32 v3, -v3, v2, v2
	v_cndmask_b32_e32 v2, v3, v6, vcc
	v_add_f32_e32 v3, v16, v4
	v_mul_f32_e32 v2, v2, v3
	v_cvt_pk_bf16_f32 v4, v2, s0
	v_lshlrev_b64 v[2:3], 11, v[120:121]
	v_lshl_add_u64 v[2:3], v[106:107], 0, v[2:3]
	global_store_short v[2:3], v4, off
	s_waitcnt vmcnt(55)
	v_lshlrev_b32_e32 v2, 16, v130
	v_fma_f32 v3, |v2|, s92, 1.0
	v_rcp_f32_e32 v3, v3
	v_cmp_gt_f32_e32 vcc, 0, v2
	v_fmamk_f32 v4, v3, 0x3f07dc22, v236
	v_fmaak_f32 v4, v3, v4, 0x3f35f0e3
	v_fmaak_f32 v4, v3, v4, 0xbe11a98e
	v_fmaak_f32 v4, v3, v4, 0x3e027906
	v_mul_f32_e32 v3, v3, v4
	v_mul_f32_e32 v4, v2, v2
	v_mul_f32_e32 v4, 0xbf38aa3b, v4
	v_exp_f32_e32 v4, v4
	s_nop 0
	v_mul_f32_e32 v3, v4, v3
	v_mul_f32_e32 v4, v3, v2
	v_fma_f32 v3, -v3, v2, v2
	v_cndmask_b32_e32 v2, v3, v4, vcc
	v_add_f32_e32 v3, v17, v5
	v_mul_f32_e32 v2, v2, v3
	v_cvt_pk_bf16_f32 v4, v2, s0
	v_lshlrev_b64 v[2:3], 11, v[114:115]
	v_lshl_add_u64 v[2:3], v[106:107], 0, v[2:3]
	global_store_short v[2:3], v4, off
	s_waitcnt vmcnt(39)
	v_mfma_f32_32x32x16_bf16 v[2:17], v[74:77], v[18:21], 0
	s_waitcnt vmcnt(31)
	v_lshlrev_b32_e32 v18, 16, v212
	v_fma_f32 v19, |v18|, s92, 1.0
	v_rcp_f32_e32 v19, v19
	v_cmp_gt_f32_e32 vcc, 0, v18
	v_fmamk_f32 v20, v19, 0x3f07dc22, v236
	v_mfma_f32_32x32x16_bf16 v[2:17], v[78:81], v[22:25], v[2:17]
	v_fmaak_f32 v20, v19, v20, 0x3f35f0e3
	v_fmaak_f32 v20, v19, v20, 0xbe11a98e
	v_fmaak_f32 v20, v19, v20, 0x3e027906
	v_mul_f32_e32 v19, v19, v20
	v_mul_f32_e32 v20, v18, v18
	v_mul_f32_e32 v20, 0xbf38aa3b, v20
	v_exp_f32_e32 v20, v20
	v_mfma_f32_32x32x16_bf16 v[2:17], v[82:85], v[26:29], v[2:17]
	v_mul_f32_e32 v19, v20, v19
	v_mul_f32_e32 v20, v19, v18
	v_fma_f32 v19, -v19, v18, v18
	v_cndmask_b32_e32 v26, v19, v20, vcc
	ds_read_b128 v[22:25], v1 offset:384
	ds_read_b128 v[18:21], v1 offset:416
	v_mfma_f32_32x32x16_bf16 v[2:17], v[86:89], v[30:33], v[2:17]
	v_mfma_f32_32x32x16_bf16 v[2:17], v[90:93], v[34:37], v[2:17]
	v_mfma_f32_32x32x16_bf16 v[2:17], v[94:97], v[38:41], v[2:17]
	v_mfma_f32_32x32x16_bf16 v[2:17], v[98:101], v[42:45], v[2:17]
	v_mfma_f32_32x32x16_bf16 v[2:17], v[102:105], v[46:49], v[2:17]
	s_waitcnt lgkmcnt(1)
	s_nop 10
	v_add_f32_e32 v2, v2, v22
	v_mul_f32_e32 v2, v26, v2
	v_lshlrev_b64 v[26:27], 11, v[142:143]
	v_cvt_pk_bf16_f32 v2, v2, s0
	v_lshl_add_u64 v[26:27], v[106:107], 0, v[26:27]
	global_store_short v[26:27], v2, off
	s_waitcnt vmcnt(31)
	v_lshlrev_b32_e32 v2, 16, v211
	v_fma_f32 v22, |v2|, s92, 1.0
	v_rcp_f32_e32 v22, v22
	v_cmp_gt_f32_e32 vcc, 0, v2
	v_add_f32_e32 v3, v3, v23
	v_fmamk_f32 v26, v22, 0x3f07dc22, v236
	v_fmaak_f32 v26, v22, v26, 0x3f35f0e3
	v_fmaak_f32 v26, v22, v26, 0xbe11a98e
	v_fmaak_f32 v26, v22, v26, 0x3e027906
	v_mul_f32_e32 v22, v22, v26
	v_mul_f32_e32 v26, v2, v2
	v_mul_f32_e32 v26, 0xbf38aa3b, v26
	v_exp_f32_e32 v26, v26
	s_nop 0
	v_mul_f32_e32 v22, v26, v22
	v_mul_f32_e32 v26, v22, v2
	v_fma_f32 v22, -v22, v2, v2
	v_cndmask_b32_e32 v2, v22, v26, vcc
	v_mul_f32_e32 v2, v2, v3
	v_cvt_pk_bf16_f32 v22, v2, s0
	v_lshlrev_b64 v[2:3], 11, v[154:155]
	v_lshl_add_u64 v[2:3], v[106:107], 0, v[2:3]
	global_store_short v[2:3], v22, off
	s_waitcnt vmcnt(31)
	v_lshlrev_b32_e32 v2, 16, v210
	v_fma_f32 v3, |v2|, s92, 1.0
	v_rcp_f32_e32 v3, v3
	v_cmp_gt_f32_e32 vcc, 0, v2
	v_fmamk_f32 v22, v3, 0x3f07dc22, v236
	v_fmaak_f32 v22, v3, v22, 0x3f35f0e3
	v_fmaak_f32 v22, v3, v22, 0xbe11a98e
	v_fmaak_f32 v22, v3, v22, 0x3e027906
	v_mul_f32_e32 v3, v3, v22
	v_mul_f32_e32 v22, v2, v2
	v_mul_f32_e32 v22, 0xbf38aa3b, v22
	v_exp_f32_e32 v22, v22
	s_nop 0
	v_mul_f32_e32 v3, v22, v3
	v_mul_f32_e32 v22, v3, v2
	v_fma_f32 v3, -v3, v2, v2
	v_cndmask_b32_e32 v2, v3, v22, vcc
	v_add_f32_e32 v3, v4, v24
	v_mul_f32_e32 v2, v2, v3
	v_cvt_pk_bf16_f32 v4, v2, s0
	v_lshlrev_b64 v[2:3], 11, v[152:153]
	v_lshl_add_u64 v[2:3], v[106:107], 0, v[2:3]
	global_store_short v[2:3], v4, off
	s_waitcnt vmcnt(31)
	v_lshlrev_b32_e32 v2, 16, v209
	v_fma_f32 v3, |v2|, s92, 1.0
	v_rcp_f32_e32 v3, v3
	v_cmp_gt_f32_e32 vcc, 0, v2
	v_fmamk_f32 v4, v3, 0x3f07dc22, v236
	v_fmaak_f32 v4, v3, v4, 0x3f35f0e3
	v_fmaak_f32 v4, v3, v4, 0xbe11a98e
	v_fmaak_f32 v4, v3, v4, 0x3e027906
	v_mul_f32_e32 v3, v3, v4
	v_mul_f32_e32 v4, v2, v2
	v_mul_f32_e32 v4, 0xbf38aa3b, v4
	v_exp_f32_e32 v4, v4
	s_nop 0
	v_mul_f32_e32 v3, v4, v3
	v_mul_f32_e32 v4, v3, v2
	v_fma_f32 v3, -v3, v2, v2
	v_cndmask_b32_e32 v2, v3, v4, vcc
	v_add_f32_e32 v3, v5, v25
	v_mul_f32_e32 v2, v2, v3
	v_cvt_pk_bf16_f32 v4, v2, s0
	v_lshlrev_b64 v[2:3], 11, v[148:149]
	v_lshl_add_u64 v[2:3], v[106:107], 0, v[2:3]
	global_store_short v[2:3], v4, off
	s_waitcnt vmcnt(31)
	v_lshlrev_b32_e32 v2, 16, v208
	v_fma_f32 v3, |v2|, s92, 1.0
	v_rcp_f32_e32 v3, v3
	v_cmp_gt_f32_e32 vcc, 0, v2
	v_fmamk_f32 v4, v3, 0x3f07dc22, v236
	v_fmaak_f32 v4, v3, v4, 0x3f35f0e3
	v_fmaak_f32 v4, v3, v4, 0xbe11a98e
	v_fmaak_f32 v4, v3, v4, 0x3e027906
	v_mul_f32_e32 v3, v3, v4
	v_mul_f32_e32 v4, v2, v2
	v_mul_f32_e32 v4, 0xbf38aa3b, v4
	v_exp_f32_e32 v4, v4
	s_nop 0
	v_mul_f32_e32 v3, v4, v3
	v_mul_f32_e32 v4, v3, v2
	v_fma_f32 v3, -v3, v2, v2
	v_cndmask_b32_e32 v2, v3, v4, vcc
	s_waitcnt lgkmcnt(0)
	v_add_f32_e32 v3, v6, v18
	v_mul_f32_e32 v2, v2, v3
	v_cvt_pk_bf16_f32 v4, v2, s0
	v_lshlrev_b64 v[2:3], 11, v[150:151]
	v_lshl_add_u64 v[2:3], v[106:107], 0, v[2:3]
	global_store_short v[2:3], v4, off
	s_waitcnt vmcnt(31)
	v_lshlrev_b32_e32 v2, 16, v207
	v_fma_f32 v3, |v2|, s92, 1.0
	v_rcp_f32_e32 v3, v3
	v_cmp_gt_f32_e32 vcc, 0, v2
	v_fmamk_f32 v4, v3, 0x3f07dc22, v236
	v_fmaak_f32 v4, v3, v4, 0x3f35f0e3
	v_fmaak_f32 v4, v3, v4, 0xbe11a98e
	v_fmaak_f32 v4, v3, v4, 0x3e027906
	v_mul_f32_e32 v3, v3, v4
	v_mul_f32_e32 v4, v2, v2
	v_mul_f32_e32 v4, 0xbf38aa3b, v4
	v_exp_f32_e32 v4, v4
	s_nop 0
	v_mul_f32_e32 v3, v4, v3
	v_mul_f32_e32 v4, v3, v2
	v_fma_f32 v3, -v3, v2, v2
	v_cndmask_b32_e32 v2, v3, v4, vcc
	v_add_f32_e32 v3, v7, v19
	v_mul_f32_e32 v2, v2, v3
	v_cvt_pk_bf16_f32 v4, v2, s0
	v_lshlrev_b64 v[2:3], 11, v[146:147]
	v_lshl_add_u64 v[2:3], v[106:107], 0, v[2:3]
	global_store_short v[2:3], v4, off
	s_waitcnt vmcnt(31)
	v_lshlrev_b32_e32 v2, 16, v206
	v_fma_f32 v3, |v2|, s92, 1.0
	v_rcp_f32_e32 v3, v3
	v_cmp_gt_f32_e32 vcc, 0, v2
	v_fmamk_f32 v4, v3, 0x3f07dc22, v236
	v_fmaak_f32 v4, v3, v4, 0x3f35f0e3
	v_fmaak_f32 v4, v3, v4, 0xbe11a98e
	v_fmaak_f32 v4, v3, v4, 0x3e027906
	v_mul_f32_e32 v3, v3, v4
	v_mul_f32_e32 v4, v2, v2
	v_mul_f32_e32 v4, 0xbf38aa3b, v4
	v_exp_f32_e32 v4, v4
	s_nop 0
	v_mul_f32_e32 v3, v4, v3
	v_mul_f32_e32 v4, v3, v2
	v_fma_f32 v3, -v3, v2, v2
	v_cndmask_b32_e32 v2, v3, v4, vcc
	v_add_f32_e32 v3, v8, v20
	v_mul_f32_e32 v2, v2, v3
	v_cvt_pk_bf16_f32 v4, v2, s0
	v_lshlrev_b64 v[2:3], 11, v[144:145]
	v_lshl_add_u64 v[2:3], v[106:107], 0, v[2:3]
	global_store_short v[2:3], v4, off
	s_waitcnt vmcnt(31)
	v_lshlrev_b32_e32 v2, 16, v205
	v_fma_f32 v3, |v2|, s92, 1.0
	v_rcp_f32_e32 v3, v3
	v_cmp_gt_f32_e32 vcc, 0, v2
	v_fmamk_f32 v4, v3, 0x3f07dc22, v236
	v_fmaak_f32 v4, v3, v4, 0x3f35f0e3
	v_fmaak_f32 v4, v3, v4, 0xbe11a98e
	v_fmaak_f32 v4, v3, v4, 0x3e027906
	v_mul_f32_e32 v3, v3, v4
	v_mul_f32_e32 v4, v2, v2
	v_mul_f32_e32 v4, 0xbf38aa3b, v4
	v_exp_f32_e32 v4, v4
	s_nop 0
	v_mul_f32_e32 v3, v4, v3
	v_mul_f32_e32 v4, v3, v2
	v_fma_f32 v3, -v3, v2, v2
	v_cndmask_b32_e32 v2, v3, v4, vcc
	v_add_f32_e32 v3, v9, v21
	v_mul_f32_e32 v2, v2, v3
	v_cvt_pk_bf16_f32 v4, v2, s0
	v_lshlrev_b64 v[2:3], 11, v[172:173]
	v_lshl_add_u64 v[2:3], v[106:107], 0, v[2:3]
	global_store_short v[2:3], v4, off
	s_waitcnt vmcnt(31)
	v_lshlrev_b32_e32 v2, 16, v204
	v_fma_f32 v3, |v2|, s92, 1.0
	v_rcp_f32_e32 v3, v3
	v_cmp_gt_f32_e32 vcc, 0, v2
	v_fmamk_f32 v4, v3, 0x3f07dc22, v236
	v_fmaak_f32 v4, v3, v4, 0x3f35f0e3
	v_fmaak_f32 v4, v3, v4, 0xbe11a98e
	v_fmaak_f32 v4, v3, v4, 0x3e027906
	v_mul_f32_e32 v3, v3, v4
	v_mul_f32_e32 v4, v2, v2
	v_mul_f32_e32 v4, 0xbf38aa3b, v4
	v_exp_f32_e32 v4, v4
	s_nop 0
	v_mul_f32_e32 v3, v4, v3
	v_mul_f32_e32 v4, v3, v2
	v_fma_f32 v3, -v3, v2, v2
	v_cndmask_b32_e32 v6, v3, v4, vcc
	ds_read_b128 v[2:5], v1 offset:448
	s_waitcnt lgkmcnt(0)
	v_add_f32_e32 v2, v10, v2
	v_mul_f32_e32 v2, v6, v2
	v_lshlrev_b64 v[6:7], 11, v[170:171]
	v_cvt_pk_bf16_f32 v2, v2, s0
	v_lshl_add_u64 v[6:7], v[106:107], 0, v[6:7]
	global_store_short v[6:7], v2, off
	s_waitcnt vmcnt(31)
	v_lshlrev_b32_e32 v2, 16, v203
	v_fma_f32 v6, |v2|, s92, 1.0
	v_rcp_f32_e32 v6, v6
	v_cmp_gt_f32_e32 vcc, 0, v2
	v_add_f32_e32 v3, v11, v3
	v_fmamk_f32 v7, v6, 0x3f07dc22, v236
	v_fmaak_f32 v7, v6, v7, 0x3f35f0e3
	v_fmaak_f32 v7, v6, v7, 0xbe11a98e
	v_fmaak_f32 v7, v6, v7, 0x3e027906
	v_mul_f32_e32 v6, v6, v7
	v_mul_f32_e32 v7, v2, v2
	v_mul_f32_e32 v7, 0xbf38aa3b, v7
	v_exp_f32_e32 v7, v7
	s_nop 0
	v_mul_f32_e32 v6, v7, v6
	v_mul_f32_e32 v7, v6, v2
	v_fma_f32 v6, -v6, v2, v2
	v_cndmask_b32_e32 v2, v6, v7, vcc
	v_mul_f32_e32 v2, v2, v3
	v_cvt_pk_bf16_f32 v6, v2, s0
	v_lshlrev_b64 v[2:3], 11, v[168:169]
	v_lshl_add_u64 v[2:3], v[106:107], 0, v[2:3]
	global_store_short v[2:3], v6, off
	s_waitcnt vmcnt(31)
	v_lshlrev_b32_e32 v2, 16, v179
	v_fma_f32 v3, |v2|, s92, 1.0
	v_rcp_f32_e32 v3, v3
	v_cmp_gt_f32_e32 vcc, 0, v2
	v_fmamk_f32 v6, v3, 0x3f07dc22, v236
	v_fmaak_f32 v6, v3, v6, 0x3f35f0e3
	v_fmaak_f32 v6, v3, v6, 0xbe11a98e
	v_fmaak_f32 v6, v3, v6, 0x3e027906
	v_mul_f32_e32 v3, v3, v6
	v_mul_f32_e32 v6, v2, v2
	v_mul_f32_e32 v6, 0xbf38aa3b, v6
	v_exp_f32_e32 v6, v6
	s_nop 0
	v_mul_f32_e32 v3, v6, v3
	v_mul_f32_e32 v6, v3, v2
	v_fma_f32 v3, -v3, v2, v2
	v_cndmask_b32_e32 v2, v3, v6, vcc
	v_add_f32_e32 v3, v12, v4
	v_mul_f32_e32 v2, v2, v3
	v_cvt_pk_bf16_f32 v4, v2, s0
	v_lshlrev_b64 v[2:3], 11, v[166:167]
	v_lshl_add_u64 v[2:3], v[106:107], 0, v[2:3]
	global_store_short v[2:3], v4, off
	s_waitcnt vmcnt(31)
	v_lshlrev_b32_e32 v2, 16, v178
	v_fma_f32 v3, |v2|, s92, 1.0
	v_rcp_f32_e32 v3, v3
	v_cmp_gt_f32_e32 vcc, 0, v2
	v_fmamk_f32 v4, v3, 0x3f07dc22, v236
	v_fmaak_f32 v4, v3, v4, 0x3f35f0e3
	v_fmaak_f32 v4, v3, v4, 0xbe11a98e
	v_fmaak_f32 v4, v3, v4, 0x3e027906
	v_mul_f32_e32 v3, v3, v4
	v_mul_f32_e32 v4, v2, v2
	v_mul_f32_e32 v4, 0xbf38aa3b, v4
	v_exp_f32_e32 v4, v4
	s_nop 0
	v_mul_f32_e32 v3, v4, v3
	v_mul_f32_e32 v4, v3, v2
	v_fma_f32 v3, -v3, v2, v2
	v_cndmask_b32_e32 v2, v3, v4, vcc
	v_add_f32_e32 v3, v13, v5
	v_mul_f32_e32 v2, v2, v3
	v_cvt_pk_bf16_f32 v4, v2, s0
	v_lshlrev_b64 v[2:3], 11, v[164:165]
	v_lshl_add_u64 v[2:3], v[106:107], 0, v[2:3]
	global_store_short v[2:3], v4, off
	s_waitcnt vmcnt(31)
	v_lshlrev_b32_e32 v2, 16, v177
	v_fma_f32 v3, |v2|, s92, 1.0
	v_rcp_f32_e32 v3, v3
	v_cmp_gt_f32_e32 vcc, 0, v2
	v_fmamk_f32 v4, v3, 0x3f07dc22, v236
	v_fmaak_f32 v4, v3, v4, 0x3f35f0e3
	v_fmaak_f32 v4, v3, v4, 0xbe11a98e
	v_fmaak_f32 v4, v3, v4, 0x3e027906
	v_mul_f32_e32 v3, v3, v4
	v_mul_f32_e32 v4, v2, v2
	v_mul_f32_e32 v4, 0xbf38aa3b, v4
	v_exp_f32_e32 v4, v4
	s_nop 0
	v_mul_f32_e32 v3, v4, v3
	v_mul_f32_e32 v4, v3, v2
	v_fma_f32 v3, -v3, v2, v2
	v_cndmask_b32_e32 v6, v3, v4, vcc
	ds_read_b128 v[2:5], v1 offset:480
	s_waitcnt lgkmcnt(0)
	v_add_f32_e32 v1, v14, v2
	v_mul_f32_e32 v1, v6, v1
	v_lshlrev_b64 v[6:7], 11, v[162:163]
	v_cvt_pk_bf16_f32 v1, v1, s0
	v_lshl_add_u64 v[6:7], v[106:107], 0, v[6:7]
	global_store_short v[6:7], v1, off
	s_waitcnt vmcnt(31)
	v_lshlrev_b32_e32 v1, 16, v176
	v_fma_f32 v2, |v1|, s92, 1.0
	v_rcp_f32_e32 v2, v2
	v_cmp_gt_f32_e32 vcc, 0, v1
	v_fmamk_f32 v6, v2, 0x3f07dc22, v236
	v_fmaak_f32 v6, v2, v6, 0x3f35f0e3
	v_fmaak_f32 v6, v2, v6, 0xbe11a98e
	v_fmaak_f32 v6, v2, v6, 0x3e027906
	v_mul_f32_e32 v2, v2, v6
	v_mul_f32_e32 v6, v1, v1
	v_mul_f32_e32 v6, 0xbf38aa3b, v6
	v_exp_f32_e32 v6, v6
	s_nop 0
	v_mul_f32_e32 v2, v6, v2
	v_mul_f32_e32 v6, v2, v1
	v_fma_f32 v2, -v2, v1, v1
	v_cndmask_b32_e32 v1, v2, v6, vcc
	v_add_f32_e32 v2, v15, v3
	v_mul_f32_e32 v1, v1, v2
	v_lshlrev_b64 v[2:3], 11, v[160:161]
	v_cvt_pk_bf16_f32 v1, v1, s0
	v_lshl_add_u64 v[2:3], v[106:107], 0, v[2:3]
	global_store_short v[2:3], v1, off
	s_waitcnt vmcnt(31)
	v_lshlrev_b32_e32 v1, 16, v175
	v_fma_f32 v2, |v1|, s92, 1.0
	v_rcp_f32_e32 v2, v2
	v_cmp_gt_f32_e32 vcc, 0, v1
	v_fmamk_f32 v3, v2, 0x3f07dc22, v236
	v_fmaak_f32 v3, v2, v3, 0x3f35f0e3
	v_fmaak_f32 v3, v2, v3, 0xbe11a98e
	v_fmaak_f32 v3, v2, v3, 0x3e027906
	v_mul_f32_e32 v2, v2, v3
	v_mul_f32_e32 v3, v1, v1
	v_mul_f32_e32 v3, 0xbf38aa3b, v3
	v_exp_f32_e32 v3, v3
	s_nop 0
	v_mul_f32_e32 v2, v3, v2
	v_mul_f32_e32 v3, v2, v1
	v_fma_f32 v2, -v2, v1, v1
	v_cndmask_b32_e32 v1, v2, v3, vcc
	v_add_f32_e32 v2, v16, v4
	v_mul_f32_e32 v1, v1, v2
	v_lshlrev_b64 v[2:3], 11, v[158:159]
	v_cvt_pk_bf16_f32 v1, v1, s0
	v_lshl_add_u64 v[2:3], v[106:107], 0, v[2:3]
	global_store_short v[2:3], v1, off
	s_waitcnt vmcnt(31)
	v_lshlrev_b32_e32 v1, 16, v174
	v_fma_f32 v2, |v1|, s92, 1.0
	v_rcp_f32_e32 v2, v2
	v_cmp_gt_f32_e32 vcc, 0, v1
	v_fmamk_f32 v3, v2, 0x3f07dc22, v236
	v_fmaak_f32 v3, v2, v3, 0x3f35f0e3
	v_fmaak_f32 v3, v2, v3, 0xbe11a98e
	v_fmaak_f32 v3, v2, v3, 0x3e027906
	v_mul_f32_e32 v2, v2, v3
	v_mul_f32_e32 v3, v1, v1
	v_mul_f32_e32 v3, 0xbf38aa3b, v3
	v_exp_f32_e32 v3, v3
	s_nop 0
	v_mul_f32_e32 v2, v3, v2
	v_mul_f32_e32 v3, v2, v1
	v_fma_f32 v2, -v2, v1, v1
	v_cndmask_b32_e32 v1, v2, v3, vcc
	v_add_f32_e32 v2, v17, v5
	v_mul_f32_e32 v1, v1, v2
	v_lshlrev_b64 v[2:3], 11, v[156:157]
	v_cvt_pk_bf16_f32 v1, v1, s0
	v_lshl_add_u64 v[2:3], v[106:107], 0, v[2:3]
	global_store_short v[2:3], v1, off
	s_barrier
	s_cbranch_scc0 .LBB0_254

.LBB0_257:
	s_add_i32 s7, s50, s54
	s_add_i32 s8, s51, s54
	s_cmpk_lt_i32 s8, 0x200
	s_cselect_b32 s7, s8, s7
	s_lshl_b32 s7, s7, 6
	s_and_b32 s8, s7, 0xfc0
	s_sub_i32 s10, s8, 30
	s_add_i32 s8, s10, s49
	s_and_b32 s7, s7, 0xfffff000
	s_max_i32 s8, s8, 0
	s_add_i32 s8, s8, s7
	v_and_b32_e32 v14, 0xff, v10
	v_mad_i64_i32 v[10:11], s[8:9], s8, v238, v[42:43]
	s_add_i32 s8, s10, s48
	s_max_i32 s8, s8, 0
	s_add_i32 s8, s8, s7
	v_mad_i64_i32 v[12:13], s[8:9], s8, v238, v[42:43]
	s_add_i32 s8, s10, s47
	s_max_i32 s8, s8, 0
	s_add_i32 s8, s8, s7
	s_waitcnt lgkmcnt(0)
	s_barrier
	global_load_dwordx2 v[152:153], v[10:11], off offset:1024
	global_load_dwordx2 v[154:155], v[10:11], off offset:1536
	global_load_dwordx2 v[148:149], v[12:13], off offset:1024
	global_load_dwordx2 v[150:151], v[12:13], off offset:1536
	v_mad_i64_i32 v[10:11], s[8:9], s8, v238, v[42:43]
	s_add_i32 s8, s10, s46
	s_max_i32 s8, s8, 0
	s_add_i32 s8, s8, s7
	v_mad_i64_i32 v[12:13], s[8:9], s8, v238, v[42:43]
	s_add_i32 s8, s10, s45
	s_max_i32 s8, s8, 0
	s_add_i32 s8, s8, s7
	global_load_dwordx2 v[144:145], v[10:11], off offset:1024
	global_load_dwordx2 v[146:147], v[10:11], off offset:1536
	global_load_dwordx2 v[140:141], v[12:13], off offset:1024
	global_load_dwordx2 v[142:143], v[12:13], off offset:1536
	v_mad_i64_i32 v[10:11], s[8:9], s8, v238, v[42:43]
	s_add_i32 s8, s10, s44
	s_max_i32 s8, s8, 0
	s_add_i32 s8, s8, s7
	v_mad_i64_i32 v[12:13], s[8:9], s8, v238, v[42:43]
	s_add_i32 s8, s10, s43
	s_max_i32 s8, s8, 0
	s_add_i32 s8, s8, s7
	global_load_dwordx2 v[136:137], v[10:11], off offset:1024
	global_load_dwordx2 v[138:139], v[10:11], off offset:1536
	global_load_dwordx2 v[132:133], v[12:13], off offset:1024
	global_load_dwordx2 v[134:135], v[12:13], off offset:1536
	v_mad_i64_i32 v[10:11], s[8:9], s8, v238, v[42:43]
	s_add_i32 s8, s10, s42
	s_max_i32 s8, s8, 0
	s_add_i32 s8, s8, s7
	v_mad_i64_i32 v[12:13], s[8:9], s8, v238, v[42:43]
	s_add_i32 s8, s10, s41
	s_max_i32 s8, s8, 0
	s_add_i32 s8, s8, s7
	global_load_dwordx2 v[126:127], v[10:11], off offset:1024
	global_load_dwordx2 v[128:129], v[10:11], off offset:1536
	global_load_dwordx2 v[122:123], v[12:13], off offset:1024
	global_load_dwordx2 v[124:125], v[12:13], off offset:1536
	v_mad_i64_i32 v[10:11], s[8:9], s8, v238, v[42:43]
	s_add_i32 s8, s10, s40
	s_max_i32 s8, s8, 0
	s_add_i32 s8, s8, s7
	v_mad_i64_i32 v[12:13], s[8:9], s8, v238, v[42:43]
	s_add_i32 s8, s10, s34
	s_max_i32 s8, s8, 0
	s_add_i32 s8, s8, s7
	global_load_dwordx2 v[118:119], v[10:11], off offset:1024
	global_load_dwordx2 v[120:121], v[10:11], off offset:1536
	global_load_dwordx2 v[114:115], v[12:13], off offset:1024
	global_load_dwordx2 v[116:117], v[12:13], off offset:1536
	v_mad_i64_i32 v[10:11], s[8:9], s8, v238, v[42:43]
	s_add_i32 s10, s10, s5
	s_lshl_b32 s6, s6, 7
	s_max_i32 s8, s10, 0
	s_and_b32 s6, s6, 0xffff8000
	s_add_i32 s8, s8, s7
	s_add_i32 s6, s6, 0
	v_mad_i64_i32 v[12:13], s[8:9], s8, v238, v[42:43]
	v_lshl_add_u32 v163, v14, 2, s6
	global_load_dwordx2 v[110:111], v[10:11], off offset:1024
	global_load_dwordx2 v[112:113], v[10:11], off offset:1536
	global_load_dwordx2 v[106:107], v[12:13], off offset:1024
	global_load_dwordx2 v[108:109], v[12:13], off offset:1536
	ds_read2st64_b32 v[26:27], v163 offset1:4
	ds_read2st64_b32 v[28:29], v163 offset0:8 offset1:12
	ds_read2st64_b32 v[30:31], v163 offset0:16 offset1:20
	ds_read2st64_b32 v[32:33], v163 offset0:24 offset1:28
	ds_read2st64_b32 v[160:161], v163 offset0:32 offset1:36
	ds_read2st64_b32 v[158:159], v163 offset0:40 offset1:44
	ds_read2st64_b32 v[156:157], v163 offset0:48 offset1:52
	ds_read2st64_b32 v[40:41], v163 offset0:56 offset1:60
	ds_read2st64_b32 v[38:39], v163 offset0:64 offset1:68
	ds_read2st64_b32 v[36:37], v163 offset0:72 offset1:76
	ds_read2st64_b32 v[34:35], v163 offset0:80 offset1:84
	ds_read2st64_b32 v[24:25], v163 offset0:88 offset1:92
	ds_read2st64_b32 v[22:23], v163 offset0:96 offset1:100
	ds_read2st64_b32 v[20:21], v163 offset0:104 offset1:108
	ds_read2st64_b32 v[10:11], v163 offset0:120 offset1:124
	ds_read2st64_b32 v[18:19], v163 offset0:112 offset1:116
	ds_read2st64_b32 v[12:13], v163 offset0:128 offset1:132
	ds_read2st64_b32 v[14:15], v163 offset0:136 offset1:140
	ds_read2st64_b32 v[16:17], v163 offset0:144 offset1:148
	s_waitcnt vmcnt(49) lgkmcnt(4)
	v_mul_f32_e32 v105, v103, v10
	v_mul_f32_e32 v165, v44, v27
	s_waitcnt vmcnt(24)
	v_mov_b32_e32 v164, v104
	v_pk_fma_f32 v[26:27], v[44:45], v[26:27], v[104:105]
	v_pk_fma_f32 v[164:165], v[46:47], v[28:29], v[164:165]
	v_pk_fma_f32 v[26:27], v[48:49], v[28:29], v[26:27]
	v_pk_fma_f32 v[164:165], v[50:51], v[30:31], v[164:165]
	v_pk_fma_f32 v[26:27], v[52:53], v[30:31], v[26:27]
	v_pk_fma_f32 v[164:165], v[54:55], v[32:33], v[164:165]
	v_pk_fma_f32 v[26:27], v[56:57], v[32:33], v[26:27]
	v_pk_fma_f32 v[164:165], v[58:59], v[160:161], v[164:165]
	v_pk_fma_f32 v[26:27], v[60:61], v[160:161], v[26:27]
	v_pk_fma_f32 v[164:165], v[62:63], v[158:159], v[164:165]
	v_pk_fma_f32 v[26:27], v[64:65], v[158:159], v[26:27]
	v_pk_fma_f32 v[164:165], v[66:67], v[156:157], v[164:165]
	v_pk_fma_f32 v[26:27], v[68:69], v[156:157], v[26:27]
	v_pk_fma_f32 v[164:165], v[70:71], v[40:41], v[164:165]
	v_pk_fma_f32 v[26:27], v[72:73], v[40:41], v[26:27]
	v_pk_fma_f32 v[164:165], v[74:75], v[38:39], v[164:165]
	v_pk_fma_f32 v[26:27], v[76:77], v[38:39], v[26:27]
	v_pk_fma_f32 v[164:165], v[78:79], v[36:37], v[164:165]
	v_pk_fma_f32 v[26:27], v[80:81], v[36:37], v[26:27]
	v_pk_fma_f32 v[164:165], v[82:83], v[34:35], v[164:165]
	v_pk_fma_f32 v[26:27], v[84:85], v[34:35], v[26:27]
	v_pk_fma_f32 v[164:165], v[86:87], v[24:25], v[164:165]
	v_pk_fma_f32 v[26:27], v[88:89], v[24:25], v[26:27]
	v_pk_fma_f32 v[164:165], v[90:91], v[22:23], v[164:165]
	v_pk_fma_f32 v[26:27], v[92:93], v[22:23], v[26:27]
	v_pk_fma_f32 v[164:165], v[94:95], v[20:21], v[164:165]
	v_pk_fma_f32 v[26:27], v[96:97], v[20:21], v[26:27]
	s_waitcnt lgkmcnt(3)
	v_pk_fma_f32 v[164:165], v[98:99], v[18:19], v[164:165]
	v_pk_fma_f32 v[26:27], v[100:101], v[18:19], v[26:27]
	v_pk_fma_f32 v[166:167], v[102:103], v[10:11], v[164:165]
	v_add_f32_e32 v164, v26, v27
	v_mul_f32_e32 v27, v44, v29
	v_mov_b32_e32 v26, v104
	v_pk_fma_f32 v[26:27], v[46:47], v[30:31], v[26:27]
	v_add_f32_e32 v165, v166, v167
	v_pk_fma_f32 v[26:27], v[50:51], v[32:33], v[26:27]
	s_waitcnt lgkmcnt(2)
	v_mul_f32_e32 v105, v103, v12
	v_pk_fma_f32 v[26:27], v[54:55], v[160:161], v[26:27]
	v_pk_fma_f32 v[28:29], v[44:45], v[28:29], v[104:105]
	v_pk_fma_f32 v[26:27], v[58:59], v[158:159], v[26:27]
	v_pk_fma_f32 v[28:29], v[48:49], v[30:31], v[28:29]
	v_pk_fma_f32 v[26:27], v[62:63], v[156:157], v[26:27]
	v_pk_fma_f32 v[28:29], v[52:53], v[32:33], v[28:29]
	v_pk_fma_f32 v[26:27], v[66:67], v[40:41], v[26:27]
	v_pk_fma_f32 v[28:29], v[56:57], v[160:161], v[28:29]
	v_pk_fma_f32 v[26:27], v[70:71], v[38:39], v[26:27]
	v_pk_fma_f32 v[28:29], v[60:61], v[158:159], v[28:29]
	v_pk_fma_f32 v[26:27], v[74:75], v[36:37], v[26:27]
	v_pk_fma_f32 v[28:29], v[64:65], v[156:157], v[28:29]
	v_pk_fma_f32 v[26:27], v[78:79], v[34:35], v[26:27]
	v_pk_fma_f32 v[28:29], v[68:69], v[40:41], v[28:29]
	v_pk_fma_f32 v[26:27], v[82:83], v[24:25], v[26:27]
	v_pk_fma_f32 v[28:29], v[72:73], v[38:39], v[28:29]
	v_pk_fma_f32 v[26:27], v[86:87], v[22:23], v[26:27]
	v_pk_fma_f32 v[28:29], v[76:77], v[36:37], v[28:29]
	v_pk_fma_f32 v[26:27], v[90:91], v[20:21], v[26:27]
	v_pk_fma_f32 v[28:29], v[80:81], v[34:35], v[28:29]
	v_pk_fma_f32 v[26:27], v[94:95], v[18:19], v[26:27]
	v_pk_fma_f32 v[28:29], v[84:85], v[24:25], v[28:29]
	v_pk_fma_f32 v[26:27], v[98:99], v[10:11], v[26:27]
	v_pk_fma_f32 v[28:29], v[88:89], v[22:23], v[28:29]
	v_pk_fma_f32 v[26:27], v[102:103], v[12:13], v[26:27]
	v_pk_fma_f32 v[28:29], v[92:93], v[20:21], v[28:29]
	v_add_f32_e32 v167, v26, v27
	v_mul_f32_e32 v27, v44, v31
	v_mov_b32_e32 v26, v104
	v_pk_fma_f32 v[26:27], v[46:47], v[32:33], v[26:27]
	v_pk_fma_f32 v[28:29], v[96:97], v[18:19], v[28:29]
	v_pk_fma_f32 v[26:27], v[50:51], v[160:161], v[26:27]
	v_pk_fma_f32 v[28:29], v[100:101], v[10:11], v[28:29]
	v_pk_fma_f32 v[26:27], v[54:55], v[158:159], v[26:27]
	s_waitcnt lgkmcnt(1)
	v_mul_f32_e32 v105, v103, v14
	v_pk_fma_f32 v[26:27], v[58:59], v[156:157], v[26:27]
	v_add_f32_e32 v166, v28, v29
	v_pk_fma_f32 v[26:27], v[62:63], v[40:41], v[26:27]
	v_pk_fma_f32 v[28:29], v[44:45], v[30:31], v[104:105]
	v_pk_fma_f32 v[26:27], v[66:67], v[38:39], v[26:27]
	v_pk_fma_f32 v[28:29], v[48:49], v[32:33], v[28:29]
	v_pk_fma_f32 v[26:27], v[70:71], v[36:37], v[26:27]
	v_pk_fma_f32 v[28:29], v[52:53], v[160:161], v[28:29]
	v_pk_fma_f32 v[26:27], v[74:75], v[34:35], v[26:27]
	v_pk_fma_f32 v[28:29], v[56:57], v[158:159], v[28:29]
	v_pk_fma_f32 v[26:27], v[78:79], v[24:25], v[26:27]
	v_pk_fma_f32 v[28:29], v[60:61], v[156:157], v[28:29]
	v_pk_fma_f32 v[26:27], v[82:83], v[22:23], v[26:27]
	v_pk_fma_f32 v[28:29], v[64:65], v[40:41], v[28:29]
	v_pk_fma_f32 v[26:27], v[86:87], v[20:21], v[26:27]
	v_pk_fma_f32 v[28:29], v[68:69], v[38:39], v[28:29]
	v_pk_fma_f32 v[26:27], v[90:91], v[18:19], v[26:27]
	v_pk_fma_f32 v[28:29], v[72:73], v[36:37], v[28:29]
	v_pk_fma_f32 v[26:27], v[94:95], v[10:11], v[26:27]
	v_pk_fma_f32 v[28:29], v[76:77], v[34:35], v[28:29]
	v_pk_fma_f32 v[26:27], v[98:99], v[12:13], v[26:27]
	v_pk_fma_f32 v[28:29], v[80:81], v[24:25], v[28:29]
	v_pk_fma_f32 v[26:27], v[102:103], v[14:15], v[26:27]
	v_pk_fma_f32 v[28:29], v[84:85], v[22:23], v[28:29]
	v_add_f32_e32 v169, v26, v27
	v_mul_f32_e32 v27, v44, v33
	v_mov_b32_e32 v26, v104
	v_pk_fma_f32 v[26:27], v[46:47], v[160:161], v[26:27]
	v_pk_fma_f32 v[28:29], v[88:89], v[20:21], v[28:29]
	v_pk_fma_f32 v[26:27], v[50:51], v[158:159], v[26:27]
	v_pk_fma_f32 v[28:29], v[92:93], v[18:19], v[28:29]
	v_pk_fma_f32 v[26:27], v[54:55], v[156:157], v[26:27]
	v_pk_fma_f32 v[28:29], v[96:97], v[10:11], v[28:29]
	v_pk_fma_f32 v[26:27], v[58:59], v[40:41], v[26:27]
	v_pk_fma_f32 v[28:29], v[100:101], v[12:13], v[28:29]
	v_pk_fma_f32 v[26:27], v[62:63], v[38:39], v[26:27]
	s_waitcnt lgkmcnt(0)
	v_mul_f32_e32 v105, v103, v16
	v_pk_fma_f32 v[26:27], v[66:67], v[36:37], v[26:27]
	v_add_f32_e32 v168, v28, v29
	v_pk_fma_f32 v[26:27], v[70:71], v[34:35], v[26:27]
	v_pk_fma_f32 v[28:29], v[44:45], v[32:33], v[104:105]
	v_pk_fma_f32 v[26:27], v[74:75], v[24:25], v[26:27]
	v_pk_fma_f32 v[28:29], v[48:49], v[160:161], v[28:29]
	v_pk_fma_f32 v[26:27], v[78:79], v[22:23], v[26:27]
	v_pk_fma_f32 v[28:29], v[52:53], v[158:159], v[28:29]
	v_pk_fma_f32 v[26:27], v[82:83], v[20:21], v[26:27]
	v_pk_fma_f32 v[28:29], v[56:57], v[156:157], v[28:29]
	v_pk_fma_f32 v[26:27], v[86:87], v[18:19], v[26:27]
	v_pk_fma_f32 v[28:29], v[60:61], v[40:41], v[28:29]
	v_pk_fma_f32 v[26:27], v[90:91], v[10:11], v[26:27]
	v_mul_f32_e32 v173, v44, v161
	v_pk_fma_f32 v[26:27], v[94:95], v[12:13], v[26:27]
	v_pk_fma_f32 v[28:29], v[64:65], v[38:39], v[28:29]
	v_pk_fma_f32 v[26:27], v[98:99], v[14:15], v[26:27]
	v_pk_fma_f32 v[28:29], v[68:69], v[36:37], v[28:29]
	v_pk_fma_f32 v[30:31], v[102:103], v[16:17], v[26:27]
	ds_read2st64_b32 v[26:27], v163 offset0:152 offset1:156
	v_pk_fma_f32 v[28:29], v[72:73], v[34:35], v[28:29]
	v_add_f32_e32 v171, v30, v31
	v_pk_fma_f32 v[28:29], v[76:77], v[24:25], v[28:29]
	v_mov_b32_e32 v172, v104
	s_waitcnt lgkmcnt(0)
	v_mul_f32_e32 v105, v103, v26
	v_pk_fma_f32 v[160:161], v[44:45], v[160:161], v[104:105]
	v_pk_fma_f32 v[28:29], v[80:81], v[22:23], v[28:29]
	v_pk_fma_f32 v[160:161], v[48:49], v[158:159], v[160:161]
	v_pk_fma_f32 v[28:29], v[84:85], v[20:21], v[28:29]
	v_pk_fma_f32 v[160:161], v[52:53], v[156:157], v[160:161]
	v_pk_fma_f32 v[28:29], v[88:89], v[18:19], v[28:29]
	v_pk_fma_f32 v[160:161], v[56:57], v[40:41], v[160:161]
	v_pk_fma_f32 v[28:29], v[92:93], v[10:11], v[28:29]
	v_pk_fma_f32 v[160:161], v[60:61], v[38:39], v[160:161]
	v_pk_fma_f32 v[28:29], v[96:97], v[12:13], v[28:29]
	v_pk_fma_f32 v[160:161], v[64:65], v[36:37], v[160:161]
	v_pk_fma_f32 v[28:29], v[100:101], v[14:15], v[28:29]
	v_pk_fma_f32 v[160:161], v[68:69], v[34:35], v[160:161]
	v_add_f32_e32 v170, v28, v29
	v_pk_fma_f32 v[160:161], v[72:73], v[24:25], v[160:161]
	ds_read2st64_b32 v[28:29], v163 offset0:160 offset1:164
	ds_read2st64_b32 v[30:31], v163 offset0:168 offset1:172
	ds_read2st64_b32 v[32:33], v163 offset0:176 offset1:180
	v_pk_fma_f32 v[160:161], v[76:77], v[22:23], v[160:161]
	v_pk_fma_f32 v[172:173], v[46:47], v[158:159], v[172:173]
	v_pk_fma_f32 v[160:161], v[80:81], v[20:21], v[160:161]
	s_waitcnt lgkmcnt(2)
	v_mul_f32_e32 v105, v103, v28
	v_pk_fma_f32 v[160:161], v[84:85], v[18:19], v[160:161]
	v_pk_fma_f32 v[172:173], v[50:51], v[156:157], v[172:173]
	v_pk_fma_f32 v[160:161], v[88:89], v[10:11], v[160:161]
	v_pk_fma_f32 v[172:173], v[54:55], v[40:41], v[172:173]
	v_pk_fma_f32 v[160:161], v[92:93], v[12:13], v[160:161]
	v_pk_fma_f32 v[172:173], v[58:59], v[38:39], v[172:173]
	v_pk_fma_f32 v[160:161], v[96:97], v[14:15], v[160:161]
	v_pk_fma_f32 v[172:173], v[62:63], v[36:37], v[172:173]
	v_pk_fma_f32 v[160:161], v[100:101], v[16:17], v[160:161]
	v_pk_fma_f32 v[172:173], v[66:67], v[34:35], v[172:173]
	v_add_f32_e32 v174, v160, v161
	v_mul_f32_e32 v161, v44, v159
	v_pk_fma_f32 v[158:159], v[44:45], v[158:159], v[104:105]
	v_mov_b32_e32 v160, v104
	v_pk_fma_f32 v[158:159], v[48:49], v[156:157], v[158:159]
	s_waitcnt lgkmcnt(1)
	v_mul_f32_e32 v105, v103, v30
	v_pk_fma_f32 v[158:159], v[52:53], v[40:41], v[158:159]
	v_pk_fma_f32 v[160:161], v[46:47], v[156:157], v[160:161]
	v_pk_fma_f32 v[158:159], v[56:57], v[38:39], v[158:159]
	v_pk_fma_f32 v[160:161], v[50:51], v[40:41], v[160:161]
	v_pk_fma_f32 v[158:159], v[60:61], v[36:37], v[158:159]
	v_pk_fma_f32 v[172:173], v[70:71], v[24:25], v[172:173]
	v_pk_fma_f32 v[158:159], v[64:65], v[34:35], v[158:159]
	v_pk_fma_f32 v[172:173], v[74:75], v[22:23], v[172:173]
	v_pk_fma_f32 v[158:159], v[68:69], v[24:25], v[158:159]
	v_pk_fma_f32 v[172:173], v[78:79], v[20:21], v[172:173]
	v_pk_fma_f32 v[158:159], v[72:73], v[22:23], v[158:159]
	v_pk_fma_f32 v[172:173], v[82:83], v[18:19], v[172:173]
	v_pk_fma_f32 v[158:159], v[76:77], v[20:21], v[158:159]
	v_pk_fma_f32 v[172:173], v[86:87], v[10:11], v[172:173]
	v_pk_fma_f32 v[158:159], v[80:81], v[18:19], v[158:159]
	v_pk_fma_f32 v[172:173], v[90:91], v[12:13], v[172:173]
	v_pk_fma_f32 v[158:159], v[84:85], v[10:11], v[158:159]
	v_pk_fma_f32 v[172:173], v[94:95], v[14:15], v[172:173]
	v_pk_fma_f32 v[158:159], v[88:89], v[12:13], v[158:159]
	v_pk_fma_f32 v[172:173], v[98:99], v[16:17], v[172:173]
	v_pk_fma_f32 v[158:159], v[92:93], v[14:15], v[158:159]
	v_pk_fma_f32 v[160:161], v[54:55], v[38:39], v[160:161]
	v_pk_fma_f32 v[158:159], v[96:97], v[16:17], v[158:159]
	v_pk_fma_f32 v[172:173], v[102:103], v[26:27], v[172:173]
	v_pk_fma_f32 v[158:159], v[100:101], v[26:27], v[158:159]
	v_pk_fma_f32 v[160:161], v[58:59], v[36:37], v[160:161]
	v_add_f32_e32 v176, v158, v159
	v_mul_f32_e32 v159, v44, v157
	v_pk_fma_f32 v[156:157], v[44:45], v[156:157], v[104:105]
	v_mov_b32_e32 v158, v104
	v_pk_fma_f32 v[156:157], v[48:49], v[40:41], v[156:157]
	s_waitcnt lgkmcnt(0)
	v_mul_f32_e32 v105, v103, v32
	v_pk_fma_f32 v[156:157], v[52:53], v[38:39], v[156:157]
	v_pk_fma_f32 v[158:159], v[46:47], v[40:41], v[158:159]
	v_pk_fma_f32 v[156:157], v[56:57], v[36:37], v[156:157]
	v_pk_fma_f32 v[158:159], v[50:51], v[38:39], v[158:159]
	v_pk_fma_f32 v[156:157], v[60:61], v[34:35], v[156:157]
	v_pk_fma_f32 v[158:159], v[54:55], v[36:37], v[158:159]
	v_pk_fma_f32 v[156:157], v[64:65], v[24:25], v[156:157]
	v_pk_fma_f32 v[158:159], v[58:59], v[34:35], v[158:159]
	v_pk_fma_f32 v[156:157], v[68:69], v[22:23], v[156:157]
	v_add_f32_e32 v175, v172, v173
	v_pk_fma_f32 v[156:157], v[72:73], v[20:21], v[156:157]
	v_pk_fma_f32 v[160:161], v[62:63], v[34:35], v[160:161]
	v_pk_fma_f32 v[156:157], v[76:77], v[18:19], v[156:157]
	v_pk_fma_f32 v[158:159], v[62:63], v[24:25], v[158:159]
	v_pk_fma_f32 v[156:157], v[80:81], v[10:11], v[156:157]
	v_mul_f32_e32 v173, v44, v39
	v_pk_fma_f32 v[156:157], v[84:85], v[12:13], v[156:157]
	v_pk_fma_f32 v[160:161], v[66:67], v[24:25], v[160:161]
	v_pk_fma_f32 v[156:157], v[88:89], v[14:15], v[156:157]
	v_pk_fma_f32 v[158:159], v[66:67], v[22:23], v[158:159]
	v_pk_fma_f32 v[156:157], v[92:93], v[16:17], v[156:157]
	v_pk_fma_f32 v[160:161], v[70:71], v[22:23], v[160:161]
	v_pk_fma_f32 v[156:157], v[96:97], v[26:27], v[156:157]
	v_pk_fma_f32 v[158:159], v[70:71], v[20:21], v[158:159]
	v_pk_fma_f32 v[156:157], v[100:101], v[28:29], v[156:157]
	v_pk_fma_f32 v[160:161], v[74:75], v[20:21], v[160:161]
	v_add_f32_e32 v178, v156, v157
	v_mul_f32_e32 v157, v44, v41
	v_pk_fma_f32 v[40:41], v[44:45], v[40:41], v[104:105]
	v_mov_b32_e32 v156, v104
	v_pk_fma_f32 v[40:41], v[48:49], v[38:39], v[40:41]
	v_pk_fma_f32 v[156:157], v[46:47], v[38:39], v[156:157]
	v_pk_fma_f32 v[40:41], v[52:53], v[36:37], v[40:41]
	v_pk_fma_f32 v[156:157], v[50:51], v[36:37], v[156:157]
	v_pk_fma_f32 v[40:41], v[56:57], v[34:35], v[40:41]
	v_pk_fma_f32 v[156:157], v[54:55], v[34:35], v[156:157]
	v_pk_fma_f32 v[40:41], v[60:61], v[24:25], v[40:41]
	v_pk_fma_f32 v[156:157], v[58:59], v[24:25], v[156:157]
	v_pk_fma_f32 v[40:41], v[64:65], v[22:23], v[40:41]
	v_pk_fma_f32 v[156:157], v[62:63], v[22:23], v[156:157]
	v_pk_fma_f32 v[40:41], v[68:69], v[20:21], v[40:41]
	v_pk_fma_f32 v[156:157], v[66:67], v[20:21], v[156:157]
	v_pk_fma_f32 v[40:41], v[72:73], v[18:19], v[40:41]
	v_pk_fma_f32 v[156:157], v[70:71], v[18:19], v[156:157]
	v_pk_fma_f32 v[40:41], v[76:77], v[10:11], v[40:41]
	v_pk_fma_f32 v[158:159], v[74:75], v[18:19], v[158:159]
	v_pk_fma_f32 v[40:41], v[80:81], v[12:13], v[40:41]
	v_pk_fma_f32 v[156:157], v[74:75], v[10:11], v[156:157]
	v_pk_fma_f32 v[40:41], v[84:85], v[14:15], v[40:41]
	v_pk_fma_f32 v[160:161], v[78:79], v[18:19], v[160:161]
	v_pk_fma_f32 v[40:41], v[88:89], v[16:17], v[40:41]
	v_pk_fma_f32 v[158:159], v[78:79], v[10:11], v[158:159]
	v_pk_fma_f32 v[40:41], v[92:93], v[26:27], v[40:41]
	v_pk_fma_f32 v[156:157], v[78:79], v[12:13], v[156:157]
	v_pk_fma_f32 v[40:41], v[96:97], v[28:29], v[40:41]
	v_pk_fma_f32 v[160:161], v[82:83], v[10:11], v[160:161]
	v_pk_fma_f32 v[40:41], v[100:101], v[30:31], v[40:41]
	v_pk_fma_f32 v[158:159], v[82:83], v[12:13], v[158:159]
	v_add_f32_e32 v180, v40, v41
	ds_read2st64_b32 v[40:41], v163 offset0:184 offset1:188
	v_pk_fma_f32 v[156:157], v[82:83], v[14:15], v[156:157]
	v_pk_fma_f32 v[160:161], v[86:87], v[12:13], v[160:161]
	v_pk_fma_f32 v[158:159], v[86:87], v[14:15], v[158:159]
	v_pk_fma_f32 v[156:157], v[86:87], v[16:17], v[156:157]
	s_waitcnt lgkmcnt(0)
	v_mul_f32_e32 v105, v103, v40
	v_pk_fma_f32 v[38:39], v[44:45], v[38:39], v[104:105]
	v_pk_fma_f32 v[160:161], v[90:91], v[14:15], v[160:161]
	v_pk_fma_f32 v[38:39], v[48:49], v[36:37], v[38:39]
	v_pk_fma_f32 v[158:159], v[90:91], v[16:17], v[158:159]
	v_pk_fma_f32 v[38:39], v[52:53], v[34:35], v[38:39]
	v_pk_fma_f32 v[156:157], v[90:91], v[26:27], v[156:157]
	v_pk_fma_f32 v[38:39], v[56:57], v[24:25], v[38:39]
	v_pk_fma_f32 v[160:161], v[94:95], v[16:17], v[160:161]
	v_pk_fma_f32 v[38:39], v[60:61], v[22:23], v[38:39]
	v_pk_fma_f32 v[158:159], v[94:95], v[26:27], v[158:159]
	v_pk_fma_f32 v[38:39], v[64:65], v[20:21], v[38:39]
	v_pk_fma_f32 v[156:157], v[94:95], v[28:29], v[156:157]
	v_pk_fma_f32 v[38:39], v[68:69], v[18:19], v[38:39]
	v_pk_fma_f32 v[160:161], v[98:99], v[26:27], v[160:161]
	v_pk_fma_f32 v[38:39], v[72:73], v[10:11], v[38:39]
	v_pk_fma_f32 v[158:159], v[98:99], v[28:29], v[158:159]
	v_pk_fma_f32 v[38:39], v[76:77], v[12:13], v[38:39]
	v_pk_fma_f32 v[156:157], v[98:99], v[30:31], v[156:157]
	v_pk_fma_f32 v[38:39], v[80:81], v[14:15], v[38:39]
	v_pk_fma_f32 v[160:161], v[102:103], v[28:29], v[160:161]
	v_pk_fma_f32 v[158:159], v[102:103], v[30:31], v[158:159]
	v_pk_fma_f32 v[156:157], v[102:103], v[32:33], v[156:157]
	v_pk_fma_f32 v[38:39], v[84:85], v[16:17], v[38:39]
	v_add_f32_e32 v177, v160, v161
	v_add_f32_e32 v179, v158, v159
	v_add_f32_e32 v181, v156, v157
	ds_read2st64_b32 v[156:157], v163 offset0:192 offset1:196
	ds_read2st64_b32 v[158:159], v163 offset0:200 offset1:204
	ds_read2st64_b32 v[160:161], v163 offset0:208 offset1:212
	v_pk_fma_f32 v[38:39], v[88:89], v[26:27], v[38:39]
	v_mov_b32_e32 v172, v104
	v_pk_fma_f32 v[38:39], v[92:93], v[28:29], v[38:39]
	s_waitcnt lgkmcnt(2)
	v_mul_f32_e32 v105, v103, v156
	v_pk_fma_f32 v[38:39], v[96:97], v[30:31], v[38:39]
	v_pk_fma_f32 v[172:173], v[46:47], v[36:37], v[172:173]
	v_pk_fma_f32 v[38:39], v[100:101], v[32:33], v[38:39]
	v_pk_fma_f32 v[172:173], v[50:51], v[34:35], v[172:173]
	v_add_f32_e32 v182, v38, v39
	v_mul_f32_e32 v39, v44, v37
	v_pk_fma_f32 v[36:37], v[44:45], v[36:37], v[104:105]
	v_mov_b32_e32 v38, v104
	v_pk_fma_f32 v[36:37], v[48:49], v[34:35], v[36:37]
	s_waitcnt lgkmcnt(1)
	v_mul_f32_e32 v105, v103, v158
	v_pk_fma_f32 v[36:37], v[52:53], v[24:25], v[36:37]
	v_pk_fma_f32 v[38:39], v[46:47], v[34:35], v[38:39]
	v_pk_fma_f32 v[36:37], v[56:57], v[22:23], v[36:37]
	v_pk_fma_f32 v[172:173], v[54:55], v[24:25], v[172:173]
	v_pk_fma_f32 v[36:37], v[60:61], v[20:21], v[36:37]
	v_pk_fma_f32 v[38:39], v[50:51], v[24:25], v[38:39]
	v_pk_fma_f32 v[36:37], v[64:65], v[18:19], v[36:37]
	v_pk_fma_f32 v[172:173], v[58:59], v[22:23], v[172:173]
	v_pk_fma_f32 v[36:37], v[68:69], v[10:11], v[36:37]
	v_pk_fma_f32 v[172:173], v[62:63], v[20:21], v[172:173]
	v_pk_fma_f32 v[36:37], v[72:73], v[12:13], v[36:37]
	v_pk_fma_f32 v[172:173], v[66:67], v[18:19], v[172:173]
	v_pk_fma_f32 v[36:37], v[76:77], v[14:15], v[36:37]
	v_pk_fma_f32 v[172:173], v[70:71], v[10:11], v[172:173]
	v_pk_fma_f32 v[36:37], v[80:81], v[16:17], v[36:37]
	v_pk_fma_f32 v[172:173], v[74:75], v[12:13], v[172:173]
	v_pk_fma_f32 v[36:37], v[84:85], v[26:27], v[36:37]
	v_pk_fma_f32 v[172:173], v[78:79], v[14:15], v[172:173]
	v_pk_fma_f32 v[36:37], v[88:89], v[28:29], v[36:37]
	v_pk_fma_f32 v[172:173], v[82:83], v[16:17], v[172:173]
	v_pk_fma_f32 v[36:37], v[92:93], v[30:31], v[36:37]
	v_pk_fma_f32 v[172:173], v[86:87], v[26:27], v[172:173]
	v_pk_fma_f32 v[36:37], v[96:97], v[32:33], v[36:37]
	v_pk_fma_f32 v[172:173], v[90:91], v[28:29], v[172:173]
	v_pk_fma_f32 v[36:37], v[100:101], v[40:41], v[36:37]
	v_pk_fma_f32 v[172:173], v[94:95], v[30:31], v[172:173]
	v_add_f32_e32 v184, v36, v37
	v_mul_f32_e32 v37, v44, v35
	v_pk_fma_f32 v[34:35], v[44:45], v[34:35], v[104:105]
	v_mov_b32_e32 v36, v104
	v_pk_fma_f32 v[34:35], v[48:49], v[24:25], v[34:35]
	s_waitcnt lgkmcnt(0)
	v_mul_f32_e32 v105, v103, v160
	v_pk_fma_f32 v[34:35], v[52:53], v[22:23], v[34:35]
	v_pk_fma_f32 v[36:37], v[46:47], v[24:25], v[36:37]
	v_pk_fma_f32 v[34:35], v[56:57], v[20:21], v[34:35]
	v_pk_fma_f32 v[36:37], v[50:51], v[22:23], v[36:37]
	v_pk_fma_f32 v[34:35], v[60:61], v[18:19], v[34:35]
	v_pk_fma_f32 v[172:173], v[98:99], v[32:33], v[172:173]
	v_pk_fma_f32 v[34:35], v[64:65], v[10:11], v[34:35]
	v_pk_fma_f32 v[38:39], v[54:55], v[22:23], v[38:39]
	v_pk_fma_f32 v[34:35], v[68:69], v[12:13], v[34:35]
	v_pk_fma_f32 v[36:37], v[54:55], v[20:21], v[36:37]
	v_pk_fma_f32 v[34:35], v[72:73], v[14:15], v[34:35]
	v_pk_fma_f32 v[172:173], v[102:103], v[40:41], v[172:173]
	v_pk_fma_f32 v[34:35], v[76:77], v[16:17], v[34:35]
	v_pk_fma_f32 v[38:39], v[58:59], v[20:21], v[38:39]
	v_pk_fma_f32 v[34:35], v[80:81], v[26:27], v[34:35]
	v_pk_fma_f32 v[36:37], v[58:59], v[18:19], v[36:37]
	v_pk_fma_f32 v[34:35], v[84:85], v[28:29], v[34:35]
	v_add_f32_e32 v183, v172, v173
	v_pk_fma_f32 v[34:35], v[88:89], v[30:31], v[34:35]
	v_pk_fma_f32 v[38:39], v[62:63], v[18:19], v[38:39]
	v_pk_fma_f32 v[34:35], v[92:93], v[32:33], v[34:35]
	v_pk_fma_f32 v[36:37], v[62:63], v[10:11], v[36:37]
	v_pk_fma_f32 v[34:35], v[96:97], v[40:41], v[34:35]
	v_mul_f32_e32 v173, v44, v23
	v_pk_fma_f32 v[34:35], v[100:101], v[156:157], v[34:35]
	v_pk_fma_f32 v[38:39], v[66:67], v[10:11], v[38:39]
	v_add_f32_e32 v186, v34, v35
	v_mul_f32_e32 v35, v44, v25
	v_pk_fma_f32 v[24:25], v[44:45], v[24:25], v[104:105]
	v_mov_b32_e32 v34, v104
	v_pk_fma_f32 v[24:25], v[48:49], v[22:23], v[24:25]
	v_pk_fma_f32 v[34:35], v[46:47], v[22:23], v[34:35]
	v_pk_fma_f32 v[24:25], v[52:53], v[20:21], v[24:25]
	v_pk_fma_f32 v[34:35], v[50:51], v[20:21], v[34:35]
	v_pk_fma_f32 v[24:25], v[56:57], v[18:19], v[24:25]
	v_pk_fma_f32 v[34:35], v[54:55], v[18:19], v[34:35]
	v_pk_fma_f32 v[24:25], v[60:61], v[10:11], v[24:25]
	v_pk_fma_f32 v[34:35], v[58:59], v[10:11], v[34:35]
	v_pk_fma_f32 v[24:25], v[64:65], v[12:13], v[24:25]
	v_pk_fma_f32 v[34:35], v[62:63], v[12:13], v[34:35]
	v_pk_fma_f32 v[24:25], v[68:69], v[14:15], v[24:25]
	v_pk_fma_f32 v[36:37], v[66:67], v[12:13], v[36:37]
	v_pk_fma_f32 v[24:25], v[72:73], v[16:17], v[24:25]
	v_pk_fma_f32 v[34:35], v[66:67], v[14:15], v[34:35]
	v_pk_fma_f32 v[24:25], v[76:77], v[26:27], v[24:25]
	v_pk_fma_f32 v[38:39], v[70:71], v[12:13], v[38:39]
	v_pk_fma_f32 v[24:25], v[80:81], v[28:29], v[24:25]
	v_pk_fma_f32 v[36:37], v[70:71], v[14:15], v[36:37]
	v_pk_fma_f32 v[24:25], v[84:85], v[30:31], v[24:25]
	v_pk_fma_f32 v[34:35], v[70:71], v[16:17], v[34:35]
	v_pk_fma_f32 v[24:25], v[88:89], v[32:33], v[24:25]
	v_pk_fma_f32 v[38:39], v[74:75], v[14:15], v[38:39]
	v_pk_fma_f32 v[24:25], v[92:93], v[40:41], v[24:25]
	v_pk_fma_f32 v[36:37], v[74:75], v[16:17], v[36:37]
	v_pk_fma_f32 v[24:25], v[96:97], v[156:157], v[24:25]
	v_pk_fma_f32 v[34:35], v[74:75], v[26:27], v[34:35]
	v_pk_fma_f32 v[24:25], v[100:101], v[158:159], v[24:25]
	v_pk_fma_f32 v[38:39], v[78:79], v[16:17], v[38:39]
	v_add_f32_e32 v188, v24, v25
	ds_read2st64_b32 v[24:25], v163 offset0:216 offset1:220
	v_pk_fma_f32 v[36:37], v[78:79], v[26:27], v[36:37]
	v_pk_fma_f32 v[34:35], v[78:79], v[28:29], v[34:35]
	v_pk_fma_f32 v[38:39], v[82:83], v[26:27], v[38:39]
	v_pk_fma_f32 v[36:37], v[82:83], v[28:29], v[36:37]
	s_waitcnt lgkmcnt(0)
	v_mul_f32_e32 v105, v103, v24
	v_pk_fma_f32 v[22:23], v[44:45], v[22:23], v[104:105]
	v_pk_fma_f32 v[34:35], v[82:83], v[30:31], v[34:35]
	v_pk_fma_f32 v[22:23], v[48:49], v[20:21], v[22:23]
	v_pk_fma_f32 v[38:39], v[86:87], v[28:29], v[38:39]
	v_pk_fma_f32 v[22:23], v[52:53], v[18:19], v[22:23]
	v_pk_fma_f32 v[36:37], v[86:87], v[30:31], v[36:37]
	v_pk_fma_f32 v[22:23], v[56:57], v[10:11], v[22:23]
	v_pk_fma_f32 v[34:35], v[86:87], v[32:33], v[34:35]
	v_pk_fma_f32 v[22:23], v[60:61], v[12:13], v[22:23]
	v_pk_fma_f32 v[38:39], v[90:91], v[30:31], v[38:39]
	v_pk_fma_f32 v[22:23], v[64:65], v[14:15], v[22:23]
	v_pk_fma_f32 v[36:37], v[90:91], v[32:33], v[36:37]
	v_pk_fma_f32 v[22:23], v[68:69], v[16:17], v[22:23]
	v_pk_fma_f32 v[34:35], v[90:91], v[40:41], v[34:35]
	v_pk_fma_f32 v[22:23], v[72:73], v[26:27], v[22:23]
	v_pk_fma_f32 v[38:39], v[94:95], v[32:33], v[38:39]
	v_pk_fma_f32 v[36:37], v[94:95], v[40:41], v[36:37]
	v_pk_fma_f32 v[34:35], v[94:95], v[156:157], v[34:35]
	v_pk_fma_f32 v[22:23], v[76:77], v[28:29], v[22:23]
	v_pk_fma_f32 v[38:39], v[98:99], v[40:41], v[38:39]
	v_pk_fma_f32 v[36:37], v[98:99], v[156:157], v[36:37]
	v_pk_fma_f32 v[34:35], v[98:99], v[158:159], v[34:35]
	v_pk_fma_f32 v[22:23], v[80:81], v[30:31], v[22:23]
	v_pk_fma_f32 v[38:39], v[102:103], v[156:157], v[38:39]
	v_pk_fma_f32 v[36:37], v[102:103], v[158:159], v[36:37]
	v_pk_fma_f32 v[34:35], v[102:103], v[160:161], v[34:35]
	v_pk_fma_f32 v[22:23], v[84:85], v[32:33], v[22:23]
	v_add_f32_e32 v185, v38, v39
	v_add_f32_e32 v187, v36, v37
	v_add_f32_e32 v189, v34, v35
	ds_read2st64_b32 v[34:35], v163 offset0:224 offset1:228
	ds_read2st64_b32 v[36:37], v163 offset0:232 offset1:236
	ds_read2st64_b32 v[38:39], v163 offset0:240 offset1:244
	v_pk_fma_f32 v[22:23], v[88:89], v[40:41], v[22:23]
	v_mov_b32_e32 v172, v104
	v_pk_fma_f32 v[22:23], v[92:93], v[156:157], v[22:23]
	s_waitcnt lgkmcnt(2)
	v_mul_f32_e32 v105, v103, v34
	v_pk_fma_f32 v[22:23], v[96:97], v[158:159], v[22:23]
	v_pk_fma_f32 v[172:173], v[46:47], v[20:21], v[172:173]
	v_pk_fma_f32 v[22:23], v[100:101], v[160:161], v[22:23]
	v_pk_fma_f32 v[172:173], v[50:51], v[18:19], v[172:173]
	v_add_f32_e32 v190, v22, v23
	v_mul_f32_e32 v23, v44, v21
	v_pk_fma_f32 v[20:21], v[44:45], v[20:21], v[104:105]
	v_pk_fma_f32 v[172:173], v[54:55], v[10:11], v[172:173]
	v_pk_fma_f32 v[20:21], v[48:49], v[18:19], v[20:21]
	v_pk_fma_f32 v[172:173], v[58:59], v[12:13], v[172:173]
	v_pk_fma_f32 v[20:21], v[52:53], v[10:11], v[20:21]
	v_pk_fma_f32 v[172:173], v[62:63], v[14:15], v[172:173]
	v_pk_fma_f32 v[20:21], v[56:57], v[12:13], v[20:21]
	v_pk_fma_f32 v[172:173], v[66:67], v[16:17], v[172:173]
	v_pk_fma_f32 v[20:21], v[60:61], v[14:15], v[20:21]
	v_pk_fma_f32 v[172:173], v[70:71], v[26:27], v[172:173]
	v_pk_fma_f32 v[20:21], v[64:65], v[16:17], v[20:21]
	v_pk_fma_f32 v[172:173], v[74:75], v[28:29], v[172:173]
	v_pk_fma_f32 v[20:21], v[68:69], v[26:27], v[20:21]
	v_pk_fma_f32 v[172:173], v[78:79], v[30:31], v[172:173]
	v_pk_fma_f32 v[20:21], v[72:73], v[28:29], v[20:21]
	v_pk_fma_f32 v[172:173], v[82:83], v[32:33], v[172:173]
	v_pk_fma_f32 v[20:21], v[76:77], v[30:31], v[20:21]
	v_pk_fma_f32 v[172:173], v[86:87], v[40:41], v[172:173]
	v_pk_fma_f32 v[20:21], v[80:81], v[32:33], v[20:21]
	v_pk_fma_f32 v[172:173], v[90:91], v[156:157], v[172:173]
	v_pk_fma_f32 v[20:21], v[84:85], v[40:41], v[20:21]
	v_pk_fma_f32 v[172:173], v[94:95], v[158:159], v[172:173]
	v_pk_fma_f32 v[20:21], v[88:89], v[156:157], v[20:21]
	v_pk_fma_f32 v[172:173], v[98:99], v[160:161], v[172:173]
	v_pk_fma_f32 v[20:21], v[92:93], v[158:159], v[20:21]
	v_pk_fma_f32 v[172:173], v[102:103], v[24:25], v[172:173]
	v_pk_fma_f32 v[20:21], v[96:97], v[160:161], v[20:21]
	v_mov_b32_e32 v22, v104
	v_pk_fma_f32 v[20:21], v[100:101], v[24:25], v[20:21]
	s_waitcnt lgkmcnt(1)
	v_mul_f32_e32 v105, v103, v36
	v_add_f32_e32 v172, v172, v173
	v_pk_fma_f32 v[22:23], v[46:47], v[18:19], v[22:23]
	v_add_f32_e32 v173, v20, v21
	v_mul_f32_e32 v21, v44, v19
	v_pk_fma_f32 v[18:19], v[44:45], v[18:19], v[104:105]
	v_pk_fma_f32 v[22:23], v[50:51], v[10:11], v[22:23]
	v_pk_fma_f32 v[18:19], v[48:49], v[10:11], v[18:19]
	v_pk_fma_f32 v[22:23], v[54:55], v[12:13], v[22:23]
	v_pk_fma_f32 v[18:19], v[52:53], v[12:13], v[18:19]
	v_pk_fma_f32 v[22:23], v[58:59], v[14:15], v[22:23]
	v_pk_fma_f32 v[18:19], v[56:57], v[14:15], v[18:19]
	v_pk_fma_f32 v[22:23], v[62:63], v[16:17], v[22:23]
	v_pk_fma_f32 v[18:19], v[60:61], v[16:17], v[18:19]
	v_pk_fma_f32 v[22:23], v[66:67], v[26:27], v[22:23]
	v_pk_fma_f32 v[18:19], v[64:65], v[26:27], v[18:19]
	v_pk_fma_f32 v[22:23], v[70:71], v[28:29], v[22:23]
	v_pk_fma_f32 v[18:19], v[68:69], v[28:29], v[18:19]
	v_pk_fma_f32 v[22:23], v[74:75], v[30:31], v[22:23]
	v_pk_fma_f32 v[18:19], v[72:73], v[30:31], v[18:19]
	v_pk_fma_f32 v[22:23], v[78:79], v[32:33], v[22:23]
	v_pk_fma_f32 v[18:19], v[76:77], v[32:33], v[18:19]
	v_pk_fma_f32 v[22:23], v[82:83], v[40:41], v[22:23]
	v_pk_fma_f32 v[18:19], v[80:81], v[40:41], v[18:19]
	v_pk_fma_f32 v[22:23], v[86:87], v[156:157], v[22:23]
	v_pk_fma_f32 v[18:19], v[84:85], v[156:157], v[18:19]
	v_pk_fma_f32 v[22:23], v[90:91], v[158:159], v[22:23]
	v_pk_fma_f32 v[18:19], v[88:89], v[158:159], v[18:19]
	v_pk_fma_f32 v[22:23], v[94:95], v[160:161], v[22:23]
	v_pk_fma_f32 v[18:19], v[92:93], v[160:161], v[18:19]
	v_pk_fma_f32 v[22:23], v[98:99], v[24:25], v[22:23]
	v_pk_fma_f32 v[18:19], v[96:97], v[24:25], v[18:19]
	v_pk_fma_f32 v[22:23], v[102:103], v[34:35], v[22:23]
	v_pk_fma_f32 v[18:19], v[100:101], v[34:35], v[18:19]
	v_add_f32_e32 v22, v22, v23
	v_mov_b32_e32 v20, v104
	v_add_f32_e32 v23, v18, v19
	s_waitcnt lgkmcnt(0)
	v_mul_f32_e32 v105, v103, v38
	v_mul_f32_e32 v19, v44, v11
	v_mov_b32_e32 v18, v104
	v_pk_fma_f32 v[20:21], v[46:47], v[10:11], v[20:21]
	v_pk_fma_f32 v[10:11], v[44:45], v[10:11], v[104:105]
	v_pk_fma_f32 v[18:19], v[46:47], v[12:13], v[18:19]
	v_pk_fma_f32 v[20:21], v[50:51], v[12:13], v[20:21]
	v_pk_fma_f32 v[10:11], v[48:49], v[12:13], v[10:11]
	v_pk_fma_f32 v[12:13], v[50:51], v[14:15], v[18:19]
	v_pk_fma_f32 v[20:21], v[54:55], v[14:15], v[20:21]
	v_pk_fma_f32 v[10:11], v[52:53], v[14:15], v[10:11]
	v_pk_fma_f32 v[12:13], v[54:55], v[16:17], v[12:13]
	v_pk_fma_f32 v[20:21], v[58:59], v[16:17], v[20:21]
	v_pk_fma_f32 v[10:11], v[56:57], v[16:17], v[10:11]
	v_pk_fma_f32 v[12:13], v[58:59], v[26:27], v[12:13]
	v_pk_fma_f32 v[20:21], v[62:63], v[26:27], v[20:21]
	v_pk_fma_f32 v[10:11], v[60:61], v[26:27], v[10:11]
	v_pk_fma_f32 v[12:13], v[62:63], v[28:29], v[12:13]
	v_pk_fma_f32 v[20:21], v[66:67], v[28:29], v[20:21]
	v_pk_fma_f32 v[10:11], v[64:65], v[28:29], v[10:11]
	v_pk_fma_f32 v[12:13], v[66:67], v[30:31], v[12:13]
	v_pk_fma_f32 v[20:21], v[70:71], v[30:31], v[20:21]
	v_pk_fma_f32 v[10:11], v[68:69], v[30:31], v[10:11]
	v_pk_fma_f32 v[12:13], v[70:71], v[32:33], v[12:13]
	v_pk_fma_f32 v[20:21], v[74:75], v[32:33], v[20:21]
	v_pk_fma_f32 v[10:11], v[72:73], v[32:33], v[10:11]
	v_pk_fma_f32 v[12:13], v[74:75], v[40:41], v[12:13]
	v_pk_fma_f32 v[20:21], v[78:79], v[40:41], v[20:21]
	v_pk_fma_f32 v[10:11], v[76:77], v[40:41], v[10:11]
	v_pk_fma_f32 v[12:13], v[78:79], v[156:157], v[12:13]
	v_pk_fma_f32 v[20:21], v[82:83], v[156:157], v[20:21]
	v_pk_fma_f32 v[10:11], v[80:81], v[156:157], v[10:11]
	v_pk_fma_f32 v[12:13], v[82:83], v[158:159], v[12:13]
	v_pk_fma_f32 v[20:21], v[86:87], v[158:159], v[20:21]
	v_pk_fma_f32 v[10:11], v[84:85], v[158:159], v[10:11]
	v_pk_fma_f32 v[12:13], v[86:87], v[160:161], v[12:13]
	v_pk_fma_f32 v[20:21], v[90:91], v[160:161], v[20:21]
	v_pk_fma_f32 v[10:11], v[88:89], v[160:161], v[10:11]
	v_pk_fma_f32 v[12:13], v[90:91], v[24:25], v[12:13]
	v_pk_fma_f32 v[20:21], v[94:95], v[24:25], v[20:21]
	v_pk_fma_f32 v[10:11], v[92:93], v[24:25], v[10:11]
	v_pk_fma_f32 v[12:13], v[94:95], v[34:35], v[12:13]
	s_lshl_b32 s6, s28, 10
	v_pk_fma_f32 v[20:21], v[98:99], v[34:35], v[20:21]
	v_pk_fma_f32 v[10:11], v[96:97], v[34:35], v[10:11]
	v_pk_fma_f32 v[12:13], v[98:99], v[36:37], v[12:13]
	s_add_i32 s6, s6, 0
	v_pk_fma_f32 v[20:21], v[102:103], v[36:37], v[20:21]
	v_pk_fma_f32 v[10:11], v[100:101], v[36:37], v[10:11]
	v_pk_fma_f32 v[12:13], v[102:103], v[38:39], v[12:13]
	v_add_u32_e32 v105, s6, v162
	v_add_f32_e32 v20, v20, v21
	v_add_f32_e32 v10, v10, v11
	v_add_f32_e32 v11, v12, v13
	s_barrier
	ds_write2st64_b32 v163, v164, v165 offset1:4
	ds_write2st64_b32 v163, v166, v167 offset0:8 offset1:12
	ds_write2st64_b32 v163, v168, v169 offset0:16 offset1:20
	ds_write2st64_b32 v163, v170, v171 offset0:24 offset1:28
	ds_write2st64_b32 v163, v174, v175 offset0:32 offset1:36
	ds_write2st64_b32 v163, v176, v177 offset0:40 offset1:44
	ds_write2st64_b32 v163, v178, v179 offset0:48 offset1:52
	ds_write2st64_b32 v163, v180, v181 offset0:56 offset1:60
	ds_write2st64_b32 v163, v182, v183 offset0:64 offset1:68
	ds_write2st64_b32 v163, v184, v185 offset0:72 offset1:76
	ds_write2st64_b32 v163, v186, v187 offset0:80 offset1:84
	ds_write2st64_b32 v163, v188, v189 offset0:88 offset1:92
	ds_write2st64_b32 v163, v190, v172 offset0:96 offset1:100
	ds_write2st64_b32 v163, v173, v22 offset0:104 offset1:108
	ds_write2st64_b32 v163, v23, v20 offset0:112 offset1:116
	ds_write2st64_b32 v163, v10, v11 offset0:120 offset1:124
	s_waitcnt lgkmcnt(0)
	s_barrier
	ds_read_b128 v[38:41], v105
	ds_read_b128 v[34:37], v105 offset:8192
	ds_read_b128 v[30:33], v105 offset:16384
	ds_read_b128 v[26:29], v105 offset:24576
	ds_read_b128 v[22:25], v105 offset:32768
	ds_read_b128 v[18:21], v105 offset:40960
	s_waitcnt lgkmcnt(5)
	v_mov_b32_e32 v10, v39
	v_mov_b32_e32 v11, v40
	v_mov_b32_e32 v12, v38
	v_mov_b32_e32 v13, v41
	v_pk_add_f32 v[10:11], v[10:11], v[12:13]
	s_waitcnt lgkmcnt(4)
	v_mov_b32_e32 v12, v34
	v_add_f32_e32 v160, v10, v11
	v_mov_b32_e32 v10, v35
	v_mov_b32_e32 v11, v36
	v_mov_b32_e32 v13, v37
	v_pk_add_f32 v[10:11], v[10:11], v[12:13]
	s_waitcnt lgkmcnt(3)
	v_mov_b32_e32 v12, v30
	v_add_f32_e32 v161, v10, v11
	v_mov_b32_e32 v10, v31
	v_mov_b32_e32 v11, v32
	v_mov_b32_e32 v13, v33
	v_pk_add_f32 v[10:11], v[10:11], v[12:13]
	s_waitcnt lgkmcnt(2)
	v_mov_b32_e32 v12, v26
	v_add_f32_e32 v162, v10, v11
	v_mov_b32_e32 v10, v27
	v_mov_b32_e32 v11, v28
	v_mov_b32_e32 v13, v29
	v_pk_add_f32 v[10:11], v[10:11], v[12:13]
	s_waitcnt lgkmcnt(1)
	v_mov_b32_e32 v12, v22
	v_add_f32_e32 v163, v10, v11
	v_mov_b32_e32 v10, v23
	v_mov_b32_e32 v11, v24
	v_mov_b32_e32 v13, v25
	v_pk_add_f32 v[10:11], v[10:11], v[12:13]
	s_waitcnt lgkmcnt(0)
	v_mov_b32_e32 v12, v18
	v_add_f32_e32 v164, v10, v11
	v_mov_b32_e32 v10, v19
	v_mov_b32_e32 v11, v20
	ds_read_b128 v[14:17], v105 offset:49152
	v_mov_b32_e32 v13, v21
	v_pk_add_f32 v[10:11], v[10:11], v[12:13]
	s_add_i32 s28, s52, s28
	v_add_f32_e32 v165, v10, v11
	ds_read_b128 v[10:13], v105 offset:57344
	s_waitcnt lgkmcnt(1)
	v_mov_b32_e32 v156, v15
	v_mov_b32_e32 v157, v16
	v_mov_b32_e32 v158, v14
	v_mov_b32_e32 v159, v17
	v_pk_add_f32 v[156:157], v[156:157], v[158:159]
	s_waitcnt lgkmcnt(0)
	v_mov_b32_e32 v158, v10
	v_add_f32_e32 v105, v156, v157
	v_mov_b32_e32 v156, v11
	v_mov_b32_e32 v157, v12
	v_mov_b32_e32 v159, v13
	v_pk_add_f32 v[156:157], v[156:157], v[158:159]
	v_add_f32_dpp v158, v161, v161 quad_perm:[1,0,3,2] row_mask:0xf bank_mask:0xf bound_ctrl:1
	v_add_f32_e32 v156, v156, v157
	v_add_f32_dpp v157, v160, v160 quad_perm:[1,0,3,2] row_mask:0xf bank_mask:0xf bound_ctrl:1
	v_add_f32_dpp v160, v163, v163 quad_perm:[1,0,3,2] row_mask:0xf bank_mask:0xf bound_ctrl:1
	v_add_f32_dpp v158, v158, v158 quad_perm:[2,3,0,1] row_mask:0xf bank_mask:0xf bound_ctrl:1
	v_add_f32_dpp v157, v157, v157 quad_perm:[2,3,0,1] row_mask:0xf bank_mask:0xf bound_ctrl:1
	v_mov_b32_e32 v163, v131
	v_add_f32_dpp v159, v162, v162 quad_perm:[1,0,3,2] row_mask:0xf bank_mask:0xf bound_ctrl:1
	v_add_f32_dpp v157, v157, v157 row_half_mirror row_mask:0xf bank_mask:0xf bound_ctrl:1
	v_add_f32_dpp v158, v158, v158 row_half_mirror row_mask:0xf bank_mask:0xf bound_ctrl:1
	v_add_f32_dpp v159, v159, v159 quad_perm:[2,3,0,1] row_mask:0xf bank_mask:0xf bound_ctrl:1
	v_add_f32_dpp v157, v157, v157 row_mirror row_mask:0xf bank_mask:0xf bound_ctrl:1
	v_add_f32_dpp v158, v158, v158 row_mirror row_mask:0xf bank_mask:0xf bound_ctrl:1
	v_add_f32_dpp v159, v159, v159 row_half_mirror row_mask:0xf bank_mask:0xf bound_ctrl:1
	v_mov_b32_dpp v163, v157 row_bcast:15 row_mask:0xa bank_mask:0xf
	v_add_f32_e32 v157, v157, v163
	v_mov_b32_e32 v163, v131
	v_add_f32_dpp v160, v160, v160 quad_perm:[2,3,0,1] row_mask:0xf bank_mask:0xf bound_ctrl:1
	v_add_f32_dpp v159, v159, v159 row_mirror row_mask:0xf bank_mask:0xf bound_ctrl:1
	v_mov_b32_dpp v163, v158 row_bcast:15 row_mask:0xa bank_mask:0xf
	v_add_f32_e32 v158, v158, v163
	v_mov_b32_e32 v163, v131
	v_add_f32_dpp v161, v164, v164 quad_perm:[1,0,3,2] row_mask:0xf bank_mask:0xf bound_ctrl:1
	v_add_f32_dpp v160, v160, v160 row_half_mirror row_mask:0xf bank_mask:0xf bound_ctrl:1
	v_mov_b32_dpp v163, v159 row_bcast:15 row_mask:0xa bank_mask:0xf
	v_add_f32_dpp v161, v161, v161 quad_perm:[2,3,0,1] row_mask:0xf bank_mask:0xf bound_ctrl:1
	v_add_f32_dpp v160, v160, v160 row_mirror row_mask:0xf bank_mask:0xf bound_ctrl:1
	v_add_f32_e32 v159, v159, v163
	v_mov_b32_e32 v163, v131
	v_add_f32_dpp v162, v165, v165 quad_perm:[1,0,3,2] row_mask:0xf bank_mask:0xf bound_ctrl:1
	v_add_f32_dpp v161, v161, v161 row_half_mirror row_mask:0xf bank_mask:0xf bound_ctrl:1
	v_mov_b32_dpp v163, v160 row_bcast:15 row_mask:0xa bank_mask:0xf
	v_add_f32_dpp v162, v162, v162 quad_perm:[2,3,0,1] row_mask:0xf bank_mask:0xf bound_ctrl:1
	v_add_f32_dpp v161, v161, v161 row_mirror row_mask:0xf bank_mask:0xf bound_ctrl:1
	v_add_f32_e32 v160, v160, v163
	v_mov_b32_e32 v163, v131
	v_add_f32_dpp v105, v105, v105 quad_perm:[1,0,3,2] row_mask:0xf bank_mask:0xf bound_ctrl:1
	v_add_f32_dpp v162, v162, v162 row_half_mirror row_mask:0xf bank_mask:0xf bound_ctrl:1
	v_mov_b32_dpp v163, v161 row_bcast:15 row_mask:0xa bank_mask:0xf
	v_add_f32_dpp v105, v105, v105 quad_perm:[2,3,0,1] row_mask:0xf bank_mask:0xf bound_ctrl:1
	v_add_f32_dpp v162, v162, v162 row_mirror row_mask:0xf bank_mask:0xf bound_ctrl:1
	v_add_f32_e32 v161, v161, v163
	v_mov_b32_e32 v163, v131
	v_add_f32_dpp v156, v156, v156 quad_perm:[1,0,3,2] row_mask:0xf bank_mask:0xf bound_ctrl:1
	v_add_f32_dpp v105, v105, v105 row_half_mirror row_mask:0xf bank_mask:0xf bound_ctrl:1
	v_mov_b32_dpp v163, v162 row_bcast:15 row_mask:0xa bank_mask:0xf
	v_add_f32_dpp v156, v156, v156 quad_perm:[2,3,0,1] row_mask:0xf bank_mask:0xf bound_ctrl:1
	v_add_f32_dpp v105, v105, v105 row_mirror row_mask:0xf bank_mask:0xf bound_ctrl:1
	v_add_f32_e32 v162, v162, v163
	v_mov_b32_e32 v163, v131
	v_add_f32_dpp v156, v156, v156 row_half_mirror row_mask:0xf bank_mask:0xf bound_ctrl:1
	s_nop 0
	v_mov_b32_dpp v163, v105 row_bcast:15 row_mask:0xa bank_mask:0xf
	v_add_f32_dpp v156, v156, v156 row_mirror row_mask:0xf bank_mask:0xf bound_ctrl:1
	v_add_f32_e32 v105, v105, v163
	v_mov_b32_e32 v163, v131
	s_nop 1
	v_mov_b32_dpp v163, v156 row_bcast:15 row_mask:0xa bank_mask:0xf
	v_add_f32_e32 v156, v156, v163
	v_mov_b32_e32 v163, v131
	s_nop 1
	v_mov_b32_dpp v163, v157 row_bcast:31 row_mask:0xc bank_mask:0xf
	v_add_f32_e32 v157, v157, v163
	v_mov_b32_e32 v163, v131
	v_readlane_b32 s6, v157, 63
	s_nop 0
	v_mov_b32_dpp v163, v158 row_bcast:31 row_mask:0xc bank_mask:0xf
	v_add_f32_e32 v158, v158, v163
	v_mov_b32_e32 v163, v131
	v_fma_f32 v39, s6, v239, v39
	v_fma_f32 v38, s6, v239, v38
	v_mov_b32_dpp v163, v159 row_bcast:31 row_mask:0xc bank_mask:0xf
	v_add_f32_e32 v159, v159, v163
	v_mov_b32_e32 v163, v131
	v_fma_f32 v41, s6, v239, v41
	v_fmac_f32_e32 v40, s6, v239
	v_mov_b32_dpp v163, v160 row_bcast:31 row_mask:0xc bank_mask:0xf
	v_add_f32_e32 v160, v160, v163
	v_mov_b32_e32 v163, v131
	v_readlane_b32 s7, v158, 63
	v_readlane_b32 s8, v159, 63
	v_mov_b32_dpp v163, v161 row_bcast:31 row_mask:0xc bank_mask:0xf
	v_add_f32_e32 v161, v161, v163
	v_mov_b32_e32 v163, v131
	v_pk_mul_f32 v[158:159], v[38:39], v[38:39]
	v_readlane_b32 s9, v160, 63
	v_mov_b32_dpp v163, v162 row_bcast:31 row_mask:0xc bank_mask:0xf
	v_add_f32_e32 v162, v162, v163
	v_mov_b32_e32 v163, v131
	v_readlane_b32 s10, v161, 63
	v_fma_f32 v35, s7, v239, v35
	v_mov_b32_dpp v163, v105 row_bcast:31 row_mask:0xc bank_mask:0xf
	v_add_f32_e32 v105, v105, v163
	v_mov_b32_e32 v163, v131
	v_fma_f32 v34, s7, v239, v34
	v_fma_f32 v37, s7, v239, v37
	v_mov_b32_dpp v163, v156 row_bcast:31 row_mask:0xc bank_mask:0xf
	v_add_f32_e32 v156, v156, v163
	v_fmac_f32_e32 v36, s7, v239
	v_readlane_b32 s55, v156, 63
	v_pk_mul_f32 v[156:157], v[40:41], v[40:41]
	v_readlane_b32 s29, v105, 63
	v_pk_mov_b32 v[160:161], v[158:159], v[156:157] op_sel:[1,0]
	v_mov_b32_e32 v159, v157
	v_pk_add_f32 v[156:157], v[160:161], v[158:159]
	v_pk_mul_f32 v[158:159], v[34:35], v[34:35]
	v_add_f32_e32 v105, v156, v157
	v_pk_mul_f32 v[156:157], v[36:37], v[36:37]
	v_fma_f32 v31, s8, v239, v31
	v_pk_mov_b32 v[160:161], v[158:159], v[156:157] op_sel:[1,0]
	v_mov_b32_e32 v159, v157
	v_pk_add_f32 v[156:157], v[160:161], v[158:159]
	v_fma_f32 v30, s8, v239, v30
	v_fma_f32 v33, s8, v239, v33
	v_fmac_f32_e32 v32, s8, v239
	v_readlane_b32 s11, v162, 63
	v_add_f32_e32 v162, v156, v157
	v_pk_mul_f32 v[156:157], v[32:33], v[32:33]
	v_pk_mul_f32 v[158:159], v[30:31], v[30:31]
	v_fma_f32 v27, s9, v239, v27
	v_pk_mov_b32 v[160:161], v[158:159], v[156:157] op_sel:[1,0]
	v_mov_b32_e32 v159, v157
	v_pk_add_f32 v[156:157], v[160:161], v[158:159]
	v_fma_f32 v26, s9, v239, v26
	v_fma_f32 v29, s9, v239, v29
	v_fmac_f32_e32 v28, s9, v239
	v_add_f32_e32 v163, v156, v157
	v_pk_mul_f32 v[156:157], v[28:29], v[28:29]
	v_pk_mul_f32 v[158:159], v[26:27], v[26:27]
	v_fma_f32 v23, s10, v239, v23
	v_pk_mov_b32 v[160:161], v[158:159], v[156:157] op_sel:[1,0]
	v_mov_b32_e32 v159, v157
	v_pk_add_f32 v[156:157], v[160:161], v[158:159]
	v_fma_f32 v22, s10, v239, v22
	v_fma_f32 v25, s10, v239, v25
	v_fmac_f32_e32 v24, s10, v239
	v_add_f32_e32 v164, v156, v157
	v_pk_mul_f32 v[156:157], v[24:25], v[24:25]
	v_pk_mul_f32 v[158:159], v[22:23], v[22:23]
	v_fma_f32 v19, s11, v239, v19
	v_pk_mov_b32 v[160:161], v[158:159], v[156:157] op_sel:[1,0]
	v_mov_b32_e32 v159, v157
	v_pk_add_f32 v[156:157], v[160:161], v[158:159]
	v_fma_f32 v18, s11, v239, v18
	v_fma_f32 v21, s11, v239, v21
	v_fmac_f32_e32 v20, s11, v239
	v_add_f32_e32 v165, v156, v157
	v_pk_mul_f32 v[156:157], v[20:21], v[20:21]
	v_pk_mul_f32 v[158:159], v[18:19], v[18:19]
	v_fma_f32 v15, s29, v239, v15
	v_pk_mov_b32 v[160:161], v[158:159], v[156:157] op_sel:[1,0]
	v_mov_b32_e32 v159, v157
	v_pk_add_f32 v[156:157], v[160:161], v[158:159]
	v_fma_f32 v14, s29, v239, v14
	v_fma_f32 v17, s29, v239, v17
	v_fmac_f32_e32 v16, s29, v239
	v_add_f32_e32 v166, v156, v157
	v_pk_mul_f32 v[156:157], v[16:17], v[16:17]
	v_pk_mul_f32 v[158:159], v[14:15], v[14:15]
	v_fma_f32 v11, s55, v239, v11
	v_pk_mov_b32 v[160:161], v[158:159], v[156:157] op_sel:[1,0]
	v_mov_b32_e32 v159, v157
	v_pk_add_f32 v[156:157], v[160:161], v[158:159]
	v_fma_f32 v10, s55, v239, v10
	v_fma_f32 v13, s55, v239, v13
	v_fmac_f32_e32 v12, s55, v239
	v_add_f32_e32 v167, v156, v157
	v_pk_mul_f32 v[156:157], v[12:13], v[12:13]
	v_pk_mul_f32 v[158:159], v[10:11], v[10:11]
	v_add_f32_dpp v105, v105, v105 quad_perm:[1,0,3,2] row_mask:0xf bank_mask:0xf bound_ctrl:1
	v_pk_mov_b32 v[160:161], v[158:159], v[156:157] op_sel:[1,0]
	v_mov_b32_e32 v159, v157
	v_pk_add_f32 v[156:157], v[160:161], v[158:159]
	v_add_f32_dpp v105, v105, v105 quad_perm:[2,3,0,1] row_mask:0xf bank_mask:0xf bound_ctrl:1
	v_add_f32_e32 v156, v156, v157
	v_add_f32_dpp v157, v162, v162 quad_perm:[1,0,3,2] row_mask:0xf bank_mask:0xf bound_ctrl:1
	v_add_f32_dpp v105, v105, v105 row_half_mirror row_mask:0xf bank_mask:0xf bound_ctrl:1
	v_add_f32_dpp v158, v163, v163 quad_perm:[1,0,3,2] row_mask:0xf bank_mask:0xf bound_ctrl:1
	v_add_f32_dpp v157, v157, v157 quad_perm:[2,3,0,1] row_mask:0xf bank_mask:0xf bound_ctrl:1
	v_add_f32_dpp v105, v105, v105 row_mirror row_mask:0xf bank_mask:0xf bound_ctrl:1
	v_mov_b32_e32 v163, v131
	v_add_f32_dpp v157, v157, v157 row_half_mirror row_mask:0xf bank_mask:0xf bound_ctrl:1
	v_add_f32_dpp v158, v158, v158 quad_perm:[2,3,0,1] row_mask:0xf bank_mask:0xf bound_ctrl:1
	v_mov_b32_dpp v163, v105 row_bcast:15 row_mask:0xa bank_mask:0xf
	v_add_f32_dpp v157, v157, v157 row_mirror row_mask:0xf bank_mask:0xf bound_ctrl:1
	v_add_f32_e32 v105, v105, v163
	v_mov_b32_e32 v163, v131
	v_add_f32_dpp v159, v164, v164 quad_perm:[1,0,3,2] row_mask:0xf bank_mask:0xf bound_ctrl:1
	v_add_f32_dpp v158, v158, v158 row_half_mirror row_mask:0xf bank_mask:0xf bound_ctrl:1
	v_mov_b32_dpp v163, v157 row_bcast:15 row_mask:0xa bank_mask:0xf
	v_add_f32_dpp v159, v159, v159 quad_perm:[2,3,0,1] row_mask:0xf bank_mask:0xf bound_ctrl:1
	v_add_f32_dpp v158, v158, v158 row_mirror row_mask:0xf bank_mask:0xf bound_ctrl:1
	v_add_f32_e32 v157, v157, v163
	v_mov_b32_e32 v163, v131
	v_add_f32_dpp v160, v165, v165 quad_perm:[1,0,3,2] row_mask:0xf bank_mask:0xf bound_ctrl:1
	v_add_f32_dpp v159, v159, v159 row_half_mirror row_mask:0xf bank_mask:0xf bound_ctrl:1
	v_mov_b32_dpp v163, v158 row_bcast:15 row_mask:0xa bank_mask:0xf
	v_add_f32_dpp v160, v160, v160 quad_perm:[2,3,0,1] row_mask:0xf bank_mask:0xf bound_ctrl:1
	v_add_f32_dpp v159, v159, v159 row_mirror row_mask:0xf bank_mask:0xf bound_ctrl:1
	v_add_f32_e32 v158, v158, v163
	v_mov_b32_e32 v163, v131
	v_add_f32_dpp v161, v166, v166 quad_perm:[1,0,3,2] row_mask:0xf bank_mask:0xf bound_ctrl:1
	v_add_f32_dpp v160, v160, v160 row_half_mirror row_mask:0xf bank_mask:0xf bound_ctrl:1
	v_mov_b32_dpp v163, v159 row_bcast:15 row_mask:0xa bank_mask:0xf
	v_add_f32_dpp v161, v161, v161 quad_perm:[2,3,0,1] row_mask:0xf bank_mask:0xf bound_ctrl:1
	v_add_f32_dpp v160, v160, v160 row_mirror row_mask:0xf bank_mask:0xf bound_ctrl:1
	v_add_f32_e32 v159, v159, v163
	v_mov_b32_e32 v163, v131
	v_add_f32_dpp v162, v167, v167 quad_perm:[1,0,3,2] row_mask:0xf bank_mask:0xf bound_ctrl:1
	v_add_f32_dpp v161, v161, v161 row_half_mirror row_mask:0xf bank_mask:0xf bound_ctrl:1
	v_mov_b32_dpp v163, v160 row_bcast:15 row_mask:0xa bank_mask:0xf
	v_add_f32_dpp v162, v162, v162 quad_perm:[2,3,0,1] row_mask:0xf bank_mask:0xf bound_ctrl:1
	v_add_f32_dpp v161, v161, v161 row_mirror row_mask:0xf bank_mask:0xf bound_ctrl:1
	v_add_f32_e32 v160, v160, v163
	v_mov_b32_e32 v163, v131
	v_add_f32_dpp v156, v156, v156 quad_perm:[1,0,3,2] row_mask:0xf bank_mask:0xf bound_ctrl:1
	v_add_f32_dpp v162, v162, v162 row_half_mirror row_mask:0xf bank_mask:0xf bound_ctrl:1
	v_mov_b32_dpp v163, v161 row_bcast:15 row_mask:0xa bank_mask:0xf
	v_add_f32_dpp v156, v156, v156 quad_perm:[2,3,0,1] row_mask:0xf bank_mask:0xf bound_ctrl:1
	v_add_f32_dpp v162, v162, v162 row_mirror row_mask:0xf bank_mask:0xf bound_ctrl:1
	v_add_f32_e32 v161, v161, v163
	v_mov_b32_e32 v163, v131
	v_add_f32_dpp v156, v156, v156 row_half_mirror row_mask:0xf bank_mask:0xf bound_ctrl:1
	s_add_i32 s8, s28, -8
	v_mov_b32_dpp v163, v162 row_bcast:15 row_mask:0xa bank_mask:0xf
	v_add_f32_dpp v156, v156, v156 row_mirror row_mask:0xf bank_mask:0xf bound_ctrl:1
	v_add_f32_e32 v162, v162, v163
	v_mov_b32_e32 v163, v131
	s_ashr_i32 s9, s8, 31
	s_lshl_b64 s[8:9], s[8:9], 11
	v_mov_b32_dpp v163, v156 row_bcast:15 row_mask:0xa bank_mask:0xf
	v_add_f32_e32 v156, v156, v163
	v_mov_b32_e32 v163, v131
	s_add_u32 s8, s76, s8
	s_addc_u32 s9, s77, s9
	v_mov_b32_dpp v163, v105 row_bcast:31 row_mask:0xc bank_mask:0xf
	v_add_f32_e32 v105, v105, v163
	v_mov_b32_e32 v163, v131
	v_readlane_b32 s6, v105, 63
	s_ashr_i32 s29, s28, 31
	v_mov_b32_dpp v163, v157 row_bcast:31 row_mask:0xc bank_mask:0xf
	v_add_f32_e32 v157, v157, v163
	v_mov_b32_e32 v163, v131
	v_fma_f32 v105, s6, v235, v225
	v_readlane_b32 s10, v157, 63
	v_mov_b32_dpp v163, v158 row_bcast:31 row_mask:0xc bank_mask:0xf
	v_add_f32_e32 v158, v158, v163
	v_mov_b32_e32 v163, v131
	v_readlane_b32 s11, v158, 63
	s_nop 0
	v_mov_b32_dpp v163, v159 row_bcast:31 row_mask:0xc bank_mask:0xf
	v_add_f32_e32 v159, v159, v163
	v_mov_b32_e32 v163, v131
	v_readlane_b32 s57, v159, 63
	s_nop 0
	v_mov_b32_dpp v163, v160 row_bcast:31 row_mask:0xc bank_mask:0xf
	v_add_f32_e32 v160, v160, v163
	v_mov_b32_e32 v163, v131
	v_readlane_b32 s56, v160, 63
	s_nop 0
	v_mov_b32_dpp v163, v161 row_bcast:31 row_mask:0xc bank_mask:0xf
	v_add_f32_e32 v161, v161, v163
	v_mov_b32_e32 v163, v131
	v_readlane_b32 s55, v161, 63
	s_nop 0
	v_mov_b32_dpp v163, v162 row_bcast:31 row_mask:0xc bank_mask:0xf
	v_add_f32_e32 v162, v162, v163
	v_mov_b32_e32 v163, v131
	v_readlane_b32 s7, v162, 63
	s_nop 0
	v_mov_b32_dpp v163, v156 row_bcast:31 row_mask:0xc bank_mask:0xf
	v_add_f32_e32 v163, v156, v163
	v_rsq_f32_e32 v156, v105
	v_readlane_b32 s6, v163, 63
	v_pk_mul_f32 v[38:39], v[38:39], v[156:157] op_sel_hi:[1,0]
	s_nop 0
	v_pk_fma_f32 v[38:39], v[2:3], v[38:39], v[6:7]
	v_pk_mul_f32 v[40:41], v[40:41], v[156:157] op_sel_hi:[1,0]
	v_mul_f32_e32 v105, 0xbfb8aa3b, v38
	v_exp_f32_e32 v105, v105
	v_mul_f32_e32 v156, 0xbfb8aa3b, v39
	v_exp_f32_e32 v157, v156
	v_pk_fma_f32 v[40:41], v[4:5], v[40:41], v[8:9]
	v_add_f32_e32 v105, 1.0, v105
	v_rcp_f32_e32 v156, v105
	v_add_f32_e32 v105, 1.0, v157
	v_mul_f32_e32 v157, 0xbfb8aa3b, v40
	v_exp_f32_e32 v158, v157
	v_mul_f32_e32 v157, 0xbfb8aa3b, v41
	v_exp_f32_e32 v159, v157
	v_rcp_f32_e32 v157, v105
	v_add_f32_e32 v105, 1.0, v158
	v_rcp_f32_e32 v158, v105
	v_add_f32_e32 v105, 1.0, v159
	v_rcp_f32_e32 v159, v105
	v_pk_mul_f32 v[38:39], v[38:39], v[156:157]
	v_lshlrev_b32_e32 v105, 3, v130
	v_cvt_pk_bf16_f32 v38, v38, v39
	v_pk_mul_f32 v[40:41], v[40:41], v[158:159]
	v_cvt_pk_bf16_f32 v39, v40, v41
	v_fma_f32 v40, s10, v235, v225
	v_rsq_f32_e32 v40, v40
	global_store_dwordx2 v105, v[38:39], s[8:9] offset:512
	s_lshl_b64 s[8:9], s[28:29], 11
	s_add_u32 s8, s76, s8
	v_pk_mul_f32 v[36:37], v[36:37], v[40:41] op_sel_hi:[1,0]
	v_pk_mul_f32 v[34:35], v[34:35], v[40:41] op_sel_hi:[1,0]
	v_pk_fma_f32 v[36:37], v[4:5], v[36:37], v[8:9]
	v_pk_fma_f32 v[34:35], v[2:3], v[34:35], v[6:7]
	v_mul_f32_e32 v130, 0xbfb8aa3b, v36
	v_mul_f32_e32 v40, 0xbfb8aa3b, v34
	v_mul_f32_e32 v41, 0xbfb8aa3b, v35
	v_exp_f32_e32 v130, v130
	v_mul_f32_e32 v156, 0xbfb8aa3b, v37
	v_exp_f32_e32 v40, v40
	v_exp_f32_e32 v41, v41
	v_exp_f32_e32 v157, v156
	v_add_f32_e32 v130, 1.0, v130
	v_add_f32_e32 v40, 1.0, v40
	v_add_f32_e32 v41, 1.0, v41
	v_rcp_f32_e32 v156, v130
	v_add_f32_e32 v130, 1.0, v157
	v_rcp_f32_e32 v40, v40
	v_rcp_f32_e32 v41, v41
	v_rcp_f32_e32 v157, v130
	s_addc_u32 s9, s77, s9
	v_pk_mul_f32 v[34:35], v[34:35], v[40:41]
	v_pk_mul_f32 v[36:37], v[36:37], v[156:157]
	v_cvt_pk_bf16_f32 v34, v34, v35
	v_cvt_pk_bf16_f32 v35, v36, v37
	v_fma_f32 v36, s11, v235, v225
	v_rsq_f32_e32 v36, v36
	global_store_dwordx2 v105, v[34:35], s[8:9] offset:512
	s_add_i32 s8, s28, 8
	s_ashr_i32 s9, s8, 31
	v_pk_mul_f32 v[30:31], v[30:31], v[36:37] op_sel_hi:[1,0]
	v_pk_mul_f32 v[32:33], v[32:33], v[36:37] op_sel_hi:[1,0]
	v_pk_fma_f32 v[30:31], v[2:3], v[30:31], v[6:7]
	v_pk_fma_f32 v[32:33], v[4:5], v[32:33], v[8:9]
	v_mul_f32_e32 v36, 0xbfb8aa3b, v30
	v_mul_f32_e32 v37, 0xbfb8aa3b, v31
	v_mul_f32_e32 v38, 0xbfb8aa3b, v32
	v_mul_f32_e32 v39, 0xbfb8aa3b, v33
	v_exp_f32_e32 v36, v36
	v_exp_f32_e32 v37, v37
	v_exp_f32_e32 v38, v38
	v_exp_f32_e32 v39, v39
	v_add_f32_e32 v36, 1.0, v36
	v_add_f32_e32 v37, 1.0, v37
	v_add_f32_e32 v38, 1.0, v38
	v_add_f32_e32 v39, 1.0, v39
	v_rcp_f32_e32 v36, v36
	v_rcp_f32_e32 v37, v37
	v_rcp_f32_e32 v38, v38
	v_rcp_f32_e32 v39, v39
	s_lshl_b64 s[8:9], s[8:9], 11
	v_pk_mul_f32 v[30:31], v[30:31], v[36:37]
	s_add_u32 s8, s76, s8
	v_pk_mul_f32 v[32:33], v[32:33], v[38:39]
	v_cvt_pk_bf16_f32 v30, v30, v31
	v_cvt_pk_bf16_f32 v31, v32, v33
	v_fma_f32 v32, s57, v235, v225
	v_rsq_f32_e32 v32, v32
	s_addc_u32 s9, s77, s9
	global_store_dwordx2 v105, v[30:31], s[8:9] offset:512
	s_add_i32 s8, s28, 16
	v_pk_mul_f32 v[26:27], v[26:27], v[32:33] op_sel_hi:[1,0]
	v_pk_mul_f32 v[28:29], v[28:29], v[32:33] op_sel_hi:[1,0]
	v_pk_fma_f32 v[26:27], v[2:3], v[26:27], v[6:7]
	v_pk_fma_f32 v[28:29], v[4:5], v[28:29], v[8:9]
	v_mul_f32_e32 v32, 0xbfb8aa3b, v26
	v_mul_f32_e32 v33, 0xbfb8aa3b, v27
	v_mul_f32_e32 v34, 0xbfb8aa3b, v28
	v_mul_f32_e32 v35, 0xbfb8aa3b, v29
	v_exp_f32_e32 v32, v32
	v_exp_f32_e32 v33, v33
	v_exp_f32_e32 v34, v34
	v_exp_f32_e32 v35, v35
	v_add_f32_e32 v32, 1.0, v32
	v_add_f32_e32 v33, 1.0, v33
	v_add_f32_e32 v34, 1.0, v34
	v_add_f32_e32 v35, 1.0, v35
	v_rcp_f32_e32 v32, v32
	v_rcp_f32_e32 v33, v33
	v_rcp_f32_e32 v34, v34
	v_rcp_f32_e32 v35, v35
	s_ashr_i32 s9, s8, 31
	v_pk_mul_f32 v[26:27], v[26:27], v[32:33]
	s_lshl_b64 s[8:9], s[8:9], 11
	v_pk_mul_f32 v[28:29], v[28:29], v[34:35]
	v_cvt_pk_bf16_f32 v26, v26, v27
	v_cvt_pk_bf16_f32 v27, v28, v29
	v_fma_f32 v28, s56, v235, v225
	v_rsq_f32_e32 v28, v28
	s_add_u32 s8, s76, s8
	s_addc_u32 s9, s77, s9
	global_store_dwordx2 v105, v[26:27], s[8:9] offset:512
	v_pk_mul_f32 v[22:23], v[22:23], v[28:29] op_sel_hi:[1,0]
	v_pk_mul_f32 v[24:25], v[24:25], v[28:29] op_sel_hi:[1,0]
	v_pk_fma_f32 v[22:23], v[2:3], v[22:23], v[6:7]
	v_pk_fma_f32 v[24:25], v[4:5], v[24:25], v[8:9]
	v_mul_f32_e32 v28, 0xbfb8aa3b, v22
	v_mul_f32_e32 v29, 0xbfb8aa3b, v23
	v_mul_f32_e32 v30, 0xbfb8aa3b, v24
	v_mul_f32_e32 v31, 0xbfb8aa3b, v25
	v_exp_f32_e32 v28, v28
	v_exp_f32_e32 v29, v29
	v_exp_f32_e32 v30, v30
	v_exp_f32_e32 v31, v31
	v_add_f32_e32 v28, 1.0, v28
	v_add_f32_e32 v29, 1.0, v29
	v_add_f32_e32 v30, 1.0, v30
	v_add_f32_e32 v31, 1.0, v31
	v_rcp_f32_e32 v28, v28
	v_rcp_f32_e32 v29, v29
	v_rcp_f32_e32 v30, v30
	v_rcp_f32_e32 v31, v31
	s_add_i32 s8, s28, 24
	v_pk_mul_f32 v[22:23], v[22:23], v[28:29]
	s_ashr_i32 s9, s8, 31
	v_pk_mul_f32 v[24:25], v[24:25], v[30:31]
	v_cvt_pk_bf16_f32 v22, v22, v23
	v_cvt_pk_bf16_f32 v23, v24, v25
	v_fma_f32 v24, s55, v235, v225
	v_rsq_f32_e32 v24, v24
	s_lshl_b64 s[8:9], s[8:9], 11
	s_add_u32 s8, s76, s8
	s_addc_u32 s9, s77, s9
	v_pk_mul_f32 v[18:19], v[18:19], v[24:25] op_sel_hi:[1,0]
	v_pk_mul_f32 v[20:21], v[20:21], v[24:25] op_sel_hi:[1,0]
	v_pk_fma_f32 v[18:19], v[2:3], v[18:19], v[6:7]
	v_pk_fma_f32 v[20:21], v[4:5], v[20:21], v[8:9]
	v_mul_f32_e32 v24, 0xbfb8aa3b, v18
	v_mul_f32_e32 v25, 0xbfb8aa3b, v19
	v_mul_f32_e32 v26, 0xbfb8aa3b, v20
	v_mul_f32_e32 v27, 0xbfb8aa3b, v21
	v_exp_f32_e32 v24, v24
	v_exp_f32_e32 v25, v25
	v_exp_f32_e32 v26, v26
	v_exp_f32_e32 v27, v27
	v_add_f32_e32 v24, 1.0, v24
	v_add_f32_e32 v25, 1.0, v25
	v_add_f32_e32 v26, 1.0, v26
	v_add_f32_e32 v27, 1.0, v27
	v_rcp_f32_e32 v24, v24
	v_rcp_f32_e32 v25, v25
	v_rcp_f32_e32 v26, v26
	v_rcp_f32_e32 v27, v27
	global_store_dwordx2 v105, v[22:23], s[8:9] offset:512
	v_pk_mul_f32 v[18:19], v[18:19], v[24:25]
	s_add_i32 s8, s28, 32
	v_pk_mul_f32 v[20:21], v[20:21], v[26:27]
	v_cvt_pk_bf16_f32 v18, v18, v19
	v_cvt_pk_bf16_f32 v19, v20, v21
	v_fma_f32 v20, s7, v235, v225
	v_rsq_f32_e32 v20, v20
	s_ashr_i32 s9, s8, 31
	s_lshl_b64 s[8:9], s[8:9], 11
	s_add_u32 s8, s76, s8
	v_pk_mul_f32 v[14:15], v[14:15], v[20:21] op_sel_hi:[1,0]
	v_pk_mul_f32 v[16:17], v[16:17], v[20:21] op_sel_hi:[1,0]
	v_pk_fma_f32 v[14:15], v[2:3], v[14:15], v[6:7]
	v_pk_fma_f32 v[16:17], v[4:5], v[16:17], v[8:9]
	v_mul_f32_e32 v20, 0xbfb8aa3b, v14
	v_mul_f32_e32 v21, 0xbfb8aa3b, v15
	v_mul_f32_e32 v22, 0xbfb8aa3b, v16
	v_mul_f32_e32 v23, 0xbfb8aa3b, v17
	v_exp_f32_e32 v20, v20
	v_exp_f32_e32 v21, v21
	v_exp_f32_e32 v22, v22
	v_exp_f32_e32 v23, v23
	v_add_f32_e32 v20, 1.0, v20
	v_add_f32_e32 v21, 1.0, v21
	v_add_f32_e32 v22, 1.0, v22
	v_add_f32_e32 v23, 1.0, v23
	v_rcp_f32_e32 v20, v20
	v_rcp_f32_e32 v21, v21
	v_rcp_f32_e32 v22, v22
	v_rcp_f32_e32 v23, v23
	s_addc_u32 s9, s77, s9
	v_pk_mul_f32 v[14:15], v[14:15], v[20:21]
	global_store_dwordx2 v105, v[18:19], s[8:9] offset:512
	v_pk_mul_f32 v[16:17], v[16:17], v[22:23]
	v_cvt_pk_bf16_f32 v14, v14, v15
	v_cvt_pk_bf16_f32 v15, v16, v17
	v_fma_f32 v16, s6, v235, v225
	v_rsq_f32_e32 v16, v16
	s_add_i32 s8, s28, 40
	s_ashr_i32 s9, s8, 31
	s_lshl_b64 s[6:7], s[8:9], 11
	v_pk_mul_f32 v[10:11], v[10:11], v[16:17] op_sel_hi:[1,0]
	v_pk_mul_f32 v[12:13], v[12:13], v[16:17] op_sel_hi:[1,0]
	v_pk_fma_f32 v[10:11], v[2:3], v[10:11], v[6:7]
	v_pk_fma_f32 v[12:13], v[4:5], v[12:13], v[8:9]
	v_mul_f32_e32 v16, 0xbfb8aa3b, v10
	v_mul_f32_e32 v17, 0xbfb8aa3b, v11
	v_mul_f32_e32 v18, 0xbfb8aa3b, v12
	v_mul_f32_e32 v19, 0xbfb8aa3b, v13
	v_exp_f32_e32 v16, v16
	v_exp_f32_e32 v17, v17
	v_exp_f32_e32 v18, v18
	v_exp_f32_e32 v19, v19
	s_add_u32 s6, s76, s6
	v_add_f32_e32 v16, 1.0, v16
	v_add_f32_e32 v17, 1.0, v17
	v_add_f32_e32 v18, 1.0, v18
	v_add_f32_e32 v19, 1.0, v19
	s_addc_u32 s7, s77, s7
	v_rcp_f32_e32 v16, v16
	v_rcp_f32_e32 v17, v17
	v_rcp_f32_e32 v18, v18
	v_rcp_f32_e32 v19, v19
	global_store_dwordx2 v105, v[14:15], s[6:7] offset:512
	s_add_i32 s6, s28, 48
	s_ashr_i32 s7, s6, 31
	s_lshl_b64 s[6:7], s[6:7], 11
	v_pk_mul_f32 v[10:11], v[10:11], v[16:17]
	v_pk_mul_f32 v[12:13], v[12:13], v[18:19]
	s_add_u32 s6, s76, s6
	v_cvt_pk_bf16_f32 v10, v10, v11
	v_cvt_pk_bf16_f32 v11, v12, v13
	s_addc_u32 s7, s77, s7
	s_add_i32 s54, s54, s60
	global_store_dwordx2 v105, v[10:11], s[6:7] offset:512
	s_add_i32 s6, s50, s54
	s_add_i32 s52, s52, s53
	s_cmpk_gt_i32 s6, 0x1ff
	s_barrier
	s_cbranch_scc1 .LBB0_282

.LBB0_283:
	s_andn2_b64 vcc, exec, s[28:29]
	s_cbranch_vccnz .LBB0_345
	v_readlane_b32 s6, v250, 24
	v_readlane_b32 s7, v250, 25
	s_mov_b64 s[28:29], -1
	s_and_b64 vcc, exec, s[6:7]
	s_cbranch_vccz .LBB0_317
	s_waitcnt vmcnt(0)
	v_mov_b32_e32 v1, v242
	v_readlane_b32 s65, v250, 26
	v_readfirstlane_b32 s5, v1
	s_ashr_i32 s34, s5, 6
	s_lshl_b32 s6, s34, 4
	s_add_i32 s6, s6, s65
	s_mul_i32 s8, s6, 0x1800
	s_mul_hi_i32 s7, s6, 0x1800
	s_add_u32 s28, s80, s8
	s_addc_u32 s29, s81, s7
	s_or_b32 s7, s6, 1
	s_mul_hi_i32 s8, s7, 0x1800
	s_mulk_i32 s7, 0x1800
	s_add_u32 s40, s80, s7
	v_and_b32_e32 v66, 63, v1
	s_addc_u32 s41, s81, s8
	v_lshlrev_b32_e32 v38, 1, v66
	global_load_ushort v3, v38, s[40:41] offset:512
	global_load_ushort v14, v38, s[40:41] offset:640
	global_load_ushort v20, v38, s[40:41] offset:768
	global_load_ushort v24, v38, s[40:41] offset:896
	global_load_ushort v2, v38, s[28:29] offset:512
	global_load_ushort v15, v38, s[28:29] offset:640
	global_load_ushort v21, v38, s[28:29] offset:768
	global_load_ushort v25, v38, s[28:29] offset:896
	s_or_b32 s7, s6, 2
	s_mul_hi_i32 s9, s7, 0x1800
	s_mulk_i32 s7, 0x1800
	s_add_u32 s8, s80, s7
	s_addc_u32 s9, s81, s9
	s_or_b32 s7, s6, 3
	s_mul_hi_i32 s11, s7, 0x1800
	s_mulk_i32 s7, 0x1800
	s_add_u32 s10, s80, s7
	s_addc_u32 s11, s81, s11
	global_load_ushort v12, v38, s[10:11] offset:512
	global_load_ushort v13, v38, s[10:11] offset:640
	global_load_ushort v16, v38, s[10:11] offset:768
	global_load_ushort v26, v38, s[10:11] offset:896
	global_load_ushort v17, v38, s[8:9] offset:512
	global_load_ushort v22, v38, s[8:9] offset:640
	global_load_ushort v23, v38, s[8:9] offset:768
	global_load_ushort v27, v38, s[8:9] offset:896
	s_mov_b32 s8, 0xbf3a00e3
	v_mov_b64_e32 v[18:19], s[8:9]
	s_mov_b32 s10, 0x3f07dc22
	s_mov_b32 s14, 0x3f35f0e3
	s_mov_b32 s16, 0xbe11a98e
	s_mov_b32 s18, 0x3e027906
	s_or_b32 s7, s6, 4
	s_mul_hi_i32 s8, s7, 0x1800
	s_mulk_i32 s7, 0x1800
	s_add_u32 s28, s80, s7
	s_addc_u32 s29, s81, s8
	s_or_b32 s7, s6, 5
	s_mul_hi_i32 s8, s7, 0x1800
	s_mulk_i32 s7, 0x1800
	s_add_u32 s40, s80, s7
	s_addc_u32 s41, s81, s8
	s_or_b32 s7, s6, 6
	v_writelane_b32 v255, s58, 23
	s_mul_hi_i32 s8, s7, 0x1800
	s_mulk_i32 s7, 0x1800
	v_writelane_b32 v255, s59, 24
	s_add_u32 s58, s80, s7
	s_addc_u32 s59, s81, s8
	s_or_b32 s7, s6, 7
	s_mul_hi_i32 s8, s7, 0x1800
	s_mulk_i32 s7, 0x1800
	s_add_u32 s60, s80, s7
	s_addc_u32 s61, s81, s8
	s_or_b32 s7, s6, 8
	s_mul_hi_i32 s8, s7, 0x1800
	s_mulk_i32 s7, 0x1800
	s_add_u32 s46, s80, s7
	s_addc_u32 s47, s81, s8
	s_or_b32 s7, s6, 9
	s_mul_hi_i32 s8, s7, 0x1800
	s_mulk_i32 s7, 0x1800
	s_add_u32 s54, s80, s7
	s_addc_u32 s55, s81, s8
	s_or_b32 s7, s6, 10
	s_mul_hi_i32 s8, s7, 0x1800
	s_mulk_i32 s7, 0x1800
	s_add_u32 s48, s80, s7
	s_addc_u32 s49, s81, s8
	s_or_b32 s7, s6, 11
	s_mul_hi_i32 s8, s7, 0x1800
	s_mulk_i32 s7, 0x1800
	s_add_u32 s56, s80, s7
	s_addc_u32 s57, s81, s8
	s_or_b32 s7, s6, 12
	s_mul_hi_i32 s8, s7, 0x1800
	s_mulk_i32 s7, 0x1800
	s_add_u32 s42, s80, s7
	s_addc_u32 s43, s81, s8
	s_or_b32 s7, s6, 13
	s_mul_hi_i32 s8, s7, 0x1800
	s_mulk_i32 s7, 0x1800
	s_add_u32 s50, s80, s7
	s_addc_u32 s51, s81, s8
	s_or_b32 s7, s6, 14
	s_mul_hi_i32 s8, s7, 0x1800
	s_mulk_i32 s7, 0x1800
	s_waitcnt vmcnt(15)
	v_lshlrev_b32_e32 v3, 16, v3
	v_mul_f32_e32 v7, v3, v3
	v_mul_f32_e32 v7, 0xbf38aa3b, v7
	v_exp_f32_e32 v7, v7
	s_waitcnt vmcnt(11)
	v_lshlrev_b32_e32 v2, 16, v2
	s_waitcnt lgkmcnt(0)
	v_mul_f32_e32 v5, v2, v2
	v_mul_f32_e32 v5, 0xbf38aa3b, v5
	v_fma_f32 v4, |v2|, s92, 1.0
	v_exp_f32_e32 v6, v5
	v_fma_f32 v5, |v3|, s92, 1.0
	v_rcp_f32_e32 v4, v4
	v_rcp_f32_e32 v5, v5
	v_cmp_gt_f32_e32 vcc, 0, v3
	s_add_u32 s44, s80, s7
	s_addc_u32 s45, s81, s8
	v_pk_fma_f32 v[8:9], v[4:5], s[10:11], v[18:19] op_sel_hi:[1,0,0]
	s_or_b32 s6, s6, 15
	v_pk_fma_f32 v[8:9], v[4:5], v[8:9], s[14:15] op_sel_hi:[1,1,0]
	s_mul_hi_i32 s7, s6, 0x1800
	v_pk_fma_f32 v[8:9], v[4:5], v[8:9], s[16:17] op_sel_hi:[1,1,0]
	s_mulk_i32 s6, 0x1800
	v_pk_fma_f32 v[8:9], v[4:5], v[8:9], s[18:19] op_sel_hi:[1,1,0]
	s_add_u32 s52, s80, s6
	v_pk_mul_f32 v[4:5], v[4:5], v[8:9]
	s_addc_u32 s53, s81, s7
	v_pk_mul_f32 v[4:5], v[6:7], v[4:5]
	s_mov_b32 s8, 0x3b800000
	v_pk_mul_f32 v[6:7], v[4:5], v[2:3]
	v_pk_fma_f32 v[4:5], v[4:5], v[2:3], v[2:3] neg_lo:[1,0,0] neg_hi:[1,0,0]
	s_ashr_i32 s5, s5, 7
	v_cndmask_b32_e32 v11, v5, v7, vcc
	v_cmp_gt_f32_e32 vcc, 0, v2
	s_waitcnt vmcnt(3)
	v_lshlrev_b32_e32 v2, 16, v17
	v_fma_f32 v3, |v2|, s92, 1.0
	v_mul_f32_e32 v5, v2, v2
	v_cndmask_b32_e32 v10, v4, v6, vcc
	v_rcp_f32_e32 v4, v3
	v_mul_f32_e32 v5, 0xbf38aa3b, v5
	v_lshlrev_b32_e32 v3, 16, v12
	v_exp_f32_e32 v6, v5
	v_fma_f32 v5, |v3|, s92, 1.0
	v_rcp_f32_e32 v5, v5
	v_mul_f32_e32 v7, v3, v3
	v_mul_f32_e32 v7, 0xbf38aa3b, v7
	v_exp_f32_e32 v7, v7
	v_pk_fma_f32 v[8:9], v[4:5], s[10:11], v[18:19] op_sel_hi:[1,0,0]
	v_cmp_gt_f32_e32 vcc, 0, v3
	v_pk_fma_f32 v[8:9], v[4:5], v[8:9], s[14:15] op_sel_hi:[1,1,0]
	v_lshlrev_b32_e32 v130, 4, v66
	v_pk_fma_f32 v[8:9], v[4:5], v[8:9], s[16:17] op_sel_hi:[1,1,0]
	s_nop 0
	v_pk_fma_f32 v[8:9], v[4:5], v[8:9], s[18:19] op_sel_hi:[1,1,0]
	v_pk_mul_f32 v[4:5], v[4:5], v[8:9]
	v_pk_mul_f32 v[4:5], v[6:7], v[4:5]
	v_pk_mul_f32 v[6:7], v[4:5], v[2:3]
	v_pk_fma_f32 v[4:5], v[4:5], v[2:3], v[2:3] neg_lo:[1,0,0] neg_hi:[1,0,0]
	s_nop 0
	v_cndmask_b32_e32 v3, v5, v7, vcc
	v_cmp_gt_f32_e32 vcc, 0, v2
	s_nop 1
	v_cndmask_b32_e32 v2, v4, v6, vcc
	s_waitcnt vmcnt(2)
	v_lshlrev_b32_e32 v4, 16, v22
	v_fma_f32 v5, |v4|, s92, 1.0
	v_mul_f32_e32 v7, v4, v4
	v_rcp_f32_e32 v6, v5
	v_mul_f32_e32 v7, 0xbf38aa3b, v7
	v_lshlrev_b32_e32 v5, 16, v13
	v_exp_f32_e32 v8, v7
	v_fma_f32 v7, |v5|, s92, 1.0
	v_rcp_f32_e32 v7, v7
	v_mul_f32_e32 v9, v5, v5
	v_mul_f32_e32 v9, 0xbf38aa3b, v9
	v_exp_f32_e32 v9, v9
	v_pk_fma_f32 v[12:13], v[6:7], s[10:11], v[18:19] op_sel_hi:[1,0,0]
	v_cmp_gt_f32_e32 vcc, 0, v5
	v_pk_fma_f32 v[12:13], v[6:7], v[12:13], s[14:15] op_sel_hi:[1,1,0]
	s_nop 0
	v_pk_fma_f32 v[12:13], v[6:7], v[12:13], s[16:17] op_sel_hi:[1,1,0]
	s_nop 0
	v_pk_fma_f32 v[12:13], v[6:7], v[12:13], s[18:19] op_sel_hi:[1,1,0]
	v_pk_mul_f32 v[6:7], v[6:7], v[12:13]
	v_pk_mul_f32 v[6:7], v[8:9], v[6:7]
	v_pk_mul_f32 v[8:9], v[6:7], v[4:5]
	v_pk_fma_f32 v[6:7], v[6:7], v[4:5], v[4:5] neg_lo:[1,0,0] neg_hi:[1,0,0]
	v_lshlrev_b32_e32 v5, 16, v14
	v_cndmask_b32_e32 v7, v7, v9, vcc
	v_cmp_gt_f32_e32 vcc, 0, v4
	v_lshlrev_b32_e32 v4, 16, v15
	v_mul_f32_e32 v9, v4, v4
	v_mul_f32_e32 v9, 0xbf38aa3b, v9
	v_cndmask_b32_e32 v6, v6, v8, vcc
	v_fma_f32 v8, |v4|, s92, 1.0
	v_exp_f32_e32 v12, v9
	v_fma_f32 v9, |v5|, s92, 1.0
	v_rcp_f32_e32 v8, v8
	v_rcp_f32_e32 v9, v9
	v_mul_f32_e32 v13, v5, v5
	v_mul_f32_e32 v13, 0xbf38aa3b, v13
	v_exp_f32_e32 v13, v13
	v_pk_fma_f32 v[14:15], v[8:9], s[10:11], v[18:19] op_sel_hi:[1,0,0]
	v_cmp_gt_f32_e32 vcc, 0, v5
	v_pk_fma_f32 v[14:15], v[8:9], v[14:15], s[14:15] op_sel_hi:[1,1,0]
	s_nop 0
	v_pk_fma_f32 v[14:15], v[8:9], v[14:15], s[16:17] op_sel_hi:[1,1,0]
	s_nop 0
	v_pk_fma_f32 v[14:15], v[8:9], v[14:15], s[18:19] op_sel_hi:[1,1,0]
	v_pk_mul_f32 v[8:9], v[8:9], v[14:15]
	v_pk_mul_f32 v[8:9], v[12:13], v[8:9]
	v_pk_mul_f32 v[12:13], v[8:9], v[4:5]
	v_pk_fma_f32 v[8:9], v[8:9], v[4:5], v[4:5] neg_lo:[1,0,0] neg_hi:[1,0,0]
	v_lshlrev_b32_e32 v5, 16, v16
	v_cndmask_b32_e32 v13, v9, v13, vcc
	v_cmp_gt_f32_e32 vcc, 0, v4
	s_waitcnt vmcnt(1)
	v_lshlrev_b32_e32 v4, 16, v23
	v_fma_f32 v9, |v5|, s92, 1.0
	v_cndmask_b32_e32 v12, v8, v12, vcc
	v_fma_f32 v8, |v4|, s92, 1.0
	v_rcp_f32_e32 v8, v8
	v_rcp_f32_e32 v9, v9
	v_mul_f32_e32 v14, v4, v4
	v_mul_f32_e32 v15, v5, v5
	v_mul_f32_e32 v14, 0xbf38aa3b, v14
	v_pk_fma_f32 v[16:17], v[8:9], s[10:11], v[18:19] op_sel_hi:[1,0,0]
	v_mul_f32_e32 v15, 0xbf38aa3b, v15
	v_exp_f32_e32 v14, v14
	v_pk_fma_f32 v[16:17], v[8:9], v[16:17], s[14:15] op_sel_hi:[1,1,0]
	v_exp_f32_e32 v15, v15
	v_pk_fma_f32 v[16:17], v[8:9], v[16:17], s[16:17] op_sel_hi:[1,1,0]
	v_cmp_gt_f32_e32 vcc, 0, v5
	v_pk_fma_f32 v[16:17], v[8:9], v[16:17], s[18:19] op_sel_hi:[1,1,0]
	s_nop 0
	v_pk_mul_f32 v[8:9], v[8:9], v[16:17]
	v_pk_mul_f32 v[8:9], v[14:15], v[8:9]
	v_pk_mul_f32 v[14:15], v[8:9], v[4:5]
	v_pk_fma_f32 v[8:9], v[8:9], v[4:5], v[4:5] neg_lo:[1,0,0] neg_hi:[1,0,0]
	v_lshlrev_b32_e32 v5, 16, v20
	v_cndmask_b32_e32 v15, v9, v15, vcc
	v_cmp_gt_f32_e32 vcc, 0, v4
	v_lshlrev_b32_e32 v4, 16, v21
	v_mul_f32_e32 v9, v4, v4
	v_mul_f32_e32 v9, 0xbf38aa3b, v9
	v_cndmask_b32_e32 v14, v8, v14, vcc
	v_fma_f32 v8, |v4|, s92, 1.0
	v_exp_f32_e32 v16, v9
	v_fma_f32 v9, |v5|, s92, 1.0
	v_rcp_f32_e32 v8, v8
	v_rcp_f32_e32 v9, v9
	v_mul_f32_e32 v17, v5, v5
	v_mul_f32_e32 v17, 0xbf38aa3b, v17
	v_exp_f32_e32 v17, v17
	v_pk_fma_f32 v[20:21], v[8:9], s[10:11], v[18:19] op_sel_hi:[1,0,0]
	v_cmp_gt_f32_e32 vcc, 0, v5
	v_pk_fma_f32 v[20:21], v[8:9], v[20:21], s[14:15] op_sel_hi:[1,1,0]
	s_nop 0
	v_pk_fma_f32 v[20:21], v[8:9], v[20:21], s[16:17] op_sel_hi:[1,1,0]
	s_nop 0
	v_pk_fma_f32 v[20:21], v[8:9], v[20:21], s[18:19] op_sel_hi:[1,1,0]
	v_pk_mul_f32 v[8:9], v[8:9], v[20:21]
	v_pk_mul_f32 v[8:9], v[16:17], v[8:9]
	v_pk_mul_f32 v[16:17], v[8:9], v[4:5]
	v_pk_fma_f32 v[8:9], v[8:9], v[4:5], v[4:5] neg_lo:[1,0,0] neg_hi:[1,0,0]
	v_lshlrev_b32_e32 v5, 16, v26
	v_cndmask_b32_e32 v23, v9, v17, vcc
	v_cmp_gt_f32_e32 vcc, 0, v4
	s_waitcnt vmcnt(0)
	v_lshlrev_b32_e32 v4, 16, v27
	v_fma_f32 v9, |v5|, s92, 1.0
	v_cndmask_b32_e32 v22, v8, v16, vcc
	v_fma_f32 v8, |v4|, s92, 1.0
	v_rcp_f32_e32 v8, v8
	v_rcp_f32_e32 v9, v9
	v_mul_f32_e32 v16, v4, v4
	v_mul_f32_e32 v17, v5, v5
	v_mul_f32_e32 v16, 0xbf38aa3b, v16
	v_pk_fma_f32 v[20:21], v[8:9], s[10:11], v[18:19] op_sel_hi:[1,0,0]
	v_mul_f32_e32 v17, 0xbf38aa3b, v17
	v_exp_f32_e32 v16, v16
	v_pk_fma_f32 v[20:21], v[8:9], v[20:21], s[14:15] op_sel_hi:[1,1,0]
	v_exp_f32_e32 v17, v17
	v_pk_fma_f32 v[20:21], v[8:9], v[20:21], s[16:17] op_sel_hi:[1,1,0]
	v_cmp_gt_f32_e32 vcc, 0, v5
	v_pk_fma_f32 v[20:21], v[8:9], v[20:21], s[18:19] op_sel_hi:[1,1,0]
	v_mov_b32_e32 v26, v13
	v_pk_mul_f32 v[8:9], v[8:9], v[20:21]
	v_pk_mul_f32 v[8:9], v[16:17], v[8:9]
	v_pk_mul_f32 v[16:17], v[8:9], v[4:5]
	v_pk_fma_f32 v[8:9], v[8:9], v[4:5], v[4:5] neg_lo:[1,0,0] neg_hi:[1,0,0]
	v_lshlrev_b32_e32 v5, 16, v24
	v_cndmask_b32_e32 v17, v9, v17, vcc
	v_cmp_gt_f32_e32 vcc, 0, v4
	v_lshlrev_b32_e32 v4, 16, v25
	v_mul_f32_e32 v9, v4, v4
	v_mul_f32_e32 v9, 0xbf38aa3b, v9
	v_cndmask_b32_e32 v16, v8, v16, vcc
	v_fma_f32 v8, |v4|, s92, 1.0
	v_exp_f32_e32 v20, v9
	v_fma_f32 v9, |v5|, s92, 1.0
	v_rcp_f32_e32 v8, v8
	v_rcp_f32_e32 v9, v9
	v_mul_f32_e32 v21, v5, v5
	v_mul_f32_e32 v21, 0xbf38aa3b, v21
	v_exp_f32_e32 v21, v21
	v_pk_fma_f32 v[24:25], v[8:9], s[10:11], v[18:19] op_sel_hi:[1,0,0]
	v_cmp_gt_f32_e32 vcc, 0, v5
	v_pk_fma_f32 v[24:25], v[8:9], v[24:25], s[14:15] op_sel_hi:[1,1,0]
	s_nop 0
	v_pk_fma_f32 v[24:25], v[8:9], v[24:25], s[16:17] op_sel_hi:[1,1,0]
	s_nop 0
	v_pk_fma_f32 v[24:25], v[8:9], v[24:25], s[18:19] op_sel_hi:[1,1,0]
	v_pk_mul_f32 v[8:9], v[8:9], v[24:25]
	v_pk_mul_f32 v[8:9], v[20:21], v[8:9]
	v_pk_mul_f32 v[20:21], v[8:9], v[4:5]
	v_pk_fma_f32 v[8:9], v[8:9], v[4:5], v[4:5] neg_lo:[1,0,0] neg_hi:[1,0,0]
	v_mov_b32_e32 v5, v14
	v_cndmask_b32_e32 v25, v9, v21, vcc
	v_cmp_gt_f32_e32 vcc, 0, v4
	v_mov_b32_e32 v4, v2
	v_mov_b32_e32 v9, v16
	v_cndmask_b32_e32 v24, v8, v20, vcc
	v_mov_b32_e32 v8, v6
	v_pk_add_f32 v[4:5], v[4:5], v[8:9]
	v_mov_b32_e32 v8, v3
	v_add_f32_e32 v4, v4, v5
	v_mov_b32_e32 v5, v131
	v_mov_b32_e32 v9, v15
	v_add_f32_dpp v4, v4, v4 quad_perm:[1,0,3,2] row_mask:0xf bank_mask:0xf bound_ctrl:1
	v_mov_b32_e32 v20, v7
	v_mov_b32_e32 v21, v17
	v_add_f32_dpp v4, v4, v4 quad_perm:[2,3,0,1] row_mask:0xf bank_mask:0xf bound_ctrl:1
	v_pk_add_f32 v[8:9], v[8:9], v[20:21]
	v_mov_b64_e32 v[20:21], s[8:9]
	v_add_f32_dpp v4, v4, v4 row_half_mirror row_mask:0xf bank_mask:0xf bound_ctrl:1
	v_mov_b32_e32 v27, v25
	s_mov_b32 s8, 0x3e027906
	v_add_f32_dpp v4, v4, v4 row_mirror row_mask:0xf bank_mask:0xf bound_ctrl:1
	s_nop 1
	v_mov_b32_dpp v5, v4 row_bcast:15 row_mask:0xa bank_mask:0xf
	v_add_f32_e32 v4, v4, v5
	v_mov_b32_e32 v5, v131
	s_nop 1
	v_mov_b32_dpp v5, v4 row_bcast:31 row_mask:0xc bank_mask:0xf
	v_add_f32_e32 v4, v4, v5
	v_add_f32_e32 v5, v8, v9
	v_mov_b32_e32 v8, v131
	v_readlane_b32 s6, v4, 63
	v_add_f32_dpp v5, v5, v5 quad_perm:[1,0,3,2] row_mask:0xf bank_mask:0xf bound_ctrl:1
	s_xor_b32 s6, s6, 0x80000000
	s_nop 0
	v_add_f32_dpp v5, v5, v5 quad_perm:[2,3,0,1] row_mask:0xf bank_mask:0xf bound_ctrl:1
	s_nop 1
	v_add_f32_dpp v5, v5, v5 row_half_mirror row_mask:0xf bank_mask:0xf bound_ctrl:1
	s_nop 1
	v_add_f32_dpp v5, v5, v5 row_mirror row_mask:0xf bank_mask:0xf bound_ctrl:1
	s_nop 1
	v_mov_b32_dpp v8, v5 row_bcast:15 row_mask:0xa bank_mask:0xf
	v_add_f32_e32 v5, v5, v8
	v_mov_b32_e32 v8, v131
	s_nop 1
	v_mov_b32_dpp v8, v5 row_bcast:31 row_mask:0xc bank_mask:0xf
	v_add_f32_e32 v5, v5, v8
	s_nop 0
	v_readlane_b32 s7, v5, 63
	s_xor_b32 s7, s7, 0x80000000
	s_nop 0
	v_pk_fma_f32 v[4:5], s[6:7], v[20:21], v[2:3] op_sel_hi:[1,0,1]
	v_pk_fma_f32 v[8:9], s[6:7], v[20:21], v[6:7] op_sel_hi:[1,0,1]
	v_pk_fma_f32 v[6:7], s[6:7], v[20:21], v[14:15] op_sel_hi:[1,0,1]
	v_pk_fma_f32 v[2:3], s[6:7], v[20:21], v[16:17] op_sel_hi:[1,0,1]
	v_mov_b32_e32 v14, v10
	v_mov_b32_e32 v15, v22
	v_mov_b32_e32 v16, v12
	v_mov_b32_e32 v17, v24
	v_pk_add_f32 v[14:15], v[14:15], v[16:17]
	v_mov_b32_e32 v16, v11
	v_add_f32_e32 v14, v14, v15
	v_mov_b32_e32 v15, v131
	v_mov_b32_e32 v17, v23
	v_add_f32_dpp v14, v14, v14 quad_perm:[1,0,3,2] row_mask:0xf bank_mask:0xf bound_ctrl:1
	v_pk_add_f32 v[16:17], v[16:17], v[26:27]
	s_nop 0
	v_add_f32_dpp v14, v14, v14 quad_perm:[2,3,0,1] row_mask:0xf bank_mask:0xf bound_ctrl:1
	s_nop 1
	v_add_f32_dpp v14, v14, v14 row_half_mirror row_mask:0xf bank_mask:0xf bound_ctrl:1
	s_nop 1
	v_add_f32_dpp v14, v14, v14 row_mirror row_mask:0xf bank_mask:0xf bound_ctrl:1
	s_nop 1
	v_mov_b32_dpp v15, v14 row_bcast:15 row_mask:0xa bank_mask:0xf
	v_add_f32_e32 v14, v14, v15
	v_mov_b32_e32 v15, v131
	s_nop 1
	v_mov_b32_dpp v15, v14 row_bcast:31 row_mask:0xc bank_mask:0xf
	v_add_f32_e32 v14, v14, v15
	v_add_f32_e32 v15, v16, v17
	v_mov_b32_e32 v16, v131
	v_readlane_b32 s6, v14, 63
	v_add_f32_dpp v15, v15, v15 quad_perm:[1,0,3,2] row_mask:0xf bank_mask:0xf bound_ctrl:1
	s_xor_b32 s6, s6, 0x80000000
	s_nop 0
	v_add_f32_dpp v15, v15, v15 quad_perm:[2,3,0,1] row_mask:0xf bank_mask:0xf bound_ctrl:1
	s_nop 1
	v_add_f32_dpp v15, v15, v15 row_half_mirror row_mask:0xf bank_mask:0xf bound_ctrl:1
	s_nop 1
	v_add_f32_dpp v15, v15, v15 row_mirror row_mask:0xf bank_mask:0xf bound_ctrl:1
	s_nop 1
	v_mov_b32_dpp v16, v15 row_bcast:15 row_mask:0xa bank_mask:0xf
	v_add_f32_e32 v15, v15, v16
	v_mov_b32_e32 v16, v131
	s_nop 1
	v_mov_b32_dpp v16, v15 row_bcast:31 row_mask:0xc bank_mask:0xf
	v_add_f32_e32 v15, v15, v16
	s_nop 0
	v_readlane_b32 s7, v15, 63
	s_xor_b32 s7, s7, 0x80000000
	s_nop 0
	v_pk_fma_f32 v[16:17], s[6:7], v[20:21], v[10:11] op_sel_hi:[1,0,1]
	v_pk_fma_f32 v[14:15], s[6:7], v[20:21], v[12:13] op_sel_hi:[1,0,1]
	v_pk_fma_f32 v[12:13], s[6:7], v[20:21], v[22:23] op_sel_hi:[1,0,1]
	v_pk_fma_f32 v[10:11], s[6:7], v[20:21], v[24:25] op_sel_hi:[1,0,1]
	global_load_ushort v22, v38, s[60:61] offset:512
	global_load_ushort v32, v38, s[60:61] offset:640
	global_load_ushort v36, v38, s[60:61] offset:768
	global_load_ushort v39, v38, s[60:61] offset:896
	global_load_ushort v24, v38, s[58:59] offset:512
	global_load_ushort v33, v38, s[58:59] offset:640
	global_load_ushort v37, v38, s[58:59] offset:768
	global_load_ushort v42, v38, s[58:59] offset:896
	s_waitcnt vmcnt(7)
	v_lshlrev_b32_e32 v23, 16, v22
	v_fma_f32 v25, |v23|, s92, 1.0
	v_rcp_f32_e32 v25, v25
	v_mul_f32_e32 v27, v23, v23
	s_waitcnt vmcnt(3)
	v_lshlrev_b32_e32 v22, 16, v24
	v_fma_f32 v24, |v22|, s92, 1.0
	v_rcp_f32_e32 v24, v24
	v_mul_f32_e32 v26, v22, v22
	v_mul_f32_e32 v26, 0xbf38aa3b, v26
	v_mul_f32_e32 v27, 0xbf38aa3b, v27
	v_pk_fma_f32 v[28:29], v[24:25], s[10:11], v[18:19] op_sel_hi:[1,0,0]
	v_exp_f32_e32 v26, v26
	v_pk_fma_f32 v[28:29], v[24:25], v[28:29], s[14:15] op_sel_hi:[1,1,0]
	v_exp_f32_e32 v27, v27
	v_pk_fma_f32 v[28:29], v[24:25], v[28:29], s[16:17] op_sel_hi:[1,1,0]
	v_cmp_gt_f32_e32 vcc, 0, v23
	v_pk_fma_f32 v[28:29], v[24:25], v[28:29], s[18:19] op_sel_hi:[1,1,0]
	v_readlane_b32 s11, v254, 26
	v_pk_mul_f32 v[24:25], v[24:25], v[28:29]
	s_nop 0
	v_pk_mul_f32 v[24:25], v[26:27], v[24:25]
	v_pk_mul_f32 v[26:27], v[24:25], v[22:23]
	v_pk_fma_f32 v[24:25], v[24:25], v[22:23], v[22:23] neg_lo:[1,0,0] neg_hi:[1,0,0]
	s_nop 0
	v_cndmask_b32_e32 v23, v25, v27, vcc
	v_cmp_gt_f32_e32 vcc, 0, v22
	s_nop 1
	v_cndmask_b32_e32 v22, v24, v26, vcc
	global_load_ushort v24, v38, s[40:41] offset:512
	global_load_ushort v34, v38, s[40:41] offset:640
	global_load_ushort v40, v38, s[40:41] offset:768
	global_load_ushort v44, v38, s[40:41] offset:896
	global_load_ushort v26, v38, s[28:29] offset:512
	global_load_ushort v35, v38, s[28:29] offset:640
	global_load_ushort v41, v38, s[28:29] offset:768
	global_load_ushort v45, v38, s[28:29] offset:896
	s_waitcnt vmcnt(7)
	v_lshlrev_b32_e32 v25, 16, v24
	s_waitcnt vmcnt(3)
	v_lshlrev_b32_e32 v24, 16, v26
	v_mul_f32_e32 v27, v24, v24
	v_mul_f32_e32 v27, 0xbf38aa3b, v27
	v_fma_f32 v26, |v24|, s92, 1.0
	v_exp_f32_e32 v28, v27
	v_fma_f32 v27, |v25|, s92, 1.0
	v_rcp_f32_e32 v26, v26
	v_rcp_f32_e32 v27, v27
	v_mul_f32_e32 v29, v25, v25
	v_mul_f32_e32 v29, 0xbf38aa3b, v29
	v_exp_f32_e32 v29, v29
	v_pk_fma_f32 v[30:31], v[26:27], s[10:11], v[18:19] op_sel_hi:[1,0,0]
	v_cmp_gt_f32_e32 vcc, 0, v25
	v_pk_fma_f32 v[30:31], v[26:27], v[30:31], s[14:15] op_sel_hi:[1,1,0]
	s_nop 0
	v_pk_fma_f32 v[30:31], v[26:27], v[30:31], s[16:17] op_sel_hi:[1,1,0]
	s_nop 0
	v_pk_fma_f32 v[30:31], v[26:27], v[30:31], s[18:19] op_sel_hi:[1,1,0]
	v_pk_mul_f32 v[26:27], v[26:27], v[30:31]
	v_pk_mul_f32 v[26:27], v[28:29], v[26:27]
	v_pk_mul_f32 v[28:29], v[26:27], v[24:25]
	v_pk_fma_f32 v[26:27], v[26:27], v[24:25], v[24:25] neg_lo:[1,0,0] neg_hi:[1,0,0]
	v_lshlrev_b32_e32 v25, 16, v32
	v_cndmask_b32_e32 v31, v27, v29, vcc
	v_cmp_gt_f32_e32 vcc, 0, v24
	v_lshlrev_b32_e32 v24, 16, v33
	v_fma_f32 v27, |v25|, s92, 1.0
	v_cndmask_b32_e32 v30, v26, v28, vcc
	v_fma_f32 v26, |v24|, s92, 1.0
	v_rcp_f32_e32 v26, v26
	v_rcp_f32_e32 v27, v27
	v_mul_f32_e32 v28, v24, v24
	v_mul_f32_e32 v29, v25, v25
	v_mul_f32_e32 v28, 0xbf38aa3b, v28
	v_pk_fma_f32 v[32:33], v[26:27], s[10:11], v[18:19] op_sel_hi:[1,0,0]
	v_mul_f32_e32 v29, 0xbf38aa3b, v29
	v_exp_f32_e32 v28, v28
	v_pk_fma_f32 v[32:33], v[26:27], v[32:33], s[14:15] op_sel_hi:[1,1,0]
	v_exp_f32_e32 v29, v29
	v_pk_fma_f32 v[32:33], v[26:27], v[32:33], s[16:17] op_sel_hi:[1,1,0]
	v_cmp_gt_f32_e32 vcc, 0, v25
	v_pk_fma_f32 v[32:33], v[26:27], v[32:33], s[18:19] op_sel_hi:[1,1,0]
	s_nop 0
	v_pk_mul_f32 v[26:27], v[26:27], v[32:33]
	v_pk_mul_f32 v[26:27], v[28:29], v[26:27]
	v_pk_mul_f32 v[28:29], v[26:27], v[24:25]
	v_pk_fma_f32 v[26:27], v[26:27], v[24:25], v[24:25] neg_lo:[1,0,0] neg_hi:[1,0,0]
	s_nop 0
	v_cndmask_b32_e32 v25, v27, v29, vcc
	v_cmp_gt_f32_e32 vcc, 0, v24
	v_lshlrev_b32_e32 v27, 16, v34
	v_mul_f32_e32 v33, v27, v27
	v_cndmask_b32_e32 v24, v26, v28, vcc
	s_waitcnt vmcnt(2)
	v_lshlrev_b32_e32 v26, 16, v35
	v_mul_f32_e32 v29, v26, v26
	v_mul_f32_e32 v29, 0xbf38aa3b, v29
	v_fma_f32 v28, |v26|, s92, 1.0
	v_exp_f32_e32 v32, v29
	v_fma_f32 v29, |v27|, s92, 1.0
	v_rcp_f32_e32 v28, v28
	v_rcp_f32_e32 v29, v29
	v_mul_f32_e32 v33, 0xbf38aa3b, v33
	v_exp_f32_e32 v33, v33
	v_cmp_gt_f32_e32 vcc, 0, v27
	v_pk_fma_f32 v[34:35], v[28:29], s[10:11], v[18:19] op_sel_hi:[1,0,0]
	s_nop 0
	v_pk_fma_f32 v[34:35], v[28:29], v[34:35], s[14:15] op_sel_hi:[1,1,0]
	s_nop 0
	v_pk_fma_f32 v[34:35], v[28:29], v[34:35], s[16:17] op_sel_hi:[1,1,0]
	s_nop 0
	v_pk_fma_f32 v[34:35], v[28:29], v[34:35], s[18:19] op_sel_hi:[1,1,0]
	v_pk_mul_f32 v[28:29], v[28:29], v[34:35]
	v_pk_mul_f32 v[28:29], v[32:33], v[28:29]
	v_pk_mul_f32 v[32:33], v[28:29], v[26:27]
	v_pk_fma_f32 v[28:29], v[28:29], v[26:27], v[26:27] neg_lo:[1,0,0] neg_hi:[1,0,0]
	v_lshlrev_b32_e32 v27, 16, v36
	v_cndmask_b32_e32 v33, v29, v33, vcc
	v_cmp_gt_f32_e32 vcc, 0, v26
	v_lshlrev_b32_e32 v26, 16, v37
	v_fma_f32 v29, |v27|, s92, 1.0
	v_cndmask_b32_e32 v32, v28, v32, vcc
	v_fma_f32 v28, |v26|, s92, 1.0
	v_rcp_f32_e32 v28, v28
	v_rcp_f32_e32 v29, v29
	v_mul_f32_e32 v34, v26, v26
	v_mul_f32_e32 v35, v27, v27
	v_mul_f32_e32 v34, 0xbf38aa3b, v34
	v_pk_fma_f32 v[36:37], v[28:29], s[10:11], v[18:19] op_sel_hi:[1,0,0]
	v_mul_f32_e32 v35, 0xbf38aa3b, v35
	v_exp_f32_e32 v34, v34
	v_pk_fma_f32 v[36:37], v[28:29], v[36:37], s[14:15] op_sel_hi:[1,1,0]
	v_exp_f32_e32 v35, v35
	v_pk_fma_f32 v[36:37], v[28:29], v[36:37], s[16:17] op_sel_hi:[1,1,0]
	v_cmp_gt_f32_e32 vcc, 0, v27
	v_pk_fma_f32 v[36:37], v[28:29], v[36:37], s[18:19] op_sel_hi:[1,1,0]
	s_nop 0
	v_pk_mul_f32 v[28:29], v[28:29], v[36:37]
	v_pk_mul_f32 v[28:29], v[34:35], v[28:29]
	v_pk_mul_f32 v[34:35], v[28:29], v[26:27]
	v_pk_fma_f32 v[28:29], v[28:29], v[26:27], v[26:27] neg_lo:[1,0,0] neg_hi:[1,0,0]
	v_lshlrev_b32_e32 v27, 16, v40
	v_cndmask_b32_e32 v35, v29, v35, vcc
	v_cmp_gt_f32_e32 vcc, 0, v26
	s_waitcnt vmcnt(1)
	v_lshlrev_b32_e32 v26, 16, v41
	v_mul_f32_e32 v29, v26, v26
	v_mul_f32_e32 v29, 0xbf38aa3b, v29
	v_cndmask_b32_e32 v34, v28, v34, vcc
	v_fma_f32 v28, |v26|, s92, 1.0
	v_exp_f32_e32 v36, v29
	v_fma_f32 v29, |v27|, s92, 1.0
	v_rcp_f32_e32 v28, v28
	v_rcp_f32_e32 v29, v29
	v_mul_f32_e32 v37, v27, v27
	v_mul_f32_e32 v37, 0xbf38aa3b, v37
	v_exp_f32_e32 v37, v37
	v_pk_fma_f32 v[40:41], v[28:29], s[10:11], v[18:19] op_sel_hi:[1,0,0]
	v_cmp_gt_f32_e32 vcc, 0, v27
	v_pk_fma_f32 v[40:41], v[28:29], v[40:41], s[14:15] op_sel_hi:[1,1,0]
	s_nop 0
	v_pk_fma_f32 v[40:41], v[28:29], v[40:41], s[16:17] op_sel_hi:[1,1,0]
	s_nop 0
	v_pk_fma_f32 v[40:41], v[28:29], v[40:41], s[18:19] op_sel_hi:[1,1,0]
	v_pk_mul_f32 v[28:29], v[28:29], v[40:41]
	v_pk_mul_f32 v[28:29], v[36:37], v[28:29]
	v_pk_mul_f32 v[36:37], v[28:29], v[26:27]
	v_pk_fma_f32 v[28:29], v[28:29], v[26:27], v[26:27] neg_lo:[1,0,0] neg_hi:[1,0,0]
	v_lshlrev_b32_e32 v27, 16, v39
	v_cndmask_b32_e32 v41, v29, v37, vcc
	v_cmp_gt_f32_e32 vcc, 0, v26
	v_lshlrev_b32_e32 v26, 16, v42
	v_fma_f32 v29, |v27|, s92, 1.0
	v_cndmask_b32_e32 v40, v28, v36, vcc
	v_fma_f32 v28, |v26|, s92, 1.0
	v_rcp_f32_e32 v28, v28
	v_rcp_f32_e32 v29, v29
	v_mul_f32_e32 v36, v26, v26
	v_mul_f32_e32 v37, v27, v27
	v_mul_f32_e32 v36, 0xbf38aa3b, v36
	v_pk_fma_f32 v[42:43], v[28:29], s[10:11], v[18:19] op_sel_hi:[1,0,0]
	v_mul_f32_e32 v37, 0xbf38aa3b, v37
	v_exp_f32_e32 v36, v36
	v_pk_fma_f32 v[42:43], v[28:29], v[42:43], s[14:15] op_sel_hi:[1,1,0]
	v_exp_f32_e32 v37, v37
	v_pk_fma_f32 v[42:43], v[28:29], v[42:43], s[16:17] op_sel_hi:[1,1,0]
	v_cmp_gt_f32_e32 vcc, 0, v27
	v_pk_fma_f32 v[42:43], v[28:29], v[42:43], s[18:19] op_sel_hi:[1,1,0]
	s_nop 0
	v_pk_mul_f32 v[28:29], v[28:29], v[42:43]
	v_pk_mul_f32 v[28:29], v[36:37], v[28:29]
	v_pk_mul_f32 v[36:37], v[28:29], v[26:27]
	v_pk_fma_f32 v[28:29], v[28:29], v[26:27], v[26:27] neg_lo:[1,0,0] neg_hi:[1,0,0]
	v_lshlrev_b32_e32 v27, 16, v44
	v_cndmask_b32_e32 v37, v29, v37, vcc
	v_cmp_gt_f32_e32 vcc, 0, v26
	s_waitcnt vmcnt(0)
	v_lshlrev_b32_e32 v26, 16, v45
	v_mul_f32_e32 v29, v26, v26
	v_mul_f32_e32 v29, 0xbf38aa3b, v29
	v_cndmask_b32_e32 v36, v28, v36, vcc
	v_fma_f32 v28, |v26|, s92, 1.0
	v_exp_f32_e32 v42, v29
	v_fma_f32 v29, |v27|, s92, 1.0
	v_rcp_f32_e32 v28, v28
	v_rcp_f32_e32 v29, v29
	v_mul_f32_e32 v39, v27, v27
	v_mul_f32_e32 v39, 0xbf38aa3b, v39
	v_exp_f32_e32 v43, v39
	v_pk_fma_f32 v[44:45], v[28:29], s[10:11], v[18:19] op_sel_hi:[1,0,0]
	v_cmp_gt_f32_e32 vcc, 0, v27
	v_pk_fma_f32 v[44:45], v[28:29], v[44:45], s[14:15] op_sel_hi:[1,1,0]
	s_nop 0
	v_pk_fma_f32 v[44:45], v[28:29], v[44:45], s[16:17] op_sel_hi:[1,1,0]
	s_nop 0
	v_pk_fma_f32 v[44:45], v[28:29], v[44:45], s[18:19] op_sel_hi:[1,1,0]
	v_pk_mul_f32 v[28:29], v[28:29], v[44:45]
	v_mov_b32_e32 v44, v25
	v_pk_mul_f32 v[28:29], v[42:43], v[28:29]
	v_mov_b32_e32 v45, v37
	v_pk_mul_f32 v[42:43], v[28:29], v[26:27]
	v_pk_fma_f32 v[28:29], v[28:29], v[26:27], v[26:27] neg_lo:[1,0,0] neg_hi:[1,0,0]
	v_mov_b32_e32 v27, v34
	v_cndmask_b32_e32 v43, v29, v43, vcc
	v_cmp_gt_f32_e32 vcc, 0, v26
	v_mov_b32_e32 v26, v22
	v_mov_b32_e32 v29, v36
	v_cndmask_b32_e32 v42, v28, v42, vcc
	v_mov_b32_e32 v28, v24
	v_pk_add_f32 v[26:27], v[26:27], v[28:29]
	v_mov_b32_e32 v28, v23
	v_add_f32_e32 v26, v26, v27
	v_mov_b32_e32 v27, v131
	v_mov_b32_e32 v29, v35
	v_add_f32_dpp v26, v26, v26 quad_perm:[1,0,3,2] row_mask:0xf bank_mask:0xf bound_ctrl:1
	v_pk_add_f32 v[28:29], v[28:29], v[44:45]
	v_mov_b32_e32 v44, v33
	v_add_f32_dpp v26, v26, v26 quad_perm:[2,3,0,1] row_mask:0xf bank_mask:0xf bound_ctrl:1
	v_mov_b32_e32 v45, v43
	s_nop 0
	v_add_f32_dpp v26, v26, v26 row_half_mirror row_mask:0xf bank_mask:0xf bound_ctrl:1
	s_nop 1
	v_add_f32_dpp v26, v26, v26 row_mirror row_mask:0xf bank_mask:0xf bound_ctrl:1
	s_nop 1
	v_mov_b32_dpp v27, v26 row_bcast:15 row_mask:0xa bank_mask:0xf
	v_add_f32_e32 v26, v26, v27
	v_mov_b32_e32 v27, v131
	s_nop 1
	v_mov_b32_dpp v27, v26 row_bcast:31 row_mask:0xc bank_mask:0xf
	v_add_f32_e32 v26, v26, v27
	v_add_f32_e32 v27, v28, v29
	v_mov_b32_e32 v28, v131
	v_readlane_b32 s6, v26, 63
	v_add_f32_dpp v27, v27, v27 quad_perm:[1,0,3,2] row_mask:0xf bank_mask:0xf bound_ctrl:1
	s_xor_b32 s6, s6, 0x80000000
	s_nop 0
	v_add_f32_dpp v27, v27, v27 quad_perm:[2,3,0,1] row_mask:0xf bank_mask:0xf bound_ctrl:1
	s_nop 1
	v_add_f32_dpp v27, v27, v27 row_half_mirror row_mask:0xf bank_mask:0xf bound_ctrl:1
	s_nop 1
	v_add_f32_dpp v27, v27, v27 row_mirror row_mask:0xf bank_mask:0xf bound_ctrl:1
	s_nop 1
	v_mov_b32_dpp v28, v27 row_bcast:15 row_mask:0xa bank_mask:0xf
	v_add_f32_e32 v27, v27, v28
	v_mov_b32_e32 v28, v131
	s_nop 1
	v_mov_b32_dpp v28, v27 row_bcast:31 row_mask:0xc bank_mask:0xf
	v_add_f32_e32 v27, v27, v28
	s_nop 0
	v_readlane_b32 s7, v27, 63
	s_xor_b32 s7, s7, 0x80000000
	s_nop 0
	v_pk_fma_f32 v[28:29], s[6:7], v[20:21], v[22:23] op_sel_hi:[1,0,1]
	v_pk_fma_f32 v[26:27], s[6:7], v[20:21], v[24:25] op_sel_hi:[1,0,1]
	v_pk_fma_f32 v[24:25], s[6:7], v[20:21], v[34:35] op_sel_hi:[1,0,1]
	v_pk_fma_f32 v[22:23], s[6:7], v[20:21], v[36:37] op_sel_hi:[1,0,1]
	v_mov_b32_e32 v34, v30
	v_mov_b32_e32 v35, v40
	v_mov_b32_e32 v36, v32
	v_mov_b32_e32 v37, v42
	v_pk_add_f32 v[34:35], v[34:35], v[36:37]
	v_mov_b32_e32 v36, v31
	v_add_f32_e32 v34, v34, v35
	v_mov_b32_e32 v35, v131
	v_mov_b32_e32 v37, v41
	v_add_f32_dpp v34, v34, v34 quad_perm:[1,0,3,2] row_mask:0xf bank_mask:0xf bound_ctrl:1
	v_pk_add_f32 v[36:37], v[36:37], v[44:45]
	s_nop 0
	v_add_f32_dpp v34, v34, v34 quad_perm:[2,3,0,1] row_mask:0xf bank_mask:0xf bound_ctrl:1
	s_nop 1
	v_add_f32_dpp v34, v34, v34 row_half_mirror row_mask:0xf bank_mask:0xf bound_ctrl:1
	s_nop 1
	v_add_f32_dpp v34, v34, v34 row_mirror row_mask:0xf bank_mask:0xf bound_ctrl:1
	s_nop 1
	v_mov_b32_dpp v35, v34 row_bcast:15 row_mask:0xa bank_mask:0xf
	v_add_f32_e32 v34, v34, v35
	v_mov_b32_e32 v35, v131
	s_nop 1
	v_mov_b32_dpp v35, v34 row_bcast:31 row_mask:0xc bank_mask:0xf
	v_add_f32_e32 v34, v34, v35
	v_add_f32_e32 v35, v36, v37
	v_mov_b32_e32 v36, v131
	v_readlane_b32 s6, v34, 63
	v_add_f32_dpp v35, v35, v35 quad_perm:[1,0,3,2] row_mask:0xf bank_mask:0xf bound_ctrl:1
	s_xor_b32 s6, s6, 0x80000000
	s_nop 0
	v_add_f32_dpp v35, v35, v35 quad_perm:[2,3,0,1] row_mask:0xf bank_mask:0xf bound_ctrl:1
	s_nop 1
	v_add_f32_dpp v35, v35, v35 row_half_mirror row_mask:0xf bank_mask:0xf bound_ctrl:1
	s_nop 1
	v_add_f32_dpp v35, v35, v35 row_mirror row_mask:0xf bank_mask:0xf bound_ctrl:1
	s_nop 1
	v_mov_b32_dpp v36, v35 row_bcast:15 row_mask:0xa bank_mask:0xf
	v_add_f32_e32 v35, v35, v36
	v_mov_b32_e32 v36, v131
	s_nop 1
	v_mov_b32_dpp v36, v35 row_bcast:31 row_mask:0xc bank_mask:0xf
	v_add_f32_e32 v35, v35, v36
	s_nop 0
	v_readlane_b32 s7, v35, 63
	s_xor_b32 s7, s7, 0x80000000
	s_nop 0
	v_pk_fma_f32 v[34:35], s[6:7], v[20:21], v[32:33] op_sel_hi:[1,0,1]
	v_pk_fma_f32 v[32:33], s[6:7], v[20:21], v[40:41] op_sel_hi:[1,0,1]
	global_load_ushort v46, v38, s[54:55] offset:512
	global_load_ushort v50, v38, s[54:55] offset:640
	global_load_ushort v71, v38, s[54:55] offset:768
	global_load_ushort v76, v38, s[54:55] offset:896
	global_load_ushort v47, v38, s[46:47] offset:512
	global_load_ushort v51, v38, s[46:47] offset:640
	global_load_ushort v72, v38, s[46:47] offset:768
	global_load_ushort v77, v38, s[46:47] offset:896
	global_load_ushort v39, v38, s[56:57] offset:512
	global_load_ushort v48, v38, s[56:57] offset:640
	global_load_ushort v52, v38, s[56:57] offset:768
	global_load_ushort v74, v38, s[56:57] offset:896
	global_load_ushort v40, v38, s[48:49] offset:512
	global_load_ushort v49, v38, s[48:49] offset:640
	global_load_ushort v53, v38, s[48:49] offset:768
	global_load_ushort v75, v38, s[48:49] offset:896
	global_load_ushort v60, v38, s[50:51] offset:512
	global_load_ushort v62, v38, s[50:51] offset:640
	global_load_ushort v67, v38, s[50:51] offset:768
	global_load_ushort v58, v38, s[50:51] offset:896
	global_load_ushort v61, v38, s[42:43] offset:512
	global_load_ushort v63, v38, s[42:43] offset:640
	global_load_ushort v68, v38, s[42:43] offset:768
	global_load_ushort v59, v38, s[42:43] offset:896
	global_load_ushort v54, v38, s[52:53] offset:512
	global_load_ushort v56, v38, s[52:53] offset:640
	global_load_ushort v69, v38, s[52:53] offset:768
	global_load_ushort v64, v38, s[52:53] offset:896
	global_load_ushort v55, v38, s[44:45] offset:512
	global_load_ushort v57, v38, s[44:45] offset:640
	global_load_ushort v70, v38, s[44:45] offset:768
	global_load_ushort v65, v38, s[44:45] offset:896
	v_pk_fma_f32 v[36:37], s[6:7], v[20:21], v[30:31] op_sel_hi:[1,0,1]
	v_pk_fma_f32 v[30:31], s[6:7], v[20:21], v[42:43] op_sel_hi:[1,0,1]
	s_load_dwordx2 s[42:43], s[0:1], 0x30
	s_load_dwordx4 s[52:55], s[0:1], 0x18
	s_waitcnt vmcnt(23)
	v_lshlrev_b32_e32 v39, 16, v39
	v_fma_f32 v41, |v39|, s92, 1.0
	v_rcp_f32_e32 v41, v41
	v_mul_f32_e32 v43, v39, v39
	s_waitcnt vmcnt(19)
	v_lshlrev_b32_e32 v38, 16, v40
	v_fma_f32 v40, |v38|, s92, 1.0
	v_rcp_f32_e32 v40, v40
	v_mul_f32_e32 v42, v38, v38
	v_mul_f32_e32 v42, 0xbf38aa3b, v42
	v_mul_f32_e32 v43, 0xbf38aa3b, v43
	v_pk_fma_f32 v[44:45], v[40:41], s[10:11], v[18:19] op_sel_hi:[1,0,0]
	v_exp_f32_e32 v42, v42
	v_pk_fma_f32 v[44:45], v[40:41], v[44:45], s[14:15] op_sel_hi:[1,1,0]
	v_exp_f32_e32 v43, v43
	v_pk_fma_f32 v[44:45], v[40:41], v[44:45], s[16:17] op_sel_hi:[1,1,0]
	v_cmp_gt_f32_e32 vcc, 0, v39
	v_pk_fma_f32 v[44:45], v[40:41], v[44:45], s[18:19] op_sel_hi:[1,1,0]
	s_waitcnt vmcnt(9)
	v_lshlrev_b32_e32 v68, 16, v68
	v_pk_mul_f32 v[40:41], v[40:41], v[44:45]
	s_waitcnt vmcnt(1)
	v_lshlrev_b32_e32 v70, 16, v70
	v_pk_mul_f32 v[40:41], v[42:43], v[40:41]
	v_pk_mul_f32 v[42:43], v[40:41], v[38:39]
	v_pk_fma_f32 v[40:41], v[40:41], v[38:39], v[38:39] neg_lo:[1,0,0] neg_hi:[1,0,0]
	s_nop 0
	v_cndmask_b32_e32 v39, v41, v43, vcc
	v_cmp_gt_f32_e32 vcc, 0, v38
	v_lshlrev_b32_e32 v41, 16, v46
	v_mul_f32_e32 v45, v41, v41
	v_cndmask_b32_e32 v38, v40, v42, vcc
	v_lshlrev_b32_e32 v40, 16, v47
	v_mul_f32_e32 v43, v40, v40
	v_mul_f32_e32 v43, 0xbf38aa3b, v43
	v_fma_f32 v42, |v40|, s92, 1.0
	v_exp_f32_e32 v44, v43
	v_fma_f32 v43, |v41|, s92, 1.0
	v_rcp_f32_e32 v42, v42
	v_rcp_f32_e32 v43, v43
	v_mul_f32_e32 v45, 0xbf38aa3b, v45
	v_exp_f32_e32 v45, v45
	v_cmp_gt_f32_e32 vcc, 0, v41
	v_pk_fma_f32 v[46:47], v[42:43], s[10:11], v[18:19] op_sel_hi:[1,0,0]
	s_nop 0
	v_pk_fma_f32 v[46:47], v[42:43], v[46:47], s[14:15] op_sel_hi:[1,1,0]
	s_nop 0
	v_pk_fma_f32 v[46:47], v[42:43], v[46:47], s[16:17] op_sel_hi:[1,1,0]
	s_nop 0
	v_pk_fma_f32 v[46:47], v[42:43], v[46:47], s[18:19] op_sel_hi:[1,1,0]
	v_pk_mul_f32 v[42:43], v[42:43], v[46:47]
	v_pk_mul_f32 v[42:43], v[44:45], v[42:43]
	v_pk_mul_f32 v[44:45], v[42:43], v[40:41]
	v_pk_fma_f32 v[42:43], v[42:43], v[40:41], v[40:41] neg_lo:[1,0,0] neg_hi:[1,0,0]
	v_lshlrev_b32_e32 v41, 16, v48
	v_cndmask_b32_e32 v47, v43, v45, vcc
	v_cmp_gt_f32_e32 vcc, 0, v40
	v_lshlrev_b32_e32 v40, 16, v49
	v_fma_f32 v43, |v41|, s92, 1.0
	v_cndmask_b32_e32 v46, v42, v44, vcc
	v_fma_f32 v42, |v40|, s92, 1.0
	v_rcp_f32_e32 v42, v42
	v_rcp_f32_e32 v43, v43
	v_mul_f32_e32 v44, v40, v40
	v_mul_f32_e32 v45, v41, v41
	v_mul_f32_e32 v44, 0xbf38aa3b, v44
	v_pk_fma_f32 v[48:49], v[42:43], s[10:11], v[18:19] op_sel_hi:[1,0,0]
	v_mul_f32_e32 v45, 0xbf38aa3b, v45
	v_exp_f32_e32 v44, v44
	v_pk_fma_f32 v[48:49], v[42:43], v[48:49], s[14:15] op_sel_hi:[1,1,0]
	v_exp_f32_e32 v45, v45
	v_pk_fma_f32 v[48:49], v[42:43], v[48:49], s[16:17] op_sel_hi:[1,1,0]
	v_cmp_gt_f32_e32 vcc, 0, v41
	v_pk_fma_f32 v[48:49], v[42:43], v[48:49], s[18:19] op_sel_hi:[1,1,0]
	s_nop 0
	v_pk_mul_f32 v[42:43], v[42:43], v[48:49]
	v_pk_mul_f32 v[42:43], v[44:45], v[42:43]
	v_pk_mul_f32 v[44:45], v[42:43], v[40:41]
	v_pk_fma_f32 v[42:43], v[42:43], v[40:41], v[40:41] neg_lo:[1,0,0] neg_hi:[1,0,0]
	v_lshlrev_b32_e32 v41, 16, v50
	v_cndmask_b32_e32 v43, v43, v45, vcc
	v_cmp_gt_f32_e32 vcc, 0, v40
	v_lshlrev_b32_e32 v40, 16, v51
	v_mul_f32_e32 v45, v40, v40
	v_mul_f32_e32 v45, 0xbf38aa3b, v45
	v_cndmask_b32_e32 v42, v42, v44, vcc
	v_fma_f32 v44, |v40|, s92, 1.0
	v_exp_f32_e32 v48, v45
	v_fma_f32 v45, |v41|, s92, 1.0
	v_rcp_f32_e32 v44, v44
	v_rcp_f32_e32 v45, v45
	v_mul_f32_e32 v49, v41, v41
	v_mul_f32_e32 v49, 0xbf38aa3b, v49
	v_exp_f32_e32 v49, v49
	v_pk_fma_f32 v[50:51], v[44:45], s[10:11], v[18:19] op_sel_hi:[1,0,0]
	v_cmp_gt_f32_e32 vcc, 0, v41
	v_pk_fma_f32 v[50:51], v[44:45], v[50:51], s[14:15] op_sel_hi:[1,1,0]
	s_nop 0
	v_pk_fma_f32 v[50:51], v[44:45], v[50:51], s[16:17] op_sel_hi:[1,1,0]
	s_nop 0
	v_pk_fma_f32 v[50:51], v[44:45], v[50:51], s[18:19] op_sel_hi:[1,1,0]
	v_pk_mul_f32 v[44:45], v[44:45], v[50:51]
	v_pk_mul_f32 v[44:45], v[48:49], v[44:45]
	v_pk_mul_f32 v[48:49], v[44:45], v[40:41]
	v_pk_fma_f32 v[44:45], v[44:45], v[40:41], v[40:41] neg_lo:[1,0,0] neg_hi:[1,0,0]
	v_lshlrev_b32_e32 v41, 16, v52
	v_cndmask_b32_e32 v49, v45, v49, vcc
	v_cmp_gt_f32_e32 vcc, 0, v40
	v_lshlrev_b32_e32 v40, 16, v53
	v_fma_f32 v45, |v41|, s92, 1.0
	v_cndmask_b32_e32 v48, v44, v48, vcc
	v_fma_f32 v44, |v40|, s92, 1.0
	v_rcp_f32_e32 v44, v44
	v_rcp_f32_e32 v45, v45
	v_mul_f32_e32 v50, v40, v40
	v_mul_f32_e32 v51, v41, v41
	v_mul_f32_e32 v50, 0xbf38aa3b, v50
	v_pk_fma_f32 v[52:53], v[44:45], s[10:11], v[18:19] op_sel_hi:[1,0,0]
	v_mul_f32_e32 v51, 0xbf38aa3b, v51
	v_exp_f32_e32 v50, v50
	v_pk_fma_f32 v[52:53], v[44:45], v[52:53], s[14:15] op_sel_hi:[1,1,0]
	v_exp_f32_e32 v51, v51
	v_pk_fma_f32 v[52:53], v[44:45], v[52:53], s[16:17] op_sel_hi:[1,1,0]
	v_cmp_gt_f32_e32 vcc, 0, v41
	v_pk_fma_f32 v[52:53], v[44:45], v[52:53], s[18:19] op_sel_hi:[1,1,0]
	s_nop 0
	v_pk_mul_f32 v[44:45], v[44:45], v[52:53]
	v_pk_mul_f32 v[44:45], v[50:51], v[44:45]
	v_pk_mul_f32 v[50:51], v[44:45], v[40:41]
	v_pk_fma_f32 v[44:45], v[44:45], v[40:41], v[40:41] neg_lo:[1,0,0] neg_hi:[1,0,0]
	v_lshlrev_b32_e32 v41, 16, v71
	v_cndmask_b32_e32 v51, v45, v51, vcc
	v_cmp_gt_f32_e32 vcc, 0, v40
	v_lshlrev_b32_e32 v40, 16, v72
	v_mul_f32_e32 v45, v40, v40
	v_mul_f32_e32 v45, 0xbf38aa3b, v45
	v_cndmask_b32_e32 v50, v44, v50, vcc
	v_fma_f32 v44, |v40|, s92, 1.0
	v_exp_f32_e32 v52, v45
	v_fma_f32 v45, |v41|, s92, 1.0
	v_rcp_f32_e32 v44, v44
	v_rcp_f32_e32 v45, v45
	v_mul_f32_e32 v53, v41, v41
	v_mul_f32_e32 v53, 0xbf38aa3b, v53
	v_exp_f32_e32 v53, v53
	v_pk_fma_f32 v[72:73], v[44:45], s[10:11], v[18:19] op_sel_hi:[1,0,0]
	v_cmp_gt_f32_e32 vcc, 0, v41
	v_pk_fma_f32 v[72:73], v[44:45], v[72:73], s[14:15] op_sel_hi:[1,1,0]
	s_nop 0
	v_pk_fma_f32 v[72:73], v[44:45], v[72:73], s[16:17] op_sel_hi:[1,1,0]
	s_nop 0
	v_pk_fma_f32 v[72:73], v[44:45], v[72:73], s[18:19] op_sel_hi:[1,1,0]
	v_pk_mul_f32 v[44:45], v[44:45], v[72:73]
	v_pk_mul_f32 v[44:45], v[52:53], v[44:45]
	v_pk_mul_f32 v[52:53], v[44:45], v[40:41]
	v_pk_fma_f32 v[44:45], v[44:45], v[40:41], v[40:41] neg_lo:[1,0,0] neg_hi:[1,0,0]
	v_lshlrev_b32_e32 v41, 16, v74
	v_cndmask_b32_e32 v73, v45, v53, vcc
	v_cmp_gt_f32_e32 vcc, 0, v40
	v_lshlrev_b32_e32 v40, 16, v75
	v_fma_f32 v45, |v41|, s92, 1.0
	v_cndmask_b32_e32 v72, v44, v52, vcc
	v_fma_f32 v44, |v40|, s92, 1.0
	v_rcp_f32_e32 v44, v44
	v_rcp_f32_e32 v45, v45
	v_mul_f32_e32 v52, v40, v40
	v_mul_f32_e32 v53, v41, v41
	v_mul_f32_e32 v52, 0xbf38aa3b, v52
	v_pk_fma_f32 v[74:75], v[44:45], s[10:11], v[18:19] op_sel_hi:[1,0,0]
	v_mul_f32_e32 v53, 0xbf38aa3b, v53
	v_exp_f32_e32 v52, v52
	v_pk_fma_f32 v[74:75], v[44:45], v[74:75], s[14:15] op_sel_hi:[1,1,0]
	v_exp_f32_e32 v53, v53
	v_pk_fma_f32 v[74:75], v[44:45], v[74:75], s[16:17] op_sel_hi:[1,1,0]
	v_cmp_gt_f32_e32 vcc, 0, v41
	v_pk_fma_f32 v[74:75], v[44:45], v[74:75], s[18:19] op_sel_hi:[1,1,0]
	s_nop 0
	v_pk_mul_f32 v[44:45], v[44:45], v[74:75]
	v_pk_mul_f32 v[44:45], v[52:53], v[44:45]
	v_pk_mul_f32 v[52:53], v[44:45], v[40:41]
	v_pk_fma_f32 v[44:45], v[44:45], v[40:41], v[40:41] neg_lo:[1,0,0] neg_hi:[1,0,0]
	v_lshlrev_b32_e32 v41, 16, v76
	v_cndmask_b32_e32 v53, v45, v53, vcc
	v_cmp_gt_f32_e32 vcc, 0, v40
	v_lshlrev_b32_e32 v40, 16, v77
	v_mul_f32_e32 v45, v40, v40
	v_mul_f32_e32 v45, 0xbf38aa3b, v45
	v_cndmask_b32_e32 v52, v44, v52, vcc
	v_fma_f32 v44, |v40|, s92, 1.0
	v_exp_f32_e32 v74, v45
	v_fma_f32 v45, |v41|, s92, 1.0
	v_rcp_f32_e32 v44, v44
	v_rcp_f32_e32 v45, v45
	v_mul_f32_e32 v71, v41, v41
	v_mul_f32_e32 v71, 0xbf38aa3b, v71
	v_exp_f32_e32 v75, v71
	v_pk_fma_f32 v[76:77], v[44:45], s[10:11], v[18:19] op_sel_hi:[1,0,0]
	v_cmp_gt_f32_e32 vcc, 0, v41
	v_pk_fma_f32 v[76:77], v[44:45], v[76:77], s[14:15] op_sel_hi:[1,1,0]
	s_nop 0
	v_pk_fma_f32 v[76:77], v[44:45], v[76:77], s[16:17] op_sel_hi:[1,1,0]
	s_nop 0
	v_pk_fma_f32 v[76:77], v[44:45], v[76:77], s[18:19] op_sel_hi:[1,1,0]
	v_pk_mul_f32 v[44:45], v[44:45], v[76:77]
	v_mov_b32_e32 v76, v43
	v_pk_mul_f32 v[44:45], v[74:75], v[44:45]
	v_mov_b32_e32 v77, v53
	v_pk_mul_f32 v[74:75], v[44:45], v[40:41]
	v_pk_fma_f32 v[44:45], v[44:45], v[40:41], v[40:41] neg_lo:[1,0,0] neg_hi:[1,0,0]
	v_mov_b32_e32 v41, v50
	v_cndmask_b32_e32 v75, v45, v75, vcc
	v_cmp_gt_f32_e32 vcc, 0, v40
	v_mov_b32_e32 v40, v38
	v_mov_b32_e32 v45, v52
	v_cndmask_b32_e32 v74, v44, v74, vcc
	v_mov_b32_e32 v44, v42
	v_pk_add_f32 v[40:41], v[40:41], v[44:45]
	v_mov_b32_e32 v44, v39
	v_add_f32_e32 v40, v40, v41
	v_mov_b32_e32 v41, v131
	v_mov_b32_e32 v45, v51
	v_add_f32_dpp v40, v40, v40 quad_perm:[1,0,3,2] row_mask:0xf bank_mask:0xf bound_ctrl:1
	v_pk_add_f32 v[44:45], v[44:45], v[76:77]
	v_mov_b32_e32 v76, v49
	v_add_f32_dpp v40, v40, v40 quad_perm:[2,3,0,1] row_mask:0xf bank_mask:0xf bound_ctrl:1
	v_mov_b32_e32 v77, v75
	s_nop 0
	v_add_f32_dpp v40, v40, v40 row_half_mirror row_mask:0xf bank_mask:0xf bound_ctrl:1
	s_nop 1
	v_add_f32_dpp v40, v40, v40 row_mirror row_mask:0xf bank_mask:0xf bound_ctrl:1
	s_nop 1
	v_mov_b32_dpp v41, v40 row_bcast:15 row_mask:0xa bank_mask:0xf
	v_add_f32_e32 v40, v40, v41
	v_mov_b32_e32 v41, v131
	s_nop 1
	v_mov_b32_dpp v41, v40 row_bcast:31 row_mask:0xc bank_mask:0xf
	v_add_f32_e32 v40, v40, v41
	v_add_f32_e32 v41, v44, v45
	v_mov_b32_e32 v44, v131
	v_readlane_b32 s6, v40, 63
	v_add_f32_dpp v41, v41, v41 quad_perm:[1,0,3,2] row_mask:0xf bank_mask:0xf bound_ctrl:1
	s_xor_b32 s6, s6, 0x80000000
	s_nop 0
	v_add_f32_dpp v41, v41, v41 quad_perm:[2,3,0,1] row_mask:0xf bank_mask:0xf bound_ctrl:1
	s_nop 1
	v_add_f32_dpp v41, v41, v41 row_half_mirror row_mask:0xf bank_mask:0xf bound_ctrl:1
	s_nop 1
	v_add_f32_dpp v41, v41, v41 row_mirror row_mask:0xf bank_mask:0xf bound_ctrl:1
	s_nop 1
	v_mov_b32_dpp v44, v41 row_bcast:15 row_mask:0xa bank_mask:0xf
	v_add_f32_e32 v41, v41, v44
	v_mov_b32_e32 v44, v131
	s_nop 1
	v_mov_b32_dpp v44, v41 row_bcast:31 row_mask:0xc bank_mask:0xf
	v_add_f32_e32 v41, v41, v44
	s_nop 0
	v_readlane_b32 s7, v41, 63
	s_xor_b32 s7, s7, 0x80000000
	s_nop 0
	v_pk_fma_f32 v[40:41], s[6:7], v[20:21], v[38:39] op_sel_hi:[1,0,1]
	v_pk_fma_f32 v[44:45], s[6:7], v[20:21], v[42:43] op_sel_hi:[1,0,1]
	v_pk_fma_f32 v[42:43], s[6:7], v[20:21], v[50:51] op_sel_hi:[1,0,1]
	v_pk_fma_f32 v[38:39], s[6:7], v[20:21], v[52:53] op_sel_hi:[1,0,1]
	v_mov_b32_e32 v50, v46
	v_mov_b32_e32 v51, v72
	v_mov_b32_e32 v52, v48
	v_mov_b32_e32 v53, v74
	v_pk_add_f32 v[50:51], v[50:51], v[52:53]
	v_mov_b32_e32 v52, v47
	v_add_f32_e32 v50, v50, v51
	v_mov_b32_e32 v51, v131
	v_mov_b32_e32 v53, v73
	v_add_f32_dpp v50, v50, v50 quad_perm:[1,0,3,2] row_mask:0xf bank_mask:0xf bound_ctrl:1
	v_pk_add_f32 v[52:53], v[52:53], v[76:77]
	s_nop 0
	v_add_f32_dpp v50, v50, v50 quad_perm:[2,3,0,1] row_mask:0xf bank_mask:0xf bound_ctrl:1
	s_nop 1
	v_add_f32_dpp v50, v50, v50 row_half_mirror row_mask:0xf bank_mask:0xf bound_ctrl:1
	s_nop 1
	v_add_f32_dpp v50, v50, v50 row_mirror row_mask:0xf bank_mask:0xf bound_ctrl:1
	s_nop 1
	v_mov_b32_dpp v51, v50 row_bcast:15 row_mask:0xa bank_mask:0xf
	v_add_f32_e32 v50, v50, v51
	v_mov_b32_e32 v51, v131
	s_nop 1
	v_mov_b32_dpp v51, v50 row_bcast:31 row_mask:0xc bank_mask:0xf
	v_add_f32_e32 v50, v50, v51
	v_add_f32_e32 v51, v52, v53
	v_mov_b32_e32 v52, v131
	v_readlane_b32 s6, v50, 63
	v_add_f32_dpp v51, v51, v51 quad_perm:[1,0,3,2] row_mask:0xf bank_mask:0xf bound_ctrl:1
	s_xor_b32 s6, s6, 0x80000000
	s_nop 0
	v_add_f32_dpp v51, v51, v51 quad_perm:[2,3,0,1] row_mask:0xf bank_mask:0xf bound_ctrl:1
	s_nop 1
	v_add_f32_dpp v51, v51, v51 row_half_mirror row_mask:0xf bank_mask:0xf bound_ctrl:1
	s_nop 1
	v_add_f32_dpp v51, v51, v51 row_mirror row_mask:0xf bank_mask:0xf bound_ctrl:1
	s_nop 1
	v_mov_b32_dpp v52, v51 row_bcast:15 row_mask:0xa bank_mask:0xf
	v_add_f32_e32 v51, v51, v52
	v_mov_b32_e32 v52, v131
	s_nop 1
	v_mov_b32_dpp v52, v51 row_bcast:31 row_mask:0xc bank_mask:0xf
	v_add_f32_e32 v51, v51, v52
	s_nop 0
	v_readlane_b32 s7, v51, 63
	s_xor_b32 s7, s7, 0x80000000
	s_nop 0
	v_pk_fma_f32 v[50:51], s[6:7], v[20:21], v[48:49] op_sel_hi:[1,0,1]
	v_pk_fma_f32 v[48:49], s[6:7], v[20:21], v[72:73] op_sel_hi:[1,0,1]
	v_lshlrev_b32_e32 v73, 16, v54
	v_lshlrev_b32_e32 v72, 16, v55
	v_fma_f32 v54, |v72|, s92, 1.0
	v_fma_f32 v55, |v73|, s92, 1.0
	v_rcp_f32_e32 v54, v54
	v_rcp_f32_e32 v55, v55
	v_mul_f32_e32 v71, v72, v72
	v_mul_f32_e32 v71, 0xbf38aa3b, v71
	v_pk_fma_f32 v[52:53], s[6:7], v[20:21], v[46:47] op_sel_hi:[1,0,1]
	v_pk_fma_f32 v[46:47], s[6:7], v[20:21], v[74:75] op_sel_hi:[1,0,1]
	v_exp_f32_e32 v74, v71
	v_mul_f32_e32 v71, v73, v73
	v_pk_fma_f32 v[76:77], v[54:55], s[10:11], v[18:19] op_sel_hi:[1,0,0]
	v_mul_f32_e32 v71, 0xbf38aa3b, v71
	v_pk_fma_f32 v[76:77], v[54:55], v[76:77], s[14:15] op_sel_hi:[1,1,0]
	v_exp_f32_e32 v75, v71
	v_pk_fma_f32 v[76:77], v[54:55], v[76:77], s[16:17] op_sel_hi:[1,1,0]
	v_cmp_gt_f32_e32 vcc, 0, v73
	v_pk_fma_f32 v[76:77], v[54:55], v[76:77], s[18:19] op_sel_hi:[1,1,0]
	s_mov_b32 s6, 0xbe11a98e
	v_pk_mul_f32 v[54:55], v[54:55], v[76:77]
	v_pk_mul_f32 v[54:55], v[74:75], v[54:55]
	v_pk_mul_f32 v[74:75], v[54:55], v[72:73]
	v_pk_fma_f32 v[54:55], v[54:55], v[72:73], v[72:73] neg_lo:[1,0,0] neg_hi:[1,0,0]
	v_lshlrev_b32_e32 v73, 16, v60
	v_cndmask_b32_e32 v55, v55, v75, vcc
	v_cmp_gt_f32_e32 vcc, 0, v72
	v_lshlrev_b32_e32 v72, 16, v61
	v_mul_f32_e32 v61, v72, v72
	v_mul_f32_e32 v61, 0xbf38aa3b, v61
	v_cndmask_b32_e32 v54, v54, v74, vcc
	v_fma_f32 v60, |v72|, s92, 1.0
	v_exp_f32_e32 v74, v61
	v_fma_f32 v61, |v73|, s92, 1.0
	v_rcp_f32_e32 v60, v60
	v_rcp_f32_e32 v61, v61
	v_mul_f32_e32 v71, v73, v73
	v_mul_f32_e32 v71, 0xbf38aa3b, v71
	v_exp_f32_e32 v75, v71
	v_pk_fma_f32 v[76:77], v[60:61], s[10:11], v[18:19] op_sel_hi:[1,0,0]
	v_cmp_gt_f32_e32 vcc, 0, v73
	v_pk_fma_f32 v[76:77], v[60:61], v[76:77], s[14:15] op_sel_hi:[1,1,0]
	s_nop 0
	v_pk_fma_f32 v[76:77], v[60:61], v[76:77], s[16:17] op_sel_hi:[1,1,0]
	s_nop 0
	v_pk_fma_f32 v[76:77], v[60:61], v[76:77], s[18:19] op_sel_hi:[1,1,0]
	v_pk_mul_f32 v[60:61], v[60:61], v[76:77]
	v_pk_mul_f32 v[60:61], v[74:75], v[60:61]
	v_pk_mul_f32 v[74:75], v[60:61], v[72:73]
	v_pk_fma_f32 v[60:61], v[60:61], v[72:73], v[72:73] neg_lo:[1,0,0] neg_hi:[1,0,0]
	v_lshlrev_b32_e32 v73, 16, v56
	v_cndmask_b32_e32 v61, v61, v75, vcc
	v_cmp_gt_f32_e32 vcc, 0, v72
	v_lshlrev_b32_e32 v72, 16, v57
	v_fma_f32 v56, |v72|, s92, 1.0
	v_fma_f32 v57, |v73|, s92, 1.0
	v_rcp_f32_e32 v56, v56
	v_rcp_f32_e32 v57, v57
	v_mul_f32_e32 v71, v72, v72
	v_mul_f32_e32 v71, 0xbf38aa3b, v71
	v_cndmask_b32_e32 v60, v60, v74, vcc
	v_exp_f32_e32 v74, v71
	v_mul_f32_e32 v71, v73, v73
	v_pk_fma_f32 v[76:77], v[56:57], s[10:11], v[18:19] op_sel_hi:[1,0,0]
	v_mul_f32_e32 v71, 0xbf38aa3b, v71
	v_pk_fma_f32 v[76:77], v[56:57], v[76:77], s[14:15] op_sel_hi:[1,1,0]
	v_exp_f32_e32 v75, v71
	v_pk_fma_f32 v[76:77], v[56:57], v[76:77], s[16:17] op_sel_hi:[1,1,0]
	v_cmp_gt_f32_e32 vcc, 0, v73
	v_pk_fma_f32 v[76:77], v[56:57], v[76:77], s[18:19] op_sel_hi:[1,1,0]
	s_nop 0
	v_pk_mul_f32 v[56:57], v[56:57], v[76:77]
	v_pk_mul_f32 v[56:57], v[74:75], v[56:57]
	v_pk_mul_f32 v[74:75], v[56:57], v[72:73]
	v_pk_fma_f32 v[56:57], v[56:57], v[72:73], v[72:73] neg_lo:[1,0,0] neg_hi:[1,0,0]
	v_lshlrev_b32_e32 v73, 16, v62
	v_cndmask_b32_e32 v57, v57, v75, vcc
	v_cmp_gt_f32_e32 vcc, 0, v72
	v_lshlrev_b32_e32 v72, 16, v63
	v_mul_f32_e32 v63, v72, v72
	v_mul_f32_e32 v63, 0xbf38aa3b, v63
	v_cndmask_b32_e32 v56, v56, v74, vcc
	v_fma_f32 v62, |v72|, s92, 1.0
	v_exp_f32_e32 v74, v63
	v_fma_f32 v63, |v73|, s92, 1.0
	v_rcp_f32_e32 v62, v62
	v_rcp_f32_e32 v63, v63
	v_mul_f32_e32 v71, v73, v73
	v_mul_f32_e32 v71, 0xbf38aa3b, v71
	v_exp_f32_e32 v75, v71
	v_pk_fma_f32 v[76:77], v[62:63], s[10:11], v[18:19] op_sel_hi:[1,0,0]
	v_cmp_gt_f32_e32 vcc, 0, v73
	v_pk_fma_f32 v[76:77], v[62:63], v[76:77], s[14:15] op_sel_hi:[1,1,0]
	v_lshlrev_b32_e32 v71, 16, v69
	v_pk_fma_f32 v[76:77], v[62:63], v[76:77], s[16:17] op_sel_hi:[1,1,0]
	v_fma_f32 v69, |v70|, s92, 1.0
	v_pk_fma_f32 v[76:77], v[62:63], v[76:77], s[18:19] op_sel_hi:[1,1,0]
	v_pk_mul_f32 v[62:63], v[62:63], v[76:77]
	v_pk_mul_f32 v[62:63], v[74:75], v[62:63]
	v_pk_mul_f32 v[74:75], v[62:63], v[72:73]
	v_pk_fma_f32 v[62:63], v[62:63], v[72:73], v[72:73] neg_lo:[1,0,0] neg_hi:[1,0,0]
	s_nop 0
	v_cndmask_b32_e32 v63, v63, v75, vcc
	v_cmp_gt_f32_e32 vcc, 0, v72
	v_rcp_f32_e32 v72, v69
	v_fma_f32 v69, |v71|, s92, 1.0
	v_rcp_f32_e32 v73, v69
	v_mul_f32_e32 v69, v70, v70
	v_mul_f32_e32 v69, 0xbf38aa3b, v69
	v_cndmask_b32_e32 v62, v62, v74, vcc
	v_exp_f32_e32 v74, v69
	v_mul_f32_e32 v69, v71, v71
	v_pk_fma_f32 v[76:77], v[72:73], s[10:11], v[18:19] op_sel_hi:[1,0,0]
	v_mul_f32_e32 v69, 0xbf38aa3b, v69
	v_pk_fma_f32 v[76:77], v[72:73], v[76:77], s[14:15] op_sel_hi:[1,1,0]
	v_exp_f32_e32 v75, v69
	v_pk_fma_f32 v[76:77], v[72:73], v[76:77], s[16:17] op_sel_hi:[1,1,0]
	v_cmp_gt_f32_e32 vcc, 0, v71
	v_pk_fma_f32 v[76:77], v[72:73], v[76:77], s[18:19] op_sel_hi:[1,1,0]
	v_lshlrev_b32_e32 v69, 16, v67
	v_pk_mul_f32 v[72:73], v[72:73], v[76:77]
	v_fma_f32 v67, |v68|, s92, 1.0
	v_pk_mul_f32 v[72:73], v[74:75], v[72:73]
	v_pk_mul_f32 v[74:75], v[72:73], v[70:71]
	v_pk_fma_f32 v[72:73], v[72:73], v[70:71], v[70:71] neg_lo:[1,0,0] neg_hi:[1,0,0]
	s_nop 0
	v_cndmask_b32_e32 v71, v73, v75, vcc
	v_cmp_gt_f32_e32 vcc, 0, v70
	s_nop 1
	v_cndmask_b32_e32 v70, v72, v74, vcc
	v_rcp_f32_e32 v72, v67
	v_mul_f32_e32 v67, v68, v68
	v_mul_f32_e32 v67, 0xbf38aa3b, v67
	v_exp_f32_e32 v74, v67
	v_fma_f32 v67, |v69|, s92, 1.0
	v_rcp_f32_e32 v73, v67
	v_mul_f32_e32 v67, v69, v69
	v_mul_f32_e32 v67, 0xbf38aa3b, v67
	v_exp_f32_e32 v75, v67
	v_pk_fma_f32 v[76:77], v[72:73], s[10:11], v[18:19] op_sel_hi:[1,0,0]
	v_cmp_gt_f32_e32 vcc, 0, v69
	v_pk_fma_f32 v[76:77], v[72:73], v[76:77], s[14:15] op_sel_hi:[1,1,0]
	s_nop 0
	v_pk_fma_f32 v[76:77], v[72:73], v[76:77], s[16:17] op_sel_hi:[1,1,0]
	s_nop 0
	v_pk_fma_f32 v[76:77], v[72:73], v[76:77], s[18:19] op_sel_hi:[1,1,0]
	v_pk_mul_f32 v[72:73], v[72:73], v[76:77]
	v_pk_mul_f32 v[72:73], v[74:75], v[72:73]
	v_pk_mul_f32 v[74:75], v[72:73], v[68:69]
	v_pk_fma_f32 v[72:73], v[72:73], v[68:69], v[68:69] neg_lo:[1,0,0] neg_hi:[1,0,0]
	s_nop 0
	v_cndmask_b32_e32 v69, v73, v75, vcc
	v_cmp_gt_f32_e32 vcc, 0, v68
	v_lshlrev_b32_e32 v73, 16, v64
	s_nop 0
	v_cndmask_b32_e32 v68, v72, v74, vcc
	s_waitcnt vmcnt(0)
	v_lshlrev_b32_e32 v72, 16, v65
	v_fma_f32 v64, |v72|, s92, 1.0
	v_fma_f32 v65, |v73|, s92, 1.0
	v_rcp_f32_e32 v64, v64
	v_rcp_f32_e32 v65, v65
	v_mul_f32_e32 v67, v72, v72
	v_mul_f32_e32 v67, 0xbf38aa3b, v67
	v_exp_f32_e32 v74, v67
	v_mul_f32_e32 v67, v73, v73
	v_pk_fma_f32 v[76:77], v[64:65], s[10:11], v[18:19] op_sel_hi:[1,0,0]
	v_mul_f32_e32 v67, 0xbf38aa3b, v67
	v_pk_fma_f32 v[76:77], v[64:65], v[76:77], s[14:15] op_sel_hi:[1,1,0]
	v_exp_f32_e32 v75, v67
	v_pk_fma_f32 v[76:77], v[64:65], v[76:77], s[16:17] op_sel_hi:[1,1,0]
	v_cmp_gt_f32_e32 vcc, 0, v73
	v_pk_fma_f32 v[76:77], v[64:65], v[76:77], s[18:19] op_sel_hi:[1,1,0]
	s_nop 0
	v_pk_mul_f32 v[64:65], v[64:65], v[76:77]
	v_pk_mul_f32 v[64:65], v[74:75], v[64:65]
	v_pk_mul_f32 v[74:75], v[64:65], v[72:73]
	v_pk_fma_f32 v[64:65], v[64:65], v[72:73], v[72:73] neg_lo:[1,0,0] neg_hi:[1,0,0]
	v_lshlrev_b32_e32 v73, 16, v58
	v_cndmask_b32_e32 v65, v65, v75, vcc
	v_cmp_gt_f32_e32 vcc, 0, v72
	v_lshlrev_b32_e32 v72, 16, v59
	v_mul_f32_e32 v59, v72, v72
	v_mul_f32_e32 v59, 0xbf38aa3b, v59
	v_cndmask_b32_e32 v64, v64, v74, vcc
	v_fma_f32 v58, |v72|, s92, 1.0
	v_exp_f32_e32 v74, v59
	v_fma_f32 v59, |v73|, s92, 1.0
	v_rcp_f32_e32 v58, v58
	v_rcp_f32_e32 v59, v59
	v_mul_f32_e32 v67, v73, v73
	v_mul_f32_e32 v67, 0xbf38aa3b, v67
	v_exp_f32_e32 v75, v67
	v_pk_fma_f32 v[18:19], v[58:59], s[10:11], v[18:19] op_sel_hi:[1,0,0]
	v_cmp_gt_f32_e32 vcc, 0, v73
	v_pk_fma_f32 v[18:19], v[58:59], v[18:19], s[14:15] op_sel_hi:[1,1,0]
	v_mov_b32_e32 v67, v131
	v_pk_fma_f32 v[18:19], v[58:59], v[18:19], s[6:7] op_sel_hi:[1,1,0]
	s_nop 0
	v_pk_fma_f32 v[18:19], v[58:59], v[18:19], s[8:9] op_sel_hi:[1,1,0]
	v_readlane_b32 s9, v253, 54
	v_pk_mul_f32 v[18:19], v[58:59], v[18:19]
	s_nop 0
	v_pk_mul_f32 v[18:19], v[74:75], v[18:19]
	v_mov_b32_e32 v74, v57
	v_pk_mul_f32 v[58:59], v[18:19], v[72:73]
	v_pk_fma_f32 v[18:19], v[18:19], v[72:73], v[72:73] neg_lo:[1,0,0] neg_hi:[1,0,0]
	v_mov_b32_e32 v75, v65
	v_cndmask_b32_e32 v73, v19, v59, vcc
	v_cmp_gt_f32_e32 vcc, 0, v72
	v_mov_b32_e32 v19, v70
	v_mov_b32_e32 v59, v64
	v_cndmask_b32_e32 v72, v18, v58, vcc
	v_mov_b32_e32 v18, v54
	v_mov_b32_e32 v58, v56
	v_pk_add_f32 v[18:19], v[18:19], v[58:59]
	v_mov_b32_e32 v58, v55
	v_add_f32_e32 v18, v18, v19
	v_mov_b32_e32 v19, v131
	v_mov_b32_e32 v59, v71
	v_add_f32_dpp v18, v18, v18 quad_perm:[1,0,3,2] row_mask:0xf bank_mask:0xf bound_ctrl:1
	v_pk_add_f32 v[58:59], v[58:59], v[74:75]
	v_mov_b32_e32 v74, v63
	v_add_f32_dpp v18, v18, v18 quad_perm:[2,3,0,1] row_mask:0xf bank_mask:0xf bound_ctrl:1
	v_mov_b32_e32 v75, v73
	s_nop 0
	v_add_f32_dpp v18, v18, v18 row_half_mirror row_mask:0xf bank_mask:0xf bound_ctrl:1
	s_nop 1
	v_add_f32_dpp v18, v18, v18 row_mirror row_mask:0xf bank_mask:0xf bound_ctrl:1
	s_nop 1
	v_mov_b32_dpp v19, v18 row_bcast:15 row_mask:0xa bank_mask:0xf
	v_add_f32_e32 v18, v18, v19
	v_mov_b32_e32 v19, v131
	s_nop 1
	v_mov_b32_dpp v19, v18 row_bcast:31 row_mask:0xc bank_mask:0xf
	v_add_f32_e32 v18, v18, v19
	v_add_f32_e32 v19, v58, v59
	v_mov_b32_e32 v58, v131
	v_readlane_b32 s6, v18, 63
	v_add_f32_dpp v19, v19, v19 quad_perm:[1,0,3,2] row_mask:0xf bank_mask:0xf bound_ctrl:1
	s_xor_b32 s6, s6, 0x80000000
	s_nop 0
	v_add_f32_dpp v19, v19, v19 quad_perm:[2,3,0,1] row_mask:0xf bank_mask:0xf bound_ctrl:1
	s_nop 1
	v_add_f32_dpp v19, v19, v19 row_half_mirror row_mask:0xf bank_mask:0xf bound_ctrl:1
	s_nop 1
	v_add_f32_dpp v19, v19, v19 row_mirror row_mask:0xf bank_mask:0xf bound_ctrl:1
	s_nop 1
	v_mov_b32_dpp v58, v19 row_bcast:15 row_mask:0xa bank_mask:0xf
	v_add_f32_e32 v19, v19, v58
	v_mov_b32_e32 v58, v131
	s_nop 1
	v_mov_b32_dpp v58, v19 row_bcast:31 row_mask:0xc bank_mask:0xf
	v_add_f32_e32 v19, v19, v58
	s_nop 0
	v_readlane_b32 s7, v19, 63
	s_xor_b32 s7, s7, 0x80000000
	s_nop 0
	v_pk_fma_f32 v[58:59], s[6:7], v[20:21], v[54:55] op_sel_hi:[1,0,1]
	v_pk_fma_f32 v[54:55], s[6:7], v[20:21], v[70:71] op_sel_hi:[1,0,1]
	v_pk_fma_f32 v[18:19], s[6:7], v[20:21], v[64:65] op_sel_hi:[1,0,1]
	v_mov_b32_e32 v64, v60
	v_mov_b32_e32 v65, v68
	v_mov_b32_e32 v70, v62
	v_mov_b32_e32 v71, v72
	v_pk_add_f32 v[64:65], v[64:65], v[70:71]
	v_mov_b32_e32 v70, v61
	v_add_f32_e32 v64, v64, v65
	v_mov_b32_e32 v65, v131
	v_mov_b32_e32 v71, v69
	v_add_f32_dpp v64, v64, v64 quad_perm:[1,0,3,2] row_mask:0xf bank_mask:0xf bound_ctrl:1
	v_pk_add_f32 v[70:71], v[70:71], v[74:75]
	v_pk_fma_f32 v[56:57], s[6:7], v[20:21], v[56:57] op_sel_hi:[1,0,1]
	v_add_f32_dpp v64, v64, v64 quad_perm:[2,3,0,1] row_mask:0xf bank_mask:0xf bound_ctrl:1
	s_nop 1
	v_add_f32_dpp v64, v64, v64 row_half_mirror row_mask:0xf bank_mask:0xf bound_ctrl:1
	s_nop 1
	v_add_f32_dpp v64, v64, v64 row_mirror row_mask:0xf bank_mask:0xf bound_ctrl:1
	s_nop 1
	v_mov_b32_dpp v65, v64 row_bcast:15 row_mask:0xa bank_mask:0xf
	v_add_f32_e32 v64, v64, v65
	v_mov_b32_e32 v65, v131
	s_nop 1
	v_mov_b32_dpp v65, v64 row_bcast:31 row_mask:0xc bank_mask:0xf
	v_add_f32_e32 v64, v64, v65
	v_add_f32_e32 v65, v70, v71
	v_readlane_b32 s6, v64, 63
	s_xor_b32 s6, s6, 0x80000000
	v_add_f32_dpp v65, v65, v65 quad_perm:[1,0,3,2] row_mask:0xf bank_mask:0xf bound_ctrl:1
	v_mov_b32_e32 v70, v14
	v_mov_b32_e32 v71, v10
	v_add_f32_dpp v65, v65, v65 quad_perm:[2,3,0,1] row_mask:0xf bank_mask:0xf bound_ctrl:1
	v_pk_mul_f32 v[70:71], v[70:71], v[70:71]
	s_nop 0
	v_add_f32_dpp v65, v65, v65 row_half_mirror row_mask:0xf bank_mask:0xf bound_ctrl:1
	s_nop 1
	v_add_f32_dpp v65, v65, v65 row_mirror row_mask:0xf bank_mask:0xf bound_ctrl:1
	s_nop 1
	v_mov_b32_dpp v67, v65 row_bcast:15 row_mask:0xa bank_mask:0xf
	v_add_f32_e32 v65, v65, v67
	v_mov_b32_e32 v67, v131
	s_nop 1
	v_mov_b32_dpp v67, v65 row_bcast:31 row_mask:0xc bank_mask:0xf
	v_add_f32_e32 v65, v65, v67
	s_nop 0
	v_readlane_b32 s7, v65, 63
	s_xor_b32 s7, s7, 0x80000000
	s_nop 0
	v_pk_fma_f32 v[64:65], s[6:7], v[20:21], v[60:61] op_sel_hi:[1,0,1]
	v_pk_fma_f32 v[60:61], s[6:7], v[20:21], v[68:69] op_sel_hi:[1,0,1]
	v_mov_b32_e32 v68, v16
	v_mov_b32_e32 v69, v12
	v_pk_fma_f32 v[68:69], v[68:69], v[68:69], v[70:71]
	v_pk_fma_f32 v[62:63], s[6:7], v[20:21], v[62:63] op_sel_hi:[1,0,1]
	v_add_f32_e32 v68, v68, v69
	v_mov_b32_e32 v69, v131
	v_pk_fma_f32 v[20:21], s[6:7], v[20:21], v[72:73] op_sel_hi:[1,0,1]
	v_add_f32_dpp v68, v68, v68 quad_perm:[1,0,3,2] row_mask:0xf bank_mask:0xf bound_ctrl:1
	s_lshl_b32 s6, s34, 5
	s_add_i32 s7, s6, 0
	v_add_f32_dpp v68, v68, v68 quad_perm:[2,3,0,1] row_mask:0xf bank_mask:0xf bound_ctrl:1
	v_mov_b32_e32 v70, v15
	v_mov_b32_e32 v71, v11
	v_add_f32_dpp v68, v68, v68 row_half_mirror row_mask:0xf bank_mask:0xf bound_ctrl:1
	v_mov_b32_e32 v67, s7
	v_pk_mul_f32 v[70:71], v[70:71], v[70:71]
	v_add_f32_dpp v68, v68, v68 row_mirror row_mask:0xf bank_mask:0xf bound_ctrl:1
	s_nop 1
	v_mov_b32_dpp v69, v68 row_bcast:15 row_mask:0xa bank_mask:0xf
	v_add_f32_e32 v68, v68, v69
	v_mov_b32_e32 v69, v131
	s_nop 1
	v_mov_b32_dpp v69, v68 row_bcast:31 row_mask:0xc bank_mask:0xf
	v_add_f32_e32 v68, v68, v69
	v_mov_b32_e32 v69, v13
	v_readlane_b32 s7, v68, 63
	v_mov_b32_e32 v68, v17
	v_pk_fma_f32 v[68:69], v[68:69], v[68:69], v[70:71]
	v_mov_b32_e32 v70, v8
	v_add_f32_e32 v68, v68, v69
	v_mov_b32_e32 v69, v131
	v_mov_b32_e32 v71, v2
	v_add_f32_dpp v68, v68, v68 quad_perm:[1,0,3,2] row_mask:0xf bank_mask:0xf bound_ctrl:1
	v_fma_f32 v73, s7, v235, v225
	v_pk_mul_f32 v[70:71], v[70:71], v[70:71]
	v_add_f32_dpp v68, v68, v68 quad_perm:[2,3,0,1] row_mask:0xf bank_mask:0xf bound_ctrl:1
	v_rsq_f32_e32 v84, v73
	s_nop 0
	v_add_f32_dpp v68, v68, v68 row_half_mirror row_mask:0xf bank_mask:0xf bound_ctrl:1
	s_nop 1
	v_add_f32_dpp v68, v68, v68 row_mirror row_mask:0xf bank_mask:0xf bound_ctrl:1
	s_nop 1
	v_mov_b32_dpp v69, v68 row_bcast:15 row_mask:0xa bank_mask:0xf
	v_add_f32_e32 v68, v68, v69
	v_mov_b32_e32 v69, v131
	s_nop 1
	v_mov_b32_dpp v69, v68 row_bcast:31 row_mask:0xc bank_mask:0xf
	v_add_f32_e32 v68, v68, v69
	v_mov_b32_e32 v69, v6
	v_readlane_b32 s7, v68, 63
	v_mov_b32_e32 v68, v4
	v_pk_fma_f32 v[68:69], v[68:69], v[68:69], v[70:71]
	v_mov_b32_e32 v70, v9
	v_add_f32_e32 v68, v68, v69
	v_mov_b32_e32 v69, v131
	v_mov_b32_e32 v71, v3
	v_add_f32_dpp v68, v68, v68 quad_perm:[1,0,3,2] row_mask:0xf bank_mask:0xf bound_ctrl:1
	v_fma_f32 v75, s7, v235, v225
	v_pk_mul_f32 v[70:71], v[70:71], v[70:71]
	v_add_f32_dpp v68, v68, v68 quad_perm:[2,3,0,1] row_mask:0xf bank_mask:0xf bound_ctrl:1
	v_rsq_f32_e32 v85, v75
	s_nop 0
	v_add_f32_dpp v68, v68, v68 row_half_mirror row_mask:0xf bank_mask:0xf bound_ctrl:1
	v_pk_mul_f32 v[16:17], v[16:17], v[84:85]
	s_nop 0
	v_add_f32_dpp v68, v68, v68 row_mirror row_mask:0xf bank_mask:0xf bound_ctrl:1
	s_nop 1
	v_mov_b32_dpp v69, v68 row_bcast:15 row_mask:0xa bank_mask:0xf
	v_add_f32_e32 v68, v68, v69
	v_mov_b32_e32 v69, v131
	s_nop 1
	v_mov_b32_dpp v69, v68 row_bcast:31 row_mask:0xc bank_mask:0xf
	v_add_f32_e32 v68, v68, v69
	v_mov_b32_e32 v69, v7
	v_readlane_b32 s7, v68, 63
	v_mov_b32_e32 v68, v5
	v_pk_fma_f32 v[68:69], v[68:69], v[68:69], v[70:71]
	v_mov_b32_e32 v70, v34
	v_add_f32_e32 v68, v68, v69
	v_mov_b32_e32 v69, v131
	v_mov_b32_e32 v71, v30
	v_add_f32_dpp v68, v68, v68 quad_perm:[1,0,3,2] row_mask:0xf bank_mask:0xf bound_ctrl:1
	v_fma_f32 v77, s7, v235, v225
	v_pk_mul_f32 v[70:71], v[70:71], v[70:71]
	v_add_f32_dpp v68, v68, v68 quad_perm:[2,3,0,1] row_mask:0xf bank_mask:0xf bound_ctrl:1
	v_rsq_f32_e32 v86, v77
	s_nop 0
	v_add_f32_dpp v68, v68, v68 row_half_mirror row_mask:0xf bank_mask:0xf bound_ctrl:1
	s_nop 1
	v_add_f32_dpp v68, v68, v68 row_mirror row_mask:0xf bank_mask:0xf bound_ctrl:1
	s_nop 1
	v_mov_b32_dpp v69, v68 row_bcast:15 row_mask:0xa bank_mask:0xf
	v_add_f32_e32 v68, v68, v69
	v_mov_b32_e32 v69, v131
	s_nop 1
	v_mov_b32_dpp v69, v68 row_bcast:31 row_mask:0xc bank_mask:0xf
	v_add_f32_e32 v68, v68, v69
	v_mov_b32_e32 v69, v32
	v_readlane_b32 s7, v68, 63
	v_mov_b32_e32 v68, v36
	v_pk_fma_f32 v[68:69], v[68:69], v[68:69], v[70:71]
	v_mov_b32_e32 v70, v35
	v_add_f32_e32 v68, v68, v69
	v_mov_b32_e32 v69, v131
	v_mov_b32_e32 v71, v31
	v_add_f32_dpp v68, v68, v68 quad_perm:[1,0,3,2] row_mask:0xf bank_mask:0xf bound_ctrl:1
	v_fma_f32 v79, s7, v235, v225
	v_pk_mul_f32 v[70:71], v[70:71], v[70:71]
	v_add_f32_dpp v68, v68, v68 quad_perm:[2,3,0,1] row_mask:0xf bank_mask:0xf bound_ctrl:1
	v_rsq_f32_e32 v87, v79
	s_nop 0
	v_add_f32_dpp v68, v68, v68 row_half_mirror row_mask:0xf bank_mask:0xf bound_ctrl:1
	v_pk_mul_f32 v[4:5], v[4:5], v[86:87]
	s_nop 0
	v_add_f32_dpp v68, v68, v68 row_mirror row_mask:0xf bank_mask:0xf bound_ctrl:1
	v_pk_mul_f32 v[2:3], v[2:3], v[86:87]
	v_pk_mul_f32 v[8:9], v[8:9], v[86:87]
	v_mov_b32_dpp v69, v68 row_bcast:15 row_mask:0xa bank_mask:0xf
	v_add_f32_e32 v68, v68, v69
	v_mov_b32_e32 v69, v131
	v_pk_mul_f32 v[6:7], v[6:7], v[86:87]
	s_nop 0
	v_mov_b32_dpp v69, v68 row_bcast:31 row_mask:0xc bank_mask:0xf
	v_add_f32_e32 v68, v68, v69
	v_mov_b32_e32 v69, v33
	v_readlane_b32 s7, v68, 63
	v_mov_b32_e32 v68, v37
	v_pk_fma_f32 v[68:69], v[68:69], v[68:69], v[70:71]
	v_mov_b32_e32 v70, v26
	v_add_f32_e32 v68, v68, v69
	v_mov_b32_e32 v69, v131
	v_mov_b32_e32 v71, v22
	v_add_f32_dpp v68, v68, v68 quad_perm:[1,0,3,2] row_mask:0xf bank_mask:0xf bound_ctrl:1
	v_fma_f32 v81, s7, v235, v225
	v_pk_mul_f32 v[70:71], v[70:71], v[70:71]
	v_add_f32_dpp v68, v68, v68 quad_perm:[2,3,0,1] row_mask:0xf bank_mask:0xf bound_ctrl:1
	s_nop 1
	v_add_f32_dpp v68, v68, v68 row_half_mirror row_mask:0xf bank_mask:0xf bound_ctrl:1
	s_nop 1
	v_add_f32_dpp v68, v68, v68 row_mirror row_mask:0xf bank_mask:0xf bound_ctrl:1
	s_nop 1
	v_mov_b32_dpp v69, v68 row_bcast:15 row_mask:0xa bank_mask:0xf
	v_add_f32_e32 v68, v68, v69
	v_mov_b32_e32 v69, v131
	s_nop 1
	v_mov_b32_dpp v69, v68 row_bcast:31 row_mask:0xc bank_mask:0xf
	v_add_f32_e32 v68, v68, v69
	v_mov_b32_e32 v69, v24
	v_readlane_b32 s7, v68, 63
	v_mov_b32_e32 v68, v28
	v_pk_fma_f32 v[68:69], v[68:69], v[68:69], v[70:71]
	v_mov_b32_e32 v70, v27
	v_add_f32_e32 v68, v68, v69
	v_mov_b32_e32 v69, v131
	v_mov_b32_e32 v71, v23
	v_add_f32_dpp v68, v68, v68 quad_perm:[1,0,3,2] row_mask:0xf bank_mask:0xf bound_ctrl:1
	v_fma_f32 v83, s7, v235, v225
	v_pk_mul_f32 v[70:71], v[70:71], v[70:71]
	v_add_f32_dpp v68, v68, v68 quad_perm:[2,3,0,1] row_mask:0xf bank_mask:0xf bound_ctrl:1
	s_nop 1
	v_add_f32_dpp v68, v68, v68 row_half_mirror row_mask:0xf bank_mask:0xf bound_ctrl:1
	s_nop 1
	v_add_f32_dpp v68, v68, v68 row_mirror row_mask:0xf bank_mask:0xf bound_ctrl:1
	s_nop 1
	v_mov_b32_dpp v69, v68 row_bcast:15 row_mask:0xa bank_mask:0xf
	v_add_f32_e32 v68, v68, v69
	v_mov_b32_e32 v69, v131
	s_nop 1
	v_mov_b32_dpp v69, v68 row_bcast:31 row_mask:0xc bank_mask:0xf
	v_add_f32_e32 v68, v68, v69
	v_mov_b32_e32 v69, v25
	v_readlane_b32 s7, v68, 63
	v_mov_b32_e32 v68, v29
	v_pk_fma_f32 v[68:69], v[68:69], v[68:69], v[70:71]
	v_mov_b32_e32 v70, v50
	v_add_f32_e32 v68, v68, v69
	v_mov_b32_e32 v69, v131
	v_mov_b32_e32 v71, v46
	v_add_f32_dpp v68, v68, v68 quad_perm:[1,0,3,2] row_mask:0xf bank_mask:0xf bound_ctrl:1
	v_fma_f32 v90, s7, v235, v225
	v_pk_mul_f32 v[70:71], v[70:71], v[70:71]
	v_add_f32_dpp v68, v68, v68 quad_perm:[2,3,0,1] row_mask:0xf bank_mask:0xf bound_ctrl:1
	s_nop 1
	v_add_f32_dpp v68, v68, v68 row_half_mirror row_mask:0xf bank_mask:0xf bound_ctrl:1
	s_nop 1
	v_add_f32_dpp v68, v68, v68 row_mirror row_mask:0xf bank_mask:0xf bound_ctrl:1
	s_nop 1
	v_mov_b32_dpp v69, v68 row_bcast:15 row_mask:0xa bank_mask:0xf
	v_add_f32_e32 v68, v68, v69
	v_mov_b32_e32 v69, v131
	s_nop 1
	v_mov_b32_dpp v69, v68 row_bcast:31 row_mask:0xc bank_mask:0xf
	v_add_f32_e32 v68, v68, v69
	v_mov_b32_e32 v69, v48
	v_readlane_b32 s7, v68, 63
	v_mov_b32_e32 v68, v52
	v_pk_fma_f32 v[68:69], v[68:69], v[68:69], v[70:71]
	v_mov_b32_e32 v70, v51
	v_add_f32_e32 v68, v68, v69
	v_mov_b32_e32 v69, v131
	v_mov_b32_e32 v71, v47
	v_add_f32_dpp v68, v68, v68 quad_perm:[1,0,3,2] row_mask:0xf bank_mask:0xf bound_ctrl:1
	v_fma_f32 v91, s7, v235, v225
	v_pk_mul_f32 v[70:71], v[70:71], v[70:71]
	v_add_f32_dpp v68, v68, v68 quad_perm:[2,3,0,1] row_mask:0xf bank_mask:0xf bound_ctrl:1
	s_nop 1
	v_add_f32_dpp v68, v68, v68 row_half_mirror row_mask:0xf bank_mask:0xf bound_ctrl:1
	s_nop 1
	v_add_f32_dpp v68, v68, v68 row_mirror row_mask:0xf bank_mask:0xf bound_ctrl:1
	s_nop 1
	v_mov_b32_dpp v69, v68 row_bcast:15 row_mask:0xa bank_mask:0xf
	v_add_f32_e32 v68, v68, v69
	v_mov_b32_e32 v69, v131
	s_nop 1
	v_mov_b32_dpp v69, v68 row_bcast:31 row_mask:0xc bank_mask:0xf
	v_add_f32_e32 v68, v68, v69
	v_mov_b32_e32 v69, v49
	v_readlane_b32 s7, v68, 63
	v_mov_b32_e32 v68, v53
	v_pk_fma_f32 v[68:69], v[68:69], v[68:69], v[70:71]
	v_mov_b32_e32 v70, v44
	v_add_f32_e32 v68, v68, v69
	v_mov_b32_e32 v69, v131
	v_mov_b32_e32 v71, v38
	v_add_f32_dpp v68, v68, v68 quad_perm:[1,0,3,2] row_mask:0xf bank_mask:0xf bound_ctrl:1
	v_fma_f32 v92, s7, v235, v225
	v_pk_mul_f32 v[70:71], v[70:71], v[70:71]
	v_add_f32_dpp v68, v68, v68 quad_perm:[2,3,0,1] row_mask:0xf bank_mask:0xf bound_ctrl:1
	s_nop 1
	v_add_f32_dpp v68, v68, v68 row_half_mirror row_mask:0xf bank_mask:0xf bound_ctrl:1
	s_nop 1
	v_add_f32_dpp v68, v68, v68 row_mirror row_mask:0xf bank_mask:0xf bound_ctrl:1
	s_nop 1
	v_mov_b32_dpp v69, v68 row_bcast:15 row_mask:0xa bank_mask:0xf
	v_add_f32_e32 v68, v68, v69
	v_mov_b32_e32 v69, v131
	s_nop 1
	v_mov_b32_dpp v69, v68 row_bcast:31 row_mask:0xc bank_mask:0xf
	v_add_f32_e32 v68, v68, v69
	v_mov_b32_e32 v69, v42
	v_readlane_b32 s7, v68, 63
	v_mov_b32_e32 v68, v40
	v_pk_fma_f32 v[68:69], v[68:69], v[68:69], v[70:71]
	v_mov_b32_e32 v70, v45
	v_add_f32_e32 v68, v68, v69
	v_mov_b32_e32 v69, v131
	v_mov_b32_e32 v71, v39
	v_add_f32_dpp v68, v68, v68 quad_perm:[1,0,3,2] row_mask:0xf bank_mask:0xf bound_ctrl:1
	v_fma_f32 v93, s7, v235, v225
	v_pk_mul_f32 v[70:71], v[70:71], v[70:71]
	v_add_f32_dpp v68, v68, v68 quad_perm:[2,3,0,1] row_mask:0xf bank_mask:0xf bound_ctrl:1
	s_nop 1
	v_add_f32_dpp v68, v68, v68 row_half_mirror row_mask:0xf bank_mask:0xf bound_ctrl:1
	s_nop 1
	v_add_f32_dpp v68, v68, v68 row_mirror row_mask:0xf bank_mask:0xf bound_ctrl:1
	s_nop 1
	v_mov_b32_dpp v69, v68 row_bcast:15 row_mask:0xa bank_mask:0xf
	v_add_f32_e32 v68, v68, v69
	v_mov_b32_e32 v69, v131
	s_nop 1
	v_mov_b32_dpp v69, v68 row_bcast:31 row_mask:0xc bank_mask:0xf
	v_add_f32_e32 v68, v68, v69
	v_mov_b32_e32 v69, v43
	v_readlane_b32 s7, v68, 63
	v_mov_b32_e32 v68, v41
	v_pk_fma_f32 v[68:69], v[68:69], v[68:69], v[70:71]
	v_mov_b32_e32 v70, v62
	v_add_f32_e32 v68, v68, v69
	v_mov_b32_e32 v69, v131
	v_mov_b32_e32 v71, v20
	v_add_f32_dpp v68, v68, v68 quad_perm:[1,0,3,2] row_mask:0xf bank_mask:0xf bound_ctrl:1
	v_fma_f32 v94, s7, v235, v225
	v_pk_mul_f32 v[70:71], v[70:71], v[70:71]
	v_add_f32_dpp v68, v68, v68 quad_perm:[2,3,0,1] row_mask:0xf bank_mask:0xf bound_ctrl:1
	s_nop 1
	v_add_f32_dpp v68, v68, v68 row_half_mirror row_mask:0xf bank_mask:0xf bound_ctrl:1
	s_nop 1
	v_add_f32_dpp v68, v68, v68 row_mirror row_mask:0xf bank_mask:0xf bound_ctrl:1
	s_nop 1
	v_mov_b32_dpp v69, v68 row_bcast:15 row_mask:0xa bank_mask:0xf
	v_add_f32_e32 v68, v68, v69
	v_mov_b32_e32 v69, v131
	s_nop 1
	v_mov_b32_dpp v69, v68 row_bcast:31 row_mask:0xc bank_mask:0xf
	v_add_f32_e32 v68, v68, v69
	v_mov_b32_e32 v69, v60
	v_readlane_b32 s7, v68, 63
	v_mov_b32_e32 v68, v64
	v_pk_fma_f32 v[68:69], v[68:69], v[68:69], v[70:71]
	v_mov_b32_e32 v70, v63
	v_add_f32_e32 v68, v68, v69
	v_mov_b32_e32 v69, v131
	v_mov_b32_e32 v71, v21
	v_add_f32_dpp v68, v68, v68 quad_perm:[1,0,3,2] row_mask:0xf bank_mask:0xf bound_ctrl:1
	v_fma_f32 v95, s7, v235, v225
	v_pk_mul_f32 v[70:71], v[70:71], v[70:71]
	v_add_f32_dpp v68, v68, v68 quad_perm:[2,3,0,1] row_mask:0xf bank_mask:0xf bound_ctrl:1
	s_nop 1
	v_add_f32_dpp v68, v68, v68 row_half_mirror row_mask:0xf bank_mask:0xf bound_ctrl:1
	s_nop 1
	v_add_f32_dpp v68, v68, v68 row_mirror row_mask:0xf bank_mask:0xf bound_ctrl:1
	s_nop 1
	v_mov_b32_dpp v69, v68 row_bcast:15 row_mask:0xa bank_mask:0xf
	v_add_f32_e32 v68, v68, v69
	v_mov_b32_e32 v69, v131
	s_nop 1
	v_mov_b32_dpp v69, v68 row_bcast:31 row_mask:0xc bank_mask:0xf
	v_add_f32_e32 v68, v68, v69
	v_mov_b32_e32 v69, v61
	v_readlane_b32 s7, v68, 63
	v_mov_b32_e32 v68, v65
	v_pk_fma_f32 v[68:69], v[68:69], v[68:69], v[70:71]
	v_mov_b32_e32 v70, v56
	v_add_f32_e32 v68, v68, v69
	v_mov_b32_e32 v69, v131
	v_mov_b32_e32 v71, v18
	v_add_f32_dpp v68, v68, v68 quad_perm:[1,0,3,2] row_mask:0xf bank_mask:0xf bound_ctrl:1
	v_fma_f32 v96, s7, v235, v225
	v_pk_mul_f32 v[70:71], v[70:71], v[70:71]
	v_add_f32_dpp v68, v68, v68 quad_perm:[2,3,0,1] row_mask:0xf bank_mask:0xf bound_ctrl:1
	s_nop 1
	v_add_f32_dpp v68, v68, v68 row_half_mirror row_mask:0xf bank_mask:0xf bound_ctrl:1
	s_nop 1
	v_add_f32_dpp v68, v68, v68 row_mirror row_mask:0xf bank_mask:0xf bound_ctrl:1
	s_nop 1
	v_mov_b32_dpp v69, v68 row_bcast:15 row_mask:0xa bank_mask:0xf
	v_add_f32_e32 v68, v68, v69
	v_mov_b32_e32 v69, v131
	s_nop 1
	v_mov_b32_dpp v69, v68 row_bcast:31 row_mask:0xc bank_mask:0xf
	v_add_f32_e32 v68, v68, v69
	v_mov_b32_e32 v69, v54
	v_readlane_b32 s7, v68, 63
	v_mov_b32_e32 v68, v58
	v_pk_fma_f32 v[68:69], v[68:69], v[68:69], v[70:71]
	v_mov_b32_e32 v70, v57
	v_add_f32_e32 v68, v68, v69
	v_mov_b32_e32 v69, v131
	v_mov_b32_e32 v71, v19
	v_add_f32_dpp v68, v68, v68 quad_perm:[1,0,3,2] row_mask:0xf bank_mask:0xf bound_ctrl:1
	v_fma_f32 v97, s7, v235, v225
	v_pk_mul_f32 v[70:71], v[70:71], v[70:71]
	v_add_f32_dpp v68, v68, v68 quad_perm:[2,3,0,1] row_mask:0xf bank_mask:0xf bound_ctrl:1
	s_nop 1
	v_add_f32_dpp v68, v68, v68 row_half_mirror row_mask:0xf bank_mask:0xf bound_ctrl:1
	s_nop 1
	v_add_f32_dpp v68, v68, v68 row_mirror row_mask:0xf bank_mask:0xf bound_ctrl:1
	s_nop 1
	v_mov_b32_dpp v69, v68 row_bcast:15 row_mask:0xa bank_mask:0xf
	v_add_f32_e32 v68, v68, v69
	v_mov_b32_e32 v69, v131
	s_nop 1
	v_mov_b32_dpp v69, v68 row_bcast:31 row_mask:0xc bank_mask:0xf
	v_add_f32_e32 v68, v68, v69
	v_mov_b32_e32 v69, v55
	v_readlane_b32 s7, v68, 63
	v_mov_b32_e32 v68, v59
	v_pk_fma_f32 v[68:69], v[68:69], v[68:69], v[70:71]
	v_fma_f32 v98, s7, v235, v225
	v_add_f32_e32 v68, v68, v69
	v_mov_b32_e32 v69, v131
	s_nop 0
	v_add_f32_dpp v68, v68, v68 quad_perm:[1,0,3,2] row_mask:0xf bank_mask:0xf bound_ctrl:1
	s_nop 1
	v_add_f32_dpp v68, v68, v68 quad_perm:[2,3,0,1] row_mask:0xf bank_mask:0xf bound_ctrl:1
	s_nop 1
	v_add_f32_dpp v68, v68, v68 row_half_mirror row_mask:0xf bank_mask:0xf bound_ctrl:1
	s_nop 1
	v_add_f32_dpp v68, v68, v68 row_mirror row_mask:0xf bank_mask:0xf bound_ctrl:1
	s_nop 1
	v_mov_b32_dpp v69, v68 row_bcast:15 row_mask:0xa bank_mask:0xf
	v_add_f32_e32 v68, v68, v69
	v_mov_b32_e32 v69, v131
	s_nop 1
	v_mov_b32_dpp v69, v68 row_bcast:31 row_mask:0xc bank_mask:0xf
	v_add_f32_e32 v68, v68, v69
	s_nop 0
	v_readlane_b32 s7, v68, 63
	v_add_u32_e32 v68, s66, v1
	v_ashrrev_i32_e32 v69, 31, v68
	s_waitcnt lgkmcnt(0)
	v_lshl_add_u64 v[68:69], v[68:69], 2, s[42:43]
	global_load_dword v88, v[68:69], off
	v_or_b32_e32 v68, s84, v66
	v_ashrrev_i32_e32 v69, 31, v68
	v_lshlrev_b64 v[68:69], 2, v[68:69]
	v_lshl_add_u64 v[70:71], s[52:53], 0, v[68:69]
	v_lshl_add_u64 v[68:69], s[54:55], 0, v[68:69]
	global_load_dword v72, v[68:69], off
	global_load_dword v74, v[70:71], off
	global_load_dword v76, v[70:71], off offset:256
	global_load_dword v78, v[68:69], off offset:256
	global_load_dword v80, v[68:69], off offset:512
	global_load_dword v82, v[70:71], off offset:512
	s_nop 0
	global_load_dword v70, v[70:71], off offset:768
	s_nop 0
	global_load_dword v68, v[68:69], off offset:768
	v_lshl_add_u32 v69, v1, 2, s9
	v_fma_f32 v99, s7, v235, v225
	s_add_i32 s7, s5, s11
	s_lshl_b32 s5, s5, 9
	s_add_u32 s34, s78, 0x3420000
	s_mul_hi_i32 s8, s7, 0x5000
	s_mulk_i32 s7, 0x5000
	s_addc_u32 s64, s79, 0
	s_add_u32 s28, s34, s7
	s_addc_u32 s29, s64, s8
	s_movk_i32 s8, 0x110
	v_mad_u32_u24 v67, v66, s8, v67
	s_movk_i32 s7, 0x2000
	s_add_i32 s5, s9, s5
	s_waitcnt vmcnt(8)
	ds_write_b32 v69, v88
	s_waitcnt vmcnt(6)
	v_pk_fma_f32 v[88:89], v[74:75], v[4:5], v[72:73] op_sel_hi:[0,1,0]
	v_pk_mul_f32 v[4:5], v[14:15], v[84:85]
	v_pk_fma_f32 v[16:17], v[74:75], v[16:17], v[72:73] op_sel_hi:[0,1,0]
	s_waitcnt vmcnt(4)
	v_pk_fma_f32 v[14:15], v[76:77], v[4:5], v[78:79] op_sel_hi:[0,1,0]
	v_pk_mul_f32 v[4:5], v[12:13], v[84:85]
	s_waitcnt vmcnt(0)
	v_pk_fma_f32 v[86:87], v[70:71], v[2:3], v[68:69] op_sel_hi:[0,1,0]
	v_pk_fma_f32 v[12:13], v[82:83], v[4:5], v[80:81] op_sel_hi:[0,1,0]
	v_pk_mul_f32 v[4:5], v[10:11], v[84:85]
	v_rsq_f32_e32 v10, v81
	v_rsq_f32_e32 v11, v83
	v_rsq_f32_e32 v84, v90
	v_rsq_f32_e32 v85, v91
	v_pk_fma_f32 v[90:91], v[70:71], v[4:5], v[68:69] op_sel_hi:[0,1,0]
	v_pk_mul_f32 v[2:3], v[36:37], v[10:11]
	v_pk_fma_f32 v[8:9], v[76:77], v[8:9], v[78:79] op_sel_hi:[0,1,0]
	v_pk_mul_f32 v[4:5], v[28:29], v[84:85]
	v_pk_fma_f32 v[2:3], v[74:75], v[2:3], v[72:73] op_sel_hi:[0,1,0]
	v_pk_fma_f32 v[4:5], v[74:75], v[4:5], v[72:73] op_sel_hi:[0,1,0]
	v_cvt_pk_bf16_f32 v5, v4, v5
	v_cvt_pk_bf16_f32 v4, v2, v3
	v_cvt_pk_bf16_f32 v3, v88, v89
	v_cvt_pk_bf16_f32 v2, v16, v17
	ds_write_b128 v67, v[2:5]
	v_pk_mul_f32 v[2:3], v[34:35], v[10:11]
	v_pk_mul_f32 v[4:5], v[26:27], v[84:85]
	v_pk_fma_f32 v[2:3], v[76:77], v[2:3], v[78:79] op_sel_hi:[0,1,0]
	v_pk_fma_f32 v[4:5], v[76:77], v[4:5], v[78:79] op_sel_hi:[0,1,0]
	v_cvt_pk_bf16_f32 v5, v4, v5
	v_cvt_pk_bf16_f32 v4, v2, v3
	v_cvt_pk_bf16_f32 v3, v8, v9
	v_cvt_pk_bf16_f32 v2, v14, v15
	ds_write_b128 v67, v[2:5] offset:17408
	v_pk_mul_f32 v[2:3], v[32:33], v[10:11]
	v_pk_mul_f32 v[4:5], v[24:25], v[84:85]
	v_pk_fma_f32 v[6:7], v[82:83], v[6:7], v[80:81] op_sel_hi:[0,1,0]
	v_pk_fma_f32 v[4:5], v[82:83], v[4:5], v[80:81] op_sel_hi:[0,1,0]
	v_pk_fma_f32 v[2:3], v[82:83], v[2:3], v[80:81] op_sel_hi:[0,1,0]
	v_cvt_pk_bf16_f32 v5, v4, v5
	v_cvt_pk_bf16_f32 v4, v2, v3
	v_cvt_pk_bf16_f32 v3, v6, v7
	v_cvt_pk_bf16_f32 v2, v12, v13
	v_rsq_f32_e32 v6, v92
	v_rsq_f32_e32 v7, v93
	v_rsq_f32_e32 v8, v94
	v_rsq_f32_e32 v9, v95
	ds_write_b128 v67, v[2:5] offset:34816
	v_pk_mul_f32 v[2:3], v[30:31], v[10:11]
	v_pk_mul_f32 v[4:5], v[22:23], v[84:85]
	v_pk_fma_f32 v[2:3], v[70:71], v[2:3], v[68:69] op_sel_hi:[0,1,0]
	v_pk_fma_f32 v[4:5], v[70:71], v[4:5], v[68:69] op_sel_hi:[0,1,0]
	v_cvt_pk_bf16_f32 v5, v4, v5
	v_cvt_pk_bf16_f32 v4, v2, v3
	v_cvt_pk_bf16_f32 v3, v86, v87
	v_cvt_pk_bf16_f32 v2, v90, v91
	ds_write_b128 v67, v[2:5] offset:52224
	v_pk_mul_f32 v[2:3], v[52:53], v[6:7]
	v_pk_mul_f32 v[4:5], v[40:41], v[8:9]
	v_pk_fma_f32 v[12:13], v[74:75], v[2:3], v[72:73] op_sel_hi:[0,1,0]
	v_pk_fma_f32 v[10:11], v[74:75], v[4:5], v[72:73] op_sel_hi:[0,1,0]
	v_pk_mul_f32 v[2:3], v[50:51], v[6:7]
	v_pk_mul_f32 v[4:5], v[44:45], v[8:9]
	v_pk_fma_f32 v[16:17], v[76:77], v[2:3], v[78:79] op_sel_hi:[0,1,0]
	v_pk_fma_f32 v[14:15], v[76:77], v[4:5], v[78:79] op_sel_hi:[0,1,0]
	v_pk_mul_f32 v[2:3], v[48:49], v[6:7]
	v_pk_mul_f32 v[4:5], v[42:43], v[8:9]
	v_pk_fma_f32 v[24:25], v[82:83], v[2:3], v[80:81] op_sel_hi:[0,1,0]
	v_pk_fma_f32 v[22:23], v[82:83], v[4:5], v[80:81] op_sel_hi:[0,1,0]
	v_pk_mul_f32 v[2:3], v[46:47], v[6:7]
	v_pk_mul_f32 v[4:5], v[38:39], v[8:9]
	v_rsq_f32_e32 v6, v96
	v_rsq_f32_e32 v7, v97
	v_rsq_f32_e32 v8, v98
	v_rsq_f32_e32 v9, v99
	v_pk_fma_f32 v[26:27], v[70:71], v[4:5], v[68:69] op_sel_hi:[0,1,0]
	v_pk_fma_f32 v[28:29], v[70:71], v[2:3], v[68:69] op_sel_hi:[0,1,0]
	v_pk_mul_f32 v[2:3], v[64:65], v[6:7]
	v_pk_mul_f32 v[4:5], v[58:59], v[8:9]
	v_pk_fma_f32 v[2:3], v[74:75], v[2:3], v[72:73] op_sel_hi:[0,1,0]
	v_pk_fma_f32 v[4:5], v[74:75], v[4:5], v[72:73] op_sel_hi:[0,1,0]
	v_cvt_pk_bf16_f32 v5, v4, v5
	v_cvt_pk_bf16_f32 v4, v2, v3
	v_cvt_pk_bf16_f32 v3, v10, v11
	v_cvt_pk_bf16_f32 v2, v12, v13
	ds_write_b128 v67, v[2:5] offset:16
	v_pk_mul_f32 v[2:3], v[62:63], v[6:7]
	v_pk_mul_f32 v[4:5], v[56:57], v[8:9]
	v_pk_fma_f32 v[2:3], v[76:77], v[2:3], v[78:79] op_sel_hi:[0,1,0]
	v_pk_fma_f32 v[4:5], v[76:77], v[4:5], v[78:79] op_sel_hi:[0,1,0]
	v_cvt_pk_bf16_f32 v5, v4, v5
	v_cvt_pk_bf16_f32 v4, v2, v3
	v_cvt_pk_bf16_f32 v3, v14, v15
	v_cvt_pk_bf16_f32 v2, v16, v17
	ds_write_b128 v67, v[2:5] offset:17424
	v_pk_mul_f32 v[2:3], v[60:61], v[6:7]
	v_pk_mul_f32 v[4:5], v[54:55], v[8:9]
	v_pk_fma_f32 v[2:3], v[82:83], v[2:3], v[80:81] op_sel_hi:[0,1,0]
	v_pk_fma_f32 v[4:5], v[82:83], v[4:5], v[80:81] op_sel_hi:[0,1,0]
	v_cvt_pk_bf16_f32 v5, v4, v5
	v_cvt_pk_bf16_f32 v4, v2, v3
	v_cvt_pk_bf16_f32 v3, v22, v23
	v_cvt_pk_bf16_f32 v2, v24, v25
	ds_write_b128 v67, v[2:5] offset:34832
	v_pk_mul_f32 v[2:3], v[20:21], v[6:7]
	v_pk_mul_f32 v[4:5], v[18:19], v[8:9]
	v_and_or_b32 v8, v1, 31, s6
	v_pk_fma_f32 v[4:5], v[70:71], v[4:5], v[68:69] op_sel_hi:[0,1,0]
	v_pk_fma_f32 v[2:3], v[70:71], v[2:3], v[68:69] op_sel_hi:[0,1,0]
	v_lshl_add_u64 v[6:7], s[28:29], 0, v[130:131]
	v_bfe_u32 v10, v1, 5, 1
	v_ashrrev_i32_e32 v9, 31, v8
	v_cvt_pk_bf16_f32 v5, v4, v5
	v_cvt_pk_bf16_f32 v4, v2, v3
	v_cvt_pk_bf16_f32 v3, v26, v27
	v_cvt_pk_bf16_f32 v2, v28, v29
	v_add_co_u32_e32 v66, vcc, s90, v6
	v_lshlrev_b32_e32 v1, 2, v10
	v_lshlrev_b64 v[68:69], 1, v[8:9]
	ds_write_b128 v67, v[2:5] offset:52240
	v_addc_co_u32_e32 v67, vcc, 0, v7, vcc
	v_or_b32_e32 v82, s65, v1
	v_lshl_add_u64 v[84:85], s[80:81], 0, v[68:69]
	v_add_co_u32_e32 v86, vcc, s7, v6
	v_mad_u64_u32 v[12:13], s[6:7], v82, s87, v[84:85]
	s_waitcnt lgkmcnt(0)
	s_barrier
	global_load_dwordx4 v[2:5], v130, s[28:29]
	global_load_dwordx4 v[58:61], v130, s[28:29] offset:1024
	global_load_dwordx4 v[22:25], v130, s[28:29] offset:2048
	global_load_dwordx4 v[18:21], v130, s[28:29] offset:3072
	global_load_ushort v9, v[12:13], off
	v_or_b32_e32 v11, 1, v82
	v_mad_u64_u32 v[12:13], s[6:7], v11, s87, v[84:85]
	global_load_ushort v11, v[12:13], off
	v_or_b32_e32 v12, 2, v82
	v_mad_u64_u32 v[12:13], s[6:7], v12, s87, v[84:85]
	global_load_ushort v28, v[12:13], off
	v_or_b32_e32 v12, 3, v82
	v_mad_u64_u32 v[12:13], s[6:7], v12, s87, v[84:85]
	global_load_ushort v29, v[12:13], off
	v_or_b32_e32 v12, 8, v82
	v_or_b32_e32 v14, 9, v82
	v_mad_u64_u32 v[12:13], s[6:7], v12, s87, v[84:85]
	v_mad_u64_u32 v[14:15], s[6:7], v14, s87, v[84:85]
	v_or_b32_e32 v16, 10, v82
	v_or_b32_e32 v26, 11, v82
	v_mad_u64_u32 v[16:17], s[6:7], v16, s87, v[84:85]
	v_mad_u64_u32 v[26:27], s[6:7], v26, s87, v[84:85]
	global_load_ushort v12, v[12:13], off
	s_nop 0
	global_load_ushort v13, v[14:15], off
	s_nop 0
	global_load_ushort v14, v[16:17], off
	global_load_ushort v15, v[26:27], off
	v_addc_co_u32_e32 v87, vcc, 0, v7, vcc
	v_mov_b32_e32 v83, v131
	v_lshl_add_u64 v[88:89], s[76:77], 0, v[68:69]
	v_lshlrev_b64 v[68:69], 11, v[82:83]
	v_lshl_add_u64 v[68:69], v[88:89], 0, v[68:69]
	s_mov_b64 s[28:29], -1
	s_waitcnt vmcnt(7)
	v_lshlrev_b32_e32 v9, 16, v9
	v_fma_f32 v16, |v9|, s92, 1.0
	v_rcp_f32_e32 v16, v16
	v_mul_f32_e32 v26, v9, v9
	v_mul_f32_e32 v26, 0xbf38aa3b, v26
	v_exp_f32_e32 v26, v26
	v_fmamk_f32 v17, v16, 0x3f07dc22, v236
	v_fmaak_f32 v17, v16, v17, 0x3f35f0e3
	v_fmaak_f32 v17, v16, v17, 0xbe11a98e
	v_fmaak_f32 v17, v16, v17, 0x3e027906
	v_mul_f32_e32 v16, v16, v17
	v_mul_f32_e32 v16, v26, v16
	v_mul_f32_e32 v17, v16, v9
	v_fma_f32 v16, -v16, v9, v9
	v_cmp_gt_f32_e32 vcc, 0, v9
	s_waitcnt vmcnt(6)
	v_lshlrev_b32_e32 v9, 16, v11
	v_fma_f32 v11, |v9|, s92, 1.0
	v_rcp_f32_e32 v11, v11
	v_cndmask_b32_e32 v70, v16, v17, vcc
	v_mul_f32_e32 v17, v9, v9
	v_mul_f32_e32 v17, 0xbf38aa3b, v17
	v_fmamk_f32 v16, v11, 0x3f07dc22, v236
	v_fmaak_f32 v16, v11, v16, 0x3f35f0e3
	v_exp_f32_e32 v17, v17
	v_fmaak_f32 v16, v11, v16, 0xbe11a98e
	v_fmaak_f32 v16, v11, v16, 0x3e027906
	v_mul_f32_e32 v11, v11, v16
	v_mul_f32_e32 v11, v17, v11
	v_mul_f32_e32 v16, v11, v9
	v_fma_f32 v11, -v11, v9, v9
	v_cmp_gt_f32_e32 vcc, 0, v9
	s_waitcnt vmcnt(5)
	v_lshlrev_b32_e32 v9, 16, v28
	v_mul_f32_e32 v17, v9, v9
	v_cndmask_b32_e32 v71, v11, v16, vcc
	v_fma_f32 v11, |v9|, s92, 1.0
	v_rcp_f32_e32 v11, v11
	v_mul_f32_e32 v17, 0xbf38aa3b, v17
	v_exp_f32_e32 v17, v17
	v_cmp_gt_f32_e32 vcc, 0, v9
	v_fmamk_f32 v16, v11, 0x3f07dc22, v236
	v_fmaak_f32 v16, v11, v16, 0x3f35f0e3
	v_fmaak_f32 v16, v11, v16, 0xbe11a98e
	v_fmaak_f32 v16, v11, v16, 0x3e027906
	v_mul_f32_e32 v11, v11, v16
	v_mul_f32_e32 v11, v17, v11
	v_mul_f32_e32 v16, v11, v9
	v_fma_f32 v11, -v11, v9, v9
	s_waitcnt vmcnt(4)
	v_lshlrev_b32_e32 v9, 16, v29
	v_cndmask_b32_e32 v72, v11, v16, vcc
	v_fma_f32 v11, |v9|, s92, 1.0
	v_rcp_f32_e32 v11, v11
	v_mul_f32_e32 v17, v9, v9
	v_mul_f32_e32 v17, 0xbf38aa3b, v17
	v_exp_f32_e32 v17, v17
	v_fmamk_f32 v16, v11, 0x3f07dc22, v236
	v_fmaak_f32 v16, v11, v16, 0x3f35f0e3
	v_fmaak_f32 v16, v11, v16, 0xbe11a98e
	v_fmaak_f32 v16, v11, v16, 0x3e027906
	v_mul_f32_e32 v11, v11, v16
	v_mul_f32_e32 v11, v17, v11
	v_mul_f32_e32 v16, v11, v9
	v_fma_f32 v11, -v11, v9, v9
	v_cmp_gt_f32_e32 vcc, 0, v9
	s_waitcnt vmcnt(3)
	v_lshlrev_b32_e32 v9, 16, v12
	v_or_b32_e32 v26, 27, v82
	v_cndmask_b32_e32 v73, v11, v16, vcc
	v_fma_f32 v11, |v9|, s92, 1.0
	v_rcp_f32_e32 v11, v11
	v_mul_f32_e32 v16, v9, v9
	v_mul_f32_e32 v16, 0xbf38aa3b, v16
	v_exp_f32_e32 v16, v16
	v_fmamk_f32 v12, v11, 0x3f07dc22, v236
	v_fmaak_f32 v12, v11, v12, 0x3f35f0e3
	v_fmaak_f32 v12, v11, v12, 0xbe11a98e
	v_fmaak_f32 v12, v11, v12, 0x3e027906
	v_mul_f32_e32 v11, v11, v12
	v_mul_f32_e32 v11, v16, v11
	v_mul_f32_e32 v12, v11, v9
	v_fma_f32 v11, -v11, v9, v9
	v_cmp_gt_f32_e32 vcc, 0, v9
	s_waitcnt vmcnt(2)
	v_lshlrev_b32_e32 v9, 16, v13
	v_mul_f32_e32 v13, v9, v9
	v_cndmask_b32_e32 v74, v11, v12, vcc
	v_fma_f32 v11, |v9|, s92, 1.0
	v_rcp_f32_e32 v11, v11
	v_mul_f32_e32 v13, 0xbf38aa3b, v13
	v_exp_f32_e32 v13, v13
	v_cmp_gt_f32_e32 vcc, 0, v9
	v_fmamk_f32 v12, v11, 0x3f07dc22, v236
	v_fmaak_f32 v12, v11, v12, 0x3f35f0e3
	v_fmaak_f32 v12, v11, v12, 0xbe11a98e
	v_fmaak_f32 v12, v11, v12, 0x3e027906
	v_mul_f32_e32 v11, v11, v12
	v_mul_f32_e32 v11, v13, v11
	v_mul_f32_e32 v12, v11, v9
	v_fma_f32 v11, -v11, v9, v9
	s_waitcnt vmcnt(1)
	v_lshlrev_b32_e32 v9, 16, v14
	v_cndmask_b32_e32 v75, v11, v12, vcc
	v_fma_f32 v11, |v9|, s92, 1.0
	v_rcp_f32_e32 v11, v11
	v_mul_f32_e32 v13, v9, v9
	v_mul_f32_e32 v13, 0xbf38aa3b, v13
	v_exp_f32_e32 v13, v13
	v_fmamk_f32 v12, v11, 0x3f07dc22, v236
	v_fmaak_f32 v12, v11, v12, 0x3f35f0e3
	v_fmaak_f32 v12, v11, v12, 0xbe11a98e
	v_fmaak_f32 v12, v11, v12, 0x3e027906
	v_mul_f32_e32 v11, v11, v12
	v_mul_f32_e32 v11, v13, v11
	v_mul_f32_e32 v12, v11, v9
	v_fma_f32 v11, -v11, v9, v9
	v_cmp_gt_f32_e32 vcc, 0, v9
	s_waitcnt vmcnt(0)
	v_lshlrev_b32_e32 v9, 16, v15
	v_mul_f32_e32 v13, v9, v9
	v_cndmask_b32_e32 v76, v11, v12, vcc
	v_fma_f32 v11, |v9|, s92, 1.0
	v_rcp_f32_e32 v11, v11
	v_mul_f32_e32 v13, 0xbf38aa3b, v13
	v_exp_f32_e32 v13, v13
	v_cmp_gt_f32_e32 vcc, 0, v9
	v_fmamk_f32 v12, v11, 0x3f07dc22, v236
	v_fmaak_f32 v12, v11, v12, 0x3f35f0e3
	v_fmaak_f32 v12, v11, v12, 0xbe11a98e
	v_fmaak_f32 v12, v11, v12, 0x3e027906
	v_mul_f32_e32 v11, v11, v12
	v_mul_f32_e32 v11, v13, v11
	v_mul_f32_e32 v12, v11, v9
	v_fma_f32 v11, -v11, v9, v9
	v_or_b32_e32 v9, 16, v82
	v_cndmask_b32_e32 v77, v11, v12, vcc
	v_mad_u64_u32 v[12:13], s[6:7], v9, s87, v[84:85]
	global_load_ushort v9, v[12:13], off
	v_or_b32_e32 v11, 17, v82
	v_mad_u64_u32 v[12:13], s[6:7], v11, s87, v[84:85]
	global_load_ushort v11, v[12:13], off
	v_or_b32_e32 v12, 18, v82
	v_mad_u64_u32 v[12:13], s[6:7], v12, s87, v[84:85]
	global_load_ushort v28, v[12:13], off
	v_or_b32_e32 v12, 19, v82
	v_mad_u64_u32 v[12:13], s[6:7], v12, s87, v[84:85]
	global_load_ushort v29, v[12:13], off
	v_or_b32_e32 v12, 24, v82
	v_or_b32_e32 v14, 25, v82
	v_mad_u64_u32 v[12:13], s[6:7], v12, s87, v[84:85]
	v_mad_u64_u32 v[14:15], s[6:7], v14, s87, v[84:85]
	v_or_b32_e32 v16, 26, v82
	v_mad_u64_u32 v[16:17], s[6:7], v16, s87, v[84:85]
	v_mad_u64_u32 v[26:27], s[6:7], v26, s87, v[84:85]
	global_load_ushort v12, v[12:13], off
	s_nop 0
	global_load_ushort v13, v[14:15], off
	s_nop 0
	global_load_ushort v14, v[16:17], off
	global_load_ushort v15, v[26:27], off
	s_waitcnt vmcnt(7)
	v_lshlrev_b32_e32 v9, 16, v9
	v_fma_f32 v16, |v9|, s92, 1.0
	v_rcp_f32_e32 v16, v16
	v_mul_f32_e32 v26, v9, v9
	v_mul_f32_e32 v26, 0xbf38aa3b, v26
	v_exp_f32_e32 v26, v26
	v_fmamk_f32 v17, v16, 0x3f07dc22, v236
	v_fmaak_f32 v17, v16, v17, 0x3f35f0e3
	v_fmaak_f32 v17, v16, v17, 0xbe11a98e
	v_fmaak_f32 v17, v16, v17, 0x3e027906
	v_mul_f32_e32 v16, v16, v17
	v_mul_f32_e32 v16, v26, v16
	v_mul_f32_e32 v17, v16, v9
	v_fma_f32 v16, -v16, v9, v9
	v_cmp_gt_f32_e32 vcc, 0, v9
	s_waitcnt vmcnt(6)
	v_lshlrev_b32_e32 v9, 16, v11
	v_fma_f32 v11, |v9|, s92, 1.0
	v_rcp_f32_e32 v11, v11
	v_cndmask_b32_e32 v95, v16, v17, vcc
	v_mul_f32_e32 v17, v9, v9
	v_mul_f32_e32 v17, 0xbf38aa3b, v17
	v_fmamk_f32 v16, v11, 0x3f07dc22, v236
	v_fmaak_f32 v16, v11, v16, 0x3f35f0e3
	v_exp_f32_e32 v17, v17
	v_fmaak_f32 v16, v11, v16, 0xbe11a98e
	v_fmaak_f32 v16, v11, v16, 0x3e027906
	v_mul_f32_e32 v11, v11, v16
	v_mul_f32_e32 v11, v17, v11
	v_mul_f32_e32 v16, v11, v9
	v_fma_f32 v11, -v11, v9, v9
	v_cmp_gt_f32_e32 vcc, 0, v9
	s_waitcnt vmcnt(5)
	v_lshlrev_b32_e32 v9, 16, v28
	v_mul_f32_e32 v17, v9, v9
	v_cndmask_b32_e32 v96, v11, v16, vcc
	v_fma_f32 v11, |v9|, s92, 1.0
	v_rcp_f32_e32 v11, v11
	v_mul_f32_e32 v17, 0xbf38aa3b, v17
	v_exp_f32_e32 v17, v17
	v_cmp_gt_f32_e32 vcc, 0, v9
	v_fmamk_f32 v16, v11, 0x3f07dc22, v236
	v_fmaak_f32 v16, v11, v16, 0x3f35f0e3
	v_fmaak_f32 v16, v11, v16, 0xbe11a98e
	v_fmaak_f32 v16, v11, v16, 0x3e027906
	v_mul_f32_e32 v11, v11, v16
	v_mul_f32_e32 v11, v17, v11
	v_mul_f32_e32 v16, v11, v9
	v_fma_f32 v11, -v11, v9, v9
	s_waitcnt vmcnt(4)
	v_lshlrev_b32_e32 v9, 16, v29
	v_cndmask_b32_e32 v98, v11, v16, vcc
	v_fma_f32 v11, |v9|, s92, 1.0
	v_rcp_f32_e32 v11, v11
	v_mul_f32_e32 v17, v9, v9
	v_mul_f32_e32 v17, 0xbf38aa3b, v17
	v_exp_f32_e32 v17, v17
	v_fmamk_f32 v16, v11, 0x3f07dc22, v236
	v_fmaak_f32 v16, v11, v16, 0x3f35f0e3
	v_fmaak_f32 v16, v11, v16, 0xbe11a98e
	v_fmaak_f32 v16, v11, v16, 0x3e027906
	v_mul_f32_e32 v11, v11, v16
	v_mul_f32_e32 v11, v17, v11
	v_mul_f32_e32 v16, v11, v9
	v_fma_f32 v11, -v11, v9, v9
	v_cmp_gt_f32_e32 vcc, 0, v9
	s_waitcnt vmcnt(3)
	v_lshlrev_b32_e32 v9, 16, v12
	v_or_b32_e32 v26, 43, v82
	v_cndmask_b32_e32 v100, v11, v16, vcc
	v_fma_f32 v11, |v9|, s92, 1.0
	v_rcp_f32_e32 v11, v11
	v_mul_f32_e32 v16, v9, v9
	v_mul_f32_e32 v16, 0xbf38aa3b, v16
	v_exp_f32_e32 v16, v16
	v_fmamk_f32 v12, v11, 0x3f07dc22, v236
	v_fmaak_f32 v12, v11, v12, 0x3f35f0e3
	v_fmaak_f32 v12, v11, v12, 0xbe11a98e
	v_fmaak_f32 v12, v11, v12, 0x3e027906
	v_mul_f32_e32 v11, v11, v12
	v_mul_f32_e32 v11, v16, v11
	v_mul_f32_e32 v12, v11, v9
	v_fma_f32 v11, -v11, v9, v9
	v_cmp_gt_f32_e32 vcc, 0, v9
	s_waitcnt vmcnt(2)
	v_lshlrev_b32_e32 v9, 16, v13
	v_mul_f32_e32 v13, v9, v9
	v_cndmask_b32_e32 v102, v11, v12, vcc
	v_fma_f32 v11, |v9|, s92, 1.0
	v_rcp_f32_e32 v11, v11
	v_mul_f32_e32 v13, 0xbf38aa3b, v13
	v_exp_f32_e32 v13, v13
	v_cmp_gt_f32_e32 vcc, 0, v9
	v_fmamk_f32 v12, v11, 0x3f07dc22, v236
	v_fmaak_f32 v12, v11, v12, 0x3f35f0e3
	v_fmaak_f32 v12, v11, v12, 0xbe11a98e
	v_fmaak_f32 v12, v11, v12, 0x3e027906
	v_mul_f32_e32 v11, v11, v12
	v_mul_f32_e32 v11, v13, v11
	v_mul_f32_e32 v12, v11, v9
	v_fma_f32 v11, -v11, v9, v9
	s_waitcnt vmcnt(1)
	v_lshlrev_b32_e32 v9, 16, v14
	v_cndmask_b32_e32 v104, v11, v12, vcc
	v_fma_f32 v11, |v9|, s92, 1.0
	v_rcp_f32_e32 v11, v11
	v_mul_f32_e32 v13, v9, v9
	v_mul_f32_e32 v13, 0xbf38aa3b, v13
	v_exp_f32_e32 v13, v13
	v_fmamk_f32 v12, v11, 0x3f07dc22, v236
	v_fmaak_f32 v12, v11, v12, 0x3f35f0e3
	v_fmaak_f32 v12, v11, v12, 0xbe11a98e
	v_fmaak_f32 v12, v11, v12, 0x3e027906
	v_mul_f32_e32 v11, v11, v12
	v_mul_f32_e32 v11, v13, v11
	v_mul_f32_e32 v12, v11, v9
	v_fma_f32 v11, -v11, v9, v9
	v_cmp_gt_f32_e32 vcc, 0, v9
	s_waitcnt vmcnt(0)
	v_lshlrev_b32_e32 v9, 16, v15
	v_mul_f32_e32 v13, v9, v9
	v_cndmask_b32_e32 v106, v11, v12, vcc
	v_fma_f32 v11, |v9|, s92, 1.0
	v_rcp_f32_e32 v11, v11
	v_mul_f32_e32 v13, 0xbf38aa3b, v13
	v_exp_f32_e32 v13, v13
	v_cmp_gt_f32_e32 vcc, 0, v9
	v_fmamk_f32 v12, v11, 0x3f07dc22, v236
	v_fmaak_f32 v12, v11, v12, 0x3f35f0e3
	v_fmaak_f32 v12, v11, v12, 0xbe11a98e
	v_fmaak_f32 v12, v11, v12, 0x3e027906
	v_mul_f32_e32 v11, v11, v12
	v_mul_f32_e32 v11, v13, v11
	v_mul_f32_e32 v12, v11, v9
	v_fma_f32 v11, -v11, v9, v9
	v_or_b32_e32 v9, 32, v82
	v_cndmask_b32_e32 v110, v11, v12, vcc
	v_mad_u64_u32 v[12:13], s[6:7], v9, s87, v[84:85]
	global_load_ushort v9, v[12:13], off
	v_or_b32_e32 v11, 33, v82
	v_mad_u64_u32 v[12:13], s[6:7], v11, s87, v[84:85]
	global_load_ushort v11, v[12:13], off
	v_or_b32_e32 v12, 34, v82
	v_mad_u64_u32 v[12:13], s[6:7], v12, s87, v[84:85]
	global_load_ushort v28, v[12:13], off
	v_or_b32_e32 v12, 35, v82
	v_mad_u64_u32 v[12:13], s[6:7], v12, s87, v[84:85]
	global_load_ushort v29, v[12:13], off
	v_or_b32_e32 v12, 40, v82
	v_or_b32_e32 v14, 41, v82
	v_mad_u64_u32 v[12:13], s[6:7], v12, s87, v[84:85]
	v_mad_u64_u32 v[14:15], s[6:7], v14, s87, v[84:85]
	v_or_b32_e32 v16, 42, v82
	v_mad_u64_u32 v[16:17], s[6:7], v16, s87, v[84:85]
	v_mad_u64_u32 v[26:27], s[6:7], v26, s87, v[84:85]
	global_load_ushort v12, v[12:13], off
	s_nop 0
	global_load_ushort v13, v[14:15], off
	s_nop 0
	global_load_ushort v14, v[16:17], off
	global_load_ushort v15, v[26:27], off
	s_waitcnt vmcnt(7)
	v_lshlrev_b32_e32 v9, 16, v9
	v_fma_f32 v16, |v9|, s92, 1.0
	v_rcp_f32_e32 v16, v16
	v_mul_f32_e32 v26, v9, v9
	v_mul_f32_e32 v26, 0xbf38aa3b, v26
	v_exp_f32_e32 v26, v26
	v_fmamk_f32 v17, v16, 0x3f07dc22, v236
	v_fmaak_f32 v17, v16, v17, 0x3f35f0e3
	v_fmaak_f32 v17, v16, v17, 0xbe11a98e
	v_fmaak_f32 v17, v16, v17, 0x3e027906
	v_mul_f32_e32 v16, v16, v17
	v_mul_f32_e32 v16, v26, v16
	v_mul_f32_e32 v17, v16, v9
	v_fma_f32 v16, -v16, v9, v9
	v_cmp_gt_f32_e32 vcc, 0, v9
	s_waitcnt vmcnt(6)
	v_lshlrev_b32_e32 v9, 16, v11
	v_fma_f32 v11, |v9|, s92, 1.0
	v_rcp_f32_e32 v11, v11
	v_cndmask_b32_e32 v97, v16, v17, vcc
	v_mul_f32_e32 v17, v9, v9
	v_mul_f32_e32 v17, 0xbf38aa3b, v17
	v_fmamk_f32 v16, v11, 0x3f07dc22, v236
	v_fmaak_f32 v16, v11, v16, 0x3f35f0e3
	v_exp_f32_e32 v17, v17
	v_fmaak_f32 v16, v11, v16, 0xbe11a98e
	v_fmaak_f32 v16, v11, v16, 0x3e027906
	v_mul_f32_e32 v11, v11, v16
	v_mul_f32_e32 v11, v17, v11
	v_mul_f32_e32 v16, v11, v9
	v_fma_f32 v11, -v11, v9, v9
	v_cmp_gt_f32_e32 vcc, 0, v9
	s_waitcnt vmcnt(5)
	v_lshlrev_b32_e32 v9, 16, v28
	v_mul_f32_e32 v17, v9, v9
	v_cndmask_b32_e32 v99, v11, v16, vcc
	v_fma_f32 v11, |v9|, s92, 1.0
	v_rcp_f32_e32 v11, v11
	v_mul_f32_e32 v17, 0xbf38aa3b, v17
	v_exp_f32_e32 v17, v17
	v_cmp_gt_f32_e32 vcc, 0, v9
	v_fmamk_f32 v16, v11, 0x3f07dc22, v236
	v_fmaak_f32 v16, v11, v16, 0x3f35f0e3
	v_fmaak_f32 v16, v11, v16, 0xbe11a98e
	v_fmaak_f32 v16, v11, v16, 0x3e027906
	v_mul_f32_e32 v11, v11, v16
	v_mul_f32_e32 v11, v17, v11
	v_mul_f32_e32 v16, v11, v9
	v_fma_f32 v11, -v11, v9, v9
	s_waitcnt vmcnt(4)
	v_lshlrev_b32_e32 v9, 16, v29
	v_cndmask_b32_e32 v101, v11, v16, vcc
	v_fma_f32 v11, |v9|, s92, 1.0
	v_rcp_f32_e32 v11, v11
	v_mul_f32_e32 v17, v9, v9
	v_mul_f32_e32 v17, 0xbf38aa3b, v17
	v_exp_f32_e32 v17, v17
	v_fmamk_f32 v16, v11, 0x3f07dc22, v236
	v_fmaak_f32 v16, v11, v16, 0x3f35f0e3
	v_fmaak_f32 v16, v11, v16, 0xbe11a98e
	v_fmaak_f32 v16, v11, v16, 0x3e027906
	v_mul_f32_e32 v11, v11, v16
	v_mul_f32_e32 v11, v17, v11
	v_mul_f32_e32 v16, v11, v9
	v_fma_f32 v11, -v11, v9, v9
	v_cmp_gt_f32_e32 vcc, 0, v9
	s_waitcnt vmcnt(3)
	v_lshlrev_b32_e32 v9, 16, v12
	v_or_b32_e32 v26, 59, v82
	v_cndmask_b32_e32 v103, v11, v16, vcc
	v_fma_f32 v11, |v9|, s92, 1.0
	v_rcp_f32_e32 v11, v11
	v_mul_f32_e32 v16, v9, v9
	v_mul_f32_e32 v16, 0xbf38aa3b, v16
	v_exp_f32_e32 v16, v16
	v_fmamk_f32 v12, v11, 0x3f07dc22, v236
	v_fmaak_f32 v12, v11, v12, 0x3f35f0e3
	v_fmaak_f32 v12, v11, v12, 0xbe11a98e
	v_fmaak_f32 v12, v11, v12, 0x3e027906
	v_mul_f32_e32 v11, v11, v12
	v_mul_f32_e32 v11, v16, v11
	v_mul_f32_e32 v12, v11, v9
	v_fma_f32 v11, -v11, v9, v9
	v_cmp_gt_f32_e32 vcc, 0, v9
	s_waitcnt vmcnt(2)
	v_lshlrev_b32_e32 v9, 16, v13
	v_mul_f32_e32 v13, v9, v9
	v_cndmask_b32_e32 v105, v11, v12, vcc
	v_fma_f32 v11, |v9|, s92, 1.0
	v_rcp_f32_e32 v11, v11
	v_mul_f32_e32 v13, 0xbf38aa3b, v13
	v_exp_f32_e32 v13, v13
	v_cmp_gt_f32_e32 vcc, 0, v9
	v_fmamk_f32 v12, v11, 0x3f07dc22, v236
	v_fmaak_f32 v12, v11, v12, 0x3f35f0e3
	v_fmaak_f32 v12, v11, v12, 0xbe11a98e
	v_fmaak_f32 v12, v11, v12, 0x3e027906
	v_mul_f32_e32 v11, v11, v12
	v_mul_f32_e32 v11, v13, v11
	v_mul_f32_e32 v12, v11, v9
	v_fma_f32 v11, -v11, v9, v9
	s_waitcnt vmcnt(1)
	v_lshlrev_b32_e32 v9, 16, v14
	v_cndmask_b32_e32 v107, v11, v12, vcc
	v_fma_f32 v11, |v9|, s92, 1.0
	v_rcp_f32_e32 v11, v11
	v_mul_f32_e32 v13, v9, v9
	v_mul_f32_e32 v13, 0xbf38aa3b, v13
	v_exp_f32_e32 v13, v13
	v_fmamk_f32 v12, v11, 0x3f07dc22, v236
	v_fmaak_f32 v12, v11, v12, 0x3f35f0e3
	v_fmaak_f32 v12, v11, v12, 0xbe11a98e
	v_fmaak_f32 v12, v11, v12, 0x3e027906
	v_mul_f32_e32 v11, v11, v12
	v_mul_f32_e32 v11, v13, v11
	v_mul_f32_e32 v12, v11, v9
	v_fma_f32 v11, -v11, v9, v9
	v_cmp_gt_f32_e32 vcc, 0, v9
	s_waitcnt vmcnt(0)
	v_lshlrev_b32_e32 v9, 16, v15
	v_mul_f32_e32 v13, v9, v9
	v_cndmask_b32_e32 v108, v11, v12, vcc
	v_fma_f32 v11, |v9|, s92, 1.0
	v_rcp_f32_e32 v11, v11
	v_mul_f32_e32 v13, 0xbf38aa3b, v13
	v_exp_f32_e32 v13, v13
	v_cmp_gt_f32_e32 vcc, 0, v9
	v_fmamk_f32 v12, v11, 0x3f07dc22, v236
	v_fmaak_f32 v12, v11, v12, 0x3f35f0e3
	v_fmaak_f32 v12, v11, v12, 0xbe11a98e
	v_fmaak_f32 v12, v11, v12, 0x3e027906
	v_mul_f32_e32 v11, v11, v12
	v_mul_f32_e32 v11, v13, v11
	v_mul_f32_e32 v12, v11, v9
	v_fma_f32 v11, -v11, v9, v9
	v_or_b32_e32 v9, 48, v82
	v_cndmask_b32_e32 v109, v11, v12, vcc
	v_mad_u64_u32 v[12:13], s[6:7], v9, s87, v[84:85]
	global_load_ushort v9, v[12:13], off
	v_or_b32_e32 v11, 49, v82
	v_mad_u64_u32 v[12:13], s[6:7], v11, s87, v[84:85]
	global_load_ushort v11, v[12:13], off
	v_or_b32_e32 v12, 50, v82
	v_mad_u64_u32 v[12:13], s[6:7], v12, s87, v[84:85]
	global_load_ushort v28, v[12:13], off
	v_or_b32_e32 v12, 51, v82
	v_mad_u64_u32 v[12:13], s[6:7], v12, s87, v[84:85]
	global_load_ushort v29, v[12:13], off
	v_or_b32_e32 v12, 56, v82
	v_or_b32_e32 v14, 57, v82
	v_mad_u64_u32 v[12:13], s[6:7], v12, s87, v[84:85]
	v_mad_u64_u32 v[14:15], s[6:7], v14, s87, v[84:85]
	v_or_b32_e32 v16, 58, v82
	v_mad_u64_u32 v[16:17], s[6:7], v16, s87, v[84:85]
	v_mad_u64_u32 v[26:27], s[6:7], v26, s87, v[84:85]
	global_load_ushort v12, v[12:13], off
	s_nop 0
	global_load_ushort v13, v[14:15], off
	s_nop 0
	global_load_ushort v14, v[16:17], off
	global_load_ushort v15, v[26:27], off
	s_movk_i32 s6, 0x3000
	s_waitcnt vmcnt(7)
	v_lshlrev_b32_e32 v9, 16, v9
	v_fma_f32 v16, |v9|, s92, 1.0
	v_rcp_f32_e32 v16, v16
	v_mul_f32_e32 v26, v9, v9
	v_mul_f32_e32 v26, 0xbf38aa3b, v26
	v_exp_f32_e32 v26, v26
	v_fmamk_f32 v17, v16, 0x3f07dc22, v236
	v_fmaak_f32 v17, v16, v17, 0x3f35f0e3
	v_fmaak_f32 v17, v16, v17, 0xbe11a98e
	v_fmaak_f32 v17, v16, v17, 0x3e027906
	v_mul_f32_e32 v16, v16, v17
	v_mul_f32_e32 v16, v26, v16
	v_mul_f32_e32 v17, v16, v9
	v_fma_f32 v16, -v16, v9, v9
	v_cmp_gt_f32_e32 vcc, 0, v9
	s_waitcnt vmcnt(6)
	v_lshlrev_b32_e32 v9, 16, v11
	v_fma_f32 v11, |v9|, s92, 1.0
	v_rcp_f32_e32 v11, v11
	v_cndmask_b32_e32 v113, v16, v17, vcc
	v_mul_f32_e32 v17, v9, v9
	v_mul_f32_e32 v17, 0xbf38aa3b, v17
	v_fmamk_f32 v16, v11, 0x3f07dc22, v236
	v_fmaak_f32 v16, v11, v16, 0x3f35f0e3
	v_exp_f32_e32 v17, v17
	v_fmaak_f32 v16, v11, v16, 0xbe11a98e
	v_fmaak_f32 v16, v11, v16, 0x3e027906
	v_mul_f32_e32 v11, v11, v16
	v_mul_f32_e32 v11, v17, v11
	v_mul_f32_e32 v16, v11, v9
	v_fma_f32 v11, -v11, v9, v9
	v_cmp_gt_f32_e32 vcc, 0, v9
	s_waitcnt vmcnt(5)
	v_lshlrev_b32_e32 v9, 16, v28
	v_mul_f32_e32 v17, v9, v9
	v_cndmask_b32_e32 v115, v11, v16, vcc
	v_fma_f32 v11, |v9|, s92, 1.0
	v_rcp_f32_e32 v11, v11
	v_mul_f32_e32 v17, 0xbf38aa3b, v17
	v_exp_f32_e32 v17, v17
	v_cmp_gt_f32_e32 vcc, 0, v9
	v_fmamk_f32 v16, v11, 0x3f07dc22, v236
	v_fmaak_f32 v16, v11, v16, 0x3f35f0e3
	v_fmaak_f32 v16, v11, v16, 0xbe11a98e
	v_fmaak_f32 v16, v11, v16, 0x3e027906
	v_mul_f32_e32 v11, v11, v16
	v_mul_f32_e32 v11, v17, v11
	v_mul_f32_e32 v16, v11, v9
	v_fma_f32 v11, -v11, v9, v9
	s_waitcnt vmcnt(4)
	v_lshlrev_b32_e32 v9, 16, v29
	v_cndmask_b32_e32 v117, v11, v16, vcc
	v_fma_f32 v11, |v9|, s92, 1.0
	v_rcp_f32_e32 v11, v11
	v_mul_f32_e32 v17, v9, v9
	v_mul_f32_e32 v17, 0xbf38aa3b, v17
	v_exp_f32_e32 v17, v17
	v_fmamk_f32 v16, v11, 0x3f07dc22, v236
	v_fmaak_f32 v16, v11, v16, 0x3f35f0e3
	v_fmaak_f32 v16, v11, v16, 0xbe11a98e
	v_fmaak_f32 v16, v11, v16, 0x3e027906
	v_mul_f32_e32 v11, v11, v16
	v_mul_f32_e32 v11, v17, v11
	v_mul_f32_e32 v16, v11, v9
	v_fma_f32 v11, -v11, v9, v9
	v_cmp_gt_f32_e32 vcc, 0, v9
	s_waitcnt vmcnt(3)
	v_lshlrev_b32_e32 v9, 16, v12
	v_cndmask_b32_e32 v119, v11, v16, vcc
	v_fma_f32 v11, |v9|, s92, 1.0
	v_rcp_f32_e32 v11, v11
	v_mul_f32_e32 v16, v9, v9
	v_mul_f32_e32 v16, 0xbf38aa3b, v16
	v_exp_f32_e32 v16, v16
	v_fmamk_f32 v12, v11, 0x3f07dc22, v236
	v_fmaak_f32 v12, v11, v12, 0x3f35f0e3
	v_fmaak_f32 v12, v11, v12, 0xbe11a98e
	v_fmaak_f32 v12, v11, v12, 0x3e027906
	v_mul_f32_e32 v11, v11, v12
	v_mul_f32_e32 v11, v16, v11
	v_mul_f32_e32 v12, v11, v9
	v_fma_f32 v11, -v11, v9, v9
	v_cmp_gt_f32_e32 vcc, 0, v9
	s_waitcnt vmcnt(2)
	v_lshlrev_b32_e32 v9, 16, v13
	v_mul_f32_e32 v13, v9, v9
	v_cndmask_b32_e32 v120, v11, v12, vcc
	v_fma_f32 v11, |v9|, s92, 1.0
	v_rcp_f32_e32 v11, v11
	v_mul_f32_e32 v13, 0xbf38aa3b, v13
	v_exp_f32_e32 v13, v13
	v_cmp_gt_f32_e32 vcc, 0, v9
	v_fmamk_f32 v12, v11, 0x3f07dc22, v236
	v_fmaak_f32 v12, v11, v12, 0x3f35f0e3
	v_fmaak_f32 v12, v11, v12, 0xbe11a98e
	v_fmaak_f32 v12, v11, v12, 0x3e027906
	v_mul_f32_e32 v11, v11, v12
	v_mul_f32_e32 v11, v13, v11
	v_mul_f32_e32 v12, v11, v9
	v_fma_f32 v11, -v11, v9, v9
	s_waitcnt vmcnt(1)
	v_lshlrev_b32_e32 v9, 16, v14
	v_cndmask_b32_e32 v121, v11, v12, vcc
	v_fma_f32 v11, |v9|, s92, 1.0
	v_rcp_f32_e32 v11, v11
	v_mul_f32_e32 v13, v9, v9
	v_mul_f32_e32 v13, 0xbf38aa3b, v13
	v_exp_f32_e32 v13, v13
	v_fmamk_f32 v12, v11, 0x3f07dc22, v236
	v_fmaak_f32 v12, v11, v12, 0x3f35f0e3
	v_fmaak_f32 v12, v11, v12, 0xbe11a98e
	v_fmaak_f32 v12, v11, v12, 0x3e027906
	v_mul_f32_e32 v11, v11, v12
	v_mul_f32_e32 v11, v13, v11
	v_mul_f32_e32 v12, v11, v9
	v_fma_f32 v11, -v11, v9, v9
	v_cmp_gt_f32_e32 vcc, 0, v9
	s_waitcnt vmcnt(0)
	v_lshlrev_b32_e32 v9, 16, v15
	v_mul_f32_e32 v13, v9, v9
	v_cndmask_b32_e32 v122, v11, v12, vcc
	v_fma_f32 v11, |v9|, s92, 1.0
	v_rcp_f32_e32 v11, v11
	v_mul_f32_e32 v13, 0xbf38aa3b, v13
	v_exp_f32_e32 v13, v13
	v_cmp_gt_f32_e32 vcc, 0, v9
	v_fmamk_f32 v12, v11, 0x3f07dc22, v236
	v_fmaak_f32 v12, v11, v12, 0x3f35f0e3
	v_fmaak_f32 v12, v11, v12, 0xbe11a98e
	v_fmaak_f32 v12, v11, v12, 0x3e027906
	v_mul_f32_e32 v11, v11, v12
	v_mul_f32_e32 v11, v13, v11
	v_mul_f32_e32 v12, v11, v9
	v_fma_f32 v11, -v11, v9, v9
	v_cndmask_b32_e32 v123, v11, v12, vcc
	v_add_co_u32_e32 v90, vcc, s6, v6
	s_nop 1
	v_addc_co_u32_e32 v91, vcc, 0, v7, vcc
	v_add_co_u32_e32 v92, vcc, s97, v6
	v_lshlrev_b32_e32 v6, 4, v10
	s_nop 0
	v_addc_co_u32_e32 v93, vcc, 0, v7, vcc
	v_mul_lo_u32 v7, v8, s8
	v_add3_u32 v26, 0, v7, v6
	ds_read_b128 v[54:57], v26
	ds_read_b128 v[50:53], v26 offset:32
	ds_read_b128 v[46:49], v26 offset:64
	ds_read_b128 v[42:45], v26 offset:96
	v_add_u32_e32 v94, s5, v6
	s_waitcnt lgkmcnt(3)
	v_mfma_f32_32x32x16_bf16 v[2:17], v[2:5], v[54:57], 0
	global_load_dwordx4 v[78:81], v[66:67], off offset:1024
	ds_read_b128 v[38:41], v26 offset:128
	ds_read_b128 v[34:37], v26 offset:160
	ds_read_b128 v[30:33], v26 offset:192
	ds_read_b128 v[26:29], v26 offset:224
	global_load_dwordx4 v[62:65], v[86:87], off offset:-4096
	ds_read_b128 v[124:127], v94
	v_readlane_b32 s5, v251, 32
	s_waitcnt lgkmcnt(7)
	v_mfma_f32_32x32x16_bf16 v[2:17], v[58:61], v[50:53], v[2:17]
	ds_read_b128 v[58:61], v94 offset:32
	v_or_b32_e32 v130, s5, v1
	v_readlane_b32 s5, v251, 33
	s_waitcnt lgkmcnt(1)
	s_nop 7
	v_add_f32_e32 v2, v2, v124
	v_mul_f32_e32 v2, v70, v2
	v_cvt_pk_bf16_f32 v2, v2, s0
	global_store_short v[68:69], v2, off
	v_add_f32_e32 v2, v3, v125
	v_mul_f32_e32 v2, v71, v2
	v_cvt_pk_bf16_f32 v68, v2, s0
	v_lshlrev_b64 v[2:3], 11, v[130:131]
	v_lshl_add_u64 v[2:3], v[88:89], 0, v[2:3]
	global_store_short v[2:3], v68, off
	v_add_f32_e32 v2, v4, v126
	v_mul_f32_e32 v2, v72, v2
	v_or_b32_e32 v130, s5, v1
	v_cvt_pk_bf16_f32 v4, v2, s0
	v_lshlrev_b64 v[2:3], 11, v[130:131]
	v_lshl_add_u64 v[2:3], v[88:89], 0, v[2:3]
	global_store_short v[2:3], v4, off
	v_add_f32_e32 v2, v5, v127
	v_readlane_b32 s5, v251, 34
	v_mul_f32_e32 v2, v73, v2
	v_cvt_pk_bf16_f32 v4, v2, s0
	v_or_b32_e32 v130, s5, v1
	v_lshlrev_b64 v[2:3], 11, v[130:131]
	v_lshl_add_u64 v[2:3], v[88:89], 0, v[2:3]
	global_store_short v[2:3], v4, off
	s_waitcnt lgkmcnt(0)
	v_add_f32_e32 v2, v6, v58
	v_readlane_b32 s5, v251, 35
	v_mul_f32_e32 v2, v74, v2
	v_cvt_pk_bf16_f32 v4, v2, s0
	v_or_b32_e32 v130, s5, v1
	v_lshlrev_b64 v[2:3], 11, v[130:131]
	v_lshl_add_u64 v[2:3], v[88:89], 0, v[2:3]
	global_store_short v[2:3], v4, off
	v_add_f32_e32 v2, v7, v59
	v_readlane_b32 s5, v251, 36
	v_mul_f32_e32 v2, v75, v2
	v_cvt_pk_bf16_f32 v4, v2, s0
	v_or_b32_e32 v130, s5, v1
	v_lshlrev_b64 v[2:3], 11, v[130:131]
	v_lshl_add_u64 v[2:3], v[88:89], 0, v[2:3]
	global_store_short v[2:3], v4, off
	v_add_f32_e32 v2, v8, v60
	v_readlane_b32 s5, v251, 37
	v_mul_f32_e32 v2, v76, v2
	v_cvt_pk_bf16_f32 v4, v2, s0
	v_or_b32_e32 v130, s5, v1
	v_lshlrev_b64 v[2:3], 11, v[130:131]
	v_lshl_add_u64 v[2:3], v[88:89], 0, v[2:3]
	global_store_short v[2:3], v4, off
	v_add_f32_e32 v2, v9, v61
	v_mul_f32_e32 v2, v77, v2
	v_cvt_pk_bf16_f32 v8, v2, s0
	ds_read_b128 v[2:5], v94 offset:64
	v_readlane_b32 s5, v251, 38
	s_nop 1
	v_or_b32_e32 v130, s5, v1
	v_lshlrev_b64 v[6:7], 11, v[130:131]
	v_lshl_add_u64 v[6:7], v[88:89], 0, v[6:7]
	v_readlane_b32 s5, v251, 39
	global_store_short v[6:7], v8, off
	ds_read_b128 v[6:9], v94 offset:96
	s_waitcnt lgkmcnt(1)
	v_add_f32_e32 v2, v10, v2
	v_or_b32_e32 v130, s5, v1
	v_mul_f32_e32 v2, v95, v2
	v_lshlrev_b64 v[58:59], 11, v[130:131]
	v_cvt_pk_bf16_f32 v2, v2, s0
	v_lshl_add_u64 v[58:59], v[88:89], 0, v[58:59]
	global_store_short v[58:59], v2, off
	v_add_f32_e32 v2, v11, v3
	v_readlane_b32 s5, v251, 40
	v_mul_f32_e32 v2, v96, v2
	v_cvt_pk_bf16_f32 v10, v2, s0
	v_or_b32_e32 v130, s5, v1
	v_lshlrev_b64 v[2:3], 11, v[130:131]
	v_lshl_add_u64 v[2:3], v[88:89], 0, v[2:3]
	global_store_short v[2:3], v10, off
	v_add_f32_e32 v2, v12, v4
	v_readlane_b32 s5, v251, 41
	v_mul_f32_e32 v2, v98, v2
	v_cvt_pk_bf16_f32 v4, v2, s0
	v_or_b32_e32 v130, s5, v1
	v_lshlrev_b64 v[2:3], 11, v[130:131]
	v_lshl_add_u64 v[2:3], v[88:89], 0, v[2:3]
	global_store_short v[2:3], v4, off
	v_add_f32_e32 v2, v13, v5
	v_readlane_b32 s5, v251, 42
	v_mul_f32_e32 v2, v100, v2
	v_cvt_pk_bf16_f32 v4, v2, s0
	v_or_b32_e32 v130, s5, v1
	v_lshlrev_b64 v[2:3], 11, v[130:131]
	v_lshl_add_u64 v[2:3], v[88:89], 0, v[2:3]
	global_store_short v[2:3], v4, off
	s_waitcnt lgkmcnt(0)
	v_add_f32_e32 v2, v14, v6
	v_readlane_b32 s5, v251, 43
	v_mul_f32_e32 v2, v102, v2
	v_cvt_pk_bf16_f32 v4, v2, s0
	v_or_b32_e32 v130, s5, v1
	v_lshlrev_b64 v[2:3], 11, v[130:131]
	v_lshl_add_u64 v[2:3], v[88:89], 0, v[2:3]
	global_store_short v[2:3], v4, off
	v_add_f32_e32 v2, v15, v7
	v_readlane_b32 s5, v251, 44
	v_mul_f32_e32 v2, v104, v2
	v_cvt_pk_bf16_f32 v4, v2, s0
	v_or_b32_e32 v130, s5, v1
	v_lshlrev_b64 v[2:3], 11, v[130:131]
	v_lshl_add_u64 v[2:3], v[88:89], 0, v[2:3]
	global_store_short v[2:3], v4, off
	v_add_f32_e32 v2, v16, v8
	v_readlane_b32 s5, v251, 45
	v_mul_f32_e32 v2, v106, v2
	v_cvt_pk_bf16_f32 v4, v2, s0
	v_or_b32_e32 v130, s5, v1
	v_lshlrev_b64 v[2:3], 11, v[130:131]
	v_lshl_add_u64 v[2:3], v[88:89], 0, v[2:3]
	global_store_short v[2:3], v4, off
	v_add_f32_e32 v2, v17, v9
	v_readlane_b32 s5, v251, 46
	v_mul_f32_e32 v2, v110, v2
	v_cvt_pk_bf16_f32 v4, v2, s0
	v_or_b32_e32 v130, s5, v1
	v_lshlrev_b64 v[2:3], 11, v[130:131]
	v_lshl_add_u64 v[2:3], v[88:89], 0, v[2:3]
	global_store_short v[2:3], v4, off
	v_or_b32_e32 v2, 64, v82
	v_mad_i64_i32 v[2:3], s[6:7], v2, s87, v[84:85]
	global_load_ushort v10, v[2:3], off
	v_or_b32_e32 v2, 0x41, v82
	v_mad_i64_i32 v[2:3], s[6:7], v2, s87, v[84:85]
	global_load_ushort v11, v[2:3], off
	v_or_b32_e32 v2, 0x42, v82
	v_mad_i64_i32 v[2:3], s[6:7], v2, s87, v[84:85]
	global_load_ushort v12, v[2:3], off
	v_or_b32_e32 v2, 0x43, v82
	v_mad_i64_i32 v[2:3], s[6:7], v2, s87, v[84:85]
	global_load_ushort v13, v[2:3], off
	v_or_b32_e32 v2, 0x48, v82
	v_or_b32_e32 v4, 0x49, v82
	v_mad_i64_i32 v[2:3], s[6:7], v2, s87, v[84:85]
	v_mad_i64_i32 v[4:5], s[6:7], v4, s87, v[84:85]
	v_or_b32_e32 v6, 0x4a, v82
	v_or_b32_e32 v8, 0x4b, v82
	v_mad_i64_i32 v[6:7], s[6:7], v6, s87, v[84:85]
	v_mad_i64_i32 v[8:9], s[6:7], v8, s87, v[84:85]
	global_load_ushort v2, v[2:3], off
	s_nop 0
	global_load_ushort v3, v[4:5], off
	s_nop 0
	global_load_ushort v4, v[6:7], off
	global_load_ushort v5, v[8:9], off
	v_readlane_b32 s5, v251, 47
	s_waitcnt vmcnt(7)
	v_lshlrev_b32_e32 v6, 16, v10
	v_fma_f32 v7, |v6|, s92, 1.0
	v_rcp_f32_e32 v7, v7
	v_mul_f32_e32 v9, v6, v6
	v_mul_f32_e32 v9, 0xbf38aa3b, v9
	v_exp_f32_e32 v9, v9
	v_fmamk_f32 v8, v7, 0x3f07dc22, v236
	v_fmaak_f32 v8, v7, v8, 0x3f35f0e3
	v_fmaak_f32 v8, v7, v8, 0xbe11a98e
	v_fmaak_f32 v8, v7, v8, 0x3e027906
	v_mul_f32_e32 v7, v7, v8
	v_mul_f32_e32 v7, v9, v7
	v_mul_f32_e32 v8, v7, v6
	v_fma_f32 v7, -v7, v6, v6
	v_cmp_gt_f32_e32 vcc, 0, v6
	s_waitcnt vmcnt(6)
	v_lshlrev_b32_e32 v6, 16, v11
	v_mul_f32_e32 v9, v6, v6
	v_cndmask_b32_e32 v83, v7, v8, vcc
	v_fma_f32 v7, |v6|, s92, 1.0
	v_rcp_f32_e32 v7, v7
	v_mul_f32_e32 v9, 0xbf38aa3b, v9
	v_exp_f32_e32 v9, v9
	v_cmp_gt_f32_e32 vcc, 0, v6
	v_fmamk_f32 v8, v7, 0x3f07dc22, v236
	v_fmaak_f32 v8, v7, v8, 0x3f35f0e3
	v_fmaak_f32 v8, v7, v8, 0xbe11a98e
	v_fmaak_f32 v8, v7, v8, 0x3e027906
	v_mul_f32_e32 v7, v7, v8
	v_mul_f32_e32 v7, v9, v7
	v_mul_f32_e32 v8, v7, v6
	v_fma_f32 v7, -v7, v6, v6
	s_waitcnt vmcnt(5)
	v_lshlrev_b32_e32 v6, 16, v12
	v_cndmask_b32_e32 v95, v7, v8, vcc
	v_fma_f32 v7, |v6|, s92, 1.0
	v_rcp_f32_e32 v7, v7
	v_mul_f32_e32 v9, v6, v6
	v_mul_f32_e32 v9, 0xbf38aa3b, v9
	v_exp_f32_e32 v9, v9
	v_fmamk_f32 v8, v7, 0x3f07dc22, v236
	v_fmaak_f32 v8, v7, v8, 0x3f35f0e3
	v_fmaak_f32 v8, v7, v8, 0xbe11a98e
	v_fmaak_f32 v8, v7, v8, 0x3e027906
	v_mul_f32_e32 v7, v7, v8
	v_mul_f32_e32 v7, v9, v7
	v_mul_f32_e32 v8, v7, v6
	v_fma_f32 v7, -v7, v6, v6
	v_cmp_gt_f32_e32 vcc, 0, v6
	s_waitcnt vmcnt(4)
	v_lshlrev_b32_e32 v6, 16, v13
	v_mul_f32_e32 v9, v6, v6
	v_cndmask_b32_e32 v96, v7, v8, vcc
	v_fma_f32 v7, |v6|, s92, 1.0
	v_rcp_f32_e32 v7, v7
	v_mul_f32_e32 v9, 0xbf38aa3b, v9
	v_exp_f32_e32 v9, v9
	s_waitcnt vmcnt(3)
	v_lshlrev_b32_e32 v2, 16, v2
	v_fmamk_f32 v8, v7, 0x3f07dc22, v236
	v_fmaak_f32 v8, v7, v8, 0x3f35f0e3
	v_fmaak_f32 v8, v7, v8, 0xbe11a98e
	v_fmaak_f32 v8, v7, v8, 0x3e027906
	v_mul_f32_e32 v7, v7, v8
	v_mul_f32_e32 v7, v9, v7
	v_mul_f32_e32 v8, v7, v6
	v_fma_f32 v7, -v7, v6, v6
	v_cmp_gt_f32_e32 vcc, 0, v6
	v_fma_f32 v6, |v2|, s92, 1.0
	v_rcp_f32_e32 v6, v6
	v_cndmask_b32_e32 v98, v7, v8, vcc
	v_mul_f32_e32 v8, v2, v2
	v_mul_f32_e32 v8, 0xbf38aa3b, v8
	v_fmamk_f32 v7, v6, 0x3f07dc22, v236
	v_fmaak_f32 v7, v6, v7, 0x3f35f0e3
	v_exp_f32_e32 v8, v8
	v_fmaak_f32 v7, v6, v7, 0xbe11a98e
	v_fmaak_f32 v7, v6, v7, 0x3e027906
	v_mul_f32_e32 v6, v6, v7
	v_mul_f32_e32 v6, v8, v6
	v_mul_f32_e32 v7, v6, v2
	v_fma_f32 v6, -v6, v2, v2
	v_cmp_gt_f32_e32 vcc, 0, v2
	s_waitcnt vmcnt(2)
	v_lshlrev_b32_e32 v2, 16, v3
	v_fma_f32 v3, |v2|, s92, 1.0
	v_rcp_f32_e32 v3, v3
	v_cndmask_b32_e32 v100, v6, v7, vcc
	v_mul_f32_e32 v7, v2, v2
	v_mul_f32_e32 v7, 0xbf38aa3b, v7
	v_fmamk_f32 v6, v3, 0x3f07dc22, v236
	v_fmaak_f32 v6, v3, v6, 0x3f35f0e3
	v_exp_f32_e32 v7, v7
	v_fmaak_f32 v6, v3, v6, 0xbe11a98e
	v_fmaak_f32 v6, v3, v6, 0x3e027906
	v_mul_f32_e32 v3, v3, v6
	v_mul_f32_e32 v3, v7, v3
	v_mul_f32_e32 v6, v3, v2
	v_fma_f32 v3, -v3, v2, v2
	v_cmp_gt_f32_e32 vcc, 0, v2
	s_waitcnt vmcnt(1)
	v_lshlrev_b32_e32 v2, 16, v4
	v_or_b32_e32 v8, 0x5b, v82
	v_cndmask_b32_e32 v102, v3, v6, vcc
	v_fma_f32 v3, |v2|, s92, 1.0
	v_rcp_f32_e32 v3, v3
	v_mul_f32_e32 v6, v2, v2
	v_mul_f32_e32 v6, 0xbf38aa3b, v6
	v_exp_f32_e32 v6, v6
	v_fmamk_f32 v4, v3, 0x3f07dc22, v236
	v_fmaak_f32 v4, v3, v4, 0x3f35f0e3
	v_fmaak_f32 v4, v3, v4, 0xbe11a98e
	v_fmaak_f32 v4, v3, v4, 0x3e027906
	v_mul_f32_e32 v3, v3, v4
	v_mul_f32_e32 v3, v6, v3
	v_mul_f32_e32 v4, v3, v2
	v_fma_f32 v3, -v3, v2, v2
	v_cmp_gt_f32_e32 vcc, 0, v2
	s_waitcnt vmcnt(0)
	v_lshlrev_b32_e32 v2, 16, v5
	v_mul_f32_e32 v5, v2, v2
	v_cndmask_b32_e32 v104, v3, v4, vcc
	v_fma_f32 v3, |v2|, s92, 1.0
	v_rcp_f32_e32 v3, v3
	v_mul_f32_e32 v5, 0xbf38aa3b, v5
	v_exp_f32_e32 v5, v5
	v_cmp_gt_f32_e32 vcc, 0, v2
	v_fmamk_f32 v4, v3, 0x3f07dc22, v236
	v_fmaak_f32 v4, v3, v4, 0x3f35f0e3
	v_fmaak_f32 v4, v3, v4, 0xbe11a98e
	v_fmaak_f32 v4, v3, v4, 0x3e027906
	v_mul_f32_e32 v3, v3, v4
	v_mul_f32_e32 v3, v5, v3
	v_mul_f32_e32 v4, v3, v2
	v_fma_f32 v3, -v3, v2, v2
	v_or_b32_e32 v2, 0x50, v82
	v_cndmask_b32_e32 v106, v3, v4, vcc
	v_mad_i64_i32 v[2:3], s[6:7], v2, s87, v[84:85]
	global_load_ushort v10, v[2:3], off
	v_or_b32_e32 v2, 0x51, v82
	v_mad_i64_i32 v[2:3], s[6:7], v2, s87, v[84:85]
	global_load_ushort v11, v[2:3], off
	v_or_b32_e32 v2, 0x52, v82
	v_mad_i64_i32 v[2:3], s[6:7], v2, s87, v[84:85]
	global_load_ushort v12, v[2:3], off
	v_or_b32_e32 v2, 0x53, v82
	v_mad_i64_i32 v[2:3], s[6:7], v2, s87, v[84:85]
	global_load_ushort v13, v[2:3], off
	v_or_b32_e32 v2, 0x58, v82
	v_or_b32_e32 v4, 0x59, v82
	v_mad_i64_i32 v[2:3], s[6:7], v2, s87, v[84:85]
	v_mad_i64_i32 v[4:5], s[6:7], v4, s87, v[84:85]
	v_or_b32_e32 v6, 0x5a, v82
	v_mad_i64_i32 v[6:7], s[6:7], v6, s87, v[84:85]
	v_mad_i64_i32 v[8:9], s[6:7], v8, s87, v[84:85]
	global_load_ushort v2, v[2:3], off
	s_nop 0
	global_load_ushort v3, v[4:5], off
	s_nop 0
	global_load_ushort v4, v[6:7], off
	global_load_ushort v58, v[8:9], off
	v_or_b32_e32 v130, s5, v1
	v_readlane_b32 s5, v251, 48
	s_waitcnt vmcnt(7)
	v_lshlrev_b32_e32 v5, 16, v10
	v_fma_f32 v6, |v5|, s92, 1.0
	v_rcp_f32_e32 v6, v6
	v_mul_f32_e32 v8, v5, v5
	v_mul_f32_e32 v8, 0xbf38aa3b, v8
	v_exp_f32_e32 v8, v8
	v_fmamk_f32 v7, v6, 0x3f07dc22, v236
	v_fmaak_f32 v7, v6, v7, 0x3f35f0e3
	v_fmaak_f32 v7, v6, v7, 0xbe11a98e
	v_fmaak_f32 v7, v6, v7, 0x3e027906
	v_mul_f32_e32 v6, v6, v7
	v_mul_f32_e32 v6, v8, v6
	v_mul_f32_e32 v7, v6, v5
	v_fma_f32 v6, -v6, v5, v5
	v_cmp_gt_f32_e32 vcc, 0, v5
	s_waitcnt vmcnt(6)
	v_lshlrev_b32_e32 v5, 16, v11
	v_mul_f32_e32 v8, v5, v5
	v_cndmask_b32_e32 v110, v6, v7, vcc
	v_fma_f32 v6, |v5|, s92, 1.0
	v_rcp_f32_e32 v6, v6
	v_mul_f32_e32 v8, 0xbf38aa3b, v8
	v_exp_f32_e32 v8, v8
	v_cmp_gt_f32_e32 vcc, 0, v5
	v_fmamk_f32 v7, v6, 0x3f07dc22, v236
	v_fmaak_f32 v7, v6, v7, 0x3f35f0e3
	v_fmaak_f32 v7, v6, v7, 0xbe11a98e
	v_fmaak_f32 v7, v6, v7, 0x3e027906
	v_mul_f32_e32 v6, v6, v7
	v_mul_f32_e32 v6, v8, v6
	v_mul_f32_e32 v7, v6, v5
	v_fma_f32 v6, -v6, v5, v5
	s_waitcnt vmcnt(5)
	v_lshlrev_b32_e32 v5, 16, v12
	v_cndmask_b32_e32 v111, v6, v7, vcc
	v_fma_f32 v6, |v5|, s92, 1.0
	v_rcp_f32_e32 v6, v6
	v_mul_f32_e32 v8, v5, v5
	v_mul_f32_e32 v8, 0xbf38aa3b, v8
	v_exp_f32_e32 v8, v8
	v_fmamk_f32 v7, v6, 0x3f07dc22, v236
	v_fmaak_f32 v7, v6, v7, 0x3f35f0e3
	v_fmaak_f32 v7, v6, v7, 0xbe11a98e
	v_fmaak_f32 v7, v6, v7, 0x3e027906
	v_mul_f32_e32 v6, v6, v7
	v_mul_f32_e32 v6, v8, v6
	v_mul_f32_e32 v7, v6, v5
	v_fma_f32 v6, -v6, v5, v5
	v_cmp_gt_f32_e32 vcc, 0, v5
	s_waitcnt vmcnt(4)
	v_lshlrev_b32_e32 v5, 16, v13
	v_mul_f32_e32 v8, v5, v5
	v_cndmask_b32_e32 v112, v6, v7, vcc
	v_fma_f32 v6, |v5|, s92, 1.0
	v_rcp_f32_e32 v6, v6
	v_mul_f32_e32 v8, 0xbf38aa3b, v8
	v_exp_f32_e32 v8, v8
	s_waitcnt vmcnt(3)
	v_lshlrev_b32_e32 v2, 16, v2
	v_fmamk_f32 v7, v6, 0x3f07dc22, v236
	v_fmaak_f32 v7, v6, v7, 0x3f35f0e3
	v_fmaak_f32 v7, v6, v7, 0xbe11a98e
	v_fmaak_f32 v7, v6, v7, 0x3e027906
	v_mul_f32_e32 v6, v6, v7
	v_mul_f32_e32 v6, v8, v6
	v_mul_f32_e32 v7, v6, v5
	v_fma_f32 v6, -v6, v5, v5
	v_cmp_gt_f32_e32 vcc, 0, v5
	v_fma_f32 v5, |v2|, s92, 1.0
	v_rcp_f32_e32 v5, v5
	v_cndmask_b32_e32 v114, v6, v7, vcc
	v_mul_f32_e32 v7, v2, v2
	v_mul_f32_e32 v7, 0xbf38aa3b, v7
	v_fmamk_f32 v6, v5, 0x3f07dc22, v236
	v_fmaak_f32 v6, v5, v6, 0x3f35f0e3
	v_exp_f32_e32 v7, v7
	v_fmaak_f32 v6, v5, v6, 0xbe11a98e
	v_fmaak_f32 v6, v5, v6, 0x3e027906
	v_mul_f32_e32 v5, v5, v6
	v_mul_f32_e32 v5, v7, v5
	v_mul_f32_e32 v6, v5, v2
	v_fma_f32 v5, -v5, v2, v2
	v_cmp_gt_f32_e32 vcc, 0, v2
	s_waitcnt vmcnt(2)
	v_lshlrev_b32_e32 v2, 16, v3
	v_fma_f32 v3, |v2|, s92, 1.0
	v_rcp_f32_e32 v3, v3
	v_cndmask_b32_e32 v116, v5, v6, vcc
	v_mul_f32_e32 v6, v2, v2
	v_mul_f32_e32 v6, 0xbf38aa3b, v6
	v_fmamk_f32 v5, v3, 0x3f07dc22, v236
	v_fmaak_f32 v5, v3, v5, 0x3f35f0e3
	v_exp_f32_e32 v6, v6
	v_fmaak_f32 v5, v3, v5, 0xbe11a98e
	v_fmaak_f32 v5, v3, v5, 0x3e027906
	v_mul_f32_e32 v3, v3, v5
	v_mul_f32_e32 v3, v6, v3
	s_waitcnt vmcnt(1)
	v_lshlrev_b32_e32 v59, 16, v4
	v_mul_f32_e32 v5, v3, v2
	v_fma_f32 v3, -v3, v2, v2
	v_cmp_gt_f32_e32 vcc, 0, v2
	v_fma_f32 v2, |v59|, s92, 1.0
	v_rcp_f32_e32 v60, v2
	v_cndmask_b32_e32 v118, v3, v5, vcc
	v_mfma_f32_32x32x16_bf16 v[2:17], v[22:25], v[54:57], 0
	v_mul_f32_e32 v23, v59, v59
	v_fmamk_f32 v22, v60, 0x3f07dc22, v236
	v_mul_f32_e32 v23, 0xbf38aa3b, v23
	v_fmaak_f32 v22, v60, v22, 0x3f35f0e3
	v_exp_f32_e32 v23, v23
	v_fmaak_f32 v22, v60, v22, 0xbe11a98e
	v_fmaak_f32 v22, v60, v22, 0x3e027906
	v_mfma_f32_32x32x16_bf16 v[2:17], v[18:21], v[50:53], v[2:17]
	v_mul_f32_e32 v22, v60, v22
	v_mul_f32_e32 v22, v23, v22
	v_mul_f32_e32 v23, v22, v59
	v_fma_f32 v22, -v22, v59, v59
	v_cmp_gt_f32_e32 vcc, 0, v59
	s_nop 1
	v_cndmask_b32_e32 v24, v22, v23, vcc
	s_waitcnt vmcnt(0)
	v_lshlrev_b32_e32 v22, 16, v58
	v_fma_f32 v23, |v22|, s92, 1.0
	v_rcp_f32_e32 v23, v23
	v_mfma_f32_32x32x16_bf16 v[2:17], v[62:65], v[46:49], v[2:17]
	v_mul_f32_e32 v19, v22, v22
	v_mul_f32_e32 v19, 0xbf38aa3b, v19
	v_fmamk_f32 v18, v23, 0x3f07dc22, v236
	v_fmaak_f32 v18, v23, v18, 0x3f35f0e3
	v_exp_f32_e32 v19, v19
	v_fmaak_f32 v18, v23, v18, 0xbe11a98e
	v_fmaak_f32 v18, v23, v18, 0x3e027906
	v_mul_f32_e32 v18, v23, v18
	v_mul_f32_e32 v18, v19, v18
	v_mfma_f32_32x32x16_bf16 v[2:17], v[78:81], v[42:45], v[2:17]
	v_mul_f32_e32 v19, v18, v22
	v_fma_f32 v18, -v18, v22, v22
	v_cmp_gt_f32_e32 vcc, 0, v22
	v_lshlrev_b64 v[22:23], 11, v[130:131]
	v_lshl_add_u64 v[22:23], v[88:89], 0, v[22:23]
	v_cndmask_b32_e32 v25, v18, v19, vcc
	global_load_dwordx4 v[18:21], v[66:67], off offset:2048
	global_load_dwordx4 v[74:77], v[66:67], off offset:3072
	global_load_dwordx4 v[70:73], v[86:87], off
	s_nop 0
	global_load_dwordx4 v[66:69], v[86:87], off offset:1024
	global_load_dwordx4 v[62:65], v[86:87], off offset:2048
	global_load_dwordx4 v[58:61], v[86:87], off offset:3072
	ds_read_b128 v[124:127], v94 offset:128
	ds_read_b128 v[78:81], v94 offset:160
	v_or_b32_e32 v130, s5, v1
	v_readlane_b32 s5, v251, 49
	s_waitcnt lgkmcnt(1)
	v_add_f32_e32 v2, v2, v124
	v_mul_f32_e32 v2, v97, v2
	v_cvt_pk_bf16_f32 v2, v2, s0
	global_store_short v[22:23], v2, off
	v_add_f32_e32 v2, v3, v125
	v_mul_f32_e32 v2, v99, v2
	v_cvt_pk_bf16_f32 v22, v2, s0
	v_lshlrev_b64 v[2:3], 11, v[130:131]
	v_lshl_add_u64 v[2:3], v[88:89], 0, v[2:3]
	global_store_short v[2:3], v22, off
	v_add_f32_e32 v2, v4, v126
	v_mul_f32_e32 v2, v101, v2
	v_or_b32_e32 v130, s5, v1
	v_cvt_pk_bf16_f32 v4, v2, s0
	v_lshlrev_b64 v[2:3], 11, v[130:131]
	v_lshl_add_u64 v[2:3], v[88:89], 0, v[2:3]
	global_store_short v[2:3], v4, off
	v_add_f32_e32 v2, v5, v127
	v_readlane_b32 s5, v251, 50
	v_mul_f32_e32 v2, v103, v2
	v_cvt_pk_bf16_f32 v4, v2, s0
	v_or_b32_e32 v130, s5, v1
	v_lshlrev_b64 v[2:3], 11, v[130:131]
	v_lshl_add_u64 v[2:3], v[88:89], 0, v[2:3]
	global_store_short v[2:3], v4, off
	s_waitcnt lgkmcnt(0)
	v_add_f32_e32 v2, v6, v78
	v_readlane_b32 s5, v251, 51
	v_mul_f32_e32 v2, v105, v2
	v_cvt_pk_bf16_f32 v4, v2, s0
	v_or_b32_e32 v130, s5, v1
	v_lshlrev_b64 v[2:3], 11, v[130:131]
	v_lshl_add_u64 v[2:3], v[88:89], 0, v[2:3]
	global_store_short v[2:3], v4, off
	v_add_f32_e32 v2, v7, v79
	v_readlane_b32 s5, v251, 52
	v_mul_f32_e32 v2, v107, v2
	v_cvt_pk_bf16_f32 v4, v2, s0
	v_or_b32_e32 v130, s5, v1
	v_lshlrev_b64 v[2:3], 11, v[130:131]
	v_lshl_add_u64 v[2:3], v[88:89], 0, v[2:3]
	global_store_short v[2:3], v4, off
	v_add_f32_e32 v2, v8, v80
	v_readlane_b32 s5, v251, 53
	v_mul_f32_e32 v2, v108, v2
	v_cvt_pk_bf16_f32 v4, v2, s0
	v_or_b32_e32 v130, s5, v1
	v_lshlrev_b64 v[2:3], 11, v[130:131]
	v_lshl_add_u64 v[2:3], v[88:89], 0, v[2:3]
	global_store_short v[2:3], v4, off
	v_add_f32_e32 v2, v9, v81
	v_mul_f32_e32 v2, v109, v2
	v_cvt_pk_bf16_f32 v8, v2, s0
	ds_read_b128 v[2:5], v94 offset:192
	v_readlane_b32 s5, v251, 54
	s_nop 1
	v_or_b32_e32 v130, s5, v1
	v_lshlrev_b64 v[6:7], 11, v[130:131]
	v_lshl_add_u64 v[6:7], v[88:89], 0, v[6:7]
	v_readlane_b32 s5, v251, 55
	global_store_short v[6:7], v8, off
	ds_read_b128 v[6:9], v94 offset:224
	s_waitcnt lgkmcnt(1)
	v_add_f32_e32 v2, v10, v2
	v_or_b32_e32 v130, s5, v1
	v_mul_f32_e32 v2, v113, v2
	v_lshlrev_b64 v[22:23], 11, v[130:131]
	v_cvt_pk_bf16_f32 v2, v2, s0
	v_lshl_add_u64 v[22:23], v[88:89], 0, v[22:23]
	global_store_short v[22:23], v2, off
	v_add_f32_e32 v2, v11, v3
	v_readlane_b32 s5, v251, 56
	v_mul_f32_e32 v2, v115, v2
	v_cvt_pk_bf16_f32 v10, v2, s0
	v_or_b32_e32 v130, s5, v1
	v_lshlrev_b64 v[2:3], 11, v[130:131]
	v_lshl_add_u64 v[2:3], v[88:89], 0, v[2:3]
	global_store_short v[2:3], v10, off
	v_add_f32_e32 v2, v12, v4
	v_readlane_b32 s5, v251, 57
	v_mul_f32_e32 v2, v117, v2
	v_cvt_pk_bf16_f32 v4, v2, s0
	v_or_b32_e32 v130, s5, v1
	v_lshlrev_b64 v[2:3], 11, v[130:131]
	v_lshl_add_u64 v[2:3], v[88:89], 0, v[2:3]
	global_store_short v[2:3], v4, off
	v_add_f32_e32 v2, v13, v5
	v_readlane_b32 s5, v251, 58
	v_mul_f32_e32 v2, v119, v2
	v_cvt_pk_bf16_f32 v4, v2, s0
	v_or_b32_e32 v130, s5, v1
	v_lshlrev_b64 v[2:3], 11, v[130:131]
	v_lshl_add_u64 v[2:3], v[88:89], 0, v[2:3]
	global_store_short v[2:3], v4, off
	s_waitcnt lgkmcnt(0)
	v_add_f32_e32 v2, v14, v6
	v_readlane_b32 s5, v251, 59
	v_mul_f32_e32 v2, v120, v2
	v_cvt_pk_bf16_f32 v4, v2, s0
	v_or_b32_e32 v130, s5, v1
	v_lshlrev_b64 v[2:3], 11, v[130:131]
	v_lshl_add_u64 v[2:3], v[88:89], 0, v[2:3]
	global_store_short v[2:3], v4, off
	v_add_f32_e32 v2, v15, v7
	v_readlane_b32 s5, v251, 60
	v_mul_f32_e32 v2, v121, v2
	v_cvt_pk_bf16_f32 v4, v2, s0
	v_or_b32_e32 v130, s5, v1
	v_lshlrev_b64 v[2:3], 11, v[130:131]
	v_lshl_add_u64 v[2:3], v[88:89], 0, v[2:3]
	global_store_short v[2:3], v4, off
	v_add_f32_e32 v2, v16, v8
	v_readlane_b32 s5, v251, 61
	v_mul_f32_e32 v2, v122, v2
	v_cvt_pk_bf16_f32 v4, v2, s0
	v_or_b32_e32 v130, s5, v1
	v_lshlrev_b64 v[2:3], 11, v[130:131]
	v_lshl_add_u64 v[2:3], v[88:89], 0, v[2:3]
	global_store_short v[2:3], v4, off
	v_add_f32_e32 v2, v17, v9
	v_readlane_b32 s5, v251, 62
	v_mul_f32_e32 v2, v123, v2
	v_cvt_pk_bf16_f32 v4, v2, s0
	v_or_b32_e32 v130, s5, v1
	v_lshlrev_b64 v[2:3], 11, v[130:131]
	v_lshl_add_u64 v[2:3], v[88:89], 0, v[2:3]
	global_store_short v[2:3], v4, off
	v_or_b32_e32 v2, 0x60, v82
	v_mad_i64_i32 v[2:3], s[6:7], v2, s87, v[84:85]
	global_load_ushort v10, v[2:3], off
	v_or_b32_e32 v2, 0x61, v82
	v_mad_i64_i32 v[2:3], s[6:7], v2, s87, v[84:85]
	global_load_ushort v11, v[2:3], off
	v_or_b32_e32 v2, 0x62, v82
	v_mad_i64_i32 v[2:3], s[6:7], v2, s87, v[84:85]
	global_load_ushort v12, v[2:3], off
	v_or_b32_e32 v2, 0x63, v82
	v_mad_i64_i32 v[2:3], s[6:7], v2, s87, v[84:85]
	global_load_ushort v13, v[2:3], off
	v_or_b32_e32 v2, 0x68, v82
	v_or_b32_e32 v4, 0x69, v82
	v_mad_i64_i32 v[2:3], s[6:7], v2, s87, v[84:85]
	v_mad_i64_i32 v[4:5], s[6:7], v4, s87, v[84:85]
	v_or_b32_e32 v6, 0x6a, v82
	v_or_b32_e32 v8, 0x6b, v82
	v_mad_i64_i32 v[6:7], s[6:7], v6, s87, v[84:85]
	v_mad_i64_i32 v[8:9], s[6:7], v8, s87, v[84:85]
	global_load_ushort v2, v[2:3], off
	s_nop 0
	global_load_ushort v3, v[4:5], off
	s_nop 0
	global_load_ushort v4, v[6:7], off
	global_load_ushort v5, v[8:9], off
	v_readlane_b32 s5, v251, 63
	s_waitcnt vmcnt(7)
	v_lshlrev_b32_e32 v6, 16, v10
	v_fma_f32 v7, |v6|, s92, 1.0
	v_rcp_f32_e32 v7, v7
	v_mul_f32_e32 v9, v6, v6
	v_mul_f32_e32 v9, 0xbf38aa3b, v9
	v_exp_f32_e32 v9, v9
	v_fmamk_f32 v8, v7, 0x3f07dc22, v236
	v_fmaak_f32 v8, v7, v8, 0x3f35f0e3
	v_fmaak_f32 v8, v7, v8, 0xbe11a98e
	v_fmaak_f32 v8, v7, v8, 0x3e027906
	v_mul_f32_e32 v7, v7, v8
	v_mul_f32_e32 v7, v9, v7
	v_mul_f32_e32 v8, v7, v6
	v_fma_f32 v7, -v7, v6, v6
	v_cmp_gt_f32_e32 vcc, 0, v6
	s_waitcnt vmcnt(6)
	v_lshlrev_b32_e32 v6, 16, v11
	v_mul_f32_e32 v9, v6, v6
	v_cndmask_b32_e32 v78, v7, v8, vcc
	v_fma_f32 v7, |v6|, s92, 1.0
	v_rcp_f32_e32 v7, v7
	v_mul_f32_e32 v9, 0xbf38aa3b, v9
	v_exp_f32_e32 v9, v9
	v_cmp_gt_f32_e32 vcc, 0, v6
	v_fmamk_f32 v8, v7, 0x3f07dc22, v236
	v_fmaak_f32 v8, v7, v8, 0x3f35f0e3
	v_fmaak_f32 v8, v7, v8, 0xbe11a98e
	v_fmaak_f32 v8, v7, v8, 0x3e027906
	v_mul_f32_e32 v7, v7, v8
	v_mul_f32_e32 v7, v9, v7
	v_mul_f32_e32 v8, v7, v6
	v_fma_f32 v7, -v7, v6, v6
	s_waitcnt vmcnt(5)
	v_lshlrev_b32_e32 v6, 16, v12
	v_cndmask_b32_e32 v79, v7, v8, vcc
	v_fma_f32 v7, |v6|, s92, 1.0
	v_rcp_f32_e32 v7, v7
	v_mul_f32_e32 v9, v6, v6
	v_mul_f32_e32 v9, 0xbf38aa3b, v9
	v_exp_f32_e32 v9, v9
	v_fmamk_f32 v8, v7, 0x3f07dc22, v236
	v_fmaak_f32 v8, v7, v8, 0x3f35f0e3
	v_fmaak_f32 v8, v7, v8, 0xbe11a98e
	v_fmaak_f32 v8, v7, v8, 0x3e027906
	v_mul_f32_e32 v7, v7, v8
	v_mul_f32_e32 v7, v9, v7
	v_mul_f32_e32 v8, v7, v6
	v_fma_f32 v7, -v7, v6, v6
	v_cmp_gt_f32_e32 vcc, 0, v6
	s_waitcnt vmcnt(4)
	v_lshlrev_b32_e32 v6, 16, v13
	v_mul_f32_e32 v9, v6, v6
	v_cndmask_b32_e32 v80, v7, v8, vcc
	v_fma_f32 v7, |v6|, s92, 1.0
	v_rcp_f32_e32 v7, v7
	v_mul_f32_e32 v9, 0xbf38aa3b, v9
	v_exp_f32_e32 v9, v9
	s_waitcnt vmcnt(3)
	v_lshlrev_b32_e32 v2, 16, v2
	v_fmamk_f32 v8, v7, 0x3f07dc22, v236
	v_fmaak_f32 v8, v7, v8, 0x3f35f0e3
	v_fmaak_f32 v8, v7, v8, 0xbe11a98e
	v_fmaak_f32 v8, v7, v8, 0x3e027906
	v_mul_f32_e32 v7, v7, v8
	v_mul_f32_e32 v7, v9, v7
	v_mul_f32_e32 v8, v7, v6
	v_fma_f32 v7, -v7, v6, v6
	v_cmp_gt_f32_e32 vcc, 0, v6
	v_fma_f32 v6, |v2|, s92, 1.0
	v_rcp_f32_e32 v6, v6
	v_cndmask_b32_e32 v81, v7, v8, vcc
	v_mul_f32_e32 v8, v2, v2
	v_mul_f32_e32 v8, 0xbf38aa3b, v8
	v_fmamk_f32 v7, v6, 0x3f07dc22, v236
	v_fmaak_f32 v7, v6, v7, 0x3f35f0e3
	v_exp_f32_e32 v8, v8
	v_fmaak_f32 v7, v6, v7, 0xbe11a98e
	v_fmaak_f32 v7, v6, v7, 0x3e027906
	v_mul_f32_e32 v6, v6, v7
	v_mul_f32_e32 v6, v8, v6
	v_mul_f32_e32 v7, v6, v2
	v_fma_f32 v6, -v6, v2, v2
	v_cmp_gt_f32_e32 vcc, 0, v2
	s_waitcnt vmcnt(2)
	v_lshlrev_b32_e32 v2, 16, v3
	v_fma_f32 v3, |v2|, s92, 1.0
	v_rcp_f32_e32 v3, v3
	v_cndmask_b32_e32 v86, v6, v7, vcc
	v_mul_f32_e32 v7, v2, v2
	v_mul_f32_e32 v7, 0xbf38aa3b, v7
	v_fmamk_f32 v6, v3, 0x3f07dc22, v236
	v_fmaak_f32 v6, v3, v6, 0x3f35f0e3
	v_exp_f32_e32 v7, v7
	v_fmaak_f32 v6, v3, v6, 0xbe11a98e
	v_fmaak_f32 v6, v3, v6, 0x3e027906
	v_mul_f32_e32 v3, v3, v6
	v_mul_f32_e32 v3, v7, v3
	v_mul_f32_e32 v6, v3, v2
	v_fma_f32 v3, -v3, v2, v2
	v_cmp_gt_f32_e32 vcc, 0, v2
	s_waitcnt vmcnt(1)
	v_lshlrev_b32_e32 v2, 16, v4
	v_or_b32_e32 v8, 0x7b, v82
	v_cndmask_b32_e32 v87, v3, v6, vcc
	v_fma_f32 v3, |v2|, s92, 1.0
	v_rcp_f32_e32 v3, v3
	v_mul_f32_e32 v6, v2, v2
	v_mul_f32_e32 v6, 0xbf38aa3b, v6
	v_exp_f32_e32 v6, v6
	v_fmamk_f32 v4, v3, 0x3f07dc22, v236
	v_fmaak_f32 v4, v3, v4, 0x3f35f0e3
	v_fmaak_f32 v4, v3, v4, 0xbe11a98e
	v_fmaak_f32 v4, v3, v4, 0x3e027906
	v_mul_f32_e32 v3, v3, v4
	v_mul_f32_e32 v3, v6, v3
	v_mul_f32_e32 v4, v3, v2
	v_fma_f32 v3, -v3, v2, v2
	v_cmp_gt_f32_e32 vcc, 0, v2
	s_waitcnt vmcnt(0)
	v_lshlrev_b32_e32 v2, 16, v5
	v_mul_f32_e32 v5, v2, v2
	v_cndmask_b32_e32 v97, v3, v4, vcc
	v_fma_f32 v3, |v2|, s92, 1.0
	v_rcp_f32_e32 v3, v3
	v_mul_f32_e32 v5, 0xbf38aa3b, v5
	v_exp_f32_e32 v5, v5
	v_cmp_gt_f32_e32 vcc, 0, v2
	v_fmamk_f32 v4, v3, 0x3f07dc22, v236
	v_fmaak_f32 v4, v3, v4, 0x3f35f0e3
	v_fmaak_f32 v4, v3, v4, 0xbe11a98e
	v_fmaak_f32 v4, v3, v4, 0x3e027906
	v_mul_f32_e32 v3, v3, v4
	v_mul_f32_e32 v3, v5, v3
	v_mul_f32_e32 v4, v3, v2
	v_fma_f32 v3, -v3, v2, v2
	v_or_b32_e32 v2, 0x70, v82
	v_cndmask_b32_e32 v99, v3, v4, vcc
	v_mad_i64_i32 v[2:3], s[6:7], v2, s87, v[84:85]
	global_load_ushort v10, v[2:3], off
	v_or_b32_e32 v2, 0x71, v82
	v_mad_i64_i32 v[2:3], s[6:7], v2, s87, v[84:85]
	global_load_ushort v11, v[2:3], off
	v_or_b32_e32 v2, 0x72, v82
	v_mad_i64_i32 v[2:3], s[6:7], v2, s87, v[84:85]
	global_load_ushort v12, v[2:3], off
	v_or_b32_e32 v2, 0x73, v82
	v_mad_i64_i32 v[2:3], s[6:7], v2, s87, v[84:85]
	global_load_ushort v13, v[2:3], off
	v_or_b32_e32 v2, 0x78, v82
	v_or_b32_e32 v4, 0x79, v82
	v_mad_i64_i32 v[2:3], s[6:7], v2, s87, v[84:85]
	v_mad_i64_i32 v[4:5], s[6:7], v4, s87, v[84:85]
	v_or_b32_e32 v6, 0x7a, v82
	v_mad_i64_i32 v[6:7], s[6:7], v6, s87, v[84:85]
	v_mad_i64_i32 v[8:9], s[6:7], v8, s87, v[84:85]
	global_load_ushort v2, v[2:3], off
	s_nop 0
	global_load_ushort v3, v[4:5], off
	s_nop 0
	global_load_ushort v4, v[6:7], off
	global_load_ushort v5, v[8:9], off
	v_or_b32_e32 v130, s5, v1
	v_readlane_b32 s5, v252, 0
	v_readlane_b32 s6, v250, 27
	v_readlane_b32 s7, v250, 28
	s_waitcnt vmcnt(7)
	v_lshlrev_b32_e32 v6, 16, v10
	v_fma_f32 v7, |v6|, s92, 1.0
	v_rcp_f32_e32 v7, v7
	v_mul_f32_e32 v9, v6, v6
	v_mul_f32_e32 v9, 0xbf38aa3b, v9
	v_exp_f32_e32 v9, v9
	v_fmamk_f32 v8, v7, 0x3f07dc22, v236
	v_fmaak_f32 v8, v7, v8, 0x3f35f0e3
	v_fmaak_f32 v8, v7, v8, 0xbe11a98e
	v_fmaak_f32 v8, v7, v8, 0x3e027906
	v_mul_f32_e32 v7, v7, v8
	v_mul_f32_e32 v7, v9, v7
	v_mul_f32_e32 v8, v7, v6
	v_fma_f32 v7, -v7, v6, v6
	v_cmp_gt_f32_e32 vcc, 0, v6
	s_waitcnt vmcnt(6)
	v_lshlrev_b32_e32 v6, 16, v11
	v_mul_f32_e32 v9, v6, v6
	v_cndmask_b32_e32 v82, v7, v8, vcc
	v_fma_f32 v7, |v6|, s92, 1.0
	v_rcp_f32_e32 v7, v7
	v_mul_f32_e32 v9, 0xbf38aa3b, v9
	v_exp_f32_e32 v9, v9
	v_cmp_gt_f32_e32 vcc, 0, v6
	v_fmamk_f32 v8, v7, 0x3f07dc22, v236
	v_fmaak_f32 v8, v7, v8, 0x3f35f0e3
	v_fmaak_f32 v8, v7, v8, 0xbe11a98e
	v_fmaak_f32 v8, v7, v8, 0x3e027906
	v_mul_f32_e32 v7, v7, v8
	v_mul_f32_e32 v7, v9, v7
	v_mul_f32_e32 v8, v7, v6
	v_fma_f32 v7, -v7, v6, v6
	s_waitcnt vmcnt(5)
	v_lshlrev_b32_e32 v6, 16, v12
	v_cndmask_b32_e32 v84, v7, v8, vcc
	v_fma_f32 v7, |v6|, s92, 1.0
	v_rcp_f32_e32 v7, v7
	v_mul_f32_e32 v9, v6, v6
	v_mul_f32_e32 v9, 0xbf38aa3b, v9
	v_exp_f32_e32 v9, v9
	v_fmamk_f32 v8, v7, 0x3f07dc22, v236
	v_fmaak_f32 v8, v7, v8, 0x3f35f0e3
	v_fmaak_f32 v8, v7, v8, 0xbe11a98e
	v_fmaak_f32 v8, v7, v8, 0x3e027906
	v_mul_f32_e32 v7, v7, v8
	v_mul_f32_e32 v7, v9, v7
	v_mul_f32_e32 v8, v7, v6
	v_fma_f32 v7, -v7, v6, v6
	v_cmp_gt_f32_e32 vcc, 0, v6
	s_waitcnt vmcnt(4)
	v_lshlrev_b32_e32 v6, 16, v13
	v_mul_f32_e32 v9, v6, v6
	v_cndmask_b32_e32 v85, v7, v8, vcc
	v_fma_f32 v7, |v6|, s92, 1.0
	v_rcp_f32_e32 v7, v7
	v_mul_f32_e32 v9, 0xbf38aa3b, v9
	v_exp_f32_e32 v9, v9
	s_waitcnt vmcnt(3)
	v_lshlrev_b32_e32 v2, 16, v2
	v_fmamk_f32 v8, v7, 0x3f07dc22, v236
	v_fmaak_f32 v8, v7, v8, 0x3f35f0e3
	v_fmaak_f32 v8, v7, v8, 0xbe11a98e
	v_fmaak_f32 v8, v7, v8, 0x3e027906
	v_mul_f32_e32 v7, v7, v8
	v_mul_f32_e32 v7, v9, v7
	v_mul_f32_e32 v8, v7, v6
	v_fma_f32 v7, -v7, v6, v6
	v_cmp_gt_f32_e32 vcc, 0, v6
	v_fma_f32 v6, |v2|, s92, 1.0
	v_rcp_f32_e32 v6, v6
	v_cndmask_b32_e32 v101, v7, v8, vcc
	v_mul_f32_e32 v8, v2, v2
	v_mul_f32_e32 v8, 0xbf38aa3b, v8
	v_fmamk_f32 v7, v6, 0x3f07dc22, v236
	v_fmaak_f32 v7, v6, v7, 0x3f35f0e3
	v_exp_f32_e32 v8, v8
	v_fmaak_f32 v7, v6, v7, 0xbe11a98e
	v_fmaak_f32 v7, v6, v7, 0x3e027906
	v_mul_f32_e32 v6, v6, v7
	v_mul_f32_e32 v6, v8, v6
	v_mul_f32_e32 v7, v6, v2
	v_fma_f32 v6, -v6, v2, v2
	v_cmp_gt_f32_e32 vcc, 0, v2
	s_waitcnt vmcnt(2)
	v_lshlrev_b32_e32 v2, 16, v3
	v_fma_f32 v3, |v2|, s92, 1.0
	v_rcp_f32_e32 v3, v3
	v_cndmask_b32_e32 v107, v6, v7, vcc
	v_mul_f32_e32 v7, v2, v2
	v_mul_f32_e32 v7, 0xbf38aa3b, v7
	v_fmamk_f32 v6, v3, 0x3f07dc22, v236
	v_fmaak_f32 v6, v3, v6, 0x3f35f0e3
	v_exp_f32_e32 v7, v7
	v_fmaak_f32 v6, v3, v6, 0xbe11a98e
	v_fmaak_f32 v6, v3, v6, 0x3e027906
	v_mul_f32_e32 v3, v3, v6
	v_mul_f32_e32 v3, v7, v3
	v_mul_f32_e32 v6, v3, v2
	v_fma_f32 v3, -v3, v2, v2
	v_cmp_gt_f32_e32 vcc, 0, v2
	s_waitcnt vmcnt(1)
	v_lshlrev_b32_e32 v2, 16, v4
	v_mfma_f32_32x32x16_bf16 v[8:23], v[18:21], v[54:57], 0
	v_cndmask_b32_e32 v108, v3, v6, vcc
	v_fma_f32 v3, |v2|, s92, 1.0
	v_rcp_f32_e32 v3, v3
	v_mul_f32_e32 v6, v2, v2
	v_mul_f32_e32 v6, 0xbf38aa3b, v6
	v_exp_f32_e32 v6, v6
	v_fmamk_f32 v4, v3, 0x3f07dc22, v236
	v_fmaak_f32 v4, v3, v4, 0x3f35f0e3
	v_fmaak_f32 v4, v3, v4, 0xbe11a98e
	v_fmaak_f32 v4, v3, v4, 0x3e027906
	v_mfma_f32_32x32x16_bf16 v[8:23], v[74:77], v[50:53], v[8:23]
	v_mul_f32_e32 v3, v3, v4
	v_mul_f32_e32 v3, v6, v3
	v_mul_f32_e32 v4, v3, v2
	v_fma_f32 v3, -v3, v2, v2
	v_cmp_gt_f32_e32 vcc, 0, v2
	s_waitcnt vmcnt(0)
	v_lshlrev_b32_e32 v2, 16, v5
	v_mul_f32_e32 v5, v2, v2
	v_cndmask_b32_e32 v109, v3, v4, vcc
	v_fma_f32 v3, |v2|, s92, 1.0
	v_rcp_f32_e32 v3, v3
	v_mfma_f32_32x32x16_bf16 v[8:23], v[70:73], v[46:49], v[8:23]
	v_mul_f32_e32 v5, 0xbf38aa3b, v5
	v_exp_f32_e32 v5, v5
	v_fmamk_f32 v4, v3, 0x3f07dc22, v236
	v_fmaak_f32 v4, v3, v4, 0x3f35f0e3
	v_fmaak_f32 v4, v3, v4, 0xbe11a98e
	v_fmaak_f32 v4, v3, v4, 0x3e027906
	v_mul_f32_e32 v3, v3, v4
	v_mul_f32_e32 v3, v5, v3
	v_mul_f32_e32 v4, v3, v2
	v_fma_f32 v3, -v3, v2, v2
	v_cmp_gt_f32_e32 vcc, 0, v2
	v_mfma_f32_32x32x16_bf16 v[8:23], v[66:69], v[42:45], v[8:23]
	s_nop 0
	v_cndmask_b32_e32 v113, v3, v4, vcc
	global_load_dwordx4 v[2:5], v[92:93], off offset:-4096
	global_load_dwordx4 v[66:69], v[90:91], off offset:1024
	global_load_dwordx4 v[70:73], v[90:91], off offset:2048
	s_and_b64 vcc, exec, s[6:7]
	v_mfma_f32_32x32x16_bf16 v[8:23], v[62:65], v[38:41], v[8:23]
	global_load_dwordx4 v[62:65], v[90:91], off offset:3072
	global_load_dwordx4 v[74:77], v[92:93], off
	global_load_dwordx4 v[120:123], v[92:93], off offset:1024
	global_load_dwordx4 v[124:127], v[92:93], off offset:2048
	s_nop 0
	global_load_dwordx4 v[90:93], v[92:93], off offset:3072
	ds_read_b128 v[132:135], v94 offset:256
	v_mfma_f32_32x32x16_bf16 v[8:23], v[58:61], v[34:37], v[8:23]
	ds_read_b128 v[58:61], v94 offset:288
	s_waitcnt lgkmcnt(1)
	s_nop 9
	v_add_f32_e32 v6, v8, v132
	v_mul_f32_e32 v6, v83, v6
	v_cvt_pk_bf16_f32 v8, v6, s0
	v_lshlrev_b64 v[6:7], 11, v[130:131]
	v_lshl_add_u64 v[6:7], v[88:89], 0, v[6:7]
	global_store_short v[6:7], v8, off
	v_add_f32_e32 v6, v9, v133
	v_mul_f32_e32 v6, v95, v6
	v_or_b32_e32 v130, s5, v1
	v_cvt_pk_bf16_f32 v8, v6, s0
	v_lshlrev_b64 v[6:7], 11, v[130:131]
	v_lshl_add_u64 v[6:7], v[88:89], 0, v[6:7]
	global_store_short v[6:7], v8, off
	v_add_f32_e32 v6, v10, v134
	v_readlane_b32 s5, v252, 1
	v_mul_f32_e32 v6, v96, v6
	v_cvt_pk_bf16_f32 v8, v6, s0
	v_or_b32_e32 v130, s5, v1
	v_lshlrev_b64 v[6:7], 11, v[130:131]
	v_lshl_add_u64 v[6:7], v[88:89], 0, v[6:7]
	global_store_short v[6:7], v8, off
	v_add_f32_e32 v6, v11, v135
	v_readlane_b32 s5, v252, 2
	v_mul_f32_e32 v6, v98, v6
	v_cvt_pk_bf16_f32 v8, v6, s0
	v_or_b32_e32 v130, s5, v1
	v_lshlrev_b64 v[6:7], 11, v[130:131]
	v_lshl_add_u64 v[6:7], v[88:89], 0, v[6:7]
	global_store_short v[6:7], v8, off
	s_waitcnt lgkmcnt(0)
	v_add_f32_e32 v6, v12, v58
	v_readlane_b32 s5, v252, 3
	v_mul_f32_e32 v6, v100, v6
	v_cvt_pk_bf16_f32 v8, v6, s0
	v_or_b32_e32 v130, s5, v1
	v_lshlrev_b64 v[6:7], 11, v[130:131]
	v_lshl_add_u64 v[6:7], v[88:89], 0, v[6:7]
	global_store_short v[6:7], v8, off
	v_add_f32_e32 v6, v13, v59
	v_readlane_b32 s5, v252, 4
	v_mul_f32_e32 v6, v102, v6
	v_cvt_pk_bf16_f32 v8, v6, s0
	v_or_b32_e32 v130, s5, v1
	v_lshlrev_b64 v[6:7], 11, v[130:131]
	v_lshl_add_u64 v[6:7], v[88:89], 0, v[6:7]
	global_store_short v[6:7], v8, off
	v_add_f32_e32 v6, v14, v60
	v_readlane_b32 s5, v252, 5
	v_mul_f32_e32 v6, v104, v6
	v_cvt_pk_bf16_f32 v8, v6, s0
	v_or_b32_e32 v130, s5, v1
	v_lshlrev_b64 v[6:7], 11, v[130:131]
	v_lshl_add_u64 v[6:7], v[88:89], 0, v[6:7]
	global_store_short v[6:7], v8, off
	v_add_f32_e32 v6, v15, v61
	ds_read_b128 v[58:61], v94 offset:320
	ds_read_b128 v[102:105], v94 offset:352
	v_readlane_b32 s5, v252, 6
	v_mul_f32_e32 v6, v106, v6
	v_cvt_pk_bf16_f32 v8, v6, s0
	v_or_b32_e32 v130, s5, v1
	v_lshlrev_b64 v[6:7], 11, v[130:131]
	v_lshl_add_u64 v[6:7], v[88:89], 0, v[6:7]
	global_store_short v[6:7], v8, off
	s_waitcnt lgkmcnt(1)
	v_add_f32_e32 v6, v16, v58
	v_readlane_b32 s5, v252, 7
	v_mul_f32_e32 v6, v110, v6
	v_cvt_pk_bf16_f32 v8, v6, s0
	v_or_b32_e32 v130, s5, v1
	v_lshlrev_b64 v[6:7], 11, v[130:131]
	v_lshl_add_u64 v[6:7], v[88:89], 0, v[6:7]
	global_store_short v[6:7], v8, off
	v_add_f32_e32 v6, v17, v59
	v_mul_f32_e32 v58, v111, v6
	s_waitcnt vmcnt(16)
	v_mfma_f32_32x32x16_bf16 v[2:17], v[2:5], v[54:57], 0
	v_readlane_b32 s5, v252, 8
	v_add_f32_e32 v18, v18, v60
	v_mul_f32_e32 v18, v112, v18
	v_or_b32_e32 v130, s5, v1
	v_readlane_b32 s5, v252, 9
	v_lshlrev_b64 v[54:55], 11, v[130:131]
	v_cvt_pk_bf16_f32 v18, v18, s0
	s_waitcnt vmcnt(15)
	v_mfma_f32_32x32x16_bf16 v[2:17], v[66:69], v[50:53], v[2:17]
	v_or_b32_e32 v130, s5, v1
	v_lshlrev_b64 v[50:51], 11, v[130:131]
	v_lshl_add_u64 v[50:51], v[88:89], 0, v[50:51]
	global_store_short v[50:51], v18, off
	v_add_f32_e32 v18, v19, v61
	v_readlane_b32 s5, v252, 10
	v_mul_f32_e32 v18, v114, v18
	s_waitcnt vmcnt(15)
	v_mfma_f32_32x32x16_bf16 v[2:17], v[70:73], v[46:49], v[2:17]
	v_or_b32_e32 v130, s5, v1
	v_cvt_pk_bf16_f32 v46, v18, s0
	v_lshlrev_b64 v[18:19], 11, v[130:131]
	v_lshl_add_u64 v[18:19], v[88:89], 0, v[18:19]
	global_store_short v[18:19], v46, off
	s_waitcnt lgkmcnt(0)
	v_add_f32_e32 v18, v20, v102
	v_readlane_b32 s5, v252, 11
	s_waitcnt vmcnt(15)
	v_mfma_f32_32x32x16_bf16 v[2:17], v[62:65], v[42:45], v[2:17]
	v_mul_f32_e32 v18, v116, v18
	v_or_b32_e32 v130, s5, v1
	v_cvt_pk_bf16_f32 v20, v18, s0
	v_lshlrev_b64 v[18:19], 11, v[130:131]
	v_lshl_add_u64 v[18:19], v[88:89], 0, v[18:19]
	global_store_short v[18:19], v20, off
	v_add_f32_e32 v18, v21, v103
	s_waitcnt vmcnt(15)
	v_mfma_f32_32x32x16_bf16 v[2:17], v[74:77], v[38:41], v[2:17]
	v_readlane_b32 s5, v252, 12
	v_mul_f32_e32 v18, v118, v18
	v_cvt_pk_bf16_f32 v20, v18, s0
	v_or_b32_e32 v130, s5, v1
	v_lshlrev_b64 v[18:19], 11, v[130:131]
	v_lshl_add_u64 v[18:19], v[88:89], 0, v[18:19]
	global_store_short v[18:19], v20, off
	s_waitcnt vmcnt(15)
	v_mfma_f32_32x32x16_bf16 v[2:17], v[120:123], v[34:37], v[2:17]
	v_add_f32_e32 v18, v22, v104
	v_readlane_b32 s5, v252, 13
	v_mul_f32_e32 v18, v24, v18
	v_cvt_pk_bf16_f32 v20, v18, s0
	v_or_b32_e32 v130, s5, v1
	v_lshlrev_b64 v[18:19], 11, v[130:131]
	v_lshl_add_u64 v[18:19], v[88:89], 0, v[18:19]
	s_waitcnt vmcnt(14)
	v_mfma_f32_32x32x16_bf16 v[2:17], v[124:127], v[30:33], v[2:17]
	global_store_short v[18:19], v20, off
	v_add_f32_e32 v18, v23, v105
	v_readlane_b32 s5, v252, 14
	v_mul_f32_e32 v18, v25, v18
	v_cvt_pk_bf16_f32 v20, v18, s0
	v_or_b32_e32 v130, s5, v1
	v_lshlrev_b64 v[18:19], 11, v[130:131]
	v_cvt_pk_bf16_f32 v56, v58, s0
	v_lshl_add_u64 v[54:55], v[88:89], 0, v[54:55]
	v_lshl_add_u64 v[18:19], v[88:89], 0, v[18:19]
	s_waitcnt vmcnt(14)
	v_mfma_f32_32x32x16_bf16 v[2:17], v[90:93], v[26:29], v[2:17]
	global_store_short v[54:55], v56, off
	global_store_short v[18:19], v20, off
	ds_read_b128 v[18:21], v94 offset:384
	ds_read_b128 v[22:25], v94 offset:416
	v_readlane_b32 s5, v252, 15
	s_waitcnt lgkmcnt(1)
	s_nop 5
	v_add_f32_e32 v2, v2, v18
	v_or_b32_e32 v130, s5, v1
	v_mul_f32_e32 v2, v78, v2
	v_lshlrev_b64 v[26:27], 11, v[130:131]
	v_cvt_pk_bf16_f32 v2, v2, s0
	v_lshl_add_u64 v[26:27], v[88:89], 0, v[26:27]
	global_store_short v[26:27], v2, off
	v_add_f32_e32 v2, v3, v19
	v_readlane_b32 s5, v252, 16
	v_mul_f32_e32 v2, v79, v2
	v_cvt_pk_bf16_f32 v18, v2, s0
	v_or_b32_e32 v130, s5, v1
	v_lshlrev_b64 v[2:3], 11, v[130:131]
	v_lshl_add_u64 v[2:3], v[88:89], 0, v[2:3]
	global_store_short v[2:3], v18, off
	v_add_f32_e32 v2, v4, v20
	v_readlane_b32 s5, v252, 17
	v_mul_f32_e32 v2, v80, v2
	v_cvt_pk_bf16_f32 v4, v2, s0
	v_or_b32_e32 v130, s5, v1
	v_lshlrev_b64 v[2:3], 11, v[130:131]
	v_lshl_add_u64 v[2:3], v[88:89], 0, v[2:3]
	global_store_short v[2:3], v4, off
	v_add_f32_e32 v2, v5, v21
	v_readlane_b32 s5, v252, 18
	v_mul_f32_e32 v2, v81, v2
	v_cvt_pk_bf16_f32 v4, v2, s0
	v_or_b32_e32 v130, s5, v1
	v_lshlrev_b64 v[2:3], 11, v[130:131]
	v_lshl_add_u64 v[2:3], v[88:89], 0, v[2:3]
	global_store_short v[2:3], v4, off
	s_waitcnt lgkmcnt(0)
	v_add_f32_e32 v2, v6, v22
	v_readlane_b32 s5, v252, 19
	v_mul_f32_e32 v2, v86, v2
	v_cvt_pk_bf16_f32 v4, v2, s0
	v_or_b32_e32 v130, s5, v1
	v_lshlrev_b64 v[2:3], 11, v[130:131]
	v_lshl_add_u64 v[2:3], v[88:89], 0, v[2:3]
	global_store_short v[2:3], v4, off
	v_add_f32_e32 v2, v7, v23
	v_readlane_b32 s5, v252, 20
	v_mul_f32_e32 v2, v87, v2
	v_cvt_pk_bf16_f32 v4, v2, s0
	v_or_b32_e32 v130, s5, v1
	v_lshlrev_b64 v[2:3], 11, v[130:131]
	v_lshl_add_u64 v[2:3], v[88:89], 0, v[2:3]
	global_store_short v[2:3], v4, off
	v_add_f32_e32 v2, v8, v24
	v_readlane_b32 s5, v252, 21
	v_mul_f32_e32 v2, v97, v2
	v_cvt_pk_bf16_f32 v4, v2, s0
	v_or_b32_e32 v130, s5, v1
	v_lshlrev_b64 v[2:3], 11, v[130:131]
	v_lshl_add_u64 v[2:3], v[88:89], 0, v[2:3]
	global_store_short v[2:3], v4, off
	v_add_f32_e32 v2, v9, v25
	v_mul_f32_e32 v2, v99, v2
	v_cvt_pk_bf16_f32 v8, v2, s0
	ds_read_b128 v[2:5], v94 offset:448
	v_readlane_b32 s5, v252, 22
	s_nop 1
	v_or_b32_e32 v130, s5, v1
	v_lshlrev_b64 v[6:7], 11, v[130:131]
	v_lshl_add_u64 v[6:7], v[88:89], 0, v[6:7]
	v_readlane_b32 s5, v252, 23
	global_store_short v[6:7], v8, off
	ds_read_b128 v[6:9], v94 offset:480
	s_waitcnt lgkmcnt(1)
	v_add_f32_e32 v2, v10, v2
	v_or_b32_e32 v130, s5, v1
	v_mul_f32_e32 v2, v82, v2
	v_lshlrev_b64 v[18:19], 11, v[130:131]
	v_cvt_pk_bf16_f32 v2, v2, s0
	v_lshl_add_u64 v[18:19], v[88:89], 0, v[18:19]
	global_store_short v[18:19], v2, off
	v_add_f32_e32 v2, v11, v3
	v_readlane_b32 s5, v252, 24
	v_mul_f32_e32 v2, v84, v2
	v_cvt_pk_bf16_f32 v10, v2, s0
	v_or_b32_e32 v130, s5, v1
	v_lshlrev_b64 v[2:3], 11, v[130:131]
	v_lshl_add_u64 v[2:3], v[88:89], 0, v[2:3]
	global_store_short v[2:3], v10, off
	v_add_f32_e32 v2, v12, v4
	v_readlane_b32 s5, v252, 25
	v_mul_f32_e32 v2, v85, v2
	v_cvt_pk_bf16_f32 v4, v2, s0
	v_or_b32_e32 v130, s5, v1
	v_lshlrev_b64 v[2:3], 11, v[130:131]
	v_lshl_add_u64 v[2:3], v[88:89], 0, v[2:3]
	global_store_short v[2:3], v4, off
	v_add_f32_e32 v2, v13, v5
	v_readlane_b32 s5, v252, 26
	v_mul_f32_e32 v2, v101, v2
	v_cvt_pk_bf16_f32 v4, v2, s0
	v_or_b32_e32 v130, s5, v1
	v_lshlrev_b64 v[2:3], 11, v[130:131]
	v_lshl_add_u64 v[2:3], v[88:89], 0, v[2:3]
	global_store_short v[2:3], v4, off
	s_waitcnt lgkmcnt(0)
	v_add_f32_e32 v2, v14, v6
	v_readlane_b32 s5, v252, 27
	v_mul_f32_e32 v2, v107, v2
	v_cvt_pk_bf16_f32 v4, v2, s0
	v_or_b32_e32 v130, s5, v1
	v_lshlrev_b64 v[2:3], 11, v[130:131]
	v_lshl_add_u64 v[2:3], v[88:89], 0, v[2:3]
	global_store_short v[2:3], v4, off
	v_add_f32_e32 v2, v15, v7
	v_readlane_b32 s5, v252, 28
	v_mul_f32_e32 v2, v108, v2
	v_cvt_pk_bf16_f32 v4, v2, s0
	v_or_b32_e32 v130, s5, v1
	v_lshlrev_b64 v[2:3], 11, v[130:131]
	v_lshl_add_u64 v[2:3], v[88:89], 0, v[2:3]
	global_store_short v[2:3], v4, off
	v_add_f32_e32 v2, v16, v8
	v_readlane_b32 s5, v252, 29
	v_mul_f32_e32 v2, v109, v2
	v_cvt_pk_bf16_f32 v4, v2, s0
	v_or_b32_e32 v130, s5, v1
	v_lshlrev_b64 v[2:3], 11, v[130:131]
	v_lshl_add_u64 v[2:3], v[88:89], 0, v[2:3]
	global_store_short v[2:3], v4, off
	v_add_f32_e32 v2, v17, v9
	v_readlane_b32 s5, v252, 30
	v_mul_f32_e32 v2, v113, v2
	v_cvt_pk_bf16_f32 v4, v2, s0
	v_or_b32_e32 v130, s5, v1
	v_lshlrev_b64 v[2:3], 11, v[130:131]
	v_lshl_add_u64 v[2:3], v[88:89], 0, v[2:3]
	global_store_short v[2:3], v4, off
	s_barrier
	s_cbranch_vccz .LBB0_314
	v_readlane_b32 s6, v253, 48
	v_mov_b32_e32 v1, v242
	v_readlane_b32 s7, v253, 49
	s_andn2_b64 vcc, exec, s[6:7]
	v_readfirstlane_b32 s5, v1
	s_cbranch_vccnz .LBB0_313
	s_load_dwordx8 s[44:51], s[0:1], 0x38
	v_mov_b32_e32 v2, 2
	v_lshlrev_b32_sdwa v130, v2, v1 dst_sel:DWORD dst_unused:UNUSED_PAD src0_sel:DWORD src1_sel:BYTE_0
	v_readlane_b32 s8, v254, 39
	v_readlane_b32 s9, v254, 40
	s_waitcnt lgkmcnt(0)
	v_lshl_add_u64 v[2:3], s[44:45], 0, v[130:131]
	v_lshl_add_u64 v[4:5], v[2:3], 0, s[62:63]
	global_load_dword v42, v[4:5], off
	v_lshl_add_u64 v[4:5], v[2:3], 0, s[8:9]
	v_readlane_b32 s8, v254, 41
	v_readlane_b32 s9, v254, 42
	global_load_dword v43, v[4:5], off
	s_ashr_i32 s6, s5, 6
	v_lshl_add_u64 v[4:5], v[2:3], 0, s[8:9]
	v_readlane_b32 s8, v254, 43
	v_readlane_b32 s9, v254, 44
	global_load_dword v45, v[4:5], off
	v_mov_b32_e32 v10, s46
	v_lshl_add_u64 v[4:5], v[2:3], 0, s[8:9]
	v_readlane_b32 s8, v254, 45
	v_readlane_b32 s9, v254, 46
	global_load_dword v47, v[4:5], off
	v_mov_b32_e32 v11, s47
	v_lshl_add_u64 v[4:5], v[2:3], 0, s[8:9]
	v_readlane_b32 s8, v254, 47
	v_readlane_b32 s9, v254, 48
	global_load_dword v49, v[4:5], off
	v_readlane_b32 s57, v253, 32
	v_lshl_add_u64 v[4:5], v[2:3], 0, s[8:9]
	v_readlane_b32 s8, v254, 49
	v_readlane_b32 s9, v254, 50
	global_load_dword v51, v[4:5], off
	s_mov_b32 s58, s2
	v_lshl_add_u64 v[4:5], v[2:3], 0, s[8:9]
	v_readlane_b32 s8, v254, 51
	v_readlane_b32 s9, v254, 52
	global_load_dword v53, v[4:5], off
	s_waitcnt vmcnt(5)
	v_mov_b32_e32 v44, v43
	v_lshl_add_u64 v[4:5], v[2:3], 0, s[8:9]
	v_readlane_b32 s8, v254, 53
	v_readlane_b32 s9, v254, 54
	global_load_dword v55, v[4:5], off
	s_waitcnt vmcnt(5)
	v_mov_b32_e32 v46, v45
	v_lshl_add_u64 v[4:5], v[2:3], 0, s[8:9]
	v_readlane_b32 s8, v254, 55
	v_readlane_b32 s9, v254, 56
	global_load_dword v57, v[4:5], off
	s_waitcnt vmcnt(5)
	v_mov_b32_e32 v48, v47
	v_lshl_add_u64 v[4:5], v[2:3], 0, s[8:9]
	v_readlane_b32 s8, v254, 57
	v_readlane_b32 s9, v254, 58
	global_load_dword v59, v[4:5], off
	s_waitcnt vmcnt(5)
	v_mov_b32_e32 v50, v49
	v_lshl_add_u64 v[4:5], v[2:3], 0, s[8:9]
	v_readlane_b32 s8, v254, 59
	v_readlane_b32 s9, v254, 60
	global_load_dword v61, v[4:5], off
	s_waitcnt vmcnt(5)
	v_mov_b32_e32 v52, v51
	v_lshl_add_u64 v[4:5], v[2:3], 0, s[8:9]
	v_readlane_b32 s8, v254, 61
	v_readlane_b32 s9, v254, 62
	global_load_dword v63, v[4:5], off
	s_waitcnt vmcnt(5)
	v_mov_b32_e32 v54, v53
	v_lshl_add_u64 v[4:5], v[2:3], 0, s[8:9]
	v_readlane_b32 s8, v254, 63
	v_readlane_b32 s9, v255, 0
	global_load_dword v65, v[4:5], off
	s_waitcnt vmcnt(5)
	v_mov_b32_e32 v56, v55
	v_lshl_add_u64 v[4:5], v[2:3], 0, s[8:9]
	v_readlane_b32 s8, v255, 1
	v_readlane_b32 s9, v255, 2
	global_load_dword v67, v[4:5], off
	s_waitcnt vmcnt(5)
	v_mov_b32_e32 v58, v57
	v_lshl_add_u64 v[4:5], v[2:3], 0, s[8:9]
	v_readlane_b32 s8, v255, 3
	v_readlane_b32 s9, v255, 4
	global_load_dword v69, v[4:5], off
	s_waitcnt vmcnt(5)
	v_mov_b32_e32 v60, v59
	v_lshl_add_u64 v[4:5], v[2:3], 0, s[8:9]
	v_readlane_b32 s8, v255, 5
	v_readlane_b32 s9, v255, 6
	global_load_dword v71, v[4:5], off
	s_waitcnt vmcnt(5)
	v_mov_b32_e32 v62, v61
	v_lshl_add_u64 v[4:5], v[2:3], 0, s[8:9]
	v_readlane_b32 s8, v255, 7
	v_readlane_b32 s9, v255, 8
	global_load_dword v73, v[4:5], off
	s_waitcnt vmcnt(5)
	v_mov_b32_e32 v64, v63
	v_lshl_add_u64 v[4:5], v[2:3], 0, s[8:9]
	v_readlane_b32 s8, v255, 9
	v_readlane_b32 s9, v255, 10
	global_load_dword v75, v[4:5], off
	s_waitcnt vmcnt(5)
	v_mov_b32_e32 v66, v65
	v_lshl_add_u64 v[4:5], v[2:3], 0, s[8:9]
	v_readlane_b32 s8, v255, 11
	v_readlane_b32 s9, v255, 12
	global_load_dword v77, v[4:5], off
	s_waitcnt vmcnt(5)
	v_mov_b32_e32 v68, v67
	v_lshl_add_u64 v[4:5], v[2:3], 0, s[8:9]
	v_readlane_b32 s8, v255, 13
	v_readlane_b32 s9, v255, 14
	global_load_dword v79, v[4:5], off
	s_waitcnt vmcnt(5)
	v_mov_b32_e32 v70, v69
	v_lshl_add_u64 v[4:5], v[2:3], 0, s[8:9]
	v_readlane_b32 s8, v255, 15
	v_readlane_b32 s9, v255, 16
	global_load_dword v81, v[4:5], off
	s_waitcnt vmcnt(5)
	v_mov_b32_e32 v72, v71
	v_lshl_add_u64 v[4:5], v[2:3], 0, s[8:9]
	v_readlane_b32 s8, v255, 17
	v_readlane_b32 s9, v255, 18
	global_load_dword v83, v[4:5], off
	s_waitcnt vmcnt(5)
	v_mov_b32_e32 v74, v73
	v_lshl_add_u64 v[4:5], v[2:3], 0, s[8:9]
	v_readlane_b32 s8, v255, 19
	v_readlane_b32 s9, v255, 20
	global_load_dword v85, v[4:5], off
	s_waitcnt vmcnt(5)
	v_mov_b32_e32 v76, v75
	v_lshl_add_u64 v[4:5], v[2:3], 0, s[8:9]
	v_readlane_b32 s8, v255, 21
	v_readlane_b32 s9, v255, 22
	global_load_dword v87, v[4:5], off
	s_waitcnt vmcnt(5)
	v_mov_b32_e32 v78, v77
	v_lshl_add_u64 v[4:5], v[2:3], 0, s[8:9]
	v_readlane_b32 s8, v254, 37
	v_readlane_b32 s9, v254, 38
	global_load_dword v89, v[4:5], off
	s_waitcnt vmcnt(5)
	v_mov_b32_e32 v80, v79
	v_lshl_add_u64 v[4:5], v[2:3], 0, s[8:9]
	v_readlane_b32 s8, v254, 35
	v_readlane_b32 s9, v254, 36
	global_load_dword v91, v[4:5], off
	s_waitcnt vmcnt(5)
	v_mov_b32_e32 v82, v81
	v_lshl_add_u64 v[4:5], v[2:3], 0, s[8:9]
	v_readlane_b32 s8, v255, 23
	v_readlane_b32 s9, v255, 24
	global_load_dword v93, v[4:5], off
	s_waitcnt vmcnt(5)
	v_mov_b32_e32 v84, v83
	v_lshl_add_u64 v[4:5], v[2:3], 0, s[8:9]
	global_load_dword v95, v[4:5], off
	v_lshl_add_u64 v[4:5], v[2:3], 0, s[68:69]
	s_lshl_b64 s[8:9], s[84:85], 2
	global_load_dword v97, v[4:5], off
	v_lshl_add_u64 v[4:5], v[2:3], 0, s[94:95]
	v_lshl_add_u64 v[2:3], v[2:3], 0, s[88:89]
	s_add_u32 s10, s48, s8
	global_load_dword v99, v[4:5], off
	global_load_dword v101, v[2:3], off
	s_addc_u32 s11, s49, s9
	v_lshlrev_b32_e32 v2, 2, v1
	v_and_b32_e32 v12, 0xfc, v2
	s_add_u32 s8, s50, s8
	v_lshlrev_b32_e32 v6, 2, v12
	s_addc_u32 s9, s51, s9
	s_min_i32 s5, s6, 5
	global_load_dwordx4 v[2:5], v6, s[10:11]
	s_addk_i32 s5, 0x58
	v_readlane_b32 s10, v250, 29
	s_add_i32 s7, s5, s10
	v_lshlrev_b32_e32 v130, 1, v12
	s_max_i32 s7, s7, 0
	v_readlane_b32 s11, v250, 30
	s_min_i32 s40, s6, 13
	v_lshl_add_u64 v[102:103], s[80:81], 0, v[130:131]
	s_add_i32 s7, s7, s11
	s_addk_i32 s40, 0x50
	global_load_dwordx4 v[6:9], v6, s[8:9]
	v_mad_u64_u32 v[12:13], s[8:9], s7, v238, v[102:103]
	s_add_i32 s7, s40, s10
	s_max_i32 s7, s7, 0
	s_min_i32 s41, s6, 21
	s_add_i32 s7, s7, s11
	s_addk_i32 s41, 0x48
	global_load_dwordx2 v[106:107], v[12:13], off offset:1536
	global_load_dwordx2 v[104:105], v[12:13], off offset:1024
	v_mad_u64_u32 v[12:13], s[8:9], s7, v238, v[102:103]
	s_add_i32 s7, s41, s10
	s_max_i32 s7, s7, 0
	s_min_i32 s44, s6, 29
	s_add_i32 s7, s7, s11
	s_add_i32 s44, s44, 64
	global_load_dwordx2 v[112:113], v[12:13], off offset:1536
	global_load_dwordx2 v[110:111], v[12:13], off offset:1024
	v_mad_u64_u32 v[12:13], s[8:9], s7, v238, v[102:103]
	s_add_i32 s7, s44, s10
	s_max_i32 s7, s7, 0
	s_min_i32 s45, s6, 37
	s_add_i32 s7, s7, s11
	s_add_i32 s45, s45, 56
	global_load_dwordx2 v[116:117], v[12:13], off offset:1536
	global_load_dwordx2 v[114:115], v[12:13], off offset:1024
	v_mad_u64_u32 v[12:13], s[8:9], s7, v238, v[102:103]
	s_add_i32 s7, s45, s10
	s_max_i32 s7, s7, 0
	s_min_i32 s46, s6, 45
	s_add_i32 s7, s7, s11
	s_add_i32 s46, s46, 48
	global_load_dwordx2 v[120:121], v[12:13], off offset:1536
	global_load_dwordx2 v[118:119], v[12:13], off offset:1024
	v_mad_u64_u32 v[12:13], s[8:9], s7, v238, v[102:103]
	s_add_i32 s7, s46, s10
	s_max_i32 s7, s7, 0
	s_min_i32 s47, s6, 53
	s_add_i32 s7, s7, s11
	s_add_i32 s47, s47, 40
	global_load_dwordx2 v[124:125], v[12:13], off offset:1536
	global_load_dwordx2 v[122:123], v[12:13], off offset:1024
	v_mad_u64_u32 v[12:13], s[8:9], s7, v238, v[102:103]
	s_add_i32 s7, s47, s10
	s_max_i32 s7, s7, 0
	s_min_i32 s48, s6, 61
	s_add_i32 s7, s7, s11
	s_add_i32 s48, s48, 32
	global_load_dwordx2 v[128:129], v[12:13], off offset:1536
	global_load_dwordx2 v[126:127], v[12:13], off offset:1024
	v_mad_u64_u32 v[12:13], s[8:9], s7, v238, v[102:103]
	s_add_i32 s7, s48, s10
	s_max_i32 s7, s7, 0
	s_min_i32 s49, s6, 0x45
	s_add_i32 s7, s7, s11
	s_add_i32 s49, s49, 24
	global_load_dwordx2 v[134:135], v[12:13], off offset:1536
	global_load_dwordx2 v[132:133], v[12:13], off offset:1024
	v_mad_u64_u32 v[12:13], s[8:9], s7, v238, v[102:103]
	s_add_i32 s7, s49, s10
	s_max_i32 s7, s7, 0
	s_min_i32 s50, s6, 0x4d
	s_add_i32 s7, s7, s11
	s_add_i32 s50, s50, 16
	global_load_dwordx2 v[138:139], v[12:13], off offset:1536
	global_load_dwordx2 v[136:137], v[12:13], off offset:1024
	v_mad_u64_u32 v[12:13], s[8:9], s7, v238, v[102:103]
	s_add_i32 s7, s50, s10
	s_max_i32 s7, s7, 0
	s_min_i32 s51, s6, 0x55
	s_add_i32 s7, s7, s11
	s_add_i32 s51, s51, 8
	global_load_dwordx2 v[142:143], v[12:13], off offset:1536
	global_load_dwordx2 v[140:141], v[12:13], off offset:1024
	v_mad_u64_u32 v[12:13], s[8:9], s7, v238, v[102:103]
	s_add_i32 s7, s51, s10
	s_min_i32 s56, s6, 0x5d
	s_max_i32 s7, s7, 0
	s_add_i32 s6, s56, s10
	s_add_i32 s7, s7, s11
	s_max_i32 s6, s6, 0
	global_load_dwordx2 v[146:147], v[12:13], off offset:1536
	global_load_dwordx2 v[144:145], v[12:13], off offset:1024
	v_mad_u64_u32 v[12:13], s[8:9], s7, v238, v[102:103]
	s_add_i32 s6, s6, s11
	global_load_dwordx2 v[150:151], v[12:13], off offset:1536
	global_load_dwordx2 v[148:149], v[12:13], off offset:1024
	v_mad_u64_u32 v[12:13], s[6:7], s6, v238, v[102:103]
	global_load_dwordx2 v[154:155], v[12:13], off offset:1536
	global_load_dwordx2 v[152:153], v[12:13], off offset:1024
	v_or_b32_sdwa v12, v1, s84 dst_sel:DWORD dst_unused:UNUSED_PAD src0_sel:BYTE_0 src1_sel:DWORD
	v_ashrrev_i32_e32 v13, 31, v12
	v_lshl_add_u64 v[10:11], v[12:13], 2, v[10:11]
	global_load_dword v108, v[10:11], off
	s_waitcnt vmcnt(35)
	v_mov_b32_e32 v86, v85
	s_waitcnt vmcnt(34)
	v_mov_b32_e32 v88, v87
	s_waitcnt vmcnt(33)
	v_mov_b32_e32 v90, v89
	s_waitcnt vmcnt(32)
	v_mov_b32_e32 v92, v91
	s_waitcnt vmcnt(31)
	v_mov_b32_e32 v94, v93
	s_waitcnt vmcnt(30)
	v_mov_b32_e32 v96, v95
	s_waitcnt vmcnt(29)
	v_mov_b32_e32 v98, v97
	s_waitcnt vmcnt(28)
	v_mov_b32_e32 v100, v99
	s_branch .LBB0_289
.LBB0_288:
	s_add_i32 s59, s58, 0xffffff80
	s_cmpk_lt_i32 s59, 0x100
	s_cselect_b32 s7, s58, s59
	s_lshl_b32 s7, s7, 6
	s_and_b32 s8, s7, 0xfc0
	s_sub_i32 s10, s8, 30
	s_add_i32 s8, s10, s56
	s_and_b32 s7, s7, 0xfffff000
	s_max_i32 s8, s8, 0
	s_add_i32 s8, s8, s7
	v_and_b32_e32 v14, 0xff, v10
	v_mad_i64_i32 v[10:11], s[8:9], s8, v238, v[102:103]
	s_add_i32 s8, s10, s51
	s_max_i32 s8, s8, 0
	s_add_i32 s8, s8, s7
	v_mad_i64_i32 v[12:13], s[8:9], s8, v238, v[102:103]
	s_add_i32 s8, s10, s50
	s_max_i32 s8, s8, 0
	s_add_i32 s8, s8, s7
	s_waitcnt lgkmcnt(0)
	s_barrier
	global_load_dwordx2 v[152:153], v[10:11], off offset:1024
	global_load_dwordx2 v[154:155], v[10:11], off offset:1536
	global_load_dwordx2 v[148:149], v[12:13], off offset:1024
	global_load_dwordx2 v[150:151], v[12:13], off offset:1536
	v_mad_i64_i32 v[10:11], s[8:9], s8, v238, v[102:103]
	s_add_i32 s8, s10, s49
	s_max_i32 s8, s8, 0
	s_add_i32 s8, s8, s7
	v_mad_i64_i32 v[12:13], s[8:9], s8, v238, v[102:103]
	s_add_i32 s8, s10, s48
	s_max_i32 s8, s8, 0
	s_add_i32 s8, s8, s7
	global_load_dwordx2 v[144:145], v[10:11], off offset:1024
	global_load_dwordx2 v[146:147], v[10:11], off offset:1536
	global_load_dwordx2 v[140:141], v[12:13], off offset:1024
	global_load_dwordx2 v[142:143], v[12:13], off offset:1536
	v_mad_i64_i32 v[10:11], s[8:9], s8, v238, v[102:103]
	s_add_i32 s8, s10, s47
	s_max_i32 s8, s8, 0
	s_add_i32 s8, s8, s7
	v_mad_i64_i32 v[12:13], s[8:9], s8, v238, v[102:103]
	s_add_i32 s8, s10, s46
	s_max_i32 s8, s8, 0
	s_add_i32 s8, s8, s7
	global_load_dwordx2 v[136:137], v[10:11], off offset:1024
	global_load_dwordx2 v[138:139], v[10:11], off offset:1536
	global_load_dwordx2 v[132:133], v[12:13], off offset:1024
	global_load_dwordx2 v[134:135], v[12:13], off offset:1536
	v_mad_i64_i32 v[10:11], s[8:9], s8, v238, v[102:103]
	s_add_i32 s8, s10, s45
	s_max_i32 s8, s8, 0
	s_add_i32 s8, s8, s7
	v_mad_i64_i32 v[12:13], s[8:9], s8, v238, v[102:103]
	s_add_i32 s8, s10, s44
	s_max_i32 s8, s8, 0
	s_add_i32 s8, s8, s7
	global_load_dwordx2 v[126:127], v[10:11], off offset:1024
	global_load_dwordx2 v[128:129], v[10:11], off offset:1536
	global_load_dwordx2 v[122:123], v[12:13], off offset:1024
	global_load_dwordx2 v[124:125], v[12:13], off offset:1536
	v_mad_i64_i32 v[10:11], s[8:9], s8, v238, v[102:103]
	s_add_i32 s8, s10, s41
	s_max_i32 s8, s8, 0
	s_add_i32 s8, s8, s7
	v_mad_i64_i32 v[12:13], s[8:9], s8, v238, v[102:103]
	s_add_i32 s8, s10, s40
	s_max_i32 s8, s8, 0
	s_add_i32 s8, s8, s7
	global_load_dwordx2 v[118:119], v[10:11], off offset:1024
	global_load_dwordx2 v[120:121], v[10:11], off offset:1536
	global_load_dwordx2 v[114:115], v[12:13], off offset:1024
	global_load_dwordx2 v[116:117], v[12:13], off offset:1536
	v_mad_i64_i32 v[10:11], s[8:9], s8, v238, v[102:103]
	s_add_i32 s10, s10, s5
	s_lshl_b32 s6, s6, 7
	s_max_i32 s8, s10, 0
	s_and_b32 s6, s6, 0xffff8000
	s_add_i32 s8, s8, s7
	s_add_i32 s6, s6, 0
	v_mad_i64_i32 v[12:13], s[8:9], s8, v238, v[102:103]
	v_lshl_add_u32 v163, v14, 2, s6
	global_load_dwordx2 v[110:111], v[10:11], off offset:1024
	global_load_dwordx2 v[112:113], v[10:11], off offset:1536
	global_load_dwordx2 v[104:105], v[12:13], off offset:1024
	global_load_dwordx2 v[106:107], v[12:13], off offset:1536
	ds_read2st64_b32 v[26:27], v163 offset1:4
	ds_read2st64_b32 v[28:29], v163 offset0:8 offset1:12
	ds_read2st64_b32 v[30:31], v163 offset0:16 offset1:20
	ds_read2st64_b32 v[32:33], v163 offset0:24 offset1:28
	ds_read2st64_b32 v[160:161], v163 offset0:32 offset1:36
	ds_read2st64_b32 v[158:159], v163 offset0:40 offset1:44
	ds_read2st64_b32 v[156:157], v163 offset0:48 offset1:52
	ds_read2st64_b32 v[40:41], v163 offset0:56 offset1:60
	ds_read2st64_b32 v[38:39], v163 offset0:64 offset1:68
	ds_read2st64_b32 v[36:37], v163 offset0:72 offset1:76
	ds_read2st64_b32 v[34:35], v163 offset0:80 offset1:84
	ds_read2st64_b32 v[24:25], v163 offset0:88 offset1:92
	ds_read2st64_b32 v[22:23], v163 offset0:96 offset1:100
	ds_read2st64_b32 v[20:21], v163 offset0:104 offset1:108
	ds_read2st64_b32 v[10:11], v163 offset0:120 offset1:124
	ds_read2st64_b32 v[18:19], v163 offset0:112 offset1:116
	ds_read2st64_b32 v[12:13], v163 offset0:128 offset1:132
	ds_read2st64_b32 v[14:15], v163 offset0:136 offset1:140
	ds_read2st64_b32 v[16:17], v163 offset0:144 offset1:148
	s_waitcnt vmcnt(51) lgkmcnt(4)
	v_mul_f32_e32 v109, v101, v10
	v_mul_f32_e32 v165, v42, v27
	s_waitcnt vmcnt(24)
	v_mov_b32_e32 v164, v108
	v_pk_fma_f32 v[26:27], v[42:43], v[26:27], v[108:109]
	v_pk_fma_f32 v[164:165], v[44:45], v[28:29], v[164:165]
	v_pk_fma_f32 v[26:27], v[46:47], v[28:29], v[26:27]
	v_pk_fma_f32 v[164:165], v[48:49], v[30:31], v[164:165]
	v_pk_fma_f32 v[26:27], v[50:51], v[30:31], v[26:27]
	v_pk_fma_f32 v[164:165], v[52:53], v[32:33], v[164:165]
	v_pk_fma_f32 v[26:27], v[54:55], v[32:33], v[26:27]
	v_pk_fma_f32 v[164:165], v[56:57], v[160:161], v[164:165]
	v_pk_fma_f32 v[26:27], v[58:59], v[160:161], v[26:27]
	v_pk_fma_f32 v[164:165], v[60:61], v[158:159], v[164:165]
	v_pk_fma_f32 v[26:27], v[62:63], v[158:159], v[26:27]
	v_pk_fma_f32 v[164:165], v[64:65], v[156:157], v[164:165]
	v_pk_fma_f32 v[26:27], v[66:67], v[156:157], v[26:27]
	v_pk_fma_f32 v[164:165], v[68:69], v[40:41], v[164:165]
	v_pk_fma_f32 v[26:27], v[70:71], v[40:41], v[26:27]
	v_pk_fma_f32 v[164:165], v[72:73], v[38:39], v[164:165]
	v_pk_fma_f32 v[26:27], v[74:75], v[38:39], v[26:27]
	v_pk_fma_f32 v[164:165], v[76:77], v[36:37], v[164:165]
	v_pk_fma_f32 v[26:27], v[78:79], v[36:37], v[26:27]
	v_pk_fma_f32 v[164:165], v[80:81], v[34:35], v[164:165]
	v_pk_fma_f32 v[26:27], v[82:83], v[34:35], v[26:27]
	v_pk_fma_f32 v[164:165], v[84:85], v[24:25], v[164:165]
	v_pk_fma_f32 v[26:27], v[86:87], v[24:25], v[26:27]
	v_pk_fma_f32 v[164:165], v[88:89], v[22:23], v[164:165]
	v_pk_fma_f32 v[26:27], v[90:91], v[22:23], v[26:27]
	v_pk_fma_f32 v[164:165], v[92:93], v[20:21], v[164:165]
	v_pk_fma_f32 v[26:27], v[94:95], v[20:21], v[26:27]
	s_waitcnt lgkmcnt(3)
	v_pk_fma_f32 v[164:165], v[96:97], v[18:19], v[164:165]
	v_pk_fma_f32 v[26:27], v[98:99], v[18:19], v[26:27]
	v_pk_fma_f32 v[166:167], v[100:101], v[10:11], v[164:165]
	v_add_f32_e32 v164, v26, v27
	v_mul_f32_e32 v27, v42, v29
	v_mov_b32_e32 v26, v108
	v_pk_fma_f32 v[26:27], v[44:45], v[30:31], v[26:27]
	v_add_f32_e32 v165, v166, v167
	v_pk_fma_f32 v[26:27], v[48:49], v[32:33], v[26:27]
	s_waitcnt lgkmcnt(2)
	v_mul_f32_e32 v109, v101, v12
	v_pk_fma_f32 v[26:27], v[52:53], v[160:161], v[26:27]
	v_pk_fma_f32 v[28:29], v[42:43], v[28:29], v[108:109]
	v_pk_fma_f32 v[26:27], v[56:57], v[158:159], v[26:27]
	v_pk_fma_f32 v[28:29], v[46:47], v[30:31], v[28:29]
	v_pk_fma_f32 v[26:27], v[60:61], v[156:157], v[26:27]
	v_pk_fma_f32 v[28:29], v[50:51], v[32:33], v[28:29]
	v_pk_fma_f32 v[26:27], v[64:65], v[40:41], v[26:27]
	v_pk_fma_f32 v[28:29], v[54:55], v[160:161], v[28:29]
	v_pk_fma_f32 v[26:27], v[68:69], v[38:39], v[26:27]
	v_pk_fma_f32 v[28:29], v[58:59], v[158:159], v[28:29]
	v_pk_fma_f32 v[26:27], v[72:73], v[36:37], v[26:27]
	v_pk_fma_f32 v[28:29], v[62:63], v[156:157], v[28:29]
	v_pk_fma_f32 v[26:27], v[76:77], v[34:35], v[26:27]
	v_pk_fma_f32 v[28:29], v[66:67], v[40:41], v[28:29]
	v_pk_fma_f32 v[26:27], v[80:81], v[24:25], v[26:27]
	v_pk_fma_f32 v[28:29], v[70:71], v[38:39], v[28:29]
	v_pk_fma_f32 v[26:27], v[84:85], v[22:23], v[26:27]
	v_pk_fma_f32 v[28:29], v[74:75], v[36:37], v[28:29]
	v_pk_fma_f32 v[26:27], v[88:89], v[20:21], v[26:27]
	v_pk_fma_f32 v[28:29], v[78:79], v[34:35], v[28:29]
	v_pk_fma_f32 v[26:27], v[92:93], v[18:19], v[26:27]
	v_pk_fma_f32 v[28:29], v[82:83], v[24:25], v[28:29]
	v_pk_fma_f32 v[26:27], v[96:97], v[10:11], v[26:27]
	v_pk_fma_f32 v[28:29], v[86:87], v[22:23], v[28:29]
	v_pk_fma_f32 v[26:27], v[100:101], v[12:13], v[26:27]
	v_pk_fma_f32 v[28:29], v[90:91], v[20:21], v[28:29]
	v_add_f32_e32 v167, v26, v27
	v_mul_f32_e32 v27, v42, v31
	v_mov_b32_e32 v26, v108
	v_pk_fma_f32 v[26:27], v[44:45], v[32:33], v[26:27]
	v_pk_fma_f32 v[28:29], v[94:95], v[18:19], v[28:29]
	v_pk_fma_f32 v[26:27], v[48:49], v[160:161], v[26:27]
	v_pk_fma_f32 v[28:29], v[98:99], v[10:11], v[28:29]
	v_pk_fma_f32 v[26:27], v[52:53], v[158:159], v[26:27]
	s_waitcnt lgkmcnt(1)
	v_mul_f32_e32 v109, v101, v14
	v_pk_fma_f32 v[26:27], v[56:57], v[156:157], v[26:27]
	v_add_f32_e32 v166, v28, v29
	v_pk_fma_f32 v[26:27], v[60:61], v[40:41], v[26:27]
	v_pk_fma_f32 v[28:29], v[42:43], v[30:31], v[108:109]
	v_pk_fma_f32 v[26:27], v[64:65], v[38:39], v[26:27]
	v_pk_fma_f32 v[28:29], v[46:47], v[32:33], v[28:29]
	v_pk_fma_f32 v[26:27], v[68:69], v[36:37], v[26:27]
	v_pk_fma_f32 v[28:29], v[50:51], v[160:161], v[28:29]
	v_pk_fma_f32 v[26:27], v[72:73], v[34:35], v[26:27]
	v_pk_fma_f32 v[28:29], v[54:55], v[158:159], v[28:29]
	v_pk_fma_f32 v[26:27], v[76:77], v[24:25], v[26:27]
	v_pk_fma_f32 v[28:29], v[58:59], v[156:157], v[28:29]
	v_pk_fma_f32 v[26:27], v[80:81], v[22:23], v[26:27]
	v_pk_fma_f32 v[28:29], v[62:63], v[40:41], v[28:29]
	v_pk_fma_f32 v[26:27], v[84:85], v[20:21], v[26:27]
	v_pk_fma_f32 v[28:29], v[66:67], v[38:39], v[28:29]
	v_pk_fma_f32 v[26:27], v[88:89], v[18:19], v[26:27]
	v_pk_fma_f32 v[28:29], v[70:71], v[36:37], v[28:29]
	v_pk_fma_f32 v[26:27], v[92:93], v[10:11], v[26:27]
	v_pk_fma_f32 v[28:29], v[74:75], v[34:35], v[28:29]
	v_pk_fma_f32 v[26:27], v[96:97], v[12:13], v[26:27]
	v_pk_fma_f32 v[28:29], v[78:79], v[24:25], v[28:29]
	v_pk_fma_f32 v[26:27], v[100:101], v[14:15], v[26:27]
	v_pk_fma_f32 v[28:29], v[82:83], v[22:23], v[28:29]
	v_add_f32_e32 v169, v26, v27
	v_mul_f32_e32 v27, v42, v33
	v_mov_b32_e32 v26, v108
	v_pk_fma_f32 v[26:27], v[44:45], v[160:161], v[26:27]
	v_pk_fma_f32 v[28:29], v[86:87], v[20:21], v[28:29]
	v_pk_fma_f32 v[26:27], v[48:49], v[158:159], v[26:27]
	v_pk_fma_f32 v[28:29], v[90:91], v[18:19], v[28:29]
	v_pk_fma_f32 v[26:27], v[52:53], v[156:157], v[26:27]
	v_pk_fma_f32 v[28:29], v[94:95], v[10:11], v[28:29]
	v_pk_fma_f32 v[26:27], v[56:57], v[40:41], v[26:27]
	v_pk_fma_f32 v[28:29], v[98:99], v[12:13], v[28:29]
	v_pk_fma_f32 v[26:27], v[60:61], v[38:39], v[26:27]
	s_waitcnt lgkmcnt(0)
	v_mul_f32_e32 v109, v101, v16
	v_pk_fma_f32 v[26:27], v[64:65], v[36:37], v[26:27]
	v_add_f32_e32 v168, v28, v29
	v_pk_fma_f32 v[26:27], v[68:69], v[34:35], v[26:27]
	v_pk_fma_f32 v[28:29], v[42:43], v[32:33], v[108:109]
	v_pk_fma_f32 v[26:27], v[72:73], v[24:25], v[26:27]
	v_pk_fma_f32 v[28:29], v[46:47], v[160:161], v[28:29]
	v_pk_fma_f32 v[26:27], v[76:77], v[22:23], v[26:27]
	v_pk_fma_f32 v[28:29], v[50:51], v[158:159], v[28:29]
	v_pk_fma_f32 v[26:27], v[80:81], v[20:21], v[26:27]
	v_pk_fma_f32 v[28:29], v[54:55], v[156:157], v[28:29]
	v_pk_fma_f32 v[26:27], v[84:85], v[18:19], v[26:27]
	v_pk_fma_f32 v[28:29], v[58:59], v[40:41], v[28:29]
	v_pk_fma_f32 v[26:27], v[88:89], v[10:11], v[26:27]
	v_mul_f32_e32 v173, v42, v161
	v_pk_fma_f32 v[26:27], v[92:93], v[12:13], v[26:27]
	v_pk_fma_f32 v[28:29], v[62:63], v[38:39], v[28:29]
	v_pk_fma_f32 v[26:27], v[96:97], v[14:15], v[26:27]
	v_pk_fma_f32 v[28:29], v[66:67], v[36:37], v[28:29]
	v_pk_fma_f32 v[30:31], v[100:101], v[16:17], v[26:27]
	ds_read2st64_b32 v[26:27], v163 offset0:152 offset1:156
	v_pk_fma_f32 v[28:29], v[70:71], v[34:35], v[28:29]
	v_add_f32_e32 v171, v30, v31
	v_pk_fma_f32 v[28:29], v[74:75], v[24:25], v[28:29]
	v_mov_b32_e32 v172, v108
	s_waitcnt lgkmcnt(0)
	v_mul_f32_e32 v109, v101, v26
	v_pk_fma_f32 v[160:161], v[42:43], v[160:161], v[108:109]
	v_pk_fma_f32 v[28:29], v[78:79], v[22:23], v[28:29]
	v_pk_fma_f32 v[160:161], v[46:47], v[158:159], v[160:161]
	v_pk_fma_f32 v[28:29], v[82:83], v[20:21], v[28:29]
	v_pk_fma_f32 v[160:161], v[50:51], v[156:157], v[160:161]
	v_pk_fma_f32 v[28:29], v[86:87], v[18:19], v[28:29]
	v_pk_fma_f32 v[160:161], v[54:55], v[40:41], v[160:161]
	v_pk_fma_f32 v[28:29], v[90:91], v[10:11], v[28:29]
	v_pk_fma_f32 v[160:161], v[58:59], v[38:39], v[160:161]
	v_pk_fma_f32 v[28:29], v[94:95], v[12:13], v[28:29]
	v_pk_fma_f32 v[160:161], v[62:63], v[36:37], v[160:161]
	v_pk_fma_f32 v[28:29], v[98:99], v[14:15], v[28:29]
	v_pk_fma_f32 v[160:161], v[66:67], v[34:35], v[160:161]
	v_add_f32_e32 v170, v28, v29
	v_pk_fma_f32 v[160:161], v[70:71], v[24:25], v[160:161]
	ds_read2st64_b32 v[28:29], v163 offset0:160 offset1:164
	ds_read2st64_b32 v[30:31], v163 offset0:168 offset1:172
	ds_read2st64_b32 v[32:33], v163 offset0:176 offset1:180
	v_pk_fma_f32 v[160:161], v[74:75], v[22:23], v[160:161]
	v_pk_fma_f32 v[172:173], v[44:45], v[158:159], v[172:173]
	v_pk_fma_f32 v[160:161], v[78:79], v[20:21], v[160:161]
	s_waitcnt lgkmcnt(2)
	v_mul_f32_e32 v109, v101, v28
	v_pk_fma_f32 v[160:161], v[82:83], v[18:19], v[160:161]
	v_pk_fma_f32 v[172:173], v[48:49], v[156:157], v[172:173]
	v_pk_fma_f32 v[160:161], v[86:87], v[10:11], v[160:161]
	v_pk_fma_f32 v[172:173], v[52:53], v[40:41], v[172:173]
	v_pk_fma_f32 v[160:161], v[90:91], v[12:13], v[160:161]
	v_pk_fma_f32 v[172:173], v[56:57], v[38:39], v[172:173]
	v_pk_fma_f32 v[160:161], v[94:95], v[14:15], v[160:161]
	v_pk_fma_f32 v[172:173], v[60:61], v[36:37], v[172:173]
	v_pk_fma_f32 v[160:161], v[98:99], v[16:17], v[160:161]
	v_pk_fma_f32 v[172:173], v[64:65], v[34:35], v[172:173]
	v_add_f32_e32 v174, v160, v161
	v_mul_f32_e32 v161, v42, v159
	v_pk_fma_f32 v[158:159], v[42:43], v[158:159], v[108:109]
	v_mov_b32_e32 v160, v108
	v_pk_fma_f32 v[158:159], v[46:47], v[156:157], v[158:159]
	s_waitcnt lgkmcnt(1)
	v_mul_f32_e32 v109, v101, v30
	v_pk_fma_f32 v[158:159], v[50:51], v[40:41], v[158:159]
	v_pk_fma_f32 v[160:161], v[44:45], v[156:157], v[160:161]
	v_pk_fma_f32 v[158:159], v[54:55], v[38:39], v[158:159]
	v_pk_fma_f32 v[160:161], v[48:49], v[40:41], v[160:161]
	v_pk_fma_f32 v[158:159], v[58:59], v[36:37], v[158:159]
	v_pk_fma_f32 v[172:173], v[68:69], v[24:25], v[172:173]
	v_pk_fma_f32 v[158:159], v[62:63], v[34:35], v[158:159]
	v_pk_fma_f32 v[172:173], v[72:73], v[22:23], v[172:173]
	v_pk_fma_f32 v[158:159], v[66:67], v[24:25], v[158:159]
	v_pk_fma_f32 v[172:173], v[76:77], v[20:21], v[172:173]
	v_pk_fma_f32 v[158:159], v[70:71], v[22:23], v[158:159]
	v_pk_fma_f32 v[172:173], v[80:81], v[18:19], v[172:173]
	v_pk_fma_f32 v[158:159], v[74:75], v[20:21], v[158:159]
	v_pk_fma_f32 v[172:173], v[84:85], v[10:11], v[172:173]
	v_pk_fma_f32 v[158:159], v[78:79], v[18:19], v[158:159]
	v_pk_fma_f32 v[172:173], v[88:89], v[12:13], v[172:173]
	v_pk_fma_f32 v[158:159], v[82:83], v[10:11], v[158:159]
	v_pk_fma_f32 v[172:173], v[92:93], v[14:15], v[172:173]
	v_pk_fma_f32 v[158:159], v[86:87], v[12:13], v[158:159]
	v_pk_fma_f32 v[172:173], v[96:97], v[16:17], v[172:173]
	v_pk_fma_f32 v[158:159], v[90:91], v[14:15], v[158:159]
	v_pk_fma_f32 v[160:161], v[52:53], v[38:39], v[160:161]
	v_pk_fma_f32 v[158:159], v[94:95], v[16:17], v[158:159]
	v_pk_fma_f32 v[172:173], v[100:101], v[26:27], v[172:173]
	v_pk_fma_f32 v[158:159], v[98:99], v[26:27], v[158:159]
	v_pk_fma_f32 v[160:161], v[56:57], v[36:37], v[160:161]
	v_add_f32_e32 v176, v158, v159
	v_mul_f32_e32 v159, v42, v157
	v_pk_fma_f32 v[156:157], v[42:43], v[156:157], v[108:109]
	v_mov_b32_e32 v158, v108
	v_pk_fma_f32 v[156:157], v[46:47], v[40:41], v[156:157]
	s_waitcnt lgkmcnt(0)
	v_mul_f32_e32 v109, v101, v32
	v_pk_fma_f32 v[156:157], v[50:51], v[38:39], v[156:157]
	v_pk_fma_f32 v[158:159], v[44:45], v[40:41], v[158:159]
	v_pk_fma_f32 v[156:157], v[54:55], v[36:37], v[156:157]
	v_pk_fma_f32 v[158:159], v[48:49], v[38:39], v[158:159]
	v_pk_fma_f32 v[156:157], v[58:59], v[34:35], v[156:157]
	v_pk_fma_f32 v[158:159], v[52:53], v[36:37], v[158:159]
	v_pk_fma_f32 v[156:157], v[62:63], v[24:25], v[156:157]
	v_pk_fma_f32 v[158:159], v[56:57], v[34:35], v[158:159]
	v_pk_fma_f32 v[156:157], v[66:67], v[22:23], v[156:157]
	v_add_f32_e32 v175, v172, v173
	v_pk_fma_f32 v[156:157], v[70:71], v[20:21], v[156:157]
	v_pk_fma_f32 v[160:161], v[60:61], v[34:35], v[160:161]
	v_pk_fma_f32 v[156:157], v[74:75], v[18:19], v[156:157]
	v_pk_fma_f32 v[158:159], v[60:61], v[24:25], v[158:159]
	v_pk_fma_f32 v[156:157], v[78:79], v[10:11], v[156:157]
	v_mul_f32_e32 v173, v42, v39
	v_pk_fma_f32 v[156:157], v[82:83], v[12:13], v[156:157]
	v_pk_fma_f32 v[160:161], v[64:65], v[24:25], v[160:161]
	v_pk_fma_f32 v[156:157], v[86:87], v[14:15], v[156:157]
	v_pk_fma_f32 v[158:159], v[64:65], v[22:23], v[158:159]
	v_pk_fma_f32 v[156:157], v[90:91], v[16:17], v[156:157]
	v_pk_fma_f32 v[160:161], v[68:69], v[22:23], v[160:161]
	v_pk_fma_f32 v[156:157], v[94:95], v[26:27], v[156:157]
	v_pk_fma_f32 v[158:159], v[68:69], v[20:21], v[158:159]
	v_pk_fma_f32 v[156:157], v[98:99], v[28:29], v[156:157]
	v_pk_fma_f32 v[160:161], v[72:73], v[20:21], v[160:161]
	v_add_f32_e32 v178, v156, v157
	v_mul_f32_e32 v157, v42, v41
	v_pk_fma_f32 v[40:41], v[42:43], v[40:41], v[108:109]
	v_mov_b32_e32 v156, v108
	v_pk_fma_f32 v[40:41], v[46:47], v[38:39], v[40:41]
	v_pk_fma_f32 v[156:157], v[44:45], v[38:39], v[156:157]
	v_pk_fma_f32 v[40:41], v[50:51], v[36:37], v[40:41]
	v_pk_fma_f32 v[156:157], v[48:49], v[36:37], v[156:157]
	v_pk_fma_f32 v[40:41], v[54:55], v[34:35], v[40:41]
	v_pk_fma_f32 v[156:157], v[52:53], v[34:35], v[156:157]
	v_pk_fma_f32 v[40:41], v[58:59], v[24:25], v[40:41]
	v_pk_fma_f32 v[156:157], v[56:57], v[24:25], v[156:157]
	v_pk_fma_f32 v[40:41], v[62:63], v[22:23], v[40:41]
	v_pk_fma_f32 v[156:157], v[60:61], v[22:23], v[156:157]
	v_pk_fma_f32 v[40:41], v[66:67], v[20:21], v[40:41]
	v_pk_fma_f32 v[156:157], v[64:65], v[20:21], v[156:157]
	v_pk_fma_f32 v[40:41], v[70:71], v[18:19], v[40:41]
	v_pk_fma_f32 v[156:157], v[68:69], v[18:19], v[156:157]
	v_pk_fma_f32 v[40:41], v[74:75], v[10:11], v[40:41]
	v_pk_fma_f32 v[158:159], v[72:73], v[18:19], v[158:159]
	v_pk_fma_f32 v[40:41], v[78:79], v[12:13], v[40:41]
	v_pk_fma_f32 v[156:157], v[72:73], v[10:11], v[156:157]
	v_pk_fma_f32 v[40:41], v[82:83], v[14:15], v[40:41]
	v_pk_fma_f32 v[160:161], v[76:77], v[18:19], v[160:161]
	v_pk_fma_f32 v[40:41], v[86:87], v[16:17], v[40:41]
	v_pk_fma_f32 v[158:159], v[76:77], v[10:11], v[158:159]
	v_pk_fma_f32 v[40:41], v[90:91], v[26:27], v[40:41]
	v_pk_fma_f32 v[156:157], v[76:77], v[12:13], v[156:157]
	v_pk_fma_f32 v[40:41], v[94:95], v[28:29], v[40:41]
	v_pk_fma_f32 v[160:161], v[80:81], v[10:11], v[160:161]
	v_pk_fma_f32 v[40:41], v[98:99], v[30:31], v[40:41]
	v_pk_fma_f32 v[158:159], v[80:81], v[12:13], v[158:159]
	v_add_f32_e32 v180, v40, v41
	ds_read2st64_b32 v[40:41], v163 offset0:184 offset1:188
	v_pk_fma_f32 v[156:157], v[80:81], v[14:15], v[156:157]
	v_pk_fma_f32 v[160:161], v[84:85], v[12:13], v[160:161]
	v_pk_fma_f32 v[158:159], v[84:85], v[14:15], v[158:159]
	v_pk_fma_f32 v[156:157], v[84:85], v[16:17], v[156:157]
	s_waitcnt lgkmcnt(0)
	v_mul_f32_e32 v109, v101, v40
	v_pk_fma_f32 v[38:39], v[42:43], v[38:39], v[108:109]
	v_pk_fma_f32 v[160:161], v[88:89], v[14:15], v[160:161]
	v_pk_fma_f32 v[38:39], v[46:47], v[36:37], v[38:39]
	v_pk_fma_f32 v[158:159], v[88:89], v[16:17], v[158:159]
	v_pk_fma_f32 v[38:39], v[50:51], v[34:35], v[38:39]
	v_pk_fma_f32 v[156:157], v[88:89], v[26:27], v[156:157]
	v_pk_fma_f32 v[38:39], v[54:55], v[24:25], v[38:39]
	v_pk_fma_f32 v[160:161], v[92:93], v[16:17], v[160:161]
	v_pk_fma_f32 v[38:39], v[58:59], v[22:23], v[38:39]
	v_pk_fma_f32 v[158:159], v[92:93], v[26:27], v[158:159]
	v_pk_fma_f32 v[38:39], v[62:63], v[20:21], v[38:39]
	v_pk_fma_f32 v[156:157], v[92:93], v[28:29], v[156:157]
	v_pk_fma_f32 v[38:39], v[66:67], v[18:19], v[38:39]
	v_pk_fma_f32 v[160:161], v[96:97], v[26:27], v[160:161]
	v_pk_fma_f32 v[38:39], v[70:71], v[10:11], v[38:39]
	v_pk_fma_f32 v[158:159], v[96:97], v[28:29], v[158:159]
	v_pk_fma_f32 v[38:39], v[74:75], v[12:13], v[38:39]
	v_pk_fma_f32 v[156:157], v[96:97], v[30:31], v[156:157]
	v_pk_fma_f32 v[38:39], v[78:79], v[14:15], v[38:39]
	v_pk_fma_f32 v[160:161], v[100:101], v[28:29], v[160:161]
	v_pk_fma_f32 v[158:159], v[100:101], v[30:31], v[158:159]
	v_pk_fma_f32 v[156:157], v[100:101], v[32:33], v[156:157]
	v_pk_fma_f32 v[38:39], v[82:83], v[16:17], v[38:39]
	v_add_f32_e32 v177, v160, v161
	v_add_f32_e32 v179, v158, v159
	v_add_f32_e32 v181, v156, v157
	ds_read2st64_b32 v[156:157], v163 offset0:192 offset1:196
	ds_read2st64_b32 v[158:159], v163 offset0:200 offset1:204
	ds_read2st64_b32 v[160:161], v163 offset0:208 offset1:212
	v_pk_fma_f32 v[38:39], v[86:87], v[26:27], v[38:39]
	v_mov_b32_e32 v172, v108
	v_pk_fma_f32 v[38:39], v[90:91], v[28:29], v[38:39]
	s_waitcnt lgkmcnt(2)
	v_mul_f32_e32 v109, v101, v156
	v_pk_fma_f32 v[38:39], v[94:95], v[30:31], v[38:39]
	v_pk_fma_f32 v[172:173], v[44:45], v[36:37], v[172:173]
	v_pk_fma_f32 v[38:39], v[98:99], v[32:33], v[38:39]
	v_pk_fma_f32 v[172:173], v[48:49], v[34:35], v[172:173]
	v_add_f32_e32 v182, v38, v39
	v_mul_f32_e32 v39, v42, v37
	v_pk_fma_f32 v[36:37], v[42:43], v[36:37], v[108:109]
	v_mov_b32_e32 v38, v108
	v_pk_fma_f32 v[36:37], v[46:47], v[34:35], v[36:37]
	s_waitcnt lgkmcnt(1)
	v_mul_f32_e32 v109, v101, v158
	v_pk_fma_f32 v[36:37], v[50:51], v[24:25], v[36:37]
	v_pk_fma_f32 v[38:39], v[44:45], v[34:35], v[38:39]
	v_pk_fma_f32 v[36:37], v[54:55], v[22:23], v[36:37]
	v_pk_fma_f32 v[172:173], v[52:53], v[24:25], v[172:173]
	v_pk_fma_f32 v[36:37], v[58:59], v[20:21], v[36:37]
	v_pk_fma_f32 v[38:39], v[48:49], v[24:25], v[38:39]
	v_pk_fma_f32 v[36:37], v[62:63], v[18:19], v[36:37]
	v_pk_fma_f32 v[172:173], v[56:57], v[22:23], v[172:173]
	v_pk_fma_f32 v[36:37], v[66:67], v[10:11], v[36:37]
	v_pk_fma_f32 v[172:173], v[60:61], v[20:21], v[172:173]
	v_pk_fma_f32 v[36:37], v[70:71], v[12:13], v[36:37]
	v_pk_fma_f32 v[172:173], v[64:65], v[18:19], v[172:173]
	v_pk_fma_f32 v[36:37], v[74:75], v[14:15], v[36:37]
	v_pk_fma_f32 v[172:173], v[68:69], v[10:11], v[172:173]
	v_pk_fma_f32 v[36:37], v[78:79], v[16:17], v[36:37]
	v_pk_fma_f32 v[172:173], v[72:73], v[12:13], v[172:173]
	v_pk_fma_f32 v[36:37], v[82:83], v[26:27], v[36:37]
	v_pk_fma_f32 v[172:173], v[76:77], v[14:15], v[172:173]
	v_pk_fma_f32 v[36:37], v[86:87], v[28:29], v[36:37]
	v_pk_fma_f32 v[172:173], v[80:81], v[16:17], v[172:173]
	v_pk_fma_f32 v[36:37], v[90:91], v[30:31], v[36:37]
	v_pk_fma_f32 v[172:173], v[84:85], v[26:27], v[172:173]
	v_pk_fma_f32 v[36:37], v[94:95], v[32:33], v[36:37]
	v_pk_fma_f32 v[172:173], v[88:89], v[28:29], v[172:173]
	v_pk_fma_f32 v[36:37], v[98:99], v[40:41], v[36:37]
	v_pk_fma_f32 v[172:173], v[92:93], v[30:31], v[172:173]
	v_add_f32_e32 v184, v36, v37
	v_mul_f32_e32 v37, v42, v35
	v_pk_fma_f32 v[34:35], v[42:43], v[34:35], v[108:109]
	v_mov_b32_e32 v36, v108
	v_pk_fma_f32 v[34:35], v[46:47], v[24:25], v[34:35]
	s_waitcnt lgkmcnt(0)
	v_mul_f32_e32 v109, v101, v160
	v_pk_fma_f32 v[34:35], v[50:51], v[22:23], v[34:35]
	v_pk_fma_f32 v[36:37], v[44:45], v[24:25], v[36:37]
	v_pk_fma_f32 v[34:35], v[54:55], v[20:21], v[34:35]
	v_pk_fma_f32 v[36:37], v[48:49], v[22:23], v[36:37]
	v_pk_fma_f32 v[34:35], v[58:59], v[18:19], v[34:35]
	v_pk_fma_f32 v[172:173], v[96:97], v[32:33], v[172:173]
	v_pk_fma_f32 v[34:35], v[62:63], v[10:11], v[34:35]
	v_pk_fma_f32 v[38:39], v[52:53], v[22:23], v[38:39]
	v_pk_fma_f32 v[34:35], v[66:67], v[12:13], v[34:35]
	v_pk_fma_f32 v[36:37], v[52:53], v[20:21], v[36:37]
	v_pk_fma_f32 v[34:35], v[70:71], v[14:15], v[34:35]
	v_pk_fma_f32 v[172:173], v[100:101], v[40:41], v[172:173]
	v_pk_fma_f32 v[34:35], v[74:75], v[16:17], v[34:35]
	v_pk_fma_f32 v[38:39], v[56:57], v[20:21], v[38:39]
	v_pk_fma_f32 v[34:35], v[78:79], v[26:27], v[34:35]
	v_pk_fma_f32 v[36:37], v[56:57], v[18:19], v[36:37]
	v_pk_fma_f32 v[34:35], v[82:83], v[28:29], v[34:35]
	v_add_f32_e32 v183, v172, v173
	v_pk_fma_f32 v[34:35], v[86:87], v[30:31], v[34:35]
	v_pk_fma_f32 v[38:39], v[60:61], v[18:19], v[38:39]
	v_pk_fma_f32 v[34:35], v[90:91], v[32:33], v[34:35]
	v_pk_fma_f32 v[36:37], v[60:61], v[10:11], v[36:37]
	v_pk_fma_f32 v[34:35], v[94:95], v[40:41], v[34:35]
	v_mul_f32_e32 v173, v42, v23
	v_pk_fma_f32 v[34:35], v[98:99], v[156:157], v[34:35]
	v_pk_fma_f32 v[38:39], v[64:65], v[10:11], v[38:39]
	v_add_f32_e32 v186, v34, v35
	v_mul_f32_e32 v35, v42, v25
	v_pk_fma_f32 v[24:25], v[42:43], v[24:25], v[108:109]
	v_mov_b32_e32 v34, v108
	v_pk_fma_f32 v[24:25], v[46:47], v[22:23], v[24:25]
	v_pk_fma_f32 v[34:35], v[44:45], v[22:23], v[34:35]
	v_pk_fma_f32 v[24:25], v[50:51], v[20:21], v[24:25]
	v_pk_fma_f32 v[34:35], v[48:49], v[20:21], v[34:35]
	v_pk_fma_f32 v[24:25], v[54:55], v[18:19], v[24:25]
	v_pk_fma_f32 v[34:35], v[52:53], v[18:19], v[34:35]
	v_pk_fma_f32 v[24:25], v[58:59], v[10:11], v[24:25]
	v_pk_fma_f32 v[34:35], v[56:57], v[10:11], v[34:35]
	v_pk_fma_f32 v[24:25], v[62:63], v[12:13], v[24:25]
	v_pk_fma_f32 v[34:35], v[60:61], v[12:13], v[34:35]
	v_pk_fma_f32 v[24:25], v[66:67], v[14:15], v[24:25]
	v_pk_fma_f32 v[36:37], v[64:65], v[12:13], v[36:37]
	v_pk_fma_f32 v[24:25], v[70:71], v[16:17], v[24:25]
	v_pk_fma_f32 v[34:35], v[64:65], v[14:15], v[34:35]
	v_pk_fma_f32 v[24:25], v[74:75], v[26:27], v[24:25]
	v_pk_fma_f32 v[38:39], v[68:69], v[12:13], v[38:39]
	v_pk_fma_f32 v[24:25], v[78:79], v[28:29], v[24:25]
	v_pk_fma_f32 v[36:37], v[68:69], v[14:15], v[36:37]
	v_pk_fma_f32 v[24:25], v[82:83], v[30:31], v[24:25]
	v_pk_fma_f32 v[34:35], v[68:69], v[16:17], v[34:35]
	v_pk_fma_f32 v[24:25], v[86:87], v[32:33], v[24:25]
	v_pk_fma_f32 v[38:39], v[72:73], v[14:15], v[38:39]
	v_pk_fma_f32 v[24:25], v[90:91], v[40:41], v[24:25]
	v_pk_fma_f32 v[36:37], v[72:73], v[16:17], v[36:37]
	v_pk_fma_f32 v[24:25], v[94:95], v[156:157], v[24:25]
	v_pk_fma_f32 v[34:35], v[72:73], v[26:27], v[34:35]
	v_pk_fma_f32 v[24:25], v[98:99], v[158:159], v[24:25]
	v_pk_fma_f32 v[38:39], v[76:77], v[16:17], v[38:39]
	v_add_f32_e32 v188, v24, v25
	ds_read2st64_b32 v[24:25], v163 offset0:216 offset1:220
	v_pk_fma_f32 v[36:37], v[76:77], v[26:27], v[36:37]
	v_pk_fma_f32 v[34:35], v[76:77], v[28:29], v[34:35]
	v_pk_fma_f32 v[38:39], v[80:81], v[26:27], v[38:39]
	v_pk_fma_f32 v[36:37], v[80:81], v[28:29], v[36:37]
	s_waitcnt lgkmcnt(0)
	v_mul_f32_e32 v109, v101, v24
	v_pk_fma_f32 v[22:23], v[42:43], v[22:23], v[108:109]
	v_pk_fma_f32 v[34:35], v[80:81], v[30:31], v[34:35]
	v_pk_fma_f32 v[22:23], v[46:47], v[20:21], v[22:23]
	v_pk_fma_f32 v[38:39], v[84:85], v[28:29], v[38:39]
	v_pk_fma_f32 v[22:23], v[50:51], v[18:19], v[22:23]
	v_pk_fma_f32 v[36:37], v[84:85], v[30:31], v[36:37]
	v_pk_fma_f32 v[22:23], v[54:55], v[10:11], v[22:23]
	v_pk_fma_f32 v[34:35], v[84:85], v[32:33], v[34:35]
	v_pk_fma_f32 v[22:23], v[58:59], v[12:13], v[22:23]
	v_pk_fma_f32 v[38:39], v[88:89], v[30:31], v[38:39]
	v_pk_fma_f32 v[22:23], v[62:63], v[14:15], v[22:23]
	v_pk_fma_f32 v[36:37], v[88:89], v[32:33], v[36:37]
	v_pk_fma_f32 v[22:23], v[66:67], v[16:17], v[22:23]
	v_pk_fma_f32 v[34:35], v[88:89], v[40:41], v[34:35]
	v_pk_fma_f32 v[22:23], v[70:71], v[26:27], v[22:23]
	v_pk_fma_f32 v[38:39], v[92:93], v[32:33], v[38:39]
	v_pk_fma_f32 v[36:37], v[92:93], v[40:41], v[36:37]
	v_pk_fma_f32 v[34:35], v[92:93], v[156:157], v[34:35]
	v_pk_fma_f32 v[22:23], v[74:75], v[28:29], v[22:23]
	v_pk_fma_f32 v[38:39], v[96:97], v[40:41], v[38:39]
	v_pk_fma_f32 v[36:37], v[96:97], v[156:157], v[36:37]
	v_pk_fma_f32 v[34:35], v[96:97], v[158:159], v[34:35]
	v_pk_fma_f32 v[22:23], v[78:79], v[30:31], v[22:23]
	v_pk_fma_f32 v[38:39], v[100:101], v[156:157], v[38:39]
	v_pk_fma_f32 v[36:37], v[100:101], v[158:159], v[36:37]
	v_pk_fma_f32 v[34:35], v[100:101], v[160:161], v[34:35]
	v_pk_fma_f32 v[22:23], v[82:83], v[32:33], v[22:23]
	v_add_f32_e32 v185, v38, v39
	v_add_f32_e32 v187, v36, v37
	v_add_f32_e32 v189, v34, v35
	ds_read2st64_b32 v[34:35], v163 offset0:224 offset1:228
	ds_read2st64_b32 v[36:37], v163 offset0:232 offset1:236
	ds_read2st64_b32 v[38:39], v163 offset0:240 offset1:244
	v_pk_fma_f32 v[22:23], v[86:87], v[40:41], v[22:23]
	v_mov_b32_e32 v172, v108
	v_pk_fma_f32 v[22:23], v[90:91], v[156:157], v[22:23]
	s_waitcnt lgkmcnt(2)
	v_mul_f32_e32 v109, v101, v34
	v_pk_fma_f32 v[22:23], v[94:95], v[158:159], v[22:23]
	v_pk_fma_f32 v[172:173], v[44:45], v[20:21], v[172:173]
	v_pk_fma_f32 v[22:23], v[98:99], v[160:161], v[22:23]
	v_pk_fma_f32 v[172:173], v[48:49], v[18:19], v[172:173]
	v_add_f32_e32 v190, v22, v23
	v_mul_f32_e32 v23, v42, v21
	v_pk_fma_f32 v[20:21], v[42:43], v[20:21], v[108:109]
	v_pk_fma_f32 v[172:173], v[52:53], v[10:11], v[172:173]
	v_pk_fma_f32 v[20:21], v[46:47], v[18:19], v[20:21]
	v_pk_fma_f32 v[172:173], v[56:57], v[12:13], v[172:173]
	v_pk_fma_f32 v[20:21], v[50:51], v[10:11], v[20:21]
	v_pk_fma_f32 v[172:173], v[60:61], v[14:15], v[172:173]
	v_pk_fma_f32 v[20:21], v[54:55], v[12:13], v[20:21]
	v_pk_fma_f32 v[172:173], v[64:65], v[16:17], v[172:173]
	v_pk_fma_f32 v[20:21], v[58:59], v[14:15], v[20:21]
	v_pk_fma_f32 v[172:173], v[68:69], v[26:27], v[172:173]
	v_pk_fma_f32 v[20:21], v[62:63], v[16:17], v[20:21]
	v_pk_fma_f32 v[172:173], v[72:73], v[28:29], v[172:173]
	v_pk_fma_f32 v[20:21], v[66:67], v[26:27], v[20:21]
	v_pk_fma_f32 v[172:173], v[76:77], v[30:31], v[172:173]
	v_pk_fma_f32 v[20:21], v[70:71], v[28:29], v[20:21]
	v_pk_fma_f32 v[172:173], v[80:81], v[32:33], v[172:173]
	v_pk_fma_f32 v[20:21], v[74:75], v[30:31], v[20:21]
	v_pk_fma_f32 v[172:173], v[84:85], v[40:41], v[172:173]
	v_pk_fma_f32 v[20:21], v[78:79], v[32:33], v[20:21]
	v_pk_fma_f32 v[172:173], v[88:89], v[156:157], v[172:173]
	v_pk_fma_f32 v[20:21], v[82:83], v[40:41], v[20:21]
	v_pk_fma_f32 v[172:173], v[92:93], v[158:159], v[172:173]
	v_pk_fma_f32 v[20:21], v[86:87], v[156:157], v[20:21]
	v_pk_fma_f32 v[172:173], v[96:97], v[160:161], v[172:173]
	v_pk_fma_f32 v[20:21], v[90:91], v[158:159], v[20:21]
	v_pk_fma_f32 v[172:173], v[100:101], v[24:25], v[172:173]
	v_pk_fma_f32 v[20:21], v[94:95], v[160:161], v[20:21]
	v_mov_b32_e32 v22, v108
	v_pk_fma_f32 v[20:21], v[98:99], v[24:25], v[20:21]
	s_waitcnt lgkmcnt(1)
	v_mul_f32_e32 v109, v101, v36
	v_add_f32_e32 v172, v172, v173
	v_pk_fma_f32 v[22:23], v[44:45], v[18:19], v[22:23]
	v_add_f32_e32 v173, v20, v21
	v_mul_f32_e32 v21, v42, v19
	v_pk_fma_f32 v[18:19], v[42:43], v[18:19], v[108:109]
	v_pk_fma_f32 v[22:23], v[48:49], v[10:11], v[22:23]
	v_pk_fma_f32 v[18:19], v[46:47], v[10:11], v[18:19]
	v_pk_fma_f32 v[22:23], v[52:53], v[12:13], v[22:23]
	v_pk_fma_f32 v[18:19], v[50:51], v[12:13], v[18:19]
	v_pk_fma_f32 v[22:23], v[56:57], v[14:15], v[22:23]
	v_pk_fma_f32 v[18:19], v[54:55], v[14:15], v[18:19]
	v_pk_fma_f32 v[22:23], v[60:61], v[16:17], v[22:23]
	v_pk_fma_f32 v[18:19], v[58:59], v[16:17], v[18:19]
	v_pk_fma_f32 v[22:23], v[64:65], v[26:27], v[22:23]
	v_pk_fma_f32 v[18:19], v[62:63], v[26:27], v[18:19]
	v_pk_fma_f32 v[22:23], v[68:69], v[28:29], v[22:23]
	v_pk_fma_f32 v[18:19], v[66:67], v[28:29], v[18:19]
	v_pk_fma_f32 v[22:23], v[72:73], v[30:31], v[22:23]
	v_pk_fma_f32 v[18:19], v[70:71], v[30:31], v[18:19]
	v_pk_fma_f32 v[22:23], v[76:77], v[32:33], v[22:23]
	v_pk_fma_f32 v[18:19], v[74:75], v[32:33], v[18:19]
	v_pk_fma_f32 v[22:23], v[80:81], v[40:41], v[22:23]
	v_pk_fma_f32 v[18:19], v[78:79], v[40:41], v[18:19]
	v_pk_fma_f32 v[22:23], v[84:85], v[156:157], v[22:23]
	v_pk_fma_f32 v[18:19], v[82:83], v[156:157], v[18:19]
	v_pk_fma_f32 v[22:23], v[88:89], v[158:159], v[22:23]
	v_pk_fma_f32 v[18:19], v[86:87], v[158:159], v[18:19]
	v_pk_fma_f32 v[22:23], v[92:93], v[160:161], v[22:23]
	v_pk_fma_f32 v[18:19], v[90:91], v[160:161], v[18:19]
	v_pk_fma_f32 v[22:23], v[96:97], v[24:25], v[22:23]
	v_pk_fma_f32 v[18:19], v[94:95], v[24:25], v[18:19]
	v_pk_fma_f32 v[22:23], v[100:101], v[34:35], v[22:23]
	v_pk_fma_f32 v[18:19], v[98:99], v[34:35], v[18:19]
	v_add_f32_e32 v22, v22, v23
	v_mov_b32_e32 v20, v108
	v_add_f32_e32 v23, v18, v19
	s_waitcnt lgkmcnt(0)
	v_mul_f32_e32 v109, v101, v38
	v_mul_f32_e32 v19, v42, v11
	v_mov_b32_e32 v18, v108
	v_pk_fma_f32 v[20:21], v[44:45], v[10:11], v[20:21]
	v_pk_fma_f32 v[10:11], v[42:43], v[10:11], v[108:109]
	v_pk_fma_f32 v[18:19], v[44:45], v[12:13], v[18:19]
	v_pk_fma_f32 v[20:21], v[48:49], v[12:13], v[20:21]
	v_pk_fma_f32 v[10:11], v[46:47], v[12:13], v[10:11]
	v_pk_fma_f32 v[12:13], v[48:49], v[14:15], v[18:19]
	v_pk_fma_f32 v[20:21], v[52:53], v[14:15], v[20:21]
	v_pk_fma_f32 v[10:11], v[50:51], v[14:15], v[10:11]
	v_pk_fma_f32 v[12:13], v[52:53], v[16:17], v[12:13]
	v_pk_fma_f32 v[20:21], v[56:57], v[16:17], v[20:21]
	v_pk_fma_f32 v[10:11], v[54:55], v[16:17], v[10:11]
	v_pk_fma_f32 v[12:13], v[56:57], v[26:27], v[12:13]
	v_pk_fma_f32 v[20:21], v[60:61], v[26:27], v[20:21]
	v_pk_fma_f32 v[10:11], v[58:59], v[26:27], v[10:11]
	v_pk_fma_f32 v[12:13], v[60:61], v[28:29], v[12:13]
	v_pk_fma_f32 v[20:21], v[64:65], v[28:29], v[20:21]
	v_pk_fma_f32 v[10:11], v[62:63], v[28:29], v[10:11]
	v_pk_fma_f32 v[12:13], v[64:65], v[30:31], v[12:13]
	v_pk_fma_f32 v[20:21], v[68:69], v[30:31], v[20:21]
	v_pk_fma_f32 v[10:11], v[66:67], v[30:31], v[10:11]
	v_pk_fma_f32 v[12:13], v[68:69], v[32:33], v[12:13]
	v_pk_fma_f32 v[20:21], v[72:73], v[32:33], v[20:21]
	v_pk_fma_f32 v[10:11], v[70:71], v[32:33], v[10:11]
	v_pk_fma_f32 v[12:13], v[72:73], v[40:41], v[12:13]
	v_pk_fma_f32 v[20:21], v[76:77], v[40:41], v[20:21]
	v_pk_fma_f32 v[10:11], v[74:75], v[40:41], v[10:11]
	v_pk_fma_f32 v[12:13], v[76:77], v[156:157], v[12:13]
	v_pk_fma_f32 v[20:21], v[80:81], v[156:157], v[20:21]
	v_pk_fma_f32 v[10:11], v[78:79], v[156:157], v[10:11]
	v_pk_fma_f32 v[12:13], v[80:81], v[158:159], v[12:13]
	v_pk_fma_f32 v[20:21], v[84:85], v[158:159], v[20:21]
	v_pk_fma_f32 v[10:11], v[82:83], v[158:159], v[10:11]
	v_pk_fma_f32 v[12:13], v[84:85], v[160:161], v[12:13]
	v_pk_fma_f32 v[20:21], v[88:89], v[160:161], v[20:21]
	v_pk_fma_f32 v[10:11], v[86:87], v[160:161], v[10:11]
	v_pk_fma_f32 v[12:13], v[88:89], v[24:25], v[12:13]
	v_pk_fma_f32 v[20:21], v[92:93], v[24:25], v[20:21]
	v_pk_fma_f32 v[10:11], v[90:91], v[24:25], v[10:11]
	v_pk_fma_f32 v[12:13], v[92:93], v[34:35], v[12:13]
	s_lshl_b32 s6, s28, 10
	v_pk_fma_f32 v[20:21], v[96:97], v[34:35], v[20:21]
	v_pk_fma_f32 v[10:11], v[94:95], v[34:35], v[10:11]
	v_pk_fma_f32 v[12:13], v[96:97], v[36:37], v[12:13]
	s_add_i32 s6, s6, 0
	v_pk_fma_f32 v[20:21], v[100:101], v[36:37], v[20:21]
	v_pk_fma_f32 v[10:11], v[98:99], v[36:37], v[10:11]
	v_pk_fma_f32 v[12:13], v[100:101], v[38:39], v[12:13]
	v_add_u32_e32 v109, s6, v162
	v_add_f32_e32 v20, v20, v21
	v_add_f32_e32 v10, v10, v11
	v_add_f32_e32 v11, v12, v13
	s_barrier
	ds_write2st64_b32 v163, v164, v165 offset1:4
	ds_write2st64_b32 v163, v166, v167 offset0:8 offset1:12
	ds_write2st64_b32 v163, v168, v169 offset0:16 offset1:20
	ds_write2st64_b32 v163, v170, v171 offset0:24 offset1:28
	ds_write2st64_b32 v163, v174, v175 offset0:32 offset1:36
	ds_write2st64_b32 v163, v176, v177 offset0:40 offset1:44
	ds_write2st64_b32 v163, v178, v179 offset0:48 offset1:52
	ds_write2st64_b32 v163, v180, v181 offset0:56 offset1:60
	ds_write2st64_b32 v163, v182, v183 offset0:64 offset1:68
	ds_write2st64_b32 v163, v184, v185 offset0:72 offset1:76
	ds_write2st64_b32 v163, v186, v187 offset0:80 offset1:84
	ds_write2st64_b32 v163, v188, v189 offset0:88 offset1:92
	ds_write2st64_b32 v163, v190, v172 offset0:96 offset1:100
	ds_write2st64_b32 v163, v173, v22 offset0:104 offset1:108
	ds_write2st64_b32 v163, v23, v20 offset0:112 offset1:116
	ds_write2st64_b32 v163, v10, v11 offset0:120 offset1:124
	s_waitcnt lgkmcnt(0)
	s_barrier
	ds_read_b128 v[38:41], v109
	ds_read_b128 v[34:37], v109 offset:8192
	ds_read_b128 v[30:33], v109 offset:16384
	ds_read_b128 v[26:29], v109 offset:24576
	ds_read_b128 v[22:25], v109 offset:32768
	ds_read_b128 v[18:21], v109 offset:40960
	s_waitcnt lgkmcnt(5)
	v_mov_b32_e32 v10, v39
	v_mov_b32_e32 v11, v40
	v_mov_b32_e32 v12, v38
	v_mov_b32_e32 v13, v41
	v_pk_add_f32 v[10:11], v[10:11], v[12:13]
	s_waitcnt lgkmcnt(4)
	v_mov_b32_e32 v12, v34
	v_add_f32_e32 v160, v10, v11
	v_mov_b32_e32 v10, v35
	v_mov_b32_e32 v11, v36
	v_mov_b32_e32 v13, v37
	v_pk_add_f32 v[10:11], v[10:11], v[12:13]
	s_waitcnt lgkmcnt(3)
	v_mov_b32_e32 v12, v30
	v_add_f32_e32 v161, v10, v11
	v_mov_b32_e32 v10, v31
	v_mov_b32_e32 v11, v32
	v_mov_b32_e32 v13, v33
	v_pk_add_f32 v[10:11], v[10:11], v[12:13]
	s_waitcnt lgkmcnt(2)
	v_mov_b32_e32 v12, v26
	v_add_f32_e32 v162, v10, v11
	v_mov_b32_e32 v10, v27
	v_mov_b32_e32 v11, v28
	v_mov_b32_e32 v13, v29
	v_pk_add_f32 v[10:11], v[10:11], v[12:13]
	s_waitcnt lgkmcnt(1)
	v_mov_b32_e32 v12, v22
	v_add_f32_e32 v163, v10, v11
	v_mov_b32_e32 v10, v23
	v_mov_b32_e32 v11, v24
	v_mov_b32_e32 v13, v25
	v_pk_add_f32 v[10:11], v[10:11], v[12:13]
	s_waitcnt lgkmcnt(0)
	v_mov_b32_e32 v12, v18
	v_add_f32_e32 v164, v10, v11
	v_mov_b32_e32 v10, v19
	v_mov_b32_e32 v11, v20
	ds_read_b128 v[14:17], v109 offset:49152
	v_mov_b32_e32 v13, v21
	v_pk_add_f32 v[10:11], v[10:11], v[12:13]
	s_add_i32 s28, s57, s28
	v_add_f32_e32 v165, v10, v11
	ds_read_b128 v[10:13], v109 offset:57344
	s_waitcnt lgkmcnt(1)
	v_mov_b32_e32 v156, v15
	v_mov_b32_e32 v157, v16
	v_mov_b32_e32 v158, v14
	v_mov_b32_e32 v159, v17
	v_pk_add_f32 v[156:157], v[156:157], v[158:159]
	s_waitcnt lgkmcnt(0)
	v_mov_b32_e32 v158, v10
	v_add_f32_e32 v109, v156, v157
	v_mov_b32_e32 v156, v11
	v_mov_b32_e32 v157, v12
	v_mov_b32_e32 v159, v13
	v_pk_add_f32 v[156:157], v[156:157], v[158:159]
	v_add_f32_dpp v158, v161, v161 quad_perm:[1,0,3,2] row_mask:0xf bank_mask:0xf bound_ctrl:1
	v_add_f32_e32 v156, v156, v157
	v_add_f32_dpp v157, v160, v160 quad_perm:[1,0,3,2] row_mask:0xf bank_mask:0xf bound_ctrl:1
	v_add_f32_dpp v160, v163, v163 quad_perm:[1,0,3,2] row_mask:0xf bank_mask:0xf bound_ctrl:1
	v_add_f32_dpp v158, v158, v158 quad_perm:[2,3,0,1] row_mask:0xf bank_mask:0xf bound_ctrl:1
	v_add_f32_dpp v157, v157, v157 quad_perm:[2,3,0,1] row_mask:0xf bank_mask:0xf bound_ctrl:1
	v_mov_b32_e32 v163, v131
	v_add_f32_dpp v159, v162, v162 quad_perm:[1,0,3,2] row_mask:0xf bank_mask:0xf bound_ctrl:1
	v_add_f32_dpp v157, v157, v157 row_half_mirror row_mask:0xf bank_mask:0xf bound_ctrl:1
	v_add_f32_dpp v158, v158, v158 row_half_mirror row_mask:0xf bank_mask:0xf bound_ctrl:1
	v_add_f32_dpp v159, v159, v159 quad_perm:[2,3,0,1] row_mask:0xf bank_mask:0xf bound_ctrl:1
	v_add_f32_dpp v157, v157, v157 row_mirror row_mask:0xf bank_mask:0xf bound_ctrl:1
	v_add_f32_dpp v158, v158, v158 row_mirror row_mask:0xf bank_mask:0xf bound_ctrl:1
	v_add_f32_dpp v159, v159, v159 row_half_mirror row_mask:0xf bank_mask:0xf bound_ctrl:1
	v_mov_b32_dpp v163, v157 row_bcast:15 row_mask:0xa bank_mask:0xf
	v_add_f32_e32 v157, v157, v163
	v_mov_b32_e32 v163, v131
	v_add_f32_dpp v160, v160, v160 quad_perm:[2,3,0,1] row_mask:0xf bank_mask:0xf bound_ctrl:1
	v_add_f32_dpp v159, v159, v159 row_mirror row_mask:0xf bank_mask:0xf bound_ctrl:1
	v_mov_b32_dpp v163, v158 row_bcast:15 row_mask:0xa bank_mask:0xf
	v_add_f32_e32 v158, v158, v163
	v_mov_b32_e32 v163, v131
	v_add_f32_dpp v161, v164, v164 quad_perm:[1,0,3,2] row_mask:0xf bank_mask:0xf bound_ctrl:1
	v_add_f32_dpp v160, v160, v160 row_half_mirror row_mask:0xf bank_mask:0xf bound_ctrl:1
	v_mov_b32_dpp v163, v159 row_bcast:15 row_mask:0xa bank_mask:0xf
	v_add_f32_dpp v161, v161, v161 quad_perm:[2,3,0,1] row_mask:0xf bank_mask:0xf bound_ctrl:1
	v_add_f32_dpp v160, v160, v160 row_mirror row_mask:0xf bank_mask:0xf bound_ctrl:1
	v_add_f32_e32 v159, v159, v163
	v_mov_b32_e32 v163, v131
	v_add_f32_dpp v162, v165, v165 quad_perm:[1,0,3,2] row_mask:0xf bank_mask:0xf bound_ctrl:1
	v_add_f32_dpp v161, v161, v161 row_half_mirror row_mask:0xf bank_mask:0xf bound_ctrl:1
	v_mov_b32_dpp v163, v160 row_bcast:15 row_mask:0xa bank_mask:0xf
	v_add_f32_dpp v162, v162, v162 quad_perm:[2,3,0,1] row_mask:0xf bank_mask:0xf bound_ctrl:1
	v_add_f32_dpp v161, v161, v161 row_mirror row_mask:0xf bank_mask:0xf bound_ctrl:1
	v_add_f32_e32 v160, v160, v163
	v_mov_b32_e32 v163, v131
	v_add_f32_dpp v109, v109, v109 quad_perm:[1,0,3,2] row_mask:0xf bank_mask:0xf bound_ctrl:1
	v_add_f32_dpp v162, v162, v162 row_half_mirror row_mask:0xf bank_mask:0xf bound_ctrl:1
	v_mov_b32_dpp v163, v161 row_bcast:15 row_mask:0xa bank_mask:0xf
	v_add_f32_dpp v109, v109, v109 quad_perm:[2,3,0,1] row_mask:0xf bank_mask:0xf bound_ctrl:1
	v_add_f32_dpp v162, v162, v162 row_mirror row_mask:0xf bank_mask:0xf bound_ctrl:1
	v_add_f32_e32 v161, v161, v163
	v_mov_b32_e32 v163, v131
	v_add_f32_dpp v156, v156, v156 quad_perm:[1,0,3,2] row_mask:0xf bank_mask:0xf bound_ctrl:1
	v_add_f32_dpp v109, v109, v109 row_half_mirror row_mask:0xf bank_mask:0xf bound_ctrl:1
	v_mov_b32_dpp v163, v162 row_bcast:15 row_mask:0xa bank_mask:0xf
	v_add_f32_dpp v156, v156, v156 quad_perm:[2,3,0,1] row_mask:0xf bank_mask:0xf bound_ctrl:1
	v_add_f32_dpp v109, v109, v109 row_mirror row_mask:0xf bank_mask:0xf bound_ctrl:1
	v_add_f32_e32 v162, v162, v163
	v_mov_b32_e32 v163, v131
	v_add_f32_dpp v156, v156, v156 row_half_mirror row_mask:0xf bank_mask:0xf bound_ctrl:1
	s_nop 0
	v_mov_b32_dpp v163, v109 row_bcast:15 row_mask:0xa bank_mask:0xf
	v_add_f32_dpp v156, v156, v156 row_mirror row_mask:0xf bank_mask:0xf bound_ctrl:1
	v_add_f32_e32 v109, v109, v163
	v_mov_b32_e32 v163, v131
	s_nop 1
	v_mov_b32_dpp v163, v156 row_bcast:15 row_mask:0xa bank_mask:0xf
	v_add_f32_e32 v156, v156, v163
	v_mov_b32_e32 v163, v131
	s_nop 1
	v_mov_b32_dpp v163, v157 row_bcast:31 row_mask:0xc bank_mask:0xf
	v_add_f32_e32 v157, v157, v163
	v_mov_b32_e32 v163, v131
	v_readlane_b32 s6, v157, 63
	s_nop 0
	v_mov_b32_dpp v163, v158 row_bcast:31 row_mask:0xc bank_mask:0xf
	v_add_f32_e32 v158, v158, v163
	v_mov_b32_e32 v163, v131
	v_fma_f32 v39, s6, v239, v39
	v_fma_f32 v38, s6, v239, v38
	v_mov_b32_dpp v163, v159 row_bcast:31 row_mask:0xc bank_mask:0xf
	v_add_f32_e32 v159, v159, v163
	v_mov_b32_e32 v163, v131
	v_fma_f32 v41, s6, v239, v41
	v_fmac_f32_e32 v40, s6, v239
	v_mov_b32_dpp v163, v160 row_bcast:31 row_mask:0xc bank_mask:0xf
	v_add_f32_e32 v160, v160, v163
	v_mov_b32_e32 v163, v131
	v_readlane_b32 s7, v158, 63
	v_readlane_b32 s8, v159, 63
	v_mov_b32_dpp v163, v161 row_bcast:31 row_mask:0xc bank_mask:0xf
	v_add_f32_e32 v161, v161, v163
	v_mov_b32_e32 v163, v131
	v_pk_mul_f32 v[158:159], v[38:39], v[38:39]
	v_readlane_b32 s9, v160, 63
	v_mov_b32_dpp v163, v162 row_bcast:31 row_mask:0xc bank_mask:0xf
	v_add_f32_e32 v162, v162, v163
	v_mov_b32_e32 v163, v131
	v_readlane_b32 s10, v161, 63
	v_fma_f32 v35, s7, v239, v35
	v_mov_b32_dpp v163, v109 row_bcast:31 row_mask:0xc bank_mask:0xf
	v_add_f32_e32 v109, v109, v163
	v_mov_b32_e32 v163, v131
	v_fma_f32 v34, s7, v239, v34
	v_fma_f32 v37, s7, v239, v37
	v_mov_b32_dpp v163, v156 row_bcast:31 row_mask:0xc bank_mask:0xf
	v_add_f32_e32 v156, v156, v163
	v_fmac_f32_e32 v36, s7, v239
	v_readlane_b32 s60, v156, 63
	v_pk_mul_f32 v[156:157], v[40:41], v[40:41]
	v_readlane_b32 s29, v109, 63
	v_pk_mov_b32 v[160:161], v[158:159], v[156:157] op_sel:[1,0]
	v_mov_b32_e32 v159, v157
	v_pk_add_f32 v[156:157], v[160:161], v[158:159]
	v_pk_mul_f32 v[158:159], v[34:35], v[34:35]
	v_add_f32_e32 v109, v156, v157
	v_pk_mul_f32 v[156:157], v[36:37], v[36:37]
	v_fma_f32 v31, s8, v239, v31
	v_pk_mov_b32 v[160:161], v[158:159], v[156:157] op_sel:[1,0]
	v_mov_b32_e32 v159, v157
	v_pk_add_f32 v[156:157], v[160:161], v[158:159]
	v_fma_f32 v30, s8, v239, v30
	v_fma_f32 v33, s8, v239, v33
	v_fmac_f32_e32 v32, s8, v239
	v_readlane_b32 s11, v162, 63
	v_add_f32_e32 v162, v156, v157
	v_pk_mul_f32 v[156:157], v[32:33], v[32:33]
	v_pk_mul_f32 v[158:159], v[30:31], v[30:31]
	v_fma_f32 v27, s9, v239, v27
	v_pk_mov_b32 v[160:161], v[158:159], v[156:157] op_sel:[1,0]
	v_mov_b32_e32 v159, v157
	v_pk_add_f32 v[156:157], v[160:161], v[158:159]
	v_fma_f32 v26, s9, v239, v26
	v_fma_f32 v29, s9, v239, v29
	v_fmac_f32_e32 v28, s9, v239
	v_add_f32_e32 v163, v156, v157
	v_pk_mul_f32 v[156:157], v[28:29], v[28:29]
	v_pk_mul_f32 v[158:159], v[26:27], v[26:27]
	v_fma_f32 v23, s10, v239, v23
	v_pk_mov_b32 v[160:161], v[158:159], v[156:157] op_sel:[1,0]
	v_mov_b32_e32 v159, v157
	v_pk_add_f32 v[156:157], v[160:161], v[158:159]
	v_fma_f32 v22, s10, v239, v22
	v_fma_f32 v25, s10, v239, v25
	v_fmac_f32_e32 v24, s10, v239
	v_add_f32_e32 v164, v156, v157
	v_pk_mul_f32 v[156:157], v[24:25], v[24:25]
	v_pk_mul_f32 v[158:159], v[22:23], v[22:23]
	v_fma_f32 v19, s11, v239, v19
	v_pk_mov_b32 v[160:161], v[158:159], v[156:157] op_sel:[1,0]
	v_mov_b32_e32 v159, v157
	v_pk_add_f32 v[156:157], v[160:161], v[158:159]
	v_fma_f32 v18, s11, v239, v18
	v_fma_f32 v21, s11, v239, v21
	v_fmac_f32_e32 v20, s11, v239
	v_add_f32_e32 v165, v156, v157
	v_pk_mul_f32 v[156:157], v[20:21], v[20:21]
	v_pk_mul_f32 v[158:159], v[18:19], v[18:19]
	v_fma_f32 v15, s29, v239, v15
	v_pk_mov_b32 v[160:161], v[158:159], v[156:157] op_sel:[1,0]
	v_mov_b32_e32 v159, v157
	v_pk_add_f32 v[156:157], v[160:161], v[158:159]
	v_fma_f32 v14, s29, v239, v14
	v_fma_f32 v17, s29, v239, v17
	v_fmac_f32_e32 v16, s29, v239
	v_add_f32_e32 v166, v156, v157
	v_pk_mul_f32 v[156:157], v[16:17], v[16:17]
	v_pk_mul_f32 v[158:159], v[14:15], v[14:15]
	v_fma_f32 v11, s60, v239, v11
	v_pk_mov_b32 v[160:161], v[158:159], v[156:157] op_sel:[1,0]
	v_mov_b32_e32 v159, v157
	v_pk_add_f32 v[156:157], v[160:161], v[158:159]
	v_fma_f32 v10, s60, v239, v10
	v_fma_f32 v13, s60, v239, v13
	v_fmac_f32_e32 v12, s60, v239
	v_add_f32_e32 v167, v156, v157
	v_pk_mul_f32 v[156:157], v[12:13], v[12:13]
	v_pk_mul_f32 v[158:159], v[10:11], v[10:11]
	v_add_f32_dpp v109, v109, v109 quad_perm:[1,0,3,2] row_mask:0xf bank_mask:0xf bound_ctrl:1
	v_pk_mov_b32 v[160:161], v[158:159], v[156:157] op_sel:[1,0]
	v_mov_b32_e32 v159, v157
	v_pk_add_f32 v[156:157], v[160:161], v[158:159]
	v_add_f32_dpp v109, v109, v109 quad_perm:[2,3,0,1] row_mask:0xf bank_mask:0xf bound_ctrl:1
	v_add_f32_e32 v156, v156, v157
	v_add_f32_dpp v157, v162, v162 quad_perm:[1,0,3,2] row_mask:0xf bank_mask:0xf bound_ctrl:1
	v_add_f32_dpp v109, v109, v109 row_half_mirror row_mask:0xf bank_mask:0xf bound_ctrl:1
	v_add_f32_dpp v158, v163, v163 quad_perm:[1,0,3,2] row_mask:0xf bank_mask:0xf bound_ctrl:1
	v_add_f32_dpp v157, v157, v157 quad_perm:[2,3,0,1] row_mask:0xf bank_mask:0xf bound_ctrl:1
	v_add_f32_dpp v109, v109, v109 row_mirror row_mask:0xf bank_mask:0xf bound_ctrl:1
	v_mov_b32_e32 v163, v131
	v_add_f32_dpp v157, v157, v157 row_half_mirror row_mask:0xf bank_mask:0xf bound_ctrl:1
	v_add_f32_dpp v158, v158, v158 quad_perm:[2,3,0,1] row_mask:0xf bank_mask:0xf bound_ctrl:1
	v_mov_b32_dpp v163, v109 row_bcast:15 row_mask:0xa bank_mask:0xf
	v_add_f32_dpp v157, v157, v157 row_mirror row_mask:0xf bank_mask:0xf bound_ctrl:1
	v_add_f32_e32 v109, v109, v163
	v_mov_b32_e32 v163, v131
	v_add_f32_dpp v159, v164, v164 quad_perm:[1,0,3,2] row_mask:0xf bank_mask:0xf bound_ctrl:1
	v_add_f32_dpp v158, v158, v158 row_half_mirror row_mask:0xf bank_mask:0xf bound_ctrl:1
	v_mov_b32_dpp v163, v157 row_bcast:15 row_mask:0xa bank_mask:0xf
	v_add_f32_dpp v159, v159, v159 quad_perm:[2,3,0,1] row_mask:0xf bank_mask:0xf bound_ctrl:1
	v_add_f32_dpp v158, v158, v158 row_mirror row_mask:0xf bank_mask:0xf bound_ctrl:1
	v_add_f32_e32 v157, v157, v163
	v_mov_b32_e32 v163, v131
	v_add_f32_dpp v160, v165, v165 quad_perm:[1,0,3,2] row_mask:0xf bank_mask:0xf bound_ctrl:1
	v_add_f32_dpp v159, v159, v159 row_half_mirror row_mask:0xf bank_mask:0xf bound_ctrl:1
	v_mov_b32_dpp v163, v158 row_bcast:15 row_mask:0xa bank_mask:0xf
	v_add_f32_dpp v160, v160, v160 quad_perm:[2,3,0,1] row_mask:0xf bank_mask:0xf bound_ctrl:1
	v_add_f32_dpp v159, v159, v159 row_mirror row_mask:0xf bank_mask:0xf bound_ctrl:1
	v_add_f32_e32 v158, v158, v163
	v_mov_b32_e32 v163, v131
	v_add_f32_dpp v161, v166, v166 quad_perm:[1,0,3,2] row_mask:0xf bank_mask:0xf bound_ctrl:1
	v_add_f32_dpp v160, v160, v160 row_half_mirror row_mask:0xf bank_mask:0xf bound_ctrl:1
	v_mov_b32_dpp v163, v159 row_bcast:15 row_mask:0xa bank_mask:0xf
	v_add_f32_dpp v161, v161, v161 quad_perm:[2,3,0,1] row_mask:0xf bank_mask:0xf bound_ctrl:1
	v_add_f32_dpp v160, v160, v160 row_mirror row_mask:0xf bank_mask:0xf bound_ctrl:1
	v_add_f32_e32 v159, v159, v163
	v_mov_b32_e32 v163, v131
	v_add_f32_dpp v162, v167, v167 quad_perm:[1,0,3,2] row_mask:0xf bank_mask:0xf bound_ctrl:1
	v_add_f32_dpp v161, v161, v161 row_half_mirror row_mask:0xf bank_mask:0xf bound_ctrl:1
	v_mov_b32_dpp v163, v160 row_bcast:15 row_mask:0xa bank_mask:0xf
	v_add_f32_dpp v162, v162, v162 quad_perm:[2,3,0,1] row_mask:0xf bank_mask:0xf bound_ctrl:1
	v_add_f32_dpp v161, v161, v161 row_mirror row_mask:0xf bank_mask:0xf bound_ctrl:1
	v_add_f32_e32 v160, v160, v163
	v_mov_b32_e32 v163, v131
	v_add_f32_dpp v156, v156, v156 quad_perm:[1,0,3,2] row_mask:0xf bank_mask:0xf bound_ctrl:1
	v_add_f32_dpp v162, v162, v162 row_half_mirror row_mask:0xf bank_mask:0xf bound_ctrl:1
	v_mov_b32_dpp v163, v161 row_bcast:15 row_mask:0xa bank_mask:0xf
	v_add_f32_dpp v156, v156, v156 quad_perm:[2,3,0,1] row_mask:0xf bank_mask:0xf bound_ctrl:1
	v_add_f32_dpp v162, v162, v162 row_mirror row_mask:0xf bank_mask:0xf bound_ctrl:1
	v_add_f32_e32 v161, v161, v163
	v_mov_b32_e32 v163, v131
	v_add_f32_dpp v156, v156, v156 row_half_mirror row_mask:0xf bank_mask:0xf bound_ctrl:1
	s_ashr_i32 s29, s28, 31
	v_mov_b32_dpp v163, v162 row_bcast:15 row_mask:0xa bank_mask:0xf
	v_add_f32_dpp v156, v156, v156 row_mirror row_mask:0xf bank_mask:0xf bound_ctrl:1
	v_add_f32_e32 v162, v162, v163
	v_mov_b32_e32 v163, v131
	s_lshl_b64 s[8:9], s[28:29], 11
	s_add_u32 s8, s76, s8
	v_mov_b32_dpp v163, v156 row_bcast:15 row_mask:0xa bank_mask:0xf
	v_add_f32_e32 v156, v156, v163
	v_mov_b32_e32 v163, v131
	s_addc_u32 s9, s77, s9
	s_nop 0
	v_mov_b32_dpp v163, v109 row_bcast:31 row_mask:0xc bank_mask:0xf
	v_add_f32_e32 v109, v109, v163
	v_mov_b32_e32 v163, v131
	v_readlane_b32 s6, v109, 63
	s_nop 0
	v_mov_b32_dpp v163, v157 row_bcast:31 row_mask:0xc bank_mask:0xf
	v_add_f32_e32 v157, v157, v163
	v_mov_b32_e32 v163, v131
	v_fma_f32 v109, s6, v235, v225
	v_readlane_b32 s10, v157, 63
	v_mov_b32_dpp v163, v158 row_bcast:31 row_mask:0xc bank_mask:0xf
	v_add_f32_e32 v158, v158, v163
	v_mov_b32_e32 v163, v131
	v_readlane_b32 s11, v158, 63
	s_nop 0
	v_mov_b32_dpp v163, v159 row_bcast:31 row_mask:0xc bank_mask:0xf
	v_add_f32_e32 v159, v159, v163
	v_mov_b32_e32 v163, v131
	v_readlane_b32 s65, v159, 63
	s_nop 0
	v_mov_b32_dpp v163, v160 row_bcast:31 row_mask:0xc bank_mask:0xf
	v_add_f32_e32 v160, v160, v163
	v_mov_b32_e32 v163, v131
	v_readlane_b32 s61, v160, 63
	s_nop 0
	v_mov_b32_dpp v163, v161 row_bcast:31 row_mask:0xc bank_mask:0xf
	v_add_f32_e32 v161, v161, v163
	v_mov_b32_e32 v163, v131
	v_readlane_b32 s60, v161, 63
	s_nop 0
	v_mov_b32_dpp v163, v162 row_bcast:31 row_mask:0xc bank_mask:0xf
	v_add_f32_e32 v162, v162, v163
	v_mov_b32_e32 v163, v131
	v_readlane_b32 s7, v162, 63
	s_nop 0
	v_mov_b32_dpp v163, v156 row_bcast:31 row_mask:0xc bank_mask:0xf
	v_add_f32_e32 v163, v156, v163
	v_rsq_f32_e32 v156, v109
	v_readlane_b32 s6, v163, 63
	v_pk_mul_f32 v[38:39], v[38:39], v[156:157] op_sel_hi:[1,0]
	s_nop 0
	v_pk_fma_f32 v[38:39], v[2:3], v[38:39], v[6:7]
	v_pk_mul_f32 v[40:41], v[40:41], v[156:157] op_sel_hi:[1,0]
	v_mul_f32_e32 v109, 0xbfb8aa3b, v38
	v_exp_f32_e32 v109, v109
	v_mul_f32_e32 v156, 0xbfb8aa3b, v39
	v_exp_f32_e32 v157, v156
	v_pk_fma_f32 v[40:41], v[4:5], v[40:41], v[8:9]
	v_add_f32_e32 v109, 1.0, v109
	v_rcp_f32_e32 v156, v109
	v_add_f32_e32 v109, 1.0, v157
	v_mul_f32_e32 v157, 0xbfb8aa3b, v40
	v_exp_f32_e32 v158, v157
	v_mul_f32_e32 v157, 0xbfb8aa3b, v41
	v_exp_f32_e32 v159, v157
	v_rcp_f32_e32 v157, v109
	v_add_f32_e32 v109, 1.0, v158
	v_rcp_f32_e32 v158, v109
	v_add_f32_e32 v109, 1.0, v159
	v_rcp_f32_e32 v159, v109
	v_pk_mul_f32 v[38:39], v[38:39], v[156:157]
	v_lshlrev_b32_e32 v109, 3, v130
	v_cvt_pk_bf16_f32 v38, v38, v39
	v_pk_mul_f32 v[40:41], v[40:41], v[158:159]
	v_cvt_pk_bf16_f32 v39, v40, v41
	v_fma_f32 v40, s10, v235, v225
	v_rsq_f32_e32 v40, v40
	global_store_dwordx2 v109, v[38:39], s[8:9] offset:512
	s_add_i32 s8, s28, 8
	s_ashr_i32 s9, s8, 31
	v_pk_mul_f32 v[36:37], v[36:37], v[40:41] op_sel_hi:[1,0]
	v_pk_mul_f32 v[34:35], v[34:35], v[40:41] op_sel_hi:[1,0]
	v_pk_fma_f32 v[36:37], v[4:5], v[36:37], v[8:9]
	v_pk_fma_f32 v[34:35], v[2:3], v[34:35], v[6:7]
	v_mul_f32_e32 v130, 0xbfb8aa3b, v36
	v_mul_f32_e32 v40, 0xbfb8aa3b, v34
	v_mul_f32_e32 v41, 0xbfb8aa3b, v35
	v_exp_f32_e32 v130, v130
	v_mul_f32_e32 v156, 0xbfb8aa3b, v37
	v_exp_f32_e32 v40, v40
	v_exp_f32_e32 v41, v41
	v_exp_f32_e32 v157, v156
	v_add_f32_e32 v130, 1.0, v130
	v_add_f32_e32 v40, 1.0, v40
	v_add_f32_e32 v41, 1.0, v41
	v_rcp_f32_e32 v156, v130
	v_add_f32_e32 v130, 1.0, v157
	v_rcp_f32_e32 v40, v40
	v_rcp_f32_e32 v41, v41
	v_rcp_f32_e32 v157, v130
	s_lshl_b64 s[8:9], s[8:9], 11
	s_add_u32 s8, s76, s8
	v_pk_mul_f32 v[34:35], v[34:35], v[40:41]
	v_pk_mul_f32 v[36:37], v[36:37], v[156:157]
	v_cvt_pk_bf16_f32 v34, v34, v35
	v_cvt_pk_bf16_f32 v35, v36, v37
	v_fma_f32 v36, s11, v235, v225
	v_rsq_f32_e32 v36, v36
	s_addc_u32 s9, s77, s9
	global_store_dwordx2 v109, v[34:35], s[8:9] offset:512
	s_add_i32 s8, s28, 16
	v_pk_mul_f32 v[30:31], v[30:31], v[36:37] op_sel_hi:[1,0]
	v_pk_mul_f32 v[32:33], v[32:33], v[36:37] op_sel_hi:[1,0]
	v_pk_fma_f32 v[30:31], v[2:3], v[30:31], v[6:7]
	v_pk_fma_f32 v[32:33], v[4:5], v[32:33], v[8:9]
	v_mul_f32_e32 v36, 0xbfb8aa3b, v30
	v_mul_f32_e32 v37, 0xbfb8aa3b, v31
	v_mul_f32_e32 v38, 0xbfb8aa3b, v32
	v_mul_f32_e32 v39, 0xbfb8aa3b, v33
	v_exp_f32_e32 v36, v36
	v_exp_f32_e32 v37, v37
	v_exp_f32_e32 v38, v38
	v_exp_f32_e32 v39, v39
	v_add_f32_e32 v36, 1.0, v36
	v_add_f32_e32 v37, 1.0, v37
	v_add_f32_e32 v38, 1.0, v38
	v_add_f32_e32 v39, 1.0, v39
	v_rcp_f32_e32 v36, v36
	v_rcp_f32_e32 v37, v37
	v_rcp_f32_e32 v38, v38
	v_rcp_f32_e32 v39, v39
	s_ashr_i32 s9, s8, 31
	v_pk_mul_f32 v[30:31], v[30:31], v[36:37]
	s_lshl_b64 s[8:9], s[8:9], 11
	v_pk_mul_f32 v[32:33], v[32:33], v[38:39]
	v_cvt_pk_bf16_f32 v30, v30, v31
	v_cvt_pk_bf16_f32 v31, v32, v33
	v_fma_f32 v32, s65, v235, v225
	v_rsq_f32_e32 v32, v32
	s_add_u32 s8, s76, s8
	s_addc_u32 s9, s77, s9
	global_store_dwordx2 v109, v[30:31], s[8:9] offset:512
	v_pk_mul_f32 v[26:27], v[26:27], v[32:33] op_sel_hi:[1,0]
	v_pk_mul_f32 v[28:29], v[28:29], v[32:33] op_sel_hi:[1,0]
	v_pk_fma_f32 v[26:27], v[2:3], v[26:27], v[6:7]
	v_pk_fma_f32 v[28:29], v[4:5], v[28:29], v[8:9]
	v_mul_f32_e32 v32, 0xbfb8aa3b, v26
	v_mul_f32_e32 v33, 0xbfb8aa3b, v27
	v_mul_f32_e32 v34, 0xbfb8aa3b, v28
	v_mul_f32_e32 v35, 0xbfb8aa3b, v29
	v_exp_f32_e32 v32, v32
	v_exp_f32_e32 v33, v33
	v_exp_f32_e32 v34, v34
	v_exp_f32_e32 v35, v35
	v_add_f32_e32 v32, 1.0, v32
	v_add_f32_e32 v33, 1.0, v33
	v_add_f32_e32 v34, 1.0, v34
	v_add_f32_e32 v35, 1.0, v35
	v_rcp_f32_e32 v32, v32
	v_rcp_f32_e32 v33, v33
	v_rcp_f32_e32 v34, v34
	v_rcp_f32_e32 v35, v35
	s_add_i32 s8, s28, 24
	v_pk_mul_f32 v[26:27], v[26:27], v[32:33]
	s_ashr_i32 s9, s8, 31
	v_pk_mul_f32 v[28:29], v[28:29], v[34:35]
	v_cvt_pk_bf16_f32 v26, v26, v27
	v_cvt_pk_bf16_f32 v27, v28, v29
	v_fma_f32 v28, s61, v235, v225
	v_rsq_f32_e32 v28, v28
	s_lshl_b64 s[8:9], s[8:9], 11
	s_add_u32 s8, s76, s8
	s_addc_u32 s9, s77, s9
	v_pk_mul_f32 v[22:23], v[22:23], v[28:29] op_sel_hi:[1,0]
	v_pk_mul_f32 v[24:25], v[24:25], v[28:29] op_sel_hi:[1,0]
	v_pk_fma_f32 v[22:23], v[2:3], v[22:23], v[6:7]
	v_pk_fma_f32 v[24:25], v[4:5], v[24:25], v[8:9]
	v_mul_f32_e32 v28, 0xbfb8aa3b, v22
	v_mul_f32_e32 v29, 0xbfb8aa3b, v23
	v_mul_f32_e32 v30, 0xbfb8aa3b, v24
	v_mul_f32_e32 v31, 0xbfb8aa3b, v25
	v_exp_f32_e32 v28, v28
	v_exp_f32_e32 v29, v29
	v_exp_f32_e32 v30, v30
	v_exp_f32_e32 v31, v31
	v_add_f32_e32 v28, 1.0, v28
	v_add_f32_e32 v29, 1.0, v29
	v_add_f32_e32 v30, 1.0, v30
	v_add_f32_e32 v31, 1.0, v31
	v_rcp_f32_e32 v28, v28
	v_rcp_f32_e32 v29, v29
	v_rcp_f32_e32 v30, v30
	v_rcp_f32_e32 v31, v31
	global_store_dwordx2 v109, v[26:27], s[8:9] offset:512
	v_pk_mul_f32 v[22:23], v[22:23], v[28:29]
	s_add_i32 s8, s28, 32
	v_pk_mul_f32 v[24:25], v[24:25], v[30:31]
	v_cvt_pk_bf16_f32 v22, v22, v23
	v_cvt_pk_bf16_f32 v23, v24, v25
	v_fma_f32 v24, s60, v235, v225
	v_rsq_f32_e32 v24, v24
	s_ashr_i32 s9, s8, 31
	s_lshl_b64 s[8:9], s[8:9], 11
	s_add_u32 s8, s76, s8
	v_pk_mul_f32 v[18:19], v[18:19], v[24:25] op_sel_hi:[1,0]
	v_pk_mul_f32 v[20:21], v[20:21], v[24:25] op_sel_hi:[1,0]
	v_pk_fma_f32 v[18:19], v[2:3], v[18:19], v[6:7]
	v_pk_fma_f32 v[20:21], v[4:5], v[20:21], v[8:9]
	v_mul_f32_e32 v24, 0xbfb8aa3b, v18
	v_mul_f32_e32 v25, 0xbfb8aa3b, v19
	v_mul_f32_e32 v26, 0xbfb8aa3b, v20
	v_mul_f32_e32 v27, 0xbfb8aa3b, v21
	v_exp_f32_e32 v24, v24
	v_exp_f32_e32 v25, v25
	v_exp_f32_e32 v26, v26
	v_exp_f32_e32 v27, v27
	v_add_f32_e32 v24, 1.0, v24
	v_add_f32_e32 v25, 1.0, v25
	v_add_f32_e32 v26, 1.0, v26
	v_add_f32_e32 v27, 1.0, v27
	v_rcp_f32_e32 v24, v24
	v_rcp_f32_e32 v25, v25
	v_rcp_f32_e32 v26, v26
	v_rcp_f32_e32 v27, v27
	s_addc_u32 s9, s77, s9
	v_pk_mul_f32 v[18:19], v[18:19], v[24:25]
	global_store_dwordx2 v109, v[22:23], s[8:9] offset:512
	v_pk_mul_f32 v[20:21], v[20:21], v[26:27]
	v_cvt_pk_bf16_f32 v18, v18, v19
	v_cvt_pk_bf16_f32 v19, v20, v21
	v_fma_f32 v20, s7, v235, v225
	v_rsq_f32_e32 v20, v20
	s_add_i32 s8, s28, 40
	s_ashr_i32 s9, s8, 31
	s_lshl_b64 s[8:9], s[8:9], 11
	v_pk_mul_f32 v[14:15], v[14:15], v[20:21] op_sel_hi:[1,0]
	v_pk_mul_f32 v[16:17], v[16:17], v[20:21] op_sel_hi:[1,0]
	v_pk_fma_f32 v[14:15], v[2:3], v[14:15], v[6:7]
	v_pk_fma_f32 v[16:17], v[4:5], v[16:17], v[8:9]
	v_mul_f32_e32 v20, 0xbfb8aa3b, v14
	v_mul_f32_e32 v21, 0xbfb8aa3b, v15
	v_mul_f32_e32 v22, 0xbfb8aa3b, v16
	v_mul_f32_e32 v23, 0xbfb8aa3b, v17
	v_exp_f32_e32 v20, v20
	v_exp_f32_e32 v21, v21
	v_exp_f32_e32 v22, v22
	v_exp_f32_e32 v23, v23
	v_add_f32_e32 v20, 1.0, v20
	v_add_f32_e32 v21, 1.0, v21
	v_add_f32_e32 v22, 1.0, v22
	v_add_f32_e32 v23, 1.0, v23
	v_rcp_f32_e32 v20, v20
	v_rcp_f32_e32 v21, v21
	v_rcp_f32_e32 v22, v22
	v_rcp_f32_e32 v23, v23
	s_add_u32 s8, s76, s8
	v_pk_mul_f32 v[14:15], v[14:15], v[20:21]
	s_addc_u32 s9, s77, s9
	v_pk_mul_f32 v[16:17], v[16:17], v[22:23]
	v_cvt_pk_bf16_f32 v14, v14, v15
	v_cvt_pk_bf16_f32 v15, v16, v17
	v_fma_f32 v16, s6, v235, v225
	v_rsq_f32_e32 v16, v16
	global_store_dwordx2 v109, v[18:19], s[8:9] offset:512
	s_add_i32 s8, s28, 48
	s_ashr_i32 s9, s8, 31
	v_pk_mul_f32 v[10:11], v[10:11], v[16:17] op_sel_hi:[1,0]
	v_pk_mul_f32 v[12:13], v[12:13], v[16:17] op_sel_hi:[1,0]
	v_pk_fma_f32 v[10:11], v[2:3], v[10:11], v[6:7]
	v_pk_fma_f32 v[12:13], v[4:5], v[12:13], v[8:9]
	v_mul_f32_e32 v16, 0xbfb8aa3b, v10
	v_mul_f32_e32 v17, 0xbfb8aa3b, v11
	v_mul_f32_e32 v18, 0xbfb8aa3b, v12
	v_mul_f32_e32 v19, 0xbfb8aa3b, v13
	v_exp_f32_e32 v16, v16
	v_exp_f32_e32 v17, v17
	v_exp_f32_e32 v18, v18
	v_exp_f32_e32 v19, v19
	s_lshl_b64 s[6:7], s[8:9], 11
	s_add_u32 s6, s76, s6
	s_addc_u32 s7, s77, s7
	v_add_f32_e32 v16, 1.0, v16
	v_add_f32_e32 v17, 1.0, v17
	v_add_f32_e32 v18, 1.0, v18
	v_add_f32_e32 v19, 1.0, v19
	v_rcp_f32_e32 v16, v16
	v_rcp_f32_e32 v17, v17
	v_rcp_f32_e32 v18, v18
	v_rcp_f32_e32 v19, v19
	global_store_dwordx2 v109, v[14:15], s[6:7] offset:512
	s_add_i32 s6, s28, 56
	s_ashr_i32 s7, s6, 31
	s_lshl_b64 s[6:7], s[6:7], 11
	s_add_u32 s6, s76, s6
	v_pk_mul_f32 v[10:11], v[10:11], v[16:17]
	v_pk_mul_f32 v[12:13], v[12:13], v[18:19]
	s_addc_u32 s7, s77, s7
	s_addk_i32 s58, 0x80
	s_addk_i32 s57, 0x2000
	v_cvt_pk_bf16_f32 v10, v10, v11
	v_cvt_pk_bf16_f32 v11, v12, v13
	s_cmpk_gt_i32 s59, 0xff
	global_store_dwordx2 v109, v[10:11], s[6:7] offset:512
	s_barrier
	s_cbranch_scc1 .LBB0_313

.LBB0_314:
	s_andn2_b64 vcc, exec, s[28:29]
	s_cbranch_vccnz .LBB0_316
	v_mov_b32_e32 v1, v242
	s_mov_b32 s73, s11
	v_readfirstlane_b32 s5, v1
	s_ashr_i32 s65, s5, 6
	v_add_u32_e32 v6, s66, v1
	s_lshl_b32 s6, s65, 4
	v_readlane_b32 s66, v250, 31
	s_add_i32 s6, s6, s66
	s_mul_i32 s8, s6, 0x1800
	s_mul_hi_i32 s7, s6, 0x1800
	s_add_u32 s28, s80, s8
	s_addc_u32 s29, s81, s7
	s_or_b32 s7, s6, 1
	s_mul_hi_i32 s8, s7, 0x1800
	s_mulk_i32 s7, 0x1800
	v_and_b32_e32 v74, 63, v1
	s_add_u32 s40, s80, s7
	s_addc_u32 s41, s81, s8
	v_lshlrev_b32_e32 v44, 1, v74
	global_load_ushort v9, v44, s[40:41] offset:512
	global_load_ushort v20, v44, s[40:41] offset:640
	global_load_ushort v26, v44, s[40:41] offset:768
	global_load_ushort v30, v44, s[40:41] offset:896
	global_load_ushort v8, v44, s[28:29] offset:512
	global_load_ushort v21, v44, s[28:29] offset:640
	global_load_ushort v27, v44, s[28:29] offset:768
	global_load_ushort v31, v44, s[28:29] offset:896
	s_or_b32 s7, s6, 2
	s_mul_hi_i32 s9, s7, 0x1800
	s_mulk_i32 s7, 0x1800
	s_add_u32 s8, s80, s7
	s_addc_u32 s9, s81, s9
	s_or_b32 s7, s6, 3
	s_mul_hi_i32 s11, s7, 0x1800
	s_mulk_i32 s7, 0x1800
	s_add_u32 s10, s80, s7
	s_addc_u32 s11, s81, s11
	global_load_ushort v18, v44, s[10:11] offset:512
	global_load_ushort v19, v44, s[10:11] offset:640
	global_load_ushort v22, v44, s[10:11] offset:768
	global_load_ushort v32, v44, s[10:11] offset:896
	global_load_ushort v23, v44, s[8:9] offset:512
	global_load_ushort v28, v44, s[8:9] offset:640
	global_load_ushort v29, v44, s[8:9] offset:768
	global_load_ushort v33, v44, s[8:9] offset:896
	s_mov_b32 s8, 0xbf3a00e3
	v_mov_b64_e32 v[24:25], s[8:9]
	s_mov_b64 s[10:11], s[68:69]
	s_mov_b64 s[68:69], s[12:13]
	s_mov_b32 s12, 0x3f07dc22
	s_mov_b32 s14, 0x3f35f0e3
	s_mov_b32 s16, 0xbe11a98e
	s_mov_b32 s18, 0x3e027906
	s_or_b32 s7, s6, 4
	s_mul_hi_i32 s8, s7, 0x1800
	s_mulk_i32 s7, 0x1800
	s_add_u32 s28, s80, s7
	s_addc_u32 s29, s81, s8
	s_or_b32 s7, s6, 5
	s_mul_hi_i32 s8, s7, 0x1800
	s_mulk_i32 s7, 0x1800
	s_add_u32 s40, s80, s7
	s_addc_u32 s41, s81, s8
	s_or_b32 s7, s6, 6
	s_mul_hi_i32 s8, s7, 0x1800
	s_mulk_i32 s7, 0x1800
	s_add_u32 s58, s80, s7
	s_addc_u32 s59, s81, s8
	s_or_b32 s7, s6, 7
	s_mul_hi_i32 s8, s7, 0x1800
	s_mulk_i32 s7, 0x1800
	s_add_u32 s60, s80, s7
	s_addc_u32 s61, s81, s8
	s_or_b32 s7, s6, 8
	s_mul_hi_i32 s8, s7, 0x1800
	s_mulk_i32 s7, 0x1800
	v_or_b32_e32 v2, s84, v74
	s_add_u32 s46, s80, s7
	v_ashrrev_i32_e32 v3, 31, v2
	s_addc_u32 s47, s81, s8
	s_or_b32 s7, s6, 9
	v_lshlrev_b64 v[4:5], 2, v[2:3]
	s_mul_hi_i32 s8, s7, 0x1800
	s_mulk_i32 s7, 0x1800
	v_lshl_add_u64 v[2:3], s[52:53], 0, v[4:5]
	v_lshl_add_u64 v[4:5], s[54:55], 0, v[4:5]
	s_add_u32 s54, s80, s7
	s_addc_u32 s55, s81, s8
	s_or_b32 s7, s6, 10
	s_mul_hi_i32 s8, s7, 0x1800
	s_mulk_i32 s7, 0x1800
	s_add_u32 s48, s80, s7
	s_addc_u32 s49, s81, s8
	s_or_b32 s7, s6, 11
	s_mul_hi_i32 s8, s7, 0x1800
	s_mulk_i32 s7, 0x1800
	s_add_u32 s56, s80, s7
	s_addc_u32 s57, s81, s8
	s_or_b32 s7, s6, 12
	v_ashrrev_i32_e32 v7, 31, v6
	s_mul_hi_i32 s8, s7, 0x1800
	s_mulk_i32 s7, 0x1800
	v_lshl_add_u64 v[6:7], v[6:7], 2, s[42:43]
	s_add_u32 s42, s80, s7
	s_addc_u32 s43, s81, s8
	s_or_b32 s7, s6, 13
	s_waitcnt vmcnt(15)
	v_lshlrev_b32_e32 v9, 16, v9
	v_mul_f32_e32 v13, v9, v9
	v_mul_f32_e32 v13, 0xbf38aa3b, v13
	v_exp_f32_e32 v13, v13
	s_waitcnt vmcnt(11)
	v_lshlrev_b32_e32 v8, 16, v8
	v_mul_f32_e32 v11, v8, v8
	v_mul_f32_e32 v11, 0xbf38aa3b, v11
	v_fma_f32 v10, |v8|, s92, 1.0
	v_exp_f32_e32 v12, v11
	v_fma_f32 v11, |v9|, s92, 1.0
	v_rcp_f32_e32 v10, v10
	v_rcp_f32_e32 v11, v11
	v_cmp_gt_f32_e32 vcc, 0, v9
	s_mul_hi_i32 s8, s7, 0x1800
	s_mulk_i32 s7, 0x1800
	v_pk_fma_f32 v[14:15], v[10:11], s[12:13], v[24:25] op_sel_hi:[1,0,0]
	s_add_u32 s50, s80, s7
	v_pk_fma_f32 v[14:15], v[10:11], v[14:15], s[14:15] op_sel_hi:[1,1,0]
	s_addc_u32 s51, s81, s8
	v_pk_fma_f32 v[14:15], v[10:11], v[14:15], s[16:17] op_sel_hi:[1,1,0]
	s_or_b32 s7, s6, 14
	v_pk_fma_f32 v[14:15], v[10:11], v[14:15], s[18:19] op_sel_hi:[1,1,0]
	s_mul_hi_i32 s8, s7, 0x1800
	v_pk_mul_f32 v[10:11], v[10:11], v[14:15]
	s_mulk_i32 s7, 0x1800
	v_pk_mul_f32 v[10:11], v[12:13], v[10:11]
	s_add_u32 s44, s80, s7
	v_pk_mul_f32 v[12:13], v[10:11], v[8:9]
	v_pk_fma_f32 v[10:11], v[10:11], v[8:9], v[8:9] neg_lo:[1,0,0] neg_hi:[1,0,0]
	s_addc_u32 s45, s81, s8
	v_cndmask_b32_e32 v17, v11, v13, vcc
	v_cmp_gt_f32_e32 vcc, 0, v8
	s_waitcnt vmcnt(3)
	v_lshlrev_b32_e32 v8, 16, v23
	v_fma_f32 v9, |v8|, s92, 1.0
	v_mul_f32_e32 v11, v8, v8
	v_cndmask_b32_e32 v16, v10, v12, vcc
	v_rcp_f32_e32 v10, v9
	v_mul_f32_e32 v11, 0xbf38aa3b, v11
	v_lshlrev_b32_e32 v9, 16, v18
	v_exp_f32_e32 v12, v11
	v_fma_f32 v11, |v9|, s92, 1.0
	v_rcp_f32_e32 v11, v11
	v_mul_f32_e32 v13, v9, v9
	v_mul_f32_e32 v13, 0xbf38aa3b, v13
	v_exp_f32_e32 v13, v13
	v_pk_fma_f32 v[14:15], v[10:11], s[12:13], v[24:25] op_sel_hi:[1,0,0]
	v_cmp_gt_f32_e32 vcc, 0, v9
	v_pk_fma_f32 v[14:15], v[10:11], v[14:15], s[14:15] op_sel_hi:[1,1,0]
	s_or_b32 s6, s6, 15
	v_pk_fma_f32 v[14:15], v[10:11], v[14:15], s[16:17] op_sel_hi:[1,1,0]
	s_mul_hi_i32 s7, s6, 0x1800
	v_pk_fma_f32 v[14:15], v[10:11], v[14:15], s[18:19] op_sel_hi:[1,1,0]
	s_mulk_i32 s6, 0x1800
	v_pk_mul_f32 v[10:11], v[10:11], v[14:15]
	s_add_u32 s52, s80, s6
	v_pk_mul_f32 v[10:11], v[12:13], v[10:11]
	s_addc_u32 s53, s81, s7
	v_pk_mul_f32 v[12:13], v[10:11], v[8:9]
	v_pk_fma_f32 v[10:11], v[10:11], v[8:9], v[8:9] neg_lo:[1,0,0] neg_hi:[1,0,0]
	s_mov_b32 s8, 0x3b800000
	v_cndmask_b32_e32 v9, v11, v13, vcc
	v_cmp_gt_f32_e32 vcc, 0, v8
	s_ashr_i32 s5, s5, 7
	v_lshlrev_b32_e32 v130, 4, v74
	v_cndmask_b32_e32 v8, v10, v12, vcc
	s_waitcnt vmcnt(2)
	v_lshlrev_b32_e32 v10, 16, v28
	v_fma_f32 v11, |v10|, s92, 1.0
	v_rcp_f32_e32 v12, v11
	v_lshlrev_b32_e32 v11, 16, v19
	v_fma_f32 v13, |v11|, s92, 1.0
	v_rcp_f32_e32 v13, v13
	v_mul_f32_e32 v14, v10, v10
	v_mul_f32_e32 v15, v11, v11
	v_mul_f32_e32 v14, 0xbf38aa3b, v14
	v_pk_fma_f32 v[18:19], v[12:13], s[12:13], v[24:25] op_sel_hi:[1,0,0]
	v_mul_f32_e32 v15, 0xbf38aa3b, v15
	v_exp_f32_e32 v14, v14
	v_pk_fma_f32 v[18:19], v[12:13], v[18:19], s[14:15] op_sel_hi:[1,1,0]
	v_exp_f32_e32 v15, v15
	v_pk_fma_f32 v[18:19], v[12:13], v[18:19], s[16:17] op_sel_hi:[1,1,0]
	v_cmp_gt_f32_e32 vcc, 0, v11
	v_pk_fma_f32 v[18:19], v[12:13], v[18:19], s[18:19] op_sel_hi:[1,1,0]
	s_nop 0
	v_pk_mul_f32 v[12:13], v[12:13], v[18:19]
	v_pk_mul_f32 v[12:13], v[14:15], v[12:13]
	v_pk_mul_f32 v[14:15], v[12:13], v[10:11]
	v_pk_fma_f32 v[12:13], v[12:13], v[10:11], v[10:11] neg_lo:[1,0,0] neg_hi:[1,0,0]
	v_lshlrev_b32_e32 v11, 16, v20
	v_cndmask_b32_e32 v13, v13, v15, vcc
	v_cmp_gt_f32_e32 vcc, 0, v10
	v_lshlrev_b32_e32 v10, 16, v21
	v_mul_f32_e32 v15, v10, v10
	v_mul_f32_e32 v15, 0xbf38aa3b, v15
	v_cndmask_b32_e32 v12, v12, v14, vcc
	v_fma_f32 v14, |v10|, s92, 1.0
	v_exp_f32_e32 v18, v15
	v_fma_f32 v15, |v11|, s92, 1.0
	v_rcp_f32_e32 v14, v14
	v_rcp_f32_e32 v15, v15
	v_mul_f32_e32 v19, v11, v11
	v_mul_f32_e32 v19, 0xbf38aa3b, v19
	v_exp_f32_e32 v19, v19
	v_pk_fma_f32 v[20:21], v[14:15], s[12:13], v[24:25] op_sel_hi:[1,0,0]
	v_cmp_gt_f32_e32 vcc, 0, v11
	v_pk_fma_f32 v[20:21], v[14:15], v[20:21], s[14:15] op_sel_hi:[1,1,0]
	s_nop 0
	v_pk_fma_f32 v[20:21], v[14:15], v[20:21], s[16:17] op_sel_hi:[1,1,0]
	s_nop 0
	v_pk_fma_f32 v[20:21], v[14:15], v[20:21], s[18:19] op_sel_hi:[1,1,0]
	v_pk_mul_f32 v[14:15], v[14:15], v[20:21]
	v_pk_mul_f32 v[14:15], v[18:19], v[14:15]
	v_pk_mul_f32 v[18:19], v[14:15], v[10:11]
	v_pk_fma_f32 v[14:15], v[14:15], v[10:11], v[10:11] neg_lo:[1,0,0] neg_hi:[1,0,0]
	v_lshlrev_b32_e32 v11, 16, v22
	v_cndmask_b32_e32 v19, v15, v19, vcc
	v_cmp_gt_f32_e32 vcc, 0, v10
	s_waitcnt vmcnt(1)
	v_lshlrev_b32_e32 v10, 16, v29
	v_fma_f32 v15, |v11|, s92, 1.0
	v_cndmask_b32_e32 v18, v14, v18, vcc
	v_fma_f32 v14, |v10|, s92, 1.0
	v_rcp_f32_e32 v14, v14
	v_rcp_f32_e32 v15, v15
	v_mul_f32_e32 v20, v10, v10
	v_mul_f32_e32 v21, v11, v11
	v_mul_f32_e32 v20, 0xbf38aa3b, v20
	v_pk_fma_f32 v[22:23], v[14:15], s[12:13], v[24:25] op_sel_hi:[1,0,0]
	v_mul_f32_e32 v21, 0xbf38aa3b, v21
	v_exp_f32_e32 v20, v20
	v_pk_fma_f32 v[22:23], v[14:15], v[22:23], s[14:15] op_sel_hi:[1,1,0]
	v_exp_f32_e32 v21, v21
	v_pk_fma_f32 v[22:23], v[14:15], v[22:23], s[16:17] op_sel_hi:[1,1,0]
	v_cmp_gt_f32_e32 vcc, 0, v11
	v_pk_fma_f32 v[22:23], v[14:15], v[22:23], s[18:19] op_sel_hi:[1,1,0]
	s_nop 0
	v_pk_mul_f32 v[14:15], v[14:15], v[22:23]
	v_pk_mul_f32 v[14:15], v[20:21], v[14:15]
	v_pk_mul_f32 v[20:21], v[14:15], v[10:11]
	v_pk_fma_f32 v[14:15], v[14:15], v[10:11], v[10:11] neg_lo:[1,0,0] neg_hi:[1,0,0]
	v_lshlrev_b32_e32 v11, 16, v26
	v_cndmask_b32_e32 v21, v15, v21, vcc
	v_cmp_gt_f32_e32 vcc, 0, v10
	v_lshlrev_b32_e32 v10, 16, v27
	v_mul_f32_e32 v15, v10, v10
	v_mul_f32_e32 v15, 0xbf38aa3b, v15
	v_cndmask_b32_e32 v20, v14, v20, vcc
	v_fma_f32 v14, |v10|, s92, 1.0
	v_exp_f32_e32 v22, v15
	v_fma_f32 v15, |v11|, s92, 1.0
	v_rcp_f32_e32 v14, v14
	v_rcp_f32_e32 v15, v15
	v_mul_f32_e32 v23, v11, v11
	v_mul_f32_e32 v23, 0xbf38aa3b, v23
	v_exp_f32_e32 v23, v23
	v_pk_fma_f32 v[26:27], v[14:15], s[12:13], v[24:25] op_sel_hi:[1,0,0]
	v_cmp_gt_f32_e32 vcc, 0, v11
	v_pk_fma_f32 v[26:27], v[14:15], v[26:27], s[14:15] op_sel_hi:[1,1,0]
	s_nop 0
	v_pk_fma_f32 v[26:27], v[14:15], v[26:27], s[16:17] op_sel_hi:[1,1,0]
	s_nop 0
	v_pk_fma_f32 v[26:27], v[14:15], v[26:27], s[18:19] op_sel_hi:[1,1,0]
	v_pk_mul_f32 v[14:15], v[14:15], v[26:27]
	v_pk_mul_f32 v[14:15], v[22:23], v[14:15]
	v_pk_mul_f32 v[22:23], v[14:15], v[10:11]
	v_pk_fma_f32 v[14:15], v[14:15], v[10:11], v[10:11] neg_lo:[1,0,0] neg_hi:[1,0,0]
	v_lshlrev_b32_e32 v11, 16, v32
	v_cndmask_b32_e32 v29, v15, v23, vcc
	v_cmp_gt_f32_e32 vcc, 0, v10
	s_waitcnt vmcnt(0)
	v_lshlrev_b32_e32 v10, 16, v33
	v_fma_f32 v15, |v11|, s92, 1.0
	v_cndmask_b32_e32 v28, v14, v22, vcc
	v_fma_f32 v14, |v10|, s92, 1.0
	v_rcp_f32_e32 v14, v14
	v_rcp_f32_e32 v15, v15
	v_mul_f32_e32 v22, v10, v10
	v_mul_f32_e32 v23, v11, v11
	v_mul_f32_e32 v22, 0xbf38aa3b, v22
	v_pk_fma_f32 v[26:27], v[14:15], s[12:13], v[24:25] op_sel_hi:[1,0,0]
	v_mul_f32_e32 v23, 0xbf38aa3b, v23
	v_exp_f32_e32 v22, v22
	v_pk_fma_f32 v[26:27], v[14:15], v[26:27], s[14:15] op_sel_hi:[1,1,0]
	v_exp_f32_e32 v23, v23
	v_pk_fma_f32 v[26:27], v[14:15], v[26:27], s[16:17] op_sel_hi:[1,1,0]
	v_cmp_gt_f32_e32 vcc, 0, v11
	v_pk_fma_f32 v[26:27], v[14:15], v[26:27], s[18:19] op_sel_hi:[1,1,0]
	v_mov_b32_e32 v32, v19
	v_pk_mul_f32 v[14:15], v[14:15], v[26:27]
	v_pk_mul_f32 v[14:15], v[22:23], v[14:15]
	v_pk_mul_f32 v[22:23], v[14:15], v[10:11]
	v_pk_fma_f32 v[14:15], v[14:15], v[10:11], v[10:11] neg_lo:[1,0,0] neg_hi:[1,0,0]
	v_lshlrev_b32_e32 v11, 16, v30
	v_cndmask_b32_e32 v23, v15, v23, vcc
	v_cmp_gt_f32_e32 vcc, 0, v10
	v_lshlrev_b32_e32 v10, 16, v31
	v_mul_f32_e32 v15, v10, v10
	v_mul_f32_e32 v15, 0xbf38aa3b, v15
	v_cndmask_b32_e32 v22, v14, v22, vcc
	v_fma_f32 v14, |v10|, s92, 1.0
	v_exp_f32_e32 v26, v15
	v_fma_f32 v15, |v11|, s92, 1.0
	v_rcp_f32_e32 v14, v14
	v_rcp_f32_e32 v15, v15
	v_mul_f32_e32 v27, v11, v11
	v_mul_f32_e32 v27, 0xbf38aa3b, v27
	v_exp_f32_e32 v27, v27
	v_pk_fma_f32 v[30:31], v[14:15], s[12:13], v[24:25] op_sel_hi:[1,0,0]
	v_cmp_gt_f32_e32 vcc, 0, v11
	v_pk_fma_f32 v[30:31], v[14:15], v[30:31], s[14:15] op_sel_hi:[1,1,0]
	s_nop 0
	v_pk_fma_f32 v[30:31], v[14:15], v[30:31], s[16:17] op_sel_hi:[1,1,0]
	s_nop 0
	v_pk_fma_f32 v[30:31], v[14:15], v[30:31], s[18:19] op_sel_hi:[1,1,0]
	v_pk_mul_f32 v[14:15], v[14:15], v[30:31]
	v_pk_mul_f32 v[14:15], v[26:27], v[14:15]
	v_pk_mul_f32 v[26:27], v[14:15], v[10:11]
	v_pk_fma_f32 v[14:15], v[14:15], v[10:11], v[10:11] neg_lo:[1,0,0] neg_hi:[1,0,0]
	v_mov_b32_e32 v11, v20
	v_cndmask_b32_e32 v31, v15, v27, vcc
	v_cmp_gt_f32_e32 vcc, 0, v10
	v_mov_b32_e32 v10, v8
	v_mov_b32_e32 v15, v22
	v_cndmask_b32_e32 v30, v14, v26, vcc
	v_mov_b32_e32 v14, v12
	v_pk_add_f32 v[10:11], v[10:11], v[14:15]
	v_mov_b32_e32 v14, v9
	v_add_f32_e32 v10, v10, v11
	v_mov_b32_e32 v11, v131
	v_mov_b32_e32 v15, v21
	v_add_f32_dpp v10, v10, v10 quad_perm:[1,0,3,2] row_mask:0xf bank_mask:0xf bound_ctrl:1
	v_mov_b32_e32 v26, v13
	v_mov_b32_e32 v27, v23
	v_add_f32_dpp v10, v10, v10 quad_perm:[2,3,0,1] row_mask:0xf bank_mask:0xf bound_ctrl:1
	v_pk_add_f32 v[14:15], v[14:15], v[26:27]
	v_mov_b64_e32 v[26:27], s[8:9]
	v_add_f32_dpp v10, v10, v10 row_half_mirror row_mask:0xf bank_mask:0xf bound_ctrl:1
	v_mov_b32_e32 v33, v31
	s_mov_b32 s8, 0x3e027906
	v_add_f32_dpp v10, v10, v10 row_mirror row_mask:0xf bank_mask:0xf bound_ctrl:1
	s_nop 1
	v_mov_b32_dpp v11, v10 row_bcast:15 row_mask:0xa bank_mask:0xf
	v_add_f32_e32 v10, v10, v11
	v_mov_b32_e32 v11, v131
	s_nop 1
	v_mov_b32_dpp v11, v10 row_bcast:31 row_mask:0xc bank_mask:0xf
	v_add_f32_e32 v10, v10, v11
	v_add_f32_e32 v11, v14, v15
	v_mov_b32_e32 v14, v131
	v_readlane_b32 s6, v10, 63
	v_add_f32_dpp v11, v11, v11 quad_perm:[1,0,3,2] row_mask:0xf bank_mask:0xf bound_ctrl:1
	s_xor_b32 s6, s6, 0x80000000
	s_nop 0
	v_add_f32_dpp v11, v11, v11 quad_perm:[2,3,0,1] row_mask:0xf bank_mask:0xf bound_ctrl:1
	s_nop 1
	v_add_f32_dpp v11, v11, v11 row_half_mirror row_mask:0xf bank_mask:0xf bound_ctrl:1
	s_nop 1
	v_add_f32_dpp v11, v11, v11 row_mirror row_mask:0xf bank_mask:0xf bound_ctrl:1
	s_nop 1
	v_mov_b32_dpp v14, v11 row_bcast:15 row_mask:0xa bank_mask:0xf
	v_add_f32_e32 v11, v11, v14
	v_mov_b32_e32 v14, v131
	s_nop 1
	v_mov_b32_dpp v14, v11 row_bcast:31 row_mask:0xc bank_mask:0xf
	v_add_f32_e32 v11, v11, v14
	s_nop 0
	v_readlane_b32 s7, v11, 63
	s_xor_b32 s7, s7, 0x80000000
	s_nop 0
	v_pk_fma_f32 v[10:11], s[6:7], v[26:27], v[8:9] op_sel_hi:[1,0,1]
	v_pk_fma_f32 v[14:15], s[6:7], v[26:27], v[12:13] op_sel_hi:[1,0,1]
	v_pk_fma_f32 v[12:13], s[6:7], v[26:27], v[20:21] op_sel_hi:[1,0,1]
	v_pk_fma_f32 v[8:9], s[6:7], v[26:27], v[22:23] op_sel_hi:[1,0,1]
	v_mov_b32_e32 v20, v16
	v_mov_b32_e32 v21, v28
	v_mov_b32_e32 v22, v18
	v_mov_b32_e32 v23, v30
	v_pk_add_f32 v[20:21], v[20:21], v[22:23]
	v_mov_b32_e32 v22, v17
	v_add_f32_e32 v20, v20, v21
	v_mov_b32_e32 v21, v131
	v_mov_b32_e32 v23, v29
	v_add_f32_dpp v20, v20, v20 quad_perm:[1,0,3,2] row_mask:0xf bank_mask:0xf bound_ctrl:1
	v_pk_add_f32 v[22:23], v[22:23], v[32:33]
	s_nop 0
	v_add_f32_dpp v20, v20, v20 quad_perm:[2,3,0,1] row_mask:0xf bank_mask:0xf bound_ctrl:1
	s_nop 1
	v_add_f32_dpp v20, v20, v20 row_half_mirror row_mask:0xf bank_mask:0xf bound_ctrl:1
	s_nop 1
	v_add_f32_dpp v20, v20, v20 row_mirror row_mask:0xf bank_mask:0xf bound_ctrl:1
	s_nop 1
	v_mov_b32_dpp v21, v20 row_bcast:15 row_mask:0xa bank_mask:0xf
	v_add_f32_e32 v20, v20, v21
	v_mov_b32_e32 v21, v131
	s_nop 1
	v_mov_b32_dpp v21, v20 row_bcast:31 row_mask:0xc bank_mask:0xf
	v_add_f32_e32 v20, v20, v21
	v_add_f32_e32 v21, v22, v23
	v_mov_b32_e32 v22, v131
	v_readlane_b32 s6, v20, 63
	v_add_f32_dpp v21, v21, v21 quad_perm:[1,0,3,2] row_mask:0xf bank_mask:0xf bound_ctrl:1
	s_xor_b32 s6, s6, 0x80000000
	s_nop 0
	v_add_f32_dpp v21, v21, v21 quad_perm:[2,3,0,1] row_mask:0xf bank_mask:0xf bound_ctrl:1
	s_nop 1
	v_add_f32_dpp v21, v21, v21 row_half_mirror row_mask:0xf bank_mask:0xf bound_ctrl:1
	s_nop 1
	v_add_f32_dpp v21, v21, v21 row_mirror row_mask:0xf bank_mask:0xf bound_ctrl:1
	s_nop 1
	v_mov_b32_dpp v22, v21 row_bcast:15 row_mask:0xa bank_mask:0xf
	v_add_f32_e32 v21, v21, v22
	v_mov_b32_e32 v22, v131
	s_nop 1
	v_mov_b32_dpp v22, v21 row_bcast:31 row_mask:0xc bank_mask:0xf
	v_add_f32_e32 v21, v21, v22
	s_nop 0
	v_readlane_b32 s7, v21, 63
	s_xor_b32 s7, s7, 0x80000000
	s_nop 0
	v_pk_fma_f32 v[22:23], s[6:7], v[26:27], v[16:17] op_sel_hi:[1,0,1]
	v_pk_fma_f32 v[20:21], s[6:7], v[26:27], v[18:19] op_sel_hi:[1,0,1]
	v_pk_fma_f32 v[18:19], s[6:7], v[26:27], v[28:29] op_sel_hi:[1,0,1]
	v_pk_fma_f32 v[16:17], s[6:7], v[26:27], v[30:31] op_sel_hi:[1,0,1]
	global_load_ushort v28, v44, s[60:61] offset:512
	global_load_ushort v38, v44, s[60:61] offset:640
	global_load_ushort v42, v44, s[60:61] offset:768
	global_load_ushort v45, v44, s[60:61] offset:896
	global_load_ushort v30, v44, s[58:59] offset:512
	global_load_ushort v39, v44, s[58:59] offset:640
	global_load_ushort v43, v44, s[58:59] offset:768
	global_load_ushort v48, v44, s[58:59] offset:896
	s_waitcnt vmcnt(7)
	v_lshlrev_b32_e32 v29, 16, v28
	v_fma_f32 v31, |v29|, s92, 1.0
	v_rcp_f32_e32 v31, v31
	v_mul_f32_e32 v33, v29, v29
	s_waitcnt vmcnt(3)
	v_lshlrev_b32_e32 v28, 16, v30
	v_fma_f32 v30, |v28|, s92, 1.0
	v_rcp_f32_e32 v30, v30
	v_mul_f32_e32 v32, v28, v28
	v_mul_f32_e32 v32, 0xbf38aa3b, v32
	v_mul_f32_e32 v33, 0xbf38aa3b, v33
	v_pk_fma_f32 v[34:35], v[30:31], s[12:13], v[24:25] op_sel_hi:[1,0,0]
	v_exp_f32_e32 v32, v32
	v_pk_fma_f32 v[34:35], v[30:31], v[34:35], s[14:15] op_sel_hi:[1,1,0]
	v_exp_f32_e32 v33, v33
	v_pk_fma_f32 v[34:35], v[30:31], v[34:35], s[16:17] op_sel_hi:[1,1,0]
	v_cmp_gt_f32_e32 vcc, 0, v29
	v_pk_fma_f32 v[34:35], v[30:31], v[34:35], s[18:19] op_sel_hi:[1,1,0]
	s_nop 0
	v_pk_mul_f32 v[30:31], v[30:31], v[34:35]
	v_pk_mul_f32 v[30:31], v[32:33], v[30:31]
	v_pk_mul_f32 v[32:33], v[30:31], v[28:29]
	v_pk_fma_f32 v[30:31], v[30:31], v[28:29], v[28:29] neg_lo:[1,0,0] neg_hi:[1,0,0]
	s_nop 0
	v_cndmask_b32_e32 v29, v31, v33, vcc
	v_cmp_gt_f32_e32 vcc, 0, v28
	s_nop 1
	v_cndmask_b32_e32 v28, v30, v32, vcc
	global_load_ushort v30, v44, s[40:41] offset:512
	global_load_ushort v40, v44, s[40:41] offset:640
	global_load_ushort v46, v44, s[40:41] offset:768
	global_load_ushort v50, v44, s[40:41] offset:896
	global_load_ushort v32, v44, s[28:29] offset:512
	global_load_ushort v41, v44, s[28:29] offset:640
	global_load_ushort v47, v44, s[28:29] offset:768
	global_load_ushort v51, v44, s[28:29] offset:896
	s_movk_i32 s40, 0x110
	s_movk_i32 s41, 0x3000
	s_waitcnt vmcnt(7)
	v_lshlrev_b32_e32 v31, 16, v30
	v_mul_f32_e32 v35, v31, v31
	v_mul_f32_e32 v35, 0xbf38aa3b, v35
	v_exp_f32_e32 v35, v35
	s_waitcnt vmcnt(3)
	v_lshlrev_b32_e32 v30, 16, v32
	v_mul_f32_e32 v33, v30, v30
	v_mul_f32_e32 v33, 0xbf38aa3b, v33
	v_fma_f32 v32, |v30|, s92, 1.0
	v_exp_f32_e32 v34, v33
	v_fma_f32 v33, |v31|, s92, 1.0
	v_rcp_f32_e32 v32, v32
	v_rcp_f32_e32 v33, v33
	v_cmp_gt_f32_e32 vcc, 0, v31
	v_pk_fma_f32 v[36:37], v[32:33], s[12:13], v[24:25] op_sel_hi:[1,0,0]
	s_nop 0
	v_pk_fma_f32 v[36:37], v[32:33], v[36:37], s[14:15] op_sel_hi:[1,1,0]
	s_nop 0
	v_pk_fma_f32 v[36:37], v[32:33], v[36:37], s[16:17] op_sel_hi:[1,1,0]
	s_nop 0
	v_pk_fma_f32 v[36:37], v[32:33], v[36:37], s[18:19] op_sel_hi:[1,1,0]
	v_pk_mul_f32 v[32:33], v[32:33], v[36:37]
	v_pk_mul_f32 v[32:33], v[34:35], v[32:33]
	v_pk_mul_f32 v[34:35], v[32:33], v[30:31]
	v_pk_fma_f32 v[32:33], v[32:33], v[30:31], v[30:31] neg_lo:[1,0,0] neg_hi:[1,0,0]
	v_lshlrev_b32_e32 v31, 16, v38
	v_cndmask_b32_e32 v37, v33, v35, vcc
	v_cmp_gt_f32_e32 vcc, 0, v30
	v_lshlrev_b32_e32 v30, 16, v39
	v_fma_f32 v33, |v31|, s92, 1.0
	v_cndmask_b32_e32 v36, v32, v34, vcc
	v_fma_f32 v32, |v30|, s92, 1.0
	v_rcp_f32_e32 v32, v32
	v_rcp_f32_e32 v33, v33
	v_mul_f32_e32 v34, v30, v30
	v_mul_f32_e32 v35, v31, v31
	v_mul_f32_e32 v34, 0xbf38aa3b, v34
	v_pk_fma_f32 v[38:39], v[32:33], s[12:13], v[24:25] op_sel_hi:[1,0,0]
	v_mul_f32_e32 v35, 0xbf38aa3b, v35
	v_exp_f32_e32 v34, v34
	v_pk_fma_f32 v[38:39], v[32:33], v[38:39], s[14:15] op_sel_hi:[1,1,0]
	v_exp_f32_e32 v35, v35
	v_pk_fma_f32 v[38:39], v[32:33], v[38:39], s[16:17] op_sel_hi:[1,1,0]
	v_cmp_gt_f32_e32 vcc, 0, v31
	v_pk_fma_f32 v[38:39], v[32:33], v[38:39], s[18:19] op_sel_hi:[1,1,0]
	s_nop 0
	v_pk_mul_f32 v[32:33], v[32:33], v[38:39]
	v_pk_mul_f32 v[32:33], v[34:35], v[32:33]
	v_pk_mul_f32 v[34:35], v[32:33], v[30:31]
	v_pk_fma_f32 v[32:33], v[32:33], v[30:31], v[30:31] neg_lo:[1,0,0] neg_hi:[1,0,0]
	s_nop 0
	v_cndmask_b32_e32 v31, v33, v35, vcc
	v_cmp_gt_f32_e32 vcc, 0, v30
	v_lshlrev_b32_e32 v33, 16, v40
	v_mul_f32_e32 v39, v33, v33
	v_cndmask_b32_e32 v30, v32, v34, vcc
	s_waitcnt vmcnt(2)
	v_lshlrev_b32_e32 v32, 16, v41
	v_mul_f32_e32 v35, v32, v32
	v_mul_f32_e32 v35, 0xbf38aa3b, v35
	v_fma_f32 v34, |v32|, s92, 1.0
	v_exp_f32_e32 v38, v35
	v_fma_f32 v35, |v33|, s92, 1.0
	v_rcp_f32_e32 v34, v34
	v_rcp_f32_e32 v35, v35
	v_mul_f32_e32 v39, 0xbf38aa3b, v39
	v_exp_f32_e32 v39, v39
	v_cmp_gt_f32_e32 vcc, 0, v33
	v_pk_fma_f32 v[40:41], v[34:35], s[12:13], v[24:25] op_sel_hi:[1,0,0]
	s_nop 0
	v_pk_fma_f32 v[40:41], v[34:35], v[40:41], s[14:15] op_sel_hi:[1,1,0]
	s_nop 0
	v_pk_fma_f32 v[40:41], v[34:35], v[40:41], s[16:17] op_sel_hi:[1,1,0]
	s_nop 0
	v_pk_fma_f32 v[40:41], v[34:35], v[40:41], s[18:19] op_sel_hi:[1,1,0]
	v_pk_mul_f32 v[34:35], v[34:35], v[40:41]
	v_pk_mul_f32 v[34:35], v[38:39], v[34:35]
	v_pk_mul_f32 v[38:39], v[34:35], v[32:33]
	v_pk_fma_f32 v[34:35], v[34:35], v[32:33], v[32:33] neg_lo:[1,0,0] neg_hi:[1,0,0]
	v_lshlrev_b32_e32 v33, 16, v42
	v_cndmask_b32_e32 v39, v35, v39, vcc
	v_cmp_gt_f32_e32 vcc, 0, v32
	v_lshlrev_b32_e32 v32, 16, v43
	v_fma_f32 v35, |v33|, s92, 1.0
	v_cndmask_b32_e32 v38, v34, v38, vcc
	v_fma_f32 v34, |v32|, s92, 1.0
	v_rcp_f32_e32 v34, v34
	v_rcp_f32_e32 v35, v35
	v_mul_f32_e32 v40, v32, v32
	v_mul_f32_e32 v41, v33, v33
	v_mul_f32_e32 v40, 0xbf38aa3b, v40
	v_pk_fma_f32 v[42:43], v[34:35], s[12:13], v[24:25] op_sel_hi:[1,0,0]
	v_mul_f32_e32 v41, 0xbf38aa3b, v41
	v_exp_f32_e32 v40, v40
	v_pk_fma_f32 v[42:43], v[34:35], v[42:43], s[14:15] op_sel_hi:[1,1,0]
	v_exp_f32_e32 v41, v41
	v_pk_fma_f32 v[42:43], v[34:35], v[42:43], s[16:17] op_sel_hi:[1,1,0]
	v_cmp_gt_f32_e32 vcc, 0, v33
	v_pk_fma_f32 v[42:43], v[34:35], v[42:43], s[18:19] op_sel_hi:[1,1,0]
	s_nop 0
	v_pk_mul_f32 v[34:35], v[34:35], v[42:43]
	v_pk_mul_f32 v[34:35], v[40:41], v[34:35]
	v_pk_mul_f32 v[40:41], v[34:35], v[32:33]
	v_pk_fma_f32 v[34:35], v[34:35], v[32:33], v[32:33] neg_lo:[1,0,0] neg_hi:[1,0,0]
	v_lshlrev_b32_e32 v33, 16, v46
	v_cndmask_b32_e32 v41, v35, v41, vcc
	v_cmp_gt_f32_e32 vcc, 0, v32
	s_waitcnt vmcnt(1)
	v_lshlrev_b32_e32 v32, 16, v47
	v_mul_f32_e32 v35, v32, v32
	v_mul_f32_e32 v35, 0xbf38aa3b, v35
	v_cndmask_b32_e32 v40, v34, v40, vcc
	v_fma_f32 v34, |v32|, s92, 1.0
	v_exp_f32_e32 v42, v35
	v_fma_f32 v35, |v33|, s92, 1.0
	v_rcp_f32_e32 v34, v34
	v_rcp_f32_e32 v35, v35
	v_mul_f32_e32 v43, v33, v33
	v_mul_f32_e32 v43, 0xbf38aa3b, v43
	v_exp_f32_e32 v43, v43
	v_pk_fma_f32 v[46:47], v[34:35], s[12:13], v[24:25] op_sel_hi:[1,0,0]
	v_cmp_gt_f32_e32 vcc, 0, v33
	v_pk_fma_f32 v[46:47], v[34:35], v[46:47], s[14:15] op_sel_hi:[1,1,0]
	s_nop 0
	v_pk_fma_f32 v[46:47], v[34:35], v[46:47], s[16:17] op_sel_hi:[1,1,0]
	s_nop 0
	v_pk_fma_f32 v[46:47], v[34:35], v[46:47], s[18:19] op_sel_hi:[1,1,0]
	v_pk_mul_f32 v[34:35], v[34:35], v[46:47]
	v_pk_mul_f32 v[34:35], v[42:43], v[34:35]
	v_pk_mul_f32 v[42:43], v[34:35], v[32:33]
	v_pk_fma_f32 v[34:35], v[34:35], v[32:33], v[32:33] neg_lo:[1,0,0] neg_hi:[1,0,0]
	v_lshlrev_b32_e32 v33, 16, v45
	v_cndmask_b32_e32 v47, v35, v43, vcc
	v_cmp_gt_f32_e32 vcc, 0, v32
	v_lshlrev_b32_e32 v32, 16, v48
	v_fma_f32 v35, |v33|, s92, 1.0
	v_cndmask_b32_e32 v46, v34, v42, vcc
	v_fma_f32 v34, |v32|, s92, 1.0
	v_rcp_f32_e32 v34, v34
	v_rcp_f32_e32 v35, v35
	v_mul_f32_e32 v42, v32, v32
	v_mul_f32_e32 v43, v33, v33
	v_mul_f32_e32 v42, 0xbf38aa3b, v42
	v_pk_fma_f32 v[48:49], v[34:35], s[12:13], v[24:25] op_sel_hi:[1,0,0]
	v_mul_f32_e32 v43, 0xbf38aa3b, v43
	v_exp_f32_e32 v42, v42
	v_pk_fma_f32 v[48:49], v[34:35], v[48:49], s[14:15] op_sel_hi:[1,1,0]
	v_exp_f32_e32 v43, v43
	v_pk_fma_f32 v[48:49], v[34:35], v[48:49], s[16:17] op_sel_hi:[1,1,0]
	v_cmp_gt_f32_e32 vcc, 0, v33
	v_pk_fma_f32 v[48:49], v[34:35], v[48:49], s[18:19] op_sel_hi:[1,1,0]
	s_nop 0
	v_pk_mul_f32 v[34:35], v[34:35], v[48:49]
	v_pk_mul_f32 v[34:35], v[42:43], v[34:35]
	v_pk_mul_f32 v[42:43], v[34:35], v[32:33]
	v_pk_fma_f32 v[34:35], v[34:35], v[32:33], v[32:33] neg_lo:[1,0,0] neg_hi:[1,0,0]
	v_lshlrev_b32_e32 v33, 16, v50
	v_cndmask_b32_e32 v43, v35, v43, vcc
	v_cmp_gt_f32_e32 vcc, 0, v32
	s_waitcnt vmcnt(0)
	v_lshlrev_b32_e32 v32, 16, v51
	v_mul_f32_e32 v35, v32, v32
	v_mul_f32_e32 v35, 0xbf38aa3b, v35
	v_cndmask_b32_e32 v42, v34, v42, vcc
	v_fma_f32 v34, |v32|, s92, 1.0
	v_exp_f32_e32 v48, v35
	v_fma_f32 v35, |v33|, s92, 1.0
	v_rcp_f32_e32 v34, v34
	v_rcp_f32_e32 v35, v35
	v_mul_f32_e32 v45, v33, v33
	v_mul_f32_e32 v45, 0xbf38aa3b, v45
	v_exp_f32_e32 v49, v45
	v_pk_fma_f32 v[50:51], v[34:35], s[12:13], v[24:25] op_sel_hi:[1,0,0]
	v_cmp_gt_f32_e32 vcc, 0, v33
	v_pk_fma_f32 v[50:51], v[34:35], v[50:51], s[14:15] op_sel_hi:[1,1,0]
	s_nop 0
	v_pk_fma_f32 v[50:51], v[34:35], v[50:51], s[16:17] op_sel_hi:[1,1,0]
	s_nop 0
	v_pk_fma_f32 v[50:51], v[34:35], v[50:51], s[18:19] op_sel_hi:[1,1,0]
	v_pk_mul_f32 v[34:35], v[34:35], v[50:51]
	v_mov_b32_e32 v50, v31
	v_pk_mul_f32 v[34:35], v[48:49], v[34:35]
	v_mov_b32_e32 v51, v43
	v_pk_mul_f32 v[48:49], v[34:35], v[32:33]
	v_pk_fma_f32 v[34:35], v[34:35], v[32:33], v[32:33] neg_lo:[1,0,0] neg_hi:[1,0,0]
	v_mov_b32_e32 v33, v40
	v_cndmask_b32_e32 v49, v35, v49, vcc
	v_cmp_gt_f32_e32 vcc, 0, v32
	v_mov_b32_e32 v32, v28
	v_mov_b32_e32 v35, v42
	v_cndmask_b32_e32 v48, v34, v48, vcc
	v_mov_b32_e32 v34, v30
	v_pk_add_f32 v[32:33], v[32:33], v[34:35]
	v_mov_b32_e32 v34, v29
	v_add_f32_e32 v32, v32, v33
	v_mov_b32_e32 v33, v131
	v_mov_b32_e32 v35, v41
	v_add_f32_dpp v32, v32, v32 quad_perm:[1,0,3,2] row_mask:0xf bank_mask:0xf bound_ctrl:1
	v_pk_add_f32 v[34:35], v[34:35], v[50:51]
	v_mov_b32_e32 v50, v39
	v_add_f32_dpp v32, v32, v32 quad_perm:[2,3,0,1] row_mask:0xf bank_mask:0xf bound_ctrl:1
	v_mov_b32_e32 v51, v49
	s_nop 0
	v_add_f32_dpp v32, v32, v32 row_half_mirror row_mask:0xf bank_mask:0xf bound_ctrl:1
	s_nop 1
	v_add_f32_dpp v32, v32, v32 row_mirror row_mask:0xf bank_mask:0xf bound_ctrl:1
	s_nop 1
	v_mov_b32_dpp v33, v32 row_bcast:15 row_mask:0xa bank_mask:0xf
	v_add_f32_e32 v32, v32, v33
	v_mov_b32_e32 v33, v131
	s_nop 1
	v_mov_b32_dpp v33, v32 row_bcast:31 row_mask:0xc bank_mask:0xf
	v_add_f32_e32 v32, v32, v33
	v_add_f32_e32 v33, v34, v35
	v_mov_b32_e32 v34, v131
	v_readlane_b32 s6, v32, 63
	v_add_f32_dpp v33, v33, v33 quad_perm:[1,0,3,2] row_mask:0xf bank_mask:0xf bound_ctrl:1
	s_xor_b32 s6, s6, 0x80000000
	s_nop 0
	v_add_f32_dpp v33, v33, v33 quad_perm:[2,3,0,1] row_mask:0xf bank_mask:0xf bound_ctrl:1
	s_nop 1
	v_add_f32_dpp v33, v33, v33 row_half_mirror row_mask:0xf bank_mask:0xf bound_ctrl:1
	s_nop 1
	v_add_f32_dpp v33, v33, v33 row_mirror row_mask:0xf bank_mask:0xf bound_ctrl:1
	s_nop 1
	v_mov_b32_dpp v34, v33 row_bcast:15 row_mask:0xa bank_mask:0xf
	v_add_f32_e32 v33, v33, v34
	v_mov_b32_e32 v34, v131
	s_nop 1
	v_mov_b32_dpp v34, v33 row_bcast:31 row_mask:0xc bank_mask:0xf
	v_add_f32_e32 v33, v33, v34
	s_nop 0
	v_readlane_b32 s7, v33, 63
	s_xor_b32 s7, s7, 0x80000000
	s_nop 0
	v_pk_fma_f32 v[34:35], s[6:7], v[26:27], v[28:29] op_sel_hi:[1,0,1]
	v_pk_fma_f32 v[32:33], s[6:7], v[26:27], v[30:31] op_sel_hi:[1,0,1]
	v_pk_fma_f32 v[30:31], s[6:7], v[26:27], v[40:41] op_sel_hi:[1,0,1]
	v_pk_fma_f32 v[28:29], s[6:7], v[26:27], v[42:43] op_sel_hi:[1,0,1]
	v_mov_b32_e32 v40, v36
	v_mov_b32_e32 v41, v46
	v_mov_b32_e32 v42, v38
	v_mov_b32_e32 v43, v48
	v_pk_add_f32 v[40:41], v[40:41], v[42:43]
	v_mov_b32_e32 v42, v37
	v_add_f32_e32 v40, v40, v41
	v_mov_b32_e32 v41, v131
	v_mov_b32_e32 v43, v47
	v_add_f32_dpp v40, v40, v40 quad_perm:[1,0,3,2] row_mask:0xf bank_mask:0xf bound_ctrl:1
	v_pk_add_f32 v[42:43], v[42:43], v[50:51]
	s_nop 0
	v_add_f32_dpp v40, v40, v40 quad_perm:[2,3,0,1] row_mask:0xf bank_mask:0xf bound_ctrl:1
	s_nop 1
	v_add_f32_dpp v40, v40, v40 row_half_mirror row_mask:0xf bank_mask:0xf bound_ctrl:1
	s_nop 1
	v_add_f32_dpp v40, v40, v40 row_mirror row_mask:0xf bank_mask:0xf bound_ctrl:1
	s_nop 1
	v_mov_b32_dpp v41, v40 row_bcast:15 row_mask:0xa bank_mask:0xf
	v_add_f32_e32 v40, v40, v41
	v_mov_b32_e32 v41, v131
	s_nop 1
	v_mov_b32_dpp v41, v40 row_bcast:31 row_mask:0xc bank_mask:0xf
	v_add_f32_e32 v40, v40, v41
	v_add_f32_e32 v41, v42, v43
	v_mov_b32_e32 v42, v131
	v_readlane_b32 s6, v40, 63
	v_add_f32_dpp v41, v41, v41 quad_perm:[1,0,3,2] row_mask:0xf bank_mask:0xf bound_ctrl:1
	s_xor_b32 s6, s6, 0x80000000
	s_nop 0
	v_add_f32_dpp v41, v41, v41 quad_perm:[2,3,0,1] row_mask:0xf bank_mask:0xf bound_ctrl:1
	s_nop 1
	v_add_f32_dpp v41, v41, v41 row_half_mirror row_mask:0xf bank_mask:0xf bound_ctrl:1
	s_nop 1
	v_add_f32_dpp v41, v41, v41 row_mirror row_mask:0xf bank_mask:0xf bound_ctrl:1
	s_nop 1
	v_mov_b32_dpp v42, v41 row_bcast:15 row_mask:0xa bank_mask:0xf
	v_add_f32_e32 v41, v41, v42
	v_mov_b32_e32 v42, v131
	s_nop 1
	v_mov_b32_dpp v42, v41 row_bcast:31 row_mask:0xc bank_mask:0xf
	v_add_f32_e32 v41, v41, v42
	s_nop 0
	v_readlane_b32 s7, v41, 63
	s_xor_b32 s7, s7, 0x80000000
	s_nop 0
	v_pk_fma_f32 v[40:41], s[6:7], v[26:27], v[38:39] op_sel_hi:[1,0,1]
	v_pk_fma_f32 v[38:39], s[6:7], v[26:27], v[46:47] op_sel_hi:[1,0,1]
	global_load_ushort v52, v44, s[54:55] offset:512
	global_load_ushort v56, v44, s[54:55] offset:640
	global_load_ushort v77, v44, s[54:55] offset:768
	global_load_ushort v82, v44, s[54:55] offset:896
	global_load_ushort v53, v44, s[46:47] offset:512
	global_load_ushort v57, v44, s[46:47] offset:640
	global_load_ushort v78, v44, s[46:47] offset:768
	global_load_ushort v83, v44, s[46:47] offset:896
	global_load_ushort v45, v44, s[56:57] offset:512
	global_load_ushort v54, v44, s[56:57] offset:640
	global_load_ushort v58, v44, s[56:57] offset:768
	global_load_ushort v80, v44, s[56:57] offset:896
	global_load_ushort v46, v44, s[48:49] offset:512
	global_load_ushort v55, v44, s[48:49] offset:640
	global_load_ushort v59, v44, s[48:49] offset:768
	global_load_ushort v81, v44, s[48:49] offset:896
	global_load_ushort v66, v44, s[50:51] offset:512
	global_load_ushort v68, v44, s[50:51] offset:640
	global_load_ushort v72, v44, s[50:51] offset:768
	global_load_ushort v64, v44, s[50:51] offset:896
	global_load_ushort v67, v44, s[42:43] offset:512
	global_load_ushort v69, v44, s[42:43] offset:640
	global_load_ushort v73, v44, s[42:43] offset:768
	global_load_ushort v65, v44, s[42:43] offset:896
	global_load_ushort v60, v44, s[52:53] offset:512
	global_load_ushort v62, v44, s[52:53] offset:640
	global_load_ushort v75, v44, s[52:53] offset:768
	global_load_ushort v70, v44, s[52:53] offset:896
	global_load_ushort v61, v44, s[44:45] offset:512
	global_load_ushort v63, v44, s[44:45] offset:640
	global_load_ushort v76, v44, s[44:45] offset:768
	global_load_ushort v71, v44, s[44:45] offset:896
	v_pk_fma_f32 v[42:43], s[6:7], v[26:27], v[36:37] op_sel_hi:[1,0,1]
	v_pk_fma_f32 v[36:37], s[6:7], v[26:27], v[48:49] op_sel_hi:[1,0,1]
	s_movk_i32 s46, 0x2000
	s_waitcnt vmcnt(23)
	v_lshlrev_b32_e32 v45, 16, v45
	v_fma_f32 v47, |v45|, s92, 1.0
	v_rcp_f32_e32 v47, v47
	v_mul_f32_e32 v49, v45, v45
	s_waitcnt vmcnt(19)
	v_lshlrev_b32_e32 v44, 16, v46
	v_fma_f32 v46, |v44|, s92, 1.0
	v_rcp_f32_e32 v46, v46
	v_mul_f32_e32 v48, v44, v44
	v_mul_f32_e32 v48, 0xbf38aa3b, v48
	v_mul_f32_e32 v49, 0xbf38aa3b, v49
	v_pk_fma_f32 v[50:51], v[46:47], s[12:13], v[24:25] op_sel_hi:[1,0,0]
	v_exp_f32_e32 v48, v48
	v_pk_fma_f32 v[50:51], v[46:47], v[50:51], s[14:15] op_sel_hi:[1,1,0]
	v_exp_f32_e32 v49, v49
	v_pk_fma_f32 v[50:51], v[46:47], v[50:51], s[16:17] op_sel_hi:[1,1,0]
	v_cmp_gt_f32_e32 vcc, 0, v45
	v_pk_fma_f32 v[50:51], v[46:47], v[50:51], s[18:19] op_sel_hi:[1,1,0]
	s_waitcnt vmcnt(1)
	v_lshlrev_b32_e32 v76, 16, v76
	v_pk_mul_f32 v[46:47], v[46:47], v[50:51]
	v_pk_mul_f32 v[46:47], v[48:49], v[46:47]
	v_pk_mul_f32 v[48:49], v[46:47], v[44:45]
	v_pk_fma_f32 v[46:47], v[46:47], v[44:45], v[44:45] neg_lo:[1,0,0] neg_hi:[1,0,0]
	s_nop 0
	v_cndmask_b32_e32 v45, v47, v49, vcc
	v_cmp_gt_f32_e32 vcc, 0, v44
	v_lshlrev_b32_e32 v47, 16, v52
	v_mul_f32_e32 v51, v47, v47
	v_cndmask_b32_e32 v44, v46, v48, vcc
	v_lshlrev_b32_e32 v46, 16, v53
	v_mul_f32_e32 v49, v46, v46
	v_mul_f32_e32 v49, 0xbf38aa3b, v49
	v_fma_f32 v48, |v46|, s92, 1.0
	v_exp_f32_e32 v50, v49
	v_fma_f32 v49, |v47|, s92, 1.0
	v_rcp_f32_e32 v48, v48
	v_rcp_f32_e32 v49, v49
	v_mul_f32_e32 v51, 0xbf38aa3b, v51
	v_exp_f32_e32 v51, v51
	v_cmp_gt_f32_e32 vcc, 0, v47
	v_pk_fma_f32 v[52:53], v[48:49], s[12:13], v[24:25] op_sel_hi:[1,0,0]
	s_nop 0
	v_pk_fma_f32 v[52:53], v[48:49], v[52:53], s[14:15] op_sel_hi:[1,1,0]
	s_nop 0
	v_pk_fma_f32 v[52:53], v[48:49], v[52:53], s[16:17] op_sel_hi:[1,1,0]
	s_nop 0
	v_pk_fma_f32 v[52:53], v[48:49], v[52:53], s[18:19] op_sel_hi:[1,1,0]
	v_pk_mul_f32 v[48:49], v[48:49], v[52:53]
	v_pk_mul_f32 v[48:49], v[50:51], v[48:49]
	v_pk_mul_f32 v[50:51], v[48:49], v[46:47]
	v_pk_fma_f32 v[48:49], v[48:49], v[46:47], v[46:47] neg_lo:[1,0,0] neg_hi:[1,0,0]
	v_lshlrev_b32_e32 v47, 16, v54
	v_cndmask_b32_e32 v53, v49, v51, vcc
	v_cmp_gt_f32_e32 vcc, 0, v46
	v_lshlrev_b32_e32 v46, 16, v55
	v_fma_f32 v49, |v47|, s92, 1.0
	v_cndmask_b32_e32 v52, v48, v50, vcc
	v_fma_f32 v48, |v46|, s92, 1.0
	v_rcp_f32_e32 v48, v48
	v_rcp_f32_e32 v49, v49
	v_mul_f32_e32 v50, v46, v46
	v_mul_f32_e32 v51, v47, v47
	v_mul_f32_e32 v50, 0xbf38aa3b, v50
	v_pk_fma_f32 v[54:55], v[48:49], s[12:13], v[24:25] op_sel_hi:[1,0,0]
	v_mul_f32_e32 v51, 0xbf38aa3b, v51
	v_exp_f32_e32 v50, v50
	v_pk_fma_f32 v[54:55], v[48:49], v[54:55], s[14:15] op_sel_hi:[1,1,0]
	v_exp_f32_e32 v51, v51
	v_pk_fma_f32 v[54:55], v[48:49], v[54:55], s[16:17] op_sel_hi:[1,1,0]
	v_cmp_gt_f32_e32 vcc, 0, v47
	v_pk_fma_f32 v[54:55], v[48:49], v[54:55], s[18:19] op_sel_hi:[1,1,0]
	s_nop 0
	v_pk_mul_f32 v[48:49], v[48:49], v[54:55]
	v_pk_mul_f32 v[48:49], v[50:51], v[48:49]
	v_pk_mul_f32 v[50:51], v[48:49], v[46:47]
	v_pk_fma_f32 v[48:49], v[48:49], v[46:47], v[46:47] neg_lo:[1,0,0] neg_hi:[1,0,0]
	v_lshlrev_b32_e32 v47, 16, v56
	v_cndmask_b32_e32 v49, v49, v51, vcc
	v_cmp_gt_f32_e32 vcc, 0, v46
	v_lshlrev_b32_e32 v46, 16, v57
	v_mul_f32_e32 v51, v46, v46
	v_mul_f32_e32 v51, 0xbf38aa3b, v51
	v_cndmask_b32_e32 v48, v48, v50, vcc
	v_fma_f32 v50, |v46|, s92, 1.0
	v_exp_f32_e32 v54, v51
	v_fma_f32 v51, |v47|, s92, 1.0
	v_rcp_f32_e32 v50, v50
	v_rcp_f32_e32 v51, v51
	v_mul_f32_e32 v55, v47, v47
	v_mul_f32_e32 v55, 0xbf38aa3b, v55
	v_exp_f32_e32 v55, v55
	v_pk_fma_f32 v[56:57], v[50:51], s[12:13], v[24:25] op_sel_hi:[1,0,0]
	v_cmp_gt_f32_e32 vcc, 0, v47
	v_pk_fma_f32 v[56:57], v[50:51], v[56:57], s[14:15] op_sel_hi:[1,1,0]
	s_nop 0
	v_pk_fma_f32 v[56:57], v[50:51], v[56:57], s[16:17] op_sel_hi:[1,1,0]
	s_nop 0
	v_pk_fma_f32 v[56:57], v[50:51], v[56:57], s[18:19] op_sel_hi:[1,1,0]
	v_pk_mul_f32 v[50:51], v[50:51], v[56:57]
	v_pk_mul_f32 v[50:51], v[54:55], v[50:51]
	v_pk_mul_f32 v[54:55], v[50:51], v[46:47]
	v_pk_fma_f32 v[50:51], v[50:51], v[46:47], v[46:47] neg_lo:[1,0,0] neg_hi:[1,0,0]
	v_lshlrev_b32_e32 v47, 16, v58
	v_cndmask_b32_e32 v55, v51, v55, vcc
	v_cmp_gt_f32_e32 vcc, 0, v46
	v_lshlrev_b32_e32 v46, 16, v59
	v_fma_f32 v51, |v47|, s92, 1.0
	v_cndmask_b32_e32 v54, v50, v54, vcc
	v_fma_f32 v50, |v46|, s92, 1.0
	v_rcp_f32_e32 v50, v50
	v_rcp_f32_e32 v51, v51
	v_mul_f32_e32 v56, v46, v46
	v_mul_f32_e32 v57, v47, v47
	v_mul_f32_e32 v56, 0xbf38aa3b, v56
	v_pk_fma_f32 v[58:59], v[50:51], s[12:13], v[24:25] op_sel_hi:[1,0,0]
	v_mul_f32_e32 v57, 0xbf38aa3b, v57
	v_exp_f32_e32 v56, v56
	v_pk_fma_f32 v[58:59], v[50:51], v[58:59], s[14:15] op_sel_hi:[1,1,0]
	v_exp_f32_e32 v57, v57
	v_pk_fma_f32 v[58:59], v[50:51], v[58:59], s[16:17] op_sel_hi:[1,1,0]
	v_cmp_gt_f32_e32 vcc, 0, v47
	v_pk_fma_f32 v[58:59], v[50:51], v[58:59], s[18:19] op_sel_hi:[1,1,0]
	s_nop 0
	v_pk_mul_f32 v[50:51], v[50:51], v[58:59]
	v_pk_mul_f32 v[50:51], v[56:57], v[50:51]
	v_pk_mul_f32 v[56:57], v[50:51], v[46:47]
	v_pk_fma_f32 v[50:51], v[50:51], v[46:47], v[46:47] neg_lo:[1,0,0] neg_hi:[1,0,0]
	v_lshlrev_b32_e32 v47, 16, v77
	v_cndmask_b32_e32 v57, v51, v57, vcc
	v_cmp_gt_f32_e32 vcc, 0, v46
	v_lshlrev_b32_e32 v46, 16, v78
	v_mul_f32_e32 v51, v46, v46
	v_mul_f32_e32 v51, 0xbf38aa3b, v51
	v_cndmask_b32_e32 v56, v50, v56, vcc
	v_fma_f32 v50, |v46|, s92, 1.0
	v_exp_f32_e32 v58, v51
	v_fma_f32 v51, |v47|, s92, 1.0
	v_rcp_f32_e32 v50, v50
	v_rcp_f32_e32 v51, v51
	v_mul_f32_e32 v59, v47, v47
	v_mul_f32_e32 v59, 0xbf38aa3b, v59
	v_exp_f32_e32 v59, v59
	v_pk_fma_f32 v[78:79], v[50:51], s[12:13], v[24:25] op_sel_hi:[1,0,0]
	v_cmp_gt_f32_e32 vcc, 0, v47
	v_pk_fma_f32 v[78:79], v[50:51], v[78:79], s[14:15] op_sel_hi:[1,1,0]
	s_nop 0
	v_pk_fma_f32 v[78:79], v[50:51], v[78:79], s[16:17] op_sel_hi:[1,1,0]
	s_nop 0
	v_pk_fma_f32 v[78:79], v[50:51], v[78:79], s[18:19] op_sel_hi:[1,1,0]
	v_pk_mul_f32 v[50:51], v[50:51], v[78:79]
	v_pk_mul_f32 v[50:51], v[58:59], v[50:51]
	v_pk_mul_f32 v[58:59], v[50:51], v[46:47]
	v_pk_fma_f32 v[50:51], v[50:51], v[46:47], v[46:47] neg_lo:[1,0,0] neg_hi:[1,0,0]
	v_lshlrev_b32_e32 v47, 16, v80
	v_cndmask_b32_e32 v79, v51, v59, vcc
	v_cmp_gt_f32_e32 vcc, 0, v46
	v_lshlrev_b32_e32 v46, 16, v81
	v_fma_f32 v51, |v47|, s92, 1.0
	v_cndmask_b32_e32 v78, v50, v58, vcc
	v_fma_f32 v50, |v46|, s92, 1.0
	v_rcp_f32_e32 v50, v50
	v_rcp_f32_e32 v51, v51
	v_mul_f32_e32 v58, v46, v46
	v_mul_f32_e32 v59, v47, v47
	v_mul_f32_e32 v58, 0xbf38aa3b, v58
	v_pk_fma_f32 v[80:81], v[50:51], s[12:13], v[24:25] op_sel_hi:[1,0,0]
	v_mul_f32_e32 v59, 0xbf38aa3b, v59
	v_exp_f32_e32 v58, v58
	v_pk_fma_f32 v[80:81], v[50:51], v[80:81], s[14:15] op_sel_hi:[1,1,0]
	v_exp_f32_e32 v59, v59
	v_pk_fma_f32 v[80:81], v[50:51], v[80:81], s[16:17] op_sel_hi:[1,1,0]
	v_cmp_gt_f32_e32 vcc, 0, v47
	v_pk_fma_f32 v[80:81], v[50:51], v[80:81], s[18:19] op_sel_hi:[1,1,0]
	s_nop 0
	v_pk_mul_f32 v[50:51], v[50:51], v[80:81]
	v_pk_mul_f32 v[50:51], v[58:59], v[50:51]
	v_pk_mul_f32 v[58:59], v[50:51], v[46:47]
	v_pk_fma_f32 v[50:51], v[50:51], v[46:47], v[46:47] neg_lo:[1,0,0] neg_hi:[1,0,0]
	v_lshlrev_b32_e32 v47, 16, v82
	v_cndmask_b32_e32 v59, v51, v59, vcc
	v_cmp_gt_f32_e32 vcc, 0, v46
	v_lshlrev_b32_e32 v46, 16, v83
	v_mul_f32_e32 v51, v46, v46
	v_mul_f32_e32 v51, 0xbf38aa3b, v51
	v_cndmask_b32_e32 v58, v50, v58, vcc
	v_fma_f32 v50, |v46|, s92, 1.0
	v_exp_f32_e32 v80, v51
	v_fma_f32 v51, |v47|, s92, 1.0
	v_rcp_f32_e32 v50, v50
	v_rcp_f32_e32 v51, v51
	v_mul_f32_e32 v77, v47, v47
	v_mul_f32_e32 v77, 0xbf38aa3b, v77
	v_exp_f32_e32 v81, v77
	v_pk_fma_f32 v[82:83], v[50:51], s[12:13], v[24:25] op_sel_hi:[1,0,0]
	v_cmp_gt_f32_e32 vcc, 0, v47
	v_pk_fma_f32 v[82:83], v[50:51], v[82:83], s[14:15] op_sel_hi:[1,1,0]
	s_nop 0
	v_pk_fma_f32 v[82:83], v[50:51], v[82:83], s[16:17] op_sel_hi:[1,1,0]
	s_nop 0
	v_pk_fma_f32 v[82:83], v[50:51], v[82:83], s[18:19] op_sel_hi:[1,1,0]
	v_pk_mul_f32 v[50:51], v[50:51], v[82:83]
	v_mov_b32_e32 v82, v49
	v_pk_mul_f32 v[50:51], v[80:81], v[50:51]
	v_mov_b32_e32 v83, v59
	v_pk_mul_f32 v[80:81], v[50:51], v[46:47]
	v_pk_fma_f32 v[50:51], v[50:51], v[46:47], v[46:47] neg_lo:[1,0,0] neg_hi:[1,0,0]
	v_mov_b32_e32 v47, v56
	v_cndmask_b32_e32 v81, v51, v81, vcc
	v_cmp_gt_f32_e32 vcc, 0, v46
	v_mov_b32_e32 v46, v44
	v_mov_b32_e32 v51, v58
	v_cndmask_b32_e32 v80, v50, v80, vcc
	v_mov_b32_e32 v50, v48
	v_pk_add_f32 v[46:47], v[46:47], v[50:51]
	v_mov_b32_e32 v50, v45
	v_add_f32_e32 v46, v46, v47
	v_mov_b32_e32 v47, v131
	v_mov_b32_e32 v51, v57
	v_add_f32_dpp v46, v46, v46 quad_perm:[1,0,3,2] row_mask:0xf bank_mask:0xf bound_ctrl:1
	v_pk_add_f32 v[50:51], v[50:51], v[82:83]
	v_mov_b32_e32 v82, v55
	v_add_f32_dpp v46, v46, v46 quad_perm:[2,3,0,1] row_mask:0xf bank_mask:0xf bound_ctrl:1
	v_mov_b32_e32 v83, v81
	s_nop 0
	v_add_f32_dpp v46, v46, v46 row_half_mirror row_mask:0xf bank_mask:0xf bound_ctrl:1
	s_nop 1
	v_add_f32_dpp v46, v46, v46 row_mirror row_mask:0xf bank_mask:0xf bound_ctrl:1
	s_nop 1
	v_mov_b32_dpp v47, v46 row_bcast:15 row_mask:0xa bank_mask:0xf
	v_add_f32_e32 v46, v46, v47
	v_mov_b32_e32 v47, v131
	s_nop 1
	v_mov_b32_dpp v47, v46 row_bcast:31 row_mask:0xc bank_mask:0xf
	v_add_f32_e32 v46, v46, v47
	v_add_f32_e32 v47, v50, v51
	v_mov_b32_e32 v50, v131
	v_readlane_b32 s6, v46, 63
	v_add_f32_dpp v47, v47, v47 quad_perm:[1,0,3,2] row_mask:0xf bank_mask:0xf bound_ctrl:1
	s_xor_b32 s6, s6, 0x80000000
	s_nop 0
	v_add_f32_dpp v47, v47, v47 quad_perm:[2,3,0,1] row_mask:0xf bank_mask:0xf bound_ctrl:1
	s_nop 1
	v_add_f32_dpp v47, v47, v47 row_half_mirror row_mask:0xf bank_mask:0xf bound_ctrl:1
	s_nop 1
	v_add_f32_dpp v47, v47, v47 row_mirror row_mask:0xf bank_mask:0xf bound_ctrl:1
	s_nop 1
	v_mov_b32_dpp v50, v47 row_bcast:15 row_mask:0xa bank_mask:0xf
	v_add_f32_e32 v47, v47, v50
	v_mov_b32_e32 v50, v131
	s_nop 1
	v_mov_b32_dpp v50, v47 row_bcast:31 row_mask:0xc bank_mask:0xf
	v_add_f32_e32 v47, v47, v50
	s_nop 0
	v_readlane_b32 s7, v47, 63
	s_xor_b32 s7, s7, 0x80000000
	s_nop 0
	v_pk_fma_f32 v[46:47], s[6:7], v[26:27], v[44:45] op_sel_hi:[1,0,1]
	v_pk_fma_f32 v[50:51], s[6:7], v[26:27], v[48:49] op_sel_hi:[1,0,1]
	v_pk_fma_f32 v[48:49], s[6:7], v[26:27], v[56:57] op_sel_hi:[1,0,1]
	v_pk_fma_f32 v[44:45], s[6:7], v[26:27], v[58:59] op_sel_hi:[1,0,1]
	v_mov_b32_e32 v56, v52
	v_mov_b32_e32 v57, v78
	v_mov_b32_e32 v58, v54
	v_mov_b32_e32 v59, v80
	v_pk_add_f32 v[56:57], v[56:57], v[58:59]
	v_mov_b32_e32 v58, v53
	v_add_f32_e32 v56, v56, v57
	v_mov_b32_e32 v57, v131
	v_mov_b32_e32 v59, v79
	v_add_f32_dpp v56, v56, v56 quad_perm:[1,0,3,2] row_mask:0xf bank_mask:0xf bound_ctrl:1
	v_pk_add_f32 v[58:59], v[58:59], v[82:83]
	s_nop 0
	v_add_f32_dpp v56, v56, v56 quad_perm:[2,3,0,1] row_mask:0xf bank_mask:0xf bound_ctrl:1
	s_nop 1
	v_add_f32_dpp v56, v56, v56 row_half_mirror row_mask:0xf bank_mask:0xf bound_ctrl:1
	s_nop 1
	v_add_f32_dpp v56, v56, v56 row_mirror row_mask:0xf bank_mask:0xf bound_ctrl:1
	s_nop 1
	v_mov_b32_dpp v57, v56 row_bcast:15 row_mask:0xa bank_mask:0xf
	v_add_f32_e32 v56, v56, v57
	v_mov_b32_e32 v57, v131
	s_nop 1
	v_mov_b32_dpp v57, v56 row_bcast:31 row_mask:0xc bank_mask:0xf
	v_add_f32_e32 v56, v56, v57
	v_add_f32_e32 v57, v58, v59
	v_mov_b32_e32 v58, v131
	v_readlane_b32 s6, v56, 63
	v_add_f32_dpp v57, v57, v57 quad_perm:[1,0,3,2] row_mask:0xf bank_mask:0xf bound_ctrl:1
	s_xor_b32 s6, s6, 0x80000000
	s_nop 0
	v_add_f32_dpp v57, v57, v57 quad_perm:[2,3,0,1] row_mask:0xf bank_mask:0xf bound_ctrl:1
	s_nop 1
	v_add_f32_dpp v57, v57, v57 row_half_mirror row_mask:0xf bank_mask:0xf bound_ctrl:1
	s_nop 1
	v_add_f32_dpp v57, v57, v57 row_mirror row_mask:0xf bank_mask:0xf bound_ctrl:1
	s_nop 1
	v_mov_b32_dpp v58, v57 row_bcast:15 row_mask:0xa bank_mask:0xf
	v_add_f32_e32 v57, v57, v58
	v_mov_b32_e32 v58, v131
	s_nop 1
	v_mov_b32_dpp v58, v57 row_bcast:31 row_mask:0xc bank_mask:0xf
	v_add_f32_e32 v57, v57, v58
	s_nop 0
	v_readlane_b32 s7, v57, 63
	s_xor_b32 s7, s7, 0x80000000
	s_nop 0
	v_pk_fma_f32 v[56:57], s[6:7], v[26:27], v[54:55] op_sel_hi:[1,0,1]
	v_pk_fma_f32 v[54:55], s[6:7], v[26:27], v[78:79] op_sel_hi:[1,0,1]
	v_lshlrev_b32_e32 v79, 16, v60
	v_lshlrev_b32_e32 v78, 16, v61
	v_fma_f32 v60, |v78|, s92, 1.0
	v_fma_f32 v61, |v79|, s92, 1.0
	v_rcp_f32_e32 v60, v60
	v_rcp_f32_e32 v61, v61
	v_mul_f32_e32 v77, v78, v78
	v_mul_f32_e32 v77, 0xbf38aa3b, v77
	v_pk_fma_f32 v[58:59], s[6:7], v[26:27], v[52:53] op_sel_hi:[1,0,1]
	v_pk_fma_f32 v[52:53], s[6:7], v[26:27], v[80:81] op_sel_hi:[1,0,1]
	v_exp_f32_e32 v80, v77
	v_mul_f32_e32 v77, v79, v79
	v_pk_fma_f32 v[82:83], v[60:61], s[12:13], v[24:25] op_sel_hi:[1,0,0]
	v_mul_f32_e32 v77, 0xbf38aa3b, v77
	v_pk_fma_f32 v[82:83], v[60:61], v[82:83], s[14:15] op_sel_hi:[1,1,0]
	v_exp_f32_e32 v81, v77
	v_pk_fma_f32 v[82:83], v[60:61], v[82:83], s[16:17] op_sel_hi:[1,1,0]
	v_cmp_gt_f32_e32 vcc, 0, v79
	v_pk_fma_f32 v[82:83], v[60:61], v[82:83], s[18:19] op_sel_hi:[1,1,0]
	s_mov_b32 s6, 0xbe11a98e
	v_pk_mul_f32 v[60:61], v[60:61], v[82:83]
	v_pk_mul_f32 v[60:61], v[80:81], v[60:61]
	v_pk_mul_f32 v[80:81], v[60:61], v[78:79]
	v_pk_fma_f32 v[60:61], v[60:61], v[78:79], v[78:79] neg_lo:[1,0,0] neg_hi:[1,0,0]
	v_lshlrev_b32_e32 v79, 16, v66
	v_cndmask_b32_e32 v61, v61, v81, vcc
	v_cmp_gt_f32_e32 vcc, 0, v78
	v_lshlrev_b32_e32 v78, 16, v67
	v_mul_f32_e32 v67, v78, v78
	v_mul_f32_e32 v67, 0xbf38aa3b, v67
	v_cndmask_b32_e32 v60, v60, v80, vcc
	v_fma_f32 v66, |v78|, s92, 1.0
	v_exp_f32_e32 v80, v67
	v_fma_f32 v67, |v79|, s92, 1.0
	v_rcp_f32_e32 v66, v66
	v_rcp_f32_e32 v67, v67
	v_mul_f32_e32 v77, v79, v79
	v_mul_f32_e32 v77, 0xbf38aa3b, v77
	v_exp_f32_e32 v81, v77
	v_pk_fma_f32 v[82:83], v[66:67], s[12:13], v[24:25] op_sel_hi:[1,0,0]
	v_cmp_gt_f32_e32 vcc, 0, v79
	v_pk_fma_f32 v[82:83], v[66:67], v[82:83], s[14:15] op_sel_hi:[1,1,0]
	s_nop 0
	v_pk_fma_f32 v[82:83], v[66:67], v[82:83], s[16:17] op_sel_hi:[1,1,0]
	s_nop 0
	v_pk_fma_f32 v[82:83], v[66:67], v[82:83], s[18:19] op_sel_hi:[1,1,0]
	v_pk_mul_f32 v[66:67], v[66:67], v[82:83]
	v_pk_mul_f32 v[66:67], v[80:81], v[66:67]
	v_pk_mul_f32 v[80:81], v[66:67], v[78:79]
	v_pk_fma_f32 v[66:67], v[66:67], v[78:79], v[78:79] neg_lo:[1,0,0] neg_hi:[1,0,0]
	v_lshlrev_b32_e32 v79, 16, v62
	v_cndmask_b32_e32 v67, v67, v81, vcc
	v_cmp_gt_f32_e32 vcc, 0, v78
	v_lshlrev_b32_e32 v78, 16, v63
	v_fma_f32 v62, |v78|, s92, 1.0
	v_fma_f32 v63, |v79|, s92, 1.0
	v_rcp_f32_e32 v62, v62
	v_rcp_f32_e32 v63, v63
	v_mul_f32_e32 v77, v78, v78
	v_mul_f32_e32 v77, 0xbf38aa3b, v77
	v_cndmask_b32_e32 v66, v66, v80, vcc
	v_exp_f32_e32 v80, v77
	v_mul_f32_e32 v77, v79, v79
	v_pk_fma_f32 v[82:83], v[62:63], s[12:13], v[24:25] op_sel_hi:[1,0,0]
	v_mul_f32_e32 v77, 0xbf38aa3b, v77
	v_pk_fma_f32 v[82:83], v[62:63], v[82:83], s[14:15] op_sel_hi:[1,1,0]
	v_exp_f32_e32 v81, v77
	v_pk_fma_f32 v[82:83], v[62:63], v[82:83], s[16:17] op_sel_hi:[1,1,0]
	v_cmp_gt_f32_e32 vcc, 0, v79
	v_pk_fma_f32 v[82:83], v[62:63], v[82:83], s[18:19] op_sel_hi:[1,1,0]
	s_nop 0
	v_pk_mul_f32 v[62:63], v[62:63], v[82:83]
	v_pk_mul_f32 v[62:63], v[80:81], v[62:63]
	v_pk_mul_f32 v[80:81], v[62:63], v[78:79]
	v_pk_fma_f32 v[62:63], v[62:63], v[78:79], v[78:79] neg_lo:[1,0,0] neg_hi:[1,0,0]
	v_lshlrev_b32_e32 v79, 16, v68
	v_cndmask_b32_e32 v63, v63, v81, vcc
	v_cmp_gt_f32_e32 vcc, 0, v78
	v_lshlrev_b32_e32 v78, 16, v69
	v_mul_f32_e32 v69, v78, v78
	v_mul_f32_e32 v69, 0xbf38aa3b, v69
	v_cndmask_b32_e32 v62, v62, v80, vcc
	v_fma_f32 v68, |v78|, s92, 1.0
	v_exp_f32_e32 v80, v69
	v_fma_f32 v69, |v79|, s92, 1.0
	v_rcp_f32_e32 v68, v68
	v_rcp_f32_e32 v69, v69
	v_mul_f32_e32 v77, v79, v79
	v_mul_f32_e32 v77, 0xbf38aa3b, v77
	v_exp_f32_e32 v81, v77
	v_pk_fma_f32 v[82:83], v[68:69], s[12:13], v[24:25] op_sel_hi:[1,0,0]
	v_cmp_gt_f32_e32 vcc, 0, v79
	v_pk_fma_f32 v[82:83], v[68:69], v[82:83], s[14:15] op_sel_hi:[1,1,0]
	v_lshlrev_b32_e32 v77, 16, v75
	v_pk_fma_f32 v[82:83], v[68:69], v[82:83], s[16:17] op_sel_hi:[1,1,0]
	v_fma_f32 v75, |v76|, s92, 1.0
	v_pk_fma_f32 v[82:83], v[68:69], v[82:83], s[18:19] op_sel_hi:[1,1,0]
	v_pk_mul_f32 v[68:69], v[68:69], v[82:83]
	v_pk_mul_f32 v[68:69], v[80:81], v[68:69]
	v_pk_mul_f32 v[80:81], v[68:69], v[78:79]
	v_pk_fma_f32 v[68:69], v[68:69], v[78:79], v[78:79] neg_lo:[1,0,0] neg_hi:[1,0,0]
	s_nop 0
	v_cndmask_b32_e32 v69, v69, v81, vcc
	v_cmp_gt_f32_e32 vcc, 0, v78
	v_rcp_f32_e32 v78, v75
	v_fma_f32 v75, |v77|, s92, 1.0
	v_rcp_f32_e32 v79, v75
	v_mul_f32_e32 v75, v76, v76
	v_mul_f32_e32 v75, 0xbf38aa3b, v75
	v_cndmask_b32_e32 v68, v68, v80, vcc
	v_exp_f32_e32 v80, v75
	v_mul_f32_e32 v75, v77, v77
	v_pk_fma_f32 v[82:83], v[78:79], s[12:13], v[24:25] op_sel_hi:[1,0,0]
	v_mul_f32_e32 v75, 0xbf38aa3b, v75
	v_pk_fma_f32 v[82:83], v[78:79], v[82:83], s[14:15] op_sel_hi:[1,1,0]
	v_exp_f32_e32 v81, v75
	v_pk_fma_f32 v[82:83], v[78:79], v[82:83], s[16:17] op_sel_hi:[1,1,0]
	v_cmp_gt_f32_e32 vcc, 0, v77
	v_pk_fma_f32 v[82:83], v[78:79], v[82:83], s[18:19] op_sel_hi:[1,1,0]
	s_nop 0
	v_pk_mul_f32 v[78:79], v[78:79], v[82:83]
	v_pk_mul_f32 v[78:79], v[80:81], v[78:79]
	v_pk_mul_f32 v[80:81], v[78:79], v[76:77]
	v_pk_fma_f32 v[78:79], v[78:79], v[76:77], v[76:77] neg_lo:[1,0,0] neg_hi:[1,0,0]
	s_nop 0
	v_cndmask_b32_e32 v77, v79, v81, vcc
	v_cmp_gt_f32_e32 vcc, 0, v76
	v_lshlrev_b32_e32 v79, 16, v72
	v_mul_f32_e32 v75, v79, v79
	v_cndmask_b32_e32 v76, v78, v80, vcc
	v_lshlrev_b32_e32 v78, 16, v73
	v_mul_f32_e32 v73, v78, v78
	v_mul_f32_e32 v73, 0xbf38aa3b, v73
	v_fma_f32 v72, |v78|, s92, 1.0
	v_exp_f32_e32 v80, v73
	v_fma_f32 v73, |v79|, s92, 1.0
	v_rcp_f32_e32 v72, v72
	v_rcp_f32_e32 v73, v73
	v_mul_f32_e32 v75, 0xbf38aa3b, v75
	v_exp_f32_e32 v81, v75
	v_cmp_gt_f32_e32 vcc, 0, v79
	v_pk_fma_f32 v[82:83], v[72:73], s[12:13], v[24:25] op_sel_hi:[1,0,0]
	s_nop 0
	v_pk_fma_f32 v[82:83], v[72:73], v[82:83], s[14:15] op_sel_hi:[1,1,0]
	s_nop 0
	v_pk_fma_f32 v[82:83], v[72:73], v[82:83], s[16:17] op_sel_hi:[1,1,0]
	s_nop 0
	v_pk_fma_f32 v[82:83], v[72:73], v[82:83], s[18:19] op_sel_hi:[1,1,0]
	v_pk_mul_f32 v[72:73], v[72:73], v[82:83]
	v_pk_mul_f32 v[72:73], v[80:81], v[72:73]
	v_pk_mul_f32 v[80:81], v[72:73], v[78:79]
	v_pk_fma_f32 v[72:73], v[72:73], v[78:79], v[78:79] neg_lo:[1,0,0] neg_hi:[1,0,0]
	v_lshlrev_b32_e32 v79, 16, v70
	v_cndmask_b32_e32 v73, v73, v81, vcc
	v_cmp_gt_f32_e32 vcc, 0, v78
	s_waitcnt vmcnt(0)
	v_lshlrev_b32_e32 v78, 16, v71
	v_fma_f32 v70, |v78|, s92, 1.0
	v_fma_f32 v71, |v79|, s92, 1.0
	v_rcp_f32_e32 v70, v70
	v_rcp_f32_e32 v71, v71
	v_mul_f32_e32 v75, v78, v78
	v_mul_f32_e32 v75, 0xbf38aa3b, v75
	v_cndmask_b32_e32 v72, v72, v80, vcc
	v_exp_f32_e32 v80, v75
	v_mul_f32_e32 v75, v79, v79
	v_pk_fma_f32 v[82:83], v[70:71], s[12:13], v[24:25] op_sel_hi:[1,0,0]
	v_mul_f32_e32 v75, 0xbf38aa3b, v75
	v_pk_fma_f32 v[82:83], v[70:71], v[82:83], s[14:15] op_sel_hi:[1,1,0]
	v_exp_f32_e32 v81, v75
	v_pk_fma_f32 v[82:83], v[70:71], v[82:83], s[16:17] op_sel_hi:[1,1,0]
	v_cmp_gt_f32_e32 vcc, 0, v79
	v_pk_fma_f32 v[82:83], v[70:71], v[82:83], s[18:19] op_sel_hi:[1,1,0]
	s_nop 0
	v_pk_mul_f32 v[70:71], v[70:71], v[82:83]
	v_pk_mul_f32 v[70:71], v[80:81], v[70:71]
	v_pk_mul_f32 v[80:81], v[70:71], v[78:79]
	v_pk_fma_f32 v[70:71], v[70:71], v[78:79], v[78:79] neg_lo:[1,0,0] neg_hi:[1,0,0]
	v_lshlrev_b32_e32 v79, 16, v64
	v_cndmask_b32_e32 v71, v71, v81, vcc
	v_cmp_gt_f32_e32 vcc, 0, v78
	v_lshlrev_b32_e32 v78, 16, v65
	v_mul_f32_e32 v65, v78, v78
	v_mul_f32_e32 v65, 0xbf38aa3b, v65
	v_cndmask_b32_e32 v70, v70, v80, vcc
	v_fma_f32 v64, |v78|, s92, 1.0
	v_exp_f32_e32 v80, v65
	v_fma_f32 v65, |v79|, s92, 1.0
	v_rcp_f32_e32 v64, v64
	v_rcp_f32_e32 v65, v65
	v_mul_f32_e32 v75, v79, v79
	v_mul_f32_e32 v75, 0xbf38aa3b, v75
	v_exp_f32_e32 v81, v75
	v_pk_fma_f32 v[24:25], v[64:65], s[12:13], v[24:25] op_sel_hi:[1,0,0]
	v_cmp_gt_f32_e32 vcc, 0, v79
	v_pk_fma_f32 v[24:25], v[64:65], v[24:25], s[14:15] op_sel_hi:[1,1,0]
	v_mov_b32_e32 v75, v131
	v_pk_fma_f32 v[24:25], v[64:65], v[24:25], s[6:7] op_sel_hi:[1,1,0]
	s_mov_b64 s[12:13], s[68:69]
	v_pk_fma_f32 v[24:25], v[64:65], v[24:25], s[8:9] op_sel_hi:[1,1,0]
	s_mov_b64 s[68:69], s[10:11]
	v_pk_mul_f32 v[24:25], v[64:65], v[24:25]
	v_pk_mul_f32 v[24:25], v[80:81], v[24:25]
	v_mov_b32_e32 v80, v63
	v_pk_mul_f32 v[64:65], v[24:25], v[78:79]
	v_pk_fma_f32 v[24:25], v[24:25], v[78:79], v[78:79] neg_lo:[1,0,0] neg_hi:[1,0,0]
	v_mov_b32_e32 v81, v71
	v_cndmask_b32_e32 v79, v25, v65, vcc
	v_cmp_gt_f32_e32 vcc, 0, v78
	v_mov_b32_e32 v25, v76
	v_mov_b32_e32 v65, v70
	v_cndmask_b32_e32 v78, v24, v64, vcc
	v_mov_b32_e32 v24, v60
	v_mov_b32_e32 v64, v62
	v_pk_add_f32 v[24:25], v[24:25], v[64:65]
	v_mov_b32_e32 v64, v61
	v_add_f32_e32 v24, v24, v25
	v_mov_b32_e32 v25, v131
	v_mov_b32_e32 v65, v77
	v_add_f32_dpp v24, v24, v24 quad_perm:[1,0,3,2] row_mask:0xf bank_mask:0xf bound_ctrl:1
	v_pk_add_f32 v[64:65], v[64:65], v[80:81]
	v_mov_b32_e32 v80, v69
	v_add_f32_dpp v24, v24, v24 quad_perm:[2,3,0,1] row_mask:0xf bank_mask:0xf bound_ctrl:1
	v_mov_b32_e32 v81, v79
	s_nop 0
	v_add_f32_dpp v24, v24, v24 row_half_mirror row_mask:0xf bank_mask:0xf bound_ctrl:1
	s_nop 1
	v_add_f32_dpp v24, v24, v24 row_mirror row_mask:0xf bank_mask:0xf bound_ctrl:1
	s_nop 1
	v_mov_b32_dpp v25, v24 row_bcast:15 row_mask:0xa bank_mask:0xf
	v_add_f32_e32 v24, v24, v25
	v_mov_b32_e32 v25, v131
	s_nop 1
	v_mov_b32_dpp v25, v24 row_bcast:31 row_mask:0xc bank_mask:0xf
	v_add_f32_e32 v24, v24, v25
	v_add_f32_e32 v25, v64, v65
	v_mov_b32_e32 v64, v131
	v_readlane_b32 s6, v24, 63
	v_add_f32_dpp v25, v25, v25 quad_perm:[1,0,3,2] row_mask:0xf bank_mask:0xf bound_ctrl:1
	s_xor_b32 s6, s6, 0x80000000
	s_nop 0
	v_add_f32_dpp v25, v25, v25 quad_perm:[2,3,0,1] row_mask:0xf bank_mask:0xf bound_ctrl:1
	s_nop 1
	v_add_f32_dpp v25, v25, v25 row_half_mirror row_mask:0xf bank_mask:0xf bound_ctrl:1
	s_nop 1
	v_add_f32_dpp v25, v25, v25 row_mirror row_mask:0xf bank_mask:0xf bound_ctrl:1
	s_nop 1
	v_mov_b32_dpp v64, v25 row_bcast:15 row_mask:0xa bank_mask:0xf
	v_add_f32_e32 v25, v25, v64
	v_mov_b32_e32 v64, v131
	s_nop 1
	v_mov_b32_dpp v64, v25 row_bcast:31 row_mask:0xc bank_mask:0xf
	v_add_f32_e32 v25, v25, v64
	s_nop 0
	v_readlane_b32 s7, v25, 63
	s_xor_b32 s7, s7, 0x80000000
	s_nop 0
	v_pk_fma_f32 v[64:65], s[6:7], v[26:27], v[60:61] op_sel_hi:[1,0,1]
	v_pk_fma_f32 v[60:61], s[6:7], v[26:27], v[76:77] op_sel_hi:[1,0,1]
	v_pk_fma_f32 v[24:25], s[6:7], v[26:27], v[70:71] op_sel_hi:[1,0,1]
	v_mov_b32_e32 v70, v66
	v_mov_b32_e32 v71, v72
	v_mov_b32_e32 v76, v68
	v_mov_b32_e32 v77, v78
	v_pk_add_f32 v[70:71], v[70:71], v[76:77]
	v_mov_b32_e32 v76, v67
	v_add_f32_e32 v70, v70, v71
	v_mov_b32_e32 v71, v131
	v_mov_b32_e32 v77, v73
	v_add_f32_dpp v70, v70, v70 quad_perm:[1,0,3,2] row_mask:0xf bank_mask:0xf bound_ctrl:1
	v_pk_add_f32 v[76:77], v[76:77], v[80:81]
	v_pk_fma_f32 v[62:63], s[6:7], v[26:27], v[62:63] op_sel_hi:[1,0,1]
	v_add_f32_dpp v70, v70, v70 quad_perm:[2,3,0,1] row_mask:0xf bank_mask:0xf bound_ctrl:1
	s_nop 1
	v_add_f32_dpp v70, v70, v70 row_half_mirror row_mask:0xf bank_mask:0xf bound_ctrl:1
	s_nop 1
	v_add_f32_dpp v70, v70, v70 row_mirror row_mask:0xf bank_mask:0xf bound_ctrl:1
	s_nop 1
	v_mov_b32_dpp v71, v70 row_bcast:15 row_mask:0xa bank_mask:0xf
	v_add_f32_e32 v70, v70, v71
	v_mov_b32_e32 v71, v131
	s_nop 1
	v_mov_b32_dpp v71, v70 row_bcast:31 row_mask:0xc bank_mask:0xf
	v_add_f32_e32 v70, v70, v71
	v_add_f32_e32 v71, v76, v77
	v_readlane_b32 s6, v70, 63
	s_xor_b32 s6, s6, 0x80000000
	v_add_f32_dpp v71, v71, v71 quad_perm:[1,0,3,2] row_mask:0xf bank_mask:0xf bound_ctrl:1
	v_mov_b32_e32 v76, v20
	v_mov_b32_e32 v77, v16
	v_add_f32_dpp v71, v71, v71 quad_perm:[2,3,0,1] row_mask:0xf bank_mask:0xf bound_ctrl:1
	v_pk_mul_f32 v[76:77], v[76:77], v[76:77]
	s_nop 0
	v_add_f32_dpp v71, v71, v71 row_half_mirror row_mask:0xf bank_mask:0xf bound_ctrl:1
	s_nop 1
	v_add_f32_dpp v71, v71, v71 row_mirror row_mask:0xf bank_mask:0xf bound_ctrl:1
	s_nop 1
	v_mov_b32_dpp v75, v71 row_bcast:15 row_mask:0xa bank_mask:0xf
	v_add_f32_e32 v71, v71, v75
	v_mov_b32_e32 v75, v131
	s_nop 1
	v_mov_b32_dpp v75, v71 row_bcast:31 row_mask:0xc bank_mask:0xf
	v_add_f32_e32 v71, v71, v75
	s_nop 0
	v_readlane_b32 s7, v71, 63
	s_xor_b32 s7, s7, 0x80000000
	s_nop 0
	v_pk_fma_f32 v[70:71], s[6:7], v[26:27], v[66:67] op_sel_hi:[1,0,1]
	v_pk_fma_f32 v[66:67], s[6:7], v[26:27], v[72:73] op_sel_hi:[1,0,1]
	v_mov_b32_e32 v72, v22
	v_mov_b32_e32 v73, v18
	v_pk_fma_f32 v[72:73], v[72:73], v[72:73], v[76:77]
	v_pk_fma_f32 v[68:69], s[6:7], v[26:27], v[68:69] op_sel_hi:[1,0,1]
	v_add_f32_e32 v72, v72, v73
	v_mov_b32_e32 v73, v131
	v_pk_fma_f32 v[26:27], s[6:7], v[26:27], v[78:79] op_sel_hi:[1,0,1]
	v_add_f32_dpp v72, v72, v72 quad_perm:[1,0,3,2] row_mask:0xf bank_mask:0xf bound_ctrl:1
	s_lshl_b32 s6, s65, 5
	s_add_i32 s7, s5, s73
	v_add_f32_dpp v72, v72, v72 quad_perm:[2,3,0,1] row_mask:0xf bank_mask:0xf bound_ctrl:1
	s_mul_hi_i32 s8, s7, 0x5000
	s_mulk_i32 s7, 0x5000
	v_add_f32_dpp v72, v72, v72 row_half_mirror row_mask:0xf bank_mask:0xf bound_ctrl:1
	s_lshl_b32 s5, s5, 9
	s_add_i32 s9, s6, 0
	v_add_f32_dpp v72, v72, v72 row_mirror row_mask:0xf bank_mask:0xf bound_ctrl:1
	v_mov_b32_e32 v76, v21
	v_mov_b32_e32 v77, v17
	v_mov_b32_dpp v73, v72 row_bcast:15 row_mask:0xa bank_mask:0xf
	v_add_f32_e32 v72, v72, v73
	v_mov_b32_e32 v73, v131
	s_add_u32 s28, s34, s7
	v_pk_mul_f32 v[76:77], v[76:77], v[76:77]
	v_mov_b32_dpp v73, v72 row_bcast:31 row_mask:0xc bank_mask:0xf
	v_add_f32_e32 v72, v72, v73
	v_mov_b32_e32 v73, v19
	v_readlane_b32 s7, v72, 63
	v_mov_b32_e32 v72, v23
	v_pk_fma_f32 v[72:73], v[72:73], v[72:73], v[76:77]
	v_mov_b32_e32 v76, v14
	v_add_f32_e32 v72, v72, v73
	v_mov_b32_e32 v73, v131
	v_mov_b32_e32 v77, v8
	v_add_f32_dpp v72, v72, v72 quad_perm:[1,0,3,2] row_mask:0xf bank_mask:0xf bound_ctrl:1
	v_fma_f32 v79, s7, v235, v225
	v_pk_mul_f32 v[76:77], v[76:77], v[76:77]
	v_add_f32_dpp v72, v72, v72 quad_perm:[2,3,0,1] row_mask:0xf bank_mask:0xf bound_ctrl:1
	s_addc_u32 s29, s64, s8
	v_readlane_b32 s8, v253, 54
	v_add_f32_dpp v72, v72, v72 row_half_mirror row_mask:0xf bank_mask:0xf bound_ctrl:1
	v_mov_b32_e32 v75, s9
	s_add_i32 s5, s8, s5
	v_add_f32_dpp v72, v72, v72 row_mirror row_mask:0xf bank_mask:0xf bound_ctrl:1
	s_nop 1
	v_mov_b32_dpp v73, v72 row_bcast:15 row_mask:0xa bank_mask:0xf
	v_add_f32_e32 v72, v72, v73
	v_mov_b32_e32 v73, v131
	s_nop 1
	v_mov_b32_dpp v73, v72 row_bcast:31 row_mask:0xc bank_mask:0xf
	v_add_f32_e32 v72, v72, v73
	v_mov_b32_e32 v73, v12
	v_readlane_b32 s7, v72, 63
	v_mov_b32_e32 v72, v10
	v_pk_fma_f32 v[72:73], v[72:73], v[72:73], v[76:77]
	v_mov_b32_e32 v76, v15
	v_add_f32_e32 v72, v72, v73
	v_mov_b32_e32 v73, v131
	v_mov_b32_e32 v77, v9
	v_add_f32_dpp v72, v72, v72 quad_perm:[1,0,3,2] row_mask:0xf bank_mask:0xf bound_ctrl:1
	v_fma_f32 v81, s7, v235, v225
	v_pk_mul_f32 v[76:77], v[76:77], v[76:77]
	v_add_f32_dpp v72, v72, v72 quad_perm:[2,3,0,1] row_mask:0xf bank_mask:0xf bound_ctrl:1
	s_nop 1
	v_add_f32_dpp v72, v72, v72 row_half_mirror row_mask:0xf bank_mask:0xf bound_ctrl:1
	s_nop 1
	v_add_f32_dpp v72, v72, v72 row_mirror row_mask:0xf bank_mask:0xf bound_ctrl:1
	s_nop 1
	v_mov_b32_dpp v73, v72 row_bcast:15 row_mask:0xa bank_mask:0xf
	v_add_f32_e32 v72, v72, v73
	v_mov_b32_e32 v73, v131
	s_nop 1
	v_mov_b32_dpp v73, v72 row_bcast:31 row_mask:0xc bank_mask:0xf
	v_add_f32_e32 v72, v72, v73
	v_mov_b32_e32 v73, v13
	v_readlane_b32 s7, v72, 63
	v_mov_b32_e32 v72, v11
	v_pk_fma_f32 v[72:73], v[72:73], v[72:73], v[76:77]
	v_mov_b32_e32 v76, v40
	v_add_f32_e32 v72, v72, v73
	v_mov_b32_e32 v73, v131
	v_mov_b32_e32 v77, v36
	v_add_f32_dpp v72, v72, v72 quad_perm:[1,0,3,2] row_mask:0xf bank_mask:0xf bound_ctrl:1
	v_fma_f32 v83, s7, v235, v225
	v_pk_mul_f32 v[76:77], v[76:77], v[76:77]
	v_add_f32_dpp v72, v72, v72 quad_perm:[2,3,0,1] row_mask:0xf bank_mask:0xf bound_ctrl:1
	s_nop 1
	v_add_f32_dpp v72, v72, v72 row_half_mirror row_mask:0xf bank_mask:0xf bound_ctrl:1
	s_nop 1
	v_add_f32_dpp v72, v72, v72 row_mirror row_mask:0xf bank_mask:0xf bound_ctrl:1
	s_nop 1
	v_mov_b32_dpp v73, v72 row_bcast:15 row_mask:0xa bank_mask:0xf
	v_add_f32_e32 v72, v72, v73
	v_mov_b32_e32 v73, v131
	s_nop 1
	v_mov_b32_dpp v73, v72 row_bcast:31 row_mask:0xc bank_mask:0xf
	v_add_f32_e32 v72, v72, v73
	v_mov_b32_e32 v73, v38
	v_readlane_b32 s7, v72, 63
	v_mov_b32_e32 v72, v42
	v_pk_fma_f32 v[72:73], v[72:73], v[72:73], v[76:77]
	v_mov_b32_e32 v76, v41
	v_add_f32_e32 v72, v72, v73
	v_mov_b32_e32 v73, v131
	v_mov_b32_e32 v77, v37
	v_add_f32_dpp v72, v72, v72 quad_perm:[1,0,3,2] row_mask:0xf bank_mask:0xf bound_ctrl:1
	v_fma_f32 v85, s7, v235, v225
	v_pk_mul_f32 v[76:77], v[76:77], v[76:77]
	v_add_f32_dpp v72, v72, v72 quad_perm:[2,3,0,1] row_mask:0xf bank_mask:0xf bound_ctrl:1
	s_nop 1
	v_add_f32_dpp v72, v72, v72 row_half_mirror row_mask:0xf bank_mask:0xf bound_ctrl:1
	s_nop 1
	v_add_f32_dpp v72, v72, v72 row_mirror row_mask:0xf bank_mask:0xf bound_ctrl:1
	s_nop 1
	v_mov_b32_dpp v73, v72 row_bcast:15 row_mask:0xa bank_mask:0xf
	v_add_f32_e32 v72, v72, v73
	v_mov_b32_e32 v73, v131
	s_nop 1
	v_mov_b32_dpp v73, v72 row_bcast:31 row_mask:0xc bank_mask:0xf
	v_add_f32_e32 v72, v72, v73
	v_mov_b32_e32 v73, v39
	v_readlane_b32 s7, v72, 63
	v_mov_b32_e32 v72, v43
	v_pk_fma_f32 v[72:73], v[72:73], v[72:73], v[76:77]
	v_mov_b32_e32 v76, v32
	v_add_f32_e32 v72, v72, v73
	v_mov_b32_e32 v73, v131
	v_mov_b32_e32 v77, v28
	v_add_f32_dpp v72, v72, v72 quad_perm:[1,0,3,2] row_mask:0xf bank_mask:0xf bound_ctrl:1
	v_fma_f32 v87, s7, v235, v225
	v_pk_mul_f32 v[76:77], v[76:77], v[76:77]
	v_add_f32_dpp v72, v72, v72 quad_perm:[2,3,0,1] row_mask:0xf bank_mask:0xf bound_ctrl:1
	s_nop 1
	v_add_f32_dpp v72, v72, v72 row_half_mirror row_mask:0xf bank_mask:0xf bound_ctrl:1
	s_nop 1
	v_add_f32_dpp v72, v72, v72 row_mirror row_mask:0xf bank_mask:0xf bound_ctrl:1
	s_nop 1
	v_mov_b32_dpp v73, v72 row_bcast:15 row_mask:0xa bank_mask:0xf
	v_add_f32_e32 v72, v72, v73
	v_mov_b32_e32 v73, v131
	s_nop 1
	v_mov_b32_dpp v73, v72 row_bcast:31 row_mask:0xc bank_mask:0xf
	v_add_f32_e32 v72, v72, v73
	v_mov_b32_e32 v73, v30
	v_readlane_b32 s7, v72, 63
	v_mov_b32_e32 v72, v34
	v_pk_fma_f32 v[72:73], v[72:73], v[72:73], v[76:77]
	v_mov_b32_e32 v76, v33
	v_add_f32_e32 v72, v72, v73
	v_mov_b32_e32 v73, v131
	v_mov_b32_e32 v77, v29
	v_add_f32_dpp v72, v72, v72 quad_perm:[1,0,3,2] row_mask:0xf bank_mask:0xf bound_ctrl:1
	v_fma_f32 v88, s7, v235, v225
	v_pk_mul_f32 v[76:77], v[76:77], v[76:77]
	v_add_f32_dpp v72, v72, v72 quad_perm:[2,3,0,1] row_mask:0xf bank_mask:0xf bound_ctrl:1
	s_nop 1
	v_add_f32_dpp v72, v72, v72 row_half_mirror row_mask:0xf bank_mask:0xf bound_ctrl:1
	s_nop 1
	v_add_f32_dpp v72, v72, v72 row_mirror row_mask:0xf bank_mask:0xf bound_ctrl:1
	s_nop 1
	v_mov_b32_dpp v73, v72 row_bcast:15 row_mask:0xa bank_mask:0xf
	v_add_f32_e32 v72, v72, v73
	v_mov_b32_e32 v73, v131
	s_nop 1
	v_mov_b32_dpp v73, v72 row_bcast:31 row_mask:0xc bank_mask:0xf
	v_add_f32_e32 v72, v72, v73
	v_mov_b32_e32 v73, v31
	v_readlane_b32 s7, v72, 63
	v_mov_b32_e32 v72, v35
	v_pk_fma_f32 v[72:73], v[72:73], v[72:73], v[76:77]
	v_mov_b32_e32 v76, v56
	v_add_f32_e32 v72, v72, v73
	v_mov_b32_e32 v73, v131
	v_mov_b32_e32 v77, v52
	v_add_f32_dpp v72, v72, v72 quad_perm:[1,0,3,2] row_mask:0xf bank_mask:0xf bound_ctrl:1
	v_fma_f32 v89, s7, v235, v225
	v_pk_mul_f32 v[76:77], v[76:77], v[76:77]
	v_add_f32_dpp v72, v72, v72 quad_perm:[2,3,0,1] row_mask:0xf bank_mask:0xf bound_ctrl:1
	s_nop 1
	v_add_f32_dpp v72, v72, v72 row_half_mirror row_mask:0xf bank_mask:0xf bound_ctrl:1
	s_nop 1
	v_add_f32_dpp v72, v72, v72 row_mirror row_mask:0xf bank_mask:0xf bound_ctrl:1
	s_nop 1
	v_mov_b32_dpp v73, v72 row_bcast:15 row_mask:0xa bank_mask:0xf
	v_add_f32_e32 v72, v72, v73
	v_mov_b32_e32 v73, v131
	s_nop 1
	v_mov_b32_dpp v73, v72 row_bcast:31 row_mask:0xc bank_mask:0xf
	v_add_f32_e32 v72, v72, v73
	v_mov_b32_e32 v73, v54
	v_readlane_b32 s7, v72, 63
	v_mov_b32_e32 v72, v58
	v_pk_fma_f32 v[72:73], v[72:73], v[72:73], v[76:77]
	v_mov_b32_e32 v76, v57
	v_add_f32_e32 v72, v72, v73
	v_mov_b32_e32 v73, v131
	v_mov_b32_e32 v77, v53
	v_add_f32_dpp v72, v72, v72 quad_perm:[1,0,3,2] row_mask:0xf bank_mask:0xf bound_ctrl:1
	v_fma_f32 v90, s7, v235, v225
	v_pk_mul_f32 v[76:77], v[76:77], v[76:77]
	v_add_f32_dpp v72, v72, v72 quad_perm:[2,3,0,1] row_mask:0xf bank_mask:0xf bound_ctrl:1
	s_nop 1
	v_add_f32_dpp v72, v72, v72 row_half_mirror row_mask:0xf bank_mask:0xf bound_ctrl:1
	s_nop 1
	v_add_f32_dpp v72, v72, v72 row_mirror row_mask:0xf bank_mask:0xf bound_ctrl:1
	s_nop 1
	v_mov_b32_dpp v73, v72 row_bcast:15 row_mask:0xa bank_mask:0xf
	v_add_f32_e32 v72, v72, v73
	v_mov_b32_e32 v73, v131
	s_nop 1
	v_mov_b32_dpp v73, v72 row_bcast:31 row_mask:0xc bank_mask:0xf
	v_add_f32_e32 v72, v72, v73
	v_mov_b32_e32 v73, v55
	v_readlane_b32 s7, v72, 63
	v_mov_b32_e32 v72, v59
	v_pk_fma_f32 v[72:73], v[72:73], v[72:73], v[76:77]
	v_mov_b32_e32 v76, v50
	v_add_f32_e32 v72, v72, v73
	v_mov_b32_e32 v73, v131
	v_mov_b32_e32 v77, v44
	v_add_f32_dpp v72, v72, v72 quad_perm:[1,0,3,2] row_mask:0xf bank_mask:0xf bound_ctrl:1
	v_fma_f32 v92, s7, v235, v225
	v_pk_mul_f32 v[76:77], v[76:77], v[76:77]
	v_add_f32_dpp v72, v72, v72 quad_perm:[2,3,0,1] row_mask:0xf bank_mask:0xf bound_ctrl:1
	s_nop 1
	v_add_f32_dpp v72, v72, v72 row_half_mirror row_mask:0xf bank_mask:0xf bound_ctrl:1
	s_nop 1
	v_add_f32_dpp v72, v72, v72 row_mirror row_mask:0xf bank_mask:0xf bound_ctrl:1
	s_nop 1
	v_mov_b32_dpp v73, v72 row_bcast:15 row_mask:0xa bank_mask:0xf
	v_add_f32_e32 v72, v72, v73
	v_mov_b32_e32 v73, v131
	s_nop 1
	v_mov_b32_dpp v73, v72 row_bcast:31 row_mask:0xc bank_mask:0xf
	v_add_f32_e32 v72, v72, v73
	v_mov_b32_e32 v73, v48
	v_readlane_b32 s7, v72, 63
	v_mov_b32_e32 v72, v46
	v_pk_fma_f32 v[72:73], v[72:73], v[72:73], v[76:77]
	v_mov_b32_e32 v76, v51
	v_add_f32_e32 v72, v72, v73
	v_mov_b32_e32 v73, v131
	v_mov_b32_e32 v77, v45
	v_add_f32_dpp v72, v72, v72 quad_perm:[1,0,3,2] row_mask:0xf bank_mask:0xf bound_ctrl:1
	v_fma_f32 v93, s7, v235, v225
	v_pk_mul_f32 v[76:77], v[76:77], v[76:77]
	v_add_f32_dpp v72, v72, v72 quad_perm:[2,3,0,1] row_mask:0xf bank_mask:0xf bound_ctrl:1
	s_nop 1
	v_add_f32_dpp v72, v72, v72 row_half_mirror row_mask:0xf bank_mask:0xf bound_ctrl:1
	s_nop 1
	v_add_f32_dpp v72, v72, v72 row_mirror row_mask:0xf bank_mask:0xf bound_ctrl:1
	s_nop 1
	v_mov_b32_dpp v73, v72 row_bcast:15 row_mask:0xa bank_mask:0xf
	v_add_f32_e32 v72, v72, v73
	v_mov_b32_e32 v73, v131
	s_nop 1
	v_mov_b32_dpp v73, v72 row_bcast:31 row_mask:0xc bank_mask:0xf
	v_add_f32_e32 v72, v72, v73
	v_mov_b32_e32 v73, v49
	v_readlane_b32 s7, v72, 63
	v_mov_b32_e32 v72, v47
	v_pk_fma_f32 v[72:73], v[72:73], v[72:73], v[76:77]
	v_mov_b32_e32 v76, v68
	v_add_f32_e32 v72, v72, v73
	v_mov_b32_e32 v73, v131
	v_mov_b32_e32 v77, v26
	v_add_f32_dpp v72, v72, v72 quad_perm:[1,0,3,2] row_mask:0xf bank_mask:0xf bound_ctrl:1
	v_fma_f32 v94, s7, v235, v225
	v_pk_mul_f32 v[76:77], v[76:77], v[76:77]
	v_add_f32_dpp v72, v72, v72 quad_perm:[2,3,0,1] row_mask:0xf bank_mask:0xf bound_ctrl:1
	s_nop 1
	v_add_f32_dpp v72, v72, v72 row_half_mirror row_mask:0xf bank_mask:0xf bound_ctrl:1
	s_nop 1
	v_add_f32_dpp v72, v72, v72 row_mirror row_mask:0xf bank_mask:0xf bound_ctrl:1
	s_nop 1
	v_mov_b32_dpp v73, v72 row_bcast:15 row_mask:0xa bank_mask:0xf
	v_add_f32_e32 v72, v72, v73
	v_mov_b32_e32 v73, v131
	s_nop 1
	v_mov_b32_dpp v73, v72 row_bcast:31 row_mask:0xc bank_mask:0xf
	v_add_f32_e32 v72, v72, v73
	v_mov_b32_e32 v73, v66
	v_readlane_b32 s7, v72, 63
	v_mov_b32_e32 v72, v70
	v_pk_fma_f32 v[72:73], v[72:73], v[72:73], v[76:77]
	v_mov_b32_e32 v76, v69
	v_add_f32_e32 v72, v72, v73
	v_mov_b32_e32 v73, v131
	v_mov_b32_e32 v77, v27
	v_add_f32_dpp v72, v72, v72 quad_perm:[1,0,3,2] row_mask:0xf bank_mask:0xf bound_ctrl:1
	v_fma_f32 v95, s7, v235, v225
	v_pk_mul_f32 v[76:77], v[76:77], v[76:77]
	v_add_f32_dpp v72, v72, v72 quad_perm:[2,3,0,1] row_mask:0xf bank_mask:0xf bound_ctrl:1
	s_nop 1
	v_add_f32_dpp v72, v72, v72 row_half_mirror row_mask:0xf bank_mask:0xf bound_ctrl:1
	s_nop 1
	v_add_f32_dpp v72, v72, v72 row_mirror row_mask:0xf bank_mask:0xf bound_ctrl:1
	s_nop 1
	v_mov_b32_dpp v73, v72 row_bcast:15 row_mask:0xa bank_mask:0xf
	v_add_f32_e32 v72, v72, v73
	v_mov_b32_e32 v73, v131
	s_nop 1
	v_mov_b32_dpp v73, v72 row_bcast:31 row_mask:0xc bank_mask:0xf
	v_add_f32_e32 v72, v72, v73
	v_mov_b32_e32 v73, v67
	v_readlane_b32 s7, v72, 63
	v_mov_b32_e32 v72, v71
	v_pk_fma_f32 v[72:73], v[72:73], v[72:73], v[76:77]
	v_mov_b32_e32 v76, v62
	v_add_f32_e32 v72, v72, v73
	v_mov_b32_e32 v73, v131
	v_mov_b32_e32 v77, v24
	v_add_f32_dpp v72, v72, v72 quad_perm:[1,0,3,2] row_mask:0xf bank_mask:0xf bound_ctrl:1
	v_fma_f32 v96, s7, v235, v225
	v_pk_mul_f32 v[76:77], v[76:77], v[76:77]
	v_add_f32_dpp v72, v72, v72 quad_perm:[2,3,0,1] row_mask:0xf bank_mask:0xf bound_ctrl:1
	s_nop 1
	v_add_f32_dpp v72, v72, v72 row_half_mirror row_mask:0xf bank_mask:0xf bound_ctrl:1
	s_nop 1
	v_add_f32_dpp v72, v72, v72 row_mirror row_mask:0xf bank_mask:0xf bound_ctrl:1
	s_nop 1
	v_mov_b32_dpp v73, v72 row_bcast:15 row_mask:0xa bank_mask:0xf
	v_add_f32_e32 v72, v72, v73
	v_mov_b32_e32 v73, v131
	s_nop 1
	v_mov_b32_dpp v73, v72 row_bcast:31 row_mask:0xc bank_mask:0xf
	v_add_f32_e32 v72, v72, v73
	v_mov_b32_e32 v73, v60
	v_readlane_b32 s7, v72, 63
	v_mov_b32_e32 v72, v64
	v_pk_fma_f32 v[72:73], v[72:73], v[72:73], v[76:77]
	v_mov_b32_e32 v76, v63
	v_add_f32_e32 v72, v72, v73
	v_mov_b32_e32 v73, v131
	v_mov_b32_e32 v77, v25
	v_add_f32_dpp v72, v72, v72 quad_perm:[1,0,3,2] row_mask:0xf bank_mask:0xf bound_ctrl:1
	v_fma_f32 v97, s7, v235, v225
	v_pk_mul_f32 v[76:77], v[76:77], v[76:77]
	v_add_f32_dpp v72, v72, v72 quad_perm:[2,3,0,1] row_mask:0xf bank_mask:0xf bound_ctrl:1
	s_nop 1
	v_add_f32_dpp v72, v72, v72 row_half_mirror row_mask:0xf bank_mask:0xf bound_ctrl:1
	s_nop 1
	v_add_f32_dpp v72, v72, v72 row_mirror row_mask:0xf bank_mask:0xf bound_ctrl:1
	s_nop 1
	v_mov_b32_dpp v73, v72 row_bcast:15 row_mask:0xa bank_mask:0xf
	v_add_f32_e32 v72, v72, v73
	v_mov_b32_e32 v73, v131
	s_nop 1
	v_mov_b32_dpp v73, v72 row_bcast:31 row_mask:0xc bank_mask:0xf
	v_add_f32_e32 v72, v72, v73
	v_mov_b32_e32 v73, v61
	v_readlane_b32 s7, v72, 63
	v_mov_b32_e32 v72, v65
	v_pk_fma_f32 v[72:73], v[72:73], v[72:73], v[76:77]
	v_fma_f32 v98, s7, v235, v225
	v_add_f32_e32 v72, v72, v73
	v_mov_b32_e32 v73, v131
	v_lshl_add_u32 v77, v1, 2, s8
	v_add_f32_dpp v72, v72, v72 quad_perm:[1,0,3,2] row_mask:0xf bank_mask:0xf bound_ctrl:1
	s_nop 1
	v_add_f32_dpp v72, v72, v72 quad_perm:[2,3,0,1] row_mask:0xf bank_mask:0xf bound_ctrl:1
	s_nop 1
	v_add_f32_dpp v72, v72, v72 row_half_mirror row_mask:0xf bank_mask:0xf bound_ctrl:1
	s_nop 1
	v_add_f32_dpp v72, v72, v72 row_mirror row_mask:0xf bank_mask:0xf bound_ctrl:1
	s_nop 1
	v_mov_b32_dpp v73, v72 row_bcast:15 row_mask:0xa bank_mask:0xf
	v_add_f32_e32 v72, v72, v73
	v_mov_b32_e32 v73, v131
	s_nop 1
	v_mov_b32_dpp v73, v72 row_bcast:31 row_mask:0xc bank_mask:0xf
	v_add_f32_e32 v72, v72, v73
	s_nop 0
	v_readlane_b32 s7, v72, 63
	global_load_dword v7, v[6:7], off
	s_nop 0
	global_load_dword v6, v[4:5], off
	global_load_dword v72, v[2:3], off
	global_load_dword v76, v[2:3], off offset:256
	global_load_dword v78, v[4:5], off offset:256
	global_load_dword v80, v[4:5], off offset:512
	global_load_dword v82, v[2:3], off offset:512
	global_load_dword v84, v[2:3], off offset:768
	global_load_dword v86, v[4:5], off offset:768
	v_rsq_f32_e32 v2, v79
	v_rsq_f32_e32 v3, v81
	v_rsq_f32_e32 v4, v83
	v_rsq_f32_e32 v5, v85
	v_fma_f32 v73, s7, v235, v225
	v_pk_mul_f32 v[22:23], v[22:23], v[2:3]
	v_pk_mul_f32 v[20:21], v[20:21], v[2:3]
	v_pk_mul_f32 v[10:11], v[10:11], v[4:5]
	v_pk_mul_f32 v[14:15], v[14:15], v[4:5]
	v_pk_mul_f32 v[18:19], v[18:19], v[2:3]
	v_pk_mul_f32 v[12:13], v[12:13], v[4:5]
	v_pk_mul_f32 v[2:3], v[16:17], v[2:3]
	v_pk_mul_f32 v[4:5], v[8:9], v[4:5]
	v_rsq_f32_e32 v8, v87
	v_rsq_f32_e32 v9, v88
	v_rsq_f32_e32 v16, v89
	v_rsq_f32_e32 v17, v90
	s_waitcnt vmcnt(8)
	ds_write_b32 v77, v7
	v_mad_u32_u24 v7, v74, s40, v75
	s_waitcnt vmcnt(6)
	v_pk_fma_f32 v[10:11], v[72:73], v[10:11], v[6:7] op_sel_hi:[0,1,0]
	v_pk_fma_f32 v[22:23], v[72:73], v[22:23], v[6:7] op_sel_hi:[0,1,0]
	s_waitcnt vmcnt(4)
	v_pk_fma_f32 v[14:15], v[76:77], v[14:15], v[78:79] op_sel_hi:[0,1,0]
	v_pk_fma_f32 v[20:21], v[76:77], v[20:21], v[78:79] op_sel_hi:[0,1,0]
	s_waitcnt vmcnt(2)
	v_pk_fma_f32 v[12:13], v[82:83], v[12:13], v[80:81] op_sel_hi:[0,1,0]
	v_pk_fma_f32 v[18:19], v[82:83], v[18:19], v[80:81] op_sel_hi:[0,1,0]
	s_waitcnt vmcnt(0)
	v_pk_fma_f32 v[88:89], v[84:85], v[4:5], v[86:87] op_sel_hi:[0,1,0]
	v_pk_fma_f32 v[90:91], v[84:85], v[2:3], v[86:87] op_sel_hi:[0,1,0]
	v_pk_mul_f32 v[2:3], v[42:43], v[8:9]
	v_pk_mul_f32 v[4:5], v[34:35], v[16:17]
	v_pk_fma_f32 v[2:3], v[72:73], v[2:3], v[6:7] op_sel_hi:[0,1,0]
	v_pk_fma_f32 v[4:5], v[72:73], v[4:5], v[6:7] op_sel_hi:[0,1,0]
	v_cvt_pk_bf16_f32 v5, v4, v5
	v_cvt_pk_bf16_f32 v4, v2, v3
	v_cvt_pk_bf16_f32 v3, v10, v11
	v_cvt_pk_bf16_f32 v2, v22, v23
	ds_write_b128 v7, v[2:5]
	v_pk_mul_f32 v[2:3], v[40:41], v[8:9]
	v_pk_mul_f32 v[4:5], v[32:33], v[16:17]
	v_pk_fma_f32 v[2:3], v[76:77], v[2:3], v[78:79] op_sel_hi:[0,1,0]
	v_pk_fma_f32 v[4:5], v[76:77], v[4:5], v[78:79] op_sel_hi:[0,1,0]
	v_cvt_pk_bf16_f32 v5, v4, v5
	v_cvt_pk_bf16_f32 v4, v2, v3
	v_cvt_pk_bf16_f32 v3, v14, v15
	v_cvt_pk_bf16_f32 v2, v20, v21
	ds_write_b128 v7, v[2:5] offset:17408
	v_pk_mul_f32 v[2:3], v[38:39], v[8:9]
	v_pk_mul_f32 v[4:5], v[30:31], v[16:17]
	v_pk_fma_f32 v[2:3], v[82:83], v[2:3], v[80:81] op_sel_hi:[0,1,0]
	v_pk_fma_f32 v[4:5], v[82:83], v[4:5], v[80:81] op_sel_hi:[0,1,0]
	v_cvt_pk_bf16_f32 v5, v4, v5
	v_cvt_pk_bf16_f32 v4, v2, v3
	v_cvt_pk_bf16_f32 v3, v12, v13
	v_cvt_pk_bf16_f32 v2, v18, v19
	ds_write_b128 v7, v[2:5] offset:34816
	v_pk_mul_f32 v[2:3], v[36:37], v[8:9]
	v_rsq_f32_e32 v8, v92
	v_rsq_f32_e32 v9, v93
	v_rsq_f32_e32 v10, v94
	v_rsq_f32_e32 v11, v95
	v_pk_mul_f32 v[4:5], v[28:29], v[16:17]
	v_pk_fma_f32 v[2:3], v[84:85], v[2:3], v[86:87] op_sel_hi:[0,1,0]
	v_pk_fma_f32 v[4:5], v[84:85], v[4:5], v[86:87] op_sel_hi:[0,1,0]
	v_cvt_pk_bf16_f32 v5, v4, v5
	v_cvt_pk_bf16_f32 v4, v2, v3
	v_cvt_pk_bf16_f32 v3, v88, v89
	v_cvt_pk_bf16_f32 v2, v90, v91
	ds_write_b128 v7, v[2:5] offset:52224
	v_pk_mul_f32 v[2:3], v[58:59], v[8:9]
	v_pk_mul_f32 v[4:5], v[46:47], v[10:11]
	v_pk_fma_f32 v[14:15], v[72:73], v[2:3], v[6:7] op_sel_hi:[0,1,0]
	v_pk_fma_f32 v[12:13], v[72:73], v[4:5], v[6:7] op_sel_hi:[0,1,0]
	v_pk_mul_f32 v[2:3], v[56:57], v[8:9]
	v_pk_mul_f32 v[4:5], v[50:51], v[10:11]
	v_pk_fma_f32 v[18:19], v[76:77], v[2:3], v[78:79] op_sel_hi:[0,1,0]
	v_pk_fma_f32 v[16:17], v[76:77], v[4:5], v[78:79] op_sel_hi:[0,1,0]
	v_pk_mul_f32 v[2:3], v[54:55], v[8:9]
	v_pk_mul_f32 v[4:5], v[48:49], v[10:11]
	v_pk_fma_f32 v[22:23], v[82:83], v[2:3], v[80:81] op_sel_hi:[0,1,0]
	v_pk_fma_f32 v[20:21], v[82:83], v[4:5], v[80:81] op_sel_hi:[0,1,0]
	v_pk_mul_f32 v[2:3], v[52:53], v[8:9]
	v_pk_mul_f32 v[4:5], v[44:45], v[10:11]
	v_rsq_f32_e32 v8, v96
	v_rsq_f32_e32 v9, v97
	v_rsq_f32_e32 v10, v98
	v_rsq_f32_e32 v11, v73
	v_pk_fma_f32 v[28:29], v[84:85], v[4:5], v[86:87] op_sel_hi:[0,1,0]
	v_pk_fma_f32 v[30:31], v[84:85], v[2:3], v[86:87] op_sel_hi:[0,1,0]
	v_pk_mul_f32 v[2:3], v[70:71], v[8:9]
	v_pk_mul_f32 v[4:5], v[64:65], v[10:11]
	v_pk_fma_f32 v[2:3], v[72:73], v[2:3], v[6:7] op_sel_hi:[0,1,0]
	v_pk_fma_f32 v[4:5], v[72:73], v[4:5], v[6:7] op_sel_hi:[0,1,0]
	v_cvt_pk_bf16_f32 v5, v4, v5
	v_cvt_pk_bf16_f32 v4, v2, v3
	v_cvt_pk_bf16_f32 v3, v12, v13
	v_cvt_pk_bf16_f32 v2, v14, v15
	ds_write_b128 v7, v[2:5] offset:16
	v_pk_mul_f32 v[2:3], v[68:69], v[8:9]
	v_pk_mul_f32 v[4:5], v[62:63], v[10:11]
	v_pk_fma_f32 v[2:3], v[76:77], v[2:3], v[78:79] op_sel_hi:[0,1,0]
	v_pk_fma_f32 v[4:5], v[76:77], v[4:5], v[78:79] op_sel_hi:[0,1,0]
	v_cvt_pk_bf16_f32 v5, v4, v5
	v_cvt_pk_bf16_f32 v4, v2, v3
	v_cvt_pk_bf16_f32 v3, v16, v17
	v_cvt_pk_bf16_f32 v2, v18, v19
	ds_write_b128 v7, v[2:5] offset:17424
	v_pk_mul_f32 v[2:3], v[66:67], v[8:9]
	v_pk_mul_f32 v[4:5], v[60:61], v[10:11]
	v_pk_fma_f32 v[2:3], v[82:83], v[2:3], v[80:81] op_sel_hi:[0,1,0]
	v_pk_fma_f32 v[4:5], v[82:83], v[4:5], v[80:81] op_sel_hi:[0,1,0]
	v_cvt_pk_bf16_f32 v5, v4, v5
	v_cvt_pk_bf16_f32 v4, v2, v3
	v_cvt_pk_bf16_f32 v3, v20, v21
	v_cvt_pk_bf16_f32 v2, v22, v23
	ds_write_b128 v7, v[2:5] offset:34832
	v_pk_mul_f32 v[2:3], v[26:27], v[8:9]
	v_pk_mul_f32 v[4:5], v[24:25], v[10:11]
	v_pk_fma_f32 v[2:3], v[84:85], v[2:3], v[86:87] op_sel_hi:[0,1,0]
	v_pk_fma_f32 v[4:5], v[84:85], v[4:5], v[86:87] op_sel_hi:[0,1,0]
	v_cvt_pk_bf16_f32 v5, v4, v5
	v_cvt_pk_bf16_f32 v4, v2, v3
	v_cvt_pk_bf16_f32 v3, v28, v29
	v_cvt_pk_bf16_f32 v2, v30, v31
	v_lshl_add_u64 v[8:9], s[28:29], 0, v[130:131]
	v_and_or_b32 v6, v1, 31, s6
	v_bfe_u32 v73, v1, 5, 1
	ds_write_b128 v7, v[2:5] offset:52240
	v_add_co_u32_e32 v70, vcc, s90, v8
	v_lshlrev_b32_e32 v1, 2, v73
	v_ashrrev_i32_e32 v7, 31, v6
	v_addc_co_u32_e32 v71, vcc, 0, v9, vcc
	v_or_b32_e32 v72, s66, v1
	v_lshlrev_b64 v[74:75], 1, v[6:7]
	v_add_co_u32_e32 v82, vcc, s46, v8
	v_lshl_add_u64 v[26:27], s[80:81], 0, v[74:75]
	v_mul_lo_u32 v10, v72, s87
	v_mov_b32_e32 v11, v131
	v_addc_co_u32_e32 v83, vcc, 0, v9, vcc
	v_lshl_add_u64 v[10:11], v[26:27], 0, v[10:11]
	v_add_co_u32_e32 v94, vcc, s90, v10
	s_mov_b32 s6, 0xc000
	s_nop 0
	v_addc_co_u32_e32 v95, vcc, 0, v11, vcc
	v_add_co_u32_e32 v28, vcc, s41, v10
	v_or_b32_e32 v7, s33, v1
	s_nop 0
	v_addc_co_u32_e32 v29, vcc, 0, v11, vcc
	v_add_co_u32_e32 v76, vcc, s97, v10
	s_waitcnt lgkmcnt(0)
	s_nop 0
	v_addc_co_u32_e32 v77, vcc, 0, v11, vcc
	v_add_co_u32_e32 v78, vcc, s6, v10
	s_mov_b32 s6, 0xd000
	s_nop 0
	v_addc_co_u32_e32 v79, vcc, 0, v11, vcc
	v_add_co_u32_e32 v80, vcc, s6, v10
	s_mov_b32 s6, 0xf000
	s_nop 0
	v_addc_co_u32_e32 v81, vcc, 0, v11, vcc
	v_add_co_u32_e32 v84, vcc, s6, v10
	s_mov_b32 s6, 0x10000
	s_nop 0
	v_addc_co_u32_e32 v85, vcc, 0, v11, vcc
	v_add_co_u32_e32 v86, vcc, s6, v10
	s_mov_b32 s6, 0x18000
	s_nop 0
	v_addc_co_u32_e32 v87, vcc, 0, v11, vcc
	v_add_co_u32_e32 v88, vcc, s6, v10
	s_mov_b32 s6, 0x19000
	s_nop 0
	v_addc_co_u32_e32 v89, vcc, 0, v11, vcc
	v_add_co_u32_e32 v90, vcc, s6, v10
	s_mov_b32 s6, 0x1b000
	s_nop 0
	v_addc_co_u32_e32 v91, vcc, 0, v11, vcc
	v_add_co_u32_e32 v92, vcc, s6, v10
	s_mov_b32 s6, 0x1c000
	s_nop 0
	v_addc_co_u32_e32 v93, vcc, 0, v11, vcc
	v_add_co_u32_e32 v54, vcc, s6, v10
	s_mov_b32 s6, 0x24000
	s_nop 0
	v_addc_co_u32_e32 v55, vcc, 0, v11, vcc
	v_add_co_u32_e32 v56, vcc, s6, v10
	s_mov_b32 s6, 0x25000
	s_nop 0
	v_addc_co_u32_e32 v57, vcc, 0, v11, vcc
	v_add_co_u32_e32 v58, vcc, s6, v10
	s_mov_b32 s6, 0x27000
	s_nop 0
	v_addc_co_u32_e32 v59, vcc, 0, v11, vcc
	v_add_co_u32_e32 v60, vcc, s6, v10
	s_mov_b32 s6, 0x28000
	s_nop 0
	v_addc_co_u32_e32 v61, vcc, 0, v11, vcc
	v_add_co_u32_e32 v62, vcc, s6, v10
	v_mul_lo_u32 v10, v7, s87
	s_nop 0
	v_addc_co_u32_e32 v63, vcc, 0, v11, vcc
	v_mov_b32_e32 v11, v131
	v_lshl_add_u64 v[10:11], v[26:27], 0, v[10:11]
	s_mov_b32 s6, 0x6030000
	v_add_co_u32_e32 v64, vcc, s6, v10
	s_mov_b32 s6, 0x6031000
	s_nop 0
	v_addc_co_u32_e32 v65, vcc, 0, v11, vcc
	v_add_co_u32_e32 v66, vcc, s6, v10
	s_mov_b32 s6, 0x6033000
	s_nop 0
	v_addc_co_u32_e32 v67, vcc, 0, v11, vcc
	v_add_co_u32_e32 v68, vcc, s6, v10
	s_mov_b32 s6, 0x6034000
	s_nop 0
	v_addc_co_u32_e32 v69, vcc, 0, v11, vcc
	v_add_co_u32_e32 v38, vcc, s6, v10
	s_mov_b32 s6, 0x603c000
	s_nop 0
	v_addc_co_u32_e32 v39, vcc, 0, v11, vcc
	v_add_co_u32_e32 v40, vcc, s6, v10
	s_mov_b32 s6, 0x603d000
	s_nop 0
	v_addc_co_u32_e32 v41, vcc, 0, v11, vcc
	v_add_co_u32_e32 v42, vcc, s6, v10
	s_mov_b32 s6, 0x603f000
	s_nop 0
	v_addc_co_u32_e32 v43, vcc, 0, v11, vcc
	v_add_co_u32_e32 v44, vcc, s6, v10
	s_mov_b32 s6, 0x6040000
	s_nop 0
	v_addc_co_u32_e32 v45, vcc, 0, v11, vcc
	v_add_co_u32_e32 v46, vcc, s6, v10
	s_mov_b32 s6, 0x6048000
	s_nop 0
	v_addc_co_u32_e32 v47, vcc, 0, v11, vcc
	v_add_co_u32_e32 v48, vcc, s6, v10
	s_mov_b32 s6, 0x6049000
	s_nop 0
	v_addc_co_u32_e32 v49, vcc, 0, v11, vcc
	v_add_co_u32_e32 v50, vcc, s6, v10
	s_mov_b32 s6, 0x604b000
	s_nop 0
	v_addc_co_u32_e32 v51, vcc, 0, v11, vcc
	v_add_co_u32_e32 v52, vcc, s6, v10
	s_mov_b32 s6, 0x604c000
	s_nop 0
	v_addc_co_u32_e32 v53, vcc, 0, v11, vcc
	v_add_co_u32_e32 v12, vcc, s6, v10
	s_mov_b32 s6, 0x6054000
	s_nop 0
	v_addc_co_u32_e32 v13, vcc, 0, v11, vcc
	v_add_co_u32_e32 v14, vcc, s6, v10
	s_mov_b32 s6, 0x6055000
	s_nop 0
	v_addc_co_u32_e32 v15, vcc, 0, v11, vcc
	v_add_co_u32_e32 v16, vcc, s6, v10
	s_mov_b32 s6, 0x6057000
	s_nop 0
	v_addc_co_u32_e32 v17, vcc, 0, v11, vcc
	v_add_co_u32_e32 v34, vcc, s6, v10
	s_mov_b32 s6, 0x6058000
	s_nop 0
	v_addc_co_u32_e32 v35, vcc, 0, v11, vcc
	v_add_co_u32_e32 v36, vcc, s6, v10
	v_mad_u64_u32 v[26:27], s[6:7], v72, s87, v[26:27]
	s_barrier
	global_load_dwordx4 v[2:5], v130, s[28:29]
	global_load_dwordx4 v[30:33], v130, s[28:29] offset:1024
	global_load_dwordx4 v[22:25], v130, s[28:29] offset:2048
	global_load_dwordx4 v[18:21], v130, s[28:29] offset:3072
	global_load_ushort v96, v[26:27], off
	global_load_ushort v7, v[28:29], off
	s_nop 0
	global_load_dwordx4 v[26:29], v[70:71], off offset:1024
	v_addc_co_u32_e32 v37, vcc, 0, v11, vcc
	global_load_ushort v94, v[94:95], off offset:2048
	s_mov_b32 s6, 0x6060000
	v_mul_lo_u32 v6, v6, s40
	s_waitcnt vmcnt(3)
	v_lshlrev_b32_e32 v96, 16, v96
	v_fma_f32 v97, |v96|, s92, 1.0
	v_rcp_f32_e32 v97, v97
	v_mul_f32_e32 v99, v96, v96
	v_mul_f32_e32 v99, 0xbf38aa3b, v99
	v_exp_f32_e32 v99, v99
	v_fmamk_f32 v98, v97, 0x3f07dc22, v236
	v_fmaak_f32 v98, v97, v98, 0x3f35f0e3
	v_fmaak_f32 v98, v97, v98, 0xbe11a98e
	s_waitcnt vmcnt(0)
	v_lshlrev_b32_e32 v94, 16, v94
	v_fmaak_f32 v98, v97, v98, 0x3e027906
	v_fma_f32 v95, |v94|, s92, 1.0
	v_mul_f32_e32 v97, v97, v98
	v_rcp_f32_e32 v95, v95
	v_mul_f32_e32 v97, v99, v97
	v_mul_f32_e32 v98, v97, v96
	v_fma_f32 v97, -v97, v96, v96
	v_cmp_gt_f32_e32 vcc, 0, v96
	v_fmamk_f32 v96, v95, 0x3f07dc22, v236
	v_fmaak_f32 v96, v95, v96, 0x3f35f0e3
	v_cndmask_b32_e32 v130, v97, v98, vcc
	v_mul_f32_e32 v97, v94, v94
	v_mul_f32_e32 v97, 0xbf38aa3b, v97
	v_exp_f32_e32 v97, v97
	v_fmaak_f32 v96, v95, v96, 0xbe11a98e
	v_fmaak_f32 v96, v95, v96, 0x3e027906
	v_mul_f32_e32 v95, v95, v96
	v_mul_f32_e32 v95, v97, v95
	v_lshlrev_b32_e32 v7, 16, v7
	v_mul_f32_e32 v96, v95, v94
	v_fma_f32 v95, -v95, v94, v94
	v_cmp_gt_f32_e32 vcc, 0, v94
	v_fma_f32 v94, |v7|, s92, 1.0
	v_rcp_f32_e32 v94, v94
	v_cndmask_b32_e32 v167, v95, v96, vcc
	v_mul_f32_e32 v96, v7, v7
	v_mul_f32_e32 v96, 0xbf38aa3b, v96
	v_fmamk_f32 v95, v94, 0x3f07dc22, v236
	v_fmaak_f32 v95, v94, v95, 0x3f35f0e3
	v_exp_f32_e32 v96, v96
	v_fmaak_f32 v95, v94, v95, 0xbe11a98e
	v_fmaak_f32 v95, v94, v95, 0x3e027906
	v_mul_f32_e32 v94, v94, v95
	v_mul_f32_e32 v94, v96, v94
	v_mul_f32_e32 v95, v94, v7
	v_fma_f32 v94, -v94, v7, v7
	v_cmp_gt_f32_e32 vcc, 0, v7
	global_load_ushort v7, v[76:77], off offset:2048
	s_nop 0
	global_load_ushort v76, v[78:79], off
	global_load_ushort v77, v[80:81], off offset:2048
	s_nop 0
	global_load_ushort v78, v[84:85], off
	global_load_ushort v79, v[86:87], off offset:2048
	global_load_ushort v80, v[88:89], off
	global_load_ushort v81, v[90:91], off offset:2048
	s_nop 0
	global_load_ushort v84, v[92:93], off
	v_cndmask_b32_e32 v168, v94, v95, vcc
	s_waitcnt vmcnt(7)
	v_lshlrev_b32_e32 v7, 16, v7
	v_fma_f32 v85, |v7|, s92, 1.0
	v_rcp_f32_e32 v85, v85
	v_mul_f32_e32 v87, v7, v7
	v_mul_f32_e32 v87, 0xbf38aa3b, v87
	v_exp_f32_e32 v87, v87
	v_fmamk_f32 v86, v85, 0x3f07dc22, v236
	v_fmaak_f32 v86, v85, v86, 0x3f35f0e3
	v_fmaak_f32 v86, v85, v86, 0xbe11a98e
	v_fmaak_f32 v86, v85, v86, 0x3e027906
	v_mul_f32_e32 v85, v85, v86
	v_mul_f32_e32 v85, v87, v85
	v_mul_f32_e32 v86, v85, v7
	v_fma_f32 v85, -v85, v7, v7
	v_cmp_gt_f32_e32 vcc, 0, v7
	s_waitcnt vmcnt(6)
	v_lshlrev_b32_e32 v7, 16, v76
	v_fma_f32 v76, |v7|, s92, 1.0
	v_rcp_f32_e32 v76, v76
	v_cndmask_b32_e32 v169, v85, v86, vcc
	v_mul_f32_e32 v86, v7, v7
	v_mul_f32_e32 v86, 0xbf38aa3b, v86
	v_fmamk_f32 v85, v76, 0x3f07dc22, v236
	v_fmaak_f32 v85, v76, v85, 0x3f35f0e3
	v_exp_f32_e32 v86, v86
	v_fmaak_f32 v85, v76, v85, 0xbe11a98e
	v_fmaak_f32 v85, v76, v85, 0x3e027906
	v_mul_f32_e32 v76, v76, v85
	v_mul_f32_e32 v76, v86, v76
	v_mul_f32_e32 v85, v76, v7
	v_fma_f32 v76, -v76, v7, v7
	v_cmp_gt_f32_e32 vcc, 0, v7
	s_waitcnt vmcnt(5)
	v_lshlrev_b32_e32 v7, 16, v77
	v_cndmask_b32_e32 v170, v76, v85, vcc
	v_fma_f32 v76, |v7|, s92, 1.0
	v_rcp_f32_e32 v76, v76
	v_mul_f32_e32 v85, v7, v7
	v_mul_f32_e32 v85, 0xbf38aa3b, v85
	v_exp_f32_e32 v85, v85
	v_fmamk_f32 v77, v76, 0x3f07dc22, v236
	v_fmaak_f32 v77, v76, v77, 0x3f35f0e3
	v_fmaak_f32 v77, v76, v77, 0xbe11a98e
	v_fmaak_f32 v77, v76, v77, 0x3e027906
	v_mul_f32_e32 v76, v76, v77
	v_mul_f32_e32 v76, v85, v76
	v_mul_f32_e32 v77, v76, v7
	v_fma_f32 v76, -v76, v7, v7
	v_cmp_gt_f32_e32 vcc, 0, v7
	s_waitcnt vmcnt(4)
	v_lshlrev_b32_e32 v7, 16, v78
	v_mul_f32_e32 v78, v7, v7
	v_cndmask_b32_e32 v171, v76, v77, vcc
	v_fma_f32 v76, |v7|, s92, 1.0
	v_rcp_f32_e32 v76, v76
	v_mul_f32_e32 v78, 0xbf38aa3b, v78
	v_exp_f32_e32 v78, v78
	v_cmp_gt_f32_e32 vcc, 0, v7
	v_fmamk_f32 v77, v76, 0x3f07dc22, v236
	v_fmaak_f32 v77, v76, v77, 0x3f35f0e3
	v_fmaak_f32 v77, v76, v77, 0xbe11a98e
	v_fmaak_f32 v77, v76, v77, 0x3e027906
	v_mul_f32_e32 v76, v76, v77
	v_mul_f32_e32 v76, v78, v76
	v_mul_f32_e32 v77, v76, v7
	v_fma_f32 v76, -v76, v7, v7
	s_waitcnt vmcnt(3)
	v_lshlrev_b32_e32 v7, 16, v79
	v_cndmask_b32_e32 v172, v76, v77, vcc
	v_fma_f32 v76, |v7|, s92, 1.0
	v_rcp_f32_e32 v76, v76
	v_mul_f32_e32 v78, v7, v7
	v_mul_f32_e32 v78, 0xbf38aa3b, v78
	v_exp_f32_e32 v78, v78
	v_fmamk_f32 v77, v76, 0x3f07dc22, v236
	v_fmaak_f32 v77, v76, v77, 0x3f35f0e3
	v_fmaak_f32 v77, v76, v77, 0xbe11a98e
	v_fmaak_f32 v77, v76, v77, 0x3e027906
	v_mul_f32_e32 v76, v76, v77
	v_mul_f32_e32 v76, v78, v76
	v_mul_f32_e32 v77, v76, v7
	v_fma_f32 v76, -v76, v7, v7
	v_cmp_gt_f32_e32 vcc, 0, v7
	s_waitcnt vmcnt(2)
	v_lshlrev_b32_e32 v7, 16, v80
	v_mul_f32_e32 v78, v7, v7
	v_cndmask_b32_e32 v173, v76, v77, vcc
	v_fma_f32 v76, |v7|, s92, 1.0
	v_rcp_f32_e32 v76, v76
	v_mul_f32_e32 v78, 0xbf38aa3b, v78
	v_exp_f32_e32 v78, v78
	v_cmp_gt_f32_e32 vcc, 0, v7
	v_fmamk_f32 v77, v76, 0x3f07dc22, v236
	v_fmaak_f32 v77, v76, v77, 0x3f35f0e3
	v_fmaak_f32 v77, v76, v77, 0xbe11a98e
	v_fmaak_f32 v77, v76, v77, 0x3e027906
	v_mul_f32_e32 v76, v76, v77
	v_mul_f32_e32 v76, v78, v76
	v_mul_f32_e32 v77, v76, v7
	v_fma_f32 v76, -v76, v7, v7
	s_waitcnt vmcnt(1)
	v_lshlrev_b32_e32 v7, 16, v81
	v_cndmask_b32_e32 v174, v76, v77, vcc
	v_fma_f32 v76, |v7|, s92, 1.0
	v_rcp_f32_e32 v76, v76
	v_mul_f32_e32 v78, v7, v7
	v_mul_f32_e32 v78, 0xbf38aa3b, v78
	v_exp_f32_e32 v78, v78
	v_fmamk_f32 v77, v76, 0x3f07dc22, v236
	v_fmaak_f32 v77, v76, v77, 0x3f35f0e3
	v_fmaak_f32 v77, v76, v77, 0xbe11a98e
	v_fmaak_f32 v77, v76, v77, 0x3e027906
	v_mul_f32_e32 v76, v76, v77
	v_mul_f32_e32 v76, v78, v76
	v_mul_f32_e32 v77, v76, v7
	v_fma_f32 v76, -v76, v7, v7
	v_cmp_gt_f32_e32 vcc, 0, v7
	s_waitcnt vmcnt(0)
	v_lshlrev_b32_e32 v7, 16, v84
	v_mul_f32_e32 v78, v7, v7
	v_cndmask_b32_e32 v175, v76, v77, vcc
	v_fma_f32 v76, |v7|, s92, 1.0
	v_rcp_f32_e32 v76, v76
	v_mul_f32_e32 v78, 0xbf38aa3b, v78
	v_exp_f32_e32 v78, v78
	v_cmp_gt_f32_e32 vcc, 0, v7
	v_fmamk_f32 v77, v76, 0x3f07dc22, v236
	v_fmaak_f32 v77, v76, v77, 0x3f35f0e3
	v_fmaak_f32 v77, v76, v77, 0xbe11a98e
	v_fmaak_f32 v77, v76, v77, 0x3e027906
	v_mul_f32_e32 v76, v76, v77
	v_mul_f32_e32 v76, v78, v76
	v_mul_f32_e32 v77, v76, v7
	v_fma_f32 v76, -v76, v7, v7
	global_load_ushort v7, v[54:55], off offset:2048
	s_nop 0
	global_load_ushort v54, v[56:57], off
	global_load_ushort v55, v[58:59], off offset:2048
	s_nop 0
	global_load_ushort v56, v[60:61], off
	global_load_ushort v57, v[62:63], off offset:2048
	global_load_ushort v58, v[64:65], off
	global_load_ushort v59, v[66:67], off offset:2048
	s_nop 0
	global_load_ushort v60, v[68:69], off
	v_cndmask_b32_e32 v176, v76, v77, vcc
	v_lshl_add_u64 v[84:85], s[76:77], 0, v[74:75]
	s_waitcnt vmcnt(7)
	v_lshlrev_b32_e32 v7, 16, v7
	v_fma_f32 v61, |v7|, s92, 1.0
	v_rcp_f32_e32 v61, v61
	v_mul_f32_e32 v63, v7, v7
	v_mul_f32_e32 v63, 0xbf38aa3b, v63
	v_exp_f32_e32 v63, v63
	v_fmamk_f32 v62, v61, 0x3f07dc22, v236
	v_fmaak_f32 v62, v61, v62, 0x3f35f0e3
	v_fmaak_f32 v62, v61, v62, 0xbe11a98e
	v_fmaak_f32 v62, v61, v62, 0x3e027906
	v_mul_f32_e32 v61, v61, v62
	v_mul_f32_e32 v61, v63, v61
	v_mul_f32_e32 v62, v61, v7
	v_fma_f32 v61, -v61, v7, v7
	v_cmp_gt_f32_e32 vcc, 0, v7
	s_waitcnt vmcnt(6)
	v_lshlrev_b32_e32 v7, 16, v54
	v_fma_f32 v54, |v7|, s92, 1.0
	v_rcp_f32_e32 v54, v54
	v_cndmask_b32_e32 v177, v61, v62, vcc
	v_mul_f32_e32 v62, v7, v7
	v_mul_f32_e32 v62, 0xbf38aa3b, v62
	v_fmamk_f32 v61, v54, 0x3f07dc22, v236
	v_fmaak_f32 v61, v54, v61, 0x3f35f0e3
	v_exp_f32_e32 v62, v62
	v_fmaak_f32 v61, v54, v61, 0xbe11a98e
	v_fmaak_f32 v61, v54, v61, 0x3e027906
	v_mul_f32_e32 v54, v54, v61
	v_mul_f32_e32 v54, v62, v54
	v_mul_f32_e32 v61, v54, v7
	v_fma_f32 v54, -v54, v7, v7
	v_cmp_gt_f32_e32 vcc, 0, v7
	s_waitcnt vmcnt(5)
	v_lshlrev_b32_e32 v7, 16, v55
	v_cndmask_b32_e32 v178, v54, v61, vcc
	v_fma_f32 v54, |v7|, s92, 1.0
	v_rcp_f32_e32 v54, v54
	v_mul_f32_e32 v61, v7, v7
	v_mul_f32_e32 v61, 0xbf38aa3b, v61
	v_exp_f32_e32 v61, v61
	v_fmamk_f32 v55, v54, 0x3f07dc22, v236
	v_fmaak_f32 v55, v54, v55, 0x3f35f0e3
	v_fmaak_f32 v55, v54, v55, 0xbe11a98e
	v_fmaak_f32 v55, v54, v55, 0x3e027906
	v_mul_f32_e32 v54, v54, v55
	v_mul_f32_e32 v54, v61, v54
	v_mul_f32_e32 v55, v54, v7
	v_fma_f32 v54, -v54, v7, v7
	v_cmp_gt_f32_e32 vcc, 0, v7
	s_waitcnt vmcnt(4)
	v_lshlrev_b32_e32 v7, 16, v56
	v_mul_f32_e32 v56, v7, v7
	v_cndmask_b32_e32 v179, v54, v55, vcc
	v_fma_f32 v54, |v7|, s92, 1.0
	v_rcp_f32_e32 v54, v54
	v_mul_f32_e32 v56, 0xbf38aa3b, v56
	v_exp_f32_e32 v56, v56
	v_cmp_gt_f32_e32 vcc, 0, v7
	v_fmamk_f32 v55, v54, 0x3f07dc22, v236
	v_fmaak_f32 v55, v54, v55, 0x3f35f0e3
	v_fmaak_f32 v55, v54, v55, 0xbe11a98e
	v_fmaak_f32 v55, v54, v55, 0x3e027906
	v_mul_f32_e32 v54, v54, v55
	v_mul_f32_e32 v54, v56, v54
	v_mul_f32_e32 v55, v54, v7
	v_fma_f32 v54, -v54, v7, v7
	s_waitcnt vmcnt(3)
	v_lshlrev_b32_e32 v7, 16, v57
	v_cndmask_b32_e32 v180, v54, v55, vcc
	v_fma_f32 v54, |v7|, s92, 1.0
	v_rcp_f32_e32 v54, v54
	v_mul_f32_e32 v56, v7, v7
	v_mul_f32_e32 v56, 0xbf38aa3b, v56
	v_exp_f32_e32 v56, v56
	v_fmamk_f32 v55, v54, 0x3f07dc22, v236
	v_fmaak_f32 v55, v54, v55, 0x3f35f0e3
	v_fmaak_f32 v55, v54, v55, 0xbe11a98e
	v_fmaak_f32 v55, v54, v55, 0x3e027906
	v_mul_f32_e32 v54, v54, v55
	v_mul_f32_e32 v54, v56, v54
	v_mul_f32_e32 v55, v54, v7
	v_fma_f32 v54, -v54, v7, v7
	v_cmp_gt_f32_e32 vcc, 0, v7
	s_waitcnt vmcnt(2)
	v_lshlrev_b32_e32 v7, 16, v58
	v_mul_f32_e32 v56, v7, v7
	v_cndmask_b32_e32 v181, v54, v55, vcc
	v_add_co_u32_e32 v134, vcc, s6, v10
	s_mov_b32 s6, 0x6061000
	s_nop 0
	v_addc_co_u32_e32 v135, vcc, 0, v11, vcc
	v_add_co_u32_e32 v136, vcc, s6, v10
	s_mov_b32 s6, 0x6063000
	s_nop 0
	v_addc_co_u32_e32 v137, vcc, 0, v11, vcc
	v_add_co_u32_e32 v138, vcc, s6, v10
	s_mov_b32 s6, 0x6064000
	s_nop 0
	v_addc_co_u32_e32 v139, vcc, 0, v11, vcc
	v_add_co_u32_e32 v140, vcc, s6, v10
	s_mov_b32 s6, 0x606c000
	s_nop 0
	v_addc_co_u32_e32 v141, vcc, 0, v11, vcc
	v_add_co_u32_e32 v142, vcc, s6, v10
	s_mov_b32 s6, 0x606d000
	s_nop 0
	v_addc_co_u32_e32 v143, vcc, 0, v11, vcc
	v_add_co_u32_e32 v144, vcc, s6, v10
	s_mov_b32 s6, 0x606f000
	s_nop 0
	v_addc_co_u32_e32 v145, vcc, 0, v11, vcc
	v_add_co_u32_e32 v146, vcc, s6, v10
	s_mov_b32 s6, 0x6070000
	s_nop 0
	v_addc_co_u32_e32 v147, vcc, 0, v11, vcc
	v_add_co_u32_e32 v148, vcc, s6, v10
	s_mov_b32 s6, 0x6078000
	s_nop 0
	v_addc_co_u32_e32 v149, vcc, 0, v11, vcc
	v_add_co_u32_e32 v76, vcc, s6, v10
	s_mov_b32 s6, 0x6079000
	s_nop 0
	v_addc_co_u32_e32 v77, vcc, 0, v11, vcc
	v_add_co_u32_e32 v78, vcc, s6, v10
	s_mov_b32 s6, 0x607b000
	s_nop 0
	v_addc_co_u32_e32 v79, vcc, 0, v11, vcc
	v_add_co_u32_e32 v80, vcc, s6, v10
	s_mov_b32 s6, 0x607c000
	s_nop 0
	v_addc_co_u32_e32 v81, vcc, 0, v11, vcc
	v_fma_f32 v54, |v7|, s92, 1.0
	v_add_co_u32_e32 v122, vcc, s6, v10
	v_rcp_f32_e32 v54, v54
	s_nop 0
	v_addc_co_u32_e32 v123, vcc, 0, v11, vcc
	s_mov_b32 s6, 0x6084000
	v_add_co_u32_e32 v124, vcc, s6, v10
	s_mov_b32 s6, 0x6085000
	s_nop 0
	v_addc_co_u32_e32 v125, vcc, 0, v11, vcc
	v_add_co_u32_e32 v126, vcc, s6, v10
	v_fmamk_f32 v55, v54, 0x3f07dc22, v236
	v_mul_f32_e32 v56, 0xbf38aa3b, v56
	v_addc_co_u32_e32 v127, vcc, 0, v11, vcc
	s_mov_b32 s6, 0x6087000
	v_fmaak_f32 v55, v54, v55, 0x3f35f0e3
	v_exp_f32_e32 v56, v56
	v_add_co_u32_e32 v128, vcc, s6, v10
	v_fmaak_f32 v55, v54, v55, 0xbe11a98e
	s_nop 0
	v_addc_co_u32_e32 v129, vcc, 0, v11, vcc
	s_mov_b32 s6, 0x6088000
	v_fmaak_f32 v55, v54, v55, 0x3e027906
	v_add_co_u32_e32 v132, vcc, s6, v10
	v_mul_f32_e32 v54, v54, v55
	s_nop 0
	v_addc_co_u32_e32 v133, vcc, 0, v11, vcc
	v_mul_f32_e32 v54, v56, v54
	v_mul_f32_e32 v55, v54, v7
	v_fma_f32 v54, -v54, v7, v7
	v_cmp_gt_f32_e32 vcc, 0, v7
	s_waitcnt vmcnt(1)
	v_lshlrev_b32_e32 v7, 16, v59
	v_mul_f32_e32 v56, v7, v7
	v_cndmask_b32_e32 v151, v54, v55, vcc
	v_fma_f32 v54, |v7|, s92, 1.0
	v_rcp_f32_e32 v54, v54
	v_mul_f32_e32 v56, 0xbf38aa3b, v56
	v_exp_f32_e32 v56, v56
	v_cmp_gt_f32_e32 vcc, 0, v7
	v_fmamk_f32 v55, v54, 0x3f07dc22, v236
	v_fmaak_f32 v55, v54, v55, 0x3f35f0e3
	v_fmaak_f32 v55, v54, v55, 0xbe11a98e
	v_fmaak_f32 v55, v54, v55, 0x3e027906
	v_mul_f32_e32 v54, v54, v55
	v_mul_f32_e32 v54, v56, v54
	v_mul_f32_e32 v55, v54, v7
	v_fma_f32 v54, -v54, v7, v7
	s_waitcnt vmcnt(0)
	v_lshlrev_b32_e32 v7, 16, v60
	v_cndmask_b32_e32 v152, v54, v55, vcc
	v_fma_f32 v54, |v7|, s92, 1.0
	v_rcp_f32_e32 v54, v54
	v_mul_f32_e32 v56, v7, v7
	v_mul_f32_e32 v56, 0xbf38aa3b, v56
	v_exp_f32_e32 v56, v56
	v_fmamk_f32 v55, v54, 0x3f07dc22, v236
	v_fmaak_f32 v55, v54, v55, 0x3f35f0e3
	v_fmaak_f32 v55, v54, v55, 0xbe11a98e
	v_fmaak_f32 v55, v54, v55, 0x3e027906
	v_mul_f32_e32 v54, v54, v55
	v_mul_f32_e32 v54, v56, v54
	v_mul_f32_e32 v55, v54, v7
	v_fma_f32 v54, -v54, v7, v7
	v_cmp_gt_f32_e32 vcc, 0, v7
	global_load_ushort v7, v[38:39], off offset:2048
	s_nop 0
	global_load_ushort v38, v[40:41], off
	global_load_ushort v39, v[42:43], off offset:2048
	s_nop 0
	global_load_ushort v40, v[44:45], off
	global_load_ushort v41, v[46:47], off offset:2048
	global_load_ushort v42, v[48:49], off
	global_load_ushort v43, v[50:51], off offset:2048
	s_nop 0
	global_load_ushort v44, v[52:53], off
	v_cndmask_b32_e32 v153, v54, v55, vcc
	s_mov_b32 s6, 0x6090000
	s_waitcnt vmcnt(7)
	v_lshlrev_b32_e32 v7, 16, v7
	v_fma_f32 v45, |v7|, s92, 1.0
	v_rcp_f32_e32 v45, v45
	v_mul_f32_e32 v47, v7, v7
	v_mul_f32_e32 v47, 0xbf38aa3b, v47
	v_exp_f32_e32 v47, v47
	v_fmamk_f32 v46, v45, 0x3f07dc22, v236
	v_fmaak_f32 v46, v45, v46, 0x3f35f0e3
	v_fmaak_f32 v46, v45, v46, 0xbe11a98e
	v_fmaak_f32 v46, v45, v46, 0x3e027906
	v_mul_f32_e32 v45, v45, v46
	v_mul_f32_e32 v45, v47, v45
	v_mul_f32_e32 v46, v45, v7
	v_fma_f32 v45, -v45, v7, v7
	v_cmp_gt_f32_e32 vcc, 0, v7
	s_waitcnt vmcnt(6)
	v_lshlrev_b32_e32 v7, 16, v38
	v_fma_f32 v38, |v7|, s92, 1.0
	v_rcp_f32_e32 v38, v38
	v_cndmask_b32_e32 v154, v45, v46, vcc
	v_mul_f32_e32 v46, v7, v7
	v_mul_f32_e32 v46, 0xbf38aa3b, v46
	v_fmamk_f32 v45, v38, 0x3f07dc22, v236
	v_fmaak_f32 v45, v38, v45, 0x3f35f0e3
	v_exp_f32_e32 v46, v46
	v_fmaak_f32 v45, v38, v45, 0xbe11a98e
	v_fmaak_f32 v45, v38, v45, 0x3e027906
	v_mul_f32_e32 v38, v38, v45
	v_mul_f32_e32 v38, v46, v38
	v_mul_f32_e32 v45, v38, v7
	v_fma_f32 v38, -v38, v7, v7
	v_cmp_gt_f32_e32 vcc, 0, v7
	s_waitcnt vmcnt(5)
	v_lshlrev_b32_e32 v7, 16, v39
	v_cndmask_b32_e32 v155, v38, v45, vcc
	v_fma_f32 v38, |v7|, s92, 1.0
	v_rcp_f32_e32 v38, v38
	v_mul_f32_e32 v45, v7, v7
	v_mul_f32_e32 v45, 0xbf38aa3b, v45
	v_exp_f32_e32 v45, v45
	v_fmamk_f32 v39, v38, 0x3f07dc22, v236
	v_fmaak_f32 v39, v38, v39, 0x3f35f0e3
	v_fmaak_f32 v39, v38, v39, 0xbe11a98e
	v_fmaak_f32 v39, v38, v39, 0x3e027906
	v_mul_f32_e32 v38, v38, v39
	v_mul_f32_e32 v38, v45, v38
	v_mul_f32_e32 v39, v38, v7
	v_fma_f32 v38, -v38, v7, v7
	v_cmp_gt_f32_e32 vcc, 0, v7
	s_waitcnt vmcnt(4)
	v_lshlrev_b32_e32 v7, 16, v40
	v_mul_f32_e32 v40, v7, v7
	v_cndmask_b32_e32 v156, v38, v39, vcc
	v_fma_f32 v38, |v7|, s92, 1.0
	v_rcp_f32_e32 v38, v38
	v_mul_f32_e32 v40, 0xbf38aa3b, v40
	v_exp_f32_e32 v40, v40
	v_cmp_gt_f32_e32 vcc, 0, v7
	v_fmamk_f32 v39, v38, 0x3f07dc22, v236
	v_fmaak_f32 v39, v38, v39, 0x3f35f0e3
	v_fmaak_f32 v39, v38, v39, 0xbe11a98e
	v_fmaak_f32 v39, v38, v39, 0x3e027906
	v_mul_f32_e32 v38, v38, v39
	v_mul_f32_e32 v38, v40, v38
	v_mul_f32_e32 v39, v38, v7
	v_fma_f32 v38, -v38, v7, v7
	s_waitcnt vmcnt(3)
	v_lshlrev_b32_e32 v7, 16, v41
	v_cndmask_b32_e32 v157, v38, v39, vcc
	v_fma_f32 v38, |v7|, s92, 1.0
	v_rcp_f32_e32 v38, v38
	v_mul_f32_e32 v40, v7, v7
	v_mul_f32_e32 v40, 0xbf38aa3b, v40
	v_exp_f32_e32 v40, v40
	v_fmamk_f32 v39, v38, 0x3f07dc22, v236
	v_fmaak_f32 v39, v38, v39, 0x3f35f0e3
	v_fmaak_f32 v39, v38, v39, 0xbe11a98e
	v_fmaak_f32 v39, v38, v39, 0x3e027906
	v_mul_f32_e32 v38, v38, v39
	v_mul_f32_e32 v38, v40, v38
	v_mul_f32_e32 v39, v38, v7
	v_fma_f32 v38, -v38, v7, v7
	v_cmp_gt_f32_e32 vcc, 0, v7
	s_waitcnt vmcnt(2)
	v_lshlrev_b32_e32 v7, 16, v42
	v_mul_f32_e32 v40, v7, v7
	v_cndmask_b32_e32 v158, v38, v39, vcc
	v_fma_f32 v38, |v7|, s92, 1.0
	v_rcp_f32_e32 v38, v38
	v_mul_f32_e32 v40, 0xbf38aa3b, v40
	v_exp_f32_e32 v40, v40
	v_cmp_gt_f32_e32 vcc, 0, v7
	v_fmamk_f32 v39, v38, 0x3f07dc22, v236
	v_fmaak_f32 v39, v38, v39, 0x3f35f0e3
	v_fmaak_f32 v39, v38, v39, 0xbe11a98e
	v_fmaak_f32 v39, v38, v39, 0x3e027906
	v_mul_f32_e32 v38, v38, v39
	v_mul_f32_e32 v38, v40, v38
	v_mul_f32_e32 v39, v38, v7
	v_fma_f32 v38, -v38, v7, v7
	s_waitcnt vmcnt(1)
	v_lshlrev_b32_e32 v7, 16, v43
	v_cndmask_b32_e32 v159, v38, v39, vcc
	v_fma_f32 v38, |v7|, s92, 1.0
	v_rcp_f32_e32 v38, v38
	v_mul_f32_e32 v40, v7, v7
	v_mul_f32_e32 v40, 0xbf38aa3b, v40
	v_exp_f32_e32 v40, v40
	v_fmamk_f32 v39, v38, 0x3f07dc22, v236
	v_fmaak_f32 v39, v38, v39, 0x3f35f0e3
	v_fmaak_f32 v39, v38, v39, 0xbe11a98e
	v_fmaak_f32 v39, v38, v39, 0x3e027906
	v_mul_f32_e32 v38, v38, v39
	v_mul_f32_e32 v38, v40, v38
	v_mul_f32_e32 v39, v38, v7
	v_fma_f32 v38, -v38, v7, v7
	v_cmp_gt_f32_e32 vcc, 0, v7
	s_waitcnt vmcnt(0)
	v_lshlrev_b32_e32 v7, 16, v44
	v_mul_f32_e32 v40, v7, v7
	v_cndmask_b32_e32 v160, v38, v39, vcc
	v_fma_f32 v38, |v7|, s92, 1.0
	v_rcp_f32_e32 v38, v38
	v_mul_f32_e32 v40, 0xbf38aa3b, v40
	v_exp_f32_e32 v40, v40
	v_cmp_gt_f32_e32 vcc, 0, v7
	v_fmamk_f32 v39, v38, 0x3f07dc22, v236
	v_fmaak_f32 v39, v38, v39, 0x3f35f0e3
	v_fmaak_f32 v39, v38, v39, 0xbe11a98e
	v_fmaak_f32 v39, v38, v39, 0x3e027906
	v_mul_f32_e32 v38, v38, v39
	v_mul_f32_e32 v38, v40, v38
	v_mul_f32_e32 v39, v38, v7
	v_fma_f32 v38, -v38, v7, v7
	global_load_ushort v7, v[12:13], off offset:2048
	s_nop 0
	global_load_ushort v12, v[14:15], off
	global_load_ushort v13, v[16:17], off offset:2048
	s_nop 0
	global_load_ushort v14, v[34:35], off
	global_load_ushort v15, v[36:37], off offset:2048
	v_cndmask_b32_e32 v161, v38, v39, vcc
	s_waitcnt vmcnt(4)
	v_lshlrev_b32_e32 v7, 16, v7
	v_fma_f32 v16, |v7|, s92, 1.0
	v_rcp_f32_e32 v16, v16
	v_mul_f32_e32 v34, v7, v7
	v_mul_f32_e32 v34, 0xbf38aa3b, v34
	v_exp_f32_e32 v34, v34
	v_fmamk_f32 v17, v16, 0x3f07dc22, v236
	v_fmaak_f32 v17, v16, v17, 0x3f35f0e3
	v_fmaak_f32 v17, v16, v17, 0xbe11a98e
	v_fmaak_f32 v17, v16, v17, 0x3e027906
	v_mul_f32_e32 v16, v16, v17
	v_mul_f32_e32 v16, v34, v16
	v_mul_f32_e32 v17, v16, v7
	v_fma_f32 v16, -v16, v7, v7
	v_cmp_gt_f32_e32 vcc, 0, v7
	s_waitcnt vmcnt(3)
	v_lshlrev_b32_e32 v7, 16, v12
	v_fma_f32 v12, |v7|, s92, 1.0
	v_rcp_f32_e32 v12, v12
	v_cndmask_b32_e32 v162, v16, v17, vcc
	v_mul_f32_e32 v17, v7, v7
	v_mul_f32_e32 v17, 0xbf38aa3b, v17
	v_fmamk_f32 v16, v12, 0x3f07dc22, v236
	v_fmaak_f32 v16, v12, v16, 0x3f35f0e3
	v_exp_f32_e32 v17, v17
	v_fmaak_f32 v16, v12, v16, 0xbe11a98e
	v_fmaak_f32 v16, v12, v16, 0x3e027906
	v_mul_f32_e32 v12, v12, v16
	v_mul_f32_e32 v12, v17, v12
	v_mul_f32_e32 v16, v12, v7
	v_fma_f32 v12, -v12, v7, v7
	v_cmp_gt_f32_e32 vcc, 0, v7
	s_waitcnt vmcnt(2)
	v_lshlrev_b32_e32 v7, 16, v13
	v_cndmask_b32_e32 v163, v12, v16, vcc
	v_fma_f32 v12, |v7|, s92, 1.0
	v_rcp_f32_e32 v12, v12
	v_mul_f32_e32 v16, v7, v7
	v_mul_f32_e32 v16, 0xbf38aa3b, v16
	v_exp_f32_e32 v16, v16
	v_fmamk_f32 v13, v12, 0x3f07dc22, v236
	v_fmaak_f32 v13, v12, v13, 0x3f35f0e3
	v_fmaak_f32 v13, v12, v13, 0xbe11a98e
	v_fmaak_f32 v13, v12, v13, 0x3e027906
	v_mul_f32_e32 v12, v12, v13
	v_mul_f32_e32 v12, v16, v12
	v_mul_f32_e32 v13, v12, v7
	v_fma_f32 v12, -v12, v7, v7
	v_cmp_gt_f32_e32 vcc, 0, v7
	s_waitcnt vmcnt(1)
	v_lshlrev_b32_e32 v7, 16, v14
	v_mul_f32_e32 v14, v7, v7
	v_cndmask_b32_e32 v164, v12, v13, vcc
	v_fma_f32 v12, |v7|, s92, 1.0
	v_rcp_f32_e32 v12, v12
	v_mul_f32_e32 v14, 0xbf38aa3b, v14
	v_exp_f32_e32 v14, v14
	v_cmp_gt_f32_e32 vcc, 0, v7
	v_fmamk_f32 v13, v12, 0x3f07dc22, v236
	v_fmaak_f32 v13, v12, v13, 0x3f35f0e3
	v_fmaak_f32 v13, v12, v13, 0xbe11a98e
	v_fmaak_f32 v13, v12, v13, 0x3e027906
	v_mul_f32_e32 v12, v12, v13
	v_mul_f32_e32 v12, v14, v12
	v_mul_f32_e32 v13, v12, v7
	v_fma_f32 v12, -v12, v7, v7
	s_waitcnt vmcnt(0)
	v_lshlrev_b32_e32 v7, 16, v15
	v_cndmask_b32_e32 v165, v12, v13, vcc
	v_fma_f32 v12, |v7|, s92, 1.0
	v_rcp_f32_e32 v12, v12
	v_mul_f32_e32 v14, v7, v7
	v_mul_f32_e32 v14, 0xbf38aa3b, v14
	v_exp_f32_e32 v14, v14
	v_fmamk_f32 v13, v12, 0x3f07dc22, v236
	v_fmaak_f32 v13, v12, v13, 0x3f35f0e3
	v_fmaak_f32 v13, v12, v13, 0xbe11a98e
	v_fmaak_f32 v13, v12, v13, 0x3e027906
	v_mul_f32_e32 v12, v12, v13
	v_mul_f32_e32 v12, v14, v12
	v_mul_f32_e32 v13, v12, v7
	v_fma_f32 v12, -v12, v7, v7
	v_cmp_gt_f32_e32 vcc, 0, v7
	v_lshlrev_b32_e32 v7, 4, v73
	v_add3_u32 v34, 0, v6, v7
	v_cndmask_b32_e32 v166, v12, v13, vcc
	v_add_co_u32_e32 v88, vcc, s41, v8
	ds_read_b128 v[62:65], v34
	ds_read_b128 v[58:61], v34 offset:32
	ds_read_b128 v[54:57], v34 offset:64
	ds_read_b128 v[50:53], v34 offset:96
	v_addc_co_u32_e32 v89, vcc, 0, v9, vcc
	v_add_co_u32_e32 v86, vcc, s97, v8
	v_add_u32_e32 v150, s5, v7
	s_nop 0
	v_addc_co_u32_e32 v87, vcc, 0, v9, vcc
	v_add_co_u32_e32 v116, vcc, s6, v10
	s_mov_b32 s6, 0x6091000
	s_nop 0
	v_addc_co_u32_e32 v117, vcc, 0, v11, vcc
	v_add_co_u32_e32 v118, vcc, s6, v10
	s_mov_b32 s6, 0x6093000
	s_nop 0
	v_addc_co_u32_e32 v119, vcc, 0, v11, vcc
	v_add_co_u32_e32 v120, vcc, s6, v10
	s_mov_b32 s6, 0x6094000
	s_nop 0
	v_addc_co_u32_e32 v121, vcc, 0, v11, vcc
	v_add_co_u32_e32 v100, vcc, s6, v10
	s_mov_b32 s6, 0x609c000
	s_nop 0
	v_addc_co_u32_e32 v101, vcc, 0, v11, vcc
	v_add_co_u32_e32 v102, vcc, s6, v10
	s_mov_b32 s6, 0x609d000
	s_nop 0
	v_addc_co_u32_e32 v103, vcc, 0, v11, vcc
	v_add_co_u32_e32 v104, vcc, s6, v10
	s_mov_b32 s6, 0x609f000
	s_nop 0
	v_addc_co_u32_e32 v105, vcc, 0, v11, vcc
	v_add_co_u32_e32 v106, vcc, s6, v10
	s_mov_b32 s6, 0x60a0000
	s_nop 0
	v_addc_co_u32_e32 v107, vcc, 0, v11, vcc
	v_add_co_u32_e32 v108, vcc, s6, v10
	s_mov_b32 s6, 0x60a8000
	s_nop 0
	v_addc_co_u32_e32 v109, vcc, 0, v11, vcc
	v_add_co_u32_e32 v110, vcc, s6, v10
	s_mov_b32 s6, 0x60a9000
	s_nop 0
	v_addc_co_u32_e32 v111, vcc, 0, v11, vcc
	v_add_co_u32_e32 v112, vcc, s6, v10
	s_mov_b32 s6, 0x60ab000
	s_nop 0
	v_addc_co_u32_e32 v113, vcc, 0, v11, vcc
	v_add_co_u32_e32 v114, vcc, s6, v10
	s_mov_b32 s6, 0x60ac000
	s_nop 0
	v_addc_co_u32_e32 v115, vcc, 0, v11, vcc
	v_add_co_u32_e32 v90, vcc, s6, v10
	s_mov_b32 s6, 0x60b4000
	s_nop 0
	v_addc_co_u32_e32 v91, vcc, 0, v11, vcc
	v_add_co_u32_e32 v92, vcc, s6, v10
	s_mov_b32 s6, 0x60b5000
	s_nop 0
	v_addc_co_u32_e32 v93, vcc, 0, v11, vcc
	v_add_co_u32_e32 v94, vcc, s6, v10
	s_mov_b32 s6, 0x60b7000
	s_nop 0
	v_addc_co_u32_e32 v95, vcc, 0, v11, vcc
	v_add_co_u32_e32 v96, vcc, s6, v10
	s_mov_b32 s6, 0x60b8000
	s_nop 0
	v_addc_co_u32_e32 v97, vcc, 0, v11, vcc
	v_add_co_u32_e32 v98, vcc, s6, v10
	ds_read_b128 v[46:49], v34 offset:128
	ds_read_b128 v[42:45], v34 offset:160
	ds_read_b128 v[38:41], v34 offset:192
	ds_read_b128 v[34:37], v34 offset:224
	v_addc_co_u32_e32 v99, vcc, 0, v11, vcc
	s_waitcnt lgkmcnt(7)
	v_mfma_f32_32x32x16_bf16 v[2:17], v[2:5], v[62:65], 0
	global_load_dwordx4 v[66:69], v[82:83], off offset:-4096
	ds_read_b128 v[182:185], v150
	v_mov_b32_e32 v73, v131
	v_lshlrev_b64 v[72:73], 11, v[72:73]
	v_lshl_add_u64 v[72:73], v[84:85], 0, v[72:73]
	v_readlane_b32 s5, v252, 31
	s_waitcnt lgkmcnt(7)
	v_mfma_f32_32x32x16_bf16 v[2:17], v[30:33], v[58:61], v[2:17]
	ds_read_b128 v[30:33], v150 offset:32
	s_waitcnt lgkmcnt(1)
	s_nop 9
	v_add_f32_e32 v2, v2, v182
	v_mul_f32_e32 v2, v130, v2
	v_cvt_pk_bf16_f32 v2, v2, s0
	global_store_short v[72:73], v2, off
	v_add_f32_e32 v2, v3, v183
	v_mul_f32_e32 v2, v167, v2
	v_cvt_pk_bf16_f32 v72, v2, s0
	v_or_b32_e32 v2, s5, v1
	v_lshlrev_b32_e32 v130, 11, v2
	v_lshl_add_u64 v[2:3], v[84:85], 0, v[130:131]
	global_store_short v[2:3], v72, off
	v_add_f32_e32 v2, v4, v184
	v_mul_f32_e32 v2, v168, v2
	v_readlane_b32 s5, v252, 32
	v_cvt_pk_bf16_f32 v4, v2, s0
	s_nop 0
	v_or_b32_e32 v2, s5, v1
	v_lshlrev_b32_e32 v130, 11, v2
	v_lshl_add_u64 v[2:3], v[84:85], 0, v[130:131]
	global_store_short v[2:3], v4, off
	v_add_f32_e32 v2, v5, v185
	v_mul_f32_e32 v2, v169, v2
	v_readlane_b32 s5, v252, 33
	v_cvt_pk_bf16_f32 v4, v2, s0
	s_nop 0
	v_or_b32_e32 v2, s5, v1
	v_lshlrev_b32_e32 v130, 11, v2
	v_lshl_add_u64 v[2:3], v[84:85], 0, v[130:131]
	global_store_short v[2:3], v4, off
	s_waitcnt lgkmcnt(0)
	v_add_f32_e32 v2, v6, v30
	v_mul_f32_e32 v2, v170, v2
	v_readlane_b32 s5, v252, 34
	v_cvt_pk_bf16_f32 v4, v2, s0
	s_nop 0
	v_or_b32_e32 v2, s5, v1
	v_lshlrev_b32_e32 v130, 11, v2
	v_lshl_add_u64 v[2:3], v[84:85], 0, v[130:131]
	global_store_short v[2:3], v4, off
	v_add_f32_e32 v2, v7, v31
	v_mul_f32_e32 v2, v171, v2
	v_readlane_b32 s5, v252, 35
	v_cvt_pk_bf16_f32 v4, v2, s0
	s_nop 0
	v_or_b32_e32 v2, s5, v1
	v_lshlrev_b32_e32 v130, 11, v2
	v_lshl_add_u64 v[2:3], v[84:85], 0, v[130:131]
	global_store_short v[2:3], v4, off
	v_add_f32_e32 v2, v8, v32
	v_mul_f32_e32 v2, v172, v2
	v_readlane_b32 s5, v252, 36
	v_cvt_pk_bf16_f32 v4, v2, s0
	s_nop 0
	v_or_b32_e32 v2, s5, v1
	v_lshlrev_b32_e32 v130, 11, v2
	v_lshl_add_u64 v[2:3], v[84:85], 0, v[130:131]
	global_store_short v[2:3], v4, off
	v_add_f32_e32 v2, v9, v33
	v_mul_f32_e32 v2, v173, v2
	v_cvt_pk_bf16_f32 v8, v2, s0
	ds_read_b128 v[2:5], v150 offset:64
	v_readlane_b32 s5, v252, 37
	s_nop 1
	v_or_b32_e32 v6, s5, v1
	v_lshlrev_b32_e32 v130, 11, v6
	v_lshl_add_u64 v[6:7], v[84:85], 0, v[130:131]
	v_readlane_b32 s5, v252, 38
	global_store_short v[6:7], v8, off
	ds_read_b128 v[6:9], v150 offset:96
	s_waitcnt lgkmcnt(1)
	v_add_f32_e32 v2, v10, v2
	v_or_b32_e32 v10, s5, v1
	v_mul_f32_e32 v2, v174, v2
	v_lshlrev_b32_e32 v130, 11, v10
	v_cvt_pk_bf16_f32 v2, v2, s0
	v_lshl_add_u64 v[30:31], v[84:85], 0, v[130:131]
	global_store_short v[30:31], v2, off
	v_add_f32_e32 v2, v11, v3
	v_mul_f32_e32 v2, v175, v2
	v_readlane_b32 s5, v252, 39
	v_cvt_pk_bf16_f32 v10, v2, s0
	s_nop 0
	v_or_b32_e32 v2, s5, v1
	v_lshlrev_b32_e32 v130, 11, v2
	v_lshl_add_u64 v[2:3], v[84:85], 0, v[130:131]
	global_store_short v[2:3], v10, off
	v_add_f32_e32 v2, v12, v4
	v_mul_f32_e32 v2, v176, v2
	v_readlane_b32 s5, v252, 40
	v_cvt_pk_bf16_f32 v4, v2, s0
	s_nop 0
	v_or_b32_e32 v2, s5, v1
	v_lshlrev_b32_e32 v130, 11, v2
	v_lshl_add_u64 v[2:3], v[84:85], 0, v[130:131]
	global_store_short v[2:3], v4, off
	v_add_f32_e32 v2, v13, v5
	v_mul_f32_e32 v2, v177, v2
	v_readlane_b32 s5, v252, 41
	v_cvt_pk_bf16_f32 v4, v2, s0
	s_nop 0
	v_or_b32_e32 v2, s5, v1
	v_lshlrev_b32_e32 v130, 11, v2
	v_lshl_add_u64 v[2:3], v[84:85], 0, v[130:131]
	global_store_short v[2:3], v4, off
	s_waitcnt lgkmcnt(0)
	v_add_f32_e32 v2, v14, v6
	v_mul_f32_e32 v2, v178, v2
	v_readlane_b32 s5, v252, 42
	v_cvt_pk_bf16_f32 v4, v2, s0
	s_nop 0
	v_or_b32_e32 v2, s5, v1
	v_lshlrev_b32_e32 v130, 11, v2
	v_lshl_add_u64 v[2:3], v[84:85], 0, v[130:131]
	global_store_short v[2:3], v4, off
	v_add_f32_e32 v2, v15, v7
	v_mul_f32_e32 v2, v179, v2
	v_readlane_b32 s5, v252, 43
	v_cvt_pk_bf16_f32 v4, v2, s0
	s_nop 0
	v_or_b32_e32 v2, s5, v1
	v_lshlrev_b32_e32 v130, 11, v2
	v_lshl_add_u64 v[2:3], v[84:85], 0, v[130:131]
	global_store_short v[2:3], v4, off
	v_add_f32_e32 v2, v16, v8
	v_mul_f32_e32 v2, v180, v2
	v_readlane_b32 s5, v252, 44
	v_cvt_pk_bf16_f32 v4, v2, s0
	s_nop 0
	v_or_b32_e32 v2, s5, v1
	v_lshlrev_b32_e32 v130, 11, v2
	v_lshl_add_u64 v[2:3], v[84:85], 0, v[130:131]
	global_store_short v[2:3], v4, off
	v_add_f32_e32 v2, v17, v9
	v_mul_f32_e32 v2, v181, v2
	v_readlane_b32 s5, v252, 45
	v_cvt_pk_bf16_f32 v4, v2, s0
	s_nop 0
	v_or_b32_e32 v2, s5, v1
	v_lshlrev_b32_e32 v130, 11, v2
	v_lshl_add_u64 v[2:3], v[84:85], 0, v[130:131]
	global_store_short v[2:3], v4, off
	global_load_ushort v2, v[134:135], off
	global_load_ushort v3, v[136:137], off offset:2048
	global_load_ushort v4, v[138:139], off
	global_load_ushort v5, v[140:141], off offset:2048
	global_load_ushort v6, v[142:143], off
	global_load_ushort v7, v[144:145], off offset:2048
	global_load_ushort v8, v[146:147], off
	global_load_ushort v9, v[148:149], off offset:2048
	v_readlane_b32 s5, v252, 46
	s_waitcnt vmcnt(7)
	v_lshlrev_b32_e32 v2, 16, v2
	v_fma_f32 v10, |v2|, s92, 1.0
	v_rcp_f32_e32 v10, v10
	v_mul_f32_e32 v12, v2, v2
	v_mul_f32_e32 v12, 0xbf38aa3b, v12
	v_exp_f32_e32 v12, v12
	v_fmamk_f32 v11, v10, 0x3f07dc22, v236
	v_fmaak_f32 v11, v10, v11, 0x3f35f0e3
	v_fmaak_f32 v11, v10, v11, 0xbe11a98e
	v_fmaak_f32 v11, v10, v11, 0x3e027906
	v_mul_f32_e32 v10, v10, v11
	v_mul_f32_e32 v10, v12, v10
	v_mul_f32_e32 v11, v10, v2
	v_fma_f32 v10, -v10, v2, v2
	v_cmp_gt_f32_e32 vcc, 0, v2
	s_waitcnt vmcnt(6)
	v_lshlrev_b32_e32 v2, 16, v3
	v_fma_f32 v3, |v2|, s92, 1.0
	v_rcp_f32_e32 v3, v3
	v_cndmask_b32_e32 v134, v10, v11, vcc
	v_mul_f32_e32 v11, v2, v2
	v_mul_f32_e32 v11, 0xbf38aa3b, v11
	v_fmamk_f32 v10, v3, 0x3f07dc22, v236
	v_fmaak_f32 v10, v3, v10, 0x3f35f0e3
	v_exp_f32_e32 v11, v11
	v_fmaak_f32 v10, v3, v10, 0xbe11a98e
	v_fmaak_f32 v10, v3, v10, 0x3e027906
	v_mul_f32_e32 v3, v3, v10
	v_mul_f32_e32 v3, v11, v3
	v_mul_f32_e32 v10, v3, v2
	v_fma_f32 v3, -v3, v2, v2
	v_cmp_gt_f32_e32 vcc, 0, v2
	s_waitcnt vmcnt(5)
	v_lshlrev_b32_e32 v2, 16, v4
	v_cndmask_b32_e32 v135, v3, v10, vcc
	v_fma_f32 v3, |v2|, s92, 1.0
	v_rcp_f32_e32 v3, v3
	v_mul_f32_e32 v10, v2, v2
	v_mul_f32_e32 v10, 0xbf38aa3b, v10
	v_exp_f32_e32 v10, v10
	v_fmamk_f32 v4, v3, 0x3f07dc22, v236
	v_fmaak_f32 v4, v3, v4, 0x3f35f0e3
	v_fmaak_f32 v4, v3, v4, 0xbe11a98e
	v_fmaak_f32 v4, v3, v4, 0x3e027906
	v_mul_f32_e32 v3, v3, v4
	v_mul_f32_e32 v3, v10, v3
	v_mul_f32_e32 v4, v3, v2
	v_fma_f32 v3, -v3, v2, v2
	v_cmp_gt_f32_e32 vcc, 0, v2
	s_waitcnt vmcnt(4)
	v_lshlrev_b32_e32 v2, 16, v5
	v_mul_f32_e32 v5, v2, v2
	v_cndmask_b32_e32 v136, v3, v4, vcc
	v_fma_f32 v3, |v2|, s92, 1.0
	v_rcp_f32_e32 v3, v3
	v_mul_f32_e32 v5, 0xbf38aa3b, v5
	v_exp_f32_e32 v5, v5
	v_cmp_gt_f32_e32 vcc, 0, v2
	v_fmamk_f32 v4, v3, 0x3f07dc22, v236
	v_fmaak_f32 v4, v3, v4, 0x3f35f0e3
	v_fmaak_f32 v4, v3, v4, 0xbe11a98e
	v_fmaak_f32 v4, v3, v4, 0x3e027906
	v_mul_f32_e32 v3, v3, v4
	v_mul_f32_e32 v3, v5, v3
	v_mul_f32_e32 v4, v3, v2
	v_fma_f32 v3, -v3, v2, v2
	s_waitcnt vmcnt(3)
	v_lshlrev_b32_e32 v2, 16, v6
	v_cndmask_b32_e32 v137, v3, v4, vcc
	v_fma_f32 v3, |v2|, s92, 1.0
	v_rcp_f32_e32 v3, v3
	v_mul_f32_e32 v5, v2, v2
	v_mul_f32_e32 v5, 0xbf38aa3b, v5
	v_exp_f32_e32 v5, v5
	v_fmamk_f32 v4, v3, 0x3f07dc22, v236
	v_fmaak_f32 v4, v3, v4, 0x3f35f0e3
	v_fmaak_f32 v4, v3, v4, 0xbe11a98e
	v_fmaak_f32 v4, v3, v4, 0x3e027906
	v_mul_f32_e32 v3, v3, v4
	v_mul_f32_e32 v3, v5, v3
	v_mul_f32_e32 v4, v3, v2
	v_fma_f32 v3, -v3, v2, v2
	v_cmp_gt_f32_e32 vcc, 0, v2
	s_waitcnt vmcnt(2)
	v_lshlrev_b32_e32 v2, 16, v7
	v_mul_f32_e32 v5, v2, v2
	v_cndmask_b32_e32 v138, v3, v4, vcc
	v_fma_f32 v3, |v2|, s92, 1.0
	v_rcp_f32_e32 v3, v3
	v_mul_f32_e32 v5, 0xbf38aa3b, v5
	v_exp_f32_e32 v5, v5
	v_cmp_gt_f32_e32 vcc, 0, v2
	v_fmamk_f32 v4, v3, 0x3f07dc22, v236
	v_fmaak_f32 v4, v3, v4, 0x3f35f0e3
	v_fmaak_f32 v4, v3, v4, 0xbe11a98e
	v_fmaak_f32 v4, v3, v4, 0x3e027906
	v_mul_f32_e32 v3, v3, v4
	v_mul_f32_e32 v3, v5, v3
	v_mul_f32_e32 v4, v3, v2
	v_fma_f32 v3, -v3, v2, v2
	s_waitcnt vmcnt(1)
	v_lshlrev_b32_e32 v2, 16, v8
	v_cndmask_b32_e32 v139, v3, v4, vcc
	v_fma_f32 v3, |v2|, s92, 1.0
	v_rcp_f32_e32 v3, v3
	v_mul_f32_e32 v5, v2, v2
	v_mul_f32_e32 v5, 0xbf38aa3b, v5
	v_exp_f32_e32 v5, v5
	v_fmamk_f32 v4, v3, 0x3f07dc22, v236
	v_fmaak_f32 v4, v3, v4, 0x3f35f0e3
	v_fmaak_f32 v4, v3, v4, 0xbe11a98e
	v_fmaak_f32 v4, v3, v4, 0x3e027906
	v_mul_f32_e32 v3, v3, v4
	v_mul_f32_e32 v3, v5, v3
	v_mul_f32_e32 v4, v3, v2
	v_fma_f32 v3, -v3, v2, v2
	v_cmp_gt_f32_e32 vcc, 0, v2
	s_waitcnt vmcnt(0)
	v_lshlrev_b32_e32 v2, 16, v9
	v_mul_f32_e32 v5, v2, v2
	v_cndmask_b32_e32 v140, v3, v4, vcc
	v_fma_f32 v3, |v2|, s92, 1.0
	v_rcp_f32_e32 v3, v3
	v_mul_f32_e32 v5, 0xbf38aa3b, v5
	v_exp_f32_e32 v5, v5
	v_cmp_gt_f32_e32 vcc, 0, v2
	v_fmamk_f32 v4, v3, 0x3f07dc22, v236
	v_fmaak_f32 v4, v3, v4, 0x3f35f0e3
	v_fmaak_f32 v4, v3, v4, 0xbe11a98e
	v_fmaak_f32 v4, v3, v4, 0x3e027906
	v_mul_f32_e32 v3, v3, v4
	v_mul_f32_e32 v3, v5, v3
	v_mul_f32_e32 v4, v3, v2
	v_fma_f32 v3, -v3, v2, v2
	v_cndmask_b32_e32 v141, v3, v4, vcc
	global_load_ushort v2, v[76:77], off
	global_load_ushort v3, v[78:79], off offset:2048
	global_load_ushort v4, v[80:81], off
	global_load_ushort v5, v[122:123], off offset:2048
	global_load_ushort v6, v[124:125], off
	global_load_ushort v7, v[126:127], off offset:2048
	global_load_ushort v8, v[128:129], off
	global_load_ushort v30, v[132:133], off offset:2048
	s_waitcnt vmcnt(7)
	v_lshlrev_b32_e32 v2, 16, v2
	v_fma_f32 v9, |v2|, s92, 1.0
	v_rcp_f32_e32 v9, v9
	v_mul_f32_e32 v11, v2, v2
	v_mul_f32_e32 v11, 0xbf38aa3b, v11
	v_exp_f32_e32 v11, v11
	v_fmamk_f32 v10, v9, 0x3f07dc22, v236
	v_fmaak_f32 v10, v9, v10, 0x3f35f0e3
	v_fmaak_f32 v10, v9, v10, 0xbe11a98e
	v_fmaak_f32 v10, v9, v10, 0x3e027906
	v_mul_f32_e32 v9, v9, v10
	v_mul_f32_e32 v9, v11, v9
	v_mul_f32_e32 v10, v9, v2
	v_fma_f32 v9, -v9, v2, v2
	v_cmp_gt_f32_e32 vcc, 0, v2
	s_waitcnt vmcnt(6)
	v_lshlrev_b32_e32 v2, 16, v3
	v_fma_f32 v3, |v2|, s92, 1.0
	v_rcp_f32_e32 v3, v3
	v_cndmask_b32_e32 v122, v9, v10, vcc
	v_mul_f32_e32 v10, v2, v2
	v_mul_f32_e32 v10, 0xbf38aa3b, v10
	v_fmamk_f32 v9, v3, 0x3f07dc22, v236
	v_fmaak_f32 v9, v3, v9, 0x3f35f0e3
	v_exp_f32_e32 v10, v10
	v_fmaak_f32 v9, v3, v9, 0xbe11a98e
	v_fmaak_f32 v9, v3, v9, 0x3e027906
	v_mul_f32_e32 v3, v3, v9
	v_mul_f32_e32 v3, v10, v3
	v_mul_f32_e32 v9, v3, v2
	v_fma_f32 v3, -v3, v2, v2
	v_cmp_gt_f32_e32 vcc, 0, v2
	s_waitcnt vmcnt(5)
	v_lshlrev_b32_e32 v2, 16, v4
	s_waitcnt vmcnt(1)
	v_lshlrev_b32_e32 v31, 16, v8
	v_cndmask_b32_e32 v123, v3, v9, vcc
	v_fma_f32 v3, |v2|, s92, 1.0
	v_rcp_f32_e32 v3, v3
	v_mul_f32_e32 v9, v2, v2
	v_mul_f32_e32 v9, 0xbf38aa3b, v9
	v_exp_f32_e32 v9, v9
	v_fmamk_f32 v4, v3, 0x3f07dc22, v236
	v_fmaak_f32 v4, v3, v4, 0x3f35f0e3
	v_fmaak_f32 v4, v3, v4, 0xbe11a98e
	v_fmaak_f32 v4, v3, v4, 0x3e027906
	v_mul_f32_e32 v3, v3, v4
	v_mul_f32_e32 v3, v9, v3
	v_mul_f32_e32 v4, v3, v2
	v_fma_f32 v3, -v3, v2, v2
	v_cmp_gt_f32_e32 vcc, 0, v2
	v_lshlrev_b32_e32 v2, 16, v5
	v_mul_f32_e32 v5, v2, v2
	v_cndmask_b32_e32 v124, v3, v4, vcc
	v_fma_f32 v3, |v2|, s92, 1.0
	v_rcp_f32_e32 v3, v3
	v_mul_f32_e32 v5, 0xbf38aa3b, v5
	v_exp_f32_e32 v5, v5
	v_cmp_gt_f32_e32 vcc, 0, v2
	v_fmamk_f32 v4, v3, 0x3f07dc22, v236
	v_fmaak_f32 v4, v3, v4, 0x3f35f0e3
	v_fmaak_f32 v4, v3, v4, 0xbe11a98e
	v_fmaak_f32 v4, v3, v4, 0x3e027906
	v_mul_f32_e32 v3, v3, v4
	v_mul_f32_e32 v3, v5, v3
	v_mul_f32_e32 v4, v3, v2
	v_fma_f32 v3, -v3, v2, v2
	v_lshlrev_b32_e32 v2, 16, v6
	v_cndmask_b32_e32 v125, v3, v4, vcc
	v_fma_f32 v3, |v2|, s92, 1.0
	v_rcp_f32_e32 v3, v3
	v_mul_f32_e32 v5, v2, v2
	v_mul_f32_e32 v5, 0xbf38aa3b, v5
	v_exp_f32_e32 v5, v5
	v_fmamk_f32 v4, v3, 0x3f07dc22, v236
	v_fmaak_f32 v4, v3, v4, 0x3f35f0e3
	v_fmaak_f32 v4, v3, v4, 0xbe11a98e
	v_fmaak_f32 v4, v3, v4, 0x3e027906
	v_mul_f32_e32 v3, v3, v4
	v_mul_f32_e32 v3, v5, v3
	v_mul_f32_e32 v4, v3, v2
	v_fma_f32 v3, -v3, v2, v2
	v_cmp_gt_f32_e32 vcc, 0, v2
	v_lshlrev_b32_e32 v2, 16, v7
	v_mul_f32_e32 v5, v2, v2
	v_cndmask_b32_e32 v126, v3, v4, vcc
	v_fma_f32 v3, |v2|, s92, 1.0
	v_rcp_f32_e32 v3, v3
	v_mul_f32_e32 v5, 0xbf38aa3b, v5
	v_exp_f32_e32 v5, v5
	v_cmp_gt_f32_e32 vcc, 0, v2
	v_fmamk_f32 v4, v3, 0x3f07dc22, v236
	v_fmaak_f32 v4, v3, v4, 0x3f35f0e3
	v_fmaak_f32 v4, v3, v4, 0xbe11a98e
	v_fmaak_f32 v4, v3, v4, 0x3e027906
	v_mul_f32_e32 v3, v3, v4
	v_mul_f32_e32 v3, v5, v3
	v_mul_f32_e32 v4, v3, v2
	v_fma_f32 v3, -v3, v2, v2
	v_fma_f32 v2, |v31|, s92, 1.0
	v_cndmask_b32_e32 v127, v3, v4, vcc
	v_rcp_f32_e32 v32, v2
	v_mfma_f32_32x32x16_bf16 v[2:17], v[22:25], v[62:65], 0
	v_mul_f32_e32 v23, v31, v31
	v_mul_f32_e32 v23, 0xbf38aa3b, v23
	v_fmamk_f32 v22, v32, 0x3f07dc22, v236
	v_fmaak_f32 v22, v32, v22, 0x3f35f0e3
	v_exp_f32_e32 v23, v23
	v_fmaak_f32 v22, v32, v22, 0xbe11a98e
	v_fmaak_f32 v22, v32, v22, 0x3e027906
	v_mfma_f32_32x32x16_bf16 v[2:17], v[18:21], v[58:61], v[2:17]
	v_mul_f32_e32 v22, v32, v22
	v_mul_f32_e32 v22, v23, v22
	v_mul_f32_e32 v23, v22, v31
	v_fma_f32 v22, -v22, v31, v31
	v_cmp_gt_f32_e32 vcc, 0, v31
	s_nop 1
	v_cndmask_b32_e32 v128, v22, v23, vcc
	s_waitcnt vmcnt(0)
	v_lshlrev_b32_e32 v22, 16, v30
	v_fma_f32 v23, |v22|, s92, 1.0
	v_rcp_f32_e32 v23, v23
	v_mfma_f32_32x32x16_bf16 v[2:17], v[66:69], v[54:57], v[2:17]
	v_mul_f32_e32 v19, v22, v22
	v_mul_f32_e32 v19, 0xbf38aa3b, v19
	v_fmamk_f32 v18, v23, 0x3f07dc22, v236
	v_fmaak_f32 v18, v23, v18, 0x3f35f0e3
	v_exp_f32_e32 v19, v19
	v_fmaak_f32 v18, v23, v18, 0xbe11a98e
	v_fmaak_f32 v18, v23, v18, 0x3e027906
	v_mul_f32_e32 v18, v23, v18
	v_mul_f32_e32 v18, v19, v18
	v_mfma_f32_32x32x16_bf16 v[2:17], v[26:29], v[50:53], v[2:17]
	v_mul_f32_e32 v19, v18, v22
	v_fma_f32 v18, -v18, v22, v22
	v_cmp_gt_f32_e32 vcc, 0, v22
	s_nop 1
	v_cndmask_b32_e32 v129, v18, v19, vcc
	global_load_dwordx4 v[18:21], v[70:71], off offset:2048
	global_load_dwordx4 v[78:81], v[70:71], off offset:3072
	global_load_dwordx4 v[74:77], v[82:83], off
	s_nop 0
	global_load_dwordx4 v[70:73], v[82:83], off offset:1024
	global_load_dwordx4 v[66:69], v[82:83], off offset:2048
	global_load_dwordx4 v[30:33], v[82:83], off offset:3072
	ds_read_b128 v[22:25], v150 offset:128
	ds_read_b128 v[26:29], v150 offset:160
	s_waitcnt lgkmcnt(1)
	v_add_f32_e32 v2, v2, v22
	v_or_b32_e32 v22, s5, v1
	v_mul_f32_e32 v2, v151, v2
	v_lshlrev_b32_e32 v130, 11, v22
	v_cvt_pk_bf16_f32 v2, v2, s0
	v_lshl_add_u64 v[82:83], v[84:85], 0, v[130:131]
	global_store_short v[82:83], v2, off
	v_add_f32_e32 v2, v3, v23
	v_mul_f32_e32 v2, v152, v2
	v_readlane_b32 s5, v252, 47
	v_cvt_pk_bf16_f32 v22, v2, s0
	s_nop 0
	v_or_b32_e32 v2, s5, v1
	v_lshlrev_b32_e32 v130, 11, v2
	v_lshl_add_u64 v[2:3], v[84:85], 0, v[130:131]
	global_store_short v[2:3], v22, off
	v_add_f32_e32 v2, v4, v24
	v_mul_f32_e32 v2, v153, v2
	v_readlane_b32 s5, v252, 48
	v_cvt_pk_bf16_f32 v4, v2, s0
	s_nop 0
	v_or_b32_e32 v2, s5, v1
	v_lshlrev_b32_e32 v130, 11, v2
	v_lshl_add_u64 v[2:3], v[84:85], 0, v[130:131]
	global_store_short v[2:3], v4, off
	v_add_f32_e32 v2, v5, v25
	v_mul_f32_e32 v2, v154, v2
	v_readlane_b32 s5, v252, 49
	v_cvt_pk_bf16_f32 v4, v2, s0
	s_nop 0
	v_or_b32_e32 v2, s5, v1
	v_lshlrev_b32_e32 v130, 11, v2
	v_lshl_add_u64 v[2:3], v[84:85], 0, v[130:131]
	global_store_short v[2:3], v4, off
	s_waitcnt lgkmcnt(0)
	v_add_f32_e32 v2, v6, v26
	v_mul_f32_e32 v2, v155, v2
	v_readlane_b32 s5, v252, 50
	v_cvt_pk_bf16_f32 v4, v2, s0
	s_nop 0
	v_or_b32_e32 v2, s5, v1
	v_lshlrev_b32_e32 v130, 11, v2
	v_lshl_add_u64 v[2:3], v[84:85], 0, v[130:131]
	global_store_short v[2:3], v4, off
	v_add_f32_e32 v2, v7, v27
	v_mul_f32_e32 v2, v156, v2
	v_readlane_b32 s5, v252, 51
	v_cvt_pk_bf16_f32 v4, v2, s0
	s_nop 0
	v_or_b32_e32 v2, s5, v1
	v_lshlrev_b32_e32 v130, 11, v2
	v_lshl_add_u64 v[2:3], v[84:85], 0, v[130:131]
	global_store_short v[2:3], v4, off
	v_add_f32_e32 v2, v8, v28
	v_mul_f32_e32 v2, v157, v2
	v_readlane_b32 s5, v252, 52
	v_cvt_pk_bf16_f32 v4, v2, s0
	s_nop 0
	v_or_b32_e32 v2, s5, v1
	v_lshlrev_b32_e32 v130, 11, v2
	v_lshl_add_u64 v[2:3], v[84:85], 0, v[130:131]
	global_store_short v[2:3], v4, off
	v_add_f32_e32 v2, v9, v29
	v_mul_f32_e32 v2, v158, v2
	v_cvt_pk_bf16_f32 v8, v2, s0
	ds_read_b128 v[2:5], v150 offset:192
	v_readlane_b32 s5, v252, 53
	s_nop 1
	v_or_b32_e32 v6, s5, v1
	v_lshlrev_b32_e32 v130, 11, v6
	v_lshl_add_u64 v[6:7], v[84:85], 0, v[130:131]
	v_readlane_b32 s5, v252, 54
	global_store_short v[6:7], v8, off
	ds_read_b128 v[6:9], v150 offset:224
	s_waitcnt lgkmcnt(1)
	v_add_f32_e32 v2, v10, v2
	v_or_b32_e32 v10, s5, v1
	v_mul_f32_e32 v2, v159, v2
	v_lshlrev_b32_e32 v130, 11, v10
	v_cvt_pk_bf16_f32 v2, v2, s0
	v_lshl_add_u64 v[22:23], v[84:85], 0, v[130:131]
	global_store_short v[22:23], v2, off
	v_add_f32_e32 v2, v11, v3
	v_mul_f32_e32 v2, v160, v2
	v_readlane_b32 s5, v252, 55
	v_cvt_pk_bf16_f32 v10, v2, s0
	s_nop 0
	v_or_b32_e32 v2, s5, v1
	v_lshlrev_b32_e32 v130, 11, v2
	v_lshl_add_u64 v[2:3], v[84:85], 0, v[130:131]
	global_store_short v[2:3], v10, off
	v_add_f32_e32 v2, v12, v4
	v_mul_f32_e32 v2, v161, v2
	v_readlane_b32 s5, v252, 56
	v_cvt_pk_bf16_f32 v4, v2, s0
	s_nop 0
	v_or_b32_e32 v2, s5, v1
	v_lshlrev_b32_e32 v130, 11, v2
	v_lshl_add_u64 v[2:3], v[84:85], 0, v[130:131]
	global_store_short v[2:3], v4, off
	v_add_f32_e32 v2, v13, v5
	v_mul_f32_e32 v2, v162, v2
	v_readlane_b32 s5, v252, 57
	v_cvt_pk_bf16_f32 v4, v2, s0
	s_nop 0
	v_or_b32_e32 v2, s5, v1
	v_lshlrev_b32_e32 v130, 11, v2
	v_lshl_add_u64 v[2:3], v[84:85], 0, v[130:131]
	global_store_short v[2:3], v4, off
	s_waitcnt lgkmcnt(0)
	v_add_f32_e32 v2, v14, v6
	v_mul_f32_e32 v2, v163, v2
	v_readlane_b32 s5, v252, 58
	v_cvt_pk_bf16_f32 v4, v2, s0
	s_nop 0
	v_or_b32_e32 v2, s5, v1
	v_lshlrev_b32_e32 v130, 11, v2
	v_lshl_add_u64 v[2:3], v[84:85], 0, v[130:131]
	global_store_short v[2:3], v4, off
	v_add_f32_e32 v2, v15, v7
	v_mul_f32_e32 v2, v164, v2
	v_readlane_b32 s5, v252, 59
	v_cvt_pk_bf16_f32 v4, v2, s0
	s_nop 0
	v_or_b32_e32 v2, s5, v1
	v_lshlrev_b32_e32 v130, 11, v2
	v_lshl_add_u64 v[2:3], v[84:85], 0, v[130:131]
	global_store_short v[2:3], v4, off
	v_add_f32_e32 v2, v16, v8
	v_mul_f32_e32 v2, v165, v2
	v_readlane_b32 s5, v252, 60
	v_cvt_pk_bf16_f32 v4, v2, s0
	s_nop 0
	v_or_b32_e32 v2, s5, v1
	v_lshlrev_b32_e32 v130, 11, v2
	v_lshl_add_u64 v[2:3], v[84:85], 0, v[130:131]
	global_store_short v[2:3], v4, off
	v_add_f32_e32 v2, v17, v9
	v_mul_f32_e32 v2, v166, v2
	v_readlane_b32 s5, v252, 61
	v_cvt_pk_bf16_f32 v4, v2, s0
	s_nop 0
	v_or_b32_e32 v2, s5, v1
	v_lshlrev_b32_e32 v130, 11, v2
	v_lshl_add_u64 v[2:3], v[84:85], 0, v[130:131]
	global_store_short v[2:3], v4, off
	global_load_ushort v4, v[116:117], off
	global_load_ushort v3, v[118:119], off offset:2048
	global_load_ushort v2, v[120:121], off
	global_load_dwordx4 v[24:27], v[88:89], off offset:3072
	v_readlane_b32 s5, v252, 62
	s_waitcnt vmcnt(3)
	v_lshlrev_b32_e32 v4, 16, v4
	v_fma_f32 v5, |v4|, s92, 1.0
	v_rcp_f32_e32 v5, v5
	v_mul_f32_e32 v7, v4, v4
	v_mul_f32_e32 v7, 0xbf38aa3b, v7
	v_exp_f32_e32 v7, v7
	v_fmamk_f32 v6, v5, 0x3f07dc22, v236
	v_fmaak_f32 v6, v5, v6, 0x3f35f0e3
	v_fmaak_f32 v6, v5, v6, 0xbe11a98e
	v_fmaak_f32 v6, v5, v6, 0x3e027906
	v_mul_f32_e32 v5, v5, v6
	v_mul_f32_e32 v5, v7, v5
	s_waitcnt vmcnt(2)
	v_lshlrev_b32_e32 v3, 16, v3
	v_mul_f32_e32 v6, v5, v4
	v_fma_f32 v5, -v5, v4, v4
	v_cmp_gt_f32_e32 vcc, 0, v4
	v_fma_f32 v4, |v3|, s92, 1.0
	v_rcp_f32_e32 v4, v4
	v_cndmask_b32_e32 v28, v5, v6, vcc
	v_mul_f32_e32 v6, v3, v3
	v_mul_f32_e32 v6, 0xbf38aa3b, v6
	v_fmamk_f32 v5, v4, 0x3f07dc22, v236
	v_fmaak_f32 v5, v4, v5, 0x3f35f0e3
	v_exp_f32_e32 v6, v6
	v_fmaak_f32 v5, v4, v5, 0xbe11a98e
	v_fmaak_f32 v5, v4, v5, 0x3e027906
	v_mul_f32_e32 v4, v4, v5
	v_mul_f32_e32 v4, v6, v4
	s_waitcnt vmcnt(1)
	v_lshlrev_b32_e32 v2, 16, v2
	v_mul_f32_e32 v5, v4, v3
	v_fma_f32 v4, -v4, v3, v3
	v_cmp_gt_f32_e32 vcc, 0, v3
	v_fma_f32 v3, |v2|, s92, 1.0
	v_rcp_f32_e32 v3, v3
	v_cndmask_b32_e32 v29, v4, v5, vcc
	v_mul_f32_e32 v5, v2, v2
	v_mul_f32_e32 v5, 0xbf38aa3b, v5
	v_fmamk_f32 v4, v3, 0x3f07dc22, v236
	v_fmaak_f32 v4, v3, v4, 0x3f35f0e3
	v_exp_f32_e32 v5, v5
	v_fmaak_f32 v4, v3, v4, 0xbe11a98e
	v_fmaak_f32 v4, v3, v4, 0x3e027906
	v_mul_f32_e32 v3, v3, v4
	v_mul_f32_e32 v3, v5, v3
	v_mul_f32_e32 v4, v3, v2
	v_fma_f32 v3, -v3, v2, v2
	v_cmp_gt_f32_e32 vcc, 0, v2
	s_nop 1
	v_cndmask_b32_e32 v82, v3, v4, vcc
	global_load_ushort v2, v[100:101], off offset:2048
	global_load_ushort v3, v[102:103], off
	global_load_ushort v4, v[104:105], off offset:2048
	global_load_ushort v5, v[106:107], off
	global_load_ushort v6, v[108:109], off offset:2048
	global_load_ushort v7, v[110:111], off
	global_load_ushort v8, v[112:113], off offset:2048
	global_load_ushort v9, v[114:115], off
	s_waitcnt vmcnt(7)
	v_lshlrev_b32_e32 v2, 16, v2
	v_fma_f32 v10, |v2|, s92, 1.0
	v_rcp_f32_e32 v10, v10
	v_mul_f32_e32 v12, v2, v2
	v_mul_f32_e32 v12, 0xbf38aa3b, v12
	v_exp_f32_e32 v12, v12
	v_fmamk_f32 v11, v10, 0x3f07dc22, v236
	v_fmaak_f32 v11, v10, v11, 0x3f35f0e3
	v_fmaak_f32 v11, v10, v11, 0xbe11a98e
	v_fmaak_f32 v11, v10, v11, 0x3e027906
	v_mul_f32_e32 v10, v10, v11
	v_mul_f32_e32 v10, v12, v10
	v_mul_f32_e32 v11, v10, v2
	v_fma_f32 v10, -v10, v2, v2
	v_cmp_gt_f32_e32 vcc, 0, v2
	s_waitcnt vmcnt(6)
	v_lshlrev_b32_e32 v2, 16, v3
	v_fma_f32 v3, |v2|, s92, 1.0
	v_rcp_f32_e32 v3, v3
	v_cndmask_b32_e32 v83, v10, v11, vcc
	v_mul_f32_e32 v11, v2, v2
	v_mul_f32_e32 v11, 0xbf38aa3b, v11
	v_fmamk_f32 v10, v3, 0x3f07dc22, v236
	v_fmaak_f32 v10, v3, v10, 0x3f35f0e3
	v_exp_f32_e32 v11, v11
	v_fmaak_f32 v10, v3, v10, 0xbe11a98e
	v_fmaak_f32 v10, v3, v10, 0x3e027906
	v_mul_f32_e32 v3, v3, v10
	v_mul_f32_e32 v3, v11, v3
	v_mul_f32_e32 v10, v3, v2
	v_fma_f32 v3, -v3, v2, v2
	v_cmp_gt_f32_e32 vcc, 0, v2
	s_waitcnt vmcnt(5)
	v_lshlrev_b32_e32 v2, 16, v4
	v_cndmask_b32_e32 v100, v3, v10, vcc
	v_fma_f32 v3, |v2|, s92, 1.0
	v_rcp_f32_e32 v3, v3
	v_mul_f32_e32 v10, v2, v2
	v_mul_f32_e32 v10, 0xbf38aa3b, v10
	v_exp_f32_e32 v10, v10
	v_fmamk_f32 v4, v3, 0x3f07dc22, v236
	v_fmaak_f32 v4, v3, v4, 0x3f35f0e3
	v_fmaak_f32 v4, v3, v4, 0xbe11a98e
	v_fmaak_f32 v4, v3, v4, 0x3e027906
	v_mul_f32_e32 v3, v3, v4
	v_mul_f32_e32 v3, v10, v3
	v_mul_f32_e32 v4, v3, v2
	v_fma_f32 v3, -v3, v2, v2
	v_cmp_gt_f32_e32 vcc, 0, v2
	s_waitcnt vmcnt(4)
	v_lshlrev_b32_e32 v2, 16, v5
	v_mul_f32_e32 v5, v2, v2
	v_cndmask_b32_e32 v101, v3, v4, vcc
	v_fma_f32 v3, |v2|, s92, 1.0
	v_rcp_f32_e32 v3, v3
	v_mul_f32_e32 v5, 0xbf38aa3b, v5
	v_exp_f32_e32 v5, v5
	v_cmp_gt_f32_e32 vcc, 0, v2
	v_fmamk_f32 v4, v3, 0x3f07dc22, v236
	v_fmaak_f32 v4, v3, v4, 0x3f35f0e3
	v_fmaak_f32 v4, v3, v4, 0xbe11a98e
	v_fmaak_f32 v4, v3, v4, 0x3e027906
	v_mul_f32_e32 v3, v3, v4
	v_mul_f32_e32 v3, v5, v3
	v_mul_f32_e32 v4, v3, v2
	v_fma_f32 v3, -v3, v2, v2
	s_waitcnt vmcnt(3)
	v_lshlrev_b32_e32 v2, 16, v6
	v_cndmask_b32_e32 v102, v3, v4, vcc
	v_fma_f32 v3, |v2|, s92, 1.0
	v_rcp_f32_e32 v3, v3
	v_mul_f32_e32 v5, v2, v2
	v_mul_f32_e32 v5, 0xbf38aa3b, v5
	v_exp_f32_e32 v5, v5
	v_fmamk_f32 v4, v3, 0x3f07dc22, v236
	v_fmaak_f32 v4, v3, v4, 0x3f35f0e3
	v_fmaak_f32 v4, v3, v4, 0xbe11a98e
	v_fmaak_f32 v4, v3, v4, 0x3e027906
	v_mul_f32_e32 v3, v3, v4
	v_mul_f32_e32 v3, v5, v3
	v_mul_f32_e32 v4, v3, v2
	v_fma_f32 v3, -v3, v2, v2
	v_cmp_gt_f32_e32 vcc, 0, v2
	s_waitcnt vmcnt(2)
	v_lshlrev_b32_e32 v2, 16, v7
	v_mul_f32_e32 v5, v2, v2
	v_cndmask_b32_e32 v103, v3, v4, vcc
	v_fma_f32 v3, |v2|, s92, 1.0
	v_rcp_f32_e32 v3, v3
	v_mul_f32_e32 v5, 0xbf38aa3b, v5
	v_exp_f32_e32 v5, v5
	v_cmp_gt_f32_e32 vcc, 0, v2
	v_fmamk_f32 v4, v3, 0x3f07dc22, v236
	v_fmaak_f32 v4, v3, v4, 0x3f35f0e3
	v_fmaak_f32 v4, v3, v4, 0xbe11a98e
	v_fmaak_f32 v4, v3, v4, 0x3e027906
	v_mul_f32_e32 v3, v3, v4
	v_mul_f32_e32 v3, v5, v3
	v_mul_f32_e32 v4, v3, v2
	v_fma_f32 v3, -v3, v2, v2
	s_waitcnt vmcnt(1)
	v_lshlrev_b32_e32 v2, 16, v8
	v_cndmask_b32_e32 v104, v3, v4, vcc
	v_fma_f32 v3, |v2|, s92, 1.0
	v_rcp_f32_e32 v3, v3
	v_mul_f32_e32 v5, v2, v2
	v_mul_f32_e32 v5, 0xbf38aa3b, v5
	v_exp_f32_e32 v5, v5
	v_fmamk_f32 v4, v3, 0x3f07dc22, v236
	v_fmaak_f32 v4, v3, v4, 0x3f35f0e3
	v_fmaak_f32 v4, v3, v4, 0xbe11a98e
	v_fmaak_f32 v4, v3, v4, 0x3e027906
	v_mul_f32_e32 v3, v3, v4
	v_mul_f32_e32 v3, v5, v3
	v_mul_f32_e32 v4, v3, v2
	v_fma_f32 v3, -v3, v2, v2
	v_cmp_gt_f32_e32 vcc, 0, v2
	s_waitcnt vmcnt(0)
	v_lshlrev_b32_e32 v2, 16, v9
	v_mul_f32_e32 v5, v2, v2
	v_cndmask_b32_e32 v105, v3, v4, vcc
	v_fma_f32 v3, |v2|, s92, 1.0
	v_rcp_f32_e32 v3, v3
	v_mul_f32_e32 v5, 0xbf38aa3b, v5
	v_exp_f32_e32 v5, v5
	v_cmp_gt_f32_e32 vcc, 0, v2
	v_fmamk_f32 v4, v3, 0x3f07dc22, v236
	v_fmaak_f32 v4, v3, v4, 0x3f35f0e3
	v_fmaak_f32 v4, v3, v4, 0xbe11a98e
	v_fmaak_f32 v4, v3, v4, 0x3e027906
	v_mul_f32_e32 v3, v3, v4
	v_mul_f32_e32 v3, v5, v3
	v_mul_f32_e32 v4, v3, v2
	v_fma_f32 v3, -v3, v2, v2
	v_cndmask_b32_e32 v106, v3, v4, vcc
	global_load_ushort v2, v[90:91], off offset:2048
	global_load_ushort v3, v[92:93], off
	global_load_ushort v4, v[94:95], off offset:2048
	global_load_ushort v5, v[96:97], off
	global_load_ushort v6, v[98:99], off offset:2048
	s_waitcnt vmcnt(4)
	v_lshlrev_b32_e32 v2, 16, v2
	v_fma_f32 v7, |v2|, s92, 1.0
	v_rcp_f32_e32 v7, v7
	v_mul_f32_e32 v9, v2, v2
	v_mul_f32_e32 v9, 0xbf38aa3b, v9
	v_exp_f32_e32 v9, v9
	v_fmamk_f32 v8, v7, 0x3f07dc22, v236
	v_fmaak_f32 v8, v7, v8, 0x3f35f0e3
	v_fmaak_f32 v8, v7, v8, 0xbe11a98e
	v_fmaak_f32 v8, v7, v8, 0x3e027906
	v_mul_f32_e32 v7, v7, v8
	v_mul_f32_e32 v7, v9, v7
	v_mul_f32_e32 v8, v7, v2
	v_fma_f32 v7, -v7, v2, v2
	v_cmp_gt_f32_e32 vcc, 0, v2
	s_waitcnt vmcnt(3)
	v_lshlrev_b32_e32 v2, 16, v3
	v_fma_f32 v3, |v2|, s92, 1.0
	v_rcp_f32_e32 v3, v3
	v_cndmask_b32_e32 v107, v7, v8, vcc
	v_mul_f32_e32 v8, v2, v2
	v_mul_f32_e32 v8, 0xbf38aa3b, v8
	v_fmamk_f32 v7, v3, 0x3f07dc22, v236
	v_fmaak_f32 v7, v3, v7, 0x3f35f0e3
	v_exp_f32_e32 v8, v8
	v_fmaak_f32 v7, v3, v7, 0xbe11a98e
	v_fmaak_f32 v7, v3, v7, 0x3e027906
	v_mul_f32_e32 v3, v3, v7
	v_mul_f32_e32 v3, v8, v3
	v_mul_f32_e32 v7, v3, v2
	v_fma_f32 v3, -v3, v2, v2
	v_cmp_gt_f32_e32 vcc, 0, v2
	s_waitcnt vmcnt(2)
	v_lshlrev_b32_e32 v2, 16, v4
	v_mfma_f32_32x32x16_bf16 v[8:23], v[18:21], v[62:65], 0
	v_cndmask_b32_e32 v108, v3, v7, vcc
	v_fma_f32 v3, |v2|, s92, 1.0
	v_rcp_f32_e32 v3, v3
	v_mul_f32_e32 v7, v2, v2
	v_mul_f32_e32 v7, 0xbf38aa3b, v7
	v_exp_f32_e32 v7, v7
	v_fmamk_f32 v4, v3, 0x3f07dc22, v236
	v_fmaak_f32 v4, v3, v4, 0x3f35f0e3
	v_fmaak_f32 v4, v3, v4, 0xbe11a98e
	v_fmaak_f32 v4, v3, v4, 0x3e027906
	v_mul_f32_e32 v3, v3, v4
	v_mul_f32_e32 v3, v7, v3
	v_mul_f32_e32 v4, v3, v2
	v_fma_f32 v3, -v3, v2, v2
	v_cmp_gt_f32_e32 vcc, 0, v2
	s_waitcnt vmcnt(1)
	v_lshlrev_b32_e32 v2, 16, v5
	v_mul_f32_e32 v5, v2, v2
	v_cndmask_b32_e32 v109, v3, v4, vcc
	v_fma_f32 v3, |v2|, s92, 1.0
	v_rcp_f32_e32 v3, v3
	v_mul_f32_e32 v5, 0xbf38aa3b, v5
	v_exp_f32_e32 v5, v5
	v_cmp_gt_f32_e32 vcc, 0, v2
	v_fmamk_f32 v4, v3, 0x3f07dc22, v236
	v_fmaak_f32 v4, v3, v4, 0x3f35f0e3
	v_fmaak_f32 v4, v3, v4, 0xbe11a98e
	v_fmaak_f32 v4, v3, v4, 0x3e027906
	v_mul_f32_e32 v3, v3, v4
	v_mul_f32_e32 v3, v5, v3
	v_mul_f32_e32 v4, v3, v2
	v_fma_f32 v3, -v3, v2, v2
	s_waitcnt vmcnt(0)
	v_lshlrev_b32_e32 v2, 16, v6
	v_cndmask_b32_e32 v110, v3, v4, vcc
	v_fma_f32 v3, |v2|, s92, 1.0
	v_rcp_f32_e32 v3, v3
	v_mul_f32_e32 v5, v2, v2
	v_mul_f32_e32 v5, 0xbf38aa3b, v5
	v_mfma_f32_32x32x16_bf16 v[8:23], v[78:81], v[58:61], v[8:23]
	v_fmamk_f32 v4, v3, 0x3f07dc22, v236
	v_fmaak_f32 v4, v3, v4, 0x3f35f0e3
	v_exp_f32_e32 v5, v5
	v_fmaak_f32 v4, v3, v4, 0xbe11a98e
	v_fmaak_f32 v4, v3, v4, 0x3e027906
	v_mul_f32_e32 v3, v3, v4
	v_mul_f32_e32 v3, v5, v3
	v_mul_f32_e32 v4, v3, v2
	v_fma_f32 v3, -v3, v2, v2
	v_cmp_gt_f32_e32 vcc, 0, v2
	v_mfma_f32_32x32x16_bf16 v[8:23], v[74:77], v[54:57], v[8:23]
	s_nop 0
	v_cndmask_b32_e32 v111, v3, v4, vcc
	global_load_dwordx4 v[2:5], v[86:87], off offset:-4096
	v_mfma_f32_32x32x16_bf16 v[8:23], v[70:73], v[50:53], v[8:23]
	v_mfma_f32_32x32x16_bf16 v[8:23], v[66:69], v[46:49], v[8:23]
	global_load_dwordx4 v[66:69], v[88:89], off offset:1024
	global_load_dwordx4 v[70:73], v[88:89], off offset:2048
	global_load_dwordx4 v[74:77], v[86:87], off
	global_load_dwordx4 v[78:81], v[86:87], off offset:1024
	s_nop 0
	global_load_dwordx4 v[88:91], v[86:87], off offset:2048
	global_load_dwordx4 v[92:95], v[86:87], off offset:3072
	ds_read_b128 v[96:99], v150 offset:256
	v_mfma_f32_32x32x16_bf16 v[8:23], v[30:33], v[42:45], v[8:23]
	ds_read_b128 v[30:33], v150 offset:288
	s_waitcnt lgkmcnt(1)
	s_nop 9
	v_add_f32_e32 v6, v8, v96
	v_mul_f32_e32 v6, v134, v6
	v_cvt_pk_bf16_f32 v8, v6, s0
	v_or_b32_e32 v6, s5, v1
	v_lshlrev_b32_e32 v130, 11, v6
	v_lshl_add_u64 v[6:7], v[84:85], 0, v[130:131]
	global_store_short v[6:7], v8, off
	v_add_f32_e32 v6, v9, v97
	v_mul_f32_e32 v6, v135, v6
	v_readlane_b32 s5, v252, 63
	v_cvt_pk_bf16_f32 v8, v6, s0
	s_nop 0
	v_or_b32_e32 v6, s5, v1
	v_lshlrev_b32_e32 v130, 11, v6
	v_lshl_add_u64 v[6:7], v[84:85], 0, v[130:131]
	global_store_short v[6:7], v8, off
	v_add_f32_e32 v6, v10, v98
	v_mul_f32_e32 v6, v136, v6
	v_readlane_b32 s5, v253, 0
	v_cvt_pk_bf16_f32 v8, v6, s0
	s_nop 0
	v_or_b32_e32 v6, s5, v1
	v_lshlrev_b32_e32 v130, 11, v6
	v_lshl_add_u64 v[6:7], v[84:85], 0, v[130:131]
	global_store_short v[6:7], v8, off
	v_add_f32_e32 v6, v11, v99
	v_mul_f32_e32 v6, v137, v6
	v_readlane_b32 s5, v253, 1
	v_cvt_pk_bf16_f32 v8, v6, s0
	ds_read_b128 v[96:99], v150 offset:352
	v_or_b32_e32 v6, s5, v1
	v_lshlrev_b32_e32 v130, 11, v6
	v_lshl_add_u64 v[6:7], v[84:85], 0, v[130:131]
	global_store_short v[6:7], v8, off
	s_waitcnt lgkmcnt(1)
	v_add_f32_e32 v6, v12, v30
	v_mul_f32_e32 v6, v138, v6
	v_readlane_b32 s5, v253, 2
	v_cvt_pk_bf16_f32 v8, v6, s0
	s_nop 0
	v_or_b32_e32 v6, s5, v1
	v_lshlrev_b32_e32 v130, 11, v6
	v_lshl_add_u64 v[6:7], v[84:85], 0, v[130:131]
	global_store_short v[6:7], v8, off
	v_add_f32_e32 v6, v13, v31
	v_mul_f32_e32 v6, v139, v6
	v_readlane_b32 s5, v253, 3
	v_cvt_pk_bf16_f32 v8, v6, s0
	s_nop 0
	v_or_b32_e32 v6, s5, v1
	v_lshlrev_b32_e32 v130, 11, v6
	v_lshl_add_u64 v[6:7], v[84:85], 0, v[130:131]
	global_store_short v[6:7], v8, off
	v_add_f32_e32 v6, v14, v32
	v_mul_f32_e32 v6, v140, v6
	v_readlane_b32 s5, v253, 4
	v_cvt_pk_bf16_f32 v8, v6, s0
	s_nop 0
	v_or_b32_e32 v6, s5, v1
	v_lshlrev_b32_e32 v130, 11, v6
	v_lshl_add_u64 v[6:7], v[84:85], 0, v[130:131]
	global_store_short v[6:7], v8, off
	v_add_f32_e32 v6, v15, v33
	ds_read_b128 v[30:33], v150 offset:320
	v_mul_f32_e32 v6, v141, v6
	v_readlane_b32 s5, v253, 5
	v_cvt_pk_bf16_f32 v8, v6, s0
	s_waitcnt lgkmcnt(0)
	v_add_f32_e32 v18, v18, v32
	v_or_b32_e32 v6, s5, v1
	v_lshlrev_b32_e32 v130, 11, v6
	v_lshl_add_u64 v[6:7], v[84:85], 0, v[130:131]
	global_store_short v[6:7], v8, off
	v_add_f32_e32 v6, v16, v30
	v_mul_f32_e32 v6, v122, v6
	v_readlane_b32 s5, v253, 6
	v_cvt_pk_bf16_f32 v8, v6, s0
	v_mul_f32_e32 v18, v124, v18
	v_or_b32_e32 v6, s5, v1
	v_lshlrev_b32_e32 v130, 11, v6
	v_lshl_add_u64 v[6:7], v[84:85], 0, v[130:131]
	global_store_short v[6:7], v8, off
	v_add_f32_e32 v6, v17, v31
	v_mul_f32_e32 v30, v123, v6
	s_waitcnt vmcnt(15)
	v_mfma_f32_32x32x16_bf16 v[2:17], v[2:5], v[62:65], 0
	v_readlane_b32 s5, v253, 7
	v_cvt_pk_bf16_f32 v62, v30, s0
	v_cvt_pk_bf16_f32 v18, v18, s0
	v_or_b32_e32 v30, s5, v1
	v_lshlrev_b32_e32 v130, 11, v30
	v_lshl_add_u64 v[30:31], v[84:85], 0, v[130:131]
	v_readlane_b32 s5, v253, 8
	s_waitcnt vmcnt(14)
	v_mfma_f32_32x32x16_bf16 v[2:17], v[66:69], v[58:61], v[2:17]
	global_store_short v[30:31], v62, off
	v_or_b32_e32 v30, s5, v1
	v_lshlrev_b32_e32 v130, 11, v30
	v_lshl_add_u64 v[30:31], v[84:85], 0, v[130:131]
	global_store_short v[30:31], v18, off
	v_add_f32_e32 v18, v19, v33
	v_mul_f32_e32 v18, v125, v18
	s_waitcnt vmcnt(15)
	v_mfma_f32_32x32x16_bf16 v[2:17], v[70:73], v[54:57], v[2:17]
	v_readlane_b32 s5, v253, 9
	v_cvt_pk_bf16_f32 v30, v18, s0
	s_nop 0
	v_or_b32_e32 v18, s5, v1
	v_lshlrev_b32_e32 v130, 11, v18
	v_lshl_add_u64 v[18:19], v[84:85], 0, v[130:131]
	global_store_short v[18:19], v30, off
	v_mfma_f32_32x32x16_bf16 v[2:17], v[24:27], v[50:53], v[2:17]
	v_add_f32_e32 v18, v20, v96
	v_mul_f32_e32 v18, v126, v18
	v_readlane_b32 s5, v253, 10
	v_cvt_pk_bf16_f32 v20, v18, s0
	s_nop 0
	v_or_b32_e32 v18, s5, v1
	v_lshlrev_b32_e32 v130, 11, v18
	s_waitcnt vmcnt(15)
	v_mfma_f32_32x32x16_bf16 v[2:17], v[74:77], v[46:49], v[2:17]
	v_lshl_add_u64 v[18:19], v[84:85], 0, v[130:131]
	global_store_short v[18:19], v20, off
	v_add_f32_e32 v18, v21, v97
	v_mul_f32_e32 v18, v127, v18
	v_readlane_b32 s5, v253, 11
	v_cvt_pk_bf16_f32 v20, v18, s0
	s_waitcnt vmcnt(15)
	v_mfma_f32_32x32x16_bf16 v[2:17], v[78:81], v[42:45], v[2:17]
	v_or_b32_e32 v18, s5, v1
	v_lshlrev_b32_e32 v130, 11, v18
	v_lshl_add_u64 v[18:19], v[84:85], 0, v[130:131]
	global_store_short v[18:19], v20, off
	v_add_f32_e32 v18, v22, v98
	v_mul_f32_e32 v18, v128, v18
	v_readlane_b32 s5, v253, 12
	s_waitcnt vmcnt(15)
	v_mfma_f32_32x32x16_bf16 v[2:17], v[88:91], v[38:41], v[2:17]
	v_cvt_pk_bf16_f32 v20, v18, s0
	v_or_b32_e32 v18, s5, v1
	v_lshlrev_b32_e32 v130, 11, v18
	v_lshl_add_u64 v[18:19], v[84:85], 0, v[130:131]
	global_store_short v[18:19], v20, off
	v_add_f32_e32 v18, v23, v99
	v_mul_f32_e32 v18, v129, v18
	v_readlane_b32 s5, v253, 13
	v_cvt_pk_bf16_f32 v20, v18, s0
	s_waitcnt vmcnt(15)
	v_mfma_f32_32x32x16_bf16 v[2:17], v[92:95], v[34:37], v[2:17]
	v_or_b32_e32 v18, s5, v1
	v_lshlrev_b32_e32 v130, 11, v18
	v_lshl_add_u64 v[18:19], v[84:85], 0, v[130:131]
	global_store_short v[18:19], v20, off
	ds_read_b128 v[18:21], v150 offset:384
	ds_read_b128 v[22:25], v150 offset:416
	v_readlane_b32 s5, v253, 14
	s_waitcnt lgkmcnt(1)
	s_nop 3
	v_add_f32_e32 v2, v2, v18
	v_or_b32_e32 v18, s5, v1
	v_mul_f32_e32 v2, v28, v2
	v_lshlrev_b32_e32 v130, 11, v18
	v_cvt_pk_bf16_f32 v2, v2, s0
	v_lshl_add_u64 v[26:27], v[84:85], 0, v[130:131]
	global_store_short v[26:27], v2, off
	v_add_f32_e32 v2, v3, v19
	v_mul_f32_e32 v2, v29, v2
	v_readlane_b32 s5, v253, 15
	v_cvt_pk_bf16_f32 v18, v2, s0
	s_nop 0
	v_or_b32_e32 v2, s5, v1
	v_lshlrev_b32_e32 v130, 11, v2
	v_lshl_add_u64 v[2:3], v[84:85], 0, v[130:131]
	global_store_short v[2:3], v18, off
	v_add_f32_e32 v2, v4, v20
	v_mul_f32_e32 v2, v82, v2
	v_readlane_b32 s5, v253, 16
	v_cvt_pk_bf16_f32 v4, v2, s0
	s_nop 0
	v_or_b32_e32 v2, s5, v1
	v_lshlrev_b32_e32 v130, 11, v2
	v_lshl_add_u64 v[2:3], v[84:85], 0, v[130:131]
	global_store_short v[2:3], v4, off
	v_add_f32_e32 v2, v5, v21
	v_mul_f32_e32 v2, v83, v2
	v_readlane_b32 s5, v253, 17
	v_cvt_pk_bf16_f32 v4, v2, s0
	s_nop 0
	v_or_b32_e32 v2, s5, v1
	v_lshlrev_b32_e32 v130, 11, v2
	v_lshl_add_u64 v[2:3], v[84:85], 0, v[130:131]
	global_store_short v[2:3], v4, off
	s_waitcnt lgkmcnt(0)
	v_add_f32_e32 v2, v6, v22
	v_mul_f32_e32 v2, v100, v2
	v_readlane_b32 s5, v253, 18
	v_cvt_pk_bf16_f32 v4, v2, s0
	s_nop 0
	v_or_b32_e32 v2, s5, v1
	v_lshlrev_b32_e32 v130, 11, v2
	v_lshl_add_u64 v[2:3], v[84:85], 0, v[130:131]
	global_store_short v[2:3], v4, off
	v_add_f32_e32 v2, v7, v23
	v_mul_f32_e32 v2, v101, v2
	v_readlane_b32 s5, v253, 19
	v_cvt_pk_bf16_f32 v4, v2, s0
	s_nop 0
	v_or_b32_e32 v2, s5, v1
	v_lshlrev_b32_e32 v130, 11, v2
	v_lshl_add_u64 v[2:3], v[84:85], 0, v[130:131]
	global_store_short v[2:3], v4, off
	v_add_f32_e32 v2, v8, v24
	v_mul_f32_e32 v2, v102, v2
	v_readlane_b32 s5, v253, 20
	v_cvt_pk_bf16_f32 v4, v2, s0
	s_nop 0
	v_or_b32_e32 v2, s5, v1
	v_lshlrev_b32_e32 v130, 11, v2
	v_lshl_add_u64 v[2:3], v[84:85], 0, v[130:131]
	global_store_short v[2:3], v4, off
	v_add_f32_e32 v2, v9, v25
	v_mul_f32_e32 v2, v103, v2
	v_cvt_pk_bf16_f32 v8, v2, s0
	ds_read_b128 v[2:5], v150 offset:448
	v_readlane_b32 s5, v253, 21
	s_nop 1
	v_or_b32_e32 v6, s5, v1
	v_lshlrev_b32_e32 v130, 11, v6
	v_lshl_add_u64 v[6:7], v[84:85], 0, v[130:131]
	v_readlane_b32 s5, v253, 22
	global_store_short v[6:7], v8, off
	ds_read_b128 v[6:9], v150 offset:480
	s_waitcnt lgkmcnt(1)
	v_add_f32_e32 v2, v10, v2
	v_or_b32_e32 v10, s5, v1
	v_mul_f32_e32 v2, v104, v2
	v_lshlrev_b32_e32 v130, 11, v10
	v_cvt_pk_bf16_f32 v2, v2, s0
	v_lshl_add_u64 v[18:19], v[84:85], 0, v[130:131]
	global_store_short v[18:19], v2, off
	v_add_f32_e32 v2, v11, v3
	v_mul_f32_e32 v2, v105, v2
	v_readlane_b32 s5, v253, 23
	v_cvt_pk_bf16_f32 v10, v2, s0
	s_nop 0
	v_or_b32_e32 v2, s5, v1
	v_lshlrev_b32_e32 v130, 11, v2
	v_lshl_add_u64 v[2:3], v[84:85], 0, v[130:131]
	global_store_short v[2:3], v10, off
	v_add_f32_e32 v2, v12, v4
	v_mul_f32_e32 v2, v106, v2
	v_readlane_b32 s5, v253, 24
	v_cvt_pk_bf16_f32 v4, v2, s0
	s_nop 0
	v_or_b32_e32 v2, s5, v1
	v_lshlrev_b32_e32 v130, 11, v2
	v_lshl_add_u64 v[2:3], v[84:85], 0, v[130:131]
	global_store_short v[2:3], v4, off
	v_add_f32_e32 v2, v13, v5
	v_mul_f32_e32 v2, v107, v2
	v_readlane_b32 s5, v253, 25
	v_cvt_pk_bf16_f32 v4, v2, s0
	s_nop 0
	v_or_b32_e32 v2, s5, v1
	v_lshlrev_b32_e32 v130, 11, v2
	v_lshl_add_u64 v[2:3], v[84:85], 0, v[130:131]
	global_store_short v[2:3], v4, off
	s_waitcnt lgkmcnt(0)
	v_add_f32_e32 v2, v14, v6
	v_mul_f32_e32 v2, v108, v2
	v_readlane_b32 s5, v253, 26
	v_cvt_pk_bf16_f32 v4, v2, s0
	s_nop 0
	v_or_b32_e32 v2, s5, v1
	v_lshlrev_b32_e32 v130, 11, v2
	v_lshl_add_u64 v[2:3], v[84:85], 0, v[130:131]
	global_store_short v[2:3], v4, off
	v_add_f32_e32 v2, v15, v7
	v_mul_f32_e32 v2, v109, v2
	v_readlane_b32 s5, v253, 27
	v_cvt_pk_bf16_f32 v4, v2, s0
	s_nop 0
	v_or_b32_e32 v2, s5, v1
	v_lshlrev_b32_e32 v130, 11, v2
	v_lshl_add_u64 v[2:3], v[84:85], 0, v[130:131]
	global_store_short v[2:3], v4, off
	v_add_f32_e32 v2, v16, v8
	v_mul_f32_e32 v2, v110, v2
	v_readlane_b32 s5, v253, 28
	v_cvt_pk_bf16_f32 v4, v2, s0
	s_nop 0
	v_or_b32_e32 v2, s5, v1
	v_lshlrev_b32_e32 v130, 11, v2
	v_lshl_add_u64 v[2:3], v[84:85], 0, v[130:131]
	v_readlane_b32 s5, v253, 29
	global_store_short v[2:3], v4, off
	v_add_f32_e32 v2, v17, v9
	v_or_b32_e32 v1, s5, v1
	v_mul_f32_e32 v2, v111, v2
	v_lshlrev_b32_e32 v130, 11, v1
	v_cvt_pk_bf16_f32 v4, v2, s0
	v_lshl_add_u64 v[2:3], v[84:85], 0, v[130:131]
	global_store_short v[2:3], v4, off
	s_barrier

.LBB0_319:
	s_add_i32 s65, s6, 32
	s_add_i32 s6, s6, 64
	s_cmpk_lt_i32 s65, 0x1e0
	s_cselect_b32 s6, s6, s65
	s_lshl_b32 s6, s6, 6
	s_and_b32 s8, s6, 0xfc0
	s_sub_i32 s8, s8, 30
	s_add_i32 s9, s8, s63
	s_and_b32 s6, s6, 0xfffff000
	s_max_i32 s9, s9, 0
	s_add_i32 s66, s9, s6
	s_add_i32 s9, s8, s62
	s_max_i32 s9, s9, 0
	s_add_i32 s67, s9, s6
	s_add_i32 s9, s8, s61
	s_max_i32 s9, s9, 0
	s_add_i32 s68, s9, s6
	s_add_i32 s9, s8, s60
	s_max_i32 s9, s9, 0
	s_add_i32 s69, s9, s6
	s_add_i32 s9, s8, s59
	s_max_i32 s9, s9, 0
	s_add_i32 s72, s9, s6
	s_add_i32 s9, s8, s58
	s_max_i32 s9, s9, 0
	s_add_i32 s73, s9, s6
	s_add_i32 s9, s8, s41
	s_max_i32 s9, s9, 0
	s_add_i32 s84, s9, s6
	s_add_i32 s9, s8, s40
	s_max_i32 s9, s9, 0
	s_add_i32 s85, s9, s6
	s_add_i32 s9, s8, s34
	s_max_i32 s9, s9, 0
	s_add_i32 s88, s9, s6
	s_add_i32 s9, s8, s29
	s_max_i32 s9, s9, 0
	s_add_i32 s89, s9, s6
	s_add_i32 s9, s8, s28
	s_add_i32 s8, s8, s5
	s_max_i32 s9, s9, 0
	s_max_i32 s8, s8, 0
	s_add_i32 s94, s9, s6
	s_add_i32 s95, s8, s6
	s_lshl_b32 s6, s42, 7
	s_add_i32 s8, s64, s7
	s_and_b32 s6, s6, 0xffff8000
	s_sub_i32 s10, s8, 56
	s_add_i32 vcc_lo, s6, 0
	s_lshl_b32 s6, s7, 10
	s_ashr_i32 s11, s10, 31
	s_add_i32 s6, s6, 0
	s_lshl_b64 s[10:11], s[10:11], 11
	s_add_u32 s56, s76, s10
	s_addc_u32 s57, s77, s11
	s_sub_i32 s10, s8, 48
	s_ashr_i32 s11, s10, 31
	s_lshl_b64 s[10:11], s[10:11], 11
	s_add_u32 s54, s76, s10
	s_addc_u32 s55, s77, s11
	s_sub_i32 s10, s8, 40
	s_ashr_i32 s11, s10, 31
	s_lshl_b64 s[10:11], s[10:11], 11
	s_add_u32 s52, s76, s10
	s_addc_u32 s53, s77, s11
	s_sub_i32 s10, s8, 32
	s_ashr_i32 s11, s10, 31
	s_lshl_b64 s[10:11], s[10:11], 11
	s_add_u32 s50, s76, s10
	s_addc_u32 s51, s77, s11
	s_sub_i32 s10, s8, 24
	s_ashr_i32 s11, s10, 31
	s_lshl_b64 s[10:11], s[10:11], 11
	s_add_u32 s48, s76, s10
	s_addc_u32 s49, s77, s11
	s_add_i32 s10, s8, -16
	s_ashr_i32 s11, s10, 31
	s_lshl_b64 s[10:11], s[10:11], 11
	s_add_u32 s46, s76, s10
	s_addc_u32 s47, s77, s11
	s_add_i32 s10, s8, -8
	s_ashr_i32 s11, s10, 31
	s_lshl_b64 s[10:11], s[10:11], 11
	s_add_u32 s44, s76, s10
	s_addc_u32 s45, s77, s11
	s_ashr_i32 s9, s8, 31
	s_lshl_b64 s[8:9], s[8:9], 11
	s_add_u32 s42, s76, s8
	v_and_b32_e32 v12, 0xff, v10
	s_addc_u32 s43, s77, s9
	v_mad_i64_i32 v[10:11], s[8:9], s66, v238, v[102:103]
	s_waitcnt lgkmcnt(0)
	s_barrier
	global_load_dwordx2 v[152:153], v[10:11], off offset:1024
	global_load_dwordx2 v[154:155], v[10:11], off offset:1536
	v_mad_i64_i32 v[10:11], s[8:9], s67, v238, v[102:103]
	global_load_dwordx2 v[148:149], v[10:11], off offset:1024
	global_load_dwordx2 v[150:151], v[10:11], off offset:1536
	v_mad_i64_i32 v[10:11], s[8:9], s68, v238, v[102:103]
	global_load_dwordx2 v[144:145], v[10:11], off offset:1024
	global_load_dwordx2 v[146:147], v[10:11], off offset:1536
	v_mad_i64_i32 v[10:11], s[8:9], s69, v238, v[102:103]
	global_load_dwordx2 v[140:141], v[10:11], off offset:1024
	global_load_dwordx2 v[142:143], v[10:11], off offset:1536
	v_mad_i64_i32 v[10:11], s[8:9], s72, v238, v[102:103]
	global_load_dwordx2 v[136:137], v[10:11], off offset:1024
	global_load_dwordx2 v[138:139], v[10:11], off offset:1536
	v_mad_i64_i32 v[10:11], s[8:9], s73, v238, v[102:103]
	global_load_dwordx2 v[132:133], v[10:11], off offset:1024
	global_load_dwordx2 v[134:135], v[10:11], off offset:1536
	v_mad_i64_i32 v[10:11], s[8:9], s84, v238, v[102:103]
	global_load_dwordx2 v[126:127], v[10:11], off offset:1024
	global_load_dwordx2 v[128:129], v[10:11], off offset:1536
	v_mad_i64_i32 v[10:11], s[8:9], s85, v238, v[102:103]
	global_load_dwordx2 v[122:123], v[10:11], off offset:1024
	global_load_dwordx2 v[124:125], v[10:11], off offset:1536
	v_mad_i64_i32 v[10:11], s[8:9], s88, v238, v[102:103]
	global_load_dwordx2 v[118:119], v[10:11], off offset:1024
	global_load_dwordx2 v[120:121], v[10:11], off offset:1536
	v_mad_i64_i32 v[10:11], s[8:9], s89, v238, v[102:103]
	global_load_dwordx2 v[114:115], v[10:11], off offset:1024
	global_load_dwordx2 v[116:117], v[10:11], off offset:1536
	v_mad_i64_i32 v[10:11], s[8:9], s94, v238, v[102:103]
	global_load_dwordx2 v[110:111], v[10:11], off offset:1024
	global_load_dwordx2 v[112:113], v[10:11], off offset:1536
	v_mad_i64_i32 v[10:11], s[8:9], s95, v238, v[102:103]
	v_lshl_add_u32 v163, v12, 2, vcc_lo
	global_load_dwordx2 v[106:107], v[10:11], off offset:1024
	global_load_dwordx2 v[108:109], v[10:11], off offset:1536
	ds_read2st64_b32 v[26:27], v163 offset1:4
	ds_read2st64_b32 v[28:29], v163 offset0:8 offset1:12
	ds_read2st64_b32 v[30:31], v163 offset0:16 offset1:20
	ds_read2st64_b32 v[32:33], v163 offset0:24 offset1:28
	ds_read2st64_b32 v[160:161], v163 offset0:32 offset1:36
	ds_read2st64_b32 v[158:159], v163 offset0:40 offset1:44
	ds_read2st64_b32 v[156:157], v163 offset0:48 offset1:52
	ds_read2st64_b32 v[40:41], v163 offset0:56 offset1:60
	ds_read2st64_b32 v[38:39], v163 offset0:64 offset1:68
	ds_read2st64_b32 v[36:37], v163 offset0:72 offset1:76
	ds_read2st64_b32 v[34:35], v163 offset0:80 offset1:84
	ds_read2st64_b32 v[24:25], v163 offset0:88 offset1:92
	ds_read2st64_b32 v[22:23], v163 offset0:96 offset1:100
	ds_read2st64_b32 v[20:21], v163 offset0:104 offset1:108
	ds_read2st64_b32 v[18:19], v163 offset0:112 offset1:116
	ds_read2st64_b32 v[10:11], v163 offset0:120 offset1:124
	ds_read2st64_b32 v[12:13], v163 offset0:128 offset1:132
	ds_read2st64_b32 v[14:15], v163 offset0:136 offset1:140
	ds_read2st64_b32 v[16:17], v163 offset0:144 offset1:148
	s_waitcnt lgkmcnt(14)
	v_mul_f32_e32 v165, v42, v27
	s_waitcnt vmcnt(51) lgkmcnt(3)
	v_mul_f32_e32 v105, v101, v10
	s_waitcnt vmcnt(24)
	v_mov_b32_e32 v164, v104
	v_pk_fma_f32 v[26:27], v[42:43], v[26:27], v[104:105]
	v_pk_fma_f32 v[164:165], v[44:45], v[28:29], v[164:165]
	v_pk_fma_f32 v[26:27], v[46:47], v[28:29], v[26:27]
	v_pk_fma_f32 v[164:165], v[48:49], v[30:31], v[164:165]
	v_pk_fma_f32 v[26:27], v[50:51], v[30:31], v[26:27]
	v_pk_fma_f32 v[164:165], v[52:53], v[32:33], v[164:165]
	v_pk_fma_f32 v[26:27], v[54:55], v[32:33], v[26:27]
	v_pk_fma_f32 v[164:165], v[56:57], v[160:161], v[164:165]
	v_pk_fma_f32 v[26:27], v[58:59], v[160:161], v[26:27]
	v_pk_fma_f32 v[164:165], v[60:61], v[158:159], v[164:165]
	v_pk_fma_f32 v[26:27], v[62:63], v[158:159], v[26:27]
	v_pk_fma_f32 v[164:165], v[64:65], v[156:157], v[164:165]
	v_pk_fma_f32 v[26:27], v[66:67], v[156:157], v[26:27]
	v_pk_fma_f32 v[164:165], v[68:69], v[40:41], v[164:165]
	v_pk_fma_f32 v[26:27], v[70:71], v[40:41], v[26:27]
	v_pk_fma_f32 v[164:165], v[72:73], v[38:39], v[164:165]
	v_pk_fma_f32 v[26:27], v[74:75], v[38:39], v[26:27]
	v_pk_fma_f32 v[164:165], v[76:77], v[36:37], v[164:165]
	v_pk_fma_f32 v[26:27], v[78:79], v[36:37], v[26:27]
	v_pk_fma_f32 v[164:165], v[80:81], v[34:35], v[164:165]
	v_pk_fma_f32 v[26:27], v[82:83], v[34:35], v[26:27]
	v_pk_fma_f32 v[164:165], v[84:85], v[24:25], v[164:165]
	v_pk_fma_f32 v[26:27], v[86:87], v[24:25], v[26:27]
	v_pk_fma_f32 v[164:165], v[88:89], v[22:23], v[164:165]
	v_pk_fma_f32 v[26:27], v[90:91], v[22:23], v[26:27]
	v_pk_fma_f32 v[164:165], v[92:93], v[20:21], v[164:165]
	v_pk_fma_f32 v[26:27], v[94:95], v[20:21], v[26:27]
	v_pk_fma_f32 v[164:165], v[96:97], v[18:19], v[164:165]
	v_pk_fma_f32 v[26:27], v[98:99], v[18:19], v[26:27]
	v_pk_fma_f32 v[166:167], v[100:101], v[10:11], v[164:165]
	v_add_f32_e32 v164, v26, v27
	v_mul_f32_e32 v27, v42, v29
	v_mov_b32_e32 v26, v104
	v_pk_fma_f32 v[26:27], v[44:45], v[30:31], v[26:27]
	s_waitcnt lgkmcnt(2)
	v_mul_f32_e32 v105, v101, v12
	v_pk_fma_f32 v[26:27], v[48:49], v[32:33], v[26:27]
	v_pk_fma_f32 v[28:29], v[42:43], v[28:29], v[104:105]
	v_pk_fma_f32 v[26:27], v[52:53], v[160:161], v[26:27]
	v_pk_fma_f32 v[28:29], v[46:47], v[30:31], v[28:29]
	v_pk_fma_f32 v[26:27], v[56:57], v[158:159], v[26:27]
	v_pk_fma_f32 v[28:29], v[50:51], v[32:33], v[28:29]
	v_pk_fma_f32 v[26:27], v[60:61], v[156:157], v[26:27]
	v_pk_fma_f32 v[28:29], v[54:55], v[160:161], v[28:29]
	v_pk_fma_f32 v[26:27], v[64:65], v[40:41], v[26:27]
	v_pk_fma_f32 v[28:29], v[58:59], v[158:159], v[28:29]
	v_pk_fma_f32 v[26:27], v[68:69], v[38:39], v[26:27]
	v_pk_fma_f32 v[28:29], v[62:63], v[156:157], v[28:29]
	v_pk_fma_f32 v[26:27], v[72:73], v[36:37], v[26:27]
	v_pk_fma_f32 v[28:29], v[66:67], v[40:41], v[28:29]
	v_pk_fma_f32 v[26:27], v[76:77], v[34:35], v[26:27]
	v_pk_fma_f32 v[28:29], v[70:71], v[38:39], v[28:29]
	v_pk_fma_f32 v[26:27], v[80:81], v[24:25], v[26:27]
	v_pk_fma_f32 v[28:29], v[74:75], v[36:37], v[28:29]
	v_pk_fma_f32 v[26:27], v[84:85], v[22:23], v[26:27]
	v_pk_fma_f32 v[28:29], v[78:79], v[34:35], v[28:29]
	v_pk_fma_f32 v[26:27], v[88:89], v[20:21], v[26:27]
	v_pk_fma_f32 v[28:29], v[82:83], v[24:25], v[28:29]
	v_pk_fma_f32 v[26:27], v[92:93], v[18:19], v[26:27]
	v_pk_fma_f32 v[28:29], v[86:87], v[22:23], v[28:29]
	v_pk_fma_f32 v[26:27], v[96:97], v[10:11], v[26:27]
	v_pk_fma_f32 v[28:29], v[90:91], v[20:21], v[28:29]
	v_pk_fma_f32 v[26:27], v[100:101], v[12:13], v[26:27]
	v_add_f32_e32 v165, v166, v167
	v_pk_fma_f32 v[28:29], v[94:95], v[18:19], v[28:29]
	v_add_f32_e32 v167, v26, v27
	v_mul_f32_e32 v27, v42, v31
	v_mov_b32_e32 v26, v104
	v_pk_fma_f32 v[28:29], v[98:99], v[10:11], v[28:29]
	s_waitcnt lgkmcnt(1)
	v_mul_f32_e32 v105, v101, v14
	v_pk_fma_f32 v[26:27], v[44:45], v[32:33], v[26:27]
	v_add_f32_e32 v166, v28, v29
	v_pk_fma_f32 v[28:29], v[42:43], v[30:31], v[104:105]
	v_pk_fma_f32 v[26:27], v[48:49], v[160:161], v[26:27]
	v_pk_fma_f32 v[28:29], v[46:47], v[32:33], v[28:29]
	v_pk_fma_f32 v[26:27], v[52:53], v[158:159], v[26:27]
	v_pk_fma_f32 v[28:29], v[50:51], v[160:161], v[28:29]
	v_pk_fma_f32 v[26:27], v[56:57], v[156:157], v[26:27]
	v_pk_fma_f32 v[28:29], v[54:55], v[158:159], v[28:29]
	v_pk_fma_f32 v[26:27], v[60:61], v[40:41], v[26:27]
	v_pk_fma_f32 v[28:29], v[58:59], v[156:157], v[28:29]
	v_pk_fma_f32 v[26:27], v[64:65], v[38:39], v[26:27]
	v_pk_fma_f32 v[28:29], v[62:63], v[40:41], v[28:29]
	v_pk_fma_f32 v[26:27], v[68:69], v[36:37], v[26:27]
	v_pk_fma_f32 v[28:29], v[66:67], v[38:39], v[28:29]
	v_pk_fma_f32 v[26:27], v[72:73], v[34:35], v[26:27]
	v_pk_fma_f32 v[28:29], v[70:71], v[36:37], v[28:29]
	v_pk_fma_f32 v[26:27], v[76:77], v[24:25], v[26:27]
	v_pk_fma_f32 v[28:29], v[74:75], v[34:35], v[28:29]
	v_pk_fma_f32 v[26:27], v[80:81], v[22:23], v[26:27]
	v_pk_fma_f32 v[28:29], v[78:79], v[24:25], v[28:29]
	v_pk_fma_f32 v[26:27], v[84:85], v[20:21], v[26:27]
	v_pk_fma_f32 v[28:29], v[82:83], v[22:23], v[28:29]
	v_pk_fma_f32 v[26:27], v[88:89], v[18:19], v[26:27]
	v_pk_fma_f32 v[28:29], v[86:87], v[20:21], v[28:29]
	v_pk_fma_f32 v[26:27], v[92:93], v[10:11], v[26:27]
	v_pk_fma_f32 v[28:29], v[90:91], v[18:19], v[28:29]
	v_pk_fma_f32 v[26:27], v[96:97], v[12:13], v[26:27]
	v_pk_fma_f32 v[28:29], v[94:95], v[10:11], v[28:29]
	v_pk_fma_f32 v[26:27], v[100:101], v[14:15], v[26:27]
	v_pk_fma_f32 v[28:29], v[98:99], v[12:13], v[28:29]
	v_add_f32_e32 v169, v26, v27
	s_waitcnt lgkmcnt(0)
	v_mul_f32_e32 v105, v101, v16
	v_mul_f32_e32 v27, v42, v33
	v_mov_b32_e32 v26, v104
	v_add_f32_e32 v168, v28, v29
	v_pk_fma_f32 v[28:29], v[42:43], v[32:33], v[104:105]
	v_pk_fma_f32 v[26:27], v[44:45], v[160:161], v[26:27]
	v_pk_fma_f32 v[28:29], v[46:47], v[160:161], v[28:29]
	v_pk_fma_f32 v[26:27], v[48:49], v[158:159], v[26:27]
	v_pk_fma_f32 v[28:29], v[50:51], v[158:159], v[28:29]
	v_pk_fma_f32 v[26:27], v[52:53], v[156:157], v[26:27]
	v_pk_fma_f32 v[28:29], v[54:55], v[156:157], v[28:29]
	v_pk_fma_f32 v[26:27], v[56:57], v[40:41], v[26:27]
	v_pk_fma_f32 v[28:29], v[58:59], v[40:41], v[28:29]
	v_pk_fma_f32 v[26:27], v[60:61], v[38:39], v[26:27]
	v_pk_fma_f32 v[28:29], v[62:63], v[38:39], v[28:29]
	v_pk_fma_f32 v[26:27], v[64:65], v[36:37], v[26:27]
	v_pk_fma_f32 v[28:29], v[66:67], v[36:37], v[28:29]
	v_pk_fma_f32 v[26:27], v[68:69], v[34:35], v[26:27]
	v_pk_fma_f32 v[28:29], v[70:71], v[34:35], v[28:29]
	v_pk_fma_f32 v[26:27], v[72:73], v[24:25], v[26:27]
	v_pk_fma_f32 v[28:29], v[74:75], v[24:25], v[28:29]
	v_pk_fma_f32 v[26:27], v[76:77], v[22:23], v[26:27]
	v_pk_fma_f32 v[28:29], v[78:79], v[22:23], v[28:29]
	v_pk_fma_f32 v[26:27], v[80:81], v[20:21], v[26:27]
	v_pk_fma_f32 v[28:29], v[82:83], v[20:21], v[28:29]
	v_pk_fma_f32 v[26:27], v[84:85], v[18:19], v[26:27]
	v_pk_fma_f32 v[28:29], v[86:87], v[18:19], v[28:29]
	v_pk_fma_f32 v[26:27], v[88:89], v[10:11], v[26:27]
	v_pk_fma_f32 v[28:29], v[90:91], v[10:11], v[28:29]
	v_pk_fma_f32 v[26:27], v[92:93], v[12:13], v[26:27]
	v_pk_fma_f32 v[28:29], v[94:95], v[12:13], v[28:29]
	v_pk_fma_f32 v[26:27], v[96:97], v[14:15], v[26:27]
	v_pk_fma_f32 v[28:29], v[98:99], v[14:15], v[28:29]
	v_pk_fma_f32 v[26:27], v[100:101], v[16:17], v[26:27]
	v_add_f32_e32 v170, v28, v29
	v_add_f32_e32 v171, v26, v27
	ds_read2st64_b32 v[26:27], v163 offset0:152 offset1:156
	ds_read2st64_b32 v[28:29], v163 offset0:160 offset1:164
	ds_read2st64_b32 v[30:31], v163 offset0:168 offset1:172
	ds_read2st64_b32 v[32:33], v163 offset0:176 offset1:180
	v_mul_f32_e32 v173, v42, v161
	s_waitcnt lgkmcnt(3)
	v_mul_f32_e32 v105, v101, v26
	v_pk_fma_f32 v[160:161], v[42:43], v[160:161], v[104:105]
	v_mov_b32_e32 v172, v104
	v_pk_fma_f32 v[160:161], v[46:47], v[158:159], v[160:161]
	s_waitcnt lgkmcnt(2)
	v_mul_f32_e32 v105, v101, v28
	v_pk_fma_f32 v[160:161], v[50:51], v[156:157], v[160:161]
	v_pk_fma_f32 v[172:173], v[44:45], v[158:159], v[172:173]
	v_pk_fma_f32 v[160:161], v[54:55], v[40:41], v[160:161]
	v_pk_fma_f32 v[172:173], v[48:49], v[156:157], v[172:173]
	v_pk_fma_f32 v[160:161], v[58:59], v[38:39], v[160:161]
	v_pk_fma_f32 v[172:173], v[52:53], v[40:41], v[172:173]
	v_pk_fma_f32 v[160:161], v[62:63], v[36:37], v[160:161]
	v_pk_fma_f32 v[172:173], v[56:57], v[38:39], v[172:173]
	v_pk_fma_f32 v[160:161], v[66:67], v[34:35], v[160:161]
	v_pk_fma_f32 v[172:173], v[60:61], v[36:37], v[172:173]
	v_pk_fma_f32 v[160:161], v[70:71], v[24:25], v[160:161]
	v_pk_fma_f32 v[172:173], v[64:65], v[34:35], v[172:173]
	v_pk_fma_f32 v[160:161], v[74:75], v[22:23], v[160:161]
	v_pk_fma_f32 v[172:173], v[68:69], v[24:25], v[172:173]
	v_pk_fma_f32 v[160:161], v[78:79], v[20:21], v[160:161]
	v_pk_fma_f32 v[172:173], v[72:73], v[22:23], v[172:173]
	v_pk_fma_f32 v[160:161], v[82:83], v[18:19], v[160:161]
	v_pk_fma_f32 v[172:173], v[76:77], v[20:21], v[172:173]
	v_pk_fma_f32 v[160:161], v[86:87], v[10:11], v[160:161]
	v_pk_fma_f32 v[172:173], v[80:81], v[18:19], v[172:173]
	v_pk_fma_f32 v[160:161], v[90:91], v[12:13], v[160:161]
	v_pk_fma_f32 v[172:173], v[84:85], v[10:11], v[172:173]
	v_pk_fma_f32 v[160:161], v[94:95], v[14:15], v[160:161]
	v_pk_fma_f32 v[172:173], v[88:89], v[12:13], v[172:173]
	v_pk_fma_f32 v[160:161], v[98:99], v[16:17], v[160:161]
	v_pk_fma_f32 v[172:173], v[92:93], v[14:15], v[172:173]
	v_add_f32_e32 v174, v160, v161
	v_mul_f32_e32 v161, v42, v159
	v_pk_fma_f32 v[158:159], v[42:43], v[158:159], v[104:105]
	v_mov_b32_e32 v160, v104
	v_pk_fma_f32 v[158:159], v[46:47], v[156:157], v[158:159]
	s_waitcnt lgkmcnt(1)
	v_mul_f32_e32 v105, v101, v30
	v_pk_fma_f32 v[158:159], v[50:51], v[40:41], v[158:159]
	v_pk_fma_f32 v[160:161], v[44:45], v[156:157], v[160:161]
	v_pk_fma_f32 v[158:159], v[54:55], v[38:39], v[158:159]
	v_pk_fma_f32 v[160:161], v[48:49], v[40:41], v[160:161]
	v_pk_fma_f32 v[158:159], v[58:59], v[36:37], v[158:159]
	v_pk_fma_f32 v[160:161], v[52:53], v[38:39], v[160:161]
	v_pk_fma_f32 v[158:159], v[62:63], v[34:35], v[158:159]
	v_pk_fma_f32 v[160:161], v[56:57], v[36:37], v[160:161]
	v_pk_fma_f32 v[158:159], v[66:67], v[24:25], v[158:159]
	v_pk_fma_f32 v[160:161], v[60:61], v[34:35], v[160:161]
	v_pk_fma_f32 v[158:159], v[70:71], v[22:23], v[158:159]
	v_pk_fma_f32 v[160:161], v[64:65], v[24:25], v[160:161]
	v_pk_fma_f32 v[158:159], v[74:75], v[20:21], v[158:159]
	v_pk_fma_f32 v[160:161], v[68:69], v[22:23], v[160:161]
	v_pk_fma_f32 v[158:159], v[78:79], v[18:19], v[158:159]
	v_pk_fma_f32 v[160:161], v[72:73], v[20:21], v[160:161]
	v_pk_fma_f32 v[158:159], v[82:83], v[10:11], v[158:159]
	v_pk_fma_f32 v[160:161], v[76:77], v[18:19], v[160:161]
	v_pk_fma_f32 v[158:159], v[86:87], v[12:13], v[158:159]
	v_pk_fma_f32 v[160:161], v[80:81], v[10:11], v[160:161]
	v_pk_fma_f32 v[158:159], v[90:91], v[14:15], v[158:159]
	v_pk_fma_f32 v[160:161], v[84:85], v[12:13], v[160:161]
	v_pk_fma_f32 v[158:159], v[94:95], v[16:17], v[158:159]
	v_pk_fma_f32 v[160:161], v[88:89], v[14:15], v[160:161]
	v_pk_fma_f32 v[158:159], v[98:99], v[26:27], v[158:159]
	v_pk_fma_f32 v[160:161], v[92:93], v[16:17], v[160:161]
	v_add_f32_e32 v176, v158, v159
	v_mul_f32_e32 v159, v42, v157
	v_pk_fma_f32 v[156:157], v[42:43], v[156:157], v[104:105]
	v_mov_b32_e32 v158, v104
	v_pk_fma_f32 v[156:157], v[46:47], v[40:41], v[156:157]
	s_waitcnt lgkmcnt(0)
	v_mul_f32_e32 v105, v101, v32
	v_pk_fma_f32 v[156:157], v[50:51], v[38:39], v[156:157]
	v_pk_fma_f32 v[158:159], v[44:45], v[40:41], v[158:159]
	v_pk_fma_f32 v[156:157], v[54:55], v[36:37], v[156:157]
	v_pk_fma_f32 v[158:159], v[48:49], v[38:39], v[158:159]
	v_pk_fma_f32 v[156:157], v[58:59], v[34:35], v[156:157]
	v_pk_fma_f32 v[158:159], v[52:53], v[36:37], v[158:159]
	v_pk_fma_f32 v[156:157], v[62:63], v[24:25], v[156:157]
	v_pk_fma_f32 v[158:159], v[56:57], v[34:35], v[158:159]
	v_pk_fma_f32 v[156:157], v[66:67], v[22:23], v[156:157]
	v_pk_fma_f32 v[158:159], v[60:61], v[24:25], v[158:159]
	v_pk_fma_f32 v[156:157], v[70:71], v[20:21], v[156:157]
	v_pk_fma_f32 v[158:159], v[64:65], v[22:23], v[158:159]
	v_pk_fma_f32 v[156:157], v[74:75], v[18:19], v[156:157]
	v_pk_fma_f32 v[158:159], v[68:69], v[20:21], v[158:159]
	v_pk_fma_f32 v[156:157], v[78:79], v[10:11], v[156:157]
	v_pk_fma_f32 v[158:159], v[72:73], v[18:19], v[158:159]
	v_pk_fma_f32 v[156:157], v[82:83], v[12:13], v[156:157]
	v_pk_fma_f32 v[158:159], v[76:77], v[10:11], v[158:159]
	v_pk_fma_f32 v[156:157], v[86:87], v[14:15], v[156:157]
	v_pk_fma_f32 v[158:159], v[80:81], v[12:13], v[158:159]
	v_pk_fma_f32 v[156:157], v[90:91], v[16:17], v[156:157]
	v_pk_fma_f32 v[158:159], v[84:85], v[14:15], v[158:159]
	v_pk_fma_f32 v[156:157], v[94:95], v[26:27], v[156:157]
	v_pk_fma_f32 v[158:159], v[88:89], v[16:17], v[158:159]
	v_pk_fma_f32 v[156:157], v[98:99], v[28:29], v[156:157]
	v_pk_fma_f32 v[158:159], v[92:93], v[26:27], v[158:159]
	v_add_f32_e32 v178, v156, v157
	v_mul_f32_e32 v157, v42, v41
	v_mov_b32_e32 v156, v104
	v_pk_fma_f32 v[40:41], v[42:43], v[40:41], v[104:105]
	v_pk_fma_f32 v[156:157], v[44:45], v[38:39], v[156:157]
	v_pk_fma_f32 v[40:41], v[46:47], v[38:39], v[40:41]
	v_pk_fma_f32 v[156:157], v[48:49], v[36:37], v[156:157]
	v_pk_fma_f32 v[40:41], v[50:51], v[36:37], v[40:41]
	v_pk_fma_f32 v[156:157], v[52:53], v[34:35], v[156:157]
	v_pk_fma_f32 v[40:41], v[54:55], v[34:35], v[40:41]
	v_pk_fma_f32 v[156:157], v[56:57], v[24:25], v[156:157]
	v_pk_fma_f32 v[40:41], v[58:59], v[24:25], v[40:41]
	v_pk_fma_f32 v[156:157], v[60:61], v[22:23], v[156:157]
	v_pk_fma_f32 v[40:41], v[62:63], v[22:23], v[40:41]
	v_pk_fma_f32 v[156:157], v[64:65], v[20:21], v[156:157]
	v_pk_fma_f32 v[40:41], v[66:67], v[20:21], v[40:41]
	v_pk_fma_f32 v[156:157], v[68:69], v[18:19], v[156:157]
	v_pk_fma_f32 v[40:41], v[70:71], v[18:19], v[40:41]
	v_pk_fma_f32 v[156:157], v[72:73], v[10:11], v[156:157]
	v_pk_fma_f32 v[40:41], v[74:75], v[10:11], v[40:41]
	v_pk_fma_f32 v[156:157], v[76:77], v[12:13], v[156:157]
	v_pk_fma_f32 v[40:41], v[78:79], v[12:13], v[40:41]
	v_pk_fma_f32 v[156:157], v[80:81], v[14:15], v[156:157]
	v_pk_fma_f32 v[40:41], v[82:83], v[14:15], v[40:41]
	v_pk_fma_f32 v[156:157], v[84:85], v[16:17], v[156:157]
	v_pk_fma_f32 v[40:41], v[86:87], v[16:17], v[40:41]
	v_pk_fma_f32 v[156:157], v[88:89], v[26:27], v[156:157]
	v_pk_fma_f32 v[40:41], v[90:91], v[26:27], v[40:41]
	v_pk_fma_f32 v[156:157], v[92:93], v[28:29], v[156:157]
	v_pk_fma_f32 v[160:161], v[96:97], v[26:27], v[160:161]
	v_pk_fma_f32 v[158:159], v[96:97], v[28:29], v[158:159]
	v_pk_fma_f32 v[40:41], v[94:95], v[28:29], v[40:41]
	v_pk_fma_f32 v[156:157], v[96:97], v[30:31], v[156:157]
	v_pk_fma_f32 v[160:161], v[100:101], v[28:29], v[160:161]
	v_pk_fma_f32 v[158:159], v[100:101], v[30:31], v[158:159]
	v_pk_fma_f32 v[40:41], v[98:99], v[30:31], v[40:41]
	v_pk_fma_f32 v[156:157], v[100:101], v[32:33], v[156:157]
	v_add_f32_e32 v177, v160, v161
	v_add_f32_e32 v179, v158, v159
	v_add_f32_e32 v180, v40, v41
	v_add_f32_e32 v181, v156, v157
	ds_read2st64_b32 v[40:41], v163 offset0:184 offset1:188
	ds_read2st64_b32 v[156:157], v163 offset0:192 offset1:196
	ds_read2st64_b32 v[158:159], v163 offset0:200 offset1:204
	ds_read2st64_b32 v[160:161], v163 offset0:208 offset1:212
	v_pk_fma_f32 v[172:173], v[96:97], v[16:17], v[172:173]
	s_waitcnt lgkmcnt(3)
	v_mul_f32_e32 v105, v101, v40
	v_pk_fma_f32 v[172:173], v[100:101], v[26:27], v[172:173]
	s_addk_i32 s64, 0x800
	v_add_f32_e32 v175, v172, v173
	v_mul_f32_e32 v173, v42, v39
	v_pk_fma_f32 v[38:39], v[42:43], v[38:39], v[104:105]
	v_mov_b32_e32 v172, v104
	v_pk_fma_f32 v[38:39], v[46:47], v[36:37], v[38:39]
	s_waitcnt lgkmcnt(2)
	v_mul_f32_e32 v105, v101, v156
	v_pk_fma_f32 v[38:39], v[50:51], v[34:35], v[38:39]
	v_pk_fma_f32 v[172:173], v[44:45], v[36:37], v[172:173]
	v_pk_fma_f32 v[38:39], v[54:55], v[24:25], v[38:39]
	v_pk_fma_f32 v[172:173], v[48:49], v[34:35], v[172:173]
	v_pk_fma_f32 v[38:39], v[58:59], v[22:23], v[38:39]
	v_pk_fma_f32 v[172:173], v[52:53], v[24:25], v[172:173]
	v_pk_fma_f32 v[38:39], v[62:63], v[20:21], v[38:39]
	v_pk_fma_f32 v[172:173], v[56:57], v[22:23], v[172:173]
	v_pk_fma_f32 v[38:39], v[66:67], v[18:19], v[38:39]
	v_pk_fma_f32 v[172:173], v[60:61], v[20:21], v[172:173]
	v_pk_fma_f32 v[38:39], v[70:71], v[10:11], v[38:39]
	v_pk_fma_f32 v[172:173], v[64:65], v[18:19], v[172:173]
	v_pk_fma_f32 v[38:39], v[74:75], v[12:13], v[38:39]
	v_pk_fma_f32 v[172:173], v[68:69], v[10:11], v[172:173]
	v_pk_fma_f32 v[38:39], v[78:79], v[14:15], v[38:39]
	v_pk_fma_f32 v[172:173], v[72:73], v[12:13], v[172:173]
	v_pk_fma_f32 v[38:39], v[82:83], v[16:17], v[38:39]
	v_pk_fma_f32 v[172:173], v[76:77], v[14:15], v[172:173]
	v_pk_fma_f32 v[38:39], v[86:87], v[26:27], v[38:39]
	v_pk_fma_f32 v[172:173], v[80:81], v[16:17], v[172:173]
	v_pk_fma_f32 v[38:39], v[90:91], v[28:29], v[38:39]
	v_pk_fma_f32 v[172:173], v[84:85], v[26:27], v[172:173]
	v_pk_fma_f32 v[38:39], v[94:95], v[30:31], v[38:39]
	v_pk_fma_f32 v[172:173], v[88:89], v[28:29], v[172:173]
	v_pk_fma_f32 v[38:39], v[98:99], v[32:33], v[38:39]
	v_pk_fma_f32 v[172:173], v[92:93], v[30:31], v[172:173]
	v_add_f32_e32 v182, v38, v39
	v_mul_f32_e32 v39, v42, v37
	v_pk_fma_f32 v[36:37], v[42:43], v[36:37], v[104:105]
	v_mov_b32_e32 v38, v104
	v_pk_fma_f32 v[36:37], v[46:47], v[34:35], v[36:37]
	s_waitcnt lgkmcnt(1)
	v_mul_f32_e32 v105, v101, v158
	v_pk_fma_f32 v[36:37], v[50:51], v[24:25], v[36:37]
	v_pk_fma_f32 v[38:39], v[44:45], v[34:35], v[38:39]
	v_pk_fma_f32 v[36:37], v[54:55], v[22:23], v[36:37]
	v_pk_fma_f32 v[38:39], v[48:49], v[24:25], v[38:39]
	v_pk_fma_f32 v[36:37], v[58:59], v[20:21], v[36:37]
	v_pk_fma_f32 v[38:39], v[52:53], v[22:23], v[38:39]
	v_pk_fma_f32 v[36:37], v[62:63], v[18:19], v[36:37]
	v_pk_fma_f32 v[38:39], v[56:57], v[20:21], v[38:39]
	v_pk_fma_f32 v[36:37], v[66:67], v[10:11], v[36:37]
	v_pk_fma_f32 v[38:39], v[60:61], v[18:19], v[38:39]
	v_pk_fma_f32 v[36:37], v[70:71], v[12:13], v[36:37]
	v_pk_fma_f32 v[38:39], v[64:65], v[10:11], v[38:39]
	v_pk_fma_f32 v[36:37], v[74:75], v[14:15], v[36:37]
	v_pk_fma_f32 v[38:39], v[68:69], v[12:13], v[38:39]
	v_pk_fma_f32 v[36:37], v[78:79], v[16:17], v[36:37]
	v_pk_fma_f32 v[38:39], v[72:73], v[14:15], v[38:39]
	v_pk_fma_f32 v[36:37], v[82:83], v[26:27], v[36:37]
	v_pk_fma_f32 v[38:39], v[76:77], v[16:17], v[38:39]
	v_pk_fma_f32 v[36:37], v[86:87], v[28:29], v[36:37]
	v_pk_fma_f32 v[38:39], v[80:81], v[26:27], v[38:39]
	v_pk_fma_f32 v[36:37], v[90:91], v[30:31], v[36:37]
	v_pk_fma_f32 v[38:39], v[84:85], v[28:29], v[38:39]
	v_pk_fma_f32 v[36:37], v[94:95], v[32:33], v[36:37]
	v_pk_fma_f32 v[38:39], v[88:89], v[30:31], v[38:39]
	v_pk_fma_f32 v[36:37], v[98:99], v[40:41], v[36:37]
	v_pk_fma_f32 v[38:39], v[92:93], v[32:33], v[38:39]
	v_add_f32_e32 v184, v36, v37
	v_mul_f32_e32 v37, v42, v35
	v_pk_fma_f32 v[34:35], v[42:43], v[34:35], v[104:105]
	v_mov_b32_e32 v36, v104
	v_pk_fma_f32 v[34:35], v[46:47], v[24:25], v[34:35]
	s_waitcnt lgkmcnt(0)
	v_mul_f32_e32 v105, v101, v160
	v_pk_fma_f32 v[34:35], v[50:51], v[22:23], v[34:35]
	v_pk_fma_f32 v[36:37], v[44:45], v[24:25], v[36:37]
	v_pk_fma_f32 v[34:35], v[54:55], v[20:21], v[34:35]
	v_pk_fma_f32 v[36:37], v[48:49], v[22:23], v[36:37]
	v_pk_fma_f32 v[34:35], v[58:59], v[18:19], v[34:35]
	v_pk_fma_f32 v[36:37], v[52:53], v[20:21], v[36:37]
	v_pk_fma_f32 v[34:35], v[62:63], v[10:11], v[34:35]
	v_pk_fma_f32 v[36:37], v[56:57], v[18:19], v[36:37]
	v_pk_fma_f32 v[34:35], v[66:67], v[12:13], v[34:35]
	v_pk_fma_f32 v[36:37], v[60:61], v[10:11], v[36:37]
	v_pk_fma_f32 v[34:35], v[70:71], v[14:15], v[34:35]
	v_pk_fma_f32 v[36:37], v[64:65], v[12:13], v[36:37]
	v_pk_fma_f32 v[34:35], v[74:75], v[16:17], v[34:35]
	v_pk_fma_f32 v[36:37], v[68:69], v[14:15], v[36:37]
	v_pk_fma_f32 v[34:35], v[78:79], v[26:27], v[34:35]
	v_pk_fma_f32 v[36:37], v[72:73], v[16:17], v[36:37]
	v_pk_fma_f32 v[34:35], v[82:83], v[28:29], v[34:35]
	v_pk_fma_f32 v[36:37], v[76:77], v[26:27], v[36:37]
	v_pk_fma_f32 v[34:35], v[86:87], v[30:31], v[34:35]
	v_pk_fma_f32 v[36:37], v[80:81], v[28:29], v[36:37]
	v_pk_fma_f32 v[34:35], v[90:91], v[32:33], v[34:35]
	v_pk_fma_f32 v[36:37], v[84:85], v[30:31], v[36:37]
	v_pk_fma_f32 v[34:35], v[94:95], v[40:41], v[34:35]
	v_pk_fma_f32 v[36:37], v[88:89], v[32:33], v[36:37]
	v_pk_fma_f32 v[34:35], v[98:99], v[156:157], v[34:35]
	v_pk_fma_f32 v[36:37], v[92:93], v[40:41], v[36:37]
	v_add_f32_e32 v186, v34, v35
	v_mul_f32_e32 v35, v42, v25
	v_mov_b32_e32 v34, v104
	v_pk_fma_f32 v[24:25], v[42:43], v[24:25], v[104:105]
	v_pk_fma_f32 v[34:35], v[44:45], v[22:23], v[34:35]
	v_pk_fma_f32 v[24:25], v[46:47], v[22:23], v[24:25]
	v_pk_fma_f32 v[34:35], v[48:49], v[20:21], v[34:35]
	v_pk_fma_f32 v[24:25], v[50:51], v[20:21], v[24:25]
	v_pk_fma_f32 v[34:35], v[52:53], v[18:19], v[34:35]
	v_pk_fma_f32 v[24:25], v[54:55], v[18:19], v[24:25]
	v_pk_fma_f32 v[34:35], v[56:57], v[10:11], v[34:35]
	v_pk_fma_f32 v[24:25], v[58:59], v[10:11], v[24:25]
	v_pk_fma_f32 v[34:35], v[60:61], v[12:13], v[34:35]
	v_pk_fma_f32 v[24:25], v[62:63], v[12:13], v[24:25]
	v_pk_fma_f32 v[34:35], v[64:65], v[14:15], v[34:35]
	v_pk_fma_f32 v[24:25], v[66:67], v[14:15], v[24:25]
	v_pk_fma_f32 v[34:35], v[68:69], v[16:17], v[34:35]
	v_pk_fma_f32 v[24:25], v[70:71], v[16:17], v[24:25]
	v_pk_fma_f32 v[34:35], v[72:73], v[26:27], v[34:35]
	v_pk_fma_f32 v[24:25], v[74:75], v[26:27], v[24:25]
	v_pk_fma_f32 v[34:35], v[76:77], v[28:29], v[34:35]
	v_pk_fma_f32 v[24:25], v[78:79], v[28:29], v[24:25]
	v_pk_fma_f32 v[34:35], v[80:81], v[30:31], v[34:35]
	v_pk_fma_f32 v[24:25], v[82:83], v[30:31], v[24:25]
	v_pk_fma_f32 v[34:35], v[84:85], v[32:33], v[34:35]
	v_pk_fma_f32 v[24:25], v[86:87], v[32:33], v[24:25]
	v_pk_fma_f32 v[34:35], v[88:89], v[40:41], v[34:35]
	v_pk_fma_f32 v[24:25], v[90:91], v[40:41], v[24:25]
	v_pk_fma_f32 v[34:35], v[92:93], v[156:157], v[34:35]
	v_pk_fma_f32 v[38:39], v[96:97], v[40:41], v[38:39]
	v_pk_fma_f32 v[36:37], v[96:97], v[156:157], v[36:37]
	v_pk_fma_f32 v[24:25], v[94:95], v[156:157], v[24:25]
	v_pk_fma_f32 v[34:35], v[96:97], v[158:159], v[34:35]
	v_pk_fma_f32 v[38:39], v[100:101], v[156:157], v[38:39]
	v_pk_fma_f32 v[36:37], v[100:101], v[158:159], v[36:37]
	v_pk_fma_f32 v[24:25], v[98:99], v[158:159], v[24:25]
	v_pk_fma_f32 v[34:35], v[100:101], v[160:161], v[34:35]
	v_add_f32_e32 v185, v38, v39
	v_add_f32_e32 v187, v36, v37
	v_add_f32_e32 v188, v24, v25
	v_add_f32_e32 v189, v34, v35
	ds_read2st64_b32 v[24:25], v163 offset0:216 offset1:220
	ds_read2st64_b32 v[34:35], v163 offset0:224 offset1:228
	ds_read2st64_b32 v[36:37], v163 offset0:232 offset1:236
	ds_read2st64_b32 v[38:39], v163 offset0:240 offset1:244
	v_pk_fma_f32 v[172:173], v[96:97], v[32:33], v[172:173]
	s_waitcnt lgkmcnt(3)
	v_mul_f32_e32 v105, v101, v24
	v_pk_fma_f32 v[172:173], v[100:101], v[40:41], v[172:173]
	s_waitcnt lgkmcnt(0)
	v_add_f32_e32 v183, v172, v173
	v_mul_f32_e32 v173, v42, v23
	v_pk_fma_f32 v[22:23], v[42:43], v[22:23], v[104:105]
	v_mov_b32_e32 v172, v104
	v_pk_fma_f32 v[22:23], v[46:47], v[20:21], v[22:23]
	v_mul_f32_e32 v105, v101, v34
	v_pk_fma_f32 v[22:23], v[50:51], v[18:19], v[22:23]
	v_pk_fma_f32 v[172:173], v[44:45], v[20:21], v[172:173]
	v_pk_fma_f32 v[22:23], v[54:55], v[10:11], v[22:23]
	v_pk_fma_f32 v[172:173], v[48:49], v[18:19], v[172:173]
	v_pk_fma_f32 v[22:23], v[58:59], v[12:13], v[22:23]
	v_pk_fma_f32 v[172:173], v[52:53], v[10:11], v[172:173]
	v_pk_fma_f32 v[22:23], v[62:63], v[14:15], v[22:23]
	v_pk_fma_f32 v[172:173], v[56:57], v[12:13], v[172:173]
	v_pk_fma_f32 v[22:23], v[66:67], v[16:17], v[22:23]
	v_pk_fma_f32 v[172:173], v[60:61], v[14:15], v[172:173]
	v_pk_fma_f32 v[22:23], v[70:71], v[26:27], v[22:23]
	v_pk_fma_f32 v[172:173], v[64:65], v[16:17], v[172:173]
	v_pk_fma_f32 v[22:23], v[74:75], v[28:29], v[22:23]
	v_pk_fma_f32 v[172:173], v[68:69], v[26:27], v[172:173]
	v_pk_fma_f32 v[22:23], v[78:79], v[30:31], v[22:23]
	v_pk_fma_f32 v[172:173], v[72:73], v[28:29], v[172:173]
	v_pk_fma_f32 v[22:23], v[82:83], v[32:33], v[22:23]
	v_pk_fma_f32 v[172:173], v[76:77], v[30:31], v[172:173]
	v_pk_fma_f32 v[22:23], v[86:87], v[40:41], v[22:23]
	v_pk_fma_f32 v[172:173], v[80:81], v[32:33], v[172:173]
	v_pk_fma_f32 v[22:23], v[90:91], v[156:157], v[22:23]
	v_pk_fma_f32 v[172:173], v[84:85], v[40:41], v[172:173]
	v_pk_fma_f32 v[22:23], v[94:95], v[158:159], v[22:23]
	v_pk_fma_f32 v[172:173], v[88:89], v[156:157], v[172:173]
	v_pk_fma_f32 v[22:23], v[98:99], v[160:161], v[22:23]
	v_pk_fma_f32 v[172:173], v[92:93], v[158:159], v[172:173]
	v_add_f32_e32 v190, v22, v23
	v_mul_f32_e32 v23, v42, v21
	v_pk_fma_f32 v[20:21], v[42:43], v[20:21], v[104:105]
	v_pk_fma_f32 v[172:173], v[96:97], v[160:161], v[172:173]
	v_pk_fma_f32 v[20:21], v[46:47], v[18:19], v[20:21]
	v_pk_fma_f32 v[172:173], v[100:101], v[24:25], v[172:173]
	v_pk_fma_f32 v[20:21], v[50:51], v[10:11], v[20:21]
	v_mov_b32_e32 v22, v104
	v_pk_fma_f32 v[20:21], v[54:55], v[12:13], v[20:21]
	v_mul_f32_e32 v105, v101, v36
	v_pk_fma_f32 v[20:21], v[58:59], v[14:15], v[20:21]
	v_add_f32_e32 v172, v172, v173
	v_pk_fma_f32 v[20:21], v[62:63], v[16:17], v[20:21]
	v_pk_fma_f32 v[22:23], v[44:45], v[18:19], v[22:23]
	v_pk_fma_f32 v[20:21], v[66:67], v[26:27], v[20:21]
	v_pk_fma_f32 v[22:23], v[48:49], v[10:11], v[22:23]
	v_pk_fma_f32 v[20:21], v[70:71], v[28:29], v[20:21]
	v_pk_fma_f32 v[22:23], v[52:53], v[12:13], v[22:23]
	v_pk_fma_f32 v[20:21], v[74:75], v[30:31], v[20:21]
	v_pk_fma_f32 v[22:23], v[56:57], v[14:15], v[22:23]
	v_pk_fma_f32 v[20:21], v[78:79], v[32:33], v[20:21]
	v_pk_fma_f32 v[22:23], v[60:61], v[16:17], v[22:23]
	v_pk_fma_f32 v[20:21], v[82:83], v[40:41], v[20:21]
	v_pk_fma_f32 v[22:23], v[64:65], v[26:27], v[22:23]
	v_pk_fma_f32 v[20:21], v[86:87], v[156:157], v[20:21]
	v_pk_fma_f32 v[22:23], v[68:69], v[28:29], v[22:23]
	v_pk_fma_f32 v[20:21], v[90:91], v[158:159], v[20:21]
	v_pk_fma_f32 v[22:23], v[72:73], v[30:31], v[22:23]
	v_pk_fma_f32 v[20:21], v[94:95], v[160:161], v[20:21]
	v_pk_fma_f32 v[22:23], v[76:77], v[32:33], v[22:23]
	v_pk_fma_f32 v[20:21], v[98:99], v[24:25], v[20:21]
	v_pk_fma_f32 v[22:23], v[80:81], v[40:41], v[22:23]
	v_add_f32_e32 v173, v20, v21
	v_mul_f32_e32 v21, v42, v19
	v_pk_fma_f32 v[18:19], v[42:43], v[18:19], v[104:105]
	v_pk_fma_f32 v[22:23], v[84:85], v[156:157], v[22:23]
	v_pk_fma_f32 v[18:19], v[46:47], v[10:11], v[18:19]
	v_pk_fma_f32 v[22:23], v[88:89], v[158:159], v[22:23]
	v_pk_fma_f32 v[18:19], v[50:51], v[12:13], v[18:19]
	v_pk_fma_f32 v[22:23], v[92:93], v[160:161], v[22:23]
	v_pk_fma_f32 v[18:19], v[54:55], v[14:15], v[18:19]
	v_pk_fma_f32 v[22:23], v[96:97], v[24:25], v[22:23]
	v_pk_fma_f32 v[18:19], v[58:59], v[16:17], v[18:19]
	v_pk_fma_f32 v[22:23], v[100:101], v[34:35], v[22:23]
	v_pk_fma_f32 v[18:19], v[62:63], v[26:27], v[18:19]
	v_add_f32_e32 v22, v22, v23
	v_pk_fma_f32 v[18:19], v[66:67], v[28:29], v[18:19]
	v_mov_b32_e32 v20, v104
	v_pk_fma_f32 v[18:19], v[70:71], v[30:31], v[18:19]
	v_mul_f32_e32 v105, v101, v38
	v_pk_fma_f32 v[18:19], v[74:75], v[32:33], v[18:19]
	v_pk_fma_f32 v[20:21], v[44:45], v[10:11], v[20:21]
	v_pk_fma_f32 v[18:19], v[78:79], v[40:41], v[18:19]
	v_pk_fma_f32 v[20:21], v[48:49], v[12:13], v[20:21]
	v_pk_fma_f32 v[18:19], v[82:83], v[156:157], v[18:19]
	v_pk_fma_f32 v[20:21], v[52:53], v[14:15], v[20:21]
	v_pk_fma_f32 v[18:19], v[86:87], v[158:159], v[18:19]
	v_pk_fma_f32 v[20:21], v[56:57], v[16:17], v[20:21]
	v_pk_fma_f32 v[18:19], v[90:91], v[160:161], v[18:19]
	v_pk_fma_f32 v[20:21], v[60:61], v[26:27], v[20:21]
	v_pk_fma_f32 v[18:19], v[94:95], v[24:25], v[18:19]
	v_pk_fma_f32 v[20:21], v[64:65], v[28:29], v[20:21]
	v_pk_fma_f32 v[18:19], v[98:99], v[34:35], v[18:19]
	v_pk_fma_f32 v[20:21], v[68:69], v[30:31], v[20:21]
	v_add_f32_e32 v23, v18, v19
	v_mul_f32_e32 v19, v42, v11
	v_mov_b32_e32 v18, v104
	v_pk_fma_f32 v[10:11], v[42:43], v[10:11], v[104:105]
	v_pk_fma_f32 v[18:19], v[44:45], v[12:13], v[18:19]
	v_pk_fma_f32 v[10:11], v[46:47], v[12:13], v[10:11]
	v_pk_fma_f32 v[12:13], v[48:49], v[14:15], v[18:19]
	v_pk_fma_f32 v[10:11], v[50:51], v[14:15], v[10:11]
	v_pk_fma_f32 v[12:13], v[52:53], v[16:17], v[12:13]
	v_pk_fma_f32 v[10:11], v[54:55], v[16:17], v[10:11]
	v_pk_fma_f32 v[12:13], v[56:57], v[26:27], v[12:13]
	v_pk_fma_f32 v[10:11], v[58:59], v[26:27], v[10:11]
	v_pk_fma_f32 v[12:13], v[60:61], v[28:29], v[12:13]
	v_pk_fma_f32 v[10:11], v[62:63], v[28:29], v[10:11]
	v_pk_fma_f32 v[12:13], v[64:65], v[30:31], v[12:13]
	v_pk_fma_f32 v[10:11], v[66:67], v[30:31], v[10:11]
	v_pk_fma_f32 v[12:13], v[68:69], v[32:33], v[12:13]
	v_pk_fma_f32 v[20:21], v[72:73], v[32:33], v[20:21]
	v_pk_fma_f32 v[10:11], v[70:71], v[32:33], v[10:11]
	v_pk_fma_f32 v[12:13], v[72:73], v[40:41], v[12:13]
	v_pk_fma_f32 v[20:21], v[76:77], v[40:41], v[20:21]
	v_pk_fma_f32 v[10:11], v[74:75], v[40:41], v[10:11]
	v_pk_fma_f32 v[12:13], v[76:77], v[156:157], v[12:13]
	v_pk_fma_f32 v[20:21], v[80:81], v[156:157], v[20:21]
	v_pk_fma_f32 v[10:11], v[78:79], v[156:157], v[10:11]
	v_pk_fma_f32 v[12:13], v[80:81], v[158:159], v[12:13]
	v_pk_fma_f32 v[20:21], v[84:85], v[158:159], v[20:21]
	v_pk_fma_f32 v[10:11], v[82:83], v[158:159], v[10:11]
	v_pk_fma_f32 v[12:13], v[84:85], v[160:161], v[12:13]
	v_pk_fma_f32 v[20:21], v[88:89], v[160:161], v[20:21]
	v_pk_fma_f32 v[10:11], v[86:87], v[160:161], v[10:11]
	v_pk_fma_f32 v[12:13], v[88:89], v[24:25], v[12:13]
	v_pk_fma_f32 v[20:21], v[92:93], v[24:25], v[20:21]
	v_pk_fma_f32 v[10:11], v[90:91], v[24:25], v[10:11]
	v_pk_fma_f32 v[12:13], v[92:93], v[34:35], v[12:13]
	v_pk_fma_f32 v[20:21], v[96:97], v[34:35], v[20:21]
	v_pk_fma_f32 v[10:11], v[94:95], v[34:35], v[10:11]
	v_pk_fma_f32 v[12:13], v[96:97], v[36:37], v[12:13]
	v_pk_fma_f32 v[20:21], v[100:101], v[36:37], v[20:21]
	v_pk_fma_f32 v[10:11], v[98:99], v[36:37], v[10:11]
	v_pk_fma_f32 v[12:13], v[100:101], v[38:39], v[12:13]
	v_add_u32_e32 v105, s6, v162
	v_add_f32_e32 v20, v20, v21
	v_add_f32_e32 v10, v10, v11
	v_add_f32_e32 v11, v12, v13
	s_barrier
	ds_write2st64_b32 v163, v164, v165 offset1:4
	ds_write2st64_b32 v163, v166, v167 offset0:8 offset1:12
	ds_write2st64_b32 v163, v168, v169 offset0:16 offset1:20
	ds_write2st64_b32 v163, v170, v171 offset0:24 offset1:28
	ds_write2st64_b32 v163, v174, v175 offset0:32 offset1:36
	ds_write2st64_b32 v163, v176, v177 offset0:40 offset1:44
	ds_write2st64_b32 v163, v178, v179 offset0:48 offset1:52
	ds_write2st64_b32 v163, v180, v181 offset0:56 offset1:60
	ds_write2st64_b32 v163, v182, v183 offset0:64 offset1:68
	ds_write2st64_b32 v163, v184, v185 offset0:72 offset1:76
	ds_write2st64_b32 v163, v186, v187 offset0:80 offset1:84
	ds_write2st64_b32 v163, v188, v189 offset0:88 offset1:92
	ds_write2st64_b32 v163, v190, v172 offset0:96 offset1:100
	ds_write2st64_b32 v163, v173, v22 offset0:104 offset1:108
	ds_write2st64_b32 v163, v23, v20 offset0:112 offset1:116
	ds_write2st64_b32 v163, v10, v11 offset0:120 offset1:124
	s_waitcnt lgkmcnt(0)
	s_barrier
	ds_read_b128 v[38:41], v105
	ds_read_b128 v[14:17], v105 offset:49152
	ds_read_b128 v[34:37], v105 offset:8192
	ds_read_b128 v[30:33], v105 offset:16384
	ds_read_b128 v[26:29], v105 offset:24576
	s_waitcnt lgkmcnt(4)
	v_mov_b32_e32 v10, v39
	v_mov_b32_e32 v11, v40
	v_mov_b32_e32 v12, v38
	v_mov_b32_e32 v13, v41
	v_pk_add_f32 v[10:11], v[10:11], v[12:13]
	s_waitcnt lgkmcnt(2)
	v_mov_b32_e32 v12, v34
	v_add_f32_e32 v160, v10, v11
	v_mov_b32_e32 v10, v35
	v_mov_b32_e32 v11, v36
	v_mov_b32_e32 v13, v37
	v_pk_add_f32 v[10:11], v[10:11], v[12:13]
	ds_read_b128 v[22:25], v105 offset:32768
	ds_read_b128 v[18:21], v105 offset:40960
	v_add_f32_e32 v161, v10, v11
	s_waitcnt lgkmcnt(3)
	v_mov_b32_e32 v10, v31
	v_mov_b32_e32 v11, v32
	v_mov_b32_e32 v12, v30
	v_mov_b32_e32 v13, v33
	v_pk_add_f32 v[10:11], v[10:11], v[12:13]
	s_waitcnt lgkmcnt(2)
	v_mov_b32_e32 v12, v26
	v_add_f32_e32 v162, v10, v11
	v_mov_b32_e32 v10, v27
	v_mov_b32_e32 v11, v28
	v_mov_b32_e32 v13, v29
	v_pk_add_f32 v[10:11], v[10:11], v[12:13]
	s_waitcnt lgkmcnt(1)
	v_mov_b32_e32 v12, v22
	v_add_f32_e32 v163, v10, v11
	v_mov_b32_e32 v10, v23
	v_mov_b32_e32 v11, v24
	v_mov_b32_e32 v13, v25
	v_pk_add_f32 v[10:11], v[10:11], v[12:13]
	s_waitcnt lgkmcnt(0)
	v_mov_b32_e32 v12, v18
	v_add_f32_e32 v164, v10, v11
	v_mov_b32_e32 v10, v19
	v_mov_b32_e32 v11, v20
	v_mov_b32_e32 v13, v21
	v_pk_add_f32 v[10:11], v[10:11], v[12:13]
	v_mov_b32_e32 v12, v14
	v_add_f32_e32 v165, v10, v11
	v_mov_b32_e32 v10, v15
	v_mov_b32_e32 v11, v16
	v_mov_b32_e32 v13, v17
	v_pk_add_f32 v[10:11], v[10:11], v[12:13]
	s_cmpk_gt_i32 s65, 0x1df
	v_add_f32_e32 v166, v10, v11
	ds_read_b128 v[10:13], v105 offset:57344
	s_waitcnt lgkmcnt(0)
	v_mov_b32_e32 v156, v11
	v_mov_b32_e32 v157, v12
	v_mov_b32_e32 v158, v10
	v_mov_b32_e32 v159, v13
	v_pk_add_f32 v[156:157], v[156:157], v[158:159]
	v_add_f32_dpp v158, v162, v162 quad_perm:[1,0,3,2] row_mask:0xf bank_mask:0xf bound_ctrl:1
	v_add_f32_e32 v105, v156, v157
	v_add_f32_dpp v156, v160, v160 quad_perm:[1,0,3,2] row_mask:0xf bank_mask:0xf bound_ctrl:1
	v_add_f32_dpp v157, v161, v161 quad_perm:[1,0,3,2] row_mask:0xf bank_mask:0xf bound_ctrl:1
	v_add_f32_dpp v159, v163, v163 quad_perm:[1,0,3,2] row_mask:0xf bank_mask:0xf bound_ctrl:1
	v_add_f32_dpp v156, v156, v156 quad_perm:[2,3,0,1] row_mask:0xf bank_mask:0xf bound_ctrl:1
	v_add_f32_dpp v157, v157, v157 quad_perm:[2,3,0,1] row_mask:0xf bank_mask:0xf bound_ctrl:1
	v_mov_b32_e32 v163, v131
	v_add_f32_dpp v156, v156, v156 row_half_mirror row_mask:0xf bank_mask:0xf bound_ctrl:1
	v_add_f32_dpp v157, v157, v157 row_half_mirror row_mask:0xf bank_mask:0xf bound_ctrl:1
	v_add_f32_dpp v158, v158, v158 quad_perm:[2,3,0,1] row_mask:0xf bank_mask:0xf bound_ctrl:1
	v_add_f32_dpp v156, v156, v156 row_mirror row_mask:0xf bank_mask:0xf bound_ctrl:1
	v_add_f32_dpp v157, v157, v157 row_mirror row_mask:0xf bank_mask:0xf bound_ctrl:1
	v_add_f32_dpp v158, v158, v158 row_half_mirror row_mask:0xf bank_mask:0xf bound_ctrl:1
	v_mov_b32_dpp v163, v156 row_bcast:15 row_mask:0xa bank_mask:0xf
	v_add_f32_e32 v156, v156, v163
	v_mov_b32_e32 v163, v131
	v_add_f32_dpp v159, v159, v159 quad_perm:[2,3,0,1] row_mask:0xf bank_mask:0xf bound_ctrl:1
	v_add_f32_dpp v158, v158, v158 row_mirror row_mask:0xf bank_mask:0xf bound_ctrl:1
	v_mov_b32_dpp v163, v157 row_bcast:15 row_mask:0xa bank_mask:0xf
	v_add_f32_e32 v157, v157, v163
	v_mov_b32_e32 v163, v131
	v_add_f32_dpp v160, v164, v164 quad_perm:[1,0,3,2] row_mask:0xf bank_mask:0xf bound_ctrl:1
	v_add_f32_dpp v159, v159, v159 row_half_mirror row_mask:0xf bank_mask:0xf bound_ctrl:1
	v_mov_b32_dpp v163, v158 row_bcast:15 row_mask:0xa bank_mask:0xf
	v_add_f32_dpp v160, v160, v160 quad_perm:[2,3,0,1] row_mask:0xf bank_mask:0xf bound_ctrl:1
	v_add_f32_dpp v159, v159, v159 row_mirror row_mask:0xf bank_mask:0xf bound_ctrl:1
	v_add_f32_e32 v158, v158, v163
	v_mov_b32_e32 v163, v131
	v_add_f32_dpp v161, v165, v165 quad_perm:[1,0,3,2] row_mask:0xf bank_mask:0xf bound_ctrl:1
	v_add_f32_dpp v160, v160, v160 row_half_mirror row_mask:0xf bank_mask:0xf bound_ctrl:1
	v_mov_b32_dpp v163, v159 row_bcast:15 row_mask:0xa bank_mask:0xf
	v_add_f32_dpp v161, v161, v161 quad_perm:[2,3,0,1] row_mask:0xf bank_mask:0xf bound_ctrl:1
	v_add_f32_dpp v160, v160, v160 row_mirror row_mask:0xf bank_mask:0xf bound_ctrl:1
	v_add_f32_e32 v159, v159, v163
	v_mov_b32_e32 v163, v131
	v_add_f32_dpp v162, v166, v166 quad_perm:[1,0,3,2] row_mask:0xf bank_mask:0xf bound_ctrl:1
	v_add_f32_dpp v161, v161, v161 row_half_mirror row_mask:0xf bank_mask:0xf bound_ctrl:1
	v_mov_b32_dpp v163, v160 row_bcast:15 row_mask:0xa bank_mask:0xf
	v_add_f32_dpp v162, v162, v162 quad_perm:[2,3,0,1] row_mask:0xf bank_mask:0xf bound_ctrl:1
	v_add_f32_dpp v161, v161, v161 row_mirror row_mask:0xf bank_mask:0xf bound_ctrl:1
	v_add_f32_e32 v160, v160, v163
	v_mov_b32_e32 v163, v131
	v_add_f32_dpp v105, v105, v105 quad_perm:[1,0,3,2] row_mask:0xf bank_mask:0xf bound_ctrl:1
	v_add_f32_dpp v162, v162, v162 row_half_mirror row_mask:0xf bank_mask:0xf bound_ctrl:1
	v_mov_b32_dpp v163, v161 row_bcast:15 row_mask:0xa bank_mask:0xf
	v_add_f32_dpp v105, v105, v105 quad_perm:[2,3,0,1] row_mask:0xf bank_mask:0xf bound_ctrl:1
	v_add_f32_dpp v162, v162, v162 row_mirror row_mask:0xf bank_mask:0xf bound_ctrl:1
	v_add_f32_e32 v161, v161, v163
	v_mov_b32_e32 v163, v131
	v_add_f32_dpp v105, v105, v105 row_half_mirror row_mask:0xf bank_mask:0xf bound_ctrl:1
	s_nop 0
	v_mov_b32_dpp v163, v162 row_bcast:15 row_mask:0xa bank_mask:0xf
	v_add_f32_dpp v105, v105, v105 row_mirror row_mask:0xf bank_mask:0xf bound_ctrl:1
	v_add_f32_e32 v162, v162, v163
	v_mov_b32_e32 v163, v131
	s_nop 1
	v_mov_b32_dpp v163, v105 row_bcast:15 row_mask:0xa bank_mask:0xf
	v_add_f32_e32 v105, v105, v163
	v_mov_b32_e32 v163, v131
	s_nop 1
	v_mov_b32_dpp v163, v156 row_bcast:31 row_mask:0xc bank_mask:0xf
	v_add_f32_e32 v156, v156, v163
	v_mov_b32_e32 v163, v131
	v_readlane_b32 s6, v156, 63
	s_nop 0
	v_mov_b32_dpp v163, v157 row_bcast:31 row_mask:0xc bank_mask:0xf
	v_add_f32_e32 v157, v157, v163
	v_mov_b32_e32 v163, v131
	v_fma_f32 v39, s6, v239, v39
	v_fma_f32 v38, s6, v239, v38
	v_mov_b32_dpp v163, v158 row_bcast:31 row_mask:0xc bank_mask:0xf
	v_add_f32_e32 v158, v158, v163
	v_mov_b32_e32 v163, v131
	v_fma_f32 v41, s6, v239, v41
	v_fmac_f32_e32 v40, s6, v239
	v_mov_b32_dpp v163, v159 row_bcast:31 row_mask:0xc bank_mask:0xf
	v_add_f32_e32 v159, v159, v163
	v_mov_b32_e32 v163, v131
	v_readlane_b32 s7, v157, 63
	v_readlane_b32 s8, v158, 63
	v_mov_b32_dpp v163, v160 row_bcast:31 row_mask:0xc bank_mask:0xf
	v_add_f32_e32 v160, v160, v163
	v_mov_b32_e32 v163, v131
	v_readlane_b32 s9, v159, 63
	v_pk_mul_f32 v[156:157], v[40:41], v[40:41]
	v_mov_b32_dpp v163, v161 row_bcast:31 row_mask:0xc bank_mask:0xf
	v_add_f32_e32 v161, v161, v163
	v_mov_b32_e32 v163, v131
	v_pk_mul_f32 v[158:159], v[38:39], v[38:39]
	v_readlane_b32 s10, v160, 63
	v_mov_b32_dpp v163, v162 row_bcast:31 row_mask:0xc bank_mask:0xf
	v_add_f32_e32 v162, v162, v163
	v_mov_b32_e32 v163, v131
	v_readlane_b32 s11, v161, 63
	v_pk_mov_b32 v[160:161], v[158:159], v[156:157] op_sel:[1,0]
	v_mov_b32_dpp v163, v105 row_bcast:31 row_mask:0xc bank_mask:0xf
	v_mov_b32_e32 v159, v157
	v_add_f32_e32 v105, v105, v163
	v_pk_add_f32 v[156:157], v[160:161], v[158:159]
	v_fma_f32 v35, s7, v239, v35
	v_fma_f32 v34, s7, v239, v34
	v_fma_f32 v37, s7, v239, v37
	v_fmac_f32_e32 v36, s7, v239
	v_readlane_b32 s67, v105, 63
	v_add_f32_e32 v105, v156, v157
	v_pk_mul_f32 v[156:157], v[36:37], v[36:37]
	v_pk_mul_f32 v[158:159], v[34:35], v[34:35]
	v_fma_f32 v31, s8, v239, v31
	v_pk_mov_b32 v[160:161], v[158:159], v[156:157] op_sel:[1,0]
	v_mov_b32_e32 v159, v157
	v_pk_add_f32 v[156:157], v[160:161], v[158:159]
	v_fma_f32 v30, s8, v239, v30
	v_fma_f32 v33, s8, v239, v33
	v_fmac_f32_e32 v32, s8, v239
	v_readlane_b32 s66, v162, 63
	v_add_f32_e32 v162, v156, v157
	v_pk_mul_f32 v[156:157], v[32:33], v[32:33]
	v_pk_mul_f32 v[158:159], v[30:31], v[30:31]
	v_fma_f32 v27, s9, v239, v27
	v_pk_mov_b32 v[160:161], v[158:159], v[156:157] op_sel:[1,0]
	v_mov_b32_e32 v159, v157
	v_pk_add_f32 v[156:157], v[160:161], v[158:159]
	v_fma_f32 v26, s9, v239, v26
	v_fma_f32 v29, s9, v239, v29
	v_fmac_f32_e32 v28, s9, v239
	v_add_f32_e32 v163, v156, v157
	v_pk_mul_f32 v[156:157], v[28:29], v[28:29]
	v_pk_mul_f32 v[158:159], v[26:27], v[26:27]
	v_fma_f32 v23, s10, v239, v23
	v_pk_mov_b32 v[160:161], v[158:159], v[156:157] op_sel:[1,0]
	v_mov_b32_e32 v159, v157
	v_pk_add_f32 v[156:157], v[160:161], v[158:159]
	v_fma_f32 v22, s10, v239, v22
	v_fma_f32 v25, s10, v239, v25
	v_fmac_f32_e32 v24, s10, v239
	v_add_f32_e32 v164, v156, v157
	v_pk_mul_f32 v[156:157], v[24:25], v[24:25]
	v_pk_mul_f32 v[158:159], v[22:23], v[22:23]
	v_fma_f32 v19, s11, v239, v19
	v_pk_mov_b32 v[160:161], v[158:159], v[156:157] op_sel:[1,0]
	v_mov_b32_e32 v159, v157
	v_pk_add_f32 v[156:157], v[160:161], v[158:159]
	v_fma_f32 v18, s11, v239, v18
	v_fma_f32 v21, s11, v239, v21
	v_fmac_f32_e32 v20, s11, v239
	v_add_f32_e32 v165, v156, v157
	v_pk_mul_f32 v[156:157], v[20:21], v[20:21]
	v_pk_mul_f32 v[158:159], v[18:19], v[18:19]
	v_fma_f32 v15, s66, v239, v15
	v_pk_mov_b32 v[160:161], v[158:159], v[156:157] op_sel:[1,0]
	v_mov_b32_e32 v159, v157
	v_pk_add_f32 v[156:157], v[160:161], v[158:159]
	v_fma_f32 v14, s66, v239, v14
	v_fma_f32 v17, s66, v239, v17
	v_fmac_f32_e32 v16, s66, v239
	v_add_f32_e32 v166, v156, v157
	v_pk_mul_f32 v[156:157], v[16:17], v[16:17]
	v_pk_mul_f32 v[158:159], v[14:15], v[14:15]
	v_fma_f32 v11, s67, v239, v11
	v_pk_mov_b32 v[160:161], v[158:159], v[156:157] op_sel:[1,0]
	v_mov_b32_e32 v159, v157
	v_pk_add_f32 v[156:157], v[160:161], v[158:159]
	v_fma_f32 v10, s67, v239, v10
	v_fma_f32 v13, s67, v239, v13
	v_fmac_f32_e32 v12, s67, v239
	v_add_f32_e32 v167, v156, v157
	v_pk_mul_f32 v[156:157], v[12:13], v[12:13]
	v_pk_mul_f32 v[158:159], v[10:11], v[10:11]
	v_add_f32_dpp v105, v105, v105 quad_perm:[1,0,3,2] row_mask:0xf bank_mask:0xf bound_ctrl:1
	v_pk_mov_b32 v[160:161], v[158:159], v[156:157] op_sel:[1,0]
	v_mov_b32_e32 v159, v157
	v_pk_add_f32 v[156:157], v[160:161], v[158:159]
	v_add_f32_dpp v105, v105, v105 quad_perm:[2,3,0,1] row_mask:0xf bank_mask:0xf bound_ctrl:1
	v_add_f32_e32 v156, v156, v157
	v_add_f32_dpp v157, v162, v162 quad_perm:[1,0,3,2] row_mask:0xf bank_mask:0xf bound_ctrl:1
	v_add_f32_dpp v105, v105, v105 row_half_mirror row_mask:0xf bank_mask:0xf bound_ctrl:1
	v_add_f32_dpp v158, v163, v163 quad_perm:[1,0,3,2] row_mask:0xf bank_mask:0xf bound_ctrl:1
	v_add_f32_dpp v157, v157, v157 quad_perm:[2,3,0,1] row_mask:0xf bank_mask:0xf bound_ctrl:1
	v_add_f32_dpp v105, v105, v105 row_mirror row_mask:0xf bank_mask:0xf bound_ctrl:1
	v_mov_b32_e32 v163, v131
	v_add_f32_dpp v157, v157, v157 row_half_mirror row_mask:0xf bank_mask:0xf bound_ctrl:1
	v_add_f32_dpp v158, v158, v158 quad_perm:[2,3,0,1] row_mask:0xf bank_mask:0xf bound_ctrl:1
	v_mov_b32_dpp v163, v105 row_bcast:15 row_mask:0xa bank_mask:0xf
	v_add_f32_dpp v157, v157, v157 row_mirror row_mask:0xf bank_mask:0xf bound_ctrl:1
	v_add_f32_e32 v105, v105, v163
	v_mov_b32_e32 v163, v131
	v_add_f32_dpp v159, v164, v164 quad_perm:[1,0,3,2] row_mask:0xf bank_mask:0xf bound_ctrl:1
	v_add_f32_dpp v158, v158, v158 row_half_mirror row_mask:0xf bank_mask:0xf bound_ctrl:1
	v_mov_b32_dpp v163, v157 row_bcast:15 row_mask:0xa bank_mask:0xf
	v_add_f32_dpp v159, v159, v159 quad_perm:[2,3,0,1] row_mask:0xf bank_mask:0xf bound_ctrl:1
	v_add_f32_dpp v158, v158, v158 row_mirror row_mask:0xf bank_mask:0xf bound_ctrl:1
	v_add_f32_e32 v157, v157, v163
	v_mov_b32_e32 v163, v131
	v_add_f32_dpp v160, v165, v165 quad_perm:[1,0,3,2] row_mask:0xf bank_mask:0xf bound_ctrl:1
	v_add_f32_dpp v159, v159, v159 row_half_mirror row_mask:0xf bank_mask:0xf bound_ctrl:1
	v_mov_b32_dpp v163, v158 row_bcast:15 row_mask:0xa bank_mask:0xf
	v_add_f32_dpp v160, v160, v160 quad_perm:[2,3,0,1] row_mask:0xf bank_mask:0xf bound_ctrl:1
	v_add_f32_dpp v159, v159, v159 row_mirror row_mask:0xf bank_mask:0xf bound_ctrl:1
	v_add_f32_e32 v158, v158, v163
	v_mov_b32_e32 v163, v131
	v_add_f32_dpp v161, v166, v166 quad_perm:[1,0,3,2] row_mask:0xf bank_mask:0xf bound_ctrl:1
	v_add_f32_dpp v160, v160, v160 row_half_mirror row_mask:0xf bank_mask:0xf bound_ctrl:1
	v_mov_b32_dpp v163, v159 row_bcast:15 row_mask:0xa bank_mask:0xf
	v_add_f32_dpp v161, v161, v161 quad_perm:[2,3,0,1] row_mask:0xf bank_mask:0xf bound_ctrl:1
	v_add_f32_dpp v160, v160, v160 row_mirror row_mask:0xf bank_mask:0xf bound_ctrl:1
	v_add_f32_e32 v159, v159, v163
	v_mov_b32_e32 v163, v131
	v_add_f32_dpp v162, v167, v167 quad_perm:[1,0,3,2] row_mask:0xf bank_mask:0xf bound_ctrl:1
	v_add_f32_dpp v161, v161, v161 row_half_mirror row_mask:0xf bank_mask:0xf bound_ctrl:1
	v_mov_b32_dpp v163, v160 row_bcast:15 row_mask:0xa bank_mask:0xf
	v_add_f32_dpp v162, v162, v162 quad_perm:[2,3,0,1] row_mask:0xf bank_mask:0xf bound_ctrl:1
	v_add_f32_dpp v161, v161, v161 row_mirror row_mask:0xf bank_mask:0xf bound_ctrl:1
	v_add_f32_e32 v160, v160, v163
	v_mov_b32_e32 v163, v131
	v_add_f32_dpp v156, v156, v156 quad_perm:[1,0,3,2] row_mask:0xf bank_mask:0xf bound_ctrl:1
	v_add_f32_dpp v162, v162, v162 row_half_mirror row_mask:0xf bank_mask:0xf bound_ctrl:1
	v_mov_b32_dpp v163, v161 row_bcast:15 row_mask:0xa bank_mask:0xf
	v_add_f32_dpp v156, v156, v156 quad_perm:[2,3,0,1] row_mask:0xf bank_mask:0xf bound_ctrl:1
	v_add_f32_dpp v162, v162, v162 row_mirror row_mask:0xf bank_mask:0xf bound_ctrl:1
	v_add_f32_e32 v161, v161, v163
	v_mov_b32_e32 v163, v131
	v_add_f32_dpp v156, v156, v156 row_half_mirror row_mask:0xf bank_mask:0xf bound_ctrl:1
	s_nop 0
	v_mov_b32_dpp v163, v162 row_bcast:15 row_mask:0xa bank_mask:0xf
	v_add_f32_dpp v156, v156, v156 row_mirror row_mask:0xf bank_mask:0xf bound_ctrl:1
	v_add_f32_e32 v162, v162, v163
	v_mov_b32_e32 v163, v131
	s_nop 1
	v_mov_b32_dpp v163, v156 row_bcast:15 row_mask:0xa bank_mask:0xf
	v_add_f32_e32 v156, v156, v163
	v_mov_b32_e32 v163, v131
	s_nop 1
	v_mov_b32_dpp v163, v105 row_bcast:31 row_mask:0xc bank_mask:0xf
	v_add_f32_e32 v105, v105, v163
	v_mov_b32_e32 v163, v131
	v_readlane_b32 s8, v105, 63
	s_nop 0
	v_mov_b32_dpp v163, v157 row_bcast:31 row_mask:0xc bank_mask:0xf
	v_add_f32_e32 v157, v157, v163
	v_mov_b32_e32 v163, v131
	v_fma_f32 v105, s8, v235, v225
	v_readlane_b32 s9, v157, 63
	v_mov_b32_dpp v163, v158 row_bcast:31 row_mask:0xc bank_mask:0xf
	v_add_f32_e32 v158, v158, v163
	v_mov_b32_e32 v163, v131
	v_readlane_b32 s69, v158, 63
	s_nop 0
	v_mov_b32_dpp v163, v159 row_bcast:31 row_mask:0xc bank_mask:0xf
	v_add_f32_e32 v159, v159, v163
	v_mov_b32_e32 v163, v131
	v_readlane_b32 s68, v159, 63
	s_nop 0
	v_mov_b32_dpp v163, v160 row_bcast:31 row_mask:0xc bank_mask:0xf
	v_add_f32_e32 v160, v160, v163
	v_mov_b32_e32 v163, v131
	v_readlane_b32 s67, v160, 63
	s_nop 0
	v_mov_b32_dpp v163, v161 row_bcast:31 row_mask:0xc bank_mask:0xf
	v_add_f32_e32 v161, v161, v163
	v_mov_b32_e32 v163, v131
	v_readlane_b32 s66, v161, 63
	s_nop 0
	v_mov_b32_dpp v163, v162 row_bcast:31 row_mask:0xc bank_mask:0xf
	v_add_f32_e32 v162, v162, v163
	v_mov_b32_e32 v163, v131
	v_readlane_b32 s7, v162, 63
	s_nop 0
	v_mov_b32_dpp v163, v156 row_bcast:31 row_mask:0xc bank_mask:0xf
	v_add_f32_e32 v156, v156, v163
	s_nop 0
	v_readlane_b32 s6, v156, 63
	v_rsq_f32_e32 v156, v105
	s_nop 0
	v_pk_mul_f32 v[38:39], v[38:39], v[156:157] op_sel_hi:[1,0]
	v_pk_fma_f32 v[38:39], v[2:3], v[38:39], v[6:7]
	v_pk_mul_f32 v[40:41], v[40:41], v[156:157] op_sel_hi:[1,0]
	v_mul_f32_e32 v105, 0xbfb8aa3b, v38
	v_exp_f32_e32 v105, v105
	v_pk_fma_f32 v[40:41], v[4:5], v[40:41], v[8:9]
	v_add_f32_e32 v105, 1.0, v105
	v_rcp_f32_e32 v156, v105
	v_mul_f32_e32 v105, 0xbfb8aa3b, v39
	v_exp_f32_e32 v105, v105
	s_nop 0
	v_add_f32_e32 v105, 1.0, v105
	v_rcp_f32_e32 v157, v105
	v_mul_f32_e32 v105, 0xbfb8aa3b, v40
	v_exp_f32_e32 v105, v105
	v_pk_mul_f32 v[38:39], v[38:39], v[156:157]
	v_add_f32_e32 v105, 1.0, v105
	v_rcp_f32_e32 v156, v105
	v_mul_f32_e32 v105, 0xbfb8aa3b, v41
	v_exp_f32_e32 v105, v105
	s_nop 0
	v_add_f32_e32 v105, 1.0, v105
	v_rcp_f32_e32 v157, v105
	s_nop 0
	v_pk_mul_f32 v[40:41], v[40:41], v[156:157]
	v_cvt_pk_bf16_f32 v156, v38, v39
	v_fma_f32 v39, s9, v235, v225
	v_cvt_pk_bf16_f32 v157, v40, v41
	v_rsq_f32_e32 v40, v39
	v_lshlrev_b32_e32 v38, 3, v130
	global_store_dwordx2 v38, v[156:157], s[56:57] offset:512
	v_pk_mul_f32 v[34:35], v[34:35], v[40:41] op_sel_hi:[1,0]
	s_nop 0
	v_pk_fma_f32 v[34:35], v[2:3], v[34:35], v[6:7]
	v_pk_mul_f32 v[36:37], v[36:37], v[40:41] op_sel_hi:[1,0]
	v_mul_f32_e32 v39, 0xbfb8aa3b, v34
	v_exp_f32_e32 v39, v39
	v_pk_fma_f32 v[36:37], v[4:5], v[36:37], v[8:9]
	v_add_f32_e32 v39, 1.0, v39
	v_rcp_f32_e32 v40, v39
	v_mul_f32_e32 v39, 0xbfb8aa3b, v35
	v_exp_f32_e32 v39, v39
	s_nop 0
	v_add_f32_e32 v39, 1.0, v39
	v_rcp_f32_e32 v41, v39
	v_mul_f32_e32 v39, 0xbfb8aa3b, v36
	v_exp_f32_e32 v39, v39
	v_pk_mul_f32 v[34:35], v[34:35], v[40:41]
	s_nop 0
	v_cvt_pk_bf16_f32 v34, v34, v35
	v_add_f32_e32 v39, 1.0, v39
	v_rcp_f32_e32 v40, v39
	v_mul_f32_e32 v39, 0xbfb8aa3b, v37
	v_exp_f32_e32 v39, v39
	s_nop 0
	v_add_f32_e32 v39, 1.0, v39
	v_rcp_f32_e32 v41, v39
	s_nop 0
	v_pk_mul_f32 v[36:37], v[36:37], v[40:41]
	v_cvt_pk_bf16_f32 v35, v36, v37
	global_store_dwordx2 v38, v[34:35], s[54:55] offset:512
	v_fma_f32 v34, s69, v235, v225
	v_rsq_f32_e32 v34, v34
	s_nop 0
	v_pk_mul_f32 v[30:31], v[30:31], v[34:35] op_sel_hi:[1,0]
	v_pk_fma_f32 v[30:31], v[2:3], v[30:31], v[6:7]
	v_pk_mul_f32 v[32:33], v[32:33], v[34:35] op_sel_hi:[1,0]
	v_mul_f32_e32 v34, 0xbfb8aa3b, v30
	v_mul_f32_e32 v35, 0xbfb8aa3b, v31
	v_exp_f32_e32 v34, v34
	v_exp_f32_e32 v35, v35
	v_pk_fma_f32 v[32:33], v[4:5], v[32:33], v[8:9]
	v_add_f32_e32 v34, 1.0, v34
	v_add_f32_e32 v35, 1.0, v35
	v_rcp_f32_e32 v34, v34
	v_rcp_f32_e32 v35, v35
	s_nop 0
	v_pk_mul_f32 v[30:31], v[30:31], v[34:35]
	v_mul_f32_e32 v34, 0xbfb8aa3b, v32
	v_mul_f32_e32 v35, 0xbfb8aa3b, v33
	v_exp_f32_e32 v34, v34
	v_exp_f32_e32 v35, v35
	v_cvt_pk_bf16_f32 v30, v30, v31
	v_add_f32_e32 v34, 1.0, v34
	v_add_f32_e32 v35, 1.0, v35
	v_rcp_f32_e32 v34, v34
	v_rcp_f32_e32 v35, v35
	s_nop 0
	v_pk_mul_f32 v[32:33], v[32:33], v[34:35]
	v_cvt_pk_bf16_f32 v31, v32, v33
	global_store_dwordx2 v38, v[30:31], s[52:53] offset:512
	v_fma_f32 v30, s68, v235, v225
	v_rsq_f32_e32 v30, v30
	s_nop 0
	v_pk_mul_f32 v[26:27], v[26:27], v[30:31] op_sel_hi:[1,0]
	v_pk_fma_f32 v[26:27], v[2:3], v[26:27], v[6:7]
	v_pk_mul_f32 v[28:29], v[28:29], v[30:31] op_sel_hi:[1,0]
	v_mul_f32_e32 v30, 0xbfb8aa3b, v26
	v_mul_f32_e32 v31, 0xbfb8aa3b, v27
	v_exp_f32_e32 v30, v30
	v_exp_f32_e32 v31, v31
	v_pk_fma_f32 v[28:29], v[4:5], v[28:29], v[8:9]
	v_add_f32_e32 v30, 1.0, v30
	v_add_f32_e32 v31, 1.0, v31
	v_rcp_f32_e32 v30, v30
	v_rcp_f32_e32 v31, v31
	s_nop 0
	v_pk_mul_f32 v[26:27], v[26:27], v[30:31]
	v_mul_f32_e32 v30, 0xbfb8aa3b, v28
	v_mul_f32_e32 v31, 0xbfb8aa3b, v29
	v_exp_f32_e32 v30, v30
	v_exp_f32_e32 v31, v31
	v_cvt_pk_bf16_f32 v26, v26, v27
	v_add_f32_e32 v30, 1.0, v30
	v_add_f32_e32 v31, 1.0, v31
	v_rcp_f32_e32 v30, v30
	v_rcp_f32_e32 v31, v31
	s_nop 0
	v_pk_mul_f32 v[28:29], v[28:29], v[30:31]
	v_cvt_pk_bf16_f32 v27, v28, v29
	global_store_dwordx2 v38, v[26:27], s[50:51] offset:512
	v_fma_f32 v26, s67, v235, v225
	v_rsq_f32_e32 v26, v26
	s_nop 0
	v_pk_mul_f32 v[22:23], v[22:23], v[26:27] op_sel_hi:[1,0]
	v_pk_fma_f32 v[22:23], v[2:3], v[22:23], v[6:7]
	v_pk_mul_f32 v[24:25], v[24:25], v[26:27] op_sel_hi:[1,0]
	v_mul_f32_e32 v26, 0xbfb8aa3b, v22
	v_mul_f32_e32 v27, 0xbfb8aa3b, v23
	v_exp_f32_e32 v26, v26
	v_exp_f32_e32 v27, v27
	v_pk_fma_f32 v[24:25], v[4:5], v[24:25], v[8:9]
	v_add_f32_e32 v26, 1.0, v26
	v_add_f32_e32 v27, 1.0, v27
	v_rcp_f32_e32 v26, v26
	v_rcp_f32_e32 v27, v27
	s_nop 0
	v_pk_mul_f32 v[22:23], v[22:23], v[26:27]
	v_mul_f32_e32 v26, 0xbfb8aa3b, v24
	v_mul_f32_e32 v27, 0xbfb8aa3b, v25
	v_exp_f32_e32 v26, v26
	v_exp_f32_e32 v27, v27
	v_cvt_pk_bf16_f32 v22, v22, v23
	v_add_f32_e32 v26, 1.0, v26
	v_add_f32_e32 v27, 1.0, v27
	v_rcp_f32_e32 v26, v26
	v_rcp_f32_e32 v27, v27
	s_nop 0
	v_pk_mul_f32 v[24:25], v[24:25], v[26:27]
	v_cvt_pk_bf16_f32 v23, v24, v25
	global_store_dwordx2 v38, v[22:23], s[48:49] offset:512
	v_fma_f32 v22, s66, v235, v225
	v_rsq_f32_e32 v22, v22
	s_nop 0
	v_pk_mul_f32 v[18:19], v[18:19], v[22:23] op_sel_hi:[1,0]
	v_pk_fma_f32 v[18:19], v[2:3], v[18:19], v[6:7]
	v_pk_mul_f32 v[20:21], v[20:21], v[22:23] op_sel_hi:[1,0]
	v_mul_f32_e32 v22, 0xbfb8aa3b, v18
	v_mul_f32_e32 v23, 0xbfb8aa3b, v19
	v_exp_f32_e32 v22, v22
	v_exp_f32_e32 v23, v23
	v_pk_fma_f32 v[20:21], v[4:5], v[20:21], v[8:9]
	v_add_f32_e32 v22, 1.0, v22
	v_add_f32_e32 v23, 1.0, v23
	v_rcp_f32_e32 v22, v22
	v_rcp_f32_e32 v23, v23
	s_nop 0
	v_pk_mul_f32 v[18:19], v[18:19], v[22:23]
	v_mul_f32_e32 v22, 0xbfb8aa3b, v20
	v_mul_f32_e32 v23, 0xbfb8aa3b, v21
	v_exp_f32_e32 v22, v22
	v_exp_f32_e32 v23, v23
	v_cvt_pk_bf16_f32 v18, v18, v19
	v_add_f32_e32 v22, 1.0, v22
	v_add_f32_e32 v23, 1.0, v23
	v_rcp_f32_e32 v22, v22
	v_rcp_f32_e32 v23, v23
	s_nop 0
	v_pk_mul_f32 v[20:21], v[20:21], v[22:23]
	v_cvt_pk_bf16_f32 v19, v20, v21
	global_store_dwordx2 v38, v[18:19], s[46:47] offset:512
	v_fma_f32 v18, s7, v235, v225
	v_rsq_f32_e32 v18, v18
	s_nop 0
	v_pk_mul_f32 v[14:15], v[14:15], v[18:19] op_sel_hi:[1,0]
	v_pk_fma_f32 v[14:15], v[2:3], v[14:15], v[6:7]
	v_pk_mul_f32 v[16:17], v[16:17], v[18:19] op_sel_hi:[1,0]
	v_mul_f32_e32 v18, 0xbfb8aa3b, v14
	v_mul_f32_e32 v19, 0xbfb8aa3b, v15
	v_exp_f32_e32 v18, v18
	v_exp_f32_e32 v19, v19
	v_pk_fma_f32 v[16:17], v[4:5], v[16:17], v[8:9]
	v_add_f32_e32 v18, 1.0, v18
	v_add_f32_e32 v19, 1.0, v19
	v_rcp_f32_e32 v18, v18
	v_rcp_f32_e32 v19, v19
	s_nop 0
	v_pk_mul_f32 v[14:15], v[14:15], v[18:19]
	v_mul_f32_e32 v18, 0xbfb8aa3b, v16
	v_mul_f32_e32 v19, 0xbfb8aa3b, v17
	v_exp_f32_e32 v18, v18
	v_exp_f32_e32 v19, v19
	v_cvt_pk_bf16_f32 v14, v14, v15
	v_add_f32_e32 v18, 1.0, v18
	v_add_f32_e32 v19, 1.0, v19
	v_rcp_f32_e32 v18, v18
	v_rcp_f32_e32 v19, v19
	s_nop 0
	v_pk_mul_f32 v[16:17], v[16:17], v[18:19]
	v_cvt_pk_bf16_f32 v15, v16, v17
	global_store_dwordx2 v38, v[14:15], s[44:45] offset:512
	v_fma_f32 v14, s6, v235, v225
	v_rsq_f32_e32 v14, v14
	s_mov_b32 s6, s65
	v_pk_mul_f32 v[10:11], v[10:11], v[14:15] op_sel_hi:[1,0]
	v_pk_fma_f32 v[10:11], v[2:3], v[10:11], v[6:7]
	v_pk_mul_f32 v[12:13], v[12:13], v[14:15] op_sel_hi:[1,0]
	v_mul_f32_e32 v14, 0xbfb8aa3b, v10
	v_mul_f32_e32 v15, 0xbfb8aa3b, v11
	v_exp_f32_e32 v14, v14
	v_exp_f32_e32 v15, v15
	v_pk_fma_f32 v[12:13], v[4:5], v[12:13], v[8:9]
	v_add_f32_e32 v14, 1.0, v14
	v_add_f32_e32 v15, 1.0, v15
	v_rcp_f32_e32 v14, v14
	v_rcp_f32_e32 v15, v15
	s_nop 0
	v_pk_mul_f32 v[10:11], v[10:11], v[14:15]
	v_mul_f32_e32 v14, 0xbfb8aa3b, v12
	v_mul_f32_e32 v15, 0xbfb8aa3b, v13
	v_exp_f32_e32 v14, v14
	v_exp_f32_e32 v15, v15
	v_cvt_pk_bf16_f32 v10, v10, v11
	v_add_f32_e32 v14, 1.0, v14
	v_add_f32_e32 v15, 1.0, v15
	v_rcp_f32_e32 v14, v14
	v_rcp_f32_e32 v15, v15
	s_nop 0
	v_pk_mul_f32 v[12:13], v[12:13], v[14:15]
	v_cvt_pk_bf16_f32 v11, v12, v13
	global_store_dwordx2 v38, v[10:11], s[42:43] offset:512
	s_barrier
	s_cbranch_scc1 .LBB0_344

.LBB0_475:
	s_waitcnt lgkmcnt(0)
	s_nop 0
	global_load_dwordx4 v[2:5], v[8:9], off
	v_add_u32_e32 v12, s5, v1
	v_ashrrev_i32_e32 v13, 31, v12
	v_lshlrev_b64 v[14:15], 11, v[12:13]
	v_lshl_add_u64 v[78:79], v[6:7], 0, v[14:15]
	global_load_dwordx4 v[14:17], v[8:9], off offset:64
	global_load_dwordx4 v[18:21], v[78:79], off
	global_load_dwordx4 v[22:25], v[78:79], off offset:64
	global_load_dwordx4 v[26:29], v[8:9], off offset:128
	global_load_dwordx4 v[30:33], v[8:9], off offset:192
	global_load_dwordx4 v[34:37], v[78:79], off offset:128
	global_load_dwordx4 v[38:41], v[8:9], off offset:256
	global_load_dwordx4 v[42:45], v[78:79], off offset:192
	global_load_dwordx4 v[46:49], v[78:79], off offset:256
	global_load_dwordx4 v[50:53], v[8:9], off offset:320
	global_load_dwordx4 v[54:57], v[78:79], off offset:320
	global_load_dwordx4 v[58:61], v[8:9], off offset:384
	global_load_dwordx4 v[62:65], v[8:9], off offset:448
	global_load_dwordx4 v[66:69], v[78:79], off offset:384
	global_load_dwordx4 v[70:73], v[78:79], off offset:448
	s_waitcnt vmcnt(13)
	v_mfma_f32_16x16x32_bf16 v[2:5], v[2:5], v[18:21], 0
	global_load_dwordx4 v[18:21], v[8:9], off offset:512
	global_load_dwordx4 v[74:77], v[8:9], off offset:576
	s_waitcnt vmcnt(14)
	v_mfma_f32_16x16x32_bf16 v[2:5], v[14:17], v[22:25], v[2:5]
	global_load_dwordx4 v[14:17], v[78:79], off offset:512
	global_load_dwordx4 v[22:25], v[78:79], off offset:576
	s_waitcnt vmcnt(13)
	v_mfma_f32_16x16x32_bf16 v[2:5], v[26:29], v[34:37], v[2:5]
	global_load_dwordx4 v[26:29], v[8:9], off offset:640
	global_load_dwordx4 v[34:37], v[8:9], off offset:704
	s_waitcnt vmcnt(13)
	v_mfma_f32_16x16x32_bf16 v[2:5], v[30:33], v[42:45], v[2:5]
	global_load_dwordx4 v[30:33], v[78:79], off offset:640
	s_waitcnt vmcnt(13)
	v_mfma_f32_16x16x32_bf16 v[2:5], v[38:41], v[46:49], v[2:5]
	global_load_dwordx4 v[38:41], v[78:79], off offset:704
	global_load_dwordx4 v[42:45], v[8:9], off offset:768
	global_load_dwordx4 v[46:49], v[8:9], off offset:832
	s_waitcnt vmcnt(14)
	v_mfma_f32_16x16x32_bf16 v[2:5], v[50:53], v[54:57], v[2:5]
	global_load_dwordx4 v[50:53], v[78:79], off offset:768
	global_load_dwordx4 v[54:57], v[78:79], off offset:832
	s_waitcnt vmcnt(13)
	v_mfma_f32_16x16x32_bf16 v[2:5], v[58:61], v[66:69], v[2:5]
	s_waitcnt vmcnt(12)
	v_mfma_f32_16x16x32_bf16 v[2:5], v[62:65], v[70:73], v[2:5]
	global_load_dwordx4 v[58:61], v[8:9], off offset:896
	global_load_dwordx4 v[62:65], v[8:9], off offset:960
	s_waitcnt vmcnt(11)
	v_mfma_f32_16x16x32_bf16 v[2:5], v[18:21], v[14:17], v[2:5]
	global_load_dwordx4 v[14:17], v[78:79], off offset:896
	global_load_dwordx4 v[18:21], v[78:79], off offset:960
	s_waitcnt vmcnt(12)
	v_mfma_f32_16x16x32_bf16 v[2:5], v[74:77], v[22:25], v[2:5]
	global_load_dwordx4 v[22:25], v[8:9], off offset:1024
	global_load_dwordx4 v[66:69], v[8:9], off offset:1088
	s_waitcnt vmcnt(11)
	v_mfma_f32_16x16x32_bf16 v[2:5], v[26:29], v[30:33], v[2:5]
	global_load_dwordx4 v[26:29], v[78:79], off offset:1024
	global_load_dwordx4 v[30:33], v[78:79], off offset:1088
	s_waitcnt vmcnt(12)
	v_mfma_f32_16x16x32_bf16 v[2:5], v[34:37], v[38:41], v[2:5]
	global_load_dwordx4 v[34:37], v[8:9], off offset:1152
	global_load_dwordx4 v[38:41], v[8:9], off offset:1216
	s_waitcnt vmcnt(11)
	v_mfma_f32_16x16x32_bf16 v[2:5], v[42:45], v[50:53], v[2:5]
	s_waitcnt vmcnt(10)
	v_mfma_f32_16x16x32_bf16 v[2:5], v[46:49], v[54:57], v[2:5]
	global_load_dwordx4 v[42:45], v[78:79], off offset:1152
	global_load_dwordx4 v[46:49], v[78:79], off offset:1216
	s_waitcnt vmcnt(9)
	v_mfma_f32_16x16x32_bf16 v[2:5], v[58:61], v[14:17], v[2:5]
	global_load_dwordx4 v[14:17], v[8:9], off offset:1280
	global_load_dwordx4 v[50:53], v[8:9], off offset:1344
	s_waitcnt vmcnt(10)
	v_mfma_f32_16x16x32_bf16 v[2:5], v[62:65], v[18:21], v[2:5]
	global_load_dwordx4 v[18:21], v[78:79], off offset:1280
	global_load_dwordx4 v[54:57], v[8:9], off offset:1408
	s_waitcnt vmcnt(9)
	v_mfma_f32_16x16x32_bf16 v[2:5], v[22:25], v[26:29], v[2:5]
	global_load_dwordx4 v[22:25], v[78:79], off offset:1344
	global_load_dwordx4 v[26:29], v[78:79], off offset:1408
	s_waitcnt vmcnt(10)
	v_mfma_f32_16x16x32_bf16 v[2:5], v[66:69], v[30:33], v[2:5]
	s_waitcnt vmcnt(7)
	v_mfma_f32_16x16x32_bf16 v[2:5], v[34:37], v[42:45], v[2:5]
	global_load_dwordx4 v[30:33], v[8:9], off offset:1472
	global_load_dwordx4 v[34:37], v[78:79], off offset:1472
	s_waitcnt vmcnt(8)
	v_mfma_f32_16x16x32_bf16 v[2:5], v[38:41], v[46:49], v[2:5]
	global_load_dwordx4 v[38:41], v[8:9], off offset:1536
	global_load_dwordx4 v[42:45], v[8:9], off offset:1600
	s_waitcnt vmcnt(7)
	v_mfma_f32_16x16x32_bf16 v[2:5], v[14:17], v[18:21], v[2:5]
	global_load_dwordx4 v[14:17], v[78:79], off offset:1536
	global_load_dwordx4 v[18:21], v[8:9], off offset:1664
	s_waitcnt vmcnt(7)
	v_mfma_f32_16x16x32_bf16 v[2:5], v[50:53], v[22:25], v[2:5]
	global_load_dwordx4 v[22:25], v[78:79], off offset:1600
	s_waitcnt vmcnt(7)
	v_mfma_f32_16x16x32_bf16 v[2:5], v[54:57], v[26:29], v[2:5]
	global_load_dwordx4 v[26:29], v[78:79], off offset:1664
	s_waitcnt vmcnt(6)
	v_mfma_f32_16x16x32_bf16 v[2:5], v[30:33], v[34:37], v[2:5]
	global_load_dwordx4 v[30:33], v[8:9], off offset:1728
	global_load_dwordx4 v[34:37], v[78:79], off offset:1728
	s_waitcnt vmcnt(5)
	v_mfma_f32_16x16x32_bf16 v[2:5], v[38:41], v[14:17], v[2:5]
	global_load_dwordx4 v[14:17], v[8:9], off offset:1792
	global_load_dwordx4 v[38:41], v[8:9], off offset:1856
	s_waitcnt vmcnt(5)
	v_mfma_f32_16x16x32_bf16 v[2:5], v[42:45], v[22:25], v[2:5]
	global_load_dwordx4 v[22:25], v[78:79], off offset:1792
	s_waitcnt vmcnt(5)
	v_mfma_f32_16x16x32_bf16 v[2:5], v[18:21], v[26:29], v[2:5]
	global_load_dwordx4 v[18:21], v[78:79], off offset:1856
	s_waitcnt vmcnt(4)
	v_mfma_f32_16x16x32_bf16 v[2:5], v[30:33], v[34:37], v[2:5]
	global_load_dwordx4 v[26:29], v[8:9], off offset:1920
	global_load_dwordx4 v[30:33], v[8:9], off offset:1984
	s_waitcnt vmcnt(3)
	v_mfma_f32_16x16x32_bf16 v[2:5], v[14:17], v[22:25], v[2:5]
	global_load_dwordx4 v[14:17], v[78:79], off offset:1920
	s_waitcnt vmcnt(3)
	v_mfma_f32_16x16x32_bf16 v[2:5], v[38:41], v[18:21], v[2:5]
	global_load_dwordx4 v[18:21], v[78:79], off offset:1984
	s_waitcnt vmcnt(1)
	v_mfma_f32_16x16x32_bf16 v[2:5], v[26:29], v[14:17], v[2:5]
	s_waitcnt vmcnt(0)
	v_mfma_f32_16x16x32_bf16 v[2:5], v[30:33], v[18:21], v[2:5]
	s_and_saveexec_b64 s[28:29], vcc
	s_cbranch_execz .LBB0_474
	v_lshlrev_b64 v[14:15], 6, v[12:13]
	v_lshl_add_u64 v[26:27], s[30:31], 0, v[14:15]
	global_load_dwordx4 v[14:17], v[26:27], off offset:32
	global_load_dwordx4 v[18:21], v[26:27], off
	global_load_dwordx4 v[22:25], v[26:27], off offset:48
	s_nop 0
	global_load_dwordx4 v[26:29], v[26:27], off offset:16
	v_lshlrev_b64 v[12:13], 5, v[12:13]
	v_lshl_add_u64 v[12:13], v[10:11], 0, v[12:13]
	s_waitcnt vmcnt(3)
	v_mov_b32_e32 v30, v14
	s_waitcnt vmcnt(2)
	v_mov_b32_e32 v31, v18
	v_mov_b32_e32 v18, v15
	v_mov_b32_e32 v14, v16
	v_mov_b32_e32 v15, v20
	v_mov_b32_e32 v20, v17
	s_waitcnt vmcnt(1)
	v_mov_b32_e32 v16, v22
	s_waitcnt vmcnt(0)
	v_mov_b32_e32 v17, v26
	v_mov_b32_e32 v26, v23
	v_mov_b32_e32 v22, v24
	v_mov_b32_e32 v23, v28
	v_mov_b32_e32 v28, v25
	v_pk_add_f32 v[18:19], v[30:31], v[18:19]
	v_pk_add_f32 v[14:15], v[14:15], v[20:21]
	v_pk_add_f32 v[16:17], v[16:17], v[26:27]
	v_pk_add_f32 v[20:21], v[22:23], v[28:29]
	v_pk_add_f32 v[14:15], v[18:19], v[14:15]
	v_pk_add_f32 v[16:17], v[16:17], v[20:21]
	v_pk_add_f32 v[14:15], v[16:17], v[14:15]
	v_add_f32_e32 v14, v14, v15
	v_fmamk_f32 v14, v14, 0x3a800000, v225
	v_rsq_f32_e32 v14, v14
	s_nop 0
	v_pk_mul_f32 v[4:5], v[4:5], v[14:15] op_sel_hi:[1,0]
	v_pk_mul_f32 v[2:3], v[2:3], v[14:15] op_sel_hi:[1,0]
	global_store_dwordx4 v[12:13], v[2:5], off
	s_branch .LBB0_474

.LBB0_500:
	v_lshl_add_u32 v146, s6, 8, v142
	s_sub_i32 s6, s6, s5
	v_lshl_add_u32 v147, s6, 10, v143
	ds_read2_b32 v[150:151], v147 offset1:16
	v_lshl_or_b32 v148, s7, 8, v144
	v_ashrrev_i32_e32 v149, 31, v148
	s_mov_b32 s8, 0xc000
	s_mov_b64 s[28:29], -1
	s_waitcnt lgkmcnt(0)
	v_pk_mul_f32 v[126:127], v[126:127], v[150:151] op_sel_hi:[1,0]
	v_pk_mul_f32 v[118:119], v[118:119], v[150:151] op_sel_hi:[1,0]
	v_cvt_pk_bf16_f32 v152, v126, v127
	v_pk_mul_f32 v[126:127], v[128:129], v[150:151] op_sel_hi:[1,0]
	v_pk_mul_f32 v[114:115], v[114:115], v[150:151] op_sel_hi:[1,0]
	v_cvt_pk_bf16_f32 v126, v126, v127
	v_cvt_pk_bf16_f32 v127, v118, v119
	v_pk_mul_f32 v[118:119], v[120:121], v[150:151] op_sel_hi:[1,0]
	v_cvt_pk_bf16_f32 v120, v118, v119
	v_pk_mul_f32 v[118:119], v[122:123], v[150:151] op_sel_hi:[1,0]
	v_cvt_pk_bf16_f32 v121, v118, v119
	v_pk_mul_f32 v[118:119], v[124:125], v[150:151] op_sel_hi:[1,0]
	v_cvt_pk_bf16_f32 v124, v114, v115
	v_pk_mul_f32 v[114:115], v[116:117], v[150:151] op_sel_hi:[1,0]
	v_mov_b32_e32 v116, 0
	v_cvt_pk_bf16_f32 v114, v114, v115
	v_cndmask_b32_e64 v115, v127, v152, s[42:43]
	v_cvt_pk_bf16_f32 v125, v118, v119
	s_nop 0
	v_mov_b32_dpp v116, v115 row_ror:8 row_mask:0xf bank_mask:0xf
	v_cndmask_b32_e64 v118, v152, v116, s[42:43]
	v_cndmask_b32_e64 v122, v116, v127, s[42:43]
	v_cndmask_b32_e64 v115, v120, v126, s[42:43]
	v_mov_b32_e32 v116, 0
	s_nop 1
	v_mov_b32_dpp v116, v115 row_ror:8 row_mask:0xf bank_mask:0xf
	v_cndmask_b32_e64 v119, v126, v116, s[42:43]
	v_cndmask_b32_e64 v123, v116, v120, s[42:43]
	v_cndmask_b32_e64 v115, v124, v121, s[42:43]
	v_mov_b32_e32 v116, 0
	s_nop 1
	v_mov_b32_dpp v116, v115 row_ror:8 row_mask:0xf bank_mask:0xf
	v_cndmask_b32_e64 v120, v121, v116, s[42:43]
	v_cndmask_b32_e64 v124, v116, v124, s[42:43]
	v_cndmask_b32_e64 v115, v114, v125, s[42:43]
	v_mov_b32_e32 v116, 0
	s_nop 1
	v_mov_b32_dpp v116, v115 row_ror:8 row_mask:0xf bank_mask:0xf
	v_cndmask_b32_e64 v121, v125, v116, s[42:43]
	v_cndmask_b32_e64 v125, v116, v114, s[42:43]
	v_mov_b64_e32 v[114:115], s[80:81]
	v_mad_i64_i32 v[126:127], s[6:7], v146, s87, v[114:115]
	v_lshlrev_b64 v[116:117], 1, v[148:149]
	v_lshl_add_u64 v[126:127], v[126:127], 0, v[116:117]
	global_store_dwordx4 v[126:127], v[118:121], off
	s_nop 1
	v_add_co_u32_e32 v118, vcc, s8, v126
	s_nop 1
	v_addc_co_u32_e32 v119, vcc, 0, v127, vcc
	global_store_dwordx4 v[118:119], v[122:125], off
	v_mov_b32_e32 v118, v151
	v_pk_mul_f32 v[110:111], v[110:111], v[118:119] op_sel_hi:[1,0]
	v_cvt_pk_bf16_f32 v119, v110, v111
	v_pk_mul_f32 v[110:111], v[112:113], v[118:119] op_sel_hi:[1,0]
	v_pk_mul_f32 v[102:103], v[102:103], v[118:119] op_sel_hi:[1,0]
	v_cvt_pk_bf16_f32 v110, v110, v111
	v_cvt_pk_bf16_f32 v111, v102, v103
	v_pk_mul_f32 v[102:103], v[104:105], v[118:119] op_sel_hi:[1,0]
	v_pk_mul_f32 v[98:99], v[98:99], v[118:119] op_sel_hi:[1,0]
	v_cvt_pk_bf16_f32 v104, v102, v103
	v_pk_mul_f32 v[102:103], v[106:107], v[118:119] op_sel_hi:[1,0]
	v_cvt_pk_bf16_f32 v107, v98, v99
	v_pk_mul_f32 v[98:99], v[100:101], v[118:119] op_sel_hi:[1,0]
	v_cvt_pk_bf16_f32 v105, v102, v103
	v_pk_mul_f32 v[102:103], v[108:109], v[118:119] op_sel_hi:[1,0]
	v_cvt_pk_bf16_f32 v108, v98, v99
	v_cndmask_b32_e64 v98, v111, v119, s[42:43]
	v_mov_b32_e32 v99, 0
	v_cvt_pk_bf16_f32 v106, v102, v103
	v_mov_b32_e32 v100, 0
	v_mov_b32_dpp v99, v98 row_ror:8 row_mask:0xf bank_mask:0xf
	v_cndmask_b32_e64 v98, v119, v99, s[42:43]
	v_cndmask_b32_e64 v102, v99, v111, s[42:43]
	v_cndmask_b32_e64 v99, v104, v110, s[42:43]
	v_mov_b32_e32 v101, 0
	s_nop 0
	v_mov_b32_dpp v100, v99 row_ror:8 row_mask:0xf bank_mask:0xf
	v_cndmask_b32_e64 v99, v110, v100, s[42:43]
	v_cndmask_b32_e64 v103, v100, v104, s[42:43]
	v_cndmask_b32_e64 v100, v107, v105, s[42:43]
	s_nop 1
	v_mov_b32_dpp v101, v100 row_ror:8 row_mask:0xf bank_mask:0xf
	v_cndmask_b32_e64 v100, v105, v101, s[42:43]
	v_cndmask_b32_e64 v104, v101, v107, s[42:43]
	v_cndmask_b32_e64 v101, v108, v106, s[42:43]
	v_mov_b32_e32 v105, 0
	s_nop 1
	v_mov_b32_dpp v105, v101 row_ror:8 row_mask:0xf bank_mask:0xf
	v_cndmask_b32_e64 v101, v106, v105, s[42:43]
	v_or_b32_e32 v106, 16, v146
	v_mad_i64_i32 v[106:107], s[6:7], v106, s87, v[114:115]
	v_lshl_add_u64 v[106:107], v[106:107], 0, v[116:117]
	global_store_dwordx4 v[106:107], v[98:101], off
	v_cndmask_b32_e64 v105, v105, v108, s[42:43]
	s_nop 0
	v_add_co_u32_e32 v98, vcc, s8, v106
	s_nop 1
	v_addc_co_u32_e32 v99, vcc, 0, v107, vcc
	global_store_dwordx4 v[98:99], v[102:105], off
	ds_read2_b32 v[98:99], v147 offset0:32 offset1:48
	s_waitcnt lgkmcnt(0)
	v_pk_mul_f32 v[94:95], v[94:95], v[98:99] op_sel_hi:[1,0]
	v_cvt_pk_bf16_f32 v100, v94, v95
	v_pk_mul_f32 v[94:95], v[96:97], v[98:99] op_sel_hi:[1,0]
	v_pk_mul_f32 v[86:87], v[86:87], v[98:99] op_sel_hi:[1,0]
	v_cvt_pk_bf16_f32 v94, v94, v95
	v_cvt_pk_bf16_f32 v95, v86, v87
	v_pk_mul_f32 v[86:87], v[88:89], v[98:99] op_sel_hi:[1,0]
	v_pk_mul_f32 v[82:83], v[82:83], v[98:99] op_sel_hi:[1,0]
	v_cvt_pk_bf16_f32 v88, v86, v87
	v_pk_mul_f32 v[86:87], v[90:91], v[98:99] op_sel_hi:[1,0]
	v_cvt_pk_bf16_f32 v91, v82, v83
	v_pk_mul_f32 v[82:83], v[84:85], v[98:99] op_sel_hi:[1,0]
	v_cvt_pk_bf16_f32 v89, v86, v87
	v_pk_mul_f32 v[86:87], v[92:93], v[98:99] op_sel_hi:[1,0]
	v_cvt_pk_bf16_f32 v92, v82, v83
	v_cndmask_b32_e64 v82, v95, v100, s[42:43]
	v_mov_b32_e32 v83, 0
	v_cvt_pk_bf16_f32 v90, v86, v87
	v_mov_b32_e32 v84, 0
	v_mov_b32_dpp v83, v82 row_ror:8 row_mask:0xf bank_mask:0xf
	v_cndmask_b32_e64 v82, v100, v83, s[42:43]
	v_cndmask_b32_e64 v86, v83, v95, s[42:43]
	v_cndmask_b32_e64 v83, v88, v94, s[42:43]
	v_mov_b32_e32 v85, 0
	s_nop 0
	v_mov_b32_dpp v84, v83 row_ror:8 row_mask:0xf bank_mask:0xf
	v_cndmask_b32_e64 v83, v94, v84, s[42:43]
	v_cndmask_b32_e64 v87, v84, v88, s[42:43]
	v_cndmask_b32_e64 v84, v91, v89, s[42:43]
	s_nop 1
	v_mov_b32_dpp v85, v84 row_ror:8 row_mask:0xf bank_mask:0xf
	v_cndmask_b32_e64 v84, v89, v85, s[42:43]
	v_cndmask_b32_e64 v88, v85, v91, s[42:43]
	v_cndmask_b32_e64 v85, v92, v90, s[42:43]
	v_mov_b32_e32 v89, 0
	s_nop 1
	v_mov_b32_dpp v89, v85 row_ror:8 row_mask:0xf bank_mask:0xf
	v_cndmask_b32_e64 v85, v90, v89, s[42:43]
	v_or_b32_e32 v90, 32, v146
	v_mad_i64_i32 v[90:91], s[6:7], v90, s87, v[114:115]
	v_lshl_add_u64 v[90:91], v[90:91], 0, v[116:117]
	global_store_dwordx4 v[90:91], v[82:85], off
	v_cndmask_b32_e64 v89, v89, v92, s[42:43]
	s_nop 0
	v_add_co_u32_e32 v82, vcc, s8, v90
	s_nop 1
	v_addc_co_u32_e32 v83, vcc, 0, v91, vcc
	global_store_dwordx4 v[82:83], v[86:89], off
	v_mov_b32_e32 v82, v99
	v_pk_mul_f32 v[78:79], v[78:79], v[82:83] op_sel_hi:[1,0]
	v_cvt_pk_bf16_f32 v83, v78, v79
	v_pk_mul_f32 v[78:79], v[80:81], v[82:83] op_sel_hi:[1,0]
	v_pk_mul_f32 v[70:71], v[70:71], v[82:83] op_sel_hi:[1,0]
	v_cvt_pk_bf16_f32 v78, v78, v79
	v_cvt_pk_bf16_f32 v79, v70, v71
	v_pk_mul_f32 v[70:71], v[72:73], v[82:83] op_sel_hi:[1,0]
	v_pk_mul_f32 v[66:67], v[66:67], v[82:83] op_sel_hi:[1,0]
	v_cvt_pk_bf16_f32 v72, v70, v71
	v_pk_mul_f32 v[70:71], v[74:75], v[82:83] op_sel_hi:[1,0]
	v_cvt_pk_bf16_f32 v75, v66, v67
	v_pk_mul_f32 v[66:67], v[68:69], v[82:83] op_sel_hi:[1,0]
	v_cvt_pk_bf16_f32 v73, v70, v71
	v_pk_mul_f32 v[70:71], v[76:77], v[82:83] op_sel_hi:[1,0]
	v_cvt_pk_bf16_f32 v76, v66, v67
	v_cndmask_b32_e64 v66, v79, v83, s[42:43]
	v_mov_b32_e32 v67, 0
	v_cvt_pk_bf16_f32 v74, v70, v71
	v_mov_b32_e32 v68, 0
	v_mov_b32_dpp v67, v66 row_ror:8 row_mask:0xf bank_mask:0xf
	v_cndmask_b32_e64 v66, v83, v67, s[42:43]
	v_cndmask_b32_e64 v70, v67, v79, s[42:43]
	v_cndmask_b32_e64 v67, v72, v78, s[42:43]
	v_mov_b32_e32 v69, 0
	s_nop 0
	v_mov_b32_dpp v68, v67 row_ror:8 row_mask:0xf bank_mask:0xf
	v_cndmask_b32_e64 v67, v78, v68, s[42:43]
	v_cndmask_b32_e64 v71, v68, v72, s[42:43]
	v_cndmask_b32_e64 v68, v75, v73, s[42:43]
	s_nop 1
	v_mov_b32_dpp v69, v68 row_ror:8 row_mask:0xf bank_mask:0xf
	v_cndmask_b32_e64 v68, v73, v69, s[42:43]
	v_cndmask_b32_e64 v72, v69, v75, s[42:43]
	v_cndmask_b32_e64 v69, v76, v74, s[42:43]
	v_mov_b32_e32 v73, 0
	s_nop 1
	v_mov_b32_dpp v73, v69 row_ror:8 row_mask:0xf bank_mask:0xf
	v_cndmask_b32_e64 v69, v74, v73, s[42:43]
	v_or_b32_e32 v74, 48, v146
	v_mad_i64_i32 v[74:75], s[6:7], v74, s87, v[114:115]
	v_lshl_add_u64 v[74:75], v[74:75], 0, v[116:117]
	global_store_dwordx4 v[74:75], v[66:69], off
	v_cndmask_b32_e64 v73, v73, v76, s[42:43]
	s_nop 0
	v_add_co_u32_e32 v66, vcc, s8, v74
	s_nop 1
	v_addc_co_u32_e32 v67, vcc, 0, v75, vcc
	global_store_dwordx4 v[66:67], v[70:73], off
	ds_read2_b32 v[66:67], v147 offset0:128 offset1:144
	s_waitcnt lgkmcnt(0)
	v_pk_mul_f32 v[62:63], v[62:63], v[66:67] op_sel_hi:[1,0]
	v_cvt_pk_bf16_f32 v68, v62, v63
	v_pk_mul_f32 v[62:63], v[64:65], v[66:67] op_sel_hi:[1,0]
	v_pk_mul_f32 v[54:55], v[54:55], v[66:67] op_sel_hi:[1,0]
	v_cvt_pk_bf16_f32 v62, v62, v63
	v_cvt_pk_bf16_f32 v63, v54, v55
	v_pk_mul_f32 v[54:55], v[56:57], v[66:67] op_sel_hi:[1,0]
	v_pk_mul_f32 v[50:51], v[50:51], v[66:67] op_sel_hi:[1,0]
	v_cvt_pk_bf16_f32 v56, v54, v55
	v_pk_mul_f32 v[54:55], v[58:59], v[66:67] op_sel_hi:[1,0]
	v_cvt_pk_bf16_f32 v59, v50, v51
	v_pk_mul_f32 v[50:51], v[52:53], v[66:67] op_sel_hi:[1,0]
	v_cvt_pk_bf16_f32 v57, v54, v55
	v_pk_mul_f32 v[54:55], v[60:61], v[66:67] op_sel_hi:[1,0]
	v_cvt_pk_bf16_f32 v60, v50, v51
	v_cndmask_b32_e64 v50, v63, v68, s[42:43]
	v_mov_b32_e32 v51, 0
	v_cvt_pk_bf16_f32 v58, v54, v55
	v_mov_b32_e32 v52, 0
	v_mov_b32_dpp v51, v50 row_ror:8 row_mask:0xf bank_mask:0xf
	v_cndmask_b32_e64 v50, v68, v51, s[42:43]
	v_cndmask_b32_e64 v54, v51, v63, s[42:43]
	v_cndmask_b32_e64 v51, v56, v62, s[42:43]
	v_mov_b32_e32 v53, 0
	s_nop 0
	v_mov_b32_dpp v52, v51 row_ror:8 row_mask:0xf bank_mask:0xf
	v_cndmask_b32_e64 v51, v62, v52, s[42:43]
	v_cndmask_b32_e64 v55, v52, v56, s[42:43]
	v_cndmask_b32_e64 v52, v59, v57, s[42:43]
	s_nop 1
	v_mov_b32_dpp v53, v52 row_ror:8 row_mask:0xf bank_mask:0xf
	v_cndmask_b32_e64 v52, v57, v53, s[42:43]
	v_cndmask_b32_e64 v56, v53, v59, s[42:43]
	v_cndmask_b32_e64 v53, v60, v58, s[42:43]
	v_mov_b32_e32 v57, 0
	s_nop 1
	v_mov_b32_dpp v57, v53 row_ror:8 row_mask:0xf bank_mask:0xf
	v_cndmask_b32_e64 v53, v58, v57, s[42:43]
	v_add_u32_e32 v58, 0x80, v146
	v_mad_i64_i32 v[58:59], s[6:7], v58, s87, v[114:115]
	v_lshl_add_u64 v[58:59], v[58:59], 0, v[116:117]
	global_store_dwordx4 v[58:59], v[50:53], off
	v_cndmask_b32_e64 v57, v57, v60, s[42:43]
	s_nop 0
	v_add_co_u32_e32 v50, vcc, s8, v58
	s_nop 1
	v_addc_co_u32_e32 v51, vcc, 0, v59, vcc
	global_store_dwordx4 v[50:51], v[54:57], off
	v_mov_b32_e32 v50, v67
	v_pk_mul_f32 v[46:47], v[46:47], v[50:51] op_sel_hi:[1,0]
	v_cvt_pk_bf16_f32 v51, v46, v47
	v_pk_mul_f32 v[46:47], v[48:49], v[50:51] op_sel_hi:[1,0]
	v_pk_mul_f32 v[38:39], v[38:39], v[50:51] op_sel_hi:[1,0]
	v_cvt_pk_bf16_f32 v46, v46, v47
	v_cvt_pk_bf16_f32 v47, v38, v39
	v_pk_mul_f32 v[38:39], v[40:41], v[50:51] op_sel_hi:[1,0]
	v_pk_mul_f32 v[34:35], v[34:35], v[50:51] op_sel_hi:[1,0]
	v_cvt_pk_bf16_f32 v40, v38, v39
	v_pk_mul_f32 v[38:39], v[42:43], v[50:51] op_sel_hi:[1,0]
	v_cvt_pk_bf16_f32 v43, v34, v35
	v_pk_mul_f32 v[34:35], v[36:37], v[50:51] op_sel_hi:[1,0]
	v_cvt_pk_bf16_f32 v41, v38, v39
	v_pk_mul_f32 v[38:39], v[44:45], v[50:51] op_sel_hi:[1,0]
	v_cvt_pk_bf16_f32 v44, v34, v35
	v_cndmask_b32_e64 v34, v47, v51, s[42:43]
	v_mov_b32_e32 v35, 0
	v_cvt_pk_bf16_f32 v42, v38, v39
	v_mov_b32_e32 v36, 0
	v_mov_b32_dpp v35, v34 row_ror:8 row_mask:0xf bank_mask:0xf
	v_cndmask_b32_e64 v34, v51, v35, s[42:43]
	v_cndmask_b32_e64 v38, v35, v47, s[42:43]
	v_cndmask_b32_e64 v35, v40, v46, s[42:43]
	v_mov_b32_e32 v37, 0
	s_nop 0
	v_mov_b32_dpp v36, v35 row_ror:8 row_mask:0xf bank_mask:0xf
	v_cndmask_b32_e64 v35, v46, v36, s[42:43]
	v_cndmask_b32_e64 v39, v36, v40, s[42:43]
	v_cndmask_b32_e64 v36, v43, v41, s[42:43]
	s_nop 1
	v_mov_b32_dpp v37, v36 row_ror:8 row_mask:0xf bank_mask:0xf
	v_cndmask_b32_e64 v36, v41, v37, s[42:43]
	v_cndmask_b32_e64 v40, v37, v43, s[42:43]
	v_cndmask_b32_e64 v37, v44, v42, s[42:43]
	v_mov_b32_e32 v41, 0
	s_nop 1
	v_mov_b32_dpp v41, v37 row_ror:8 row_mask:0xf bank_mask:0xf
	v_cndmask_b32_e64 v37, v42, v41, s[42:43]
	v_add_u32_e32 v42, 0x90, v146
	v_mad_i64_i32 v[42:43], s[6:7], v42, s87, v[114:115]
	v_lshl_add_u64 v[42:43], v[42:43], 0, v[116:117]
	global_store_dwordx4 v[42:43], v[34:37], off
	v_cndmask_b32_e64 v41, v41, v44, s[42:43]
	s_nop 0
	v_add_co_u32_e32 v34, vcc, s8, v42
	s_nop 1
	v_addc_co_u32_e32 v35, vcc, 0, v43, vcc
	global_store_dwordx4 v[34:35], v[38:41], off
	ds_read2_b32 v[34:35], v147 offset0:160 offset1:176
	s_waitcnt lgkmcnt(0)
	v_pk_mul_f32 v[30:31], v[30:31], v[34:35] op_sel_hi:[1,0]
	v_cvt_pk_bf16_f32 v36, v30, v31
	v_pk_mul_f32 v[30:31], v[32:33], v[34:35] op_sel_hi:[1,0]
	v_pk_mul_f32 v[22:23], v[22:23], v[34:35] op_sel_hi:[1,0]
	v_cvt_pk_bf16_f32 v30, v30, v31
	v_cvt_pk_bf16_f32 v31, v22, v23
	v_pk_mul_f32 v[22:23], v[24:25], v[34:35] op_sel_hi:[1,0]
	v_pk_mul_f32 v[18:19], v[18:19], v[34:35] op_sel_hi:[1,0]
	v_cvt_pk_bf16_f32 v24, v22, v23
	v_pk_mul_f32 v[22:23], v[26:27], v[34:35] op_sel_hi:[1,0]
	v_cvt_pk_bf16_f32 v27, v18, v19
	v_pk_mul_f32 v[18:19], v[20:21], v[34:35] op_sel_hi:[1,0]
	v_cvt_pk_bf16_f32 v25, v22, v23
	v_pk_mul_f32 v[22:23], v[28:29], v[34:35] op_sel_hi:[1,0]
	v_cvt_pk_bf16_f32 v28, v18, v19
	v_cndmask_b32_e64 v18, v31, v36, s[42:43]
	v_mov_b32_e32 v19, 0
	v_cvt_pk_bf16_f32 v26, v22, v23
	v_mov_b32_e32 v20, 0
	v_mov_b32_dpp v19, v18 row_ror:8 row_mask:0xf bank_mask:0xf
	v_cndmask_b32_e64 v18, v36, v19, s[42:43]
	v_cndmask_b32_e64 v22, v19, v31, s[42:43]
	v_cndmask_b32_e64 v19, v24, v30, s[42:43]
	v_mov_b32_e32 v21, 0
	s_nop 0
	v_mov_b32_dpp v20, v19 row_ror:8 row_mask:0xf bank_mask:0xf
	v_cndmask_b32_e64 v19, v30, v20, s[42:43]
	v_cndmask_b32_e64 v23, v20, v24, s[42:43]
	v_cndmask_b32_e64 v20, v27, v25, s[42:43]
	s_nop 1
	v_mov_b32_dpp v21, v20 row_ror:8 row_mask:0xf bank_mask:0xf
	v_cndmask_b32_e64 v20, v25, v21, s[42:43]
	v_cndmask_b32_e64 v24, v21, v27, s[42:43]
	v_cndmask_b32_e64 v21, v28, v26, s[42:43]
	v_mov_b32_e32 v25, 0
	s_nop 1
	v_mov_b32_dpp v25, v21 row_ror:8 row_mask:0xf bank_mask:0xf
	v_cndmask_b32_e64 v21, v26, v25, s[42:43]
	v_add_u32_e32 v26, 0xa0, v146
	v_mad_i64_i32 v[26:27], s[6:7], v26, s87, v[114:115]
	v_lshl_add_u64 v[26:27], v[26:27], 0, v[116:117]
	global_store_dwordx4 v[26:27], v[18:21], off
	v_cndmask_b32_e64 v25, v25, v28, s[42:43]
	s_nop 0
	v_add_co_u32_e32 v18, vcc, s8, v26
	s_nop 1
	v_addc_co_u32_e32 v19, vcc, 0, v27, vcc
	global_store_dwordx4 v[18:19], v[22:25], off
	v_mov_b32_e32 v18, v35
	v_pk_mul_f32 v[14:15], v[14:15], v[18:19] op_sel_hi:[1,0]
	v_cvt_pk_bf16_f32 v19, v14, v15
	v_pk_mul_f32 v[14:15], v[16:17], v[18:19] op_sel_hi:[1,0]
	v_pk_mul_f32 v[6:7], v[6:7], v[18:19] op_sel_hi:[1,0]
	v_cvt_pk_bf16_f32 v14, v14, v15
	v_cvt_pk_bf16_f32 v15, v6, v7
	v_pk_mul_f32 v[6:7], v[8:9], v[18:19] op_sel_hi:[1,0]
	v_pk_mul_f32 v[2:3], v[2:3], v[18:19] op_sel_hi:[1,0]
	v_cvt_pk_bf16_f32 v8, v6, v7
	v_pk_mul_f32 v[6:7], v[10:11], v[18:19] op_sel_hi:[1,0]
	v_cvt_pk_bf16_f32 v11, v2, v3
	v_pk_mul_f32 v[2:3], v[4:5], v[18:19] op_sel_hi:[1,0]
	v_cvt_pk_bf16_f32 v9, v6, v7
	v_pk_mul_f32 v[6:7], v[12:13], v[18:19] op_sel_hi:[1,0]
	v_cvt_pk_bf16_f32 v12, v2, v3
	v_cndmask_b32_e64 v2, v15, v19, s[42:43]
	v_mov_b32_e32 v3, 0
	v_cvt_pk_bf16_f32 v10, v6, v7
	v_mov_b32_e32 v4, 0
	v_mov_b32_dpp v3, v2 row_ror:8 row_mask:0xf bank_mask:0xf
	v_cndmask_b32_e64 v2, v19, v3, s[42:43]
	v_cndmask_b32_e64 v6, v3, v15, s[42:43]
	v_cndmask_b32_e64 v3, v8, v14, s[42:43]
	v_mov_b32_e32 v5, 0
	s_nop 0
	v_mov_b32_dpp v4, v3 row_ror:8 row_mask:0xf bank_mask:0xf
	v_cndmask_b32_e64 v3, v14, v4, s[42:43]
	v_cndmask_b32_e64 v7, v4, v8, s[42:43]
	v_cndmask_b32_e64 v4, v11, v9, s[42:43]
	s_nop 1
	v_mov_b32_dpp v5, v4 row_ror:8 row_mask:0xf bank_mask:0xf
	v_cndmask_b32_e64 v4, v9, v5, s[42:43]
	v_cndmask_b32_e64 v8, v5, v11, s[42:43]
	v_cndmask_b32_e64 v5, v12, v10, s[42:43]
	v_mov_b32_e32 v9, 0
	s_nop 1
	v_mov_b32_dpp v9, v5 row_ror:8 row_mask:0xf bank_mask:0xf
	v_cndmask_b32_e64 v5, v10, v9, s[42:43]
	v_add_u32_e32 v10, 0xb0, v146
	v_mad_i64_i32 v[10:11], s[6:7], v10, s87, v[114:115]
	v_lshl_add_u64 v[10:11], v[10:11], 0, v[116:117]
	global_store_dwordx4 v[10:11], v[2:5], off
	v_cndmask_b32_e64 v9, v9, v12, s[42:43]
	s_nop 0
	v_add_co_u32_e32 v2, vcc, 0xc000, v10
	s_nop 1
	v_addc_co_u32_e32 v3, vcc, 0, v11, vcc
	s_andn2_b64 vcc, exec, s[44:45]
	global_store_dwordx4 v[2:3], v[6:9], off
	s_cbranch_vccnz .LBB0_493
	s_andn2_b64 vcc, exec, s[48:49]
	s_cbranch_vccnz .LBB0_492
	s_barrier
	s_branch .LBB0_492

.LBB0_508:
	s_nop 1
	global_load_dwordx4 v[2:5], v[8:9], off
	v_add_u32_e32 v12, s5, v1
	v_ashrrev_i32_e32 v13, 31, v12
	v_lshlrev_b64 v[14:15], 11, v[12:13]
	v_lshl_add_u64 v[78:79], v[6:7], 0, v[14:15]
	global_load_dwordx4 v[14:17], v[8:9], off offset:64
	global_load_dwordx4 v[18:21], v[78:79], off
	global_load_dwordx4 v[22:25], v[78:79], off offset:64
	global_load_dwordx4 v[26:29], v[8:9], off offset:128
	global_load_dwordx4 v[30:33], v[8:9], off offset:192
	global_load_dwordx4 v[34:37], v[78:79], off offset:128
	global_load_dwordx4 v[38:41], v[8:9], off offset:256
	global_load_dwordx4 v[42:45], v[78:79], off offset:192
	global_load_dwordx4 v[46:49], v[78:79], off offset:256
	global_load_dwordx4 v[50:53], v[8:9], off offset:320
	global_load_dwordx4 v[54:57], v[78:79], off offset:320
	global_load_dwordx4 v[58:61], v[8:9], off offset:384
	global_load_dwordx4 v[62:65], v[8:9], off offset:448
	global_load_dwordx4 v[66:69], v[78:79], off offset:384
	global_load_dwordx4 v[70:73], v[78:79], off offset:448
	s_waitcnt vmcnt(0)
	v_mfma_f32_16x16x32_bf16 v[2:5], v[2:5], v[18:21], 0
	global_load_dwordx4 v[18:21], v[8:9], off offset:512
	global_load_dwordx4 v[74:77], v[8:9], off offset:576
	v_mfma_f32_16x16x32_bf16 v[2:5], v[14:17], v[22:25], v[2:5]
	global_load_dwordx4 v[14:17], v[78:79], off offset:512
	global_load_dwordx4 v[22:25], v[78:79], off offset:576
	v_mfma_f32_16x16x32_bf16 v[2:5], v[26:29], v[34:37], v[2:5]
	global_load_dwordx4 v[26:29], v[8:9], off offset:640
	global_load_dwordx4 v[34:37], v[8:9], off offset:704
	v_mfma_f32_16x16x32_bf16 v[2:5], v[30:33], v[42:45], v[2:5]
	global_load_dwordx4 v[30:33], v[78:79], off offset:640
	v_mfma_f32_16x16x32_bf16 v[2:5], v[38:41], v[46:49], v[2:5]
	global_load_dwordx4 v[38:41], v[78:79], off offset:704
	global_load_dwordx4 v[42:45], v[8:9], off offset:768
	global_load_dwordx4 v[46:49], v[8:9], off offset:832
	v_mfma_f32_16x16x32_bf16 v[2:5], v[50:53], v[54:57], v[2:5]
	global_load_dwordx4 v[50:53], v[78:79], off offset:768
	global_load_dwordx4 v[54:57], v[78:79], off offset:832
	v_mfma_f32_16x16x32_bf16 v[2:5], v[58:61], v[66:69], v[2:5]
	v_mfma_f32_16x16x32_bf16 v[2:5], v[62:65], v[70:73], v[2:5]
	global_load_dwordx4 v[58:61], v[8:9], off offset:896
	global_load_dwordx4 v[62:65], v[8:9], off offset:960
	s_waitcnt vmcnt(11)
	v_mfma_f32_16x16x32_bf16 v[2:5], v[18:21], v[14:17], v[2:5]
	global_load_dwordx4 v[14:17], v[78:79], off offset:896
	global_load_dwordx4 v[18:21], v[78:79], off offset:960
	s_waitcnt vmcnt(12)
	v_mfma_f32_16x16x32_bf16 v[2:5], v[74:77], v[22:25], v[2:5]
	global_load_dwordx4 v[22:25], v[8:9], off offset:1024
	global_load_dwordx4 v[66:69], v[8:9], off offset:1088
	s_waitcnt vmcnt(11)
	v_mfma_f32_16x16x32_bf16 v[2:5], v[26:29], v[30:33], v[2:5]
	global_load_dwordx4 v[26:29], v[78:79], off offset:1024
	global_load_dwordx4 v[30:33], v[78:79], off offset:1088
	s_waitcnt vmcnt(12)
	v_mfma_f32_16x16x32_bf16 v[2:5], v[34:37], v[38:41], v[2:5]
	global_load_dwordx4 v[34:37], v[8:9], off offset:1152
	global_load_dwordx4 v[38:41], v[8:9], off offset:1216
	s_waitcnt vmcnt(11)
	v_mfma_f32_16x16x32_bf16 v[2:5], v[42:45], v[50:53], v[2:5]
	s_waitcnt vmcnt(10)
	v_mfma_f32_16x16x32_bf16 v[2:5], v[46:49], v[54:57], v[2:5]
	global_load_dwordx4 v[42:45], v[78:79], off offset:1152
	global_load_dwordx4 v[46:49], v[78:79], off offset:1216
	s_waitcnt vmcnt(9)
	v_mfma_f32_16x16x32_bf16 v[2:5], v[58:61], v[14:17], v[2:5]
	global_load_dwordx4 v[14:17], v[8:9], off offset:1280
	global_load_dwordx4 v[50:53], v[8:9], off offset:1344
	s_waitcnt vmcnt(10)
	v_mfma_f32_16x16x32_bf16 v[2:5], v[62:65], v[18:21], v[2:5]
	global_load_dwordx4 v[18:21], v[78:79], off offset:1280
	global_load_dwordx4 v[54:57], v[8:9], off offset:1408
	s_waitcnt vmcnt(9)
	v_mfma_f32_16x16x32_bf16 v[2:5], v[22:25], v[26:29], v[2:5]
	global_load_dwordx4 v[22:25], v[78:79], off offset:1344
	global_load_dwordx4 v[26:29], v[78:79], off offset:1408
	s_waitcnt vmcnt(10)
	v_mfma_f32_16x16x32_bf16 v[2:5], v[66:69], v[30:33], v[2:5]
	s_waitcnt vmcnt(7)
	v_mfma_f32_16x16x32_bf16 v[2:5], v[34:37], v[42:45], v[2:5]
	global_load_dwordx4 v[30:33], v[8:9], off offset:1472
	global_load_dwordx4 v[34:37], v[78:79], off offset:1472
	s_waitcnt vmcnt(8)
	v_mfma_f32_16x16x32_bf16 v[2:5], v[38:41], v[46:49], v[2:5]
	global_load_dwordx4 v[38:41], v[8:9], off offset:1536
	global_load_dwordx4 v[42:45], v[8:9], off offset:1600
	s_waitcnt vmcnt(7)
	v_mfma_f32_16x16x32_bf16 v[2:5], v[14:17], v[18:21], v[2:5]
	global_load_dwordx4 v[14:17], v[78:79], off offset:1536
	global_load_dwordx4 v[18:21], v[8:9], off offset:1664
	s_waitcnt vmcnt(7)
	v_mfma_f32_16x16x32_bf16 v[2:5], v[50:53], v[22:25], v[2:5]
	global_load_dwordx4 v[22:25], v[78:79], off offset:1600
	s_waitcnt vmcnt(7)
	v_mfma_f32_16x16x32_bf16 v[2:5], v[54:57], v[26:29], v[2:5]
	global_load_dwordx4 v[26:29], v[78:79], off offset:1664
	s_waitcnt vmcnt(6)
	v_mfma_f32_16x16x32_bf16 v[2:5], v[30:33], v[34:37], v[2:5]
	global_load_dwordx4 v[30:33], v[8:9], off offset:1728
	global_load_dwordx4 v[34:37], v[78:79], off offset:1728
	s_waitcnt vmcnt(5)
	v_mfma_f32_16x16x32_bf16 v[2:5], v[38:41], v[14:17], v[2:5]
	global_load_dwordx4 v[14:17], v[8:9], off offset:1792
	global_load_dwordx4 v[38:41], v[8:9], off offset:1856
	s_waitcnt vmcnt(5)
	v_mfma_f32_16x16x32_bf16 v[2:5], v[42:45], v[22:25], v[2:5]
	global_load_dwordx4 v[22:25], v[78:79], off offset:1792
	s_waitcnt vmcnt(5)
	v_mfma_f32_16x16x32_bf16 v[2:5], v[18:21], v[26:29], v[2:5]
	global_load_dwordx4 v[18:21], v[78:79], off offset:1856
	s_waitcnt vmcnt(4)
	v_mfma_f32_16x16x32_bf16 v[2:5], v[30:33], v[34:37], v[2:5]
	global_load_dwordx4 v[26:29], v[8:9], off offset:1920
	global_load_dwordx4 v[30:33], v[8:9], off offset:1984
	s_waitcnt vmcnt(3)
	v_mfma_f32_16x16x32_bf16 v[2:5], v[14:17], v[22:25], v[2:5]
	global_load_dwordx4 v[14:17], v[78:79], off offset:1920
	s_waitcnt vmcnt(3)
	v_mfma_f32_16x16x32_bf16 v[2:5], v[38:41], v[18:21], v[2:5]
	global_load_dwordx4 v[18:21], v[78:79], off offset:1984
	s_waitcnt vmcnt(1)
	v_mfma_f32_16x16x32_bf16 v[2:5], v[26:29], v[14:17], v[2:5]
	s_waitcnt vmcnt(0)
	v_mfma_f32_16x16x32_bf16 v[2:5], v[30:33], v[18:21], v[2:5]
	s_and_saveexec_b64 s[28:29], vcc
	s_cbranch_execz .LBB0_507
	v_lshlrev_b64 v[14:15], 6, v[12:13]
	v_lshl_add_u64 v[26:27], s[30:31], 0, v[14:15]
	global_load_dwordx4 v[14:17], v[26:27], off offset:32
	global_load_dwordx4 v[18:21], v[26:27], off
	global_load_dwordx4 v[22:25], v[26:27], off offset:48
	s_nop 0
	global_load_dwordx4 v[26:29], v[26:27], off offset:16
	v_lshlrev_b64 v[12:13], 5, v[12:13]
	v_lshl_add_u64 v[12:13], v[10:11], 0, v[12:13]
	s_waitcnt vmcnt(3)
	v_mov_b32_e32 v30, v14
	s_waitcnt vmcnt(2)
	v_mov_b32_e32 v31, v18
	v_mov_b32_e32 v18, v15
	v_mov_b32_e32 v14, v16
	v_mov_b32_e32 v15, v20
	v_mov_b32_e32 v20, v17
	s_waitcnt vmcnt(1)
	v_mov_b32_e32 v16, v22
	s_waitcnt vmcnt(0)
	v_mov_b32_e32 v17, v26
	v_mov_b32_e32 v26, v23
	v_mov_b32_e32 v22, v24
	v_mov_b32_e32 v23, v28
	v_mov_b32_e32 v28, v25
	v_pk_add_f32 v[18:19], v[30:31], v[18:19]
	v_pk_add_f32 v[14:15], v[14:15], v[20:21]
	v_pk_add_f32 v[16:17], v[16:17], v[26:27]
	v_pk_add_f32 v[20:21], v[22:23], v[28:29]
	v_pk_add_f32 v[14:15], v[18:19], v[14:15]
	v_pk_add_f32 v[16:17], v[16:17], v[20:21]
	v_pk_add_f32 v[14:15], v[16:17], v[14:15]
	v_add_f32_e32 v14, v14, v15
	v_fmamk_f32 v14, v14, 0x3a800000, v225
	v_rsq_f32_e32 v14, v14
	s_nop 0
	v_pk_mul_f32 v[4:5], v[4:5], v[14:15] op_sel_hi:[1,0]
	v_pk_mul_f32 v[2:3], v[2:3], v[14:15] op_sel_hi:[1,0]
	global_store_dwordx4 v[12:13], v[2:5], off
	s_branch .LBB0_507
